# SwiGLU epilogue packed + lagging-half offset barrier moved to K-loop entry (after next-unit scalar work and acc zeroing) in 14 GEMM instances
# baseline (speedup 1.0000x reference)
; #define PG8_WAIT_V(n) asm volatile("s_waitcnt vmcnt(" #n ")" ::: "memory")
; template <class Epi, class Sched, bool ALIGN_EPI = false, bool SP2 = false, bool ABLK = false, bool BBLK = false>
; __device__ __forceinline__ void gemm_phase(PG8_LAS unsigned char* lds, const Gemm g, const Sched& S, const Epi& E) {
;     ...
;     const int tid = tid_, wid = __builtin_amdgcn_readfirstlane(tid >> 6), lane = tid & 63, wr = wid >> 2, wc = wid & 3, fr = lane & 15, fq = lane >> 4;
;     const int K = g.K, nt = K / BK, LDA = g.lda ? g.lda : K, LDB = g.ldb ? g.ldb : K;
;     unsigned voffA[2], voffB[2];
; #pragma unroll
;     for (int i = 0; i < 2; ++i) { int R, C; stage_rc(tid * 16 + i * 8192, R, C); const int Rb = Epi::PERM ? ((R & ~31) + perm32(R & 31)) : R;
;         voffA[i] = ABLK ? (unsigned)(R * BK + C) * 2u : (unsigned)(R * LDA + C) * 2u; voffB[i] = BBLK ? (unsigned)(Rb * BK + C) * 2u : (unsigned)(Rb * LDB + C) * 2u; }
;     const size_t kstep = (size_t)(BK * 2);
;     const size_t hstepa = (size_t)HALF * LDA * 2, hstepb = (size_t)HALF * LDB * 2;
;     const size_t kstepA = ABLK ? (size_t)BM * BK * 2 : kstep, hstepA = ABLK ? (size_t)HALF * BK * 2 : hstepa, tstepA = ABLK ? (size_t)nt * BM * BK * 2 : 2 * hstepa;
;     const size_t kstepB = BBLK ? (size_t)BM * BK * 2 : kstep, hstepB = BBLK ? (size_t)HALF * BK * 2 : hstepb, tstepB = BBLK ? (size_t)nt * BM * BK * 2 : 2 * hstepb;
;     const unsigned ldsw = (unsigned)wid * 1024u;
;     const int aoff = lds_byte(wr * 64 + fr, fq * 8), boff = lds_byte(wc * 32 + fr, fq * 8);
;     ...
;     Unit cur, nxt; int ui = 0;
;     if (!S.next(0, cur)) return;
;     f32x4 acc[2][2][4][2];
; #pragma unroll
;     for (int a = 0; a < 2; ++a)
; #pragma unroll
;         for (int b = 0; b < 2; ++b)
; #pragma unroll
;             for (int m = 0; m < 4; ++m)
; #pragma unroll
;                 for (int n = 0; n < 2; ++n) acc[a][b][m][n] = (f32x4){0.f, 0.f, 0.f, 0.f};
;     bf16x8 At[4][2], B0[2][2], B1[2][2];
;     const char* cA = (const char*)g.A + (size_t)cur.pm * tstepA; const char* cB = (const char*)g.Bt + (size_t)cur.pn * tstepB;
;     S.a_ready(cur);
;     if constexpr (SP2) {
;         PG8_STAGE(PG8_SB(0, 0), cB, voffB); PG8_STAGE(PG8_SB(0, 1), cB + hstepB, voffB); PG8_STAGE(PG8_SA(0, 0), cA, voffA); PG8_STAGE(PG8_SA(0, 1), cA + hstepA, voffA);
;         if (wr == 1) PG8_BAR;
;         PG8_WAIT_V(2); PG8_BAR;
.LBB0_207:
	v_mov_b32_e32 v2, v0
	v_readlane_b32 s0, v254, 6
	v_readlane_b32 s33, v254, 4
	v_readlane_b32 s34, v254, 5
	s_mov_b32 s2, s17
	s_ashr_i32 s3, s2, 31
	v_readlane_b32 s0, v254, 7
	v_readlane_b32 s1, v254, 8
	s_add_u32 s30, s0, s2
	s_addc_u32 s31, s1, s3
	v_mov_b32_e32 v2, v0
	s_mov_b64 s[90:91], 0x8000
	s_cmpk_gt_i32 s34, 0x18bf
	v_readfirstlane_b32 s5, v2
	v_writelane_b32 v254, s26, 41
	s_nop 1
	v_writelane_b32 v254, s27, 42
	s_cbranch_scc1 .LBB0_223
	s_waitcnt vmcnt(10)
	v_lshlrev_b32_e32 v6, 4, v2
	v_add_u32_e32 v4, 0x2000, v6
	v_ashrrev_i32_e32 v3, 31, v4
	v_lshrrev_b32_e32 v3, 22, v3
	v_add_u32_e32 v3, v4, v3
	v_ashrrev_i32_e32 v3, 10, v3
	v_mul_i32_i24_e32 v5, 0x400, v3
	v_sub_u32_e32 v4, v4, v5
	v_lshrrev_b32_e32 v5, 4, v4
	v_bitop3_b32 v5, v5, v4, 32 bitop3:0x6c
	v_ashrrev_i32_e32 v4, 31, v5
	v_lshrrev_b32_e32 v4, 26, v4
	v_add_u32_e32 v7, v5, v4
	v_lshlrev_b32_e32 v8, 3, v3
	v_ashrrev_i32_e32 v4, 6, v7
	v_and_b32_e32 v8, -16, v8
	v_add_u32_e32 v8, v4, v8
	v_and_b32_e32 v9, 3, v4
	s_mov_b32 s0, 0x1ffffe0
	s_waitcnt vmcnt(9)
	v_lshrrev_b32_e32 v10, 2, v8
	v_lshlrev_b32_e32 v11, 1, v8
	v_and_b32_e32 v7, 0xc0, v7
	v_and_or_b32 v9, v8, s0, v9
	v_and_b32_e32 v10, 4, v10
	v_and_b32_e32 v11, 24, v11
	v_sub_u32_e32 v5, v5, v7
	v_or3_b32 v9, v9, v10, v11
	v_lshlrev_b32_e32 v10, 5, v3
	v_ashrrev_i16_sdwa v5, v232, sext(v5) dst_sel:DWORD dst_unused:UNUSED_PAD src0_sel:DWORD src1_sel:BYTE_0
	v_and_b32_e32 v10, 32, v10
	v_bfe_i32 v5, v5, 0, 16
	v_add_lshl_u32 v7, v10, v5, 1
	v_lshl_add_u32 v130, v9, 7, v7
	v_lshl_add_u32 v132, v8, 7, v7
	v_bfe_i32 v7, v2, 27, 1
	v_lshrrev_b32_e32 v7, 22, v7
	v_add_u32_e32 v7, v6, v7
	v_and_b32_e32 v7, 0xfffffc00, v7
	v_sub_u32_e32 v6, v6, v7
	v_lshrrev_b32_e32 v7, 4, v6
	v_bitop3_b32 v8, v7, v6, 32 bitop3:0x6c
	v_ashrrev_i32_e32 v7, 31, v2
	v_lshrrev_b32_e32 v7, 26, v7
	v_ashrrev_i32_e32 v6, 31, v8
	v_add_u32_e32 v7, v2, v7
	s_add_u32 s35, s30, 0xf600000
	v_lshrrev_b32_e32 v6, 26, v6
	v_ashrrev_i32_e32 v7, 6, v7
	s_addc_u32 s36, s31, 0
	v_add_u32_e32 v9, v8, v6
	v_lshlrev_b32_e32 v10, 3, v7
	s_add_u32 s37, s30, 0x3500000
	v_ashrrev_i32_e32 v6, 6, v9
	v_and_b32_e32 v10, -16, v10
	s_addc_u32 s40, s31, 0
	v_add_u32_e32 v10, v6, v10
	v_and_b32_e32 v11, 3, v6
	s_ashr_i32 s42, s34, 31
	v_and_or_b32 v11, v10, s0, v11
	s_lshr_b32 s0, s42, 29
	s_add_i32 s0, s34, s0
	s_ashr_i32 s9, s5, 6
	s_ashr_i32 s1, s0, 3
	s_and_b32 s0, s0, -8
	s_ashr_i32 s10, s5, 8
	s_lshl_b32 s41, s9, 10
	s_sub_i32 s0, s34, s0
	s_cmp_lt_i32 s0, 0
	s_movk_i32 s4, 0x319
	s_cselect_b32 s4, s4, 0x318
	s_mul_i32 s0, s0, s4
	s_add_i32 s0, s0, s1
	s_mul_hi_i32 s1, s0, 0x2e8ba2e9
	s_lshr_b32 s4, s1, 31
	s_ashr_i32 s1, s1, 5
	s_add_i32 s1, s1, s4
	s_lshl_b32 s6, s1, 2
	s_mulk_i32 s1, 0xb0
	s_sub_i32 s0, s0, s1
	s_bfe_u32 s1, s0, 0x2001d
	s_add_i32 s1, s0, s1
	s_sext_i32_i16 s4, s1
	s_and_b32 s1, s1, 0xfffc
	s_sub_i32 s0, s0, s1
	s_sext_i32_i16 s0, s0
	v_lshrrev_b32_e32 v12, 2, v10
	v_lshlrev_b32_e32 v13, 1, v10
	v_and_b32_e32 v9, 0xc0, v9
	s_lshr_b32 s4, s4, 2
	s_add_i32 s0, s6, s0
	v_and_b32_e32 v12, 4, v12
	v_and_b32_e32 v13, 24, v13
	v_sub_u32_e32 v8, v8, v9
	s_ashr_i32 s1, s0, 31
	s_bfe_i64 s[12:13], s[4:5], 0x100000
	v_or3_b32 v11, v11, v12, v13
	v_lshlrev_b32_e32 v12, 5, v7
	v_ashrrev_i16_sdwa v8, v232, sext(v8) dst_sel:DWORD dst_unused:UNUSED_PAD src0_sel:DWORD src1_sel:BYTE_0
	s_lshl_b64 s[6:7], s[0:1], 20
	s_lshl_b64 s[12:13], s[12:13], 20
	v_and_b32_e32 v12, 32, v12
	v_bfe_i32 v8, v8, 0, 16
	s_add_u32 s24, s37, s12
	v_add_lshl_u32 v9, v12, v8, 1
	s_addc_u32 s25, s40, s13
	s_add_i32 s43, s41, 0
	v_lshl_add_u32 v134, v11, 7, v9
	s_add_i32 m0, s43, 0x10000
	v_lshl_add_u32 v136, v10, 7, v9
	global_load_lds_dwordx4 v134, s[24:25]
	s_add_i32 m0, s43, 0x12000
	s_add_u32 s12, s24, 0x4000
	global_load_lds_dwordx4 v130, s[24:25]
	s_addc_u32 s13, s25, 0
	s_add_i32 m0, s43, 0x14000
	s_nop 0
	global_load_lds_dwordx4 v134, s[12:13]
	s_add_i32 m0, s43, 0x16000
	s_add_u32 s22, s35, s6
	s_addc_u32 s23, s36, s7
	s_add_i32 s44, s43, 0x2000
	global_load_lds_dwordx4 v130, s[12:13]
	s_mov_b32 m0, s43
	s_add_u32 s6, s22, 0x4000
	global_load_lds_dwordx4 v136, s[22:23]
	s_mov_b32 m0, s44
	s_addc_u32 s7, s23, 0
	s_add_i32 s45, s43, 0x4000
	global_load_lds_dwordx4 v132, s[22:23]
	s_mov_b32 m0, s45
	s_add_i32 s46, s43, 0x6000
	global_load_lds_dwordx4 v136, s[6:7]
	s_mov_b32 m0, s46
	s_cmp_eq_u32 s10, 1
	global_load_lds_dwordx4 v132, s[6:7]
	s_cselect_b64 s[6:7], -1, 0
	s_cmp_lg_u32 s10, 1
	s_cbranch_scc1 .LBB0_210
.LBB0_210:
	s_add_u32 s47, s30, 0x18600000
	s_addc_u32 s50, s31, 0
	s_and_b32 s1, s9, 3
	s_lshl_b32 s8, s10, 6
	s_lshl_b32 s12, s10, 13
	s_lshl_b32 s13, s9, 5
	s_lshl_b32 s14, s1, 12
	s_add_u32 s10, s24, 0x8000
	v_mov_b32_e32 v135, v187
	s_addc_u32 s11, s25, 0
	s_add_i32 m0, s43, 0x18000
	v_lshl_add_u64 v[10:11], s[10:11], 0, v[134:135]
	v_mov_b32_e32 v131, v187
	s_waitcnt vmcnt(2)
	s_barrier
	global_load_lds_dwordx4 v[10:11], off
	s_add_i32 m0, s43, 0x1a000
	v_lshl_add_u64 v[10:11], s[10:11], 0, v[130:131]
	s_add_u32 s10, s22, 0x8000
	v_mov_b32_e32 v137, v187
	s_addc_u32 s11, s23, 0
	s_add_i32 s51, s43, 0x8000
	v_mov_b32_e32 v133, v187
	global_load_lds_dwordx4 v[10:11], off
	v_lshl_add_u64 v[10:11], s[10:11], 0, v[136:137]
	s_mov_b32 m0, s51
	s_add_i32 s53, s43, 0xa000
	global_load_lds_dwordx4 v[10:11], off
	v_lshl_add_u64 v[10:11], s[10:11], 0, v[132:133]
	s_add_u32 s10, s24, 0xc000
	s_mov_b32 m0, s53
	s_addc_u32 s11, s25, 0
	global_load_lds_dwordx4 v[10:11], off
	s_add_i32 m0, s43, 0x1c000
	v_lshl_add_u64 v[10:11], s[10:11], 0, v[134:135]
	global_load_lds_dwordx4 v[10:11], off
	v_lshl_add_u64 v[10:11], s[10:11], 0, v[130:131]
	s_add_i32 m0, s43, 0x1e000
	v_lshrrev_b32_e32 v9, 1, v2
	global_load_lds_dwordx4 v[10:11], off
	v_and_b32_e32 v10, 24, v9
	v_and_b32_e32 v144, 15, v2
	v_lshlrev_b32_e32 v9, 1, v10
	v_lshlrev_b32_e32 v2, 2, v2
	v_lshl_or_b32 v9, v144, 6, v9
	v_and_b32_e32 v2, 32, v2
	v_bitop3_b32 v11, v9, s12, v2 bitop3:0xde
	v_bitop3_b32 v145, v9, s14, v2 bitop3:0xde
	v_lshlrev_b32_e32 v2, 10, v7
	v_and_b32_e32 v2, 0xfffff800, v2
	v_lshl_add_u32 v2, v6, 7, v2
	v_and_b32_e32 v6, 1, v7
	v_lshl_or_b32 v2, v6, 6, v2
	v_lshl_add_u32 v138, v8, 1, v2
	v_lshlrev_b32_e32 v2, 10, v3
	v_and_b32_e32 v2, 0xfffff800, v2
	s_waitcnt vmcnt(6)
	s_cmpk_lt_u32 s5, 0x100
	v_lshl_add_u32 v2, v4, 7, v2
	v_and_b32_e32 v3, 1, v3
	s_sext_i32_i16 s1, s4
	s_cselect_b64 s[10:11], -1, 0
	s_and_b32 s4, s13, 32
	v_lshl_or_b32 v2, v3, 6, v2
	s_bfe_u32 s56, s9, 0x10001
	s_ashr_i32 s9, s8, 31
	s_ashr_i32 s60, s33, 31
	v_mov_b32_e32 v139, v187
	v_lshl_add_u32 v140, v5, 1, v2
	v_mov_b32_e32 v141, v187
	s_mov_b32 s61, 0
	v_add_u32_e32 v146, 0, v11
	s_lshl_b32 s16, s4, 1
	v_lshlrev_b32_e32 v186, 1, v10
	s_barrier
	s_waitcnt vmcnt(0)
	s_branch .LBB0_213

; #define PG8_STAGE(bufoff, gbase, voff) do { _Pragma("unroll") for (int _i = 0; _i < 2; ++_i) \
;         __builtin_amdgcn_global_load_lds((const unsigned*)((const char*)(gbase) + (voff)[_i]), (PG8_LAS unsigned*)(lds + (bufoff) + ldsw + _i * 8192), 16, 0, 0); } while (0)
; #define PG8_LDA(dst, b, h) do { _Pragma("unroll") for (int m = 0; m < 4; ++m) _Pragma("unroll") for (int k = 0; k < 2; ++k) dst[m][k] = *(const PG8_LAS bf16x8*)(lds + PG8_SA(b, h) + aoff + m * 2048 + k * 1024); } while (0)
; #define PG8_LDB(dst, b, h) do { _Pragma("unroll") for (int n = 0; n < 2; ++n) _Pragma("unroll") for (int k = 0; k < 2; ++k) dst[n][k] = *(const PG8_LAS bf16x8*)(lds + PG8_SB(b, h) + boff + n * 2048 + k * 1024); } while (0)
; #define PG8_WAIT_V(n) asm volatile("s_waitcnt vmcnt(" #n ")" ::: "memory")
; #define PG8_WAIT_L(n) asm volatile("s_waitcnt lgkmcnt(" #n ")" ::: "memory")
; #define PG8_BAR __builtin_amdgcn_s_barrier()
; template <class Epi, class Sched, bool ALIGN_EPI = false, bool SP2 = false, bool ABLK = false, bool BBLK = false>
; __device__ __forceinline__ void gemm_phase(PG8_LAS unsigned char* lds, const Gemm g, const Sched& S, const Epi& E) {
;     ...
;         const bool has_next = S.next(ui + 1, nxt);
;         const char* nA = has_next ? (const char*)g.A + (size_t)nxt.pm * tstepA : cA; const char* nB = has_next ? (const char*)g.Bt + (size_t)nxt.pn * tstepB : cB;
;         for (int t = 0; t < nt; t += 2) {
;             const bool last = (t == nt - 2);
;             const char* a1 = cA + (size_t)(t + 1) * kstepA;
;             const char* a2 = last ? nA : cA + (size_t)(t + 2) * kstepA; const char* b2 = last ? nB : cB + (size_t)(t + 2) * kstepB;
;             const char* a3 = a2 + kstepA; const char* b3 = b2 + kstepB;
;             if (last && has_next) S.a_ready(nxt);
;             if constexpr (SP2) {
;             PG8_LDB(B0, 0, 0); PG8_LDB(B1, 0, 1); PG8_SCHED; PG8_LDA(At, 0, 0); PG8_STAGE(PG8_SA(1, 1), a1 + hstepA, voffA);
;             PG8_WAIT_V(8); PG8_WAIT_L(0); PG8_BAR; PG8_MMA(0, 0, At, B0); PG8_MMA(0, 1, At, B1); PG8_BAR; PG8_SCHED;
;     ...
;         for (int a = 0; a < 2; ++a)
; #pragma unroll
;             for (int b = 0; b < 2; ++b)
; #pragma unroll
;                 for (int m = 0; m < 4; ++m)
; #pragma unroll
;                     for (int n = 0; n < 2; ++n) acc[a][b][m][n] = (f32x4){0.f, 0.f, 0.f, 0.f};
.LBB0_215:
	s_ashr_i32 s15, s14, 31
	s_lshl_b64 s[18:19], s[14:15], 20
	s_add_u32 s18, s35, s18
	s_addc_u32 s19, s36, s19
	s_and_b64 s[20:21], s[4:5], exec
	s_cselect_b32 s15, s19, s23
	s_cselect_b32 s65, s18, s22
	s_ashr_i32 s13, s12, 31
	s_lshl_b64 s[20:21], s[12:13], 20
	s_add_u32 s20, s37, s20
	s_addc_u32 s21, s40, s21
	s_and_b64 s[26:27], s[4:5], exec
	s_cselect_b32 s13, s21, s25
	s_cselect_b32 s68, s20, s24
	s_add_u32 s22, s22, 0xc000
	s_addc_u32 s23, s23, 0
	s_add_u32 s72, s24, 0x10000
	v_mov_b32_e32 v2, 0
	s_addc_u32 s73, s25, 0
	s_mov_b32 s81, -2
	v_mov_b32_e32 v3, v2
	v_mov_b32_e32 v4, v2
	v_mov_b32_e32 v5, v2
	v_mov_b32_e32 v10, v2
	v_mov_b32_e32 v11, v2
	v_mov_b32_e32 v12, v2
	v_mov_b32_e32 v13, v2
	v_mov_b32_e32 v18, v2
	v_mov_b32_e32 v19, v2
	v_mov_b32_e32 v20, v2
	v_mov_b32_e32 v21, v2
	v_mov_b32_e32 v26, v2
	v_mov_b32_e32 v27, v2
	v_mov_b32_e32 v28, v2
	v_mov_b32_e32 v29, v2
	v_mov_b32_e32 v34, v2
	v_mov_b32_e32 v35, v2
	v_mov_b32_e32 v36, v2
	v_mov_b32_e32 v37, v2
	v_mov_b32_e32 v42, v2
	v_mov_b32_e32 v43, v2
	v_mov_b32_e32 v44, v2
	v_mov_b32_e32 v45, v2
	v_mov_b32_e32 v50, v2
	v_mov_b32_e32 v51, v2
	v_mov_b32_e32 v52, v2
	v_mov_b32_e32 v53, v2
	v_mov_b32_e32 v58, v2
	v_mov_b32_e32 v59, v2
	v_mov_b32_e32 v60, v2
	v_mov_b32_e32 v61, v2
	v_mov_b32_e32 v6, v2
	v_mov_b32_e32 v7, v2
	v_mov_b32_e32 v8, v2
	v_mov_b32_e32 v9, v2
	v_mov_b32_e32 v14, v2
	v_mov_b32_e32 v15, v2
	v_mov_b32_e32 v16, v2
	v_mov_b32_e32 v17, v2
	v_mov_b32_e32 v22, v2
	v_mov_b32_e32 v23, v2
	v_mov_b32_e32 v24, v2
	v_mov_b32_e32 v25, v2
	v_mov_b32_e32 v30, v2
	v_mov_b32_e32 v31, v2
	v_mov_b32_e32 v32, v2
	v_mov_b32_e32 v33, v2
	v_mov_b32_e32 v38, v2
	v_mov_b32_e32 v39, v2
	v_mov_b32_e32 v40, v2
	v_mov_b32_e32 v41, v2
	v_mov_b32_e32 v46, v2
	v_mov_b32_e32 v47, v2
	v_mov_b32_e32 v48, v2
	v_mov_b32_e32 v49, v2
	v_mov_b32_e32 v54, v2
	v_mov_b32_e32 v55, v2
	v_mov_b32_e32 v56, v2
	v_mov_b32_e32 v57, v2
	v_mov_b32_e32 v62, v2
	v_mov_b32_e32 v63, v2
	v_mov_b32_e32 v64, v2
	v_mov_b32_e32 v65, v2
	v_mov_b32_e32 v66, v2
	v_mov_b32_e32 v67, v2
	v_mov_b32_e32 v68, v2
	v_mov_b32_e32 v69, v2
	v_mov_b32_e32 v74, v2
	v_mov_b32_e32 v75, v2
	v_mov_b32_e32 v76, v2
	v_mov_b32_e32 v77, v2
	v_mov_b32_e32 v82, v2
	v_mov_b32_e32 v83, v2
	v_mov_b32_e32 v84, v2
	v_mov_b32_e32 v85, v2
	v_mov_b32_e32 v90, v2
	v_mov_b32_e32 v91, v2
	v_mov_b32_e32 v92, v2
	v_mov_b32_e32 v93, v2
	v_mov_b32_e32 v98, v2
	v_mov_b32_e32 v99, v2
	v_mov_b32_e32 v100, v2
	v_mov_b32_e32 v101, v2
	v_mov_b32_e32 v106, v2
	v_mov_b32_e32 v107, v2
	v_mov_b32_e32 v108, v2
	v_mov_b32_e32 v109, v2
	v_mov_b32_e32 v114, v2
	v_mov_b32_e32 v115, v2
	v_mov_b32_e32 v116, v2
	v_mov_b32_e32 v117, v2
	v_mov_b32_e32 v122, v2
	v_mov_b32_e32 v123, v2
	v_mov_b32_e32 v124, v2
	v_mov_b32_e32 v125, v2
	v_mov_b32_e32 v70, v2
	v_mov_b32_e32 v71, v2
	v_mov_b32_e32 v72, v2
	v_mov_b32_e32 v73, v2
	v_mov_b32_e32 v78, v2
	v_mov_b32_e32 v79, v2
	v_mov_b32_e32 v80, v2
	v_mov_b32_e32 v81, v2
	v_mov_b32_e32 v86, v2
	v_mov_b32_e32 v87, v2
	v_mov_b32_e32 v88, v2
	v_mov_b32_e32 v89, v2
	v_mov_b32_e32 v94, v2
	v_mov_b32_e32 v95, v2
	v_mov_b32_e32 v96, v2
	v_mov_b32_e32 v97, v2
	v_mov_b32_e32 v102, v2
	v_mov_b32_e32 v103, v2
	v_mov_b32_e32 v104, v2
	v_mov_b32_e32 v105, v2
	v_mov_b32_e32 v110, v2
	v_mov_b32_e32 v111, v2
	v_mov_b32_e32 v112, v2
	v_mov_b32_e32 v113, v2
	v_mov_b32_e32 v118, v2
	v_mov_b32_e32 v119, v2
	v_mov_b32_e32 v120, v2
	v_mov_b32_e32 v121, v2
	v_mov_b32_e32 v126, v2
	v_mov_b32_e32 v127, v2
	v_mov_b32_e32 v128, v2
	v_mov_b32_e32 v129, v2
	s_and_b64 vcc, exec, s[10:11]
	s_cbranch_vccnz .Lrb_f1a
	s_barrier
.Lrb_f1a:
.LBB0_216:
	s_add_u32 s24, s22, 0x4000
	s_addc_u32 s25, s23, 0
	s_cmp_eq_u32 s81, 28
	s_cselect_b32 s28, s65, s24
	s_cselect_b32 s29, s15, s25
	s_cselect_b32 s26, s68, s72
	s_cselect_b32 s27, s13, s73
	s_add_u32 s24, s28, 0x8000
	s_addc_u32 s25, s29, 0
	s_add_i32 s75, 0, 0x10000
	v_add_u32_e32 v142, s75, v145
	s_add_i32 s80, 0, 0x14000
	ds_read_b128 v[148:151], v142
	ds_read_b128 v[152:155], v142 offset:1024
	ds_read_b128 v[156:159], v142 offset:2048
	ds_read_b128 v[160:163], v142 offset:3072
	v_add_u32_e32 v142, s80, v145
	ds_read_b128 v[164:167], v142
	ds_read_b128 v[168:171], v142 offset:1024
	ds_read_b128 v[172:175], v142 offset:2048
	ds_read_b128 v[176:179], v142 offset:3072
	v_lshl_add_u64 v[142:143], s[22:23], 0, v[138:139]
	s_add_i32 m0, s43, 0xc000
	ds_read_b128 v[180:183], v146
	ds_read_b128 v[196:199], v146 offset:1024
	ds_read_b128 v[200:203], v146 offset:2048
	ds_read_b128 v[204:207], v146 offset:3072
	ds_read_b128 v[208:211], v146 offset:4096
	ds_read_b128 v[212:215], v146 offset:5120
	ds_read_b128 v[216:219], v146 offset:6144
	ds_read_b128 v[220:223], v146 offset:7168
	global_load_lds_dwordx4 v[142:143], off
	v_lshl_add_u64 v[142:143], s[22:23], 0, v[140:141]
	s_add_i32 m0, s43, 0xe000
	s_nop 0
	global_load_lds_dwordx4 v[142:143], off
	s_waitcnt vmcnt(8)
	s_waitcnt lgkmcnt(0)
	s_barrier
; #define PG8_STAGE(bufoff, gbase, voff) do { _Pragma("unroll") for (int _i = 0; _i < 2; ++_i) \
;         __builtin_amdgcn_global_load_lds((const unsigned*)((const char*)(gbase) + (voff)[_i]), (PG8_LAS unsigned*)(lds + (bufoff) + ldsw + _i * 8192), 16, 0, 0); } while (0)
; #define PG8_LDA(dst, b, h) do { _Pragma("unroll") for (int m = 0; m < 4; ++m) _Pragma("unroll") for (int k = 0; k < 2; ++k) dst[m][k] = *(const PG8_LAS bf16x8*)(lds + PG8_SA(b, h) + aoff + m * 2048 + k * 1024); } while (0)
; #define PG8_MMA(ai, bj, At, Bt) do { __builtin_amdgcn_s_setprio(1); _Pragma("unroll") for (int m = 0; m < 4; ++m) _Pragma("unroll") for (int n = 0; n < 2; ++n) _Pragma("unroll") for (int k = 0; k < 2; ++k) \
;         acc[ai][bj][m][n] = __builtin_amdgcn_mfma_f32_16x16x32_bf16(Bt[n][k], At[m][k], acc[ai][bj][m][n], 0, 0, 0); __builtin_amdgcn_s_setprio(0); } while (0)
; #define PG8_WAIT_V(n) asm volatile("s_waitcnt vmcnt(" #n ")" ::: "memory")
; #define PG8_WAIT_L(n) asm volatile("s_waitcnt lgkmcnt(" #n ")" ::: "memory")
; #define PG8_BAR __builtin_amdgcn_s_barrier()
; #define PG8_SCHED __builtin_amdgcn_sched_barrier(0)
; template <class Epi, class Sched, bool ALIGN_EPI = false, bool SP2 = false, bool ABLK = false, bool BBLK = false>
; __device__ __forceinline__ void gemm_phase(PG8_LAS unsigned char* lds, const Gemm g, const Sched& S, const Epi& E) {
;     ...
;             PG8_WAIT_V(8); PG8_WAIT_L(0); PG8_BAR; PG8_MMA(0, 0, At, B0); PG8_MMA(0, 1, At, B1); PG8_BAR; PG8_SCHED;
;             PG8_LDA(At, 0, 1); PG8_STAGE(PG8_SB(0, 0), b2, voffB); PG8_STAGE(PG8_SB(0, 1), b2 + hstepB, voffB); PG8_STAGE(PG8_SA(0, 0), a2, voffA);
;             PG8_WAIT_V(8); PG8_WAIT_L(0); PG8_BAR; PG8_MMA(1, 0, At, B0); PG8_MMA(1, 1, At, B1); PG8_BAR; PG8_SCHED;
	s_setprio 1
	s_waitcnt lgkmcnt(0)
	v_mfma_f32_16x16x32_bf16 v[126:129], v[148:151], v[180:183], v[126:129]
	v_mfma_f32_16x16x32_bf16 v[118:121], v[156:159], v[180:183], v[118:121]
	v_mfma_f32_16x16x32_bf16 v[110:113], v[148:151], v[200:203], v[110:113]
	v_mfma_f32_16x16x32_bf16 v[102:105], v[156:159], v[200:203], v[102:105]
	v_mfma_f32_16x16x32_bf16 v[94:97], v[148:151], v[208:211], v[94:97]
	v_mfma_f32_16x16x32_bf16 v[86:89], v[156:159], v[208:211], v[86:89]
	v_mfma_f32_16x16x32_bf16 v[78:81], v[148:151], v[216:219], v[78:81]
	v_mfma_f32_16x16x32_bf16 v[70:73], v[156:159], v[216:219], v[70:73]
	v_mfma_f32_16x16x32_bf16 v[126:129], v[152:155], v[196:199], v[126:129]
	v_mfma_f32_16x16x32_bf16 v[118:121], v[160:163], v[196:199], v[118:121]
	v_mfma_f32_16x16x32_bf16 v[110:113], v[152:155], v[204:207], v[110:113]
	v_mfma_f32_16x16x32_bf16 v[102:105], v[160:163], v[204:207], v[102:105]
	v_mfma_f32_16x16x32_bf16 v[94:97], v[152:155], v[212:215], v[94:97]
	v_mfma_f32_16x16x32_bf16 v[86:89], v[160:163], v[212:215], v[86:89]
	v_mfma_f32_16x16x32_bf16 v[78:81], v[152:155], v[220:223], v[78:81]
	v_mfma_f32_16x16x32_bf16 v[70:73], v[160:163], v[220:223], v[70:73]
	s_setprio 0
	s_setprio 1
	v_mfma_f32_16x16x32_bf16 v[122:125], v[164:167], v[180:183], v[122:125]
	v_mfma_f32_16x16x32_bf16 v[114:117], v[172:175], v[180:183], v[114:117]
	v_mfma_f32_16x16x32_bf16 v[106:109], v[164:167], v[200:203], v[106:109]
	v_mfma_f32_16x16x32_bf16 v[98:101], v[172:175], v[200:203], v[98:101]
	v_mfma_f32_16x16x32_bf16 v[90:93], v[164:167], v[208:211], v[90:93]
	v_mfma_f32_16x16x32_bf16 v[82:85], v[172:175], v[208:211], v[82:85]
	v_mfma_f32_16x16x32_bf16 v[74:77], v[164:167], v[216:219], v[74:77]
	v_mfma_f32_16x16x32_bf16 v[66:69], v[172:175], v[216:219], v[66:69]
	v_mfma_f32_16x16x32_bf16 v[122:125], v[168:171], v[196:199], v[122:125]
	v_mfma_f32_16x16x32_bf16 v[114:117], v[176:179], v[196:199], v[114:117]
	v_mfma_f32_16x16x32_bf16 v[106:109], v[168:171], v[204:207], v[106:109]
	v_mfma_f32_16x16x32_bf16 v[98:101], v[176:179], v[204:207], v[98:101]
	v_mfma_f32_16x16x32_bf16 v[90:93], v[168:171], v[212:215], v[90:93]
	v_mfma_f32_16x16x32_bf16 v[82:85], v[176:179], v[212:215], v[82:85]
	v_mfma_f32_16x16x32_bf16 v[74:77], v[168:171], v[220:223], v[74:77]
	v_mfma_f32_16x16x32_bf16 v[66:69], v[176:179], v[220:223], v[66:69]
	s_setprio 0
	s_barrier
	s_add_i32 s75, s75, s41
	v_lshl_add_u64 v[142:143], s[26:27], 0, v[134:135]
	s_mov_b32 m0, s75
	ds_read_b128 v[180:183], v146 offset:16384
	ds_read_b128 v[196:199], v146 offset:17408
	ds_read_b128 v[200:203], v146 offset:18432
	ds_read_b128 v[204:207], v146 offset:19456
	ds_read_b128 v[208:211], v146 offset:20480
	ds_read_b128 v[212:215], v146 offset:21504
	ds_read_b128 v[216:219], v146 offset:22528
	ds_read_b128 v[220:223], v146 offset:23552
	global_load_lds_dwordx4 v[142:143], off
	s_add_i32 m0, s75, 0x2000
	s_add_u32 s82, s26, 0x4000
	v_lshl_add_u64 v[142:143], s[26:27], 0, v[130:131]
	s_addc_u32 s83, s27, 0
	s_add_i32 s75, s80, s41
	global_load_lds_dwordx4 v[142:143], off
	v_lshl_add_u64 v[142:143], s[82:83], 0, v[134:135]
	s_mov_b32 m0, s75
	s_nop 0
	global_load_lds_dwordx4 v[142:143], off
	v_lshl_add_u64 v[142:143], s[82:83], 0, v[130:131]
	s_add_i32 m0, s75, 0x2000
	s_nop 0
	global_load_lds_dwordx4 v[142:143], off
	v_lshl_add_u64 v[142:143], s[28:29], 0, v[136:137]
	s_mov_b32 m0, s43
	s_nop 0
	global_load_lds_dwordx4 v[142:143], off
	v_lshl_add_u64 v[142:143], s[28:29], 0, v[132:133]
	s_mov_b32 m0, s44
	s_nop 0
	global_load_lds_dwordx4 v[142:143], off
	s_waitcnt vmcnt(8)
	s_waitcnt lgkmcnt(0)
	s_barrier
	s_setprio 1
	s_waitcnt lgkmcnt(0)
	v_mfma_f32_16x16x32_bf16 v[62:65], v[148:151], v[180:183], v[62:65]
	v_mfma_f32_16x16x32_bf16 v[54:57], v[156:159], v[180:183], v[54:57]
	v_mfma_f32_16x16x32_bf16 v[46:49], v[148:151], v[200:203], v[46:49]
	v_mfma_f32_16x16x32_bf16 v[38:41], v[156:159], v[200:203], v[38:41]
	v_mfma_f32_16x16x32_bf16 v[30:33], v[148:151], v[208:211], v[30:33]
	v_mfma_f32_16x16x32_bf16 v[22:25], v[156:159], v[208:211], v[22:25]
	v_mfma_f32_16x16x32_bf16 v[14:17], v[148:151], v[216:219], v[14:17]
	v_mfma_f32_16x16x32_bf16 v[6:9], v[156:159], v[216:219], v[6:9]
	v_mfma_f32_16x16x32_bf16 v[62:65], v[152:155], v[196:199], v[62:65]
	v_mfma_f32_16x16x32_bf16 v[54:57], v[160:163], v[196:199], v[54:57]
	v_mfma_f32_16x16x32_bf16 v[46:49], v[152:155], v[204:207], v[46:49]
	v_mfma_f32_16x16x32_bf16 v[38:41], v[160:163], v[204:207], v[38:41]
	v_mfma_f32_16x16x32_bf16 v[30:33], v[152:155], v[212:215], v[30:33]
	v_mfma_f32_16x16x32_bf16 v[22:25], v[160:163], v[212:215], v[22:25]
	v_mfma_f32_16x16x32_bf16 v[14:17], v[152:155], v[220:223], v[14:17]
	v_mfma_f32_16x16x32_bf16 v[6:9], v[160:163], v[220:223], v[6:9]
	s_setprio 0
	s_setprio 1
	v_mfma_f32_16x16x32_bf16 v[58:61], v[164:167], v[180:183], v[58:61]
	v_mfma_f32_16x16x32_bf16 v[50:53], v[172:175], v[180:183], v[50:53]
	v_mfma_f32_16x16x32_bf16 v[42:45], v[164:167], v[200:203], v[42:45]
	v_mfma_f32_16x16x32_bf16 v[34:37], v[172:175], v[200:203], v[34:37]
	v_mfma_f32_16x16x32_bf16 v[26:29], v[164:167], v[208:211], v[26:29]
	v_mfma_f32_16x16x32_bf16 v[18:21], v[172:175], v[208:211], v[18:21]
	v_mfma_f32_16x16x32_bf16 v[10:13], v[164:167], v[216:219], v[10:13]
	v_mfma_f32_16x16x32_bf16 v[2:5], v[172:175], v[216:219], v[2:5]
	v_mfma_f32_16x16x32_bf16 v[58:61], v[168:171], v[196:199], v[58:61]
	v_mfma_f32_16x16x32_bf16 v[50:53], v[176:179], v[196:199], v[50:53]
	v_mfma_f32_16x16x32_bf16 v[42:45], v[168:171], v[204:207], v[42:45]
	v_mfma_f32_16x16x32_bf16 v[34:37], v[176:179], v[204:207], v[34:37]
	v_mfma_f32_16x16x32_bf16 v[26:29], v[168:171], v[212:215], v[26:29]
	v_mfma_f32_16x16x32_bf16 v[18:21], v[176:179], v[212:215], v[18:21]
	v_mfma_f32_16x16x32_bf16 v[10:13], v[168:171], v[220:223], v[10:13]
	v_mfma_f32_16x16x32_bf16 v[2:5], v[176:179], v[220:223], v[2:5]
	s_setprio 0
	s_barrier
; #define PG8_STAGE(bufoff, gbase, voff) do { _Pragma("unroll") for (int _i = 0; _i < 2; ++_i) \
;         __builtin_amdgcn_global_load_lds((const unsigned*)((const char*)(gbase) + (voff)[_i]), (PG8_LAS unsigned*)(lds + (bufoff) + ldsw + _i * 8192), 16, 0, 0); } while (0)
; #define PG8_LDA(dst, b, h) do { _Pragma("unroll") for (int m = 0; m < 4; ++m) _Pragma("unroll") for (int k = 0; k < 2; ++k) dst[m][k] = *(const PG8_LAS bf16x8*)(lds + PG8_SA(b, h) + aoff + m * 2048 + k * 1024); } while (0)
; #define PG8_LDB(dst, b, h) do { _Pragma("unroll") for (int n = 0; n < 2; ++n) _Pragma("unroll") for (int k = 0; k < 2; ++k) dst[n][k] = *(const PG8_LAS bf16x8*)(lds + PG8_SB(b, h) + boff + n * 2048 + k * 1024); } while (0)
; #define PG8_MMA(ai, bj, At, Bt) do { __builtin_amdgcn_s_setprio(1); _Pragma("unroll") for (int m = 0; m < 4; ++m) _Pragma("unroll") for (int n = 0; n < 2; ++n) _Pragma("unroll") for (int k = 0; k < 2; ++k) \
;         acc[ai][bj][m][n] = __builtin_amdgcn_mfma_f32_16x16x32_bf16(Bt[n][k], At[m][k], acc[ai][bj][m][n], 0, 0, 0); __builtin_amdgcn_s_setprio(0); } while (0)
; #define PG8_WAIT_V(n) asm volatile("s_waitcnt vmcnt(" #n ")" ::: "memory")
; #define PG8_WAIT_L(n) asm volatile("s_waitcnt lgkmcnt(" #n ")" ::: "memory")
; #define PG8_BAR __builtin_amdgcn_s_barrier()
; #define PG8_SCHED __builtin_amdgcn_sched_barrier(0)
; template <class Epi, class Sched, bool ALIGN_EPI = false, bool SP2 = false, bool ABLK = false, bool BBLK = false>
; __device__ __forceinline__ void gemm_phase(PG8_LAS unsigned char* lds, const Gemm g, const Sched& S, const Epi& E) {
;     ...
;             PG8_LDB(B0, 1, 0); PG8_LDB(B1, 1, 1); PG8_SCHED; PG8_LDA(At, 1, 0); PG8_STAGE(PG8_SA(0, 1), a2 + hstepA, voffA);
;             PG8_WAIT_V(8); PG8_WAIT_L(0); PG8_BAR; PG8_MMA(0, 0, At, B0); PG8_MMA(0, 1, At, B1); PG8_BAR; PG8_SCHED;
;             PG8_LDA(At, 1, 1); PG8_STAGE(PG8_SB(1, 0), b3, voffB); PG8_STAGE(PG8_SB(1, 1), b3 + hstepB, voffB); PG8_STAGE(PG8_SA(1, 0), a3, voffA);
;             PG8_WAIT_V(8); PG8_WAIT_L(0); PG8_BAR; PG8_MMA(1, 0, At, B0); PG8_MMA(1, 1, At, B1); PG8_BAR; PG8_SCHED;
	s_add_i32 s75, 0, 0x18000
	v_add_u32_e32 v142, s75, v145
	s_add_i32 s80, 0, 0x1c000
	ds_read_b128 v[148:151], v142
	ds_read_b128 v[152:155], v142 offset:1024
	ds_read_b128 v[156:159], v142 offset:2048
	ds_read_b128 v[160:163], v142 offset:3072
	v_add_u32_e32 v142, s80, v145
	ds_read_b128 v[164:167], v142
	ds_read_b128 v[168:171], v142 offset:1024
	ds_read_b128 v[172:175], v142 offset:2048
	ds_read_b128 v[176:179], v142 offset:3072
	s_add_u32 s28, s28, 0x4000
	s_addc_u32 s29, s29, 0
	s_mov_b32 m0, s45
	v_lshl_add_u64 v[142:143], s[28:29], 0, v[136:137]
	ds_read_b128 v[180:183], v146 offset:32768
	ds_read_b128 v[196:199], v146 offset:33792
	ds_read_b128 v[200:203], v146 offset:34816
	ds_read_b128 v[204:207], v146 offset:35840
	ds_read_b128 v[208:211], v146 offset:36864
	ds_read_b128 v[212:215], v146 offset:37888
	ds_read_b128 v[216:219], v146 offset:38912
	ds_read_b128 v[220:223], v146 offset:39936
	global_load_lds_dwordx4 v[142:143], off
	v_lshl_add_u64 v[142:143], s[28:29], 0, v[132:133]
	s_mov_b32 m0, s46
	s_nop 0
	global_load_lds_dwordx4 v[142:143], off
	s_waitcnt vmcnt(8)
	s_waitcnt lgkmcnt(0)
	s_barrier
	s_setprio 1
	s_waitcnt lgkmcnt(0)
	v_mfma_f32_16x16x32_bf16 v[126:129], v[148:151], v[180:183], v[126:129]
	v_mfma_f32_16x16x32_bf16 v[118:121], v[156:159], v[180:183], v[118:121]
	v_mfma_f32_16x16x32_bf16 v[110:113], v[148:151], v[200:203], v[110:113]
	v_mfma_f32_16x16x32_bf16 v[102:105], v[156:159], v[200:203], v[102:105]
	v_mfma_f32_16x16x32_bf16 v[94:97], v[148:151], v[208:211], v[94:97]
	v_mfma_f32_16x16x32_bf16 v[86:89], v[156:159], v[208:211], v[86:89]
	v_mfma_f32_16x16x32_bf16 v[78:81], v[148:151], v[216:219], v[78:81]
	v_mfma_f32_16x16x32_bf16 v[70:73], v[156:159], v[216:219], v[70:73]
	v_mfma_f32_16x16x32_bf16 v[126:129], v[152:155], v[196:199], v[126:129]
	v_mfma_f32_16x16x32_bf16 v[118:121], v[160:163], v[196:199], v[118:121]
	v_mfma_f32_16x16x32_bf16 v[110:113], v[152:155], v[204:207], v[110:113]
	v_mfma_f32_16x16x32_bf16 v[102:105], v[160:163], v[204:207], v[102:105]
	v_mfma_f32_16x16x32_bf16 v[94:97], v[152:155], v[212:215], v[94:97]
	v_mfma_f32_16x16x32_bf16 v[86:89], v[160:163], v[212:215], v[86:89]
	v_mfma_f32_16x16x32_bf16 v[78:81], v[152:155], v[220:223], v[78:81]
	v_mfma_f32_16x16x32_bf16 v[70:73], v[160:163], v[220:223], v[70:73]
	s_setprio 0
	s_setprio 1
	v_mfma_f32_16x16x32_bf16 v[122:125], v[164:167], v[180:183], v[122:125]
	v_mfma_f32_16x16x32_bf16 v[114:117], v[172:175], v[180:183], v[114:117]
	v_mfma_f32_16x16x32_bf16 v[106:109], v[164:167], v[200:203], v[106:109]
	v_mfma_f32_16x16x32_bf16 v[98:101], v[172:175], v[200:203], v[98:101]
	v_mfma_f32_16x16x32_bf16 v[90:93], v[164:167], v[208:211], v[90:93]
	v_mfma_f32_16x16x32_bf16 v[82:85], v[172:175], v[208:211], v[82:85]
	v_mfma_f32_16x16x32_bf16 v[74:77], v[164:167], v[216:219], v[74:77]
	v_mfma_f32_16x16x32_bf16 v[66:69], v[172:175], v[216:219], v[66:69]
	v_mfma_f32_16x16x32_bf16 v[122:125], v[168:171], v[196:199], v[122:125]
	v_mfma_f32_16x16x32_bf16 v[114:117], v[176:179], v[196:199], v[114:117]
	v_mfma_f32_16x16x32_bf16 v[106:109], v[168:171], v[204:207], v[106:109]
	v_mfma_f32_16x16x32_bf16 v[98:101], v[176:179], v[204:207], v[98:101]
	v_mfma_f32_16x16x32_bf16 v[90:93], v[168:171], v[212:215], v[90:93]
	v_mfma_f32_16x16x32_bf16 v[82:85], v[176:179], v[212:215], v[82:85]
	v_mfma_f32_16x16x32_bf16 v[74:77], v[168:171], v[220:223], v[74:77]
	v_mfma_f32_16x16x32_bf16 v[66:69], v[176:179], v[220:223], v[66:69]
	s_setprio 0
	s_barrier
	s_add_u32 s28, s26, 0x8000
	s_addc_u32 s29, s27, 0
	s_add_i32 s75, s75, s41
	v_lshl_add_u64 v[142:143], s[28:29], 0, v[134:135]
	s_mov_b32 m0, s75
	ds_read_b128 v[180:183], v146 offset:49152
	ds_read_b128 v[196:199], v146 offset:50176
	ds_read_b128 v[200:203], v146 offset:51200
	ds_read_b128 v[204:207], v146 offset:52224
	ds_read_b128 v[208:211], v146 offset:53248
	ds_read_b128 v[212:215], v146 offset:54272
	ds_read_b128 v[216:219], v146 offset:55296
	ds_read_b128 v[220:223], v146 offset:56320
	global_load_lds_dwordx4 v[142:143], off
	s_add_i32 m0, s75, 0x2000
	s_add_u32 s26, s26, 0xc000
	v_lshl_add_u64 v[142:143], s[28:29], 0, v[130:131]
	s_addc_u32 s27, s27, 0
	s_add_i32 s28, s80, s41
	global_load_lds_dwordx4 v[142:143], off
	v_lshl_add_u64 v[142:143], s[26:27], 0, v[134:135]
	s_mov_b32 m0, s28
	s_nop 0
	global_load_lds_dwordx4 v[142:143], off
	v_lshl_add_u64 v[142:143], s[26:27], 0, v[130:131]
	s_add_i32 m0, s28, 0x2000
	s_nop 0
	global_load_lds_dwordx4 v[142:143], off
	v_lshl_add_u64 v[142:143], s[24:25], 0, v[136:137]
	s_mov_b32 m0, s51
	s_nop 0
	global_load_lds_dwordx4 v[142:143], off
	v_lshl_add_u64 v[142:143], s[24:25], 0, v[132:133]
	s_mov_b32 m0, s53
	s_nop 0
	global_load_lds_dwordx4 v[142:143], off
	s_waitcnt vmcnt(8)
	s_waitcnt lgkmcnt(0)
	s_barrier
; __device__ __forceinline__ float fast_sigmoid(float x) { return __builtin_amdgcn_rcpf(1.0f + __builtin_amdgcn_exp2f(-1.4426950408889634f * x)); }
; #define PG8_BAR __builtin_amdgcn_s_barrier()
;     __device__ __forceinline__ void operator()(const f32x4 (&acc)[2][2][4][2], const Unit& u, int wr, int wc, int fr_, int fq) const {
;     ...
;                 for (int j = 0; j < 4; ++j) { const float g0 = acc[ai][0][m][0][j], g1 = acc[ai][0][m][1][j];
;                     v0[j] = g0 * fast_sigmoid(g0) * acc[ai][1][m][0][j]; v1[j] = g1 * fast_sigmoid(g1) * acc[ai][1][m][1][j]; }
;                 *(u32x4*)(Hblk + (size_t)(ai * HALF + m * 16) * BK) = pack8(v0, v1); }
; template <class Epi, class Sched, bool ALIGN_EPI = false, bool SP2 = false, bool ABLK = false, bool BBLK = false>
; __device__ __forceinline__ void gemm_phase(PG8_LAS unsigned char* lds, const Gemm g, const Sched& S, const Epi& E) {
;     ...
;             PG8_WAIT_V(8); PG8_WAIT_L(0); PG8_BAR; PG8_MMA(1, 0, At, B0); PG8_MMA(1, 1, At, B1); PG8_BAR; PG8_SCHED;
;             } else {
;             PG8_LDB(B0, 0, 0); PG8_SCHED; PG8_LDA(At, 0, 0); PG8_STAGE(PG8_SA(1, 1), a1 + hstepA, voffA);
;             PG8_WAIT_L(8); PG8_BAR; PG8_WAIT_L(0); PG8_MMA(0, 0, At, B0); PG8_BAR; PG8_SCHED;
;             PG8_LDB(B1, 0, 1); PG8_STAGE(PG8_SB(0, 0), b2, voffB);
;             PG8_BAR; PG8_WAIT_L(0); PG8_MMA(0, 1, At, B1); PG8_BAR;
;             PG8_LDA(At, 0, 1); PG8_STAGE(PG8_SA(0, 0), a2, voffA);
;             PG8_BAR; PG8_WAIT_L(0); PG8_MMA(1, 0, At, B0); PG8_BAR; PG8_SCHED;
;             PG8_STAGE(PG8_SB(0, 1), b2 + hstepB, voffB);
;             PG8_WAIT_V(6); PG8_BAR; PG8_MMA(1, 1, At, B1); PG8_BAR;
;             PG8_LDB(B0, 1, 0); PG8_SCHED; PG8_LDA(At, 1, 0); PG8_STAGE(PG8_SA(0, 1), a2 + hstepA, voffA);
;             PG8_WAIT_L(8); PG8_BAR; PG8_WAIT_L(0); PG8_MMA(0, 0, At, B0); PG8_BAR; PG8_SCHED;
;             PG8_LDB(B1, 1, 1); PG8_STAGE(PG8_SB(1, 0), b3, voffB);
;             PG8_BAR; PG8_WAIT_L(0); PG8_MMA(0, 1, At, B1); PG8_BAR;
;             PG8_LDA(At, 1, 1); PG8_STAGE(PG8_SA(1, 0), a3, voffA);
;             PG8_BAR; PG8_WAIT_L(0); PG8_MMA(1, 0, At, B0); PG8_BAR; PG8_SCHED;
;             PG8_STAGE(PG8_SB(1, 1), b3 + hstepB, voffB);
;             PG8_WAIT_V(6); PG8_BAR; PG8_MMA(1, 1, At, B1); PG8_BAR;
;             }
;         }
;         if constexpr (ALIGN_EPI) { if (wr == 0) PG8_BAR; }
	s_setprio 1
	s_waitcnt lgkmcnt(0)
	v_mfma_f32_16x16x32_bf16 v[62:65], v[148:151], v[180:183], v[62:65]
	v_mfma_f32_16x16x32_bf16 v[54:57], v[156:159], v[180:183], v[54:57]
	v_mfma_f32_16x16x32_bf16 v[46:49], v[148:151], v[200:203], v[46:49]
	v_mfma_f32_16x16x32_bf16 v[38:41], v[156:159], v[200:203], v[38:41]
	v_mfma_f32_16x16x32_bf16 v[30:33], v[148:151], v[208:211], v[30:33]
	v_mfma_f32_16x16x32_bf16 v[22:25], v[156:159], v[208:211], v[22:25]
	v_mfma_f32_16x16x32_bf16 v[14:17], v[148:151], v[216:219], v[14:17]
	v_mfma_f32_16x16x32_bf16 v[6:9], v[156:159], v[216:219], v[6:9]
	v_mfma_f32_16x16x32_bf16 v[62:65], v[152:155], v[196:199], v[62:65]
	v_mfma_f32_16x16x32_bf16 v[54:57], v[160:163], v[196:199], v[54:57]
	v_mfma_f32_16x16x32_bf16 v[46:49], v[152:155], v[204:207], v[46:49]
	v_mfma_f32_16x16x32_bf16 v[38:41], v[160:163], v[204:207], v[38:41]
	v_mfma_f32_16x16x32_bf16 v[30:33], v[152:155], v[212:215], v[30:33]
	v_mfma_f32_16x16x32_bf16 v[22:25], v[160:163], v[212:215], v[22:25]
	v_mfma_f32_16x16x32_bf16 v[14:17], v[152:155], v[220:223], v[14:17]
	v_mfma_f32_16x16x32_bf16 v[6:9], v[160:163], v[220:223], v[6:9]
	s_setprio 0
	s_setprio 1
	v_mfma_f32_16x16x32_bf16 v[58:61], v[164:167], v[180:183], v[58:61]
	v_mfma_f32_16x16x32_bf16 v[50:53], v[172:175], v[180:183], v[50:53]
	v_mfma_f32_16x16x32_bf16 v[42:45], v[164:167], v[200:203], v[42:45]
	v_mfma_f32_16x16x32_bf16 v[34:37], v[172:175], v[200:203], v[34:37]
	v_mfma_f32_16x16x32_bf16 v[26:29], v[164:167], v[208:211], v[26:29]
	v_mfma_f32_16x16x32_bf16 v[18:21], v[172:175], v[208:211], v[18:21]
	v_mfma_f32_16x16x32_bf16 v[10:13], v[164:167], v[216:219], v[10:13]
	v_mfma_f32_16x16x32_bf16 v[2:5], v[172:175], v[216:219], v[2:5]
	v_mfma_f32_16x16x32_bf16 v[58:61], v[168:171], v[196:199], v[58:61]
	v_mfma_f32_16x16x32_bf16 v[50:53], v[176:179], v[196:199], v[50:53]
	v_mfma_f32_16x16x32_bf16 v[42:45], v[168:171], v[204:207], v[42:45]
	v_mfma_f32_16x16x32_bf16 v[34:37], v[176:179], v[204:207], v[34:37]
	v_mfma_f32_16x16x32_bf16 v[26:29], v[168:171], v[212:215], v[26:29]
	v_mfma_f32_16x16x32_bf16 v[18:21], v[176:179], v[212:215], v[18:21]
	v_mfma_f32_16x16x32_bf16 v[10:13], v[168:171], v[220:223], v[10:13]
	v_mfma_f32_16x16x32_bf16 v[2:5], v[176:179], v[220:223], v[2:5]
	s_setprio 0
	s_barrier
	s_add_i32 s81, s81, 2
	s_add_u32 s22, s22, 0x10000
	s_addc_u32 s23, s23, 0
	s_add_u32 s72, s72, 0x10000
	s_addc_u32 s73, s73, 0
	s_cmp_gt_u32 s81, 29
	s_cbranch_scc0 .LBB0_216
	s_and_b64 vcc, exec, s[10:11]
	s_cbranch_vccz .LBB0_219
	s_barrier
.LBB0_219:
	v_mov_b32_e32 v184, 0xbfb8aa3b
	v_mov_b32_e32 v185, 0xbfb8aa3b
	v_mov_b32_e32 v188, 1.0
	v_mov_b32_e32 v189, 1.0
	v_pk_mul_f32 v[190:191], v[126:127], v[184:185]
	v_pk_mul_f32 v[192:193], v[128:129], v[184:185]
	v_pk_mul_f32 v[224:225], v[118:119], v[184:185]
	v_pk_mul_f32 v[226:227], v[120:121], v[184:185]
	v_exp_f32_e32 v190, v190
	v_exp_f32_e32 v191, v191
	v_exp_f32_e32 v192, v192
	v_exp_f32_e32 v193, v193
	v_exp_f32_e32 v224, v224
	v_exp_f32_e32 v225, v225
	v_exp_f32_e32 v226, v226
	v_exp_f32_e32 v227, v227
	v_pk_add_f32 v[190:191], v[190:191], v[188:189]
	v_pk_add_f32 v[192:193], v[192:193], v[188:189]
	v_pk_add_f32 v[224:225], v[224:225], v[188:189]
	v_pk_add_f32 v[226:227], v[226:227], v[188:189]
	v_rcp_f32_e32 v190, v190
	v_rcp_f32_e32 v191, v191
	v_rcp_f32_e32 v192, v192
	v_rcp_f32_e32 v193, v193
	v_rcp_f32_e32 v224, v224
	v_rcp_f32_e32 v225, v225
	v_rcp_f32_e32 v226, v226
	v_rcp_f32_e32 v227, v227
	v_pk_mul_f32 v[126:127], v[126:127], v[190:191]
	v_pk_mul_f32 v[128:129], v[128:129], v[192:193]
	v_pk_mul_f32 v[118:119], v[118:119], v[224:225]
	v_pk_mul_f32 v[120:121], v[120:121], v[226:227]
	v_pk_mul_f32 v[126:127], v[126:127], v[122:123]
	v_pk_mul_f32 v[128:129], v[128:129], v[124:125]
	v_pk_mul_f32 v[118:119], v[118:119], v[114:115]
	v_pk_mul_f32 v[120:121], v[120:121], v[116:117]
	v_cvt_pk_bf16_f32 v114, v126, v127
	v_cvt_pk_bf16_f32 v115, v128, v129
	v_cvt_pk_bf16_f32 v116, v118, v119
	v_cvt_pk_bf16_f32 v117, v120, v121
	s_lshl_b32 s1, s1, 1
	s_mulk_i32 s0, 0x58
	s_or_b32 s1, s1, s56
	s_add_i32 s0, s1, s0
	v_mov_b32_e32 v142, v144
	s_ashr_i32 s1, s0, 31
	s_lshl_b64 s[0:1], s[0:1], 15
	v_ashrrev_i32_e32 v143, 31, v142
	v_lshl_add_u64 v[142:143], v[142:143], 0, s[8:9]
	s_add_u32 s0, s47, s0
	v_lshlrev_b64 v[142:143], 7, v[142:143]
	s_addc_u32 s1, s50, s1
	v_lshl_add_u64 v[142:143], s[0:1], 0, v[142:143]
	v_lshl_add_u64 v[142:143], v[142:143], 0, s[16:17]
	v_lshl_add_u64 v[142:143], v[142:143], 0, v[186:187]
	s_movk_i32 s0, 0x5000
	global_store_dwordx4 v[142:143], v[114:117], off
	v_pk_mul_f32 v[190:191], v[110:111], v[184:185]
	v_pk_mul_f32 v[192:193], v[112:113], v[184:185]
	v_pk_mul_f32 v[224:225], v[102:103], v[184:185]
	v_pk_mul_f32 v[226:227], v[104:105], v[184:185]
	v_exp_f32_e32 v190, v190
	v_exp_f32_e32 v191, v191
	v_exp_f32_e32 v192, v192
	v_exp_f32_e32 v193, v193
	v_exp_f32_e32 v224, v224
	v_exp_f32_e32 v225, v225
	v_exp_f32_e32 v226, v226
	v_exp_f32_e32 v227, v227
	v_pk_add_f32 v[190:191], v[190:191], v[188:189]
	v_pk_add_f32 v[192:193], v[192:193], v[188:189]
	v_pk_add_f32 v[224:225], v[224:225], v[188:189]
	v_pk_add_f32 v[226:227], v[226:227], v[188:189]
	v_rcp_f32_e32 v190, v190
	v_rcp_f32_e32 v191, v191
	v_rcp_f32_e32 v192, v192
	v_rcp_f32_e32 v193, v193
	v_rcp_f32_e32 v224, v224
	v_rcp_f32_e32 v225, v225
	v_rcp_f32_e32 v226, v226
	v_rcp_f32_e32 v227, v227
	v_pk_mul_f32 v[110:111], v[110:111], v[190:191]
	v_pk_mul_f32 v[112:113], v[112:113], v[192:193]
	v_pk_mul_f32 v[102:103], v[102:103], v[224:225]
	v_pk_mul_f32 v[104:105], v[104:105], v[226:227]
	v_pk_mul_f32 v[110:111], v[110:111], v[106:107]
	v_pk_mul_f32 v[112:113], v[112:113], v[108:109]
; __device__ __forceinline__ float fast_sigmoid(float x) { return __builtin_amdgcn_rcpf(1.0f + __builtin_amdgcn_exp2f(-1.4426950408889634f * x)); }
; __device__ __forceinline__ u32x4 pack8(const f32x4 v0, const f32x4 v1) { u32x4 w; w.x = cvt_pk_bf16(v0[0], v0[1]); w.y = cvt_pk_bf16(v0[2], v0[3]); w.z = cvt_pk_bf16(v1[0], v1[1]); w.w = cvt_pk_bf16(v1[2], v1[3]); return w; }
;     __device__ __forceinline__ void operator()(const f32x4 (&acc)[2][2][4][2], const Unit& u, int wr, int wc, int fr_, int fq) const {
;     ...
;                 for (int j = 0; j < 4; ++j) { const float g0 = acc[ai][0][m][0][j], g1 = acc[ai][0][m][1][j];
;                     v0[j] = g0 * fast_sigmoid(g0) * acc[ai][1][m][0][j]; v1[j] = g1 * fast_sigmoid(g1) * acc[ai][1][m][1][j]; }
;                 *(u32x4*)(Hblk + (size_t)(ai * HALF + m * 16) * BK) = pack8(v0, v1); }
	v_pk_mul_f32 v[102:103], v[102:103], v[98:99]
	v_pk_mul_f32 v[104:105], v[104:105], v[100:101]
	v_cvt_pk_bf16_f32 v98, v110, v111
	v_cvt_pk_bf16_f32 v99, v112, v113
	v_cvt_pk_bf16_f32 v100, v102, v103
	v_cvt_pk_bf16_f32 v101, v104, v105
	global_store_dwordx4 v[142:143], v[98:101], off offset:2048
	v_pk_mul_f32 v[190:191], v[94:95], v[184:185]
	v_pk_mul_f32 v[192:193], v[96:97], v[184:185]
	v_pk_mul_f32 v[224:225], v[86:87], v[184:185]
	v_pk_mul_f32 v[226:227], v[88:89], v[184:185]
	v_exp_f32_e32 v190, v190
	v_exp_f32_e32 v191, v191
	v_exp_f32_e32 v192, v192
	v_exp_f32_e32 v193, v193
	v_exp_f32_e32 v224, v224
	v_exp_f32_e32 v225, v225
	v_exp_f32_e32 v226, v226
	v_exp_f32_e32 v227, v227
	v_pk_add_f32 v[190:191], v[190:191], v[188:189]
	v_pk_add_f32 v[192:193], v[192:193], v[188:189]
	v_pk_add_f32 v[224:225], v[224:225], v[188:189]
	v_pk_add_f32 v[226:227], v[226:227], v[188:189]
	v_rcp_f32_e32 v190, v190
	v_rcp_f32_e32 v191, v191
	v_rcp_f32_e32 v192, v192
	v_rcp_f32_e32 v193, v193
	v_rcp_f32_e32 v224, v224
	v_rcp_f32_e32 v225, v225
	v_rcp_f32_e32 v226, v226
	v_rcp_f32_e32 v227, v227
	v_pk_mul_f32 v[94:95], v[94:95], v[190:191]
	v_pk_mul_f32 v[96:97], v[96:97], v[192:193]
	v_pk_mul_f32 v[86:87], v[86:87], v[224:225]
	v_pk_mul_f32 v[88:89], v[88:89], v[226:227]
	v_pk_mul_f32 v[94:95], v[94:95], v[90:91]
	v_pk_mul_f32 v[96:97], v[96:97], v[92:93]
	v_pk_mul_f32 v[86:87], v[86:87], v[82:83]
	v_pk_mul_f32 v[88:89], v[88:89], v[84:85]
	v_cvt_pk_bf16_f32 v82, v94, v95
	v_cvt_pk_bf16_f32 v83, v96, v97
	v_cvt_pk_bf16_f32 v84, v86, v87
	v_cvt_pk_bf16_f32 v85, v88, v89
	v_add_co_u32_e32 v86, vcc, s67, v142
	s_nop 1
	v_addc_co_u32_e32 v87, vcc, 0, v143, vcc
	global_store_dwordx4 v[86:87], v[82:85], off
	v_pk_mul_f32 v[190:191], v[78:79], v[184:185]
	v_pk_mul_f32 v[192:193], v[80:81], v[184:185]
	v_pk_mul_f32 v[224:225], v[70:71], v[184:185]
	v_pk_mul_f32 v[226:227], v[72:73], v[184:185]
	v_exp_f32_e32 v190, v190
	v_exp_f32_e32 v191, v191
	v_exp_f32_e32 v192, v192
	v_exp_f32_e32 v193, v193
	v_exp_f32_e32 v224, v224
	v_exp_f32_e32 v225, v225
	v_exp_f32_e32 v226, v226
	v_exp_f32_e32 v227, v227
	v_pk_add_f32 v[190:191], v[190:191], v[188:189]
	v_pk_add_f32 v[192:193], v[192:193], v[188:189]
	v_pk_add_f32 v[224:225], v[224:225], v[188:189]
	v_pk_add_f32 v[226:227], v[226:227], v[188:189]
	v_rcp_f32_e32 v190, v190
	v_rcp_f32_e32 v191, v191
	v_rcp_f32_e32 v192, v192
	v_rcp_f32_e32 v193, v193
	v_rcp_f32_e32 v224, v224
	v_rcp_f32_e32 v225, v225
	v_rcp_f32_e32 v226, v226
	v_rcp_f32_e32 v227, v227
	v_pk_mul_f32 v[78:79], v[78:79], v[190:191]
	v_pk_mul_f32 v[80:81], v[80:81], v[192:193]
	v_pk_mul_f32 v[70:71], v[70:71], v[224:225]
	v_pk_mul_f32 v[72:73], v[72:73], v[226:227]
	v_pk_mul_f32 v[78:79], v[78:79], v[74:75]
	v_pk_mul_f32 v[80:81], v[80:81], v[76:77]
	v_pk_mul_f32 v[70:71], v[70:71], v[66:67]
	v_pk_mul_f32 v[72:73], v[72:73], v[68:69]
	v_cvt_pk_bf16_f32 v66, v78, v79
	v_cvt_pk_bf16_f32 v67, v80, v81
	v_cvt_pk_bf16_f32 v68, v70, v71
	v_cvt_pk_bf16_f32 v69, v72, v73
	global_store_dwordx4 v[86:87], v[66:69], off offset:2048
	v_pk_mul_f32 v[190:191], v[62:63], v[184:185]
	v_pk_mul_f32 v[192:193], v[64:65], v[184:185]
	v_pk_mul_f32 v[224:225], v[54:55], v[184:185]
	v_pk_mul_f32 v[226:227], v[56:57], v[184:185]
	v_exp_f32_e32 v190, v190
	v_exp_f32_e32 v191, v191
	v_exp_f32_e32 v192, v192
	v_exp_f32_e32 v193, v193
	v_exp_f32_e32 v224, v224
	v_exp_f32_e32 v225, v225
	v_exp_f32_e32 v226, v226
	v_exp_f32_e32 v227, v227
	v_pk_add_f32 v[190:191], v[190:191], v[188:189]
	v_pk_add_f32 v[192:193], v[192:193], v[188:189]
	v_pk_add_f32 v[224:225], v[224:225], v[188:189]
	v_pk_add_f32 v[226:227], v[226:227], v[188:189]
	v_rcp_f32_e32 v190, v190
	v_rcp_f32_e32 v191, v191
	v_rcp_f32_e32 v192, v192
	v_rcp_f32_e32 v193, v193
	v_rcp_f32_e32 v224, v224
	v_rcp_f32_e32 v225, v225
	v_rcp_f32_e32 v226, v226
	v_rcp_f32_e32 v227, v227
	v_pk_mul_f32 v[62:63], v[62:63], v[190:191]
	v_pk_mul_f32 v[64:65], v[64:65], v[192:193]
	v_pk_mul_f32 v[54:55], v[54:55], v[224:225]
	v_pk_mul_f32 v[56:57], v[56:57], v[226:227]
	v_pk_mul_f32 v[62:63], v[62:63], v[58:59]
	v_pk_mul_f32 v[64:65], v[64:65], v[60:61]
	v_pk_mul_f32 v[54:55], v[54:55], v[50:51]
	v_pk_mul_f32 v[56:57], v[56:57], v[52:53]
	v_cvt_pk_bf16_f32 v52, v62, v63
	v_cvt_pk_bf16_f32 v53, v64, v65
	v_cvt_pk_bf16_f32 v54, v54, v55
	v_cvt_pk_bf16_f32 v55, v56, v57
; __device__ __forceinline__ float fast_sigmoid(float x) { return __builtin_amdgcn_rcpf(1.0f + __builtin_amdgcn_exp2f(-1.4426950408889634f * x)); }
; __device__ __forceinline__ u32x4 pack8(const f32x4 v0, const f32x4 v1) { u32x4 w; w.x = cvt_pk_bf16(v0[0], v0[1]); w.y = cvt_pk_bf16(v0[2], v0[3]); w.z = cvt_pk_bf16(v1[0], v1[1]); w.w = cvt_pk_bf16(v1[2], v1[3]); return w; }
; #define PG8_BAR __builtin_amdgcn_s_barrier()
;     __device__ __forceinline__ void operator()(const f32x4 (&acc)[2][2][4][2], const Unit& u, int wr, int wc, int fr_, int fq) const {
;     ...
;                 for (int j = 0; j < 4; ++j) { const float g0 = acc[ai][0][m][0][j], g1 = acc[ai][0][m][1][j];
;                     v0[j] = g0 * fast_sigmoid(g0) * acc[ai][1][m][0][j]; v1[j] = g1 * fast_sigmoid(g1) * acc[ai][1][m][1][j]; }
;                 *(u32x4*)(Hblk + (size_t)(ai * HALF + m * 16) * BK) = pack8(v0, v1); }
; template <class Epi, class Sched, bool ALIGN_EPI = false, bool SP2 = false, bool ABLK = false, bool BBLK = false>
; __device__ __forceinline__ void gemm_phase(PG8_LAS unsigned char* lds, const Gemm g, const Sched& S, const Epi& E) {
;     ...
;         if (!has_next) break;
; #pragma unroll
;         for (int a = 0; a < 2; ++a)
; #pragma unroll
;             for (int b = 0; b < 2; ++b)
; #pragma unroll
;                 for (int m = 0; m < 4; ++m)
; #pragma unroll
;                     for (int n = 0; n < 2; ++n) acc[a][b][m][n] = (f32x4){0.f, 0.f, 0.f, 0.f};
;         cur = nxt; cA = nA; cB = nB; ++ui;
;         if constexpr (ALIGN_EPI) { if (wr == 1) PG8_BAR; }
	v_add_co_u32_e32 v56, vcc, s87, v142
	s_nop 1
	v_addc_co_u32_e32 v57, vcc, 0, v143, vcc
	v_add_co_u32_e32 v50, vcc, s0, v142
	s_nop 1
	s_mov_b64 s[0:1], -1
	v_addc_co_u32_e32 v51, vcc, 0, v143, vcc
	global_store_dwordx4 v[50:51], v[52:55], off offset:-4096
	v_pk_mul_f32 v[190:191], v[46:47], v[184:185]
	v_pk_mul_f32 v[192:193], v[48:49], v[184:185]
	v_pk_mul_f32 v[224:225], v[38:39], v[184:185]
	v_pk_mul_f32 v[226:227], v[40:41], v[184:185]
	v_exp_f32_e32 v190, v190
	v_exp_f32_e32 v191, v191
	v_exp_f32_e32 v192, v192
	v_exp_f32_e32 v193, v193
	v_exp_f32_e32 v224, v224
	v_exp_f32_e32 v225, v225
	v_exp_f32_e32 v226, v226
	v_exp_f32_e32 v227, v227
	v_pk_add_f32 v[190:191], v[190:191], v[188:189]
	v_pk_add_f32 v[192:193], v[192:193], v[188:189]
	v_pk_add_f32 v[224:225], v[224:225], v[188:189]
	v_pk_add_f32 v[226:227], v[226:227], v[188:189]
	v_rcp_f32_e32 v190, v190
	v_rcp_f32_e32 v191, v191
	v_rcp_f32_e32 v192, v192
	v_rcp_f32_e32 v193, v193
	v_rcp_f32_e32 v224, v224
	v_rcp_f32_e32 v225, v225
	v_rcp_f32_e32 v226, v226
	v_rcp_f32_e32 v227, v227
	v_pk_mul_f32 v[46:47], v[46:47], v[190:191]
	v_pk_mul_f32 v[48:49], v[48:49], v[192:193]
	v_pk_mul_f32 v[38:39], v[38:39], v[224:225]
	v_pk_mul_f32 v[40:41], v[40:41], v[226:227]
	v_pk_mul_f32 v[46:47], v[46:47], v[42:43]
	v_pk_mul_f32 v[48:49], v[48:49], v[44:45]
	v_pk_mul_f32 v[38:39], v[38:39], v[34:35]
	v_pk_mul_f32 v[40:41], v[40:41], v[36:37]
	v_cvt_pk_bf16_f32 v34, v46, v47
	v_cvt_pk_bf16_f32 v35, v48, v49
	v_cvt_pk_bf16_f32 v36, v38, v39
	v_cvt_pk_bf16_f32 v37, v40, v41
	s_andn2_b64 vcc, exec, s[4:5]
	global_store_dwordx4 v[56:57], v[34:37], off offset:2048
	v_pk_mul_f32 v[190:191], v[30:31], v[184:185]
	v_pk_mul_f32 v[192:193], v[32:33], v[184:185]
	v_pk_mul_f32 v[224:225], v[22:23], v[184:185]
	v_pk_mul_f32 v[226:227], v[24:25], v[184:185]
	v_exp_f32_e32 v190, v190
	v_exp_f32_e32 v191, v191
	v_exp_f32_e32 v192, v192
	v_exp_f32_e32 v193, v193
	v_exp_f32_e32 v224, v224
	v_exp_f32_e32 v225, v225
	v_exp_f32_e32 v226, v226
	v_exp_f32_e32 v227, v227
	v_pk_add_f32 v[190:191], v[190:191], v[188:189]
	v_pk_add_f32 v[192:193], v[192:193], v[188:189]
	v_pk_add_f32 v[224:225], v[224:225], v[188:189]
	v_pk_add_f32 v[226:227], v[226:227], v[188:189]
	v_rcp_f32_e32 v190, v190
	v_rcp_f32_e32 v191, v191
	v_rcp_f32_e32 v192, v192
	v_rcp_f32_e32 v193, v193
	v_rcp_f32_e32 v224, v224
	v_rcp_f32_e32 v225, v225
	v_rcp_f32_e32 v226, v226
	v_rcp_f32_e32 v227, v227
	v_pk_mul_f32 v[30:31], v[30:31], v[190:191]
	v_pk_mul_f32 v[32:33], v[32:33], v[192:193]
	v_pk_mul_f32 v[22:23], v[22:23], v[224:225]
	v_pk_mul_f32 v[24:25], v[24:25], v[226:227]
	v_pk_mul_f32 v[30:31], v[30:31], v[26:27]
	v_pk_mul_f32 v[32:33], v[32:33], v[28:29]
	v_pk_mul_f32 v[22:23], v[22:23], v[18:19]
	v_pk_mul_f32 v[24:25], v[24:25], v[20:21]
	v_cvt_pk_bf16_f32 v18, v30, v31
	v_cvt_pk_bf16_f32 v19, v32, v33
	v_cvt_pk_bf16_f32 v20, v22, v23
	v_cvt_pk_bf16_f32 v21, v24, v25
	global_store_dwordx4 v[50:51], v[18:21], off
	v_pk_mul_f32 v[190:191], v[14:15], v[184:185]
	v_pk_mul_f32 v[192:193], v[16:17], v[184:185]
	v_pk_mul_f32 v[224:225], v[6:7], v[184:185]
	v_pk_mul_f32 v[226:227], v[8:9], v[184:185]
	v_exp_f32_e32 v190, v190
	v_exp_f32_e32 v191, v191
	v_exp_f32_e32 v192, v192
	v_exp_f32_e32 v193, v193
	v_exp_f32_e32 v224, v224
	v_exp_f32_e32 v225, v225
	v_exp_f32_e32 v226, v226
	v_exp_f32_e32 v227, v227
	v_pk_add_f32 v[190:191], v[190:191], v[188:189]
	v_pk_add_f32 v[192:193], v[192:193], v[188:189]
	v_pk_add_f32 v[224:225], v[224:225], v[188:189]
	v_pk_add_f32 v[226:227], v[226:227], v[188:189]
	v_rcp_f32_e32 v190, v190
	v_rcp_f32_e32 v191, v191
	v_rcp_f32_e32 v192, v192
	v_rcp_f32_e32 v193, v193
	v_rcp_f32_e32 v224, v224
	v_rcp_f32_e32 v225, v225
	v_rcp_f32_e32 v226, v226
	v_rcp_f32_e32 v227, v227
	v_pk_mul_f32 v[14:15], v[14:15], v[190:191]
	v_pk_mul_f32 v[16:17], v[16:17], v[192:193]
	v_pk_mul_f32 v[6:7], v[6:7], v[224:225]
	v_pk_mul_f32 v[8:9], v[8:9], v[226:227]
	v_pk_mul_f32 v[14:15], v[14:15], v[10:11]
	v_pk_mul_f32 v[16:17], v[16:17], v[12:13]
	v_pk_mul_f32 v[6:7], v[6:7], v[2:3]
	v_pk_mul_f32 v[8:9], v[8:9], v[4:5]
	v_cvt_pk_bf16_f32 v2, v14, v15
	v_cvt_pk_bf16_f32 v3, v16, v17
	v_cvt_pk_bf16_f32 v4, v6, v7
	v_cvt_pk_bf16_f32 v5, v8, v9
	global_store_dwordx4 v[50:51], v[2:5], off offset:2048
	s_cbranch_vccnz .LBB0_212
	s_andn2_b64 vcc, exec, s[6:7]
	s_cbranch_vccnz .LBB0_211
	s_branch .LBB0_211

; #define PG8_WAIT_V(n) asm volatile("s_waitcnt vmcnt(" #n ")" ::: "memory")
; template <class Epi, class Sched, bool ALIGN_EPI = false, bool SP2 = false, bool ABLK = false, bool BBLK = false>
; __device__ __forceinline__ void gemm_phase(PG8_LAS unsigned char* lds, const Gemm g, const Sched& S, const Epi& E) {
;     ...
;     const int tid = tid_, wid = __builtin_amdgcn_readfirstlane(tid >> 6), lane = tid & 63, wr = wid >> 2, wc = wid & 3, fr = lane & 15, fq = lane >> 4;
;     const int K = g.K, nt = K / BK, LDA = g.lda ? g.lda : K, LDB = g.ldb ? g.ldb : K;
;     unsigned voffA[2], voffB[2];
; #pragma unroll
;     for (int i = 0; i < 2; ++i) { int R, C; stage_rc(tid * 16 + i * 8192, R, C); const int Rb = Epi::PERM ? ((R & ~31) + perm32(R & 31)) : R;
;         voffA[i] = ABLK ? (unsigned)(R * BK + C) * 2u : (unsigned)(R * LDA + C) * 2u; voffB[i] = BBLK ? (unsigned)(Rb * BK + C) * 2u : (unsigned)(Rb * LDB + C) * 2u; }
;     const size_t kstep = (size_t)(BK * 2);
;     const size_t hstepa = (size_t)HALF * LDA * 2, hstepb = (size_t)HALF * LDB * 2;
;     const size_t kstepA = ABLK ? (size_t)BM * BK * 2 : kstep, hstepA = ABLK ? (size_t)HALF * BK * 2 : hstepa, tstepA = ABLK ? (size_t)nt * BM * BK * 2 : 2 * hstepa;
;     const size_t kstepB = BBLK ? (size_t)BM * BK * 2 : kstep, hstepB = BBLK ? (size_t)HALF * BK * 2 : hstepb, tstepB = BBLK ? (size_t)nt * BM * BK * 2 : 2 * hstepb;
;     const unsigned ldsw = (unsigned)wid * 1024u;
;     const int aoff = lds_byte(wr * 64 + fr, fq * 8), boff = lds_byte(wc * 32 + fr, fq * 8);
;     ...
;     Unit cur, nxt; int ui = 0;
;     if (!S.next(0, cur)) return;
;     f32x4 acc[2][2][4][2];
; #pragma unroll
;     for (int a = 0; a < 2; ++a)
; #pragma unroll
;         for (int b = 0; b < 2; ++b)
; #pragma unroll
;             for (int m = 0; m < 4; ++m)
; #pragma unroll
;                 for (int n = 0; n < 2; ++n) acc[a][b][m][n] = (f32x4){0.f, 0.f, 0.f, 0.f};
;     bf16x8 At[4][2], B0[2][2], B1[2][2];
;     const char* cA = (const char*)g.A + (size_t)cur.pm * tstepA; const char* cB = (const char*)g.Bt + (size_t)cur.pn * tstepB;
;     S.a_ready(cur);
;     if constexpr (SP2) {
;         PG8_STAGE(PG8_SB(0, 0), cB, voffB); PG8_STAGE(PG8_SB(0, 1), cB + hstepB, voffB); PG8_STAGE(PG8_SA(0, 0), cA, voffA); PG8_STAGE(PG8_SA(0, 1), cA + hstepA, voffA);
;         if (wr == 1) PG8_BAR;
;         PG8_WAIT_V(2); PG8_BAR;
.LBB0_289:
	s_andn2_b64 vcc, exec, s[0:1]
	s_cbranch_vccnz .LBB0_344
	v_bfe_i32 v4, v2, 27, 1
	v_lshlrev_b32_e32 v6, 4, v2
	v_lshrrev_b32_e32 v4, 22, v4
	v_ashrrev_i32_e32 v3, 31, v2
	v_add_u32_e32 v4, v6, v4
	v_lshrrev_b32_e32 v3, 26, v3
	v_and_b32_e32 v4, 0xfffffc00, v4
	v_add_u32_e32 v3, v2, v3
	v_sub_u32_e32 v4, v6, v4
	v_ashrrev_i32_e32 v3, 6, v3
	v_lshrrev_b32_e32 v5, 4, v4
	v_bitop3_b32 v5, v5, v4, 32 bitop3:0x6c
	v_lshlrev_b32_e32 v4, 3, v3
	v_and_b32_e32 v7, -16, v4
	v_ashrrev_i32_e32 v4, 31, v5
	v_lshrrev_b32_e32 v4, 26, v4
	v_add_u32_e32 v8, v5, v4
	v_ashrrev_i32_e32 v4, 6, v8
	v_and_b32_e32 v8, 0xc0, v8
	v_sub_u32_e32 v5, v5, v8
	v_lshlrev_b32_e32 v9, 5, v3
	v_ashrrev_i16_sdwa v5, v232, sext(v5) dst_sel:DWORD dst_unused:UNUSED_PAD src0_sel:DWORD src1_sel:BYTE_0
	v_and_b32_e32 v9, 32, v9
	v_bfe_i32 v5, v5, 0, 16
	v_add_u32_e32 v7, v4, v7
	v_and_b32_e32 v11, 3, v4
	s_mov_b32 s0, 0x1ffffe0
	v_add_lshl_u32 v9, v9, v5, 1
	v_lshlrev_b32_e32 v8, 1, v7
	v_lshrrev_b32_e32 v10, 2, v7
	v_and_or_b32 v11, v7, s0, v11
	v_lshl_add_u32 v178, v7, 7, v9
	v_add_u32_e32 v7, 0x2000, v6
	v_ashrrev_i32_e32 v6, 31, v7
	v_lshrrev_b32_e32 v6, 22, v6
	v_and_b32_e32 v8, 24, v8
	v_and_b32_e32 v10, 4, v10
	v_add_u32_e32 v6, v7, v6
	v_or3_b32 v8, v11, v10, v8
	v_ashrrev_i32_e32 v6, 10, v6
	v_lshl_add_u32 v186, v8, 7, v9
	v_mul_i32_i24_e32 v8, 0x400, v6
	v_sub_u32_e32 v7, v7, v8
	v_lshrrev_b32_e32 v8, 4, v7
	v_bitop3_b32 v8, v8, v7, 32 bitop3:0x6c
	v_lshlrev_b32_e32 v7, 3, v6
	v_and_b32_e32 v9, -16, v7
	v_ashrrev_i32_e32 v7, 31, v8
	v_lshrrev_b32_e32 v7, 26, v7
	v_add_u32_e32 v10, v8, v7
	s_ashr_i32 s9, s8, 6
	v_ashrrev_i32_e32 v7, 6, v10
	v_add_u32_e32 v9, v7, v9
	v_and_b32_e32 v10, 0xc0, v10
	v_and_b32_e32 v13, 3, v7
	s_ashr_i32 s16, s8, 8
	s_lshl_b32 s2, s9, 10
	s_mul_i32 s1, s30, 0x2c0000
	v_readlane_b32 s3, v254, 38
	v_sub_u32_e32 v8, v8, v10
	v_and_or_b32 v13, v9, s0, v13
	s_mul_hi_i32 s0, s30, 0x2c0000
	s_add_u32 s34, s3, s1
	v_readlane_b32 s1, v254, 39
	v_lshlrev_b32_e32 v11, 5, v6
	v_ashrrev_i16_sdwa v8, v232, sext(v8) dst_sel:DWORD dst_unused:UNUSED_PAD src0_sel:DWORD src1_sel:BYTE_0
	v_lshlrev_b32_e32 v10, 1, v9
	v_lshrrev_b32_e32 v12, 2, v9
	s_addc_u32 s35, s1, s0
	s_add_i32 s3, s2, 0
	v_and_b32_e32 v11, 32, v11
	v_bfe_i32 v8, v8, 0, 16
	v_and_b32_e32 v10, 24, v10
	v_and_b32_e32 v12, 4, v12
	s_add_i32 m0, s3, 0x10000
	v_or3_b32 v10, v13, v12, v10
	v_add_lshl_u32 v11, v11, v8, 1
	global_load_lds_dwordx4 v186, s[34:35]
	s_add_i32 m0, s3, 0x12000
	v_lshl_add_u32 v182, v10, 7, v11
	s_add_u32 s0, s34, 0x4000
	global_load_lds_dwordx4 v182, s[34:35]
	s_addc_u32 s1, s35, 0
	s_add_i32 m0, s3, 0x14000
	s_mul_i32 s7, s28, 0x2c0000
	global_load_lds_dwordx4 v186, s[0:1]
	s_add_i32 m0, s3, 0x16000
	s_mul_hi_i32 s6, s28, 0x2c0000
	global_load_lds_dwordx4 v182, s[0:1]
	v_readlane_b32 s0, v254, 32
	s_add_u32 s0, s0, s7
	v_readlane_b32 s1, v254, 36
	s_addc_u32 s1, s1, s6
	s_add_i32 s42, s3, 0x2000
	s_mov_b32 m0, s3
	s_add_u32 s6, s0, 0x4000
	v_lshl_add_u32 v180, v9, 7, v11
	global_load_lds_dwordx4 v178, s[0:1]
	s_mov_b32 m0, s42
	s_addc_u32 s7, s1, 0
	s_add_i32 s43, s3, 0x4000
	global_load_lds_dwordx4 v180, s[0:1]
	s_mov_b32 m0, s43
	s_add_i32 s53, s3, 0x6000
	global_load_lds_dwordx4 v178, s[6:7]
	s_mov_b32 m0, s53
	s_cmp_eq_u32 s16, 1
	global_load_lds_dwordx4 v180, s[6:7]
	s_load_dwordx2 s[6:7], s[4:5], 0x50
	s_cselect_b64 s[4:5], -1, 0
	s_mov_b32 s80, 0x30000
	s_mov_b32 s75, 0x10000
	s_mov_b32 s46, 0x20000
	v_writelane_b32 v254, s4, 46
	s_cmp_lg_u32 s16, 1
	s_nop 0
	v_writelane_b32 v254, s5, 47
	s_cbranch_scc1 .LBB0_292
.LBB0_292:
	v_writelane_b32 v254, s72, 52
	s_lshl_b64 s[4:5], s[72:73], 2
	v_mov_b32_e32 v183, v187
	v_writelane_b32 v254, s73, 53
	s_waitcnt vmcnt(2)
	s_barrier
	v_readlane_b32 s10, v254, 26
	v_readlane_b32 s11, v254, 27
	s_add_u32 s10, s10, s4
	s_addc_u32 s11, s11, s5
	s_add_u32 s12, s82, 0x1500000
	s_addc_u32 s13, s68, 0
	s_add_u32 s56, s82, 0x232000
	s_addc_u32 s60, s68, 0
	s_waitcnt lgkmcnt(0)
	s_add_u32 s14, s6, 0x2000
	s_addc_u32 s15, s7, 0
	s_add_u32 s61, s82, 0xf600000
	s_addc_u32 s65, s68, 0
	s_mov_b32 s4, s68
	s_add_u32 s68, s82, 0xf400000
	s_addc_u32 s72, s4, 0
	s_add_u32 s73, s82, 0x16c00
	s_addc_u32 s81, s4, 0
	s_and_b32 s6, s9, 3
	s_lshl_b32 s83, s16, 6
	s_lshl_b32 s7, s16, 13
	s_lshl_b32 s84, s6, 5
	s_lshl_b32 s18, s6, 12
	v_writelane_b32 v254, s4, 54
	s_add_u32 s4, s34, 0x8000
	s_addc_u32 s5, s35, 0
	s_add_i32 m0, s3, 0x18000
	v_lshl_add_u64 v[10:11], s[4:5], 0, v[186:187]
	global_load_lds_dwordx4 v[10:11], off
	s_add_i32 m0, s3, 0x1a000
	v_lshl_add_u64 v[10:11], s[4:5], 0, v[182:183]
	s_add_u32 s4, s0, 0x8000
	v_mov_b32_e32 v179, v187
	s_addc_u32 s5, s1, 0
	s_add_i32 s92, s3, 0x8000
	v_mov_b32_e32 v181, v187
	global_load_lds_dwordx4 v[10:11], off
	v_lshl_add_u64 v[10:11], s[4:5], 0, v[178:179]
	s_mov_b32 m0, s92
	s_add_i32 s93, s3, 0xa000
	global_load_lds_dwordx4 v[10:11], off
	v_lshl_add_u64 v[10:11], s[4:5], 0, v[180:181]
	s_add_u32 s4, s34, 0xc000
	s_mov_b32 m0, s93
	s_addc_u32 s5, s35, 0
	global_load_lds_dwordx4 v[10:11], off
	s_add_i32 m0, s3, 0x1c000
	v_lshl_add_u64 v[10:11], s[4:5], 0, v[186:187]
	global_load_lds_dwordx4 v[10:11], off
	v_lshl_add_u64 v[10:11], s[4:5], 0, v[182:183]
	s_add_i32 m0, s3, 0x1e000
	v_bfe_u32 v205, v2, 4, 2
	global_load_lds_dwordx4 v[10:11], off
	v_and_b32_e32 v204, 15, v2
	v_lshlrev_b32_e32 v9, 4, v205
	v_lshlrev_b32_e32 v2, 2, v2
	v_lshl_or_b32 v9, v204, 6, v9
	v_and_b32_e32 v2, 32, v2
	s_cmpk_lt_u32 s8, 0x100
	v_bitop3_b32 v206, v9, s18, v2 bitop3:0xde
	s_cselect_b64 s[18:19], -1, 0
	s_lshl_b32 s4, s16, 2
	s_or_b32 s94, s4, s6
	s_lshl_b32 s95, s94, 5
	s_bfe_u32 s20, s9, 0x10001
	s_and_b32 s5, s84, 32
	s_ashr_i32 s96, s50, 31
	s_ashr_i32 s97, s51, 31
	s_cmpk_lg_i32 s50, 0x100
	s_cselect_b64 s[22:23], -1, 0
	s_and_b32 s4, s51, 7
	v_bitop3_b32 v10, v9, s7, v2 bitop3:0xde
	s_lshl_b32 s4, s4, 2
	v_lshlrev_b32_e32 v2, 10, v3
	v_writelane_b32 v254, s4, 48
	s_bfe_u32 s4, s51, 0x20001
	v_and_b32_e32 v2, 0xfffff800, v2
	s_or_b32 s4, s4, 32
	v_lshl_add_u32 v2, v4, 7, v2
	v_and_b32_e32 v3, 1, v3
	v_writelane_b32 v254, s4, 50
	s_lshl_b32 s4, s51, 4
	v_lshl_or_b32 v2, v3, 6, v2
	s_ashr_i32 s47, s51, 3
	s_and_b32 s4, s4, 16
	v_lshl_add_u32 v184, v5, 1, v2
	v_lshlrev_b32_e32 v2, 10, v6
	v_writelane_b32 v254, s4, 55
	s_and_b32 s4, s47, 3
	v_and_b32_e32 v2, 0xfffff800, v2
	s_waitcnt vmcnt(6)
	v_writelane_b32 v254, s4, 57
	s_lshl_b32 s4, s6, 2
	v_lshl_add_u32 v2, v7, 7, v2
	v_and_b32_e32 v3, 1, v6
	s_add_i32 s4, s4, 0
	v_lshl_or_b32 v2, v3, 6, v2
	s_mov_b32 s21, s17
	s_add_i32 s4, s4, 0x20540
	v_mov_b32_e32 v185, v187
	v_lshl_add_u32 v196, v8, 1, v2
	v_mov_b32_e32 v197, v187
	s_mov_b32 s26, 0
	v_add_u32_e32 v207, 0, v10
	s_lshl_b32 s16, s5, 1
	s_barrier
	s_branch .LBB0_295

; #define PG8_STAGE(bufoff, gbase, voff) do { _Pragma("unroll") for (int _i = 0; _i < 2; ++_i) \
;         __builtin_amdgcn_global_load_lds((const unsigned*)((const char*)(gbase) + (voff)[_i]), (PG8_LAS unsigned*)(lds + (bufoff) + ldsw + _i * 8192), 16, 0, 0); } while (0)
; #define PG8_LDA(dst, b, h) do { _Pragma("unroll") for (int m = 0; m < 4; ++m) _Pragma("unroll") for (int k = 0; k < 2; ++k) dst[m][k] = *(const PG8_LAS bf16x8*)(lds + PG8_SA(b, h) + aoff + m * 2048 + k * 1024); } while (0)
; #define PG8_LDB(dst, b, h) do { _Pragma("unroll") for (int n = 0; n < 2; ++n) _Pragma("unroll") for (int k = 0; k < 2; ++k) dst[n][k] = *(const PG8_LAS bf16x8*)(lds + PG8_SB(b, h) + boff + n * 2048 + k * 1024); } while (0)
; #define PG8_MMA(ai, bj, At, Bt) do { __builtin_amdgcn_s_setprio(1); _Pragma("unroll") for (int m = 0; m < 4; ++m) _Pragma("unroll") for (int n = 0; n < 2; ++n) _Pragma("unroll") for (int k = 0; k < 2; ++k) \
;         acc[ai][bj][m][n] = __builtin_amdgcn_mfma_f32_16x16x32_bf16(Bt[n][k], At[m][k], acc[ai][bj][m][n], 0, 0, 0); __builtin_amdgcn_s_setprio(0); } while (0)
; #define PG8_WAIT_V(n) asm volatile("s_waitcnt vmcnt(" #n ")" ::: "memory")
; template <class Epi, class Sched, bool ALIGN_EPI = false, bool SP2 = false, bool ABLK = false, bool BBLK = false>
; __device__ __forceinline__ void gemm_phase(PG8_LAS unsigned char* lds, const Gemm g, const Sched& S, const Epi& E) {
;     ...
;         for (int t = 0; t < nt; t += 2) {
;             const bool last = (t == nt - 2);
;             const char* a1 = cA + (size_t)(t + 1) * kstepA;
;             const char* a2 = last ? nA : cA + (size_t)(t + 2) * kstepA; const char* b2 = last ? nB : cB + (size_t)(t + 2) * kstepB;
;             const char* a3 = a2 + kstepA; const char* b3 = b2 + kstepB;
;             if (last && has_next) S.a_ready(nxt);
;             if constexpr (SP2) {
;             PG8_LDB(B0, 0, 0); PG8_LDB(B1, 0, 1); PG8_SCHED; PG8_LDA(At, 0, 0); PG8_STAGE(PG8_SA(1, 1), a1 + hstepA, voffA);
;             PG8_WAIT_V(8); PG8_WAIT_L(0); PG8_BAR; PG8_MMA(0, 0, At, B0); PG8_MMA(0, 1, At, B1); PG8_BAR; PG8_SCHED;
;     ...
;         for (int a = 0; a < 2; ++a)
; #pragma unroll
;             for (int b = 0; b < 2; ++b)
; #pragma unroll
;                 for (int m = 0; m < 4; ++m)
; #pragma unroll
;                     for (int n = 0; n < 2; ++n) acc[a][b][m][n] = (f32x4){0.f, 0.f, 0.f, 0.f};
.LBB0_304:
	s_add_u32 s0, s0, 0xc000
	s_addc_u32 s1, s1, 0
	s_add_u32 s29, s34, 0x10000
	v_mov_b32_e32 v2, 0
	s_addc_u32 s31, s35, 0
	s_mov_b32 s33, -2
	v_mov_b32_e32 v3, v2
	v_mov_b32_e32 v4, v2
	v_mov_b32_e32 v5, v2
	v_mov_b32_e32 v14, v2
	v_mov_b32_e32 v15, v2
	v_mov_b32_e32 v16, v2
	v_mov_b32_e32 v17, v2
	v_mov_b32_e32 v58, v2
	v_mov_b32_e32 v59, v2
	v_mov_b32_e32 v60, v2
	v_mov_b32_e32 v61, v2
	v_mov_b32_e32 v62, v2
	v_mov_b32_e32 v63, v2
	v_mov_b32_e32 v64, v2
	v_mov_b32_e32 v65, v2
	v_mov_b32_e32 v98, v2
	v_mov_b32_e32 v99, v2
	v_mov_b32_e32 v100, v2
	v_mov_b32_e32 v101, v2
	v_mov_b32_e32 v102, v2
	v_mov_b32_e32 v103, v2
	v_mov_b32_e32 v104, v2
	v_mov_b32_e32 v105, v2
	v_mov_b32_e32 v118, v2
	v_mov_b32_e32 v119, v2
	v_mov_b32_e32 v120, v2
	v_mov_b32_e32 v121, v2
	v_mov_b32_e32 v114, v2
	v_mov_b32_e32 v115, v2
	v_mov_b32_e32 v116, v2
	v_mov_b32_e32 v117, v2
	v_mov_b32_e32 v34, v2
	v_mov_b32_e32 v35, v2
	v_mov_b32_e32 v36, v2
	v_mov_b32_e32 v37, v2
	v_mov_b32_e32 v38, v2
	v_mov_b32_e32 v39, v2
	v_mov_b32_e32 v40, v2
	v_mov_b32_e32 v41, v2
	v_mov_b32_e32 v90, v2
	v_mov_b32_e32 v91, v2
	v_mov_b32_e32 v92, v2
	v_mov_b32_e32 v93, v2
	v_mov_b32_e32 v94, v2
	v_mov_b32_e32 v95, v2
	v_mov_b32_e32 v96, v2
	v_mov_b32_e32 v97, v2
	v_mov_b32_e32 v126, v2
	v_mov_b32_e32 v127, v2
	v_mov_b32_e32 v128, v2
	v_mov_b32_e32 v129, v2
	v_mov_b32_e32 v122, v2
	v_mov_b32_e32 v123, v2
	v_mov_b32_e32 v124, v2
	v_mov_b32_e32 v125, v2
	v_mov_b32_e32 v110, v2
	v_mov_b32_e32 v111, v2
	v_mov_b32_e32 v112, v2
	v_mov_b32_e32 v113, v2
	v_mov_b32_e32 v106, v2
	v_mov_b32_e32 v107, v2
	v_mov_b32_e32 v108, v2
	v_mov_b32_e32 v109, v2
	v_mov_b32_e32 v86, v2
	v_mov_b32_e32 v87, v2
	v_mov_b32_e32 v88, v2
	v_mov_b32_e32 v89, v2
	v_mov_b32_e32 v82, v2
	v_mov_b32_e32 v83, v2
	v_mov_b32_e32 v84, v2
	v_mov_b32_e32 v85, v2
	v_mov_b32_e32 v70, v2
	v_mov_b32_e32 v71, v2
	v_mov_b32_e32 v72, v2
	v_mov_b32_e32 v73, v2
	v_mov_b32_e32 v66, v2
	v_mov_b32_e32 v67, v2
	v_mov_b32_e32 v68, v2
	v_mov_b32_e32 v69, v2
	v_mov_b32_e32 v46, v2
	v_mov_b32_e32 v47, v2
	v_mov_b32_e32 v48, v2
	v_mov_b32_e32 v49, v2
	v_mov_b32_e32 v42, v2
	v_mov_b32_e32 v43, v2
	v_mov_b32_e32 v44, v2
	v_mov_b32_e32 v45, v2
	v_mov_b32_e32 v18, v2
	v_mov_b32_e32 v19, v2
	v_mov_b32_e32 v20, v2
	v_mov_b32_e32 v21, v2
	v_mov_b32_e32 v26, v2
	v_mov_b32_e32 v27, v2
	v_mov_b32_e32 v28, v2
	v_mov_b32_e32 v29, v2
	v_mov_b32_e32 v78, v2
	v_mov_b32_e32 v79, v2
	v_mov_b32_e32 v80, v2
	v_mov_b32_e32 v81, v2
	v_mov_b32_e32 v74, v2
	v_mov_b32_e32 v75, v2
	v_mov_b32_e32 v76, v2
	v_mov_b32_e32 v77, v2
	v_mov_b32_e32 v54, v2
	v_mov_b32_e32 v55, v2
	v_mov_b32_e32 v56, v2
	v_mov_b32_e32 v57, v2
	v_mov_b32_e32 v50, v2
	v_mov_b32_e32 v51, v2
	v_mov_b32_e32 v52, v2
	v_mov_b32_e32 v53, v2
	v_mov_b32_e32 v6, v2
	v_mov_b32_e32 v7, v2
	v_mov_b32_e32 v8, v2
	v_mov_b32_e32 v9, v2
	v_mov_b32_e32 v10, v2
	v_mov_b32_e32 v11, v2
	v_mov_b32_e32 v12, v2
	v_mov_b32_e32 v13, v2
	v_mov_b32_e32 v22, v2
	v_mov_b32_e32 v23, v2
	v_mov_b32_e32 v24, v2
	v_mov_b32_e32 v25, v2
	v_mov_b32_e32 v30, v2
	v_mov_b32_e32 v31, v2
	v_mov_b32_e32 v32, v2
	v_mov_b32_e32 v33, v2
	s_and_b64 vcc, exec, s[18:19]
	s_cbranch_vccnz .Lrb_f1b0
	s_barrier
.Lrb_f1b0:
.LBB0_305:
	s_add_u32 s8, s0, 0x4000
	s_addc_u32 s9, s1, 0
	s_cmpk_eq_i32 s33, 0x54
	s_cselect_b32 s36, s24, s8
	s_cselect_b32 s37, s25, s9
	s_cselect_b32 s34, s26, s29
	s_cselect_b32 s35, s27, s31
	s_add_u32 s8, s36, 0x8000
	s_addc_u32 s9, s37, 0
	s_add_i32 s40, 0, 0x10000
	s_add_i32 s44, 0, 0x14000
	v_add_u32_e32 v142, s40, v206
	v_add_u32_e32 v158, s44, v206
	ds_read_b128 v[130:133], v142
	ds_read_b128 v[134:137], v142 offset:1024
	ds_read_b128 v[138:141], v142 offset:2048
	ds_read_b128 v[142:145], v142 offset:3072
	ds_read_b128 v[146:149], v158
	ds_read_b128 v[150:153], v158 offset:1024
	ds_read_b128 v[154:157], v158 offset:2048
	ds_read_b128 v[158:161], v158 offset:3072
	v_lshl_add_u64 v[202:203], s[0:1], 0, v[184:185]
	s_add_i32 m0, s3, 0xc000
	ds_read_b128 v[162:165], v207
	ds_read_b128 v[166:169], v207 offset:1024
	ds_read_b128 v[170:173], v207 offset:2048
	ds_read_b128 v[174:177], v207 offset:3072
	ds_read_b128 v[198:201], v207 offset:4096
	ds_read_b128 v[208:211], v207 offset:5120
	ds_read_b128 v[212:215], v207 offset:6144
	ds_read_b128 v[216:219], v207 offset:7168
	global_load_lds_dwordx4 v[202:203], off
	v_lshl_add_u64 v[202:203], s[0:1], 0, v[196:197]
	s_add_i32 m0, s3, 0xe000
	s_nop 0
	global_load_lds_dwordx4 v[202:203], off
	s_waitcnt vmcnt(8)
	s_waitcnt lgkmcnt(0)
	s_barrier
	s_setprio 1
	s_waitcnt lgkmcnt(0)
	v_mfma_f32_16x16x32_bf16 v[30:33], v[130:133], v[162:165], v[30:33]
	v_mfma_f32_16x16x32_bf16 v[22:25], v[138:141], v[162:165], v[22:25]
	v_mfma_f32_16x16x32_bf16 v[10:13], v[130:133], v[170:173], v[10:13]
	v_mfma_f32_16x16x32_bf16 v[6:9], v[138:141], v[170:173], v[6:9]
	v_mfma_f32_16x16x32_bf16 v[50:53], v[130:133], v[198:201], v[50:53]
	v_mfma_f32_16x16x32_bf16 v[54:57], v[138:141], v[198:201], v[54:57]
	v_mfma_f32_16x16x32_bf16 v[74:77], v[130:133], v[212:215], v[74:77]
	v_mfma_f32_16x16x32_bf16 v[78:81], v[138:141], v[212:215], v[78:81]
	v_mfma_f32_16x16x32_bf16 v[30:33], v[134:137], v[166:169], v[30:33]
	v_mfma_f32_16x16x32_bf16 v[22:25], v[142:145], v[166:169], v[22:25]
	v_mfma_f32_16x16x32_bf16 v[10:13], v[134:137], v[174:177], v[10:13]
	v_mfma_f32_16x16x32_bf16 v[6:9], v[142:145], v[174:177], v[6:9]
	v_mfma_f32_16x16x32_bf16 v[50:53], v[134:137], v[208:211], v[50:53]
	v_mfma_f32_16x16x32_bf16 v[54:57], v[142:145], v[208:211], v[54:57]
	v_mfma_f32_16x16x32_bf16 v[74:77], v[134:137], v[216:219], v[74:77]
	v_mfma_f32_16x16x32_bf16 v[78:81], v[142:145], v[216:219], v[78:81]
	s_setprio 0
	s_setprio 1
	v_mfma_f32_16x16x32_bf16 v[26:29], v[146:149], v[162:165], v[26:29]
	v_mfma_f32_16x16x32_bf16 v[18:21], v[154:157], v[162:165], v[18:21]
	v_mfma_f32_16x16x32_bf16 v[42:45], v[146:149], v[170:173], v[42:45]
	v_mfma_f32_16x16x32_bf16 v[46:49], v[154:157], v[170:173], v[46:49]
	v_mfma_f32_16x16x32_bf16 v[66:69], v[146:149], v[198:201], v[66:69]
	v_mfma_f32_16x16x32_bf16 v[70:73], v[154:157], v[198:201], v[70:73]
	v_mfma_f32_16x16x32_bf16 v[82:85], v[146:149], v[212:215], v[82:85]
	v_mfma_f32_16x16x32_bf16 v[86:89], v[154:157], v[212:215], v[86:89]
	v_mfma_f32_16x16x32_bf16 v[26:29], v[150:153], v[166:169], v[26:29]
	v_mfma_f32_16x16x32_bf16 v[18:21], v[158:161], v[166:169], v[18:21]
	v_mfma_f32_16x16x32_bf16 v[42:45], v[150:153], v[174:177], v[42:45]
	v_mfma_f32_16x16x32_bf16 v[46:49], v[158:161], v[174:177], v[46:49]
	v_mfma_f32_16x16x32_bf16 v[66:69], v[150:153], v[208:211], v[66:69]
	v_mfma_f32_16x16x32_bf16 v[70:73], v[158:161], v[208:211], v[70:73]
	v_mfma_f32_16x16x32_bf16 v[82:85], v[150:153], v[216:219], v[82:85]
	v_mfma_f32_16x16x32_bf16 v[86:89], v[158:161], v[216:219], v[86:89]
	s_setprio 0
	s_barrier
; #define PG8_STAGE(bufoff, gbase, voff) do { _Pragma("unroll") for (int _i = 0; _i < 2; ++_i) \
;         __builtin_amdgcn_global_load_lds((const unsigned*)((const char*)(gbase) + (voff)[_i]), (PG8_LAS unsigned*)(lds + (bufoff) + ldsw + _i * 8192), 16, 0, 0); } while (0)
; #define PG8_LDA(dst, b, h) do { _Pragma("unroll") for (int m = 0; m < 4; ++m) _Pragma("unroll") for (int k = 0; k < 2; ++k) dst[m][k] = *(const PG8_LAS bf16x8*)(lds + PG8_SA(b, h) + aoff + m * 2048 + k * 1024); } while (0)
; #define PG8_LDB(dst, b, h) do { _Pragma("unroll") for (int n = 0; n < 2; ++n) _Pragma("unroll") for (int k = 0; k < 2; ++k) dst[n][k] = *(const PG8_LAS bf16x8*)(lds + PG8_SB(b, h) + boff + n * 2048 + k * 1024); } while (0)
; #define PG8_MMA(ai, bj, At, Bt) do { __builtin_amdgcn_s_setprio(1); _Pragma("unroll") for (int m = 0; m < 4; ++m) _Pragma("unroll") for (int n = 0; n < 2; ++n) _Pragma("unroll") for (int k = 0; k < 2; ++k) \
;         acc[ai][bj][m][n] = __builtin_amdgcn_mfma_f32_16x16x32_bf16(Bt[n][k], At[m][k], acc[ai][bj][m][n], 0, 0, 0); __builtin_amdgcn_s_setprio(0); } while (0)
; #define PG8_WAIT_V(n) asm volatile("s_waitcnt vmcnt(" #n ")" ::: "memory")
; #define PG8_WAIT_L(n) asm volatile("s_waitcnt lgkmcnt(" #n ")" ::: "memory")
; #define PG8_BAR __builtin_amdgcn_s_barrier()
; #define PG8_SCHED __builtin_amdgcn_sched_barrier(0)
; template <class Epi, class Sched, bool ALIGN_EPI = false, bool SP2 = false, bool ABLK = false, bool BBLK = false>
; __device__ __forceinline__ void gemm_phase(PG8_LAS unsigned char* lds, const Gemm g, const Sched& S, const Epi& E) {
;     ...
;             PG8_LDA(At, 0, 1); PG8_STAGE(PG8_SB(0, 0), b2, voffB); PG8_STAGE(PG8_SB(0, 1), b2 + hstepB, voffB); PG8_STAGE(PG8_SA(0, 0), a2, voffA);
;             PG8_WAIT_V(8); PG8_WAIT_L(0); PG8_BAR; PG8_MMA(1, 0, At, B0); PG8_MMA(1, 1, At, B1); PG8_BAR; PG8_SCHED;
;             PG8_LDB(B0, 1, 0); PG8_LDB(B1, 1, 1); PG8_SCHED; PG8_LDA(At, 1, 0); PG8_STAGE(PG8_SA(0, 1), a2 + hstepA, voffA);
;             PG8_WAIT_V(8); PG8_WAIT_L(0); PG8_BAR; PG8_MMA(0, 0, At, B0); PG8_MMA(0, 1, At, B1); PG8_BAR; PG8_SCHED;
	s_add_i32 s40, s40, s2
	v_lshl_add_u64 v[202:203], s[34:35], 0, v[186:187]
	s_mov_b32 m0, s40
	ds_read_b128 v[162:165], v207 offset:16384
	ds_read_b128 v[166:169], v207 offset:17408
	ds_read_b128 v[170:173], v207 offset:18432
	ds_read_b128 v[174:177], v207 offset:19456
	ds_read_b128 v[198:201], v207 offset:20480
	ds_read_b128 v[208:211], v207 offset:21504
	ds_read_b128 v[212:215], v207 offset:22528
	ds_read_b128 v[216:219], v207 offset:23552
	global_load_lds_dwordx4 v[202:203], off
	s_add_i32 m0, s40, 0x2000
	s_add_u32 s40, s34, 0x4000
	v_lshl_add_u64 v[202:203], s[34:35], 0, v[182:183]
	s_addc_u32 s41, s35, 0
	s_add_i32 s44, s44, s2
	global_load_lds_dwordx4 v[202:203], off
	v_lshl_add_u64 v[202:203], s[40:41], 0, v[186:187]
	s_mov_b32 m0, s44
	s_nop 0
	global_load_lds_dwordx4 v[202:203], off
	v_lshl_add_u64 v[202:203], s[40:41], 0, v[182:183]
	s_add_i32 m0, s44, 0x2000
	s_nop 0
	global_load_lds_dwordx4 v[202:203], off
	v_lshl_add_u64 v[202:203], s[36:37], 0, v[178:179]
	s_mov_b32 m0, s3
	s_nop 0
	global_load_lds_dwordx4 v[202:203], off
	v_lshl_add_u64 v[202:203], s[36:37], 0, v[180:181]
	s_mov_b32 m0, s42
	s_nop 0
	global_load_lds_dwordx4 v[202:203], off
	s_waitcnt vmcnt(8)
	s_waitcnt lgkmcnt(0)
	s_barrier
	s_setprio 1
	s_waitcnt lgkmcnt(0)
	v_mfma_f32_16x16x32_bf16 v[106:109], v[130:133], v[162:165], v[106:109]
	v_mfma_f32_16x16x32_bf16 v[110:113], v[138:141], v[162:165], v[110:113]
	v_mfma_f32_16x16x32_bf16 v[122:125], v[130:133], v[170:173], v[122:125]
	v_mfma_f32_16x16x32_bf16 v[126:129], v[138:141], v[170:173], v[126:129]
	v_mfma_f32_16x16x32_bf16 v[94:97], v[130:133], v[198:201], v[94:97]
	v_mfma_f32_16x16x32_bf16 v[90:93], v[138:141], v[198:201], v[90:93]
	v_mfma_f32_16x16x32_bf16 v[38:41], v[130:133], v[212:215], v[38:41]
	v_mfma_f32_16x16x32_bf16 v[34:37], v[138:141], v[212:215], v[34:37]
	v_mfma_f32_16x16x32_bf16 v[106:109], v[134:137], v[166:169], v[106:109]
	v_mfma_f32_16x16x32_bf16 v[110:113], v[142:145], v[166:169], v[110:113]
	v_mfma_f32_16x16x32_bf16 v[122:125], v[134:137], v[174:177], v[122:125]
	v_mfma_f32_16x16x32_bf16 v[126:129], v[142:145], v[174:177], v[126:129]
	v_mfma_f32_16x16x32_bf16 v[94:97], v[134:137], v[208:211], v[94:97]
	v_mfma_f32_16x16x32_bf16 v[90:93], v[142:145], v[208:211], v[90:93]
	v_mfma_f32_16x16x32_bf16 v[38:41], v[134:137], v[216:219], v[38:41]
	v_mfma_f32_16x16x32_bf16 v[34:37], v[142:145], v[216:219], v[34:37]
	s_setprio 0
	s_setprio 1
	v_mfma_f32_16x16x32_bf16 v[114:117], v[146:149], v[162:165], v[114:117]
	v_mfma_f32_16x16x32_bf16 v[118:121], v[154:157], v[162:165], v[118:121]
	v_mfma_f32_16x16x32_bf16 v[102:105], v[146:149], v[170:173], v[102:105]
	v_mfma_f32_16x16x32_bf16 v[98:101], v[154:157], v[170:173], v[98:101]
	v_mfma_f32_16x16x32_bf16 v[62:65], v[146:149], v[198:201], v[62:65]
	v_mfma_f32_16x16x32_bf16 v[58:61], v[154:157], v[198:201], v[58:61]
	v_mfma_f32_16x16x32_bf16 v[14:17], v[146:149], v[212:215], v[14:17]
	v_mfma_f32_16x16x32_bf16 v[2:5], v[154:157], v[212:215], v[2:5]
	v_mfma_f32_16x16x32_bf16 v[114:117], v[150:153], v[166:169], v[114:117]
	v_mfma_f32_16x16x32_bf16 v[118:121], v[158:161], v[166:169], v[118:121]
	v_mfma_f32_16x16x32_bf16 v[102:105], v[150:153], v[174:177], v[102:105]
	v_mfma_f32_16x16x32_bf16 v[98:101], v[158:161], v[174:177], v[98:101]
	v_mfma_f32_16x16x32_bf16 v[62:65], v[150:153], v[208:211], v[62:65]
	v_mfma_f32_16x16x32_bf16 v[58:61], v[158:161], v[208:211], v[58:61]
	v_mfma_f32_16x16x32_bf16 v[14:17], v[150:153], v[216:219], v[14:17]
	v_mfma_f32_16x16x32_bf16 v[2:5], v[158:161], v[216:219], v[2:5]
	s_setprio 0
	s_barrier
	s_add_i32 s40, 0, 0x18000
	s_add_i32 s41, 0, 0x1c000
	v_add_u32_e32 v142, s40, v206
	v_add_u32_e32 v158, s41, v206
	ds_read_b128 v[130:133], v142
	ds_read_b128 v[134:137], v142 offset:1024
	ds_read_b128 v[138:141], v142 offset:2048
	ds_read_b128 v[142:145], v142 offset:3072
	ds_read_b128 v[146:149], v158
	ds_read_b128 v[150:153], v158 offset:1024
	ds_read_b128 v[154:157], v158 offset:2048
	ds_read_b128 v[158:161], v158 offset:3072
	s_add_u32 s36, s36, 0x4000
	s_addc_u32 s37, s37, 0
	s_mov_b32 m0, s43
	v_lshl_add_u64 v[202:203], s[36:37], 0, v[178:179]
	ds_read_b128 v[162:165], v207 offset:32768
	ds_read_b128 v[166:169], v207 offset:33792
	ds_read_b128 v[170:173], v207 offset:34816
	ds_read_b128 v[174:177], v207 offset:35840
	ds_read_b128 v[198:201], v207 offset:36864
	ds_read_b128 v[208:211], v207 offset:37888
	ds_read_b128 v[212:215], v207 offset:38912
	ds_read_b128 v[216:219], v207 offset:39936
	global_load_lds_dwordx4 v[202:203], off
	v_lshl_add_u64 v[202:203], s[36:37], 0, v[180:181]
	s_mov_b32 m0, s53
	s_nop 0
	global_load_lds_dwordx4 v[202:203], off
	s_waitcnt vmcnt(8)
	s_waitcnt lgkmcnt(0)
	s_barrier
; #define PG8_STAGE(bufoff, gbase, voff) do { _Pragma("unroll") for (int _i = 0; _i < 2; ++_i) \
;         __builtin_amdgcn_global_load_lds((const unsigned*)((const char*)(gbase) + (voff)[_i]), (PG8_LAS unsigned*)(lds + (bufoff) + ldsw + _i * 8192), 16, 0, 0); } while (0)
; #define PG8_WAIT_V(n) asm volatile("s_waitcnt vmcnt(" #n ")" ::: "memory")
; #define PG8_BAR __builtin_amdgcn_s_barrier()
; template <class Epi, class Sched, bool ALIGN_EPI = false, bool SP2 = false, bool ABLK = false, bool BBLK = false>
; __device__ __forceinline__ void gemm_phase(PG8_LAS unsigned char* lds, const Gemm g, const Sched& S, const Epi& E) {
;     ...
;             PG8_WAIT_V(8); PG8_WAIT_L(0); PG8_BAR; PG8_MMA(0, 0, At, B0); PG8_MMA(0, 1, At, B1); PG8_BAR; PG8_SCHED;
;             PG8_LDA(At, 1, 1); PG8_STAGE(PG8_SB(1, 0), b3, voffB); PG8_STAGE(PG8_SB(1, 1), b3 + hstepB, voffB); PG8_STAGE(PG8_SA(1, 0), a3, voffA);
;             PG8_WAIT_V(8); PG8_WAIT_L(0); PG8_BAR; PG8_MMA(1, 0, At, B0); PG8_MMA(1, 1, At, B1); PG8_BAR; PG8_SCHED;
;             } else {
;             PG8_LDB(B0, 0, 0); PG8_SCHED; PG8_LDA(At, 0, 0); PG8_STAGE(PG8_SA(1, 1), a1 + hstepA, voffA);
;             PG8_WAIT_L(8); PG8_BAR; PG8_WAIT_L(0); PG8_MMA(0, 0, At, B0); PG8_BAR; PG8_SCHED;
;             PG8_LDB(B1, 0, 1); PG8_STAGE(PG8_SB(0, 0), b2, voffB);
;             PG8_BAR; PG8_WAIT_L(0); PG8_MMA(0, 1, At, B1); PG8_BAR;
;             PG8_LDA(At, 0, 1); PG8_STAGE(PG8_SA(0, 0), a2, voffA);
;             PG8_BAR; PG8_WAIT_L(0); PG8_MMA(1, 0, At, B0); PG8_BAR; PG8_SCHED;
;             PG8_STAGE(PG8_SB(0, 1), b2 + hstepB, voffB);
;             PG8_WAIT_V(6); PG8_BAR; PG8_MMA(1, 1, At, B1); PG8_BAR;
;             PG8_LDB(B0, 1, 0); PG8_SCHED; PG8_LDA(At, 1, 0); PG8_STAGE(PG8_SA(0, 1), a2 + hstepA, voffA);
;             PG8_WAIT_L(8); PG8_BAR; PG8_WAIT_L(0); PG8_MMA(0, 0, At, B0); PG8_BAR; PG8_SCHED;
;             PG8_LDB(B1, 1, 1); PG8_STAGE(PG8_SB(1, 0), b3, voffB);
;             PG8_BAR; PG8_WAIT_L(0); PG8_MMA(0, 1, At, B1); PG8_BAR;
;             PG8_LDA(At, 1, 1); PG8_STAGE(PG8_SA(1, 0), a3, voffA);
;             PG8_BAR; PG8_WAIT_L(0); PG8_MMA(1, 0, At, B0); PG8_BAR; PG8_SCHED;
;             PG8_STAGE(PG8_SB(1, 1), b3 + hstepB, voffB);
;             PG8_WAIT_V(6); PG8_BAR; PG8_MMA(1, 1, At, B1); PG8_BAR;
;             }
;         }
;         if constexpr (ALIGN_EPI) { if (wr == 0) PG8_BAR; }
	s_setprio 1
	s_waitcnt lgkmcnt(0)
	v_mfma_f32_16x16x32_bf16 v[30:33], v[130:133], v[162:165], v[30:33]
	v_mfma_f32_16x16x32_bf16 v[22:25], v[138:141], v[162:165], v[22:25]
	v_mfma_f32_16x16x32_bf16 v[10:13], v[130:133], v[170:173], v[10:13]
	v_mfma_f32_16x16x32_bf16 v[6:9], v[138:141], v[170:173], v[6:9]
	v_mfma_f32_16x16x32_bf16 v[50:53], v[130:133], v[198:201], v[50:53]
	v_mfma_f32_16x16x32_bf16 v[54:57], v[138:141], v[198:201], v[54:57]
	v_mfma_f32_16x16x32_bf16 v[74:77], v[130:133], v[212:215], v[74:77]
	v_mfma_f32_16x16x32_bf16 v[78:81], v[138:141], v[212:215], v[78:81]
	v_mfma_f32_16x16x32_bf16 v[30:33], v[134:137], v[166:169], v[30:33]
	v_mfma_f32_16x16x32_bf16 v[22:25], v[142:145], v[166:169], v[22:25]
	v_mfma_f32_16x16x32_bf16 v[10:13], v[134:137], v[174:177], v[10:13]
	v_mfma_f32_16x16x32_bf16 v[6:9], v[142:145], v[174:177], v[6:9]
	v_mfma_f32_16x16x32_bf16 v[50:53], v[134:137], v[208:211], v[50:53]
	v_mfma_f32_16x16x32_bf16 v[54:57], v[142:145], v[208:211], v[54:57]
	v_mfma_f32_16x16x32_bf16 v[74:77], v[134:137], v[216:219], v[74:77]
	v_mfma_f32_16x16x32_bf16 v[78:81], v[142:145], v[216:219], v[78:81]
	s_setprio 0
	s_setprio 1
	v_mfma_f32_16x16x32_bf16 v[26:29], v[146:149], v[162:165], v[26:29]
	v_mfma_f32_16x16x32_bf16 v[18:21], v[154:157], v[162:165], v[18:21]
	v_mfma_f32_16x16x32_bf16 v[42:45], v[146:149], v[170:173], v[42:45]
	v_mfma_f32_16x16x32_bf16 v[46:49], v[154:157], v[170:173], v[46:49]
	v_mfma_f32_16x16x32_bf16 v[66:69], v[146:149], v[198:201], v[66:69]
	v_mfma_f32_16x16x32_bf16 v[70:73], v[154:157], v[198:201], v[70:73]
	v_mfma_f32_16x16x32_bf16 v[82:85], v[146:149], v[212:215], v[82:85]
	v_mfma_f32_16x16x32_bf16 v[86:89], v[154:157], v[212:215], v[86:89]
	v_mfma_f32_16x16x32_bf16 v[26:29], v[150:153], v[166:169], v[26:29]
	v_mfma_f32_16x16x32_bf16 v[18:21], v[158:161], v[166:169], v[18:21]
	v_mfma_f32_16x16x32_bf16 v[42:45], v[150:153], v[174:177], v[42:45]
	v_mfma_f32_16x16x32_bf16 v[46:49], v[158:161], v[174:177], v[46:49]
	v_mfma_f32_16x16x32_bf16 v[66:69], v[150:153], v[208:211], v[66:69]
	v_mfma_f32_16x16x32_bf16 v[70:73], v[158:161], v[208:211], v[70:73]
	v_mfma_f32_16x16x32_bf16 v[82:85], v[150:153], v[216:219], v[82:85]
	v_mfma_f32_16x16x32_bf16 v[86:89], v[158:161], v[216:219], v[86:89]
	s_setprio 0
	s_barrier
	s_add_u32 s36, s34, 0x8000
	s_addc_u32 s37, s35, 0
	s_add_i32 s40, s40, s2
	v_lshl_add_u64 v[202:203], s[36:37], 0, v[186:187]
	s_mov_b32 m0, s40
	ds_read_b128 v[162:165], v207 offset:49152
	ds_read_b128 v[166:169], v207 offset:50176
	ds_read_b128 v[170:173], v207 offset:51200
	ds_read_b128 v[174:177], v207 offset:52224
	ds_read_b128 v[198:201], v207 offset:53248
	ds_read_b128 v[208:211], v207 offset:54272
	ds_read_b128 v[212:215], v207 offset:55296
	ds_read_b128 v[216:219], v207 offset:56320
	global_load_lds_dwordx4 v[202:203], off
	s_add_i32 m0, s40, 0x2000
	s_add_u32 s34, s34, 0xc000
	v_lshl_add_u64 v[202:203], s[36:37], 0, v[182:183]
	s_addc_u32 s35, s35, 0
	s_add_i32 s36, s41, s2
	global_load_lds_dwordx4 v[202:203], off
	v_lshl_add_u64 v[202:203], s[34:35], 0, v[186:187]
	s_mov_b32 m0, s36
	s_nop 0
	global_load_lds_dwordx4 v[202:203], off
	v_lshl_add_u64 v[202:203], s[34:35], 0, v[182:183]
	s_add_i32 m0, s36, 0x2000
	s_nop 0
	global_load_lds_dwordx4 v[202:203], off
	v_lshl_add_u64 v[202:203], s[8:9], 0, v[178:179]
	s_mov_b32 m0, s92
	s_nop 0
	global_load_lds_dwordx4 v[202:203], off
	v_lshl_add_u64 v[202:203], s[8:9], 0, v[180:181]
	s_mov_b32 m0, s93
	s_nop 0
	global_load_lds_dwordx4 v[202:203], off
	s_waitcnt vmcnt(8)
	s_waitcnt lgkmcnt(0)
	s_barrier
	s_setprio 1
	s_waitcnt lgkmcnt(0)
	v_mfma_f32_16x16x32_bf16 v[106:109], v[130:133], v[162:165], v[106:109]
	v_mfma_f32_16x16x32_bf16 v[110:113], v[138:141], v[162:165], v[110:113]
	v_mfma_f32_16x16x32_bf16 v[122:125], v[130:133], v[170:173], v[122:125]
	v_mfma_f32_16x16x32_bf16 v[126:129], v[138:141], v[170:173], v[126:129]
	v_mfma_f32_16x16x32_bf16 v[94:97], v[130:133], v[198:201], v[94:97]
	v_mfma_f32_16x16x32_bf16 v[90:93], v[138:141], v[198:201], v[90:93]
	v_mfma_f32_16x16x32_bf16 v[38:41], v[130:133], v[212:215], v[38:41]
	v_mfma_f32_16x16x32_bf16 v[34:37], v[138:141], v[212:215], v[34:37]
	v_mfma_f32_16x16x32_bf16 v[106:109], v[134:137], v[166:169], v[106:109]
	v_mfma_f32_16x16x32_bf16 v[110:113], v[142:145], v[166:169], v[110:113]
	v_mfma_f32_16x16x32_bf16 v[122:125], v[134:137], v[174:177], v[122:125]
	v_mfma_f32_16x16x32_bf16 v[126:129], v[142:145], v[174:177], v[126:129]
	v_mfma_f32_16x16x32_bf16 v[94:97], v[134:137], v[208:211], v[94:97]
	v_mfma_f32_16x16x32_bf16 v[90:93], v[142:145], v[208:211], v[90:93]
	v_mfma_f32_16x16x32_bf16 v[38:41], v[134:137], v[216:219], v[38:41]
	v_mfma_f32_16x16x32_bf16 v[34:37], v[142:145], v[216:219], v[34:37]
	s_setprio 0
	s_setprio 1
	v_mfma_f32_16x16x32_bf16 v[114:117], v[146:149], v[162:165], v[114:117]
	v_mfma_f32_16x16x32_bf16 v[118:121], v[154:157], v[162:165], v[118:121]
	v_mfma_f32_16x16x32_bf16 v[102:105], v[146:149], v[170:173], v[102:105]
	v_mfma_f32_16x16x32_bf16 v[98:101], v[154:157], v[170:173], v[98:101]
	v_mfma_f32_16x16x32_bf16 v[62:65], v[146:149], v[198:201], v[62:65]
	v_mfma_f32_16x16x32_bf16 v[58:61], v[154:157], v[198:201], v[58:61]
	v_mfma_f32_16x16x32_bf16 v[14:17], v[146:149], v[212:215], v[14:17]
	v_mfma_f32_16x16x32_bf16 v[2:5], v[154:157], v[212:215], v[2:5]
	v_mfma_f32_16x16x32_bf16 v[114:117], v[150:153], v[166:169], v[114:117]
	v_mfma_f32_16x16x32_bf16 v[118:121], v[158:161], v[166:169], v[118:121]
	v_mfma_f32_16x16x32_bf16 v[102:105], v[150:153], v[174:177], v[102:105]
	v_mfma_f32_16x16x32_bf16 v[98:101], v[158:161], v[174:177], v[98:101]
	v_mfma_f32_16x16x32_bf16 v[62:65], v[150:153], v[208:211], v[62:65]
	v_mfma_f32_16x16x32_bf16 v[58:61], v[158:161], v[208:211], v[58:61]
	v_mfma_f32_16x16x32_bf16 v[14:17], v[150:153], v[216:219], v[14:17]
	v_mfma_f32_16x16x32_bf16 v[2:5], v[158:161], v[216:219], v[2:5]
	s_setprio 0
	s_barrier
	s_add_i32 s33, s33, 2
	s_add_u32 s0, s0, 0x10000
	s_addc_u32 s1, s1, 0
	s_add_u32 s29, s29, 0x10000
	s_addc_u32 s31, s31, 0
	s_cmpk_gt_u32 s33, 0x55
	s_cbranch_scc0 .LBB0_305
	s_and_b64 vcc, exec, s[18:19]
	s_cbranch_vccz .LBB0_308
	s_barrier

; __device__ __forceinline__ u32x4 pack8(const f32x4 v0, const f32x4 v1) { u32x4 w; w.x = cvt_pk_bf16(v0[0], v0[1]); w.y = cvt_pk_bf16(v0[2], v0[3]); w.z = cvt_pk_bf16(v1[0], v1[1]); w.w = cvt_pk_bf16(v1[2], v1[3]); return w; }
;     __device__ __forceinline__ void operator()(f32x4 (&acc)[2][2][4][2], const Unit& u, int wr, int wc, int fr_, int fq_) const {
;     ...
;             for (int n = 0; n < 2; ++n) { const int col = col0 + bj * HALF + 4 * n; const f32x4 g = *(const f32x4*)(gain + col);
;                 if (FINAL) { av[bj][n] = g; sv[bj][n] = (f32x4){0.f, 0.f, 0.f, 0.f}; }
;                 else { const float* mp = nmod + (size_t)rb * NMODC; av[bj][n] = g * (*(const f32x4*)(mp + isc * DM + col) + 1.0f); sv[bj][n] = *(const f32x4*)(mp + ish * DM + col); } }
;         if (wid == 0) { if (lane == 0) { unsigned sp = 0u; while (__hip_atomic_load(cnt + 16 * u.pm, __ATOMIC_RELAXED, __HIP_MEMORY_SCOPE_AGENT) < 64u) { __builtin_amdgcn_s_sleep(1); if (++sp > (1u << 17)) break; } } }
;         asm volatile("s_waitcnt lgkmcnt(0)" ::: "memory"); __builtin_amdgcn_s_barrier(); asm volatile("" ::: "memory");
;         if (lane < 32) { const float* slot = xbuf + ((size_t)u.pm * BM + row) * 8; float t8[8];
; #pragma unroll
;             for (int t = 0; t < 8; ++t) t8[t] = __hip_atomic_load(slot + t, __ATOMIC_RELAXED, __HIP_MEMORY_SCOPE_AGENT);
;             const float tot = ((t8[0] + t8[1]) + (t8[2] + t8[3])) + ((t8[4] + t8[5]) + (t8[6] + t8[7]));
;             S[row] = __builtin_amdgcn_rsqf(tot * (1.0f / DM) + 1e-6f); }
;         asm volatile("s_waitcnt lgkmcnt(0)" ::: "memory"); __builtin_amdgcn_s_barrier(); asm volatile("" ::: "memory");
; #pragma unroll
;         for (int ai = 0; ai < 2; ++ai)
; #pragma unroll
;             for (int m = 0; m < 4; ++m) { const int r = ai * HALF + wr * 64 + m * 16 + fr; const float rs = S[r];
; #pragma unroll
;                 for (int bj = 0; bj < 2; ++bj) { const f32x4 y0 = acc[ai][bj][m][0] * rs * av[bj][0] + sv[bj][0], y1 = acc[ai][bj][m][1] * rs * av[bj][1] + sv[bj][1];
;                     if (FINAL) { float* o = OUTF + ((size_t)u.pm * BM + r) * DM + col0 + bj * HALF; *(f32x4*)o = y0; *(f32x4*)(o + 4) = y1; }
;                     else *(u32x4*)(XN + (((size_t)u.pm * (DM / BK) + u.pn * 4 + bj * 2 + (wc >> 1)) * BM + r) * BK + (wc & 1) * 32 + 8 * fq) = pack8(y0, y1); } }
.LBB0_340:
	s_or_b64 exec, exec, s[0:1]
	s_waitcnt vmcnt(7)
	v_pk_add_f32 v[154:155], v[154:155], 1.0 op_sel_hi:[1,0]
	v_pk_add_f32 v[156:157], v[156:157], 1.0 op_sel_hi:[1,0]
	v_pk_mul_f32 v[146:147], v[146:147], v[154:155]
	v_lshl_add_u32 v154, v198, 2, 0
	s_waitcnt lgkmcnt(0)
	s_barrier
	s_lshl_b32 s8, s30, 2
	v_add_u32_e32 v154, 0x21540, v154
	v_pk_mul_f32 v[148:149], v[148:149], v[156:157]
	s_lshl_b64 s[0:1], s[28:29], 5
	s_ashr_i32 s9, s8, 31
	ds_read_b32 v156, v154
	s_add_u32 s0, s0, s8
	s_addc_u32 s1, s1, s9
	s_or_b64 s[0:1], s[0:1], s[20:21]
	s_waitcnt vmcnt(5)
	v_pk_add_f32 v[158:159], v[158:159], 1.0 op_sel_hi:[1,0]
	s_lshl_b64 s[0:1], s[0:1], 15
	v_pk_add_f32 v[160:161], v[160:161], 1.0 op_sel_hi:[1,0]
	v_pk_mul_f32 v[150:151], v[150:151], v[158:159]
	s_waitcnt lgkmcnt(0)
	v_pk_mul_f32 v[30:31], v[30:31], v[156:157] op_sel_hi:[1,0]
	v_pk_mul_f32 v[32:33], v[32:33], v[156:157] op_sel_hi:[1,0]
	v_pk_mul_f32 v[22:23], v[22:23], v[156:157] op_sel_hi:[1,0]
	s_add_u32 s0, s61, s0
	v_pk_mul_f32 v[152:153], v[152:153], v[160:161]
	v_lshlrev_b64 v[158:159], 7, v[198:199]
	s_waitcnt vmcnt(3)
	v_pk_fma_f32 v[32:33], v[148:149], v[32:33], v[144:145]
	v_pk_fma_f32 v[30:31], v[146:147], v[30:31], v[142:143]
	v_pk_mul_f32 v[24:25], v[24:25], v[156:157] op_sel_hi:[1,0]
	s_waitcnt vmcnt(1)
	v_pk_fma_f32 v[22:23], v[150:151], v[22:23], v[138:139]
	s_addc_u32 s1, s65, s1
	v_ashrrev_i32_e32 v201, 31, v200
	v_pk_fma_f32 v[24:25], v[152:153], v[24:25], v[140:141]
	v_cvt_pk_bf16_f32 v30, v30, v31
	v_cvt_pk_bf16_f32 v31, v32, v33
	v_cvt_pk_bf16_f32 v32, v22, v23
	v_lshl_add_u64 v[22:23], s[0:1], 0, v[158:159]
	v_cvt_pk_bf16_f32 v33, v24, v25
	v_lshl_add_u64 v[24:25], v[22:23], 0, s[16:17]
	v_lshlrev_b64 v[22:23], 1, v[200:201]
	v_pk_add_f32 v[176:177], v[176:177], 1.0 op_sel_hi:[1,0]
	v_pk_add_f32 v[174:175], v[174:175], 1.0 op_sel_hi:[1,0]
	v_pk_add_f32 v[172:173], v[172:173], 1.0 op_sel_hi:[1,0]
	v_lshl_add_u64 v[24:25], v[24:25], 0, v[22:23]
	v_pk_mul_f32 v[166:167], v[166:167], v[174:175]
	v_pk_mul_f32 v[168:169], v[168:169], v[176:177]
	v_pk_add_f32 v[170:171], v[170:171], 1.0 op_sel_hi:[1,0]
	v_pk_mul_f32 v[164:165], v[164:165], v[172:173]
	global_store_dwordx4 v[24:25], v[30:33], off
	v_pk_mul_f32 v[24:25], v[26:27], v[156:157] op_sel_hi:[1,0]
	v_pk_mul_f32 v[26:27], v[28:29], v[156:157] op_sel_hi:[1,0]
	v_pk_mul_f32 v[18:19], v[18:19], v[156:157] op_sel_hi:[1,0]
	v_pk_mul_f32 v[20:21], v[20:21], v[156:157] op_sel_hi:[1,0]
	v_pk_mul_f32 v[162:163], v[162:163], v[170:171]
	s_waitcnt vmcnt(1)
	v_pk_fma_f32 v[26:27], v[164:165], v[26:27], v[136:137]
	v_pk_fma_f32 v[28:29], v[168:169], v[20:21], v[132:133]
	v_pk_fma_f32 v[20:21], v[166:167], v[18:19], v[130:131]
	s_add_u32 s8, s0, 0x10000
	v_pk_fma_f32 v[24:25], v[162:163], v[24:25], v[134:135]
	s_addc_u32 s9, s1, 0
	v_cvt_pk_bf16_f32 v18, v24, v25
	v_cvt_pk_bf16_f32 v19, v26, v27
	v_cvt_pk_bf16_f32 v20, v20, v21
	v_cvt_pk_bf16_f32 v21, v28, v29
	ds_read_b32 v26, v154 offset:64
	v_lshl_add_u64 v[24:25], s[8:9], 0, v[158:159]
	v_lshl_add_u64 v[24:25], v[24:25], 0, s[16:17]
	v_lshl_add_u64 v[24:25], v[24:25], 0, v[22:23]
	global_store_dwordx4 v[24:25], v[18:21], off
	s_waitcnt lgkmcnt(0)
	v_pk_mul_f32 v[10:11], v[10:11], v[26:27] op_sel_hi:[1,0]
	v_pk_mul_f32 v[6:7], v[6:7], v[26:27] op_sel_hi:[1,0]
	v_add_u32_e32 v18, 16, v198
	v_ashrrev_i32_e32 v19, 31, v18
	v_lshlrev_b64 v[18:19], 7, v[18:19]
	v_pk_fma_f32 v[10:11], v[146:147], v[10:11], v[142:143]
	v_pk_mul_f32 v[8:9], v[8:9], v[26:27] op_sel_hi:[1,0]
	v_pk_mul_f32 v[12:13], v[12:13], v[26:27] op_sel_hi:[1,0]
	v_pk_fma_f32 v[20:21], v[152:153], v[8:9], v[140:141]
	v_pk_fma_f32 v[8:9], v[150:151], v[6:7], v[138:139]
	v_cvt_pk_bf16_f32 v6, v10, v11
	v_lshl_add_u64 v[10:11], s[0:1], 0, v[18:19]
	v_lshl_add_u64 v[10:11], v[10:11], 0, s[16:17]
	v_pk_fma_f32 v[12:13], v[148:149], v[12:13], v[144:145]
	v_lshl_add_u64 v[10:11], v[10:11], 0, v[22:23]
	v_cvt_pk_bf16_f32 v7, v12, v13
	v_cvt_pk_bf16_f32 v8, v8, v9
	v_cvt_pk_bf16_f32 v9, v20, v21
	global_store_dwordx4 v[10:11], v[6:9], off
	v_pk_mul_f32 v[10:11], v[46:47], v[26:27] op_sel_hi:[1,0]
	v_pk_mul_f32 v[12:13], v[48:49], v[26:27] op_sel_hi:[1,0]
	v_pk_mul_f32 v[6:7], v[42:43], v[26:27] op_sel_hi:[1,0]
	v_pk_mul_f32 v[8:9], v[44:45], v[26:27] op_sel_hi:[1,0]
	v_pk_fma_f32 v[6:7], v[162:163], v[6:7], v[134:135]
	v_pk_fma_f32 v[8:9], v[164:165], v[8:9], v[136:137]
	v_pk_fma_f32 v[12:13], v[168:169], v[12:13], v[132:133]
	v_pk_fma_f32 v[10:11], v[166:167], v[10:11], v[130:131]
	v_cvt_pk_bf16_f32 v6, v6, v7
	v_cvt_pk_bf16_f32 v7, v8, v9
	s_and_b64 vcc, exec, s[6:7]
	v_cvt_pk_bf16_f32 v8, v10, v11
	v_cvt_pk_bf16_f32 v9, v12, v13
	v_lshl_add_u64 v[10:11], s[8:9], 0, v[18:19]
	ds_read_b32 v12, v154 offset:128
	v_lshl_add_u64 v[10:11], v[10:11], 0, s[16:17]
	v_lshl_add_u64 v[10:11], v[10:11], 0, v[22:23]
	global_store_dwordx4 v[10:11], v[6:9], off
	s_waitcnt lgkmcnt(0)
; __device__ __forceinline__ u32x4 pack8(const f32x4 v0, const f32x4 v1) { u32x4 w; w.x = cvt_pk_bf16(v0[0], v0[1]); w.y = cvt_pk_bf16(v0[2], v0[3]); w.z = cvt_pk_bf16(v1[0], v1[1]); w.w = cvt_pk_bf16(v1[2], v1[3]); return w; }
;     __device__ __forceinline__ void operator()(f32x4 (&acc)[2][2][4][2], const Unit& u, int wr, int wc, int fr_, int fq_) const {
;     ...
; #pragma unroll
;         for (int ai = 0; ai < 2; ++ai)
; #pragma unroll
;             for (int m = 0; m < 4; ++m) { const int r = ai * HALF + wr * 64 + m * 16 + fr; const float rs = S[r];
; #pragma unroll
;                 for (int bj = 0; bj < 2; ++bj) { const f32x4 y0 = acc[ai][bj][m][0] * rs * av[bj][0] + sv[bj][0], y1 = acc[ai][bj][m][1] * rs * av[bj][1] + sv[bj][1];
;                     if (FINAL) { float* o = OUTF + ((size_t)u.pm * BM + r) * DM + col0 + bj * HALF; *(f32x4*)o = y0; *(f32x4*)(o + 4) = y1; }
;                     else *(u32x4*)(XN + (((size_t)u.pm * (DM / BK) + u.pn * 4 + bj * 2 + (wc >> 1)) * BM + r) * BK + (wc & 1) * 32 + 8 * fq) = pack8(y0, y1); } }
	v_pk_mul_f32 v[18:19], v[54:55], v[12:13] op_sel_hi:[1,0]
	v_add_u32_e32 v6, 32, v198
	v_ashrrev_i32_e32 v7, 31, v6
	v_lshlrev_b64 v[10:11], 7, v[6:7]
	v_pk_mul_f32 v[6:7], v[50:51], v[12:13] op_sel_hi:[1,0]
	v_pk_mul_f32 v[8:9], v[52:53], v[12:13] op_sel_hi:[1,0]
	v_pk_fma_f32 v[6:7], v[146:147], v[6:7], v[142:143]
	v_pk_fma_f32 v[8:9], v[148:149], v[8:9], v[144:145]
	v_pk_fma_f32 v[18:19], v[150:151], v[18:19], v[138:139]
	v_cvt_pk_bf16_f32 v6, v6, v7
	v_cvt_pk_bf16_f32 v7, v8, v9
	v_pk_mul_f32 v[20:21], v[56:57], v[12:13] op_sel_hi:[1,0]
	v_cvt_pk_bf16_f32 v8, v18, v19
	v_lshl_add_u64 v[18:19], s[0:1], 0, v[10:11]
	v_lshl_add_u64 v[18:19], v[18:19], 0, s[16:17]
	v_pk_fma_f32 v[20:21], v[152:153], v[20:21], v[140:141]
	v_lshl_add_u64 v[18:19], v[18:19], 0, v[22:23]
	v_cvt_pk_bf16_f32 v9, v20, v21
	global_store_dwordx4 v[18:19], v[6:9], off
	v_pk_mul_f32 v[18:19], v[70:71], v[12:13] op_sel_hi:[1,0]
	v_lshl_add_u64 v[10:11], s[8:9], 0, v[10:11]
	v_pk_mul_f32 v[6:7], v[66:67], v[12:13] op_sel_hi:[1,0]
	v_pk_mul_f32 v[8:9], v[68:69], v[12:13] op_sel_hi:[1,0]
	v_pk_mul_f32 v[12:13], v[72:73], v[12:13] op_sel_hi:[1,0]
	v_pk_fma_f32 v[8:9], v[164:165], v[8:9], v[136:137]
	v_pk_fma_f32 v[6:7], v[162:163], v[6:7], v[134:135]
	v_pk_fma_f32 v[12:13], v[168:169], v[12:13], v[132:133]
	v_pk_fma_f32 v[18:19], v[166:167], v[18:19], v[130:131]
	v_cvt_pk_bf16_f32 v6, v6, v7
	v_cvt_pk_bf16_f32 v7, v8, v9
	v_lshl_add_u64 v[10:11], v[10:11], 0, s[16:17]
	v_cvt_pk_bf16_f32 v8, v18, v19
	v_cvt_pk_bf16_f32 v9, v12, v13
	ds_read_b32 v12, v154 offset:192
	v_lshl_add_u64 v[10:11], v[10:11], 0, v[22:23]
	global_store_dwordx4 v[10:11], v[6:9], off
	s_waitcnt lgkmcnt(0)
	v_pk_mul_f32 v[18:19], v[78:79], v[12:13] op_sel_hi:[1,0]
	v_add_u32_e32 v6, 48, v198
	v_ashrrev_i32_e32 v7, 31, v6
	v_lshlrev_b64 v[10:11], 7, v[6:7]
	v_pk_mul_f32 v[6:7], v[74:75], v[12:13] op_sel_hi:[1,0]
	v_pk_mul_f32 v[8:9], v[76:77], v[12:13] op_sel_hi:[1,0]
	v_pk_fma_f32 v[6:7], v[146:147], v[6:7], v[142:143]
	v_pk_fma_f32 v[8:9], v[148:149], v[8:9], v[144:145]
	v_pk_fma_f32 v[18:19], v[150:151], v[18:19], v[138:139]
	v_cvt_pk_bf16_f32 v6, v6, v7
	v_cvt_pk_bf16_f32 v7, v8, v9
	v_pk_mul_f32 v[20:21], v[80:81], v[12:13] op_sel_hi:[1,0]
	v_cvt_pk_bf16_f32 v8, v18, v19
	v_lshl_add_u64 v[18:19], s[0:1], 0, v[10:11]
	v_lshl_add_u64 v[18:19], v[18:19], 0, s[16:17]
	v_pk_fma_f32 v[20:21], v[152:153], v[20:21], v[140:141]
	v_lshl_add_u64 v[18:19], v[18:19], 0, v[22:23]
	v_cvt_pk_bf16_f32 v9, v20, v21
	global_store_dwordx4 v[18:19], v[6:9], off
	v_pk_mul_f32 v[18:19], v[86:87], v[12:13] op_sel_hi:[1,0]
	v_lshl_add_u64 v[10:11], s[8:9], 0, v[10:11]
	v_pk_mul_f32 v[6:7], v[82:83], v[12:13] op_sel_hi:[1,0]
	v_pk_mul_f32 v[8:9], v[84:85], v[12:13] op_sel_hi:[1,0]
	v_pk_mul_f32 v[12:13], v[88:89], v[12:13] op_sel_hi:[1,0]
	v_pk_fma_f32 v[8:9], v[164:165], v[8:9], v[136:137]
	v_pk_fma_f32 v[6:7], v[162:163], v[6:7], v[134:135]
	v_pk_fma_f32 v[12:13], v[168:169], v[12:13], v[132:133]
	v_pk_fma_f32 v[18:19], v[166:167], v[18:19], v[130:131]
	v_cvt_pk_bf16_f32 v6, v6, v7
	v_cvt_pk_bf16_f32 v7, v8, v9
	v_lshl_add_u64 v[10:11], v[10:11], 0, s[16:17]
	v_cvt_pk_bf16_f32 v8, v18, v19
	v_cvt_pk_bf16_f32 v9, v12, v13
	ds_read_b32 v12, v154 offset:512
	v_lshl_add_u64 v[10:11], v[10:11], 0, v[22:23]
	global_store_dwordx4 v[10:11], v[6:9], off
	s_waitcnt lgkmcnt(0)
	v_pk_mul_f32 v[18:19], v[110:111], v[12:13] op_sel_hi:[1,0]
	v_add_u32_e32 v6, 0x80, v198
	v_ashrrev_i32_e32 v7, 31, v6
	v_lshlrev_b64 v[10:11], 7, v[6:7]
	v_pk_mul_f32 v[6:7], v[106:107], v[12:13] op_sel_hi:[1,0]
	v_pk_mul_f32 v[8:9], v[108:109], v[12:13] op_sel_hi:[1,0]
	v_pk_fma_f32 v[6:7], v[146:147], v[6:7], v[142:143]
	v_pk_fma_f32 v[8:9], v[148:149], v[8:9], v[144:145]
	v_pk_fma_f32 v[18:19], v[150:151], v[18:19], v[138:139]
	v_cvt_pk_bf16_f32 v6, v6, v7
	v_cvt_pk_bf16_f32 v7, v8, v9
	v_pk_mul_f32 v[20:21], v[112:113], v[12:13] op_sel_hi:[1,0]
	v_cvt_pk_bf16_f32 v8, v18, v19
	v_lshl_add_u64 v[18:19], s[0:1], 0, v[10:11]
	v_lshl_add_u64 v[18:19], v[18:19], 0, s[16:17]
	v_pk_fma_f32 v[20:21], v[152:153], v[20:21], v[140:141]
	v_lshl_add_u64 v[18:19], v[18:19], 0, v[22:23]
	v_cvt_pk_bf16_f32 v9, v20, v21
	global_store_dwordx4 v[18:19], v[6:9], off
	v_pk_mul_f32 v[18:19], v[118:119], v[12:13] op_sel_hi:[1,0]
	v_lshl_add_u64 v[10:11], s[8:9], 0, v[10:11]
	v_pk_mul_f32 v[6:7], v[114:115], v[12:13] op_sel_hi:[1,0]
	v_pk_mul_f32 v[8:9], v[116:117], v[12:13] op_sel_hi:[1,0]
	v_pk_mul_f32 v[12:13], v[120:121], v[12:13] op_sel_hi:[1,0]
	v_pk_fma_f32 v[8:9], v[164:165], v[8:9], v[136:137]
	v_pk_fma_f32 v[6:7], v[162:163], v[6:7], v[134:135]
	v_pk_fma_f32 v[12:13], v[168:169], v[12:13], v[132:133]
	v_pk_fma_f32 v[18:19], v[166:167], v[18:19], v[130:131]
	v_cvt_pk_bf16_f32 v6, v6, v7
	v_cvt_pk_bf16_f32 v7, v8, v9
	v_lshl_add_u64 v[10:11], v[10:11], 0, s[16:17]
	v_cvt_pk_bf16_f32 v8, v18, v19
	v_cvt_pk_bf16_f32 v9, v12, v13
	ds_read_b32 v12, v154 offset:576
	v_lshl_add_u64 v[10:11], v[10:11], 0, v[22:23]
	global_store_dwordx4 v[10:11], v[6:9], off
	s_waitcnt lgkmcnt(0)
; __device__ __forceinline__ u32x4 pack8(const f32x4 v0, const f32x4 v1) { u32x4 w; w.x = cvt_pk_bf16(v0[0], v0[1]); w.y = cvt_pk_bf16(v0[2], v0[3]); w.z = cvt_pk_bf16(v1[0], v1[1]); w.w = cvt_pk_bf16(v1[2], v1[3]); return w; }
; #define PG8_BAR __builtin_amdgcn_s_barrier()
;     __device__ __forceinline__ void operator()(f32x4 (&acc)[2][2][4][2], const Unit& u, int wr, int wc, int fr_, int fq_) const {
;     ...
; #pragma unroll
;         for (int ai = 0; ai < 2; ++ai)
; #pragma unroll
;             for (int m = 0; m < 4; ++m) { const int r = ai * HALF + wr * 64 + m * 16 + fr; const float rs = S[r];
; #pragma unroll
;                 for (int bj = 0; bj < 2; ++bj) { const f32x4 y0 = acc[ai][bj][m][0] * rs * av[bj][0] + sv[bj][0], y1 = acc[ai][bj][m][1] * rs * av[bj][1] + sv[bj][1];
;                     if (FINAL) { float* o = OUTF + ((size_t)u.pm * BM + r) * DM + col0 + bj * HALF; *(f32x4*)o = y0; *(f32x4*)(o + 4) = y1; }
;                     else *(u32x4*)(XN + (((size_t)u.pm * (DM / BK) + u.pn * 4 + bj * 2 + (wc >> 1)) * BM + r) * BK + (wc & 1) * 32 + 8 * fq) = pack8(y0, y1); } }
; template <class Epi, class Sched, bool ALIGN_EPI = false, bool SP2 = false, bool ABLK = false, bool BBLK = false>
; __device__ __forceinline__ void gemm_phase(PG8_LAS unsigned char* lds, const Gemm g, const Sched& S, const Epi& E) {
;     ...
;         if (!has_next) break;
; #pragma unroll
;         for (int a = 0; a < 2; ++a)
; #pragma unroll
;             for (int b = 0; b < 2; ++b)
; #pragma unroll
;                 for (int m = 0; m < 4; ++m)
; #pragma unroll
;                     for (int n = 0; n < 2; ++n) acc[a][b][m][n] = (f32x4){0.f, 0.f, 0.f, 0.f};
;         cur = nxt; cA = nA; cB = nB; ++ui;
;         if constexpr (ALIGN_EPI) { if (wr == 1) PG8_BAR; }
	v_pk_mul_f32 v[18:19], v[126:127], v[12:13] op_sel_hi:[1,0]
	v_add_u32_e32 v6, 0x90, v198
	v_ashrrev_i32_e32 v7, 31, v6
	v_lshlrev_b64 v[10:11], 7, v[6:7]
	v_pk_mul_f32 v[6:7], v[122:123], v[12:13] op_sel_hi:[1,0]
	v_pk_mul_f32 v[8:9], v[124:125], v[12:13] op_sel_hi:[1,0]
	v_pk_fma_f32 v[6:7], v[146:147], v[6:7], v[142:143]
	v_pk_fma_f32 v[8:9], v[148:149], v[8:9], v[144:145]
	v_pk_fma_f32 v[18:19], v[150:151], v[18:19], v[138:139]
	v_cvt_pk_bf16_f32 v6, v6, v7
	v_cvt_pk_bf16_f32 v7, v8, v9
	v_pk_mul_f32 v[20:21], v[128:129], v[12:13] op_sel_hi:[1,0]
	v_cvt_pk_bf16_f32 v8, v18, v19
	v_lshl_add_u64 v[18:19], s[0:1], 0, v[10:11]
	v_lshl_add_u64 v[18:19], v[18:19], 0, s[16:17]
	v_pk_fma_f32 v[20:21], v[152:153], v[20:21], v[140:141]
	v_lshl_add_u64 v[18:19], v[18:19], 0, v[22:23]
	v_cvt_pk_bf16_f32 v9, v20, v21
	global_store_dwordx4 v[18:19], v[6:9], off
	v_pk_mul_f32 v[18:19], v[98:99], v[12:13] op_sel_hi:[1,0]
	v_lshl_add_u64 v[10:11], s[8:9], 0, v[10:11]
	v_pk_mul_f32 v[6:7], v[102:103], v[12:13] op_sel_hi:[1,0]
	v_pk_mul_f32 v[8:9], v[104:105], v[12:13] op_sel_hi:[1,0]
	v_pk_mul_f32 v[12:13], v[100:101], v[12:13] op_sel_hi:[1,0]
	v_pk_fma_f32 v[8:9], v[164:165], v[8:9], v[136:137]
	v_pk_fma_f32 v[6:7], v[162:163], v[6:7], v[134:135]
	v_pk_fma_f32 v[12:13], v[168:169], v[12:13], v[132:133]
	v_pk_fma_f32 v[18:19], v[166:167], v[18:19], v[130:131]
	v_cvt_pk_bf16_f32 v6, v6, v7
	v_cvt_pk_bf16_f32 v7, v8, v9
	v_lshl_add_u64 v[10:11], v[10:11], 0, s[16:17]
	v_cvt_pk_bf16_f32 v8, v18, v19
	v_cvt_pk_bf16_f32 v9, v12, v13
	ds_read_b32 v12, v154 offset:640
	v_lshl_add_u64 v[10:11], v[10:11], 0, v[22:23]
	global_store_dwordx4 v[10:11], v[6:9], off
	s_waitcnt lgkmcnt(0)
	v_pk_mul_f32 v[18:19], v[90:91], v[12:13] op_sel_hi:[1,0]
	v_add_u32_e32 v6, 0xa0, v198
	v_ashrrev_i32_e32 v7, 31, v6
	v_lshlrev_b64 v[10:11], 7, v[6:7]
	v_pk_mul_f32 v[6:7], v[94:95], v[12:13] op_sel_hi:[1,0]
	v_pk_mul_f32 v[8:9], v[96:97], v[12:13] op_sel_hi:[1,0]
	v_pk_fma_f32 v[6:7], v[146:147], v[6:7], v[142:143]
	v_pk_fma_f32 v[8:9], v[148:149], v[8:9], v[144:145]
	v_pk_fma_f32 v[18:19], v[150:151], v[18:19], v[138:139]
	v_cvt_pk_bf16_f32 v6, v6, v7
	v_cvt_pk_bf16_f32 v7, v8, v9
	v_pk_mul_f32 v[20:21], v[92:93], v[12:13] op_sel_hi:[1,0]
	v_cvt_pk_bf16_f32 v8, v18, v19
	v_lshl_add_u64 v[18:19], s[0:1], 0, v[10:11]
	v_lshl_add_u64 v[18:19], v[18:19], 0, s[16:17]
	v_pk_fma_f32 v[20:21], v[152:153], v[20:21], v[140:141]
	v_lshl_add_u64 v[18:19], v[18:19], 0, v[22:23]
	v_cvt_pk_bf16_f32 v9, v20, v21
	global_store_dwordx4 v[18:19], v[6:9], off
	v_pk_mul_f32 v[18:19], v[58:59], v[12:13] op_sel_hi:[1,0]
	v_lshl_add_u64 v[10:11], s[8:9], 0, v[10:11]
	v_pk_mul_f32 v[6:7], v[62:63], v[12:13] op_sel_hi:[1,0]
	v_pk_mul_f32 v[8:9], v[64:65], v[12:13] op_sel_hi:[1,0]
	v_pk_mul_f32 v[12:13], v[60:61], v[12:13] op_sel_hi:[1,0]
	v_pk_fma_f32 v[8:9], v[164:165], v[8:9], v[136:137]
	v_pk_fma_f32 v[6:7], v[162:163], v[6:7], v[134:135]
	v_pk_fma_f32 v[12:13], v[168:169], v[12:13], v[132:133]
	v_pk_fma_f32 v[18:19], v[166:167], v[18:19], v[130:131]
	v_cvt_pk_bf16_f32 v6, v6, v7
	v_cvt_pk_bf16_f32 v7, v8, v9
	v_lshl_add_u64 v[10:11], v[10:11], 0, s[16:17]
	v_cvt_pk_bf16_f32 v8, v18, v19
	v_cvt_pk_bf16_f32 v9, v12, v13
	ds_read_b32 v12, v154 offset:704
	v_lshl_add_u64 v[10:11], v[10:11], 0, v[22:23]
	global_store_dwordx4 v[10:11], v[6:9], off
	s_waitcnt lgkmcnt(0)
	v_pk_mul_f32 v[18:19], v[34:35], v[12:13] op_sel_hi:[1,0]
	v_add_u32_e32 v6, 0xb0, v198
	v_ashrrev_i32_e32 v7, 31, v6
	v_lshlrev_b64 v[10:11], 7, v[6:7]
	v_pk_mul_f32 v[6:7], v[38:39], v[12:13] op_sel_hi:[1,0]
	v_pk_mul_f32 v[8:9], v[40:41], v[12:13] op_sel_hi:[1,0]
	v_pk_fma_f32 v[6:7], v[146:147], v[6:7], v[142:143]
	v_pk_fma_f32 v[8:9], v[148:149], v[8:9], v[144:145]
	v_pk_fma_f32 v[18:19], v[150:151], v[18:19], v[138:139]
	v_cvt_pk_bf16_f32 v6, v6, v7
	v_cvt_pk_bf16_f32 v7, v8, v9
	v_pk_mul_f32 v[20:21], v[36:37], v[12:13] op_sel_hi:[1,0]
	v_cvt_pk_bf16_f32 v8, v18, v19
	v_lshl_add_u64 v[18:19], s[0:1], 0, v[10:11]
	v_lshl_add_u64 v[18:19], v[18:19], 0, s[16:17]
	v_lshl_add_u64 v[18:19], v[18:19], 0, v[22:23]
	v_pk_fma_f32 v[20:21], v[152:153], v[20:21], v[140:141]
	v_pk_mul_f32 v[2:3], v[2:3], v[12:13] op_sel_hi:[1,0]
	v_cvt_pk_bf16_f32 v9, v20, v21
	global_store_dwordx4 v[18:19], v[6:9], off
	v_pk_mul_f32 v[4:5], v[4:5], v[12:13] op_sel_hi:[1,0]
	s_mov_b64 s[0:1], -1
	v_pk_mul_f32 v[6:7], v[14:15], v[12:13] op_sel_hi:[1,0]
	v_pk_mul_f32 v[8:9], v[16:17], v[12:13] op_sel_hi:[1,0]
	v_pk_fma_f32 v[6:7], v[162:163], v[6:7], v[134:135]
	v_pk_fma_f32 v[12:13], v[168:169], v[4:5], v[132:133]
	v_pk_fma_f32 v[4:5], v[166:167], v[2:3], v[130:131]
	v_cvt_pk_bf16_f32 v2, v6, v7
	v_lshl_add_u64 v[6:7], s[8:9], 0, v[10:11]
	v_lshl_add_u64 v[6:7], v[6:7], 0, s[16:17]
	v_lshl_add_u64 v[6:7], v[6:7], 0, v[22:23]
	v_pk_fma_f32 v[8:9], v[164:165], v[8:9], v[136:137]
	s_nop 0
	v_cvt_pk_bf16_f32 v3, v8, v9
	v_cvt_pk_bf16_f32 v4, v4, v5
	v_cvt_pk_bf16_f32 v5, v12, v13
	global_store_dwordx4 v[6:7], v[2:5], off
	s_cbranch_vccnz .LBB0_294
	v_readlane_b32 s0, v254, 46
	v_readlane_b32 s1, v254, 47
	s_andn2_b64 vcc, exec, s[0:1]
	s_cbranch_vccnz .LBB0_293
	s_branch .LBB0_293

; #define PG8_WAIT_V(n) asm volatile("s_waitcnt vmcnt(" #n ")" ::: "memory")
; template <class Epi, class Sched, bool ALIGN_EPI = false, bool SP2 = false, bool ABLK = false, bool BBLK = false>
; __device__ __forceinline__ void gemm_phase(PG8_LAS unsigned char* lds, const Gemm g, const Sched& S, const Epi& E) {
;     ...
;     const int tid = tid_, wid = __builtin_amdgcn_readfirstlane(tid >> 6), lane = tid & 63, wr = wid >> 2, wc = wid & 3, fr = lane & 15, fq = lane >> 4;
;     const int K = g.K, nt = K / BK, LDA = g.lda ? g.lda : K, LDB = g.ldb ? g.ldb : K;
;     unsigned voffA[2], voffB[2];
; #pragma unroll
;     for (int i = 0; i < 2; ++i) { int R, C; stage_rc(tid * 16 + i * 8192, R, C); const int Rb = Epi::PERM ? ((R & ~31) + perm32(R & 31)) : R;
;         voffA[i] = ABLK ? (unsigned)(R * BK + C) * 2u : (unsigned)(R * LDA + C) * 2u; voffB[i] = BBLK ? (unsigned)(Rb * BK + C) * 2u : (unsigned)(Rb * LDB + C) * 2u; }
;     const size_t kstep = (size_t)(BK * 2);
;     const size_t hstepa = (size_t)HALF * LDA * 2, hstepb = (size_t)HALF * LDB * 2;
;     const size_t kstepA = ABLK ? (size_t)BM * BK * 2 : kstep, hstepA = ABLK ? (size_t)HALF * BK * 2 : hstepa, tstepA = ABLK ? (size_t)nt * BM * BK * 2 : 2 * hstepa;
;     const size_t kstepB = BBLK ? (size_t)BM * BK * 2 : kstep, hstepB = BBLK ? (size_t)HALF * BK * 2 : hstepb, tstepB = BBLK ? (size_t)nt * BM * BK * 2 : 2 * hstepb;
;     const unsigned ldsw = (unsigned)wid * 1024u;
;     const int aoff = lds_byte(wr * 64 + fr, fq * 8), boff = lds_byte(wc * 32 + fr, fq * 8);
;     ...
;     Unit cur, nxt; int ui = 0;
;     if (!S.next(0, cur)) return;
;     f32x4 acc[2][2][4][2];
; #pragma unroll
;     for (int a = 0; a < 2; ++a)
; #pragma unroll
;         for (int b = 0; b < 2; ++b)
; #pragma unroll
;             for (int m = 0; m < 4; ++m)
; #pragma unroll
;                 for (int n = 0; n < 2; ++n) acc[a][b][m][n] = (f32x4){0.f, 0.f, 0.f, 0.f};
;     bf16x8 At[4][2], B0[2][2], B1[2][2];
;     const char* cA = (const char*)g.A + (size_t)cur.pm * tstepA; const char* cB = (const char*)g.Bt + (size_t)cur.pn * tstepB;
;     S.a_ready(cur);
;     if constexpr (SP2) {
;         PG8_STAGE(PG8_SB(0, 0), cB, voffB); PG8_STAGE(PG8_SB(0, 1), cB + hstepB, voffB); PG8_STAGE(PG8_SA(0, 0), cA, voffA); PG8_STAGE(PG8_SA(0, 1), cA + hstepA, voffA);
;         if (wr == 1) PG8_BAR;
;         PG8_WAIT_V(2); PG8_BAR;
.LBB0_351:
	s_andn2_b64 vcc, exec, s[0:1]
	s_cbranch_vccnz .LBB0_407
	v_bfe_i32 v4, v2, 27, 1
	v_lshlrev_b32_e32 v6, 4, v2
	v_lshrrev_b32_e32 v4, 22, v4
	v_ashrrev_i32_e32 v3, 31, v2
	v_add_u32_e32 v4, v6, v4
	v_lshrrev_b32_e32 v3, 26, v3
	v_and_b32_e32 v4, 0xfffffc00, v4
	v_add_u32_e32 v3, v2, v3
	v_sub_u32_e32 v4, v6, v4
	v_ashrrev_i32_e32 v3, 6, v3
	v_lshrrev_b32_e32 v5, 4, v4
	v_bitop3_b32 v5, v5, v4, 32 bitop3:0x6c
	v_lshlrev_b32_e32 v4, 3, v3
	v_and_b32_e32 v7, -16, v4
	v_ashrrev_i32_e32 v4, 31, v5
	v_lshrrev_b32_e32 v4, 26, v4
	v_add_u32_e32 v8, v5, v4
	v_ashrrev_i32_e32 v4, 6, v8
	v_and_b32_e32 v8, 0xc0, v8
	v_sub_u32_e32 v5, v5, v8
	v_lshlrev_b32_e32 v9, 5, v3
	v_ashrrev_i16_sdwa v5, v232, sext(v5) dst_sel:DWORD dst_unused:UNUSED_PAD src0_sel:DWORD src1_sel:BYTE_0
	v_and_b32_e32 v9, 32, v9
	v_bfe_i32 v5, v5, 0, 16
	v_add_u32_e32 v7, v4, v7
	v_and_b32_e32 v11, 3, v4
	s_mov_b32 s0, 0x1ffffe0
	v_add_lshl_u32 v9, v9, v5, 1
	v_lshlrev_b32_e32 v8, 1, v7
	v_lshrrev_b32_e32 v10, 2, v7
	v_and_or_b32 v11, v7, s0, v11
	v_lshl_add_u32 v178, v7, 7, v9
	v_add_u32_e32 v7, 0x2000, v6
	v_ashrrev_i32_e32 v6, 31, v7
	v_lshrrev_b32_e32 v6, 22, v6
	v_and_b32_e32 v8, 24, v8
	v_and_b32_e32 v10, 4, v10
	v_add_u32_e32 v6, v7, v6
	v_or3_b32 v8, v11, v10, v8
	v_ashrrev_i32_e32 v6, 10, v6
	v_lshl_add_u32 v186, v8, 7, v9
	v_mul_i32_i24_e32 v8, 0x400, v6
	v_sub_u32_e32 v7, v7, v8
	v_lshrrev_b32_e32 v8, 4, v7
	v_bitop3_b32 v8, v8, v7, 32 bitop3:0x6c
	v_lshlrev_b32_e32 v7, 3, v6
	v_and_b32_e32 v9, -16, v7
	v_ashrrev_i32_e32 v7, 31, v8
	v_lshrrev_b32_e32 v7, 26, v7
	v_add_u32_e32 v10, v8, v7
	v_writelane_b32 v254, s82, 45
	s_ashr_i32 s9, s8, 6
	v_ashrrev_i32_e32 v7, 6, v10
	v_add_u32_e32 v9, v7, v9
	v_and_b32_e32 v10, 0xc0, v10
	v_and_b32_e32 v13, 3, v7
	s_ashr_i32 s16, s8, 8
	s_lshl_b32 s81, s9, 10
	s_mul_i32 s1, s30, 0x2c0000
	v_readlane_b32 s4, v254, 38
	v_sub_u32_e32 v8, v8, v10
	v_and_or_b32 v13, v9, s0, v13
	s_mul_hi_i32 s0, s30, 0x2c0000
	s_add_u32 s34, s4, s1
	v_readlane_b32 s1, v254, 39
	v_lshlrev_b32_e32 v11, 5, v6
	v_ashrrev_i16_sdwa v8, v232, sext(v8) dst_sel:DWORD dst_unused:UNUSED_PAD src0_sel:DWORD src1_sel:BYTE_0
	v_lshlrev_b32_e32 v10, 1, v9
	v_lshrrev_b32_e32 v12, 2, v9
	s_addc_u32 s35, s1, s0
	s_add_i32 s83, s81, 0
	v_and_b32_e32 v11, 32, v11
	v_bfe_i32 v8, v8, 0, 16
	v_and_b32_e32 v10, 24, v10
	v_and_b32_e32 v12, 4, v12
	s_add_i32 m0, s83, 0x10000
	v_or3_b32 v10, v13, v12, v10
	v_add_lshl_u32 v11, v11, v8, 1
	global_load_lds_dwordx4 v186, s[34:35]
	s_add_i32 m0, s83, 0x12000
	v_lshl_add_u32 v182, v10, 7, v11
	s_add_u32 s0, s34, 0x4000
	global_load_lds_dwordx4 v182, s[34:35]
	s_addc_u32 s1, s35, 0
	s_add_i32 m0, s83, 0x14000
	s_mul_i32 s3, s28, 0x2c0000
	global_load_lds_dwordx4 v186, s[0:1]
	s_add_i32 m0, s83, 0x16000
	s_mul_hi_i32 s2, s28, 0x2c0000
	global_load_lds_dwordx4 v182, s[0:1]
	v_readlane_b32 s0, v254, 32
	s_add_u32 s0, s0, s3
	v_readlane_b32 s1, v254, 36
	s_addc_u32 s1, s1, s2
	s_add_i32 s84, s83, 0x2000
	s_mov_b32 m0, s83
	s_add_u32 s2, s0, 0x4000
	v_lshl_add_u32 v180, v9, 7, v11
	global_load_lds_dwordx4 v178, s[0:1]
	s_mov_b32 m0, s84
	s_addc_u32 s3, s1, 0
	s_add_i32 s92, s83, 0x4000
	global_load_lds_dwordx4 v180, s[0:1]
	s_mov_b32 m0, s92
	s_add_i32 s93, s83, 0x6000
	global_load_lds_dwordx4 v178, s[2:3]
	s_mov_b32 m0, s93
	s_load_dwordx2 s[12:13], s[6:7], 0x50
	global_load_lds_dwordx4 v180, s[2:3]
	s_load_dwordx2 s[2:3], s[6:7], 0x0
	s_cmp_eq_u32 s16, 1
	s_mov_b32 s82, 0x30000
	s_mov_b32 s80, 0x10000
	s_mov_b32 s75, 0x80000
	s_waitcnt lgkmcnt(0)
	v_writelane_b32 v254, s2, 46
	s_mov_b32 s52, 0x60000
	s_mov_b32 s46, 0x20000
	v_writelane_b32 v254, s3, 47
	s_load_dwordx2 s[2:3], s[6:7], 0x10
	s_waitcnt lgkmcnt(0)
	v_writelane_b32 v254, s2, 48
	s_nop 1
	v_writelane_b32 v254, s3, 49
	s_cselect_b64 s[2:3], -1, 0
	v_writelane_b32 v254, s2, 50
	s_cmp_lg_u32 s16, 1
	s_nop 0
	v_writelane_b32 v254, s3, 51
	s_cbranch_scc1 .LBB0_354
; #define PG8_STAGE(bufoff, gbase, voff) do { _Pragma("unroll") for (int _i = 0; _i < 2; ++_i) \
;         __builtin_amdgcn_global_load_lds((const unsigned*)((const char*)(gbase) + (voff)[_i]), (PG8_LAS unsigned*)(lds + (bufoff) + ldsw + _i * 8192), 16, 0, 0); } while (0)
; #define PG8_WAIT_V(n) asm volatile("s_waitcnt vmcnt(" #n ")" ::: "memory")
; #define PG8_BAR __builtin_amdgcn_s_barrier()
; template <class Epi, class Sched, bool ALIGN_EPI = false, bool SP2 = false, bool ABLK = false, bool BBLK = false>
; __device__ __forceinline__ void gemm_phase(PG8_LAS unsigned char* lds, const Gemm g, const Sched& S, const Epi& E) {
;     ...
;         PG8_WAIT_V(2); PG8_BAR;
;         PG8_STAGE(PG8_SB(1, 0), cB + kstepB, voffB); PG8_STAGE(PG8_SA(1, 0), cA + kstepA, voffA); PG8_STAGE(PG8_SB(1, 1), cB + hstepB + kstepB, voffB);
;         PG8_WAIT_V(6); PG8_BAR;
;     } else {
;         PG8_STAGE(PG8_SB(0, 0), cB, voffB); PG8_STAGE(PG8_SA(0, 0), cA, voffA); PG8_STAGE(PG8_SB(0, 1), cB + hstepB, voffB); PG8_STAGE(PG8_SA(0, 1), cA + hstepA, voffA);
;         if (wr == 1) PG8_BAR;
;         PG8_WAIT_V(4); PG8_BAR;
;         PG8_STAGE(PG8_SB(1, 0), cB + kstepB, voffB); PG8_STAGE(PG8_SA(1, 0), cA + kstepA, voffA); PG8_STAGE(PG8_SB(1, 1), cB + hstepB + kstepB, voffB);
;         PG8_WAIT_V(6); PG8_BAR;
.LBB0_354:
	v_writelane_b32 v254, s72, 52
	s_lshl_b64 s[2:3], s[72:73], 2
	v_mov_b32_e32 v183, v187
	v_writelane_b32 v254, s73, 53
	s_waitcnt vmcnt(2)
	s_barrier
	v_readlane_b32 s4, v254, 26
	v_readlane_b32 s5, v254, 27
	s_add_u32 s94, s4, s2
	s_addc_u32 s95, s5, s3
	v_readlane_b32 s4, v254, 45
	s_add_u32 s96, s4, 0x1500000
	s_addc_u32 s97, s68, 0
	s_add_u32 s42, s4, 0x100000
	s_addc_u32 s43, s68, 0
	s_add_u32 s2, s4, 0xf600000
	s_addc_u32 s3, s68, 0
	s_add_u32 s14, s4, 0xf400000
	s_addc_u32 s15, s68, 0
	s_add_u32 s4, s4, 0x10000
	s_addc_u32 s5, s68, 0
	s_and_b32 s24, s9, 3
	s_lshl_b32 s10, s16, 6
	s_lshl_b32 s18, s16, 13
	s_lshl_b32 s11, s24, 5
	s_lshl_b32 s19, s24, 12
	s_add_u32 s6, s34, 0x8000
	s_addc_u32 s7, s35, 0
	s_add_i32 m0, s83, 0x18000
	v_lshl_add_u64 v[10:11], s[6:7], 0, v[186:187]
	global_load_lds_dwordx4 v[10:11], off
	s_add_i32 m0, s83, 0x1a000
	v_lshl_add_u64 v[10:11], s[6:7], 0, v[182:183]
	s_add_u32 s6, s0, 0x8000
	v_mov_b32_e32 v179, v187
	s_addc_u32 s7, s1, 0
	s_add_i32 s22, s83, 0x8000
	v_mov_b32_e32 v181, v187
	global_load_lds_dwordx4 v[10:11], off
	v_lshl_add_u64 v[10:11], s[6:7], 0, v[178:179]
	s_mov_b32 m0, s22
	s_add_i32 s23, s83, 0xa000
	global_load_lds_dwordx4 v[10:11], off
	v_lshl_add_u64 v[10:11], s[6:7], 0, v[180:181]
	s_add_u32 s6, s34, 0xc000
	s_mov_b32 m0, s23
	s_addc_u32 s7, s35, 0
	global_load_lds_dwordx4 v[10:11], off
	s_add_i32 m0, s83, 0x1c000
	v_lshl_add_u64 v[10:11], s[6:7], 0, v[186:187]
	global_load_lds_dwordx4 v[10:11], off
	v_lshl_add_u64 v[10:11], s[6:7], 0, v[182:183]
	s_add_i32 m0, s83, 0x1e000
	v_bfe_u32 v205, v2, 4, 2
	global_load_lds_dwordx4 v[10:11], off
	v_and_b32_e32 v204, 15, v2
	v_lshlrev_b32_e32 v9, 4, v205
	v_lshlrev_b32_e32 v2, 2, v2
	v_lshl_or_b32 v9, v204, 6, v9
	v_and_b32_e32 v2, 32, v2
	s_cmpk_lt_u32 s8, 0x100
	v_bitop3_b32 v10, v9, s18, v2 bitop3:0xde
	v_bitop3_b32 v206, v9, s19, v2 bitop3:0xde
	s_cselect_b64 s[18:19], -1, 0
	s_lshl_b32 s6, s16, 2
	s_or_b32 s53, s6, s24
	s_lshl_b32 s56, s53, 5
	s_bfe_u32 s20, s9, 0x10001
	s_and_b32 s6, s11, 32
	s_ashr_i32 s60, s50, 31
	s_ashr_i32 s61, s51, 31
	s_cmpk_lg_i32 s50, 0x100
	v_writelane_b32 v254, s68, 54
	s_cselect_b64 s[8:9], -1, 0
	v_writelane_b32 v254, s8, 55
	s_and_b32 s7, s51, 7
	s_lshl_b32 s7, s7, 2
	v_writelane_b32 v254, s9, 56
	v_lshlrev_b32_e32 v2, 10, v3
	v_writelane_b32 v254, s7, 57
	s_bfe_u32 s7, s51, 0x20001
	v_and_b32_e32 v2, 0xfffff800, v2
	s_or_b32 s7, s7, 32
	v_lshl_add_u32 v2, v4, 7, v2
	v_and_b32_e32 v3, 1, v3
	v_writelane_b32 v254, s7, 58
	s_lshl_b32 s7, s51, 4
	v_lshl_or_b32 v2, v3, 6, v2
	s_ashr_i32 s8, s51, 3
	s_and_b32 s7, s7, 16
	v_lshl_add_u32 v184, v5, 1, v2
	v_lshlrev_b32_e32 v2, 10, v6
	v_writelane_b32 v254, s7, 59
	s_and_b32 s7, s8, 3
	v_and_b32_e32 v2, 0xfffff800, v2
	s_waitcnt vmcnt(6)
	v_writelane_b32 v254, s7, 60
	s_lshl_b32 s7, s24, 2
	v_lshl_add_u32 v2, v7, 7, v2
	v_and_b32_e32 v3, 1, v6
	s_add_i32 s65, s7, 0
	v_lshl_or_b32 v2, v3, 6, v2
	s_mov_b32 s21, s17
	s_mov_b32 s47, s8
	s_add_i32 s65, s65, 0x20540
	v_mov_b32_e32 v185, v187
	v_lshl_add_u32 v196, v8, 1, v2
	v_mov_b32_e32 v197, v187
	s_mov_b32 s26, 0
	v_add_u32_e32 v207, 0, v10
	s_lshl_b32 s16, s6, 1
	s_barrier
	s_branch .LBB0_357

; #define PG8_STAGE(bufoff, gbase, voff) do { _Pragma("unroll") for (int _i = 0; _i < 2; ++_i) \
;         __builtin_amdgcn_global_load_lds((const unsigned*)((const char*)(gbase) + (voff)[_i]), (PG8_LAS unsigned*)(lds + (bufoff) + ldsw + _i * 8192), 16, 0, 0); } while (0)
; #define PG8_LDA(dst, b, h) do { _Pragma("unroll") for (int m = 0; m < 4; ++m) _Pragma("unroll") for (int k = 0; k < 2; ++k) dst[m][k] = *(const PG8_LAS bf16x8*)(lds + PG8_SA(b, h) + aoff + m * 2048 + k * 1024); } while (0)
; #define PG8_LDB(dst, b, h) do { _Pragma("unroll") for (int n = 0; n < 2; ++n) _Pragma("unroll") for (int k = 0; k < 2; ++k) dst[n][k] = *(const PG8_LAS bf16x8*)(lds + PG8_SB(b, h) + boff + n * 2048 + k * 1024); } while (0)
; #define PG8_MMA(ai, bj, At, Bt) do { __builtin_amdgcn_s_setprio(1); _Pragma("unroll") for (int m = 0; m < 4; ++m) _Pragma("unroll") for (int n = 0; n < 2; ++n) _Pragma("unroll") for (int k = 0; k < 2; ++k) \
;         acc[ai][bj][m][n] = __builtin_amdgcn_mfma_f32_16x16x32_bf16(Bt[n][k], At[m][k], acc[ai][bj][m][n], 0, 0, 0); __builtin_amdgcn_s_setprio(0); } while (0)
; #define PG8_WAIT_V(n) asm volatile("s_waitcnt vmcnt(" #n ")" ::: "memory")
; #define PG8_WAIT_L(n) asm volatile("s_waitcnt lgkmcnt(" #n ")" ::: "memory")
; #define PG8_BAR __builtin_amdgcn_s_barrier()
; #define PG8_SCHED __builtin_amdgcn_sched_barrier(0)
; template <class Epi, class Sched, bool ALIGN_EPI = false, bool SP2 = false, bool ABLK = false, bool BBLK = false>
; __device__ __forceinline__ void gemm_phase(PG8_LAS unsigned char* lds, const Gemm g, const Sched& S, const Epi& E) {
;     ...
;             PG8_LDB(B0, 0, 0); PG8_LDB(B1, 0, 1); PG8_SCHED; PG8_LDA(At, 0, 0); PG8_STAGE(PG8_SA(1, 1), a1 + hstepA, voffA);
;             PG8_WAIT_V(8); PG8_WAIT_L(0); PG8_BAR; PG8_MMA(0, 0, At, B0); PG8_MMA(0, 1, At, B1); PG8_BAR; PG8_SCHED;
;     ...
;         for (int a = 0; a < 2; ++a)
; #pragma unroll
;             for (int b = 0; b < 2; ++b)
; #pragma unroll
;                 for (int m = 0; m < 4; ++m)
; #pragma unroll
;                     for (int n = 0; n < 2; ++n) acc[a][b][m][n] = (f32x4){0.f, 0.f, 0.f, 0.f};
;         cur = nxt; cA = nA; cB = nB; ++ui;
;         if constexpr (ALIGN_EPI) { if (wr == 1) PG8_BAR; }
.LBB0_366:
	s_add_u32 s0, s0, 0xc000
	s_addc_u32 s1, s1, 0
	s_add_u32 s29, s34, 0x10000
	v_mov_b32_e32 v66, 0
	s_addc_u32 s31, s35, 0
	s_mov_b32 s33, -2
	v_mov_b32_e32 v67, v66
	v_mov_b32_e32 v68, v66
	v_mov_b32_e32 v69, v66
	v_mov_b32_e32 v78, v66
	v_mov_b32_e32 v79, v66
	v_mov_b32_e32 v80, v66
	v_mov_b32_e32 v81, v66
	v_mov_b32_e32 v82, v66
	v_mov_b32_e32 v83, v66
	v_mov_b32_e32 v84, v66
	v_mov_b32_e32 v85, v66
	v_mov_b32_e32 v86, v66
	v_mov_b32_e32 v87, v66
	v_mov_b32_e32 v88, v66
	v_mov_b32_e32 v89, v66
	v_mov_b32_e32 v70, v66
	v_mov_b32_e32 v71, v66
	v_mov_b32_e32 v72, v66
	v_mov_b32_e32 v73, v66
	v_mov_b32_e32 v74, v66
	v_mov_b32_e32 v75, v66
	v_mov_b32_e32 v76, v66
	v_mov_b32_e32 v77, v66
	v_mov_b32_e32 v90, v66
	v_mov_b32_e32 v91, v66
	v_mov_b32_e32 v92, v66
	v_mov_b32_e32 v93, v66
	v_mov_b32_e32 v94, v66
	v_mov_b32_e32 v95, v66
	v_mov_b32_e32 v96, v66
	v_mov_b32_e32 v97, v66
	v_mov_b32_e32 v98, v66
	v_mov_b32_e32 v99, v66
	v_mov_b32_e32 v100, v66
	v_mov_b32_e32 v101, v66
	v_mov_b32_e32 v102, v66
	v_mov_b32_e32 v103, v66
	v_mov_b32_e32 v104, v66
	v_mov_b32_e32 v105, v66
	v_mov_b32_e32 v106, v66
	v_mov_b32_e32 v107, v66
	v_mov_b32_e32 v108, v66
	v_mov_b32_e32 v109, v66
	v_mov_b32_e32 v110, v66
	v_mov_b32_e32 v111, v66
	v_mov_b32_e32 v112, v66
	v_mov_b32_e32 v113, v66
	v_mov_b32_e32 v130, v66
	v_mov_b32_e32 v131, v66
	v_mov_b32_e32 v132, v66
	v_mov_b32_e32 v133, v66
	v_mov_b32_e32 v134, v66
	v_mov_b32_e32 v135, v66
	v_mov_b32_e32 v136, v66
	v_mov_b32_e32 v137, v66
	v_mov_b32_e32 v114, v66
	v_mov_b32_e32 v115, v66
	v_mov_b32_e32 v116, v66
	v_mov_b32_e32 v117, v66
	v_mov_b32_e32 v118, v66
	v_mov_b32_e32 v119, v66
	v_mov_b32_e32 v120, v66
	v_mov_b32_e32 v121, v66
	v_mov_b32_e32 v34, v66
	v_mov_b32_e32 v35, v66
	v_mov_b32_e32 v36, v66
	v_mov_b32_e32 v37, v66
	v_mov_b32_e32 v38, v66
	v_mov_b32_e32 v39, v66
	v_mov_b32_e32 v40, v66
	v_mov_b32_e32 v41, v66
	v_mov_b32_e32 v42, v66
	v_mov_b32_e32 v43, v66
	v_mov_b32_e32 v44, v66
	v_mov_b32_e32 v45, v66
	v_mov_b32_e32 v46, v66
	v_mov_b32_e32 v47, v66
	v_mov_b32_e32 v48, v66
	v_mov_b32_e32 v49, v66
	v_mov_b32_e32 v2, v66
	v_mov_b32_e32 v3, v66
	v_mov_b32_e32 v4, v66
	v_mov_b32_e32 v5, v66
	v_mov_b32_e32 v6, v66
	v_mov_b32_e32 v7, v66
	v_mov_b32_e32 v8, v66
	v_mov_b32_e32 v9, v66
	v_mov_b32_e32 v10, v66
	v_mov_b32_e32 v11, v66
	v_mov_b32_e32 v12, v66
	v_mov_b32_e32 v13, v66
	v_mov_b32_e32 v14, v66
	v_mov_b32_e32 v15, v66
	v_mov_b32_e32 v16, v66
	v_mov_b32_e32 v17, v66
	v_mov_b32_e32 v122, v66
	v_mov_b32_e32 v123, v66
	v_mov_b32_e32 v124, v66
	v_mov_b32_e32 v125, v66
	v_mov_b32_e32 v126, v66
	v_mov_b32_e32 v127, v66
	v_mov_b32_e32 v128, v66
	v_mov_b32_e32 v129, v66
	v_mov_b32_e32 v50, v66
	v_mov_b32_e32 v51, v66
	v_mov_b32_e32 v52, v66
	v_mov_b32_e32 v53, v66
	v_mov_b32_e32 v54, v66
	v_mov_b32_e32 v55, v66
	v_mov_b32_e32 v56, v66
	v_mov_b32_e32 v57, v66
	v_mov_b32_e32 v58, v66
	v_mov_b32_e32 v59, v66
	v_mov_b32_e32 v60, v66
	v_mov_b32_e32 v61, v66
	v_mov_b32_e32 v62, v66
	v_mov_b32_e32 v63, v66
	v_mov_b32_e32 v64, v66
	v_mov_b32_e32 v65, v66
	v_mov_b32_e32 v18, v66
	v_mov_b32_e32 v19, v66
	v_mov_b32_e32 v20, v66
	v_mov_b32_e32 v21, v66
	v_mov_b32_e32 v22, v66
	v_mov_b32_e32 v23, v66
	v_mov_b32_e32 v24, v66
	v_mov_b32_e32 v25, v66
	s_and_b64 vcc, exec, s[18:19]
	s_cbranch_vccnz .Lrb_f1b1
	s_barrier
.Lrb_f1b1:
.LBB0_367:
	s_add_u32 s8, s0, 0x4000
	s_addc_u32 s9, s1, 0
	s_cmpk_eq_i32 s33, 0x54
	s_cselect_b32 s36, s24, s8
	s_cselect_b32 s37, s25, s9
	s_cselect_b32 s34, s26, s29
	s_cselect_b32 s35, s27, s31
	s_add_u32 s8, s36, 0x8000
	s_addc_u32 s9, s37, 0
	s_add_i32 s40, 0, 0x10000
	s_add_i32 s44, 0, 0x14000
	v_add_u32_e32 v142, s40, v206
	v_add_u32_e32 v158, s44, v206
	ds_read_b128 v[26:29], v142
	ds_read_b128 v[30:33], v142 offset:1024
	ds_read_b128 v[138:141], v142 offset:2048
	ds_read_b128 v[142:145], v142 offset:3072
	ds_read_b128 v[146:149], v158
	ds_read_b128 v[150:153], v158 offset:1024
	ds_read_b128 v[154:157], v158 offset:2048
	ds_read_b128 v[158:161], v158 offset:3072
	v_lshl_add_u64 v[202:203], s[0:1], 0, v[184:185]
	s_add_i32 m0, s83, 0xc000
	ds_read_b128 v[162:165], v207
	ds_read_b128 v[166:169], v207 offset:1024
	ds_read_b128 v[170:173], v207 offset:2048
	ds_read_b128 v[174:177], v207 offset:3072
	ds_read_b128 v[198:201], v207 offset:4096
	ds_read_b128 v[208:211], v207 offset:5120
	ds_read_b128 v[212:215], v207 offset:6144
	ds_read_b128 v[216:219], v207 offset:7168
	global_load_lds_dwordx4 v[202:203], off
	v_lshl_add_u64 v[202:203], s[0:1], 0, v[196:197]
	s_add_i32 m0, s83, 0xe000
	s_nop 0
	global_load_lds_dwordx4 v[202:203], off
	s_waitcnt vmcnt(8)
	s_waitcnt lgkmcnt(0)
	s_barrier
; #define PG8_STAGE(bufoff, gbase, voff) do { _Pragma("unroll") for (int _i = 0; _i < 2; ++_i) \
;         __builtin_amdgcn_global_load_lds((const unsigned*)((const char*)(gbase) + (voff)[_i]), (PG8_LAS unsigned*)(lds + (bufoff) + ldsw + _i * 8192), 16, 0, 0); } while (0)
; #define PG8_LDA(dst, b, h) do { _Pragma("unroll") for (int m = 0; m < 4; ++m) _Pragma("unroll") for (int k = 0; k < 2; ++k) dst[m][k] = *(const PG8_LAS bf16x8*)(lds + PG8_SA(b, h) + aoff + m * 2048 + k * 1024); } while (0)
; #define PG8_MMA(ai, bj, At, Bt) do { __builtin_amdgcn_s_setprio(1); _Pragma("unroll") for (int m = 0; m < 4; ++m) _Pragma("unroll") for (int n = 0; n < 2; ++n) _Pragma("unroll") for (int k = 0; k < 2; ++k) \
;         acc[ai][bj][m][n] = __builtin_amdgcn_mfma_f32_16x16x32_bf16(Bt[n][k], At[m][k], acc[ai][bj][m][n], 0, 0, 0); __builtin_amdgcn_s_setprio(0); } while (0)
; #define PG8_WAIT_V(n) asm volatile("s_waitcnt vmcnt(" #n ")" ::: "memory")
; #define PG8_WAIT_L(n) asm volatile("s_waitcnt lgkmcnt(" #n ")" ::: "memory")
; #define PG8_BAR __builtin_amdgcn_s_barrier()
; #define PG8_SCHED __builtin_amdgcn_sched_barrier(0)
; template <class Epi, class Sched, bool ALIGN_EPI = false, bool SP2 = false, bool ABLK = false, bool BBLK = false>
; __device__ __forceinline__ void gemm_phase(PG8_LAS unsigned char* lds, const Gemm g, const Sched& S, const Epi& E) {
;     ...
;             PG8_WAIT_V(8); PG8_WAIT_L(0); PG8_BAR; PG8_MMA(0, 0, At, B0); PG8_MMA(0, 1, At, B1); PG8_BAR; PG8_SCHED;
;             PG8_LDA(At, 0, 1); PG8_STAGE(PG8_SB(0, 0), b2, voffB); PG8_STAGE(PG8_SB(0, 1), b2 + hstepB, voffB); PG8_STAGE(PG8_SA(0, 0), a2, voffA);
;             PG8_WAIT_V(8); PG8_WAIT_L(0); PG8_BAR; PG8_MMA(1, 0, At, B0); PG8_MMA(1, 1, At, B1); PG8_BAR; PG8_SCHED;
	s_setprio 1
	s_waitcnt lgkmcnt(0)
	v_mfma_f32_16x16x32_bf16 v[22:25], v[26:29], v[162:165], v[22:25]
	v_mfma_f32_16x16x32_bf16 v[18:21], v[138:141], v[162:165], v[18:21]
	v_mfma_f32_16x16x32_bf16 v[62:65], v[26:29], v[170:173], v[62:65]
	v_mfma_f32_16x16x32_bf16 v[58:61], v[138:141], v[170:173], v[58:61]
	v_mfma_f32_16x16x32_bf16 v[54:57], v[26:29], v[198:201], v[54:57]
	v_mfma_f32_16x16x32_bf16 v[50:53], v[138:141], v[198:201], v[50:53]
	v_mfma_f32_16x16x32_bf16 v[126:129], v[26:29], v[212:215], v[126:129]
	v_mfma_f32_16x16x32_bf16 v[122:125], v[138:141], v[212:215], v[122:125]
	v_mfma_f32_16x16x32_bf16 v[22:25], v[30:33], v[166:169], v[22:25]
	v_mfma_f32_16x16x32_bf16 v[18:21], v[142:145], v[166:169], v[18:21]
	v_mfma_f32_16x16x32_bf16 v[62:65], v[30:33], v[174:177], v[62:65]
	v_mfma_f32_16x16x32_bf16 v[58:61], v[142:145], v[174:177], v[58:61]
	v_mfma_f32_16x16x32_bf16 v[54:57], v[30:33], v[208:211], v[54:57]
	v_mfma_f32_16x16x32_bf16 v[50:53], v[142:145], v[208:211], v[50:53]
	v_mfma_f32_16x16x32_bf16 v[126:129], v[30:33], v[216:219], v[126:129]
	v_mfma_f32_16x16x32_bf16 v[122:125], v[142:145], v[216:219], v[122:125]
	s_setprio 0
	s_setprio 1
	v_mfma_f32_16x16x32_bf16 v[14:17], v[146:149], v[162:165], v[14:17]
	v_mfma_f32_16x16x32_bf16 v[10:13], v[154:157], v[162:165], v[10:13]
	v_mfma_f32_16x16x32_bf16 v[6:9], v[146:149], v[170:173], v[6:9]
	v_mfma_f32_16x16x32_bf16 v[2:5], v[154:157], v[170:173], v[2:5]
	v_mfma_f32_16x16x32_bf16 v[46:49], v[146:149], v[198:201], v[46:49]
	v_mfma_f32_16x16x32_bf16 v[42:45], v[154:157], v[198:201], v[42:45]
	v_mfma_f32_16x16x32_bf16 v[38:41], v[146:149], v[212:215], v[38:41]
	v_mfma_f32_16x16x32_bf16 v[34:37], v[154:157], v[212:215], v[34:37]
	v_mfma_f32_16x16x32_bf16 v[14:17], v[150:153], v[166:169], v[14:17]
	v_mfma_f32_16x16x32_bf16 v[10:13], v[158:161], v[166:169], v[10:13]
	v_mfma_f32_16x16x32_bf16 v[6:9], v[150:153], v[174:177], v[6:9]
	v_mfma_f32_16x16x32_bf16 v[2:5], v[158:161], v[174:177], v[2:5]
	v_mfma_f32_16x16x32_bf16 v[46:49], v[150:153], v[208:211], v[46:49]
	v_mfma_f32_16x16x32_bf16 v[42:45], v[158:161], v[208:211], v[42:45]
	v_mfma_f32_16x16x32_bf16 v[38:41], v[150:153], v[216:219], v[38:41]
	v_mfma_f32_16x16x32_bf16 v[34:37], v[158:161], v[216:219], v[34:37]
	s_setprio 0
	s_barrier
	s_add_i32 s40, s40, s81
	v_lshl_add_u64 v[202:203], s[34:35], 0, v[186:187]
	s_mov_b32 m0, s40
	ds_read_b128 v[162:165], v207 offset:16384
	ds_read_b128 v[166:169], v207 offset:17408
	ds_read_b128 v[170:173], v207 offset:18432
	ds_read_b128 v[174:177], v207 offset:19456
	ds_read_b128 v[198:201], v207 offset:20480
	ds_read_b128 v[208:211], v207 offset:21504
	ds_read_b128 v[212:215], v207 offset:22528
	ds_read_b128 v[216:219], v207 offset:23552
	global_load_lds_dwordx4 v[202:203], off
	s_add_i32 m0, s40, 0x2000
	s_add_u32 s40, s34, 0x4000
	v_lshl_add_u64 v[202:203], s[34:35], 0, v[182:183]
	s_addc_u32 s41, s35, 0
	s_add_i32 s44, s44, s81
	global_load_lds_dwordx4 v[202:203], off
	v_lshl_add_u64 v[202:203], s[40:41], 0, v[186:187]
	s_mov_b32 m0, s44
	s_nop 0
	global_load_lds_dwordx4 v[202:203], off
	v_lshl_add_u64 v[202:203], s[40:41], 0, v[182:183]
	s_add_i32 m0, s44, 0x2000
	s_nop 0
	global_load_lds_dwordx4 v[202:203], off
	v_lshl_add_u64 v[202:203], s[36:37], 0, v[178:179]
	s_mov_b32 m0, s83
	s_nop 0
	global_load_lds_dwordx4 v[202:203], off
	v_lshl_add_u64 v[202:203], s[36:37], 0, v[180:181]
	s_mov_b32 m0, s84
	s_nop 0
	global_load_lds_dwordx4 v[202:203], off
	s_waitcnt vmcnt(8)
	s_waitcnt lgkmcnt(0)
	s_barrier
	s_setprio 1
	s_waitcnt lgkmcnt(0)
	v_mfma_f32_16x16x32_bf16 v[118:121], v[26:29], v[162:165], v[118:121]
	v_mfma_f32_16x16x32_bf16 v[114:117], v[138:141], v[162:165], v[114:117]
	v_mfma_f32_16x16x32_bf16 v[134:137], v[26:29], v[170:173], v[134:137]
	v_mfma_f32_16x16x32_bf16 v[130:133], v[138:141], v[170:173], v[130:133]
	v_mfma_f32_16x16x32_bf16 v[110:113], v[26:29], v[198:201], v[110:113]
	v_mfma_f32_16x16x32_bf16 v[106:109], v[138:141], v[198:201], v[106:109]
	v_mfma_f32_16x16x32_bf16 v[26:29], v[26:29], v[212:215], v[102:105]
	v_mfma_f32_16x16x32_bf16 v[118:121], v[30:33], v[166:169], v[118:121]
	v_mfma_f32_16x16x32_bf16 v[114:117], v[142:145], v[166:169], v[114:117]
	v_mfma_f32_16x16x32_bf16 v[134:137], v[30:33], v[174:177], v[134:137]
	v_mfma_f32_16x16x32_bf16 v[130:133], v[142:145], v[174:177], v[130:133]
	v_mfma_f32_16x16x32_bf16 v[110:113], v[30:33], v[208:211], v[110:113]
	v_mfma_f32_16x16x32_bf16 v[106:109], v[142:145], v[208:211], v[106:109]
	v_mfma_f32_16x16x32_bf16 v[26:29], v[30:33], v[216:219], v[26:29]
	v_mfma_f32_16x16x32_bf16 v[30:33], v[138:141], v[212:215], v[98:101]
	v_mfma_f32_16x16x32_bf16 v[30:33], v[142:145], v[216:219], v[30:33]
	s_setprio 0
	s_setprio 1
	v_mfma_f32_16x16x32_bf16 v[94:97], v[146:149], v[162:165], v[94:97]
	v_mfma_f32_16x16x32_bf16 v[90:93], v[154:157], v[162:165], v[90:93]
	v_mfma_f32_16x16x32_bf16 v[74:77], v[146:149], v[170:173], v[74:77]
	v_mfma_f32_16x16x32_bf16 v[70:73], v[154:157], v[170:173], v[70:73]
	v_mfma_f32_16x16x32_bf16 v[86:89], v[146:149], v[198:201], v[86:89]
	v_mfma_f32_16x16x32_bf16 v[82:85], v[154:157], v[198:201], v[82:85]
	v_mfma_f32_16x16x32_bf16 v[78:81], v[146:149], v[212:215], v[78:81]
	v_mfma_f32_16x16x32_bf16 v[66:69], v[154:157], v[212:215], v[66:69]
	v_mfma_f32_16x16x32_bf16 v[94:97], v[150:153], v[166:169], v[94:97]
	v_mfma_f32_16x16x32_bf16 v[90:93], v[158:161], v[166:169], v[90:93]
	v_mfma_f32_16x16x32_bf16 v[74:77], v[150:153], v[174:177], v[74:77]
	v_mfma_f32_16x16x32_bf16 v[70:73], v[158:161], v[174:177], v[70:73]
	v_mfma_f32_16x16x32_bf16 v[86:89], v[150:153], v[208:211], v[86:89]
	v_mfma_f32_16x16x32_bf16 v[82:85], v[158:161], v[208:211], v[82:85]
	v_mfma_f32_16x16x32_bf16 v[78:81], v[150:153], v[216:219], v[78:81]
	v_mfma_f32_16x16x32_bf16 v[66:69], v[158:161], v[216:219], v[66:69]
	s_setprio 0
	s_barrier
; #define PG8_STAGE(bufoff, gbase, voff) do { _Pragma("unroll") for (int _i = 0; _i < 2; ++_i) \
;         __builtin_amdgcn_global_load_lds((const unsigned*)((const char*)(gbase) + (voff)[_i]), (PG8_LAS unsigned*)(lds + (bufoff) + ldsw + _i * 8192), 16, 0, 0); } while (0)
; #define PG8_LDA(dst, b, h) do { _Pragma("unroll") for (int m = 0; m < 4; ++m) _Pragma("unroll") for (int k = 0; k < 2; ++k) dst[m][k] = *(const PG8_LAS bf16x8*)(lds + PG8_SA(b, h) + aoff + m * 2048 + k * 1024); } while (0)
; #define PG8_LDB(dst, b, h) do { _Pragma("unroll") for (int n = 0; n < 2; ++n) _Pragma("unroll") for (int k = 0; k < 2; ++k) dst[n][k] = *(const PG8_LAS bf16x8*)(lds + PG8_SB(b, h) + boff + n * 2048 + k * 1024); } while (0)
; #define PG8_MMA(ai, bj, At, Bt) do { __builtin_amdgcn_s_setprio(1); _Pragma("unroll") for (int m = 0; m < 4; ++m) _Pragma("unroll") for (int n = 0; n < 2; ++n) _Pragma("unroll") for (int k = 0; k < 2; ++k) \
;         acc[ai][bj][m][n] = __builtin_amdgcn_mfma_f32_16x16x32_bf16(Bt[n][k], At[m][k], acc[ai][bj][m][n], 0, 0, 0); __builtin_amdgcn_s_setprio(0); } while (0)
; #define PG8_WAIT_V(n) asm volatile("s_waitcnt vmcnt(" #n ")" ::: "memory")
; #define PG8_WAIT_L(n) asm volatile("s_waitcnt lgkmcnt(" #n ")" ::: "memory")
; #define PG8_BAR __builtin_amdgcn_s_barrier()
; #define PG8_SCHED __builtin_amdgcn_sched_barrier(0)
; template <class Epi, class Sched, bool ALIGN_EPI = false, bool SP2 = false, bool ABLK = false, bool BBLK = false>
; __device__ __forceinline__ void gemm_phase(PG8_LAS unsigned char* lds, const Gemm g, const Sched& S, const Epi& E) {
;     ...
;             PG8_LDB(B0, 1, 0); PG8_LDB(B1, 1, 1); PG8_SCHED; PG8_LDA(At, 1, 0); PG8_STAGE(PG8_SA(0, 1), a2 + hstepA, voffA);
;             PG8_WAIT_V(8); PG8_WAIT_L(0); PG8_BAR; PG8_MMA(0, 0, At, B0); PG8_MMA(0, 1, At, B1); PG8_BAR; PG8_SCHED;
	s_add_i32 s40, 0, 0x18000
	s_add_i32 s41, 0, 0x1c000
	v_add_u32_e32 v142, s40, v206
	v_add_u32_e32 v158, s41, v206
	ds_read_b128 v[98:101], v142
	ds_read_b128 v[102:105], v142 offset:1024
	ds_read_b128 v[138:141], v142 offset:2048
	ds_read_b128 v[142:145], v142 offset:3072
	ds_read_b128 v[146:149], v158
	ds_read_b128 v[150:153], v158 offset:1024
	ds_read_b128 v[154:157], v158 offset:2048
	ds_read_b128 v[158:161], v158 offset:3072
	s_add_u32 s36, s36, 0x4000
	s_addc_u32 s37, s37, 0
	s_mov_b32 m0, s92
	v_lshl_add_u64 v[202:203], s[36:37], 0, v[178:179]
	ds_read_b128 v[162:165], v207 offset:32768
	ds_read_b128 v[166:169], v207 offset:33792
	ds_read_b128 v[170:173], v207 offset:34816
	ds_read_b128 v[174:177], v207 offset:35840
	ds_read_b128 v[198:201], v207 offset:36864
	ds_read_b128 v[208:211], v207 offset:37888
	ds_read_b128 v[212:215], v207 offset:38912
	ds_read_b128 v[216:219], v207 offset:39936
	global_load_lds_dwordx4 v[202:203], off
	v_lshl_add_u64 v[202:203], s[36:37], 0, v[180:181]
	s_mov_b32 m0, s93
	s_nop 0
	global_load_lds_dwordx4 v[202:203], off
	s_waitcnt vmcnt(8)
	s_waitcnt lgkmcnt(0)
	s_barrier
	s_setprio 1
	s_waitcnt lgkmcnt(0)
	v_mfma_f32_16x16x32_bf16 v[22:25], v[98:101], v[162:165], v[22:25]
	v_mfma_f32_16x16x32_bf16 v[18:21], v[138:141], v[162:165], v[18:21]
	v_mfma_f32_16x16x32_bf16 v[62:65], v[98:101], v[170:173], v[62:65]
	v_mfma_f32_16x16x32_bf16 v[58:61], v[138:141], v[170:173], v[58:61]
	v_mfma_f32_16x16x32_bf16 v[54:57], v[98:101], v[198:201], v[54:57]
	v_mfma_f32_16x16x32_bf16 v[50:53], v[138:141], v[198:201], v[50:53]
	v_mfma_f32_16x16x32_bf16 v[126:129], v[98:101], v[212:215], v[126:129]
	v_mfma_f32_16x16x32_bf16 v[122:125], v[138:141], v[212:215], v[122:125]
	v_mfma_f32_16x16x32_bf16 v[22:25], v[102:105], v[166:169], v[22:25]
	v_mfma_f32_16x16x32_bf16 v[18:21], v[142:145], v[166:169], v[18:21]
	v_mfma_f32_16x16x32_bf16 v[62:65], v[102:105], v[174:177], v[62:65]
	v_mfma_f32_16x16x32_bf16 v[58:61], v[142:145], v[174:177], v[58:61]
	v_mfma_f32_16x16x32_bf16 v[54:57], v[102:105], v[208:211], v[54:57]
	v_mfma_f32_16x16x32_bf16 v[50:53], v[142:145], v[208:211], v[50:53]
	v_mfma_f32_16x16x32_bf16 v[126:129], v[102:105], v[216:219], v[126:129]
	v_mfma_f32_16x16x32_bf16 v[122:125], v[142:145], v[216:219], v[122:125]
	s_setprio 0
	s_setprio 1
	v_mfma_f32_16x16x32_bf16 v[14:17], v[146:149], v[162:165], v[14:17]
	v_mfma_f32_16x16x32_bf16 v[10:13], v[154:157], v[162:165], v[10:13]
	v_mfma_f32_16x16x32_bf16 v[6:9], v[146:149], v[170:173], v[6:9]
	v_mfma_f32_16x16x32_bf16 v[2:5], v[154:157], v[170:173], v[2:5]
	v_mfma_f32_16x16x32_bf16 v[46:49], v[146:149], v[198:201], v[46:49]
	v_mfma_f32_16x16x32_bf16 v[42:45], v[154:157], v[198:201], v[42:45]
	v_mfma_f32_16x16x32_bf16 v[38:41], v[146:149], v[212:215], v[38:41]
	v_mfma_f32_16x16x32_bf16 v[34:37], v[154:157], v[212:215], v[34:37]
	v_mfma_f32_16x16x32_bf16 v[14:17], v[150:153], v[166:169], v[14:17]
	v_mfma_f32_16x16x32_bf16 v[10:13], v[158:161], v[166:169], v[10:13]
	v_mfma_f32_16x16x32_bf16 v[6:9], v[150:153], v[174:177], v[6:9]
	v_mfma_f32_16x16x32_bf16 v[2:5], v[158:161], v[174:177], v[2:5]
	v_mfma_f32_16x16x32_bf16 v[46:49], v[150:153], v[208:211], v[46:49]
	v_mfma_f32_16x16x32_bf16 v[42:45], v[158:161], v[208:211], v[42:45]
	v_mfma_f32_16x16x32_bf16 v[38:41], v[150:153], v[216:219], v[38:41]
	v_mfma_f32_16x16x32_bf16 v[34:37], v[158:161], v[216:219], v[34:37]
	s_setprio 0
	s_barrier
; #define PG8_STAGE(bufoff, gbase, voff) do { _Pragma("unroll") for (int _i = 0; _i < 2; ++_i) \
;         __builtin_amdgcn_global_load_lds((const unsigned*)((const char*)(gbase) + (voff)[_i]), (PG8_LAS unsigned*)(lds + (bufoff) + ldsw + _i * 8192), 16, 0, 0); } while (0)
; #define PG8_LDA(dst, b, h) do { _Pragma("unroll") for (int m = 0; m < 4; ++m) _Pragma("unroll") for (int k = 0; k < 2; ++k) dst[m][k] = *(const PG8_LAS bf16x8*)(lds + PG8_SA(b, h) + aoff + m * 2048 + k * 1024); } while (0)
; template <class Epi, class Sched, bool ALIGN_EPI = false, bool SP2 = false, bool ABLK = false, bool BBLK = false>
; __device__ __forceinline__ void gemm_phase(PG8_LAS unsigned char* lds, const Gemm g, const Sched& S, const Epi& E) {
;     ...
;             PG8_LDA(At, 1, 1); PG8_STAGE(PG8_SB(1, 0), b3, voffB); PG8_STAGE(PG8_SB(1, 1), b3 + hstepB, voffB); PG8_STAGE(PG8_SA(1, 0), a3, voffA);
;             PG8_WAIT_V(8); PG8_WAIT_L(0); PG8_BAR; PG8_MMA(1, 0, At, B0); PG8_MMA(1, 1, At, B1); PG8_BAR; PG8_SCHED;
;             } else {
;             PG8_LDB(B0, 0, 0); PG8_SCHED; PG8_LDA(At, 0, 0); PG8_STAGE(PG8_SA(1, 1), a1 + hstepA, voffA);
;             PG8_WAIT_L(8); PG8_BAR; PG8_WAIT_L(0); PG8_MMA(0, 0, At, B0); PG8_BAR; PG8_SCHED;
;             PG8_LDB(B1, 0, 1); PG8_STAGE(PG8_SB(0, 0), b2, voffB);
;             PG8_BAR; PG8_WAIT_L(0); PG8_MMA(0, 1, At, B1); PG8_BAR;
;             PG8_LDA(At, 0, 1); PG8_STAGE(PG8_SA(0, 0), a2, voffA);
;             PG8_BAR; PG8_WAIT_L(0); PG8_MMA(1, 0, At, B0); PG8_BAR; PG8_SCHED;
;             PG8_STAGE(PG8_SB(0, 1), b2 + hstepB, voffB);
;             PG8_WAIT_V(6); PG8_BAR; PG8_MMA(1, 1, At, B1); PG8_BAR;
;             PG8_LDB(B0, 1, 0); PG8_SCHED; PG8_LDA(At, 1, 0); PG8_STAGE(PG8_SA(0, 1), a2 + hstepA, voffA);
;             PG8_WAIT_L(8); PG8_BAR; PG8_WAIT_L(0); PG8_MMA(0, 0, At, B0); PG8_BAR; PG8_SCHED;
;             PG8_LDB(B1, 1, 1); PG8_STAGE(PG8_SB(1, 0), b3, voffB);
;             PG8_BAR; PG8_WAIT_L(0); PG8_MMA(0, 1, At, B1); PG8_BAR;
;             PG8_LDA(At, 1, 1); PG8_STAGE(PG8_SA(1, 0), a3, voffA);
;             PG8_BAR; PG8_WAIT_L(0); PG8_MMA(1, 0, At, B0); PG8_BAR; PG8_SCHED;
;             PG8_STAGE(PG8_SB(1, 1), b3 + hstepB, voffB);
;             PG8_WAIT_V(6); PG8_BAR; PG8_MMA(1, 1, At, B1); PG8_BAR;
;             }
;         }
;         if constexpr (ALIGN_EPI) { if (wr == 0) PG8_BAR; }
	s_add_u32 s36, s34, 0x8000
	s_addc_u32 s37, s35, 0
	s_add_i32 s40, s40, s81
	v_lshl_add_u64 v[202:203], s[36:37], 0, v[186:187]
	s_mov_b32 m0, s40
	ds_read_b128 v[162:165], v207 offset:49152
	ds_read_b128 v[166:169], v207 offset:50176
	ds_read_b128 v[170:173], v207 offset:51200
	ds_read_b128 v[174:177], v207 offset:52224
	ds_read_b128 v[198:201], v207 offset:53248
	ds_read_b128 v[208:211], v207 offset:54272
	ds_read_b128 v[212:215], v207 offset:55296
	ds_read_b128 v[216:219], v207 offset:56320
	global_load_lds_dwordx4 v[202:203], off
	s_add_i32 m0, s40, 0x2000
	s_add_u32 s34, s34, 0xc000
	v_lshl_add_u64 v[202:203], s[36:37], 0, v[182:183]
	s_addc_u32 s35, s35, 0
	s_add_i32 s36, s41, s81
	global_load_lds_dwordx4 v[202:203], off
	v_lshl_add_u64 v[202:203], s[34:35], 0, v[186:187]
	s_mov_b32 m0, s36
	s_nop 0
	global_load_lds_dwordx4 v[202:203], off
	v_lshl_add_u64 v[202:203], s[34:35], 0, v[182:183]
	s_add_i32 m0, s36, 0x2000
	s_nop 0
	global_load_lds_dwordx4 v[202:203], off
	v_lshl_add_u64 v[202:203], s[8:9], 0, v[178:179]
	s_mov_b32 m0, s22
	s_nop 0
	global_load_lds_dwordx4 v[202:203], off
	v_lshl_add_u64 v[202:203], s[8:9], 0, v[180:181]
	s_mov_b32 m0, s23
	s_nop 0
	global_load_lds_dwordx4 v[202:203], off
	s_waitcnt vmcnt(8)
	s_waitcnt lgkmcnt(0)
	s_barrier
	s_setprio 1
	s_waitcnt lgkmcnt(0)
	v_mfma_f32_16x16x32_bf16 v[118:121], v[98:101], v[162:165], v[118:121]
	v_mfma_f32_16x16x32_bf16 v[134:137], v[98:101], v[170:173], v[134:137]
	v_mfma_f32_16x16x32_bf16 v[110:113], v[98:101], v[198:201], v[110:113]
	v_mfma_f32_16x16x32_bf16 v[26:29], v[98:101], v[212:215], v[26:29]
	v_mfma_f32_16x16x32_bf16 v[118:121], v[102:105], v[166:169], v[118:121]
	v_mfma_f32_16x16x32_bf16 v[114:117], v[138:141], v[162:165], v[114:117]
	v_mfma_f32_16x16x32_bf16 v[134:137], v[102:105], v[174:177], v[134:137]
	v_mfma_f32_16x16x32_bf16 v[130:133], v[138:141], v[170:173], v[130:133]
	v_mfma_f32_16x16x32_bf16 v[110:113], v[102:105], v[208:211], v[110:113]
	v_mfma_f32_16x16x32_bf16 v[106:109], v[138:141], v[198:201], v[106:109]
	v_mfma_f32_16x16x32_bf16 v[102:105], v[102:105], v[216:219], v[26:29]
	v_mfma_f32_16x16x32_bf16 v[26:29], v[138:141], v[212:215], v[30:33]
	v_mfma_f32_16x16x32_bf16 v[114:117], v[142:145], v[166:169], v[114:117]
	v_mfma_f32_16x16x32_bf16 v[130:133], v[142:145], v[174:177], v[130:133]
	v_mfma_f32_16x16x32_bf16 v[106:109], v[142:145], v[208:211], v[106:109]
	v_mfma_f32_16x16x32_bf16 v[98:101], v[142:145], v[216:219], v[26:29]
	s_setprio 0
	s_setprio 1
	v_mfma_f32_16x16x32_bf16 v[26:29], v[146:149], v[162:165], v[94:97]
	v_mfma_f32_16x16x32_bf16 v[94:97], v[150:153], v[166:169], v[26:29]
	v_mfma_f32_16x16x32_bf16 v[26:29], v[154:157], v[162:165], v[90:93]
	v_mfma_f32_16x16x32_bf16 v[90:93], v[158:161], v[166:169], v[26:29]
	v_mfma_f32_16x16x32_bf16 v[26:29], v[146:149], v[170:173], v[74:77]
	v_mfma_f32_16x16x32_bf16 v[74:77], v[150:153], v[174:177], v[26:29]
	v_mfma_f32_16x16x32_bf16 v[26:29], v[154:157], v[170:173], v[70:73]
	v_mfma_f32_16x16x32_bf16 v[70:73], v[158:161], v[174:177], v[26:29]
	v_mfma_f32_16x16x32_bf16 v[26:29], v[146:149], v[198:201], v[86:89]
	v_mfma_f32_16x16x32_bf16 v[86:89], v[150:153], v[208:211], v[26:29]
	v_mfma_f32_16x16x32_bf16 v[26:29], v[154:157], v[198:201], v[82:85]
	v_mfma_f32_16x16x32_bf16 v[82:85], v[158:161], v[208:211], v[26:29]
	v_mfma_f32_16x16x32_bf16 v[26:29], v[146:149], v[212:215], v[78:81]
	v_mfma_f32_16x16x32_bf16 v[78:81], v[150:153], v[216:219], v[26:29]
	v_mfma_f32_16x16x32_bf16 v[26:29], v[154:157], v[212:215], v[66:69]
	v_mfma_f32_16x16x32_bf16 v[66:69], v[158:161], v[216:219], v[26:29]
	s_setprio 0
	s_barrier
	s_add_i32 s33, s33, 2
	s_add_u32 s0, s0, 0x10000
	s_addc_u32 s1, s1, 0
	s_add_u32 s29, s29, 0x10000
	s_addc_u32 s31, s31, 0
	s_cmpk_gt_u32 s33, 0x55
	s_cbranch_scc0 .LBB0_367
	s_and_b64 vcc, exec, s[18:19]
	s_cbranch_vccz .LBB0_370
	s_barrier

; __device__ __forceinline__ u32x4 pack8(const f32x4 v0, const f32x4 v1) { u32x4 w; w.x = cvt_pk_bf16(v0[0], v0[1]); w.y = cvt_pk_bf16(v0[2], v0[3]); w.z = cvt_pk_bf16(v1[0], v1[1]); w.w = cvt_pk_bf16(v1[2], v1[3]); return w; }
;     __device__ __forceinline__ void operator()(f32x4 (&acc)[2][2][4][2], const Unit& u, int wr, int wc, int fr_, int fq_) const {
;     ...
;             for (int n = 0; n < 2; ++n) { const int col = col0 + bj * HALF + 4 * n; const f32x4 g = *(const f32x4*)(gain + col);
;                 if (FINAL) { av[bj][n] = g; sv[bj][n] = (f32x4){0.f, 0.f, 0.f, 0.f}; }
;                 else { const float* mp = nmod + (size_t)rb * NMODC; av[bj][n] = g * (*(const f32x4*)(mp + isc * DM + col) + 1.0f); sv[bj][n] = *(const f32x4*)(mp + ish * DM + col); } }
;         if (wid == 0) { if (lane == 0) { unsigned sp = 0u; while (__hip_atomic_load(cnt + 16 * u.pm, __ATOMIC_RELAXED, __HIP_MEMORY_SCOPE_AGENT) < 64u) { __builtin_amdgcn_s_sleep(1); if (++sp > (1u << 17)) break; } } }
;         asm volatile("s_waitcnt lgkmcnt(0)" ::: "memory"); __builtin_amdgcn_s_barrier(); asm volatile("" ::: "memory");
;         if (lane < 32) { const float* slot = xbuf + ((size_t)u.pm * BM + row) * 8; float t8[8];
; #pragma unroll
;             for (int t = 0; t < 8; ++t) t8[t] = __hip_atomic_load(slot + t, __ATOMIC_RELAXED, __HIP_MEMORY_SCOPE_AGENT);
;             const float tot = ((t8[0] + t8[1]) + (t8[2] + t8[3])) + ((t8[4] + t8[5]) + (t8[6] + t8[7]));
;             S[row] = __builtin_amdgcn_rsqf(tot * (1.0f / DM) + 1e-6f); }
;         asm volatile("s_waitcnt lgkmcnt(0)" ::: "memory"); __builtin_amdgcn_s_barrier(); asm volatile("" ::: "memory");
; #pragma unroll
;         for (int ai = 0; ai < 2; ++ai)
; #pragma unroll
;             for (int m = 0; m < 4; ++m) { const int r = ai * HALF + wr * 64 + m * 16 + fr; const float rs = S[r];
; #pragma unroll
;                 for (int bj = 0; bj < 2; ++bj) { const f32x4 y0 = acc[ai][bj][m][0] * rs * av[bj][0] + sv[bj][0], y1 = acc[ai][bj][m][1] * rs * av[bj][1] + sv[bj][1];
;                     if (FINAL) { float* o = OUTF + ((size_t)u.pm * BM + r) * DM + col0 + bj * HALF; *(f32x4*)o = y0; *(f32x4*)(o + 4) = y1; }
;                     else *(u32x4*)(XN + (((size_t)u.pm * (DM / BK) + u.pn * 4 + bj * 2 + (wc >> 1)) * BM + r) * BK + (wc & 1) * 32 + 8 * fq) = pack8(y0, y1); } }
.LBB0_403:
	s_or_b64 exec, exec, s[0:1]
	s_waitcnt vmcnt(7)
	v_pk_add_f32 v[154:155], v[154:155], 1.0 op_sel_hi:[1,0]
	v_pk_add_f32 v[156:157], v[156:157], 1.0 op_sel_hi:[1,0]
	v_pk_mul_f32 v[146:147], v[146:147], v[154:155]
	v_lshl_add_u32 v154, v198, 2, 0
	s_waitcnt lgkmcnt(0)
	s_barrier
	s_lshl_b32 s8, s30, 2
	v_add_u32_e32 v154, 0x21540, v154
	v_pk_mul_f32 v[148:149], v[148:149], v[156:157]
	s_lshl_b64 s[0:1], s[28:29], 5
	s_ashr_i32 s9, s8, 31
	ds_read_b32 v156, v154
	s_add_u32 s0, s0, s8
	s_addc_u32 s1, s1, s9
	s_or_b64 s[0:1], s[0:1], s[20:21]
	s_waitcnt vmcnt(5)
	v_pk_add_f32 v[158:159], v[158:159], 1.0 op_sel_hi:[1,0]
	s_lshl_b64 s[0:1], s[0:1], 15
	v_pk_add_f32 v[160:161], v[160:161], 1.0 op_sel_hi:[1,0]
	v_pk_mul_f32 v[150:151], v[150:151], v[158:159]
	s_waitcnt lgkmcnt(0)
	v_pk_mul_f32 v[30:31], v[30:31], v[156:157] op_sel_hi:[1,0]
	v_pk_mul_f32 v[26:27], v[26:27], v[156:157] op_sel_hi:[1,0]
	s_add_u32 s0, s2, s0
	v_pk_mul_f32 v[152:153], v[152:153], v[160:161]
	v_lshlrev_b64 v[158:159], 7, v[198:199]
	v_pk_mul_f32 v[32:33], v[32:33], v[156:157] op_sel_hi:[1,0]
	s_waitcnt vmcnt(3)
	v_pk_fma_f32 v[30:31], v[146:147], v[30:31], v[142:143]
	v_pk_mul_f32 v[28:29], v[28:29], v[156:157] op_sel_hi:[1,0]
	s_waitcnt vmcnt(1)
	v_pk_fma_f32 v[26:27], v[150:151], v[26:27], v[138:139]
	s_addc_u32 s1, s3, s1
	v_ashrrev_i32_e32 v201, 31, v200
	v_pk_fma_f32 v[32:33], v[148:149], v[32:33], v[144:145]
	v_pk_fma_f32 v[160:161], v[152:153], v[28:29], v[140:141]
	v_cvt_pk_bf16_f32 v28, v30, v31
	v_cvt_pk_bf16_f32 v29, v32, v33
	v_cvt_pk_bf16_f32 v30, v26, v27
	v_lshl_add_u64 v[26:27], s[0:1], 0, v[158:159]
	v_pk_add_f32 v[176:177], v[176:177], 1.0 op_sel_hi:[1,0]
	v_pk_add_f32 v[174:175], v[174:175], 1.0 op_sel_hi:[1,0]
	v_pk_add_f32 v[172:173], v[172:173], 1.0 op_sel_hi:[1,0]
	v_lshl_add_u64 v[32:33], v[26:27], 0, s[16:17]
	v_lshlrev_b64 v[26:27], 1, v[200:201]
	v_pk_mul_f32 v[166:167], v[166:167], v[174:175]
	v_pk_mul_f32 v[168:169], v[168:169], v[176:177]
	v_pk_add_f32 v[170:171], v[170:171], 1.0 op_sel_hi:[1,0]
	v_pk_mul_f32 v[164:165], v[164:165], v[172:173]
	v_lshl_add_u64 v[32:33], v[32:33], 0, v[26:27]
	v_pk_mul_f32 v[24:25], v[24:25], v[156:157] op_sel_hi:[1,0]
	v_pk_mul_f32 v[18:19], v[18:19], v[156:157] op_sel_hi:[1,0]
	v_pk_mul_f32 v[20:21], v[20:21], v[156:157] op_sel_hi:[1,0]
	v_pk_mul_f32 v[162:163], v[162:163], v[170:171]
	v_cvt_pk_bf16_f32 v31, v160, v161
	global_store_dwordx4 v[32:33], v[28:31], off
	v_pk_mul_f32 v[22:23], v[22:23], v[156:157] op_sel_hi:[1,0]
	s_waitcnt vmcnt(1)
	v_pk_fma_f32 v[24:25], v[164:165], v[24:25], v[104:105]
	v_pk_fma_f32 v[28:29], v[168:169], v[20:21], v[100:101]
	v_pk_fma_f32 v[20:21], v[166:167], v[18:19], v[98:99]
	s_add_u32 s8, s0, 0x10000
	v_pk_fma_f32 v[22:23], v[162:163], v[22:23], v[102:103]
	s_addc_u32 s9, s1, 0
	v_cvt_pk_bf16_f32 v18, v22, v23
	v_cvt_pk_bf16_f32 v19, v24, v25
	v_cvt_pk_bf16_f32 v20, v20, v21
	v_cvt_pk_bf16_f32 v21, v28, v29
	ds_read_b32 v24, v154 offset:64
	v_lshl_add_u64 v[22:23], s[8:9], 0, v[158:159]
	v_lshl_add_u64 v[22:23], v[22:23], 0, s[16:17]
	v_lshl_add_u64 v[22:23], v[22:23], 0, v[26:27]
	global_store_dwordx4 v[22:23], v[18:21], off
	s_waitcnt lgkmcnt(0)
	v_pk_mul_f32 v[14:15], v[14:15], v[24:25] op_sel_hi:[1,0]
	v_pk_mul_f32 v[10:11], v[10:11], v[24:25] op_sel_hi:[1,0]
	v_add_u32_e32 v18, 16, v198
	v_ashrrev_i32_e32 v19, 31, v18
	v_lshlrev_b64 v[18:19], 7, v[18:19]
	v_pk_fma_f32 v[14:15], v[146:147], v[14:15], v[142:143]
	v_pk_mul_f32 v[12:13], v[12:13], v[24:25] op_sel_hi:[1,0]
	v_pk_mul_f32 v[16:17], v[16:17], v[24:25] op_sel_hi:[1,0]
	v_pk_fma_f32 v[20:21], v[152:153], v[12:13], v[140:141]
	v_pk_fma_f32 v[12:13], v[150:151], v[10:11], v[138:139]
	v_cvt_pk_bf16_f32 v10, v14, v15
	v_lshl_add_u64 v[14:15], s[0:1], 0, v[18:19]
	v_lshl_add_u64 v[14:15], v[14:15], 0, s[16:17]
	v_pk_fma_f32 v[16:17], v[148:149], v[16:17], v[144:145]
	v_lshl_add_u64 v[14:15], v[14:15], 0, v[26:27]
	v_cvt_pk_bf16_f32 v11, v16, v17
	v_pk_mul_f32 v[6:7], v[6:7], v[24:25] op_sel_hi:[1,0]
	v_pk_mul_f32 v[8:9], v[8:9], v[24:25] op_sel_hi:[1,0]
	v_pk_mul_f32 v[2:3], v[2:3], v[24:25] op_sel_hi:[1,0]
	v_pk_mul_f32 v[4:5], v[4:5], v[24:25] op_sel_hi:[1,0]
	v_cvt_pk_bf16_f32 v12, v12, v13
	v_cvt_pk_bf16_f32 v13, v20, v21
	global_store_dwordx4 v[14:15], v[10:13], off
	v_pk_fma_f32 v[8:9], v[164:165], v[8:9], v[104:105]
	v_pk_fma_f32 v[6:7], v[162:163], v[6:7], v[102:103]
	v_pk_fma_f32 v[10:11], v[168:169], v[4:5], v[100:101]
	v_pk_fma_f32 v[4:5], v[166:167], v[2:3], v[98:99]
	v_cvt_pk_bf16_f32 v2, v6, v7
	v_cvt_pk_bf16_f32 v3, v8, v9
	v_lshl_add_u64 v[6:7], s[8:9], 0, v[18:19]
	v_cvt_pk_bf16_f32 v4, v4, v5
	v_cvt_pk_bf16_f32 v5, v10, v11
	ds_read_b32 v8, v154 offset:128
	v_lshl_add_u64 v[6:7], v[6:7], 0, s[16:17]
	v_lshl_add_u64 v[6:7], v[6:7], 0, v[26:27]
	global_store_dwordx4 v[6:7], v[2:5], off
	s_and_b64 vcc, exec, s[6:7]
	s_waitcnt lgkmcnt(0)
; __device__ __forceinline__ u32x4 pack8(const f32x4 v0, const f32x4 v1) { u32x4 w; w.x = cvt_pk_bf16(v0[0], v0[1]); w.y = cvt_pk_bf16(v0[2], v0[3]); w.z = cvt_pk_bf16(v1[0], v1[1]); w.w = cvt_pk_bf16(v1[2], v1[3]); return w; }
;     __device__ __forceinline__ void operator()(f32x4 (&acc)[2][2][4][2], const Unit& u, int wr, int wc, int fr_, int fq_) const {
;     ...
; #pragma unroll
;         for (int ai = 0; ai < 2; ++ai)
; #pragma unroll
;             for (int m = 0; m < 4; ++m) { const int r = ai * HALF + wr * 64 + m * 16 + fr; const float rs = S[r];
; #pragma unroll
;                 for (int bj = 0; bj < 2; ++bj) { const f32x4 y0 = acc[ai][bj][m][0] * rs * av[bj][0] + sv[bj][0], y1 = acc[ai][bj][m][1] * rs * av[bj][1] + sv[bj][1];
;                     if (FINAL) { float* o = OUTF + ((size_t)u.pm * BM + r) * DM + col0 + bj * HALF; *(f32x4*)o = y0; *(f32x4*)(o + 4) = y1; }
;                     else *(u32x4*)(XN + (((size_t)u.pm * (DM / BK) + u.pn * 4 + bj * 2 + (wc >> 1)) * BM + r) * BK + (wc & 1) * 32 + 8 * fq) = pack8(y0, y1); } }
	v_pk_mul_f32 v[10:11], v[58:59], v[8:9] op_sel_hi:[1,0]
	v_add_u32_e32 v2, 32, v198
	v_ashrrev_i32_e32 v3, 31, v2
	v_lshlrev_b64 v[6:7], 7, v[2:3]
	v_pk_mul_f32 v[2:3], v[62:63], v[8:9] op_sel_hi:[1,0]
	v_pk_mul_f32 v[4:5], v[64:65], v[8:9] op_sel_hi:[1,0]
	v_pk_fma_f32 v[2:3], v[146:147], v[2:3], v[142:143]
	v_pk_fma_f32 v[4:5], v[148:149], v[4:5], v[144:145]
	v_pk_fma_f32 v[10:11], v[150:151], v[10:11], v[138:139]
	v_cvt_pk_bf16_f32 v2, v2, v3
	v_cvt_pk_bf16_f32 v3, v4, v5
	v_pk_mul_f32 v[12:13], v[60:61], v[8:9] op_sel_hi:[1,0]
	v_cvt_pk_bf16_f32 v4, v10, v11
	v_lshl_add_u64 v[10:11], s[0:1], 0, v[6:7]
	v_lshl_add_u64 v[10:11], v[10:11], 0, s[16:17]
	v_pk_fma_f32 v[12:13], v[152:153], v[12:13], v[140:141]
	v_lshl_add_u64 v[10:11], v[10:11], 0, v[26:27]
	v_cvt_pk_bf16_f32 v5, v12, v13
	global_store_dwordx4 v[10:11], v[2:5], off
	v_pk_mul_f32 v[10:11], v[50:51], v[8:9] op_sel_hi:[1,0]
	v_lshl_add_u64 v[6:7], s[8:9], 0, v[6:7]
	v_pk_mul_f32 v[2:3], v[54:55], v[8:9] op_sel_hi:[1,0]
	v_pk_mul_f32 v[4:5], v[56:57], v[8:9] op_sel_hi:[1,0]
	v_pk_mul_f32 v[8:9], v[52:53], v[8:9] op_sel_hi:[1,0]
	v_pk_fma_f32 v[4:5], v[164:165], v[4:5], v[104:105]
	v_pk_fma_f32 v[2:3], v[162:163], v[2:3], v[102:103]
	v_pk_fma_f32 v[8:9], v[168:169], v[8:9], v[100:101]
	v_pk_fma_f32 v[10:11], v[166:167], v[10:11], v[98:99]
	v_cvt_pk_bf16_f32 v2, v2, v3
	v_cvt_pk_bf16_f32 v3, v4, v5
	v_lshl_add_u64 v[6:7], v[6:7], 0, s[16:17]
	v_cvt_pk_bf16_f32 v4, v10, v11
	v_cvt_pk_bf16_f32 v5, v8, v9
	ds_read_b32 v8, v154 offset:192
	v_lshl_add_u64 v[6:7], v[6:7], 0, v[26:27]
	global_store_dwordx4 v[6:7], v[2:5], off
	s_waitcnt lgkmcnt(0)
	v_pk_mul_f32 v[10:11], v[42:43], v[8:9] op_sel_hi:[1,0]
	v_add_u32_e32 v2, 48, v198
	v_ashrrev_i32_e32 v3, 31, v2
	v_lshlrev_b64 v[6:7], 7, v[2:3]
	v_pk_mul_f32 v[2:3], v[46:47], v[8:9] op_sel_hi:[1,0]
	v_pk_mul_f32 v[4:5], v[48:49], v[8:9] op_sel_hi:[1,0]
	v_pk_fma_f32 v[2:3], v[146:147], v[2:3], v[142:143]
	v_pk_fma_f32 v[4:5], v[148:149], v[4:5], v[144:145]
	v_pk_fma_f32 v[10:11], v[150:151], v[10:11], v[138:139]
	v_cvt_pk_bf16_f32 v2, v2, v3
	v_cvt_pk_bf16_f32 v3, v4, v5
	v_pk_mul_f32 v[12:13], v[44:45], v[8:9] op_sel_hi:[1,0]
	v_cvt_pk_bf16_f32 v4, v10, v11
	v_lshl_add_u64 v[10:11], s[0:1], 0, v[6:7]
	v_lshl_add_u64 v[10:11], v[10:11], 0, s[16:17]
	v_pk_fma_f32 v[12:13], v[152:153], v[12:13], v[140:141]
	v_lshl_add_u64 v[10:11], v[10:11], 0, v[26:27]
	v_cvt_pk_bf16_f32 v5, v12, v13
	global_store_dwordx4 v[10:11], v[2:5], off
	v_pk_mul_f32 v[10:11], v[34:35], v[8:9] op_sel_hi:[1,0]
	v_lshl_add_u64 v[6:7], s[8:9], 0, v[6:7]
	v_pk_mul_f32 v[2:3], v[38:39], v[8:9] op_sel_hi:[1,0]
	v_pk_mul_f32 v[4:5], v[40:41], v[8:9] op_sel_hi:[1,0]
	v_pk_mul_f32 v[8:9], v[36:37], v[8:9] op_sel_hi:[1,0]
	v_pk_fma_f32 v[4:5], v[164:165], v[4:5], v[104:105]
	v_pk_fma_f32 v[2:3], v[162:163], v[2:3], v[102:103]
	v_pk_fma_f32 v[8:9], v[168:169], v[8:9], v[100:101]
	v_pk_fma_f32 v[10:11], v[166:167], v[10:11], v[98:99]
	v_cvt_pk_bf16_f32 v2, v2, v3
	v_cvt_pk_bf16_f32 v3, v4, v5
	v_lshl_add_u64 v[6:7], v[6:7], 0, s[16:17]
	v_cvt_pk_bf16_f32 v4, v10, v11
	v_cvt_pk_bf16_f32 v5, v8, v9
	ds_read_b32 v8, v154 offset:512
	v_lshl_add_u64 v[6:7], v[6:7], 0, v[26:27]
	global_store_dwordx4 v[6:7], v[2:5], off
	s_waitcnt lgkmcnt(0)
	v_pk_mul_f32 v[10:11], v[122:123], v[8:9] op_sel_hi:[1,0]
	v_add_u32_e32 v2, 0x80, v198
	v_ashrrev_i32_e32 v3, 31, v2
	v_lshlrev_b64 v[6:7], 7, v[2:3]
	v_pk_mul_f32 v[2:3], v[126:127], v[8:9] op_sel_hi:[1,0]
	v_pk_mul_f32 v[4:5], v[128:129], v[8:9] op_sel_hi:[1,0]
	v_pk_fma_f32 v[2:3], v[146:147], v[2:3], v[142:143]
	v_pk_fma_f32 v[4:5], v[148:149], v[4:5], v[144:145]
	v_pk_fma_f32 v[10:11], v[150:151], v[10:11], v[138:139]
	v_cvt_pk_bf16_f32 v2, v2, v3
	v_cvt_pk_bf16_f32 v3, v4, v5
	v_pk_mul_f32 v[12:13], v[124:125], v[8:9] op_sel_hi:[1,0]
	v_cvt_pk_bf16_f32 v4, v10, v11
	v_lshl_add_u64 v[10:11], s[0:1], 0, v[6:7]
	v_lshl_add_u64 v[10:11], v[10:11], 0, s[16:17]
	v_pk_fma_f32 v[12:13], v[152:153], v[12:13], v[140:141]
	v_lshl_add_u64 v[10:11], v[10:11], 0, v[26:27]
	v_cvt_pk_bf16_f32 v5, v12, v13
	global_store_dwordx4 v[10:11], v[2:5], off
	v_pk_mul_f32 v[10:11], v[114:115], v[8:9] op_sel_hi:[1,0]
	v_lshl_add_u64 v[6:7], s[8:9], 0, v[6:7]
	v_pk_mul_f32 v[2:3], v[118:119], v[8:9] op_sel_hi:[1,0]
	v_pk_mul_f32 v[4:5], v[120:121], v[8:9] op_sel_hi:[1,0]
	v_pk_mul_f32 v[8:9], v[116:117], v[8:9] op_sel_hi:[1,0]
	v_pk_fma_f32 v[4:5], v[164:165], v[4:5], v[104:105]
	v_pk_fma_f32 v[2:3], v[162:163], v[2:3], v[102:103]
	v_pk_fma_f32 v[8:9], v[168:169], v[8:9], v[100:101]
	v_pk_fma_f32 v[10:11], v[166:167], v[10:11], v[98:99]
	v_cvt_pk_bf16_f32 v2, v2, v3
	v_cvt_pk_bf16_f32 v3, v4, v5
	v_lshl_add_u64 v[6:7], v[6:7], 0, s[16:17]
	v_cvt_pk_bf16_f32 v4, v10, v11
	v_cvt_pk_bf16_f32 v5, v8, v9
	ds_read_b32 v8, v154 offset:576
	v_lshl_add_u64 v[6:7], v[6:7], 0, v[26:27]
	global_store_dwordx4 v[6:7], v[2:5], off
	s_waitcnt lgkmcnt(0)
; __device__ __forceinline__ u32x4 pack8(const f32x4 v0, const f32x4 v1) { u32x4 w; w.x = cvt_pk_bf16(v0[0], v0[1]); w.y = cvt_pk_bf16(v0[2], v0[3]); w.z = cvt_pk_bf16(v1[0], v1[1]); w.w = cvt_pk_bf16(v1[2], v1[3]); return w; }
; #define PG8_BAR __builtin_amdgcn_s_barrier()
;     __device__ __forceinline__ void operator()(f32x4 (&acc)[2][2][4][2], const Unit& u, int wr, int wc, int fr_, int fq_) const {
;     ...
; #pragma unroll
;         for (int ai = 0; ai < 2; ++ai)
; #pragma unroll
;             for (int m = 0; m < 4; ++m) { const int r = ai * HALF + wr * 64 + m * 16 + fr; const float rs = S[r];
; #pragma unroll
;                 for (int bj = 0; bj < 2; ++bj) { const f32x4 y0 = acc[ai][bj][m][0] * rs * av[bj][0] + sv[bj][0], y1 = acc[ai][bj][m][1] * rs * av[bj][1] + sv[bj][1];
;                     if (FINAL) { float* o = OUTF + ((size_t)u.pm * BM + r) * DM + col0 + bj * HALF; *(f32x4*)o = y0; *(f32x4*)(o + 4) = y1; }
;                     else *(u32x4*)(XN + (((size_t)u.pm * (DM / BK) + u.pn * 4 + bj * 2 + (wc >> 1)) * BM + r) * BK + (wc & 1) * 32 + 8 * fq) = pack8(y0, y1); } }
; template <class Epi, class Sched, bool ALIGN_EPI = false, bool SP2 = false, bool ABLK = false, bool BBLK = false>
; __device__ __forceinline__ void gemm_phase(PG8_LAS unsigned char* lds, const Gemm g, const Sched& S, const Epi& E) {
;     ...
;         if (!has_next) break;
; #pragma unroll
;         for (int a = 0; a < 2; ++a)
; #pragma unroll
;             for (int b = 0; b < 2; ++b)
; #pragma unroll
;                 for (int m = 0; m < 4; ++m)
; #pragma unroll
;                     for (int n = 0; n < 2; ++n) acc[a][b][m][n] = (f32x4){0.f, 0.f, 0.f, 0.f};
;         cur = nxt; cA = nA; cB = nB; ++ui;
;         if constexpr (ALIGN_EPI) { if (wr == 1) PG8_BAR; }
;     }
	v_pk_mul_f32 v[10:11], v[90:91], v[8:9] op_sel_hi:[1,0]
	v_add_u32_e32 v2, 0x90, v198
	v_ashrrev_i32_e32 v3, 31, v2
	v_lshlrev_b64 v[6:7], 7, v[2:3]
	v_pk_mul_f32 v[2:3], v[94:95], v[8:9] op_sel_hi:[1,0]
	v_pk_mul_f32 v[4:5], v[96:97], v[8:9] op_sel_hi:[1,0]
	v_pk_fma_f32 v[2:3], v[146:147], v[2:3], v[142:143]
	v_pk_fma_f32 v[4:5], v[148:149], v[4:5], v[144:145]
	v_pk_fma_f32 v[10:11], v[150:151], v[10:11], v[138:139]
	v_cvt_pk_bf16_f32 v2, v2, v3
	v_cvt_pk_bf16_f32 v3, v4, v5
	v_pk_mul_f32 v[12:13], v[92:93], v[8:9] op_sel_hi:[1,0]
	v_cvt_pk_bf16_f32 v4, v10, v11
	v_lshl_add_u64 v[10:11], s[0:1], 0, v[6:7]
	v_lshl_add_u64 v[10:11], v[10:11], 0, s[16:17]
	v_pk_fma_f32 v[12:13], v[152:153], v[12:13], v[140:141]
	v_lshl_add_u64 v[10:11], v[10:11], 0, v[26:27]
	v_cvt_pk_bf16_f32 v5, v12, v13
	global_store_dwordx4 v[10:11], v[2:5], off
	v_pk_mul_f32 v[10:11], v[70:71], v[8:9] op_sel_hi:[1,0]
	v_lshl_add_u64 v[6:7], s[8:9], 0, v[6:7]
	v_pk_mul_f32 v[2:3], v[74:75], v[8:9] op_sel_hi:[1,0]
	v_pk_mul_f32 v[4:5], v[76:77], v[8:9] op_sel_hi:[1,0]
	v_pk_mul_f32 v[8:9], v[72:73], v[8:9] op_sel_hi:[1,0]
	v_pk_fma_f32 v[4:5], v[164:165], v[4:5], v[104:105]
	v_pk_fma_f32 v[2:3], v[162:163], v[2:3], v[102:103]
	v_pk_fma_f32 v[8:9], v[168:169], v[8:9], v[100:101]
	v_pk_fma_f32 v[10:11], v[166:167], v[10:11], v[98:99]
	v_cvt_pk_bf16_f32 v2, v2, v3
	v_cvt_pk_bf16_f32 v3, v4, v5
	v_lshl_add_u64 v[6:7], v[6:7], 0, s[16:17]
	v_cvt_pk_bf16_f32 v4, v10, v11
	v_cvt_pk_bf16_f32 v5, v8, v9
	ds_read_b32 v8, v154 offset:640
	v_lshl_add_u64 v[6:7], v[6:7], 0, v[26:27]
	global_store_dwordx4 v[6:7], v[2:5], off
	s_waitcnt lgkmcnt(0)
	v_pk_mul_f32 v[10:11], v[130:131], v[8:9] op_sel_hi:[1,0]
	v_add_u32_e32 v2, 0xa0, v198
	v_ashrrev_i32_e32 v3, 31, v2
	v_lshlrev_b64 v[6:7], 7, v[2:3]
	v_pk_mul_f32 v[2:3], v[134:135], v[8:9] op_sel_hi:[1,0]
	v_pk_mul_f32 v[4:5], v[136:137], v[8:9] op_sel_hi:[1,0]
	v_pk_fma_f32 v[2:3], v[146:147], v[2:3], v[142:143]
	v_pk_fma_f32 v[4:5], v[148:149], v[4:5], v[144:145]
	v_pk_fma_f32 v[10:11], v[150:151], v[10:11], v[138:139]
	v_cvt_pk_bf16_f32 v2, v2, v3
	v_cvt_pk_bf16_f32 v3, v4, v5
	v_pk_mul_f32 v[12:13], v[132:133], v[8:9] op_sel_hi:[1,0]
	v_cvt_pk_bf16_f32 v4, v10, v11
	v_lshl_add_u64 v[10:11], s[0:1], 0, v[6:7]
	v_lshl_add_u64 v[10:11], v[10:11], 0, s[16:17]
	v_pk_fma_f32 v[12:13], v[152:153], v[12:13], v[140:141]
	v_lshl_add_u64 v[10:11], v[10:11], 0, v[26:27]
	v_cvt_pk_bf16_f32 v5, v12, v13
	global_store_dwordx4 v[10:11], v[2:5], off
	v_pk_mul_f32 v[10:11], v[106:107], v[8:9] op_sel_hi:[1,0]
	v_lshl_add_u64 v[6:7], s[8:9], 0, v[6:7]
	v_pk_mul_f32 v[2:3], v[110:111], v[8:9] op_sel_hi:[1,0]
	v_pk_mul_f32 v[4:5], v[112:113], v[8:9] op_sel_hi:[1,0]
	v_pk_mul_f32 v[8:9], v[108:109], v[8:9] op_sel_hi:[1,0]
	v_pk_fma_f32 v[4:5], v[164:165], v[4:5], v[104:105]
	v_pk_fma_f32 v[2:3], v[162:163], v[2:3], v[102:103]
	v_pk_fma_f32 v[8:9], v[168:169], v[8:9], v[100:101]
	v_pk_fma_f32 v[10:11], v[166:167], v[10:11], v[98:99]
	v_cvt_pk_bf16_f32 v2, v2, v3
	v_cvt_pk_bf16_f32 v3, v4, v5
	v_lshl_add_u64 v[6:7], v[6:7], 0, s[16:17]
	v_cvt_pk_bf16_f32 v4, v10, v11
	v_cvt_pk_bf16_f32 v5, v8, v9
	ds_read_b32 v8, v154 offset:704
	v_lshl_add_u64 v[6:7], v[6:7], 0, v[26:27]
	global_store_dwordx4 v[6:7], v[2:5], off
	s_waitcnt lgkmcnt(0)
	v_pk_mul_f32 v[10:11], v[82:83], v[8:9] op_sel_hi:[1,0]
	v_add_u32_e32 v2, 0xb0, v198
	v_ashrrev_i32_e32 v3, 31, v2
	v_lshlrev_b64 v[6:7], 7, v[2:3]
	v_pk_mul_f32 v[2:3], v[86:87], v[8:9] op_sel_hi:[1,0]
	v_pk_mul_f32 v[4:5], v[88:89], v[8:9] op_sel_hi:[1,0]
	v_pk_fma_f32 v[2:3], v[146:147], v[2:3], v[142:143]
	v_pk_fma_f32 v[4:5], v[148:149], v[4:5], v[144:145]
	v_pk_fma_f32 v[10:11], v[150:151], v[10:11], v[138:139]
	v_cvt_pk_bf16_f32 v2, v2, v3
	v_cvt_pk_bf16_f32 v3, v4, v5
	v_pk_mul_f32 v[12:13], v[84:85], v[8:9] op_sel_hi:[1,0]
	v_cvt_pk_bf16_f32 v4, v10, v11
	v_lshl_add_u64 v[10:11], s[0:1], 0, v[6:7]
	v_lshl_add_u64 v[10:11], v[10:11], 0, s[16:17]
	v_pk_fma_f32 v[12:13], v[152:153], v[12:13], v[140:141]
	v_lshl_add_u64 v[10:11], v[10:11], 0, v[26:27]
	v_cvt_pk_bf16_f32 v5, v12, v13
	v_lshl_add_u64 v[6:7], s[8:9], 0, v[6:7]
	global_store_dwordx4 v[10:11], v[2:5], off
	v_lshl_add_u64 v[6:7], v[6:7], 0, s[16:17]
	v_pk_mul_f32 v[10:11], v[66:67], v[8:9] op_sel_hi:[1,0]
	v_pk_mul_f32 v[2:3], v[78:79], v[8:9] op_sel_hi:[1,0]
	v_pk_mul_f32 v[4:5], v[80:81], v[8:9] op_sel_hi:[1,0]
	v_pk_fma_f32 v[2:3], v[162:163], v[2:3], v[102:103]
	v_pk_fma_f32 v[4:5], v[164:165], v[4:5], v[104:105]
	v_pk_mul_f32 v[8:9], v[68:69], v[8:9] op_sel_hi:[1,0]
	v_lshl_add_u64 v[6:7], v[6:7], 0, v[26:27]
	s_mov_b64 s[0:1], -1
	v_pk_fma_f32 v[8:9], v[168:169], v[8:9], v[100:101]
	v_pk_fma_f32 v[10:11], v[166:167], v[10:11], v[98:99]
	v_cvt_pk_bf16_f32 v2, v2, v3
	v_cvt_pk_bf16_f32 v3, v4, v5
	s_nop 0
	v_cvt_pk_bf16_f32 v4, v10, v11
	v_cvt_pk_bf16_f32 v5, v8, v9
	global_store_dwordx4 v[6:7], v[2:5], off
	s_cbranch_vccnz .LBB0_356
	v_readlane_b32 s0, v254, 50
	v_readlane_b32 s1, v254, 51
	s_andn2_b64 vcc, exec, s[0:1]
	s_cbranch_vccnz .LBB0_355
	s_branch .LBB0_355

; template <class Epi, class Sched, bool ALIGN_EPI = false, bool SP2 = false, bool ABLK = false, bool BBLK = false>
; __device__ __forceinline__ void gemm_phase(PG8_LAS unsigned char* lds, const Gemm g, const Sched& S, const Epi& E) {
;     ...
;     for (int i = 0; i < 2; ++i) { int R, C; stage_rc(tid * 16 + i * 8192, R, C); const int Rb = Epi::PERM ? ((R & ~31) + perm32(R & 31)) : R;
;         voffA[i] = ABLK ? (unsigned)(R * BK + C) * 2u : (unsigned)(R * LDA + C) * 2u; voffB[i] = BBLK ? (unsigned)(Rb * BK + C) * 2u : (unsigned)(Rb * LDB + C) * 2u; }
;     const size_t kstep = (size_t)(BK * 2);
;     const size_t hstepa = (size_t)HALF * LDA * 2, hstepb = (size_t)HALF * LDB * 2;
;     const size_t kstepA = ABLK ? (size_t)BM * BK * 2 : kstep, hstepA = ABLK ? (size_t)HALF * BK * 2 : hstepa, tstepA = ABLK ? (size_t)nt * BM * BK * 2 : 2 * hstepa;
;     const size_t kstepB = BBLK ? (size_t)BM * BK * 2 : kstep, hstepB = BBLK ? (size_t)HALF * BK * 2 : hstepb, tstepB = BBLK ? (size_t)nt * BM * BK * 2 : 2 * hstepb;
;     const unsigned ldsw = (unsigned)wid * 1024u;
;     const int aoff = lds_byte(wr * 64 + fr, fq * 8), boff = lds_byte(wc * 32 + fr, fq * 8);
;     ...
;     Unit cur, nxt; int ui = 0;
;     if (!S.next(0, cur)) return;
;     f32x4 acc[2][2][4][2];
; #pragma unroll
;     for (int a = 0; a < 2; ++a)
; #pragma unroll
;         for (int b = 0; b < 2; ++b)
; #pragma unroll
;             for (int m = 0; m < 4; ++m)
; #pragma unroll
;                 for (int n = 0; n < 2; ++n) acc[a][b][m][n] = (f32x4){0.f, 0.f, 0.f, 0.f};
;     bf16x8 At[4][2], B0[2][2], B1[2][2];
;     const char* cA = (const char*)g.A + (size_t)cur.pm * tstepA; const char* cB = (const char*)g.Bt + (size_t)cur.pn * tstepB;
;     S.a_ready(cur);
;     if constexpr (SP2) {
;         PG8_STAGE(PG8_SB(0, 0), cB, voffB); PG8_STAGE(PG8_SB(0, 1), cB + hstepB, voffB); PG8_STAGE(PG8_SA(0, 0), cA, voffA); PG8_STAGE(PG8_SA(0, 1), cA + hstepA, voffA);
;         if (wr == 1) PG8_BAR;
;         PG8_WAIT_V(2); PG8_BAR;
;         PG8_STAGE(PG8_SB(1, 0), cB + kstepB, voffB); PG8_STAGE(PG8_SA(1, 0), cA + kstepA, voffA); PG8_STAGE(PG8_SB(1, 1), cB + hstepB + kstepB, voffB);
;         PG8_WAIT_V(6); PG8_BAR;
;     } else {
;         PG8_STAGE(PG8_SB(0, 0), cB, voffB); PG8_STAGE(PG8_SA(0, 0), cA, voffA); PG8_STAGE(PG8_SB(0, 1), cB + hstepB, voffB); PG8_STAGE(PG8_SA(0, 1), cA + hstepA, voffA);
;         if (wr == 1) PG8_BAR;
.LBB0_585:
	v_readlane_b32 s10, v254, 7
	v_readlane_b32 s11, v254, 8
	s_add_u32 s43, s10, s0
	s_addc_u32 s50, s11, s1
	s_add_u32 s51, s43, 0xf600000
	s_addc_u32 s53, s50, 0
	s_andn2_b64 vcc, exec, s[4:5]
	s_ashr_i32 s56, s42, 31
	s_cbranch_vccnz .LBB0_649
	v_bfe_i32 v4, v2, 27, 1
	s_waitcnt vmcnt(10)
	v_lshlrev_b32_e32 v6, 4, v2
	v_lshrrev_b32_e32 v4, 22, v4
	v_ashrrev_i32_e32 v3, 31, v2
	v_add_u32_e32 v4, v6, v4
	v_lshrrev_b32_e32 v3, 26, v3
	v_and_b32_e32 v4, 0xfffffc00, v4
	v_add_u32_e32 v3, v2, v3
	v_sub_u32_e32 v4, v6, v4
	v_ashrrev_i32_e32 v3, 6, v3
	v_lshrrev_b32_e32 v5, 4, v4
	v_bitop3_b32 v5, v5, v4, 32 bitop3:0x6c
	v_lshlrev_b32_e32 v4, 3, v3
	v_and_b32_e32 v7, -16, v4
	v_ashrrev_i32_e32 v4, 31, v5
	v_lshrrev_b32_e32 v4, 26, v4
	v_add_u32_e32 v8, v5, v4
	v_ashrrev_i32_e32 v4, 6, v8
	v_and_b32_e32 v8, 0xc0, v8
	v_sub_u32_e32 v5, v5, v8
	v_lshlrev_b32_e32 v9, 5, v3
	v_ashrrev_i16_sdwa v5, v232, sext(v5) dst_sel:DWORD dst_unused:UNUSED_PAD src0_sel:DWORD src1_sel:BYTE_0
	v_and_b32_e32 v9, 32, v9
	v_bfe_i32 v5, v5, 0, 16
	v_add_u32_e32 v7, v4, v7
	s_waitcnt vmcnt(9)
	v_and_b32_e32 v11, 3, v4
	s_mov_b32 s0, 0x1ffffe0
	v_add_lshl_u32 v9, v9, v5, 1
	v_lshlrev_b32_e32 v8, 1, v7
	v_lshrrev_b32_e32 v10, 2, v7
	v_and_or_b32 v11, v7, s0, v11
	v_lshl_add_u32 v146, v7, 7, v9
	v_add_u32_e32 v7, 0x2000, v6
	v_ashrrev_i32_e32 v6, 31, v7
	v_lshrrev_b32_e32 v6, 22, v6
	v_and_b32_e32 v8, 24, v8
	v_and_b32_e32 v10, 4, v10
	v_add_u32_e32 v6, v7, v6
	v_or3_b32 v8, v11, v10, v8
	v_ashrrev_i32_e32 v6, 10, v6
	v_lshl_add_u32 v148, v8, 7, v9
	v_mul_i32_i24_e32 v8, 0x400, v6
	v_sub_u32_e32 v7, v7, v8
	v_lshrrev_b32_e32 v8, 4, v7
	v_bitop3_b32 v8, v8, v7, 32 bitop3:0x6c
	v_lshlrev_b32_e32 v7, 3, v6
	v_and_b32_e32 v9, -16, v7
	v_ashrrev_i32_e32 v7, 31, v8
	v_lshrrev_b32_e32 v7, 26, v7
	v_add_u32_e32 v10, v8, v7
	s_add_u32 s44, s43, 0x7700000
	v_ashrrev_i32_e32 v7, 6, v10
	s_addc_u32 s45, s50, 0
	v_add_u32_e32 v9, v7, v9
	v_and_b32_e32 v13, 3, v7
	s_ashr_i32 s20, s18, 6
	s_ashr_i32 s29, s28, 31
	s_ashr_i32 s9, s8, 31
	s_ashr_i32 s19, s18, 8
	v_and_b32_e32 v10, 0xc0, v10
	v_and_or_b32 v13, v9, s0, v13
	s_lshl_b32 s81, s20, 10
	s_lshl_b64 s[0:1], s[28:29], 20
	s_lshl_b64 s[4:5], s[8:9], 20
	v_sub_u32_e32 v8, v8, v10
	s_add_u32 s30, s44, s4
	v_lshlrev_b32_e32 v11, 5, v6
	v_ashrrev_i16_sdwa v8, v232, sext(v8) dst_sel:DWORD dst_unused:UNUSED_PAD src0_sel:DWORD src1_sel:BYTE_0
	v_lshlrev_b32_e32 v10, 1, v9
	v_lshrrev_b32_e32 v12, 2, v9
	s_addc_u32 s31, s45, s5
	s_add_i32 s83, s81, 0
	v_and_b32_e32 v11, 32, v11
	v_bfe_i32 v8, v8, 0, 16
	v_and_b32_e32 v10, 24, v10
	v_and_b32_e32 v12, 4, v12
	s_add_i32 m0, s83, 0x10000
	v_or3_b32 v10, v13, v12, v10
	v_add_lshl_u32 v11, v11, v8, 1
	global_load_lds_dwordx4 v148, s[30:31]
	s_add_i32 m0, s83, 0x12000
	v_lshl_add_u32 v152, v10, 7, v11
	s_add_u32 s4, s30, 0x4000
	global_load_lds_dwordx4 v152, s[30:31]
	s_addc_u32 s5, s31, 0
	s_add_i32 m0, s83, 0x14000
	v_lshl_add_u32 v150, v9, 7, v11
	global_load_lds_dwordx4 v148, s[4:5]
	s_add_i32 m0, s83, 0x16000
	s_add_u32 s0, s51, s0
	s_addc_u32 s1, s53, s1
	s_add_i32 s84, s83, 0x2000
	global_load_lds_dwordx4 v152, s[4:5]
	s_mov_b32 m0, s83
	s_add_u32 s4, s0, 0x4000
	global_load_lds_dwordx4 v146, s[0:1]
	s_mov_b32 m0, s84
	s_addc_u32 s5, s1, 0
	s_add_i32 s86, s83, 0x4000
	global_load_lds_dwordx4 v150, s[0:1]
	s_mov_b32 m0, s86
	s_add_i32 s88, s83, 0x6000
	global_load_lds_dwordx4 v146, s[4:5]
	s_mov_b32 m0, s88
	s_cmp_eq_u32 s19, 1
	global_load_lds_dwordx4 v150, s[4:5]
	s_cselect_b64 s[4:5], -1, 0
	s_cmp_lg_u32 s19, 1
	s_cbranch_scc1 .LBB0_588
.LBB0_588:
	s_add_u32 s10, s43, 0x18600000
	s_addc_u32 s11, s50, 0
	s_add_u32 s12, s43, 0x1f200000
	s_addc_u32 s13, s50, 0
	v_readlane_b32 s3, v254, 24
	s_add_u32 s14, s43, 0x2ca00000
	s_mul_i32 s16, s3, 0x1800
	v_lshrrev_b32_e32 v9, 1, v2
	s_addc_u32 s15, s50, 0
	s_lshl_b64 s[22:23], s[16:17], 2
	v_and_b32_e32 v9, 24, v9
	s_waitcnt lgkmcnt(0)
	s_add_u32 s6, s6, s22
	v_and_b32_e32 v168, 15, v2
	v_lshlrev_b32_e32 v10, 1, v9
	v_lshlrev_b32_e32 v2, 2, v2
	s_addc_u32 s7, s7, s23
	v_lshl_or_b32 v10, v168, 6, v10
	s_lshl_b32 s9, s19, 13
	v_and_b32_e32 v2, 32, v2
	v_bitop3_b32 v12, v10, s9, v2 bitop3:0xde
	s_lshl_b32 s9, s20, 5
	s_and_b32 s9, s9, 0x60
	s_lshl_b32 s89, s19, 6
	s_lshl_b32 s16, s9, 7
	s_add_u32 s20, s30, 0x8000
	v_mov_b32_e32 v149, v187
	s_addc_u32 s21, s31, 0
	v_bitop3_b32 v169, v10, s16, v2 bitop3:0xde
	s_add_i32 m0, s83, 0x18000
	v_lshl_add_u64 v[10:11], s[20:21], 0, v[148:149]
	v_mov_b32_e32 v153, v187
	s_waitcnt vmcnt(2)
	s_barrier
	global_load_lds_dwordx4 v[10:11], off
	s_add_i32 m0, s83, 0x1a000
	v_lshl_add_u64 v[10:11], s[20:21], 0, v[152:153]
	s_add_u32 s20, s0, 0x8000
	v_mov_b32_e32 v147, v187
	s_addc_u32 s21, s1, 0
	s_add_i32 s90, s83, 0x8000
	v_mov_b32_e32 v151, v187
	global_load_lds_dwordx4 v[10:11], off
	v_lshl_add_u64 v[10:11], s[20:21], 0, v[146:147]
	s_mov_b32 m0, s90
	s_add_i32 s91, s83, 0xa000
	global_load_lds_dwordx4 v[10:11], off
	v_lshl_add_u64 v[10:11], s[20:21], 0, v[150:151]
	s_add_u32 s20, s30, 0xc000
	s_mov_b32 m0, s91
	s_addc_u32 s21, s31, 0
	global_load_lds_dwordx4 v[10:11], off
	s_add_i32 m0, s83, 0x1c000
	v_lshl_add_u64 v[10:11], s[20:21], 0, v[148:149]
	global_load_lds_dwordx4 v[10:11], off
	v_lshl_add_u64 v[10:11], s[20:21], 0, v[152:153]
	s_add_i32 m0, s83, 0x1e000
	v_or_b32_e32 v2, s9, v9
	global_load_lds_dwordx4 v[10:11], off
	v_lshlrev_b32_e32 v9, 10, v3
	v_and_b32_e32 v9, 0xfffff800, v9
	v_lshl_add_u32 v4, v4, 7, v9
	v_and_b32_e32 v3, 1, v3
	v_lshl_or_b32 v3, v3, 6, v4
	v_lshl_add_u32 v156, v5, 1, v3
	v_lshlrev_b32_e32 v3, 10, v6
	v_and_b32_e32 v3, 0xfffff800, v3
	s_waitcnt vmcnt(6)
	v_lshl_add_u32 v3, v7, 7, v3
	v_and_b32_e32 v4, 1, v6
	s_cmpk_lt_u32 s18, 0x100
	v_lshlrev_b32_e32 v186, 2, v2
	v_lshl_or_b32 v3, v4, 6, v3
	s_mov_b32 s3, s17
	s_cselect_b64 s[18:19], -1, 0
	s_ashr_i32 s92, s89, 31
	v_lshl_add_u64 v[154:155], s[6:7], 0, v[186:187]
	v_mov_b32_e32 v157, v187
	v_lshl_add_u32 v158, v8, 1, v3
	v_mov_b32_e32 v159, v187
	s_mov_b32 s93, 0
	v_add_u32_e32 v170, 0, v12
	v_lshlrev_b32_e32 v186, 1, v2
	s_barrier
	s_branch .LBB0_591

; #define PG8_STAGE(bufoff, gbase, voff) do { _Pragma("unroll") for (int _i = 0; _i < 2; ++_i) \
;         __builtin_amdgcn_global_load_lds((const unsigned*)((const char*)(gbase) + (voff)[_i]), (PG8_LAS unsigned*)(lds + (bufoff) + ldsw + _i * 8192), 16, 0, 0); } while (0)
; #define PG8_LDA(dst, b, h) do { _Pragma("unroll") for (int m = 0; m < 4; ++m) _Pragma("unroll") for (int k = 0; k < 2; ++k) dst[m][k] = *(const PG8_LAS bf16x8*)(lds + PG8_SA(b, h) + aoff + m * 2048 + k * 1024); } while (0)
; #define PG8_LDB(dst, b, h) do { _Pragma("unroll") for (int n = 0; n < 2; ++n) _Pragma("unroll") for (int k = 0; k < 2; ++k) dst[n][k] = *(const PG8_LAS bf16x8*)(lds + PG8_SB(b, h) + boff + n * 2048 + k * 1024); } while (0)
; #define PG8_BAR __builtin_amdgcn_s_barrier()
; #define PG8_SCHED __builtin_amdgcn_sched_barrier(0)
; template <class Epi, class Sched, bool ALIGN_EPI = false, bool SP2 = false, bool ABLK = false, bool BBLK = false>
; __device__ __forceinline__ void gemm_phase(PG8_LAS unsigned char* lds, const Gemm g, const Sched& S, const Epi& E) {
;     ...
;         const bool has_next = S.next(ui + 1, nxt);
;         const char* nA = has_next ? (const char*)g.A + (size_t)nxt.pm * tstepA : cA; const char* nB = has_next ? (const char*)g.Bt + (size_t)nxt.pn * tstepB : cB;
;         for (int t = 0; t < nt; t += 2) {
;             const bool last = (t == nt - 2);
;             const char* a1 = cA + (size_t)(t + 1) * kstepA;
;             const char* a2 = last ? nA : cA + (size_t)(t + 2) * kstepA; const char* b2 = last ? nB : cB + (size_t)(t + 2) * kstepB;
;             const char* a3 = a2 + kstepA; const char* b3 = b2 + kstepB;
;             if (last && has_next) S.a_ready(nxt);
;             if constexpr (SP2) {
;             PG8_LDB(B0, 0, 0); PG8_LDB(B1, 0, 1); PG8_SCHED; PG8_LDA(At, 0, 0); PG8_STAGE(PG8_SA(1, 1), a1 + hstepA, voffA);
;     ...
;         for (int a = 0; a < 2; ++a)
; #pragma unroll
;             for (int b = 0; b < 2; ++b)
; #pragma unroll
;                 for (int m = 0; m < 4; ++m)
; #pragma unroll
;                     for (int n = 0; n < 2; ++n) acc[a][b][m][n] = (f32x4){0.f, 0.f, 0.f, 0.f};
;         cur = nxt; cA = nA; cB = nB; ++ui;
;         if constexpr (ALIGN_EPI) { if (wr == 1) PG8_BAR; }
.LBB0_593:
	s_ashr_i32 s21, s20, 31
	s_lshl_b64 s[24:25], s[20:21], 20
	s_add_u32 s24, s51, s24
	s_addc_u32 s25, s53, s25
	s_and_b64 s[26:27], s[6:7], exec
	s_cselect_b32 s9, s25, s1
	s_cselect_b32 s16, s24, s0
	s_ashr_i32 s23, s22, 31
	s_lshl_b64 s[26:27], s[22:23], 20
	s_add_u32 s26, s44, s26
	s_addc_u32 s27, s45, s27
	s_and_b64 s[34:35], s[6:7], exec
	s_cselect_b32 s21, s27, s31
	s_cselect_b32 s23, s26, s30
	s_add_u32 s0, s0, 0xc000
	s_addc_u32 s1, s1, 0
	s_add_u32 s29, s30, 0x10000
	v_mov_b32_e32 v2, 0
	s_addc_u32 s40, s31, 0
	s_mov_b32 s41, -2
	v_mov_b32_e32 v3, v2
	v_mov_b32_e32 v4, v2
	v_mov_b32_e32 v5, v2
	v_mov_b32_e32 v6, v2
	v_mov_b32_e32 v7, v2
	v_mov_b32_e32 v8, v2
	v_mov_b32_e32 v9, v2
	s_waitcnt vmcnt(0)
	v_mov_b32_e32 v18, v2
	v_mov_b32_e32 v19, v2
	v_mov_b32_e32 v20, v2
	v_mov_b32_e32 v21, v2
	v_mov_b32_e32 v22, v2
	v_mov_b32_e32 v23, v2
	v_mov_b32_e32 v24, v2
	v_mov_b32_e32 v25, v2
	v_mov_b32_e32 v34, v2
	v_mov_b32_e32 v35, v2
	v_mov_b32_e32 v36, v2
	v_mov_b32_e32 v37, v2
	v_mov_b32_e32 v38, v2
	v_mov_b32_e32 v39, v2
	v_mov_b32_e32 v40, v2
	v_mov_b32_e32 v41, v2
	v_mov_b32_e32 v50, v2
	v_mov_b32_e32 v51, v2
	v_mov_b32_e32 v52, v2
	v_mov_b32_e32 v53, v2
	v_mov_b32_e32 v54, v2
	v_mov_b32_e32 v55, v2
	v_mov_b32_e32 v56, v2
	v_mov_b32_e32 v57, v2
	v_mov_b32_e32 v10, v2
	v_mov_b32_e32 v11, v2
	v_mov_b32_e32 v12, v2
	v_mov_b32_e32 v13, v2
	v_mov_b32_e32 v14, v2
	v_mov_b32_e32 v15, v2
	v_mov_b32_e32 v16, v2
	v_mov_b32_e32 v17, v2
	v_mov_b32_e32 v26, v2
	v_mov_b32_e32 v27, v2
	v_mov_b32_e32 v28, v2
	v_mov_b32_e32 v29, v2
	v_mov_b32_e32 v30, v2
	v_mov_b32_e32 v31, v2
	v_mov_b32_e32 v32, v2
	v_mov_b32_e32 v33, v2
	v_mov_b32_e32 v42, v2
	v_mov_b32_e32 v43, v2
	v_mov_b32_e32 v44, v2
	v_mov_b32_e32 v45, v2
	v_mov_b32_e32 v46, v2
	v_mov_b32_e32 v47, v2
	v_mov_b32_e32 v48, v2
	v_mov_b32_e32 v49, v2
	v_mov_b32_e32 v58, v2
	v_mov_b32_e32 v59, v2
	v_mov_b32_e32 v60, v2
	v_mov_b32_e32 v61, v2
	v_mov_b32_e32 v62, v2
	v_mov_b32_e32 v63, v2
	v_mov_b32_e32 v64, v2
	v_mov_b32_e32 v65, v2
	v_mov_b32_e32 v66, v2
	v_mov_b32_e32 v67, v2
	v_mov_b32_e32 v68, v2
	v_mov_b32_e32 v69, v2
	v_mov_b32_e32 v70, v2
	v_mov_b32_e32 v71, v2
	v_mov_b32_e32 v72, v2
	v_mov_b32_e32 v73, v2
	v_mov_b32_e32 v82, v2
	v_mov_b32_e32 v83, v2
	v_mov_b32_e32 v84, v2
	v_mov_b32_e32 v85, v2
	v_mov_b32_e32 v86, v2
	v_mov_b32_e32 v87, v2
	v_mov_b32_e32 v88, v2
	v_mov_b32_e32 v89, v2
	v_mov_b32_e32 v98, v2
	v_mov_b32_e32 v99, v2
	v_mov_b32_e32 v100, v2
	v_mov_b32_e32 v101, v2
	v_mov_b32_e32 v102, v2
	v_mov_b32_e32 v103, v2
	v_mov_b32_e32 v104, v2
	v_mov_b32_e32 v105, v2
	v_mov_b32_e32 v114, v2
	v_mov_b32_e32 v115, v2
	v_mov_b32_e32 v116, v2
	v_mov_b32_e32 v117, v2
	v_mov_b32_e32 v118, v2
	v_mov_b32_e32 v119, v2
	v_mov_b32_e32 v120, v2
	v_mov_b32_e32 v121, v2
	v_mov_b32_e32 v74, v2
	v_mov_b32_e32 v75, v2
	v_mov_b32_e32 v76, v2
	v_mov_b32_e32 v77, v2
	v_mov_b32_e32 v78, v2
	v_mov_b32_e32 v79, v2
	v_mov_b32_e32 v80, v2
	v_mov_b32_e32 v81, v2
	v_mov_b32_e32 v90, v2
	v_mov_b32_e32 v91, v2
	v_mov_b32_e32 v92, v2
	v_mov_b32_e32 v93, v2
	v_mov_b32_e32 v94, v2
	v_mov_b32_e32 v95, v2
	v_mov_b32_e32 v96, v2
	v_mov_b32_e32 v97, v2
	v_mov_b32_e32 v106, v2
	v_mov_b32_e32 v107, v2
	v_mov_b32_e32 v108, v2
	v_mov_b32_e32 v109, v2
	v_mov_b32_e32 v110, v2
	v_mov_b32_e32 v111, v2
	v_mov_b32_e32 v112, v2
	v_mov_b32_e32 v113, v2
	v_mov_b32_e32 v122, v2
	v_mov_b32_e32 v123, v2
	v_mov_b32_e32 v124, v2
	v_mov_b32_e32 v125, v2
	v_mov_b32_e32 v126, v2
	v_mov_b32_e32 v127, v2
	v_mov_b32_e32 v128, v2
	v_mov_b32_e32 v129, v2
	s_and_b64 vcc, exec, s[18:19]
	s_cbranch_vccnz .Lrb_ma
	s_barrier
.Lrb_ma:
.LBB0_594:
	s_add_u32 s30, s0, 0x4000
	s_addc_u32 s31, s1, 0
	s_cmp_eq_u32 s41, 28
	s_cselect_b32 s36, s16, s30
	s_cselect_b32 s37, s9, s31
	s_cselect_b32 s34, s23, s29
	s_cselect_b32 s35, s21, s40
	s_add_u32 s30, s36, 0x8000
	s_addc_u32 s31, s37, 0
	s_add_i32 s60, 0, 0x10000
	s_add_i32 s75, 0, 0x14000
	v_add_u32_e32 v142, s60, v169
	v_add_u32_e32 v171, s75, v169
	ds_read_b128 v[130:133], v142
	ds_read_b128 v[134:137], v142 offset:1024
	ds_read_b128 v[138:141], v142 offset:2048
	ds_read_b128 v[142:145], v142 offset:3072
	ds_read_b128 v[160:163], v171
	ds_read_b128 v[164:167], v171 offset:1024
	ds_read_b128 v[172:175], v171 offset:2048
	ds_read_b128 v[176:179], v171 offset:3072
	v_lshl_add_u64 v[184:185], s[0:1], 0, v[156:157]
	s_add_i32 m0, s83, 0xc000
	ds_read_b128 v[180:183], v170
	ds_read_b128 v[196:199], v170 offset:1024
	ds_read_b128 v[200:203], v170 offset:2048
	ds_read_b128 v[204:207], v170 offset:3072
	ds_read_b128 v[208:211], v170 offset:4096
	ds_read_b128 v[212:215], v170 offset:5120
	ds_read_b128 v[216:219], v170 offset:6144
	ds_read_b128 v[220:223], v170 offset:7168
	global_load_lds_dwordx4 v[184:185], off
	v_lshl_add_u64 v[184:185], s[0:1], 0, v[158:159]
	s_add_i32 m0, s83, 0xe000
	s_nop 0
	global_load_lds_dwordx4 v[184:185], off
	s_waitcnt vmcnt(8)
	s_waitcnt lgkmcnt(0)
	s_barrier
; #define PG8_STAGE(bufoff, gbase, voff) do { _Pragma("unroll") for (int _i = 0; _i < 2; ++_i) \
;         __builtin_amdgcn_global_load_lds((const unsigned*)((const char*)(gbase) + (voff)[_i]), (PG8_LAS unsigned*)(lds + (bufoff) + ldsw + _i * 8192), 16, 0, 0); } while (0)
; #define PG8_LDA(dst, b, h) do { _Pragma("unroll") for (int m = 0; m < 4; ++m) _Pragma("unroll") for (int k = 0; k < 2; ++k) dst[m][k] = *(const PG8_LAS bf16x8*)(lds + PG8_SA(b, h) + aoff + m * 2048 + k * 1024); } while (0)
; #define PG8_MMA(ai, bj, At, Bt) do { __builtin_amdgcn_s_setprio(1); _Pragma("unroll") for (int m = 0; m < 4; ++m) _Pragma("unroll") for (int n = 0; n < 2; ++n) _Pragma("unroll") for (int k = 0; k < 2; ++k) \
;         acc[ai][bj][m][n] = __builtin_amdgcn_mfma_f32_16x16x32_bf16(Bt[n][k], At[m][k], acc[ai][bj][m][n], 0, 0, 0); __builtin_amdgcn_s_setprio(0); } while (0)
; #define PG8_WAIT_V(n) asm volatile("s_waitcnt vmcnt(" #n ")" ::: "memory")
; #define PG8_WAIT_L(n) asm volatile("s_waitcnt lgkmcnt(" #n ")" ::: "memory")
; #define PG8_BAR __builtin_amdgcn_s_barrier()
; #define PG8_SCHED __builtin_amdgcn_sched_barrier(0)
; template <class Epi, class Sched, bool ALIGN_EPI = false, bool SP2 = false, bool ABLK = false, bool BBLK = false>
; __device__ __forceinline__ void gemm_phase(PG8_LAS unsigned char* lds, const Gemm g, const Sched& S, const Epi& E) {
;     ...
;             PG8_WAIT_V(8); PG8_WAIT_L(0); PG8_BAR; PG8_MMA(0, 0, At, B0); PG8_MMA(0, 1, At, B1); PG8_BAR; PG8_SCHED;
;             PG8_LDA(At, 0, 1); PG8_STAGE(PG8_SB(0, 0), b2, voffB); PG8_STAGE(PG8_SB(0, 1), b2 + hstepB, voffB); PG8_STAGE(PG8_SA(0, 0), a2, voffA);
;             PG8_WAIT_V(8); PG8_WAIT_L(0); PG8_BAR; PG8_MMA(1, 0, At, B0); PG8_MMA(1, 1, At, B1); PG8_BAR; PG8_SCHED;
	s_setprio 1
	s_waitcnt lgkmcnt(0)
	v_mfma_f32_16x16x32_bf16 v[126:129], v[130:133], v[180:183], v[126:129]
	v_mfma_f32_16x16x32_bf16 v[122:125], v[138:141], v[180:183], v[122:125]
	v_mfma_f32_16x16x32_bf16 v[110:113], v[130:133], v[200:203], v[110:113]
	v_mfma_f32_16x16x32_bf16 v[106:109], v[138:141], v[200:203], v[106:109]
	v_mfma_f32_16x16x32_bf16 v[94:97], v[130:133], v[208:211], v[94:97]
	v_mfma_f32_16x16x32_bf16 v[90:93], v[138:141], v[208:211], v[90:93]
	v_mfma_f32_16x16x32_bf16 v[78:81], v[130:133], v[216:219], v[78:81]
	v_mfma_f32_16x16x32_bf16 v[74:77], v[138:141], v[216:219], v[74:77]
	v_mfma_f32_16x16x32_bf16 v[126:129], v[134:137], v[196:199], v[126:129]
	v_mfma_f32_16x16x32_bf16 v[122:125], v[142:145], v[196:199], v[122:125]
	v_mfma_f32_16x16x32_bf16 v[110:113], v[134:137], v[204:207], v[110:113]
	v_mfma_f32_16x16x32_bf16 v[106:109], v[142:145], v[204:207], v[106:109]
	v_mfma_f32_16x16x32_bf16 v[94:97], v[134:137], v[212:215], v[94:97]
	v_mfma_f32_16x16x32_bf16 v[90:93], v[142:145], v[212:215], v[90:93]
	v_mfma_f32_16x16x32_bf16 v[78:81], v[134:137], v[220:223], v[78:81]
	v_mfma_f32_16x16x32_bf16 v[74:77], v[142:145], v[220:223], v[74:77]
	s_setprio 0
	s_setprio 1
	v_mfma_f32_16x16x32_bf16 v[118:121], v[160:163], v[180:183], v[118:121]
	v_mfma_f32_16x16x32_bf16 v[114:117], v[172:175], v[180:183], v[114:117]
	v_mfma_f32_16x16x32_bf16 v[102:105], v[160:163], v[200:203], v[102:105]
	v_mfma_f32_16x16x32_bf16 v[98:101], v[172:175], v[200:203], v[98:101]
	v_mfma_f32_16x16x32_bf16 v[86:89], v[160:163], v[208:211], v[86:89]
	v_mfma_f32_16x16x32_bf16 v[82:85], v[172:175], v[208:211], v[82:85]
	v_mfma_f32_16x16x32_bf16 v[70:73], v[160:163], v[216:219], v[70:73]
	v_mfma_f32_16x16x32_bf16 v[66:69], v[172:175], v[216:219], v[66:69]
	v_mfma_f32_16x16x32_bf16 v[118:121], v[164:167], v[196:199], v[118:121]
	v_mfma_f32_16x16x32_bf16 v[114:117], v[176:179], v[196:199], v[114:117]
	v_mfma_f32_16x16x32_bf16 v[102:105], v[164:167], v[204:207], v[102:105]
	v_mfma_f32_16x16x32_bf16 v[98:101], v[176:179], v[204:207], v[98:101]
	v_mfma_f32_16x16x32_bf16 v[86:89], v[164:167], v[212:215], v[86:89]
	v_mfma_f32_16x16x32_bf16 v[82:85], v[176:179], v[212:215], v[82:85]
	v_mfma_f32_16x16x32_bf16 v[70:73], v[164:167], v[220:223], v[70:73]
	v_mfma_f32_16x16x32_bf16 v[66:69], v[176:179], v[220:223], v[66:69]
	s_setprio 0
	s_barrier
	s_add_i32 s60, s60, s81
	v_lshl_add_u64 v[184:185], s[34:35], 0, v[148:149]
	s_mov_b32 m0, s60
	ds_read_b128 v[180:183], v170 offset:16384
	ds_read_b128 v[196:199], v170 offset:17408
	ds_read_b128 v[200:203], v170 offset:18432
	ds_read_b128 v[204:207], v170 offset:19456
	ds_read_b128 v[208:211], v170 offset:20480
	ds_read_b128 v[212:215], v170 offset:21504
	ds_read_b128 v[216:219], v170 offset:22528
	ds_read_b128 v[220:223], v170 offset:23552
	global_load_lds_dwordx4 v[184:185], off
	s_add_i32 m0, s60, 0x2000
	s_add_u32 s60, s34, 0x4000
	v_lshl_add_u64 v[184:185], s[34:35], 0, v[152:153]
	s_addc_u32 s61, s35, 0
	s_add_i32 s75, s75, s81
	global_load_lds_dwordx4 v[184:185], off
	v_lshl_add_u64 v[184:185], s[60:61], 0, v[148:149]
	s_mov_b32 m0, s75
	s_nop 0
	global_load_lds_dwordx4 v[184:185], off
	v_lshl_add_u64 v[184:185], s[60:61], 0, v[152:153]
	s_add_i32 m0, s75, 0x2000
	s_nop 0
	global_load_lds_dwordx4 v[184:185], off
	v_lshl_add_u64 v[184:185], s[36:37], 0, v[146:147]
	s_mov_b32 m0, s83
	s_nop 0
	global_load_lds_dwordx4 v[184:185], off
	v_lshl_add_u64 v[184:185], s[36:37], 0, v[150:151]
	s_mov_b32 m0, s84
	s_nop 0
	global_load_lds_dwordx4 v[184:185], off
	s_waitcnt vmcnt(8)
	s_waitcnt lgkmcnt(0)
	s_barrier
	s_setprio 1
	s_waitcnt lgkmcnt(0)
	v_mfma_f32_16x16x32_bf16 v[62:65], v[130:133], v[180:183], v[62:65]
	v_mfma_f32_16x16x32_bf16 v[58:61], v[138:141], v[180:183], v[58:61]
	v_mfma_f32_16x16x32_bf16 v[46:49], v[130:133], v[200:203], v[46:49]
	v_mfma_f32_16x16x32_bf16 v[42:45], v[138:141], v[200:203], v[42:45]
	v_mfma_f32_16x16x32_bf16 v[30:33], v[130:133], v[208:211], v[30:33]
	v_mfma_f32_16x16x32_bf16 v[26:29], v[138:141], v[208:211], v[26:29]
	v_mfma_f32_16x16x32_bf16 v[14:17], v[130:133], v[216:219], v[14:17]
	v_mfma_f32_16x16x32_bf16 v[10:13], v[138:141], v[216:219], v[10:13]
	v_mfma_f32_16x16x32_bf16 v[62:65], v[134:137], v[196:199], v[62:65]
	v_mfma_f32_16x16x32_bf16 v[58:61], v[142:145], v[196:199], v[58:61]
	v_mfma_f32_16x16x32_bf16 v[46:49], v[134:137], v[204:207], v[46:49]
	v_mfma_f32_16x16x32_bf16 v[42:45], v[142:145], v[204:207], v[42:45]
	v_mfma_f32_16x16x32_bf16 v[30:33], v[134:137], v[212:215], v[30:33]
	v_mfma_f32_16x16x32_bf16 v[26:29], v[142:145], v[212:215], v[26:29]
	v_mfma_f32_16x16x32_bf16 v[14:17], v[134:137], v[220:223], v[14:17]
	v_mfma_f32_16x16x32_bf16 v[10:13], v[142:145], v[220:223], v[10:13]
	s_setprio 0
	s_setprio 1
	v_mfma_f32_16x16x32_bf16 v[54:57], v[160:163], v[180:183], v[54:57]
	v_mfma_f32_16x16x32_bf16 v[50:53], v[172:175], v[180:183], v[50:53]
	v_mfma_f32_16x16x32_bf16 v[38:41], v[160:163], v[200:203], v[38:41]
	v_mfma_f32_16x16x32_bf16 v[34:37], v[172:175], v[200:203], v[34:37]
	v_mfma_f32_16x16x32_bf16 v[22:25], v[160:163], v[208:211], v[22:25]
	v_mfma_f32_16x16x32_bf16 v[18:21], v[172:175], v[208:211], v[18:21]
	v_mfma_f32_16x16x32_bf16 v[6:9], v[160:163], v[216:219], v[6:9]
	v_mfma_f32_16x16x32_bf16 v[2:5], v[172:175], v[216:219], v[2:5]
	v_mfma_f32_16x16x32_bf16 v[54:57], v[164:167], v[196:199], v[54:57]
	v_mfma_f32_16x16x32_bf16 v[50:53], v[176:179], v[196:199], v[50:53]
	v_mfma_f32_16x16x32_bf16 v[38:41], v[164:167], v[204:207], v[38:41]
	v_mfma_f32_16x16x32_bf16 v[34:37], v[176:179], v[204:207], v[34:37]
	v_mfma_f32_16x16x32_bf16 v[22:25], v[164:167], v[212:215], v[22:25]
	v_mfma_f32_16x16x32_bf16 v[18:21], v[176:179], v[212:215], v[18:21]
	v_mfma_f32_16x16x32_bf16 v[6:9], v[164:167], v[220:223], v[6:9]
	v_mfma_f32_16x16x32_bf16 v[2:5], v[176:179], v[220:223], v[2:5]
	s_setprio 0
	s_barrier
; #define PG8_STAGE(bufoff, gbase, voff) do { _Pragma("unroll") for (int _i = 0; _i < 2; ++_i) \
;         __builtin_amdgcn_global_load_lds((const unsigned*)((const char*)(gbase) + (voff)[_i]), (PG8_LAS unsigned*)(lds + (bufoff) + ldsw + _i * 8192), 16, 0, 0); } while (0)
; #define PG8_LDA(dst, b, h) do { _Pragma("unroll") for (int m = 0; m < 4; ++m) _Pragma("unroll") for (int k = 0; k < 2; ++k) dst[m][k] = *(const PG8_LAS bf16x8*)(lds + PG8_SA(b, h) + aoff + m * 2048 + k * 1024); } while (0)
; #define PG8_LDB(dst, b, h) do { _Pragma("unroll") for (int n = 0; n < 2; ++n) _Pragma("unroll") for (int k = 0; k < 2; ++k) dst[n][k] = *(const PG8_LAS bf16x8*)(lds + PG8_SB(b, h) + boff + n * 2048 + k * 1024); } while (0)
; #define PG8_MMA(ai, bj, At, Bt) do { __builtin_amdgcn_s_setprio(1); _Pragma("unroll") for (int m = 0; m < 4; ++m) _Pragma("unroll") for (int n = 0; n < 2; ++n) _Pragma("unroll") for (int k = 0; k < 2; ++k) \
;         acc[ai][bj][m][n] = __builtin_amdgcn_mfma_f32_16x16x32_bf16(Bt[n][k], At[m][k], acc[ai][bj][m][n], 0, 0, 0); __builtin_amdgcn_s_setprio(0); } while (0)
; #define PG8_WAIT_V(n) asm volatile("s_waitcnt vmcnt(" #n ")" ::: "memory")
; #define PG8_WAIT_L(n) asm volatile("s_waitcnt lgkmcnt(" #n ")" ::: "memory")
; #define PG8_BAR __builtin_amdgcn_s_barrier()
; #define PG8_SCHED __builtin_amdgcn_sched_barrier(0)
; template <class Epi, class Sched, bool ALIGN_EPI = false, bool SP2 = false, bool ABLK = false, bool BBLK = false>
; __device__ __forceinline__ void gemm_phase(PG8_LAS unsigned char* lds, const Gemm g, const Sched& S, const Epi& E) {
;     ...
;             PG8_LDB(B0, 1, 0); PG8_LDB(B1, 1, 1); PG8_SCHED; PG8_LDA(At, 1, 0); PG8_STAGE(PG8_SA(0, 1), a2 + hstepA, voffA);
;             PG8_WAIT_V(8); PG8_WAIT_L(0); PG8_BAR; PG8_MMA(0, 0, At, B0); PG8_MMA(0, 1, At, B1); PG8_BAR; PG8_SCHED;
	s_add_i32 s60, 0, 0x18000
	s_add_i32 s61, 0, 0x1c000
	v_add_u32_e32 v142, s60, v169
	v_add_u32_e32 v171, s61, v169
	ds_read_b128 v[130:133], v142
	ds_read_b128 v[134:137], v142 offset:1024
	ds_read_b128 v[138:141], v142 offset:2048
	ds_read_b128 v[142:145], v142 offset:3072
	ds_read_b128 v[160:163], v171
	ds_read_b128 v[164:167], v171 offset:1024
	ds_read_b128 v[172:175], v171 offset:2048
	ds_read_b128 v[176:179], v171 offset:3072
	s_add_u32 s36, s36, 0x4000
	s_addc_u32 s37, s37, 0
	s_mov_b32 m0, s86
	v_lshl_add_u64 v[184:185], s[36:37], 0, v[146:147]
	ds_read_b128 v[180:183], v170 offset:32768
	ds_read_b128 v[196:199], v170 offset:33792
	ds_read_b128 v[200:203], v170 offset:34816
	ds_read_b128 v[204:207], v170 offset:35840
	ds_read_b128 v[208:211], v170 offset:36864
	ds_read_b128 v[212:215], v170 offset:37888
	ds_read_b128 v[216:219], v170 offset:38912
	ds_read_b128 v[220:223], v170 offset:39936
	global_load_lds_dwordx4 v[184:185], off
	v_lshl_add_u64 v[184:185], s[36:37], 0, v[150:151]
	s_mov_b32 m0, s88
	s_nop 0
	global_load_lds_dwordx4 v[184:185], off
	s_waitcnt vmcnt(8)
	s_waitcnt lgkmcnt(0)
	s_barrier
	s_setprio 1
	s_waitcnt lgkmcnt(0)
	v_mfma_f32_16x16x32_bf16 v[126:129], v[130:133], v[180:183], v[126:129]
	v_mfma_f32_16x16x32_bf16 v[122:125], v[138:141], v[180:183], v[122:125]
	v_mfma_f32_16x16x32_bf16 v[110:113], v[130:133], v[200:203], v[110:113]
	v_mfma_f32_16x16x32_bf16 v[106:109], v[138:141], v[200:203], v[106:109]
	v_mfma_f32_16x16x32_bf16 v[94:97], v[130:133], v[208:211], v[94:97]
	v_mfma_f32_16x16x32_bf16 v[90:93], v[138:141], v[208:211], v[90:93]
	v_mfma_f32_16x16x32_bf16 v[78:81], v[130:133], v[216:219], v[78:81]
	v_mfma_f32_16x16x32_bf16 v[74:77], v[138:141], v[216:219], v[74:77]
	v_mfma_f32_16x16x32_bf16 v[126:129], v[134:137], v[196:199], v[126:129]
	v_mfma_f32_16x16x32_bf16 v[122:125], v[142:145], v[196:199], v[122:125]
	v_mfma_f32_16x16x32_bf16 v[110:113], v[134:137], v[204:207], v[110:113]
	v_mfma_f32_16x16x32_bf16 v[106:109], v[142:145], v[204:207], v[106:109]
	v_mfma_f32_16x16x32_bf16 v[94:97], v[134:137], v[212:215], v[94:97]
	v_mfma_f32_16x16x32_bf16 v[90:93], v[142:145], v[212:215], v[90:93]
	v_mfma_f32_16x16x32_bf16 v[78:81], v[134:137], v[220:223], v[78:81]
	v_mfma_f32_16x16x32_bf16 v[74:77], v[142:145], v[220:223], v[74:77]
	s_setprio 0
	s_setprio 1
	v_mfma_f32_16x16x32_bf16 v[118:121], v[160:163], v[180:183], v[118:121]
	v_mfma_f32_16x16x32_bf16 v[114:117], v[172:175], v[180:183], v[114:117]
	v_mfma_f32_16x16x32_bf16 v[102:105], v[160:163], v[200:203], v[102:105]
	v_mfma_f32_16x16x32_bf16 v[98:101], v[172:175], v[200:203], v[98:101]
	v_mfma_f32_16x16x32_bf16 v[86:89], v[160:163], v[208:211], v[86:89]
	v_mfma_f32_16x16x32_bf16 v[82:85], v[172:175], v[208:211], v[82:85]
	v_mfma_f32_16x16x32_bf16 v[70:73], v[160:163], v[216:219], v[70:73]
	v_mfma_f32_16x16x32_bf16 v[66:69], v[172:175], v[216:219], v[66:69]
	v_mfma_f32_16x16x32_bf16 v[118:121], v[164:167], v[196:199], v[118:121]
	v_mfma_f32_16x16x32_bf16 v[114:117], v[176:179], v[196:199], v[114:117]
	v_mfma_f32_16x16x32_bf16 v[102:105], v[164:167], v[204:207], v[102:105]
	v_mfma_f32_16x16x32_bf16 v[98:101], v[176:179], v[204:207], v[98:101]
	v_mfma_f32_16x16x32_bf16 v[86:89], v[164:167], v[212:215], v[86:89]
	v_mfma_f32_16x16x32_bf16 v[82:85], v[176:179], v[212:215], v[82:85]
	v_mfma_f32_16x16x32_bf16 v[70:73], v[164:167], v[220:223], v[70:73]
	v_mfma_f32_16x16x32_bf16 v[66:69], v[176:179], v[220:223], v[66:69]
	s_setprio 0
	s_barrier
; #define PG8_STAGE(bufoff, gbase, voff) do { _Pragma("unroll") for (int _i = 0; _i < 2; ++_i) \
;         __builtin_amdgcn_global_load_lds((const unsigned*)((const char*)(gbase) + (voff)[_i]), (PG8_LAS unsigned*)(lds + (bufoff) + ldsw + _i * 8192), 16, 0, 0); } while (0)
; #define PG8_LDA(dst, b, h) do { _Pragma("unroll") for (int m = 0; m < 4; ++m) _Pragma("unroll") for (int k = 0; k < 2; ++k) dst[m][k] = *(const PG8_LAS bf16x8*)(lds + PG8_SA(b, h) + aoff + m * 2048 + k * 1024); } while (0)
; template <class Epi, class Sched, bool ALIGN_EPI = false, bool SP2 = false, bool ABLK = false, bool BBLK = false>
; __device__ __forceinline__ void gemm_phase(PG8_LAS unsigned char* lds, const Gemm g, const Sched& S, const Epi& E) {
;     ...
;             PG8_LDA(At, 1, 1); PG8_STAGE(PG8_SB(1, 0), b3, voffB); PG8_STAGE(PG8_SB(1, 1), b3 + hstepB, voffB); PG8_STAGE(PG8_SA(1, 0), a3, voffA);
;             PG8_WAIT_V(8); PG8_WAIT_L(0); PG8_BAR; PG8_MMA(1, 0, At, B0); PG8_MMA(1, 1, At, B1); PG8_BAR; PG8_SCHED;
;             } else {
;             PG8_LDB(B0, 0, 0); PG8_SCHED; PG8_LDA(At, 0, 0); PG8_STAGE(PG8_SA(1, 1), a1 + hstepA, voffA);
;             PG8_WAIT_L(8); PG8_BAR; PG8_WAIT_L(0); PG8_MMA(0, 0, At, B0); PG8_BAR; PG8_SCHED;
;             PG8_LDB(B1, 0, 1); PG8_STAGE(PG8_SB(0, 0), b2, voffB);
;             PG8_BAR; PG8_WAIT_L(0); PG8_MMA(0, 1, At, B1); PG8_BAR;
;             PG8_LDA(At, 0, 1); PG8_STAGE(PG8_SA(0, 0), a2, voffA);
;             PG8_BAR; PG8_WAIT_L(0); PG8_MMA(1, 0, At, B0); PG8_BAR; PG8_SCHED;
;             PG8_STAGE(PG8_SB(0, 1), b2 + hstepB, voffB);
;             PG8_WAIT_V(6); PG8_BAR; PG8_MMA(1, 1, At, B1); PG8_BAR;
;             PG8_LDB(B0, 1, 0); PG8_SCHED; PG8_LDA(At, 1, 0); PG8_STAGE(PG8_SA(0, 1), a2 + hstepA, voffA);
;             PG8_WAIT_L(8); PG8_BAR; PG8_WAIT_L(0); PG8_MMA(0, 0, At, B0); PG8_BAR; PG8_SCHED;
;             PG8_LDB(B1, 1, 1); PG8_STAGE(PG8_SB(1, 0), b3, voffB);
;             PG8_BAR; PG8_WAIT_L(0); PG8_MMA(0, 1, At, B1); PG8_BAR;
;             PG8_LDA(At, 1, 1); PG8_STAGE(PG8_SA(1, 0), a3, voffA);
;             PG8_BAR; PG8_WAIT_L(0); PG8_MMA(1, 0, At, B0); PG8_BAR; PG8_SCHED;
;             PG8_STAGE(PG8_SB(1, 1), b3 + hstepB, voffB);
;             PG8_WAIT_V(6); PG8_BAR; PG8_MMA(1, 1, At, B1); PG8_BAR;
;             }
;         }
;         if constexpr (ALIGN_EPI) { if (wr == 0) PG8_BAR; }
	s_add_u32 s36, s34, 0x8000
	s_addc_u32 s37, s35, 0
	s_add_i32 s60, s60, s81
	v_lshl_add_u64 v[184:185], s[36:37], 0, v[148:149]
	s_mov_b32 m0, s60
	ds_read_b128 v[180:183], v170 offset:49152
	ds_read_b128 v[196:199], v170 offset:50176
	ds_read_b128 v[200:203], v170 offset:51200
	ds_read_b128 v[204:207], v170 offset:52224
	ds_read_b128 v[208:211], v170 offset:53248
	ds_read_b128 v[212:215], v170 offset:54272
	ds_read_b128 v[216:219], v170 offset:55296
	ds_read_b128 v[220:223], v170 offset:56320
	global_load_lds_dwordx4 v[184:185], off
	s_add_i32 m0, s60, 0x2000
	s_add_u32 s34, s34, 0xc000
	v_lshl_add_u64 v[184:185], s[36:37], 0, v[152:153]
	s_addc_u32 s35, s35, 0
	s_add_i32 s36, s61, s81
	global_load_lds_dwordx4 v[184:185], off
	v_lshl_add_u64 v[184:185], s[34:35], 0, v[148:149]
	s_mov_b32 m0, s36
	s_nop 0
	global_load_lds_dwordx4 v[184:185], off
	v_lshl_add_u64 v[184:185], s[34:35], 0, v[152:153]
	s_add_i32 m0, s36, 0x2000
	s_nop 0
	global_load_lds_dwordx4 v[184:185], off
	v_lshl_add_u64 v[184:185], s[30:31], 0, v[146:147]
	s_mov_b32 m0, s90
	s_nop 0
	global_load_lds_dwordx4 v[184:185], off
	v_lshl_add_u64 v[184:185], s[30:31], 0, v[150:151]
	s_mov_b32 m0, s91
	s_nop 0
	global_load_lds_dwordx4 v[184:185], off
	s_waitcnt vmcnt(8)
	s_waitcnt lgkmcnt(0)
	s_barrier
	s_setprio 1
	s_waitcnt lgkmcnt(0)
	v_mfma_f32_16x16x32_bf16 v[62:65], v[130:133], v[180:183], v[62:65]
	v_mfma_f32_16x16x32_bf16 v[58:61], v[138:141], v[180:183], v[58:61]
	v_mfma_f32_16x16x32_bf16 v[46:49], v[130:133], v[200:203], v[46:49]
	v_mfma_f32_16x16x32_bf16 v[42:45], v[138:141], v[200:203], v[42:45]
	v_mfma_f32_16x16x32_bf16 v[30:33], v[130:133], v[208:211], v[30:33]
	v_mfma_f32_16x16x32_bf16 v[26:29], v[138:141], v[208:211], v[26:29]
	v_mfma_f32_16x16x32_bf16 v[14:17], v[130:133], v[216:219], v[14:17]
	v_mfma_f32_16x16x32_bf16 v[10:13], v[138:141], v[216:219], v[10:13]
	v_mfma_f32_16x16x32_bf16 v[62:65], v[134:137], v[196:199], v[62:65]
	v_mfma_f32_16x16x32_bf16 v[58:61], v[142:145], v[196:199], v[58:61]
	v_mfma_f32_16x16x32_bf16 v[46:49], v[134:137], v[204:207], v[46:49]
	v_mfma_f32_16x16x32_bf16 v[42:45], v[142:145], v[204:207], v[42:45]
	v_mfma_f32_16x16x32_bf16 v[30:33], v[134:137], v[212:215], v[30:33]
	v_mfma_f32_16x16x32_bf16 v[26:29], v[142:145], v[212:215], v[26:29]
	v_mfma_f32_16x16x32_bf16 v[14:17], v[134:137], v[220:223], v[14:17]
	v_mfma_f32_16x16x32_bf16 v[10:13], v[142:145], v[220:223], v[10:13]
	s_setprio 0
	s_setprio 1
	v_mfma_f32_16x16x32_bf16 v[54:57], v[160:163], v[180:183], v[54:57]
	v_mfma_f32_16x16x32_bf16 v[50:53], v[172:175], v[180:183], v[50:53]
	v_mfma_f32_16x16x32_bf16 v[38:41], v[160:163], v[200:203], v[38:41]
	v_mfma_f32_16x16x32_bf16 v[34:37], v[172:175], v[200:203], v[34:37]
	v_mfma_f32_16x16x32_bf16 v[22:25], v[160:163], v[208:211], v[22:25]
	v_mfma_f32_16x16x32_bf16 v[18:21], v[172:175], v[208:211], v[18:21]
	v_mfma_f32_16x16x32_bf16 v[6:9], v[160:163], v[216:219], v[6:9]
	v_mfma_f32_16x16x32_bf16 v[2:5], v[172:175], v[216:219], v[2:5]
	v_mfma_f32_16x16x32_bf16 v[54:57], v[164:167], v[196:199], v[54:57]
	v_mfma_f32_16x16x32_bf16 v[50:53], v[176:179], v[196:199], v[50:53]
	v_mfma_f32_16x16x32_bf16 v[38:41], v[164:167], v[204:207], v[38:41]
	v_mfma_f32_16x16x32_bf16 v[34:37], v[176:179], v[204:207], v[34:37]
	v_mfma_f32_16x16x32_bf16 v[22:25], v[164:167], v[212:215], v[22:25]
	v_mfma_f32_16x16x32_bf16 v[18:21], v[176:179], v[212:215], v[18:21]
	v_mfma_f32_16x16x32_bf16 v[6:9], v[164:167], v[220:223], v[6:9]
	v_mfma_f32_16x16x32_bf16 v[2:5], v[176:179], v[220:223], v[2:5]
	s_setprio 0
	s_barrier
	s_add_i32 s41, s41, 2
	s_add_u32 s0, s0, 0x10000
	s_addc_u32 s1, s1, 0
	s_add_u32 s29, s29, 0x10000
	s_addc_u32 s40, s40, 0
	s_cmp_gt_u32 s41, 29
	s_cbranch_scc0 .LBB0_594
	s_and_b64 vcc, exec, s[18:19]
	s_cbranch_vccz .LBB0_597
	s_barrier

; __device__ __forceinline__ float fast_sigmoid(float x) { return __builtin_amdgcn_rcpf(1.0f + __builtin_amdgcn_exp2f(-1.4426950408889634f * x)); }
; __device__ __forceinline__ u32x4 pack8(const f32x4 v0, const f32x4 v1) { u32x4 w; w.x = cvt_pk_bf16(v0[0], v0[1]); w.y = cvt_pk_bf16(v0[2], v0[3]); w.z = cvt_pk_bf16(v1[0], v1[1]); w.w = cvt_pk_bf16(v1[2], v1[3]); return w; }
; #define PG8_BAR __builtin_amdgcn_s_barrier()
;     __device__ __forceinline__ void operator()(const f32x4 (&acc)[2][2][4][2], const Unit& u, int wr, int wc, int fr_, int fq) const {
;     ...
;                 for (int bj = 0; bj < 2; ++bj) { f32x4 v0 = acc[ai][bj][m][0], v1 = acc[ai][bj][m][1];
;                     v0 += bv[bj][0]; v1 += bv[bj][1];
;                     if (gate) {
; #pragma unroll
;                         for (int j = 0; j < 4; ++j) { v0[j] = fast_sigmoid(v0[j]); v1[j] = fast_sigmoid(v1[j]); } }
;                     *(u32x4*)(ob + (size_t)(ai * HALF + m * 16) * ld + bj * HALF) = pack8(v0, v1); }
; template <class Epi, class Sched, bool ALIGN_EPI = false, bool SP2 = false, bool ABLK = false, bool BBLK = false>
; __device__ __forceinline__ void gemm_phase(PG8_LAS unsigned char* lds, const Gemm g, const Sched& S, const Epi& E) {
;     ...
;         if (!has_next) break;
; #pragma unroll
;         for (int a = 0; a < 2; ++a)
; #pragma unroll
;             for (int b = 0; b < 2; ++b)
; #pragma unroll
;                 for (int m = 0; m < 4; ++m)
; #pragma unroll
;                     for (int n = 0; n < 2; ++n) acc[a][b][m][n] = (f32x4){0.f, 0.f, 0.f, 0.f};
;         cur = nxt; cA = nA; cB = nB; ++ui;
;         if constexpr (ALIGN_EPI) { if (wr == 1) PG8_BAR; }
.LBB0_645:
	s_andn2_b64 vcc, exec, s[6:7]
	s_mov_b64 s[0:1], -1
	v_cvt_pk_bf16_f32 v6, v6, v7
	v_cvt_pk_bf16_f32 v7, v8, v9
	v_cvt_pk_bf16_f32 v8, v2, v3
	v_cvt_pk_bf16_f32 v9, v4, v5
	global_store_dwordx4 v[10:11], v[6:9], off offset:256
	s_cbranch_vccnz .LBB0_590
	s_andn2_b64 vcc, exec, s[4:5]
	s_cbranch_vccnz .LBB0_589
	s_branch .LBB0_589

;     __device__ __forceinline__ bool next(int i, Unit& u) const {
;         const long L = (long)i * G + c; if (L >= total) return false;
;         if (nM1 == 144 && nN1 == 8 && nM2 == 0 && G == 256) {
;             const int xcd = c & 7, o = c >> 3;
;             const int grp = (i < 4) ? xcd * 4 + i : 32 + (xcd >> 1), idx = (i < 4) ? o : (xcd & 1) * 16 + o;
;             u.pm = grp * 4 + (idx & 3); u.pn = idx >> 2; return true; }
;         int w = (int)L; { const int q = total / NXCD, r = total % NXCD, xcd = w % NXCD, off = w / NXCD; w = (xcd < r ? xcd * (q + 1) : r * (q + 1) + (xcd - r) * q) + off; }
;         int nM = nM1, nN = nN1; const bool second = w >= n1; if (second) { w -= n1; nM = nM2; nN = nN2; }
;         const int wgm = 4;
;         const int nig = wgm * nN, gid = w / nig, fm = gid * wgm, gsz = (nM - fm) < wgm ? (nM - fm) : wgm;
;         int pm = fm + ((w % nig) % gsz), pn = (w % nig) / gsz;
;         if (second) { pm += pm2; pn = pn < split ? a0 + pn : a1 + pn; }
;         u.pm = pm; u.pn = pn; return true;
; template <class Epi, class Sched, bool ALIGN_EPI = false, bool SP2 = false, bool ABLK = false, bool BBLK = false>
; __device__ __forceinline__ void gemm_phase(PG8_LAS unsigned char* lds, const Gemm g, const Sched& S, const Epi& E) {
;     ...
;     for (int i = 0; i < 2; ++i) { int R, C; stage_rc(tid * 16 + i * 8192, R, C); const int Rb = Epi::PERM ? ((R & ~31) + perm32(R & 31)) : R;
;         voffA[i] = ABLK ? (unsigned)(R * BK + C) * 2u : (unsigned)(R * LDA + C) * 2u; voffB[i] = BBLK ? (unsigned)(Rb * BK + C) * 2u : (unsigned)(Rb * LDB + C) * 2u; }
;     const size_t kstep = (size_t)(BK * 2);
;     const size_t hstepa = (size_t)HALF * LDA * 2, hstepb = (size_t)HALF * LDB * 2;
;     const size_t kstepA = ABLK ? (size_t)BM * BK * 2 : kstep, hstepA = ABLK ? (size_t)HALF * BK * 2 : hstepa, tstepA = ABLK ? (size_t)nt * BM * BK * 2 : 2 * hstepa;
;     const size_t kstepB = BBLK ? (size_t)BM * BK * 2 : kstep, hstepB = BBLK ? (size_t)HALF * BK * 2 : hstepb, tstepB = BBLK ? (size_t)nt * BM * BK * 2 : 2 * hstepb;
;     const unsigned ldsw = (unsigned)wid * 1024u;
;     const int aoff = lds_byte(wr * 64 + fr, fq * 8), boff = lds_byte(wc * 32 + fr, fq * 8);
;     ...
;     Unit cur, nxt; int ui = 0;
;     if (!S.next(0, cur)) return;
;     f32x4 acc[2][2][4][2];
; #pragma unroll
;     for (int a = 0; a < 2; ++a)
; #pragma unroll
.LBB0_649:
	v_readlane_b32 s0, v254, 41
	v_readlane_b32 s1, v254, 42
	s_and_b64 s[0:1], s[0:1], exec
	s_movk_i32 s0, 0x90
	s_cselect_b32 s5, s0, 0x80
	s_abs_i32 s2, s42
	v_cvt_f32_u32_e32 v2, s2
	s_sub_i32 s3, 0, s2
	s_ashr_i32 s0, s42, 1
	s_add_i32 s0, s0, s46
	v_rcp_iflag_f32_e32 v2, v2
	s_ashr_i32 s1, s0, 31
	s_abs_i32 s0, s0
	v_writelane_b32 v254, s5, 32
	v_mul_f32_e32 v2, 0x4f7ffffe, v2
	v_cvt_u32_f32_e32 v2, v2
	s_nop 0
	v_readfirstlane_b32 s4, v2
	s_mul_i32 s3, s3, s4
	s_mul_hi_u32 s3, s4, s3
	s_add_i32 s4, s4, s3
	s_mul_hi_u32 s3, s0, s4
	s_mul_i32 s3, s3, s2
	s_sub_i32 s0, s0, s3
	s_sub_i32 s3, s0, s2
	s_cmp_ge_u32 s0, s2
	s_cselect_b32 s0, s3, s0
	s_sub_i32 s3, s0, s2
	s_cmp_ge_u32 s0, s2
	s_cselect_b32 s0, s3, s0
	s_xor_b32 s0, s0, s1
	s_sub_i32 s30, s0, s1
	s_lshl_b32 s16, s5, 1
	v_mov_b32_e32 v2, v0
	s_cmp_lt_i32 s30, s16
	s_nop 0
	v_readfirstlane_b32 s1, v2
	s_cbranch_scc0 .LBB0_673
	s_waitcnt vmcnt(10)
	v_lshlrev_b32_e32 v6, 4, v2
	v_add_u32_e32 v4, 0x2000, v6
	v_ashrrev_i32_e32 v3, 31, v4
	v_lshrrev_b32_e32 v3, 22, v3
	v_add_u32_e32 v3, v4, v3
	v_ashrrev_i32_e32 v3, 10, v3
	v_mul_i32_i24_e32 v5, 0x400, v3
	v_sub_u32_e32 v4, v4, v5
	v_lshrrev_b32_e32 v5, 4, v4
	v_bitop3_b32 v5, v5, v4, 32 bitop3:0x6c
	v_ashrrev_i32_e32 v4, 31, v5
	v_lshrrev_b32_e32 v4, 26, v4
	v_add_u32_e32 v7, v5, v4
	v_lshlrev_b32_e32 v8, 3, v3
	v_ashrrev_i32_e32 v4, 6, v7
	v_and_b32_e32 v8, -16, v8
	s_add_u32 s31, s43, 0x9d00000
	v_readlane_b32 s0, v254, 32
	v_add_u32_e32 v8, v4, v8
	s_addc_u32 s33, s50, 0
	s_lshr_b32 s35, s0, 2
	s_lshl_b32 s36, s0, 2
	v_and_b32_e32 v9, 3, v4
	s_mov_b32 s0, 0x1ffffe0
	s_waitcnt vmcnt(9)
	v_lshrrev_b32_e32 v10, 2, v8
	v_lshlrev_b32_e32 v11, 1, v8
	v_and_b32_e32 v7, 0xc0, v7
	v_and_or_b32 v9, v8, s0, v9
	v_and_b32_e32 v10, 4, v10
	v_and_b32_e32 v11, 24, v11
	v_sub_u32_e32 v5, v5, v7
	v_or3_b32 v9, v9, v10, v11
	v_lshlrev_b32_e32 v10, 5, v3
	v_ashrrev_i16_sdwa v5, v232, sext(v5) dst_sel:DWORD dst_unused:UNUSED_PAD src0_sel:DWORD src1_sel:BYTE_0
	v_and_b32_e32 v10, 32, v10
	v_bfe_i32 v5, v5, 0, 16
	v_add_lshl_u32 v7, v10, v5, 1
	v_lshl_add_u32 v130, v9, 7, v7
	v_lshl_add_u32 v132, v8, 7, v7
	v_bfe_i32 v7, v2, 27, 1
	v_lshrrev_b32_e32 v7, 22, v7
	v_add_u32_e32 v7, v6, v7
	v_and_b32_e32 v7, 0xfffffc00, v7
	v_sub_u32_e32 v6, v6, v7
	v_lshrrev_b32_e32 v7, 4, v6
	v_bitop3_b32 v8, v7, v6, 32 bitop3:0x6c
	v_ashrrev_i32_e32 v7, 31, v2
	v_lshrrev_b32_e32 v7, 26, v7
	v_ashrrev_i32_e32 v6, 31, v8
	v_add_u32_e32 v7, v2, v7
	v_lshrrev_b32_e32 v6, 26, v6
	v_ashrrev_i32_e32 v7, 6, v7
	v_add_u32_e32 v9, v8, v6
	v_lshlrev_b32_e32 v10, 3, v7
	v_ashrrev_i32_e32 v6, 6, v9
	v_and_b32_e32 v10, -16, v10
	s_ashr_i32 s34, s30, 31
	v_add_u32_e32 v10, v6, v10
	v_and_b32_e32 v11, 3, v6
	v_and_or_b32 v11, v10, s0, v11
	s_lshr_b32 s0, s34, 29
	s_add_i32 s0, s30, s0
	s_ashr_i32 s4, s0, 3
	s_and_b32 s0, s0, -8
	s_sub_i32 s0, s30, s0
	s_lshr_b32 s5, s0, 31
	s_or_b32 s5, s35, s5
	s_ashr_i32 s3, s1, 6
	s_mul_i32 s0, s0, s5
	s_ashr_i32 s2, s1, 8
	s_lshl_b32 s37, s3, 10
	s_add_i32 s0, s0, s4
	s_cmp_lt_i32 s0, s16
	s_waitcnt lgkmcnt(0)
	s_cselect_b32 s6, s36, 4
	v_and_b32_e32 v9, 0xc0, v9
	s_cselect_b32 s4, 0, s16
	s_cselect_b32 s5, 2, 0
	s_abs_i32 s7, s6
	v_sub_u32_e32 v8, v8, v9
	v_cvt_f32_u32_e32 v9, s7
	s_sub_i32 s9, 0, s7
	s_sub_i32 s0, s0, s4
	s_abs_i32 s8, s0
	v_rcp_iflag_f32_e32 v9, v9
	s_xor_b32 s4, s0, s6
	s_ashr_i32 s4, s4, 31
	v_lshrrev_b32_e32 v12, 2, v10
	v_mul_f32_e32 v9, 0x4f7ffffe, v9
	v_cvt_u32_f32_e32 v9, v9
	v_lshlrev_b32_e32 v13, 1, v10
	v_and_b32_e32 v12, 4, v12
	v_and_b32_e32 v13, 24, v13
	v_readfirstlane_b32 s10, v9
	s_mul_i32 s9, s9, s10
	s_mul_hi_u32 s9, s10, s9
	s_add_i32 s10, s10, s9
	s_mul_hi_u32 s9, s8, s10
	s_mul_i32 s10, s9, s7
	s_sub_i32 s8, s8, s10
	s_add_i32 s10, s9, 1
	s_sub_i32 s11, s8, s7
	s_cmp_ge_u32 s8, s7
	s_cselect_b32 s9, s10, s9
	s_cselect_b32 s8, s11, s8
	s_add_i32 s10, s9, 1
	s_cmp_ge_u32 s8, s7
	s_cselect_b32 s7, s10, s9
	s_xor_b32 s7, s7, s4
	s_sub_i32 s4, s7, s4
	s_lshl_b32 s7, s4, 2
	s_sub_i32 s5, s5, s7
	s_min_i32 s8, s5, 4
	s_sext_i32_i16 s5, s8
	v_cvt_f32_i32_e32 v9, s5
	v_or3_b32 v11, v11, v12, v13
	v_lshlrev_b32_e32 v12, 5, v7
	v_ashrrev_i16_sdwa v8, v232, sext(v8) dst_sel:DWORD dst_unused:UNUSED_PAD src0_sel:DWORD src1_sel:BYTE_0
	s_mul_i32 s4, s4, s6
	v_and_b32_e32 v12, 32, v12
	v_bfe_i32 v8, v8, 0, 16
	s_sub_i32 s6, s0, s4
	v_add_lshl_u32 v12, v12, v8, 1
	s_sext_i32_i16 s0, s6
	v_lshl_add_u32 v134, v11, 7, v12
	v_lshl_add_u32 v136, v10, 7, v12
	v_cvt_f32_i32_e32 v10, s0
	v_rcp_iflag_f32_e32 v11, v9
	s_xor_b32 s0, s0, s5
	s_ashr_i32 s0, s0, 30
	s_or_b32 s0, s0, 1
	v_mul_f32_e32 v11, v10, v11
	v_trunc_f32_e32 v11, v11
	v_fma_f32 v10, -v11, v9, v10
	v_cvt_i32_f32_e32 v11, v11
	v_cmp_ge_f32_e64 s[4:5], |v10|, |v9|
	s_and_b64 s[4:5], s[4:5], exec
	s_cselect_b32 s0, s0, 0
	v_readfirstlane_b32 s4, v11
	s_add_i32 s0, s4, s0
	s_mul_i32 s4, s0, s8
	s_sub_i32 s4, s6, s4
	s_sext_i32_i16 s4, s4
	s_add_i32 s20, s7, s4
	s_ashr_i32 s21, s20, 31
	s_bfe_i64 s[6:7], s[0:1], 0x100000
	s_lshl_b64 s[4:5], s[20:21], 20
	s_lshl_b64 s[6:7], s[6:7], 20
	s_add_u32 s24, s51, s6
	s_addc_u32 s25, s53, s7
	s_add_i32 s40, s37, 0
	s_add_i32 m0, s40, 0x10000
	s_nop 0
	global_load_lds_dwordx4 v134, s[24:25]
	s_add_i32 m0, s40, 0x12000
	s_add_u32 s6, s24, 0x4000
	global_load_lds_dwordx4 v130, s[24:25]
	s_addc_u32 s7, s25, 0
	s_add_i32 m0, s40, 0x14000
	s_nop 0
	global_load_lds_dwordx4 v134, s[6:7]
	s_add_i32 m0, s40, 0x16000
	s_add_u32 s22, s31, s4
	s_addc_u32 s23, s33, s5
	s_add_i32 s41, s40, 0x2000
	global_load_lds_dwordx4 v130, s[6:7]
	s_mov_b32 m0, s40
	s_add_u32 s4, s22, 0x4000
	global_load_lds_dwordx4 v136, s[22:23]
	s_mov_b32 m0, s41
	s_addc_u32 s5, s23, 0
	s_add_i32 s44, s40, 0x4000
	global_load_lds_dwordx4 v132, s[22:23]
	s_mov_b32 m0, s44
	s_add_i32 s45, s40, 0x6000
	global_load_lds_dwordx4 v136, s[4:5]
	s_mov_b32 m0, s45
	s_cmp_eq_u32 s2, 1
	global_load_lds_dwordx4 v132, s[4:5]
	s_cselect_b64 s[4:5], -1, 0
	s_cmp_lg_u32 s2, 1
	s_cbranch_scc1 .LBB0_652
; #define PG8_STAGE(bufoff, gbase, voff) do { _Pragma("unroll") for (int _i = 0; _i < 2; ++_i) \
;         __builtin_amdgcn_global_load_lds((const unsigned*)((const char*)(gbase) + (voff)[_i]), (PG8_LAS unsigned*)(lds + (bufoff) + ldsw + _i * 8192), 16, 0, 0); } while (0)
; #define PG8_WAIT_V(n) asm volatile("s_waitcnt vmcnt(" #n ")" ::: "memory")
; #define PG8_BAR __builtin_amdgcn_s_barrier()
; template <class Epi, class Sched, bool ALIGN_EPI = false, bool SP2 = false, bool ABLK = false, bool BBLK = false>
; __device__ __forceinline__ void gemm_phase(PG8_LAS unsigned char* lds, const Gemm g, const Sched& S, const Epi& E) {
;     ...
;         if (wr == 1) PG8_BAR;
;         PG8_WAIT_V(2); PG8_BAR;
;         PG8_STAGE(PG8_SB(1, 0), cB + kstepB, voffB); PG8_STAGE(PG8_SA(1, 0), cA + kstepA, voffA); PG8_STAGE(PG8_SB(1, 1), cB + hstepB + kstepB, voffB);
;         PG8_WAIT_V(6); PG8_BAR;
;     } else {
;         PG8_STAGE(PG8_SB(0, 0), cB, voffB); PG8_STAGE(PG8_SA(0, 0), cA, voffA); PG8_STAGE(PG8_SB(0, 1), cB + hstepB, voffB); PG8_STAGE(PG8_SA(0, 1), cA + hstepA, voffA);
;         if (wr == 1) PG8_BAR;
;         PG8_WAIT_V(4); PG8_BAR;
;         PG8_STAGE(PG8_SB(1, 0), cB + kstepB, voffB); PG8_STAGE(PG8_SA(1, 0), cA + kstepA, voffA); PG8_STAGE(PG8_SB(1, 1), cB + hstepB + kstepB, voffB);
;         PG8_WAIT_V(6); PG8_BAR;
.LBB0_652:
	s_lshl_b32 s3, s3, 5
	s_and_b32 s10, s3, 0x60
	s_lshl_b32 s8, s2, 13
	s_lshl_b32 s3, s10, 7
	s_add_u32 s6, s24, 0x8000
	v_mov_b32_e32 v135, v187
	s_addc_u32 s7, s25, 0
	s_add_i32 m0, s40, 0x18000
	v_lshl_add_u64 v[10:11], s[6:7], 0, v[134:135]
	v_mov_b32_e32 v131, v187
	s_waitcnt vmcnt(2)
	s_barrier
	global_load_lds_dwordx4 v[10:11], off
	s_add_i32 m0, s40, 0x1a000
	v_lshl_add_u64 v[10:11], s[6:7], 0, v[130:131]
	s_add_u32 s6, s22, 0x8000
	v_mov_b32_e32 v137, v187
	s_addc_u32 s7, s23, 0
	s_add_i32 s46, s40, 0x8000
	v_mov_b32_e32 v133, v187
	global_load_lds_dwordx4 v[10:11], off
	v_lshl_add_u64 v[10:11], s[6:7], 0, v[136:137]
	s_mov_b32 m0, s46
	s_add_i32 s47, s40, 0xa000
	global_load_lds_dwordx4 v[10:11], off
	v_lshl_add_u64 v[10:11], s[6:7], 0, v[132:133]
	s_add_u32 s6, s24, 0xc000
	s_mov_b32 m0, s47
	s_addc_u32 s7, s25, 0
	global_load_lds_dwordx4 v[10:11], off
	s_add_i32 m0, s40, 0x1c000
	v_lshl_add_u64 v[10:11], s[6:7], 0, v[134:135]
	global_load_lds_dwordx4 v[10:11], off
	v_lshl_add_u64 v[10:11], s[6:7], 0, v[130:131]
	s_add_i32 m0, s40, 0x1e000
	v_and_b32_e32 v146, 15, v2
	global_load_lds_dwordx4 v[10:11], off
	v_lshrrev_b32_e32 v9, 1, v2
	v_and_b32_e32 v9, 24, v9
	v_lshlrev_b32_e32 v10, 6, v146
	v_lshlrev_b32_e32 v2, 2, v2
	v_lshl_or_b32 v10, v9, 1, v10
	v_and_b32_e32 v2, 32, v2
	v_bitop3_b32 v11, v10, s8, v2 bitop3:0xde
	v_bitop3_b32 v147, v10, s3, v2 bitop3:0xde
	v_lshlrev_b32_e32 v2, 10, v7
	v_and_b32_e32 v2, 0xfffff800, v2
	v_lshl_add_u32 v2, v6, 7, v2
	v_and_b32_e32 v6, 1, v7
	v_lshl_or_b32 v2, v6, 6, v2
	s_cmpk_lt_u32 s1, 0x100
	v_lshl_add_u32 v138, v8, 1, v2
	v_lshlrev_b32_e32 v2, 10, v3
	s_cselect_b64 s[8:9], -1, 0
	s_ashr_i32 s3, s2, 31
	v_and_b32_e32 v2, 0xfffff800, v2
	s_waitcnt vmcnt(6)
	s_cmp_lg_u32 s2, 1
	v_lshl_add_u32 v2, v4, 7, v2
	v_and_b32_e32 v3, 1, v3
	s_sext_i32_i16 s21, s0
	s_cselect_b64 s[0:1], -1, 0
	v_lshl_or_b32 v2, v3, 6, v2
	v_or_b32_e32 v148, s10, v9
	v_mov_b32_e32 v139, v187
	v_lshl_add_u32 v140, v5, 1, v2
	v_mov_b32_e32 v141, v187
	s_mov_b32 s60, 0
	v_add_u32_e32 v149, 0, v11
	s_xor_b64 s[10:11], s[0:1], -1
	s_barrier
	s_waitcnt vmcnt(0)
	s_branch .LBB0_655

; #define PG8_STAGE(bufoff, gbase, voff) do { _Pragma("unroll") for (int _i = 0; _i < 2; ++_i) \
;         __builtin_amdgcn_global_load_lds((const unsigned*)((const char*)(gbase) + (voff)[_i]), (PG8_LAS unsigned*)(lds + (bufoff) + ldsw + _i * 8192), 16, 0, 0); } while (0)
; #define PG8_LDA(dst, b, h) do { _Pragma("unroll") for (int m = 0; m < 4; ++m) _Pragma("unroll") for (int k = 0; k < 2; ++k) dst[m][k] = *(const PG8_LAS bf16x8*)(lds + PG8_SA(b, h) + aoff + m * 2048 + k * 1024); } while (0)
; #define PG8_LDB(dst, b, h) do { _Pragma("unroll") for (int n = 0; n < 2; ++n) _Pragma("unroll") for (int k = 0; k < 2; ++k) dst[n][k] = *(const PG8_LAS bf16x8*)(lds + PG8_SB(b, h) + boff + n * 2048 + k * 1024); } while (0)
; #define PG8_BAR __builtin_amdgcn_s_barrier()
; #define PG8_SCHED __builtin_amdgcn_sched_barrier(0)
; template <class Epi, class Sched, bool ALIGN_EPI = false, bool SP2 = false, bool ABLK = false, bool BBLK = false>
; __device__ __forceinline__ void gemm_phase(PG8_LAS unsigned char* lds, const Gemm g, const Sched& S, const Epi& E) {
;     ...
;         const bool has_next = S.next(ui + 1, nxt);
;         const char* nA = has_next ? (const char*)g.A + (size_t)nxt.pm * tstepA : cA; const char* nB = has_next ? (const char*)g.Bt + (size_t)nxt.pn * tstepB : cB;
;         for (int t = 0; t < nt; t += 2) {
;             const bool last = (t == nt - 2);
;             const char* a1 = cA + (size_t)(t + 1) * kstepA;
;             const char* a2 = last ? nA : cA + (size_t)(t + 2) * kstepA; const char* b2 = last ? nB : cB + (size_t)(t + 2) * kstepB;
;             const char* a3 = a2 + kstepA; const char* b3 = b2 + kstepB;
;             if (last && has_next) S.a_ready(nxt);
;             if constexpr (SP2) {
;             PG8_LDB(B0, 0, 0); PG8_LDB(B1, 0, 1); PG8_SCHED; PG8_LDA(At, 0, 0); PG8_STAGE(PG8_SA(1, 1), a1 + hstepA, voffA);
;     ...
;         for (int a = 0; a < 2; ++a)
; #pragma unroll
;             for (int b = 0; b < 2; ++b)
; #pragma unroll
;                 for (int m = 0; m < 4; ++m)
; #pragma unroll
;                     for (int n = 0; n < 2; ++n) acc[a][b][m][n] = (f32x4){0.f, 0.f, 0.f, 0.f};
;         cur = nxt; cA = nA; cB = nB; ++ui;
;         if constexpr (ALIGN_EPI) { if (wr == 1) PG8_BAR; }
.LBB0_657:
	s_ashr_i32 s13, s12, 31
	s_lshl_b64 s[14:15], s[12:13], 20
	s_add_u32 s14, s31, s14
	s_addc_u32 s15, s33, s15
	s_and_b64 s[18:19], s[6:7], exec
	s_cselect_b32 s13, s15, s23
	s_cselect_b32 s61, s14, s22
	s_ashr_i32 s1, s0, 31
	s_lshl_b64 s[18:19], s[0:1], 20
	s_add_u32 s18, s51, s18
	s_addc_u32 s19, s53, s19
	s_and_b64 s[26:27], s[6:7], exec
	s_cselect_b32 s1, s19, s25
	s_cselect_b32 s65, s18, s24
	s_add_u32 s22, s22, 0xc000
	s_addc_u32 s23, s23, 0
	s_add_u32 s68, s24, 0x10000
	v_mov_b32_e32 v2, 0
	s_addc_u32 s72, s25, 0
	s_mov_b32 s73, -2
	v_mov_b32_e32 v3, v2
	v_mov_b32_e32 v4, v2
	v_mov_b32_e32 v5, v2
	v_mov_b32_e32 v6, v2
	v_mov_b32_e32 v7, v2
	v_mov_b32_e32 v8, v2
	v_mov_b32_e32 v9, v2
	v_mov_b32_e32 v10, v2
	v_mov_b32_e32 v11, v2
	v_mov_b32_e32 v12, v2
	v_mov_b32_e32 v13, v2
	v_mov_b32_e32 v18, v2
	v_mov_b32_e32 v19, v2
	v_mov_b32_e32 v20, v2
	v_mov_b32_e32 v21, v2
	v_mov_b32_e32 v26, v2
	v_mov_b32_e32 v27, v2
	v_mov_b32_e32 v28, v2
	v_mov_b32_e32 v29, v2
	v_mov_b32_e32 v34, v2
	v_mov_b32_e32 v35, v2
	v_mov_b32_e32 v36, v2
	v_mov_b32_e32 v37, v2
	v_mov_b32_e32 v46, v2
	v_mov_b32_e32 v47, v2
	v_mov_b32_e32 v48, v2
	v_mov_b32_e32 v49, v2
	v_mov_b32_e32 v54, v2
	v_mov_b32_e32 v55, v2
	v_mov_b32_e32 v56, v2
	v_mov_b32_e32 v57, v2
	v_mov_b32_e32 v14, v2
	v_mov_b32_e32 v15, v2
	v_mov_b32_e32 v16, v2
	v_mov_b32_e32 v17, v2
	v_mov_b32_e32 v22, v2
	v_mov_b32_e32 v23, v2
	v_mov_b32_e32 v24, v2
	v_mov_b32_e32 v25, v2
	v_mov_b32_e32 v30, v2
	v_mov_b32_e32 v31, v2
	v_mov_b32_e32 v32, v2
	v_mov_b32_e32 v33, v2
	v_mov_b32_e32 v38, v2
	v_mov_b32_e32 v39, v2
	v_mov_b32_e32 v40, v2
	v_mov_b32_e32 v41, v2
	v_mov_b32_e32 v42, v2
	v_mov_b32_e32 v43, v2
	v_mov_b32_e32 v44, v2
	v_mov_b32_e32 v45, v2
	v_mov_b32_e32 v50, v2
	v_mov_b32_e32 v51, v2
	v_mov_b32_e32 v52, v2
	v_mov_b32_e32 v53, v2
	v_mov_b32_e32 v58, v2
	v_mov_b32_e32 v59, v2
	v_mov_b32_e32 v60, v2
	v_mov_b32_e32 v61, v2
	v_mov_b32_e32 v62, v2
	v_mov_b32_e32 v63, v2
	v_mov_b32_e32 v64, v2
	v_mov_b32_e32 v65, v2
	v_mov_b32_e32 v66, v2
	v_mov_b32_e32 v67, v2
	v_mov_b32_e32 v68, v2
	v_mov_b32_e32 v69, v2
	v_mov_b32_e32 v70, v2
	v_mov_b32_e32 v71, v2
	v_mov_b32_e32 v72, v2
	v_mov_b32_e32 v73, v2
	v_mov_b32_e32 v74, v2
	v_mov_b32_e32 v75, v2
	v_mov_b32_e32 v76, v2
	v_mov_b32_e32 v77, v2
	v_mov_b32_e32 v82, v2
	v_mov_b32_e32 v83, v2
	v_mov_b32_e32 v84, v2
	v_mov_b32_e32 v85, v2
	v_mov_b32_e32 v90, v2
	v_mov_b32_e32 v91, v2
	v_mov_b32_e32 v92, v2
	v_mov_b32_e32 v93, v2
	v_mov_b32_e32 v98, v2
	v_mov_b32_e32 v99, v2
	v_mov_b32_e32 v100, v2
	v_mov_b32_e32 v101, v2
	v_mov_b32_e32 v110, v2
	v_mov_b32_e32 v111, v2
	v_mov_b32_e32 v112, v2
	v_mov_b32_e32 v113, v2
	v_mov_b32_e32 v118, v2
	v_mov_b32_e32 v119, v2
	v_mov_b32_e32 v120, v2
	v_mov_b32_e32 v121, v2
	v_mov_b32_e32 v78, v2
	v_mov_b32_e32 v79, v2
	v_mov_b32_e32 v80, v2
	v_mov_b32_e32 v81, v2
	v_mov_b32_e32 v86, v2
	v_mov_b32_e32 v87, v2
	v_mov_b32_e32 v88, v2
	v_mov_b32_e32 v89, v2
	v_mov_b32_e32 v94, v2
	v_mov_b32_e32 v95, v2
	v_mov_b32_e32 v96, v2
	v_mov_b32_e32 v97, v2
	v_mov_b32_e32 v102, v2
	v_mov_b32_e32 v103, v2
	v_mov_b32_e32 v104, v2
	v_mov_b32_e32 v105, v2
	v_mov_b32_e32 v106, v2
	v_mov_b32_e32 v107, v2
	v_mov_b32_e32 v108, v2
	v_mov_b32_e32 v109, v2
	v_mov_b32_e32 v114, v2
	v_mov_b32_e32 v115, v2
	v_mov_b32_e32 v116, v2
	v_mov_b32_e32 v117, v2
	v_mov_b32_e32 v122, v2
	v_mov_b32_e32 v123, v2
	v_mov_b32_e32 v124, v2
	v_mov_b32_e32 v125, v2
	v_mov_b32_e32 v126, v2
	v_mov_b32_e32 v127, v2
	v_mov_b32_e32 v128, v2
	v_mov_b32_e32 v129, v2
	s_and_b64 vcc, exec, s[8:9]
	s_cbranch_vccnz .Lrb_fold
	s_barrier
.Lrb_fold:
.LBB0_658:
	s_add_u32 s24, s22, 0x4000
	s_addc_u32 s25, s23, 0
	s_cmp_eq_u32 s73, 28
	s_cselect_b32 s28, s61, s24
	s_cselect_b32 s29, s13, s25
	s_cselect_b32 s26, s65, s68
	s_cselect_b32 s27, s1, s72
	s_add_u32 s24, s28, 0x8000
	s_addc_u32 s25, s29, 0
	s_add_i32 s75, 0, 0x10000
	s_add_i32 s82, 0, 0x14000
	v_add_u32_e32 v158, s75, v147
	v_add_u32_e32 v174, s82, v147
	ds_read_b128 v[142:145], v158
	ds_read_b128 v[150:153], v158 offset:1024
	ds_read_b128 v[154:157], v158 offset:2048
	ds_read_b128 v[158:161], v158 offset:3072
	ds_read_b128 v[162:165], v174
	ds_read_b128 v[166:169], v174 offset:1024
	ds_read_b128 v[170:173], v174 offset:2048
	ds_read_b128 v[174:177], v174 offset:3072
	v_lshl_add_u64 v[220:221], s[22:23], 0, v[138:139]
	s_add_i32 m0, s40, 0xc000
	ds_read_b128 v[178:181], v149
	ds_read_b128 v[182:185], v149 offset:1024
	ds_read_b128 v[196:199], v149 offset:2048
	ds_read_b128 v[200:203], v149 offset:3072
	ds_read_b128 v[204:207], v149 offset:4096
	ds_read_b128 v[208:211], v149 offset:5120
	ds_read_b128 v[212:215], v149 offset:6144
	ds_read_b128 v[216:219], v149 offset:7168
	global_load_lds_dwordx4 v[220:221], off
	v_lshl_add_u64 v[220:221], s[22:23], 0, v[140:141]
	s_add_i32 m0, s40, 0xe000
	s_nop 0
	global_load_lds_dwordx4 v[220:221], off
	s_waitcnt vmcnt(8)
	s_waitcnt lgkmcnt(0)
	s_barrier
; #define PG8_STAGE(bufoff, gbase, voff) do { _Pragma("unroll") for (int _i = 0; _i < 2; ++_i) \
;         __builtin_amdgcn_global_load_lds((const unsigned*)((const char*)(gbase) + (voff)[_i]), (PG8_LAS unsigned*)(lds + (bufoff) + ldsw + _i * 8192), 16, 0, 0); } while (0)
; #define PG8_LDA(dst, b, h) do { _Pragma("unroll") for (int m = 0; m < 4; ++m) _Pragma("unroll") for (int k = 0; k < 2; ++k) dst[m][k] = *(const PG8_LAS bf16x8*)(lds + PG8_SA(b, h) + aoff + m * 2048 + k * 1024); } while (0)
; #define PG8_MMA(ai, bj, At, Bt) do { __builtin_amdgcn_s_setprio(1); _Pragma("unroll") for (int m = 0; m < 4; ++m) _Pragma("unroll") for (int n = 0; n < 2; ++n) _Pragma("unroll") for (int k = 0; k < 2; ++k) \
;         acc[ai][bj][m][n] = __builtin_amdgcn_mfma_f32_16x16x32_bf16(Bt[n][k], At[m][k], acc[ai][bj][m][n], 0, 0, 0); __builtin_amdgcn_s_setprio(0); } while (0)
; #define PG8_WAIT_V(n) asm volatile("s_waitcnt vmcnt(" #n ")" ::: "memory")
; #define PG8_WAIT_L(n) asm volatile("s_waitcnt lgkmcnt(" #n ")" ::: "memory")
; #define PG8_BAR __builtin_amdgcn_s_barrier()
; #define PG8_SCHED __builtin_amdgcn_sched_barrier(0)
; template <class Epi, class Sched, bool ALIGN_EPI = false, bool SP2 = false, bool ABLK = false, bool BBLK = false>
; __device__ __forceinline__ void gemm_phase(PG8_LAS unsigned char* lds, const Gemm g, const Sched& S, const Epi& E) {
;     ...
;             PG8_WAIT_V(8); PG8_WAIT_L(0); PG8_BAR; PG8_MMA(0, 0, At, B0); PG8_MMA(0, 1, At, B1); PG8_BAR; PG8_SCHED;
;             PG8_LDA(At, 0, 1); PG8_STAGE(PG8_SB(0, 0), b2, voffB); PG8_STAGE(PG8_SB(0, 1), b2 + hstepB, voffB); PG8_STAGE(PG8_SA(0, 0), a2, voffA);
;             PG8_WAIT_V(8); PG8_WAIT_L(0); PG8_BAR; PG8_MMA(1, 0, At, B0); PG8_MMA(1, 1, At, B1); PG8_BAR; PG8_SCHED;
	s_setprio 1
	s_waitcnt lgkmcnt(0)
	v_mfma_f32_16x16x32_bf16 v[126:129], v[142:145], v[178:181], v[126:129]
	v_mfma_f32_16x16x32_bf16 v[122:125], v[154:157], v[178:181], v[122:125]
	v_mfma_f32_16x16x32_bf16 v[114:117], v[142:145], v[196:199], v[114:117]
	v_mfma_f32_16x16x32_bf16 v[106:109], v[154:157], v[196:199], v[106:109]
	v_mfma_f32_16x16x32_bf16 v[102:105], v[142:145], v[204:207], v[102:105]
	v_mfma_f32_16x16x32_bf16 v[94:97], v[154:157], v[204:207], v[94:97]
	v_mfma_f32_16x16x32_bf16 v[86:89], v[142:145], v[212:215], v[86:89]
	v_mfma_f32_16x16x32_bf16 v[78:81], v[154:157], v[212:215], v[78:81]
	v_mfma_f32_16x16x32_bf16 v[126:129], v[150:153], v[182:185], v[126:129]
	v_mfma_f32_16x16x32_bf16 v[122:125], v[158:161], v[182:185], v[122:125]
	v_mfma_f32_16x16x32_bf16 v[114:117], v[150:153], v[200:203], v[114:117]
	v_mfma_f32_16x16x32_bf16 v[106:109], v[158:161], v[200:203], v[106:109]
	v_mfma_f32_16x16x32_bf16 v[102:105], v[150:153], v[208:211], v[102:105]
	v_mfma_f32_16x16x32_bf16 v[94:97], v[158:161], v[208:211], v[94:97]
	v_mfma_f32_16x16x32_bf16 v[86:89], v[150:153], v[216:219], v[86:89]
	v_mfma_f32_16x16x32_bf16 v[78:81], v[158:161], v[216:219], v[78:81]
	s_setprio 0
	s_setprio 1
	v_mfma_f32_16x16x32_bf16 v[118:121], v[162:165], v[178:181], v[118:121]
	v_mfma_f32_16x16x32_bf16 v[110:113], v[170:173], v[178:181], v[110:113]
	v_mfma_f32_16x16x32_bf16 v[98:101], v[162:165], v[196:199], v[98:101]
	v_mfma_f32_16x16x32_bf16 v[90:93], v[170:173], v[196:199], v[90:93]
	v_mfma_f32_16x16x32_bf16 v[82:85], v[162:165], v[204:207], v[82:85]
	v_mfma_f32_16x16x32_bf16 v[74:77], v[170:173], v[204:207], v[74:77]
	v_mfma_f32_16x16x32_bf16 v[70:73], v[162:165], v[212:215], v[70:73]
	v_mfma_f32_16x16x32_bf16 v[66:69], v[170:173], v[212:215], v[66:69]
	v_mfma_f32_16x16x32_bf16 v[118:121], v[166:169], v[182:185], v[118:121]
	v_mfma_f32_16x16x32_bf16 v[110:113], v[174:177], v[182:185], v[110:113]
	v_mfma_f32_16x16x32_bf16 v[98:101], v[166:169], v[200:203], v[98:101]
	v_mfma_f32_16x16x32_bf16 v[90:93], v[174:177], v[200:203], v[90:93]
	v_mfma_f32_16x16x32_bf16 v[82:85], v[166:169], v[208:211], v[82:85]
	v_mfma_f32_16x16x32_bf16 v[74:77], v[174:177], v[208:211], v[74:77]
	v_mfma_f32_16x16x32_bf16 v[70:73], v[166:169], v[216:219], v[70:73]
	v_mfma_f32_16x16x32_bf16 v[66:69], v[174:177], v[216:219], v[66:69]
	s_setprio 0
	s_barrier
	s_add_i32 s75, s75, s37
	v_lshl_add_u64 v[220:221], s[26:27], 0, v[134:135]
	s_mov_b32 m0, s75
	ds_read_b128 v[178:181], v149 offset:16384
	ds_read_b128 v[182:185], v149 offset:17408
	ds_read_b128 v[196:199], v149 offset:18432
	ds_read_b128 v[200:203], v149 offset:19456
	ds_read_b128 v[204:207], v149 offset:20480
	ds_read_b128 v[208:211], v149 offset:21504
	ds_read_b128 v[212:215], v149 offset:22528
	ds_read_b128 v[216:219], v149 offset:23552
	global_load_lds_dwordx4 v[220:221], off
	s_add_i32 m0, s75, 0x2000
	s_add_u32 s80, s26, 0x4000
	v_lshl_add_u64 v[220:221], s[26:27], 0, v[130:131]
	s_addc_u32 s81, s27, 0
	s_add_i32 s75, s82, s37
	global_load_lds_dwordx4 v[220:221], off
	v_lshl_add_u64 v[220:221], s[80:81], 0, v[134:135]
	s_mov_b32 m0, s75
	s_nop 0
	global_load_lds_dwordx4 v[220:221], off
	v_lshl_add_u64 v[220:221], s[80:81], 0, v[130:131]
	s_add_i32 m0, s75, 0x2000
	s_nop 0
	global_load_lds_dwordx4 v[220:221], off
	v_lshl_add_u64 v[220:221], s[28:29], 0, v[136:137]
	s_mov_b32 m0, s40
	s_nop 0
	global_load_lds_dwordx4 v[220:221], off
	v_lshl_add_u64 v[220:221], s[28:29], 0, v[132:133]
	s_mov_b32 m0, s41
	s_nop 0
	global_load_lds_dwordx4 v[220:221], off
	s_waitcnt vmcnt(8)
	s_waitcnt lgkmcnt(0)
	s_barrier
	s_setprio 1
	s_waitcnt lgkmcnt(0)
	v_mfma_f32_16x16x32_bf16 v[62:65], v[142:145], v[178:181], v[62:65]
	v_mfma_f32_16x16x32_bf16 v[58:61], v[154:157], v[178:181], v[58:61]
	v_mfma_f32_16x16x32_bf16 v[50:53], v[142:145], v[196:199], v[50:53]
	v_mfma_f32_16x16x32_bf16 v[42:45], v[154:157], v[196:199], v[42:45]
	v_mfma_f32_16x16x32_bf16 v[38:41], v[142:145], v[204:207], v[38:41]
	v_mfma_f32_16x16x32_bf16 v[30:33], v[154:157], v[204:207], v[30:33]
	v_mfma_f32_16x16x32_bf16 v[22:25], v[142:145], v[212:215], v[22:25]
	v_mfma_f32_16x16x32_bf16 v[14:17], v[154:157], v[212:215], v[14:17]
	v_mfma_f32_16x16x32_bf16 v[62:65], v[150:153], v[182:185], v[62:65]
	v_mfma_f32_16x16x32_bf16 v[58:61], v[158:161], v[182:185], v[58:61]
	v_mfma_f32_16x16x32_bf16 v[50:53], v[150:153], v[200:203], v[50:53]
	v_mfma_f32_16x16x32_bf16 v[42:45], v[158:161], v[200:203], v[42:45]
	v_mfma_f32_16x16x32_bf16 v[38:41], v[150:153], v[208:211], v[38:41]
	v_mfma_f32_16x16x32_bf16 v[30:33], v[158:161], v[208:211], v[30:33]
	v_mfma_f32_16x16x32_bf16 v[22:25], v[150:153], v[216:219], v[22:25]
	v_mfma_f32_16x16x32_bf16 v[14:17], v[158:161], v[216:219], v[14:17]
	s_setprio 0
	s_setprio 1
	v_mfma_f32_16x16x32_bf16 v[54:57], v[162:165], v[178:181], v[54:57]
	v_mfma_f32_16x16x32_bf16 v[46:49], v[170:173], v[178:181], v[46:49]
	v_mfma_f32_16x16x32_bf16 v[34:37], v[162:165], v[196:199], v[34:37]
	v_mfma_f32_16x16x32_bf16 v[26:29], v[170:173], v[196:199], v[26:29]
	v_mfma_f32_16x16x32_bf16 v[18:21], v[162:165], v[204:207], v[18:21]
	v_mfma_f32_16x16x32_bf16 v[10:13], v[170:173], v[204:207], v[10:13]
	v_mfma_f32_16x16x32_bf16 v[6:9], v[162:165], v[212:215], v[6:9]
	v_mfma_f32_16x16x32_bf16 v[2:5], v[170:173], v[212:215], v[2:5]
	v_mfma_f32_16x16x32_bf16 v[54:57], v[166:169], v[182:185], v[54:57]
	v_mfma_f32_16x16x32_bf16 v[46:49], v[174:177], v[182:185], v[46:49]
	v_mfma_f32_16x16x32_bf16 v[34:37], v[166:169], v[200:203], v[34:37]
	v_mfma_f32_16x16x32_bf16 v[26:29], v[174:177], v[200:203], v[26:29]
	v_mfma_f32_16x16x32_bf16 v[18:21], v[166:169], v[208:211], v[18:21]
	v_mfma_f32_16x16x32_bf16 v[10:13], v[174:177], v[208:211], v[10:13]
	v_mfma_f32_16x16x32_bf16 v[6:9], v[166:169], v[216:219], v[6:9]
	v_mfma_f32_16x16x32_bf16 v[2:5], v[174:177], v[216:219], v[2:5]
	s_setprio 0
	s_barrier
; #define PG8_STAGE(bufoff, gbase, voff) do { _Pragma("unroll") for (int _i = 0; _i < 2; ++_i) \
;         __builtin_amdgcn_global_load_lds((const unsigned*)((const char*)(gbase) + (voff)[_i]), (PG8_LAS unsigned*)(lds + (bufoff) + ldsw + _i * 8192), 16, 0, 0); } while (0)
; #define PG8_LDA(dst, b, h) do { _Pragma("unroll") for (int m = 0; m < 4; ++m) _Pragma("unroll") for (int k = 0; k < 2; ++k) dst[m][k] = *(const PG8_LAS bf16x8*)(lds + PG8_SA(b, h) + aoff + m * 2048 + k * 1024); } while (0)
; #define PG8_LDB(dst, b, h) do { _Pragma("unroll") for (int n = 0; n < 2; ++n) _Pragma("unroll") for (int k = 0; k < 2; ++k) dst[n][k] = *(const PG8_LAS bf16x8*)(lds + PG8_SB(b, h) + boff + n * 2048 + k * 1024); } while (0)
; #define PG8_MMA(ai, bj, At, Bt) do { __builtin_amdgcn_s_setprio(1); _Pragma("unroll") for (int m = 0; m < 4; ++m) _Pragma("unroll") for (int n = 0; n < 2; ++n) _Pragma("unroll") for (int k = 0; k < 2; ++k) \
;         acc[ai][bj][m][n] = __builtin_amdgcn_mfma_f32_16x16x32_bf16(Bt[n][k], At[m][k], acc[ai][bj][m][n], 0, 0, 0); __builtin_amdgcn_s_setprio(0); } while (0)
; #define PG8_WAIT_V(n) asm volatile("s_waitcnt vmcnt(" #n ")" ::: "memory")
; #define PG8_WAIT_L(n) asm volatile("s_waitcnt lgkmcnt(" #n ")" ::: "memory")
; #define PG8_BAR __builtin_amdgcn_s_barrier()
; #define PG8_SCHED __builtin_amdgcn_sched_barrier(0)
; template <class Epi, class Sched, bool ALIGN_EPI = false, bool SP2 = false, bool ABLK = false, bool BBLK = false>
; __device__ __forceinline__ void gemm_phase(PG8_LAS unsigned char* lds, const Gemm g, const Sched& S, const Epi& E) {
;     ...
;             PG8_LDB(B0, 1, 0); PG8_LDB(B1, 1, 1); PG8_SCHED; PG8_LDA(At, 1, 0); PG8_STAGE(PG8_SA(0, 1), a2 + hstepA, voffA);
;             PG8_WAIT_V(8); PG8_WAIT_L(0); PG8_BAR; PG8_MMA(0, 0, At, B0); PG8_MMA(0, 1, At, B1); PG8_BAR; PG8_SCHED;
	s_add_i32 s75, 0, 0x18000
	s_add_i32 s80, 0, 0x1c000
	v_add_u32_e32 v158, s75, v147
	v_add_u32_e32 v174, s80, v147
	ds_read_b128 v[142:145], v158
	ds_read_b128 v[150:153], v158 offset:1024
	ds_read_b128 v[154:157], v158 offset:2048
	ds_read_b128 v[158:161], v158 offset:3072
	ds_read_b128 v[162:165], v174
	ds_read_b128 v[166:169], v174 offset:1024
	ds_read_b128 v[170:173], v174 offset:2048
	ds_read_b128 v[174:177], v174 offset:3072
	s_add_u32 s28, s28, 0x4000
	s_addc_u32 s29, s29, 0
	s_mov_b32 m0, s44
	v_lshl_add_u64 v[220:221], s[28:29], 0, v[136:137]
	ds_read_b128 v[178:181], v149 offset:32768
	ds_read_b128 v[182:185], v149 offset:33792
	ds_read_b128 v[196:199], v149 offset:34816
	ds_read_b128 v[200:203], v149 offset:35840
	ds_read_b128 v[204:207], v149 offset:36864
	ds_read_b128 v[208:211], v149 offset:37888
	ds_read_b128 v[212:215], v149 offset:38912
	ds_read_b128 v[216:219], v149 offset:39936
	global_load_lds_dwordx4 v[220:221], off
	v_lshl_add_u64 v[220:221], s[28:29], 0, v[132:133]
	s_mov_b32 m0, s45
	s_nop 0
	global_load_lds_dwordx4 v[220:221], off
	s_waitcnt vmcnt(8)
	s_waitcnt lgkmcnt(0)
	s_barrier
	s_setprio 1
	s_waitcnt lgkmcnt(0)
	v_mfma_f32_16x16x32_bf16 v[126:129], v[142:145], v[178:181], v[126:129]
	v_mfma_f32_16x16x32_bf16 v[122:125], v[154:157], v[178:181], v[122:125]
	v_mfma_f32_16x16x32_bf16 v[114:117], v[142:145], v[196:199], v[114:117]
	v_mfma_f32_16x16x32_bf16 v[106:109], v[154:157], v[196:199], v[106:109]
	v_mfma_f32_16x16x32_bf16 v[102:105], v[142:145], v[204:207], v[102:105]
	v_mfma_f32_16x16x32_bf16 v[94:97], v[154:157], v[204:207], v[94:97]
	v_mfma_f32_16x16x32_bf16 v[86:89], v[142:145], v[212:215], v[86:89]
	v_mfma_f32_16x16x32_bf16 v[78:81], v[154:157], v[212:215], v[78:81]
	v_mfma_f32_16x16x32_bf16 v[126:129], v[150:153], v[182:185], v[126:129]
	v_mfma_f32_16x16x32_bf16 v[122:125], v[158:161], v[182:185], v[122:125]
	v_mfma_f32_16x16x32_bf16 v[114:117], v[150:153], v[200:203], v[114:117]
	v_mfma_f32_16x16x32_bf16 v[106:109], v[158:161], v[200:203], v[106:109]
	v_mfma_f32_16x16x32_bf16 v[102:105], v[150:153], v[208:211], v[102:105]
	v_mfma_f32_16x16x32_bf16 v[94:97], v[158:161], v[208:211], v[94:97]
	v_mfma_f32_16x16x32_bf16 v[86:89], v[150:153], v[216:219], v[86:89]
	v_mfma_f32_16x16x32_bf16 v[78:81], v[158:161], v[216:219], v[78:81]
	s_setprio 0
	s_setprio 1
	v_mfma_f32_16x16x32_bf16 v[118:121], v[162:165], v[178:181], v[118:121]
	v_mfma_f32_16x16x32_bf16 v[110:113], v[170:173], v[178:181], v[110:113]
	v_mfma_f32_16x16x32_bf16 v[98:101], v[162:165], v[196:199], v[98:101]
	v_mfma_f32_16x16x32_bf16 v[90:93], v[170:173], v[196:199], v[90:93]
	v_mfma_f32_16x16x32_bf16 v[82:85], v[162:165], v[204:207], v[82:85]
	v_mfma_f32_16x16x32_bf16 v[74:77], v[170:173], v[204:207], v[74:77]
	v_mfma_f32_16x16x32_bf16 v[70:73], v[162:165], v[212:215], v[70:73]
	v_mfma_f32_16x16x32_bf16 v[66:69], v[170:173], v[212:215], v[66:69]
	v_mfma_f32_16x16x32_bf16 v[118:121], v[166:169], v[182:185], v[118:121]
	v_mfma_f32_16x16x32_bf16 v[110:113], v[174:177], v[182:185], v[110:113]
	v_mfma_f32_16x16x32_bf16 v[98:101], v[166:169], v[200:203], v[98:101]
	v_mfma_f32_16x16x32_bf16 v[90:93], v[174:177], v[200:203], v[90:93]
	v_mfma_f32_16x16x32_bf16 v[82:85], v[166:169], v[208:211], v[82:85]
	v_mfma_f32_16x16x32_bf16 v[74:77], v[174:177], v[208:211], v[74:77]
	v_mfma_f32_16x16x32_bf16 v[70:73], v[166:169], v[216:219], v[70:73]
	v_mfma_f32_16x16x32_bf16 v[66:69], v[174:177], v[216:219], v[66:69]
	s_setprio 0
	s_barrier
; #define PG8_STAGE(bufoff, gbase, voff) do { _Pragma("unroll") for (int _i = 0; _i < 2; ++_i) \
;         __builtin_amdgcn_global_load_lds((const unsigned*)((const char*)(gbase) + (voff)[_i]), (PG8_LAS unsigned*)(lds + (bufoff) + ldsw + _i * 8192), 16, 0, 0); } while (0)
; #define PG8_LDA(dst, b, h) do { _Pragma("unroll") for (int m = 0; m < 4; ++m) _Pragma("unroll") for (int k = 0; k < 2; ++k) dst[m][k] = *(const PG8_LAS bf16x8*)(lds + PG8_SA(b, h) + aoff + m * 2048 + k * 1024); } while (0)
; template <class Epi, class Sched, bool ALIGN_EPI = false, bool SP2 = false, bool ABLK = false, bool BBLK = false>
; __device__ __forceinline__ void gemm_phase(PG8_LAS unsigned char* lds, const Gemm g, const Sched& S, const Epi& E) {
;     ...
;             PG8_LDA(At, 1, 1); PG8_STAGE(PG8_SB(1, 0), b3, voffB); PG8_STAGE(PG8_SB(1, 1), b3 + hstepB, voffB); PG8_STAGE(PG8_SA(1, 0), a3, voffA);
;             PG8_WAIT_V(8); PG8_WAIT_L(0); PG8_BAR; PG8_MMA(1, 0, At, B0); PG8_MMA(1, 1, At, B1); PG8_BAR; PG8_SCHED;
;             } else {
;             PG8_LDB(B0, 0, 0); PG8_SCHED; PG8_LDA(At, 0, 0); PG8_STAGE(PG8_SA(1, 1), a1 + hstepA, voffA);
;             PG8_WAIT_L(8); PG8_BAR; PG8_WAIT_L(0); PG8_MMA(0, 0, At, B0); PG8_BAR; PG8_SCHED;
;             PG8_LDB(B1, 0, 1); PG8_STAGE(PG8_SB(0, 0), b2, voffB);
;             PG8_BAR; PG8_WAIT_L(0); PG8_MMA(0, 1, At, B1); PG8_BAR;
;             PG8_LDA(At, 0, 1); PG8_STAGE(PG8_SA(0, 0), a2, voffA);
;             PG8_BAR; PG8_WAIT_L(0); PG8_MMA(1, 0, At, B0); PG8_BAR; PG8_SCHED;
;             PG8_STAGE(PG8_SB(0, 1), b2 + hstepB, voffB);
;             PG8_WAIT_V(6); PG8_BAR; PG8_MMA(1, 1, At, B1); PG8_BAR;
;             PG8_LDB(B0, 1, 0); PG8_SCHED; PG8_LDA(At, 1, 0); PG8_STAGE(PG8_SA(0, 1), a2 + hstepA, voffA);
;             PG8_WAIT_L(8); PG8_BAR; PG8_WAIT_L(0); PG8_MMA(0, 0, At, B0); PG8_BAR; PG8_SCHED;
;             PG8_LDB(B1, 1, 1); PG8_STAGE(PG8_SB(1, 0), b3, voffB);
;             PG8_BAR; PG8_WAIT_L(0); PG8_MMA(0, 1, At, B1); PG8_BAR;
;             PG8_LDA(At, 1, 1); PG8_STAGE(PG8_SA(1, 0), a3, voffA);
;             PG8_BAR; PG8_WAIT_L(0); PG8_MMA(1, 0, At, B0); PG8_BAR; PG8_SCHED;
;             PG8_STAGE(PG8_SB(1, 1), b3 + hstepB, voffB);
;             PG8_WAIT_V(6); PG8_BAR; PG8_MMA(1, 1, At, B1); PG8_BAR;
;             }
;         }
;         if constexpr (ALIGN_EPI) { if (wr == 0) PG8_BAR; }
	s_add_u32 s28, s26, 0x8000
	s_addc_u32 s29, s27, 0
	s_add_i32 s75, s75, s37
	v_lshl_add_u64 v[220:221], s[28:29], 0, v[134:135]
	s_mov_b32 m0, s75
	ds_read_b128 v[178:181], v149 offset:49152
	ds_read_b128 v[182:185], v149 offset:50176
	ds_read_b128 v[196:199], v149 offset:51200
	ds_read_b128 v[200:203], v149 offset:52224
	ds_read_b128 v[204:207], v149 offset:53248
	ds_read_b128 v[208:211], v149 offset:54272
	ds_read_b128 v[212:215], v149 offset:55296
	ds_read_b128 v[216:219], v149 offset:56320
	global_load_lds_dwordx4 v[220:221], off
	s_add_i32 m0, s75, 0x2000
	s_add_u32 s26, s26, 0xc000
	v_lshl_add_u64 v[220:221], s[28:29], 0, v[130:131]
	s_addc_u32 s27, s27, 0
	s_add_i32 s28, s80, s37
	global_load_lds_dwordx4 v[220:221], off
	v_lshl_add_u64 v[220:221], s[26:27], 0, v[134:135]
	s_mov_b32 m0, s28
	s_nop 0
	global_load_lds_dwordx4 v[220:221], off
	v_lshl_add_u64 v[220:221], s[26:27], 0, v[130:131]
	s_add_i32 m0, s28, 0x2000
	s_nop 0
	global_load_lds_dwordx4 v[220:221], off
	v_lshl_add_u64 v[220:221], s[24:25], 0, v[136:137]
	s_mov_b32 m0, s46
	s_nop 0
	global_load_lds_dwordx4 v[220:221], off
	v_lshl_add_u64 v[220:221], s[24:25], 0, v[132:133]
	s_mov_b32 m0, s47
	s_nop 0
	global_load_lds_dwordx4 v[220:221], off
	s_waitcnt vmcnt(8)
	s_waitcnt lgkmcnt(0)
	s_barrier
	s_setprio 1
	s_waitcnt lgkmcnt(0)
	v_mfma_f32_16x16x32_bf16 v[62:65], v[142:145], v[178:181], v[62:65]
	v_mfma_f32_16x16x32_bf16 v[58:61], v[154:157], v[178:181], v[58:61]
	v_mfma_f32_16x16x32_bf16 v[50:53], v[142:145], v[196:199], v[50:53]
	v_mfma_f32_16x16x32_bf16 v[42:45], v[154:157], v[196:199], v[42:45]
	v_mfma_f32_16x16x32_bf16 v[38:41], v[142:145], v[204:207], v[38:41]
	v_mfma_f32_16x16x32_bf16 v[30:33], v[154:157], v[204:207], v[30:33]
	v_mfma_f32_16x16x32_bf16 v[22:25], v[142:145], v[212:215], v[22:25]
	v_mfma_f32_16x16x32_bf16 v[14:17], v[154:157], v[212:215], v[14:17]
	v_mfma_f32_16x16x32_bf16 v[62:65], v[150:153], v[182:185], v[62:65]
	v_mfma_f32_16x16x32_bf16 v[58:61], v[158:161], v[182:185], v[58:61]
	v_mfma_f32_16x16x32_bf16 v[50:53], v[150:153], v[200:203], v[50:53]
	v_mfma_f32_16x16x32_bf16 v[42:45], v[158:161], v[200:203], v[42:45]
	v_mfma_f32_16x16x32_bf16 v[38:41], v[150:153], v[208:211], v[38:41]
	v_mfma_f32_16x16x32_bf16 v[30:33], v[158:161], v[208:211], v[30:33]
	v_mfma_f32_16x16x32_bf16 v[22:25], v[150:153], v[216:219], v[22:25]
	v_mfma_f32_16x16x32_bf16 v[14:17], v[158:161], v[216:219], v[14:17]
	s_setprio 0
	s_setprio 1
	v_mfma_f32_16x16x32_bf16 v[54:57], v[162:165], v[178:181], v[54:57]
	v_mfma_f32_16x16x32_bf16 v[46:49], v[170:173], v[178:181], v[46:49]
	v_mfma_f32_16x16x32_bf16 v[34:37], v[162:165], v[196:199], v[34:37]
	v_mfma_f32_16x16x32_bf16 v[26:29], v[170:173], v[196:199], v[26:29]
	v_mfma_f32_16x16x32_bf16 v[18:21], v[162:165], v[204:207], v[18:21]
	v_mfma_f32_16x16x32_bf16 v[10:13], v[170:173], v[204:207], v[10:13]
	v_mfma_f32_16x16x32_bf16 v[6:9], v[162:165], v[212:215], v[6:9]
	v_mfma_f32_16x16x32_bf16 v[2:5], v[170:173], v[212:215], v[2:5]
	v_mfma_f32_16x16x32_bf16 v[54:57], v[166:169], v[182:185], v[54:57]
	v_mfma_f32_16x16x32_bf16 v[46:49], v[174:177], v[182:185], v[46:49]
	v_mfma_f32_16x16x32_bf16 v[34:37], v[166:169], v[200:203], v[34:37]
	v_mfma_f32_16x16x32_bf16 v[26:29], v[174:177], v[200:203], v[26:29]
	v_mfma_f32_16x16x32_bf16 v[18:21], v[166:169], v[208:211], v[18:21]
	v_mfma_f32_16x16x32_bf16 v[10:13], v[174:177], v[208:211], v[10:13]
	v_mfma_f32_16x16x32_bf16 v[6:9], v[166:169], v[216:219], v[6:9]
	v_mfma_f32_16x16x32_bf16 v[2:5], v[174:177], v[216:219], v[2:5]
	s_setprio 0
	s_barrier
	s_add_i32 s73, s73, 2
	s_add_u32 s22, s22, 0x10000
	s_addc_u32 s23, s23, 0
	s_add_u32 s68, s68, 0x10000
	s_addc_u32 s72, s72, 0
	s_cmp_gt_u32 s73, 29
	s_cbranch_scc0 .LBB0_658
	s_and_b64 vcc, exec, s[8:9]
	s_cbranch_vccz .LBB0_661
	s_barrier

; __device__ __forceinline__ u32x4 pack8(const f32x4 v0, const f32x4 v1) { u32x4 w; w.x = cvt_pk_bf16(v0[0], v0[1]); w.y = cvt_pk_bf16(v0[2], v0[3]); w.z = cvt_pk_bf16(v1[0], v1[1]); w.w = cvt_pk_bf16(v1[2], v1[3]); return w; }
; #define PG8_BAR __builtin_amdgcn_s_barrier()
;     __device__ __forceinline__ void operator()(const f32x4 (&acc)[2][2][4][2], const Unit& u, int wr, int wc, int fr_, int fq) const {
;     ...
;                 for (int bj = 0; bj < 2; ++bj) { const u32x4 w = pack8(acc[ai][bj][m][0], acc[ai][bj][m][1]);
;                     *(u32x4*)(ob + (size_t)(ai * 64 + m * 16) * ld + bj * HALF) = w;
;                     if (m == 0) { if (wr == 1 && fr == 0) *(u32x4*)(on + (size_t)ai * ld + bj * HALF) = w; } }
; template <class Epi, class Sched, bool ALIGN_EPI = false, bool SP2 = false, bool ABLK = false, bool BBLK = false>
; __device__ __forceinline__ void gemm_phase(PG8_LAS unsigned char* lds, const Gemm g, const Sched& S, const Epi& E) {
;     ...
;         if (!has_next) break;
; #pragma unroll
;         for (int a = 0; a < 2; ++a)
; #pragma unroll
;             for (int b = 0; b < 2; ++b)
; #pragma unroll
;                 for (int m = 0; m < 4; ++m)
; #pragma unroll
;                     for (int n = 0; n < 2; ++n) acc[a][b][m][n] = (f32x4){0.f, 0.f, 0.f, 0.f};
;         cur = nxt; cA = nA; cB = nB; ++ui;
;         if constexpr (ALIGN_EPI) { if (wr == 1) PG8_BAR; }
.LBB0_669:
	s_or_b64 exec, exec, s[22:23]
	s_lshl_b64 s[20:21], 0x50, s1
	v_lshl_add_u64 v[54:55], s[20:21], 1, v[142:143]
	v_cvt_pk_bf16_f32 v46, v50, v51
	v_cvt_pk_bf16_f32 v47, v52, v53
	v_cvt_pk_bf16_f32 v48, v42, v43
	v_cvt_pk_bf16_f32 v49, v44, v45
	global_store_dwordx4 v[54:55], v[46:49], off
	v_cvt_pk_bf16_f32 v34, v34, v35
	v_cvt_pk_bf16_f32 v35, v36, v37
	s_lshl_b64 s[20:21], 0x60, s1
	v_cvt_pk_bf16_f32 v36, v26, v27
	v_cvt_pk_bf16_f32 v37, v28, v29
	global_store_dwordx4 v[54:55], v[34:37], off offset:256
	v_cvt_pk_bf16_f32 v26, v38, v39
	v_cvt_pk_bf16_f32 v27, v40, v41
	v_cvt_pk_bf16_f32 v28, v30, v31
	v_cvt_pk_bf16_f32 v29, v32, v33
	s_andn2_b64 vcc, exec, s[6:7]
	s_nop 0
	v_lshl_add_u64 v[34:35], s[20:21], 1, v[142:143]
	global_store_dwordx4 v[34:35], v[26:29], off
	v_cvt_pk_bf16_f32 v18, v18, v19
	v_cvt_pk_bf16_f32 v19, v20, v21
	s_lshl_b64 s[20:21], 0x70, s1
	v_cvt_pk_bf16_f32 v20, v10, v11
	v_cvt_pk_bf16_f32 v21, v12, v13
	global_store_dwordx4 v[34:35], v[18:21], off offset:256
	s_mov_b64 s[6:7], -1
	v_cvt_pk_bf16_f32 v10, v22, v23
	v_cvt_pk_bf16_f32 v11, v24, v25
	v_cvt_pk_bf16_f32 v12, v14, v15
	v_cvt_pk_bf16_f32 v13, v16, v17
	s_nop 0
	v_lshl_add_u64 v[18:19], s[20:21], 1, v[142:143]
	global_store_dwordx4 v[18:19], v[10:13], off
	v_cvt_pk_bf16_f32 v6, v6, v7
	v_cvt_pk_bf16_f32 v7, v8, v9
	v_cvt_pk_bf16_f32 v8, v2, v3
	v_cvt_pk_bf16_f32 v9, v4, v5
	global_store_dwordx4 v[18:19], v[6:9], off offset:256
	s_cbranch_vccnz .LBB0_654
	s_andn2_b64 vcc, exec, s[4:5]
	s_cbranch_vccnz .LBB0_653
	s_branch .LBB0_653

; template <class Epi, class Sched, bool ALIGN_EPI = false, bool SP2 = false, bool ABLK = false, bool BBLK = false>
; __device__ __forceinline__ void gemm_phase(PG8_LAS unsigned char* lds, const Gemm g, const Sched& S, const Epi& E) {
;     ...
;     for (int i = 0; i < 2; ++i) { int R, C; stage_rc(tid * 16 + i * 8192, R, C); const int Rb = Epi::PERM ? ((R & ~31) + perm32(R & 31)) : R;
;         voffA[i] = ABLK ? (unsigned)(R * BK + C) * 2u : (unsigned)(R * LDA + C) * 2u; voffB[i] = BBLK ? (unsigned)(Rb * BK + C) * 2u : (unsigned)(Rb * LDB + C) * 2u; }
;     const size_t kstep = (size_t)(BK * 2);
;     const size_t hstepa = (size_t)HALF * LDA * 2, hstepb = (size_t)HALF * LDB * 2;
;     const size_t kstepA = ABLK ? (size_t)BM * BK * 2 : kstep, hstepA = ABLK ? (size_t)HALF * BK * 2 : hstepa, tstepA = ABLK ? (size_t)nt * BM * BK * 2 : 2 * hstepa;
;     const size_t kstepB = BBLK ? (size_t)BM * BK * 2 : kstep, hstepB = BBLK ? (size_t)HALF * BK * 2 : hstepb, tstepB = BBLK ? (size_t)nt * BM * BK * 2 : 2 * hstepb;
;     const unsigned ldsw = (unsigned)wid * 1024u;
;     const int aoff = lds_byte(wr * 64 + fr, fq * 8), boff = lds_byte(wc * 32 + fr, fq * 8);
;     ...
;     Unit cur, nxt; int ui = 0;
;     if (!S.next(0, cur)) return;
;     f32x4 acc[2][2][4][2];
; #pragma unroll
;     for (int a = 0; a < 2; ++a)
; #pragma unroll
;         for (int b = 0; b < 2; ++b)
; #pragma unroll
;             for (int m = 0; m < 4; ++m)
; #pragma unroll
;                 for (int n = 0; n < 2; ++n) acc[a][b][m][n] = (f32x4){0.f, 0.f, 0.f, 0.f};
;     bf16x8 At[4][2], B0[2][2], B1[2][2];
;     const char* cA = (const char*)g.A + (size_t)cur.pm * tstepA; const char* cB = (const char*)g.Bt + (size_t)cur.pn * tstepB;
;     S.a_ready(cur);
;     if constexpr (SP2) {
;         PG8_STAGE(PG8_SB(0, 0), cB, voffB); PG8_STAGE(PG8_SB(0, 1), cB + hstepB, voffB); PG8_STAGE(PG8_SA(0, 0), cA, voffA); PG8_STAGE(PG8_SA(0, 1), cA + hstepA, voffA);
;         if (wr == 1) PG8_BAR;
;         PG8_WAIT_V(2); PG8_BAR;
;         PG8_STAGE(PG8_SB(1, 0), cB + kstepB, voffB); PG8_STAGE(PG8_SA(1, 0), cA + kstepA, voffA); PG8_STAGE(PG8_SB(1, 1), cB + hstepB + kstepB, voffB);
;         PG8_WAIT_V(6); PG8_BAR;
;     } else {
;         PG8_STAGE(PG8_SB(0, 0), cB, voffB); PG8_STAGE(PG8_SA(0, 0), cA, voffA); PG8_STAGE(PG8_SB(0, 1), cB + hstepB, voffB); PG8_STAGE(PG8_SA(0, 1), cA + hstepA, voffA);
;         if (wr == 1) PG8_BAR;
.LBB0_753:
	s_add_u32 s30, s2, 0x49e00000
	s_addc_u32 s31, s3, 0
	s_ashr_i32 s43, s41, 31
	v_mov_b32_e32 v11, v0
	s_barrier
	s_cmpk_lt_i32 s42, 0x80
	s_nop 0
	v_readfirstlane_b32 s7, v11
	s_cbranch_scc0 .LBB0_773
	v_lshlrev_b32_e32 v2, 4, v11
	v_add_u32_e32 v3, 0x2000, v2
	v_ashrrev_i32_e32 v4, 31, v3
	v_lshrrev_b32_e32 v4, 22, v4
	v_add_u32_e32 v4, v3, v4
	v_ashrrev_i32_e32 v10, 10, v4
	v_mul_i32_i24_e32 v4, 0x400, v10
	v_sub_u32_e32 v3, v3, v4
	v_lshrrev_b32_e32 v4, 4, v3
	v_bitop3_b32 v3, v4, v3, 32 bitop3:0x6c
	v_ashrrev_i32_e32 v4, 31, v3
	v_lshrrev_b32_e32 v4, 26, v4
	v_add_u32_e32 v4, v3, v4
	v_lshlrev_b32_e32 v5, 3, v10
	v_ashrrev_i32_e32 v12, 6, v4
	v_and_b32_e32 v5, -16, v5
	v_add_u32_e32 v5, v12, v5
	v_and_b32_e32 v6, 3, v12
	s_mov_b32 s0, 0xfffe0
	v_lshrrev_b32_e32 v7, 2, v5
	v_lshlrev_b32_e32 v8, 1, v5
	v_and_b32_e32 v4, 0xc0, v4
	v_and_or_b32 v6, v5, s0, v6
	v_and_b32_e32 v7, 4, v7
	v_and_b32_e32 v8, 24, v8
	v_sub_u32_e32 v3, v3, v4
	v_or3_b32 v6, v6, v7, v8
	v_lshlrev_b32_e32 v7, 5, v10
	v_ashrrev_i16_sdwa v3, v232, sext(v3) dst_sel:DWORD dst_unused:UNUSED_PAD src0_sel:DWORD src1_sel:BYTE_0
	v_and_b32_e32 v7, 32, v7
	v_bfe_i32 v13, v3, 0, 16
	v_add_lshl_u32 v3, v7, v13, 1
	v_lshl_add_u32 v130, v6, 12, v3
	v_lshl_add_u32 v132, v5, 12, v3
	v_bfe_i32 v3, v11, 27, 1
	v_lshrrev_b32_e32 v3, 22, v3
	v_add_u32_e32 v3, v2, v3
	v_and_b32_e32 v3, 0xfffffc00, v3
	v_sub_u32_e32 v2, v2, v3
	v_lshrrev_b32_e32 v3, 4, v2
	v_ashrrev_i32_e32 v4, 31, v11
	v_bitop3_b32 v2, v3, v2, 32 bitop3:0x6c
	v_lshrrev_b32_e32 v4, 26, v4
	v_ashrrev_i32_e32 v3, 31, v2
	v_add_u32_e32 v4, v11, v4
	s_add_u32 s33, s2, 0x400000
	v_lshrrev_b32_e32 v3, 26, v3
	v_ashrrev_i32_e32 v15, 6, v4
	s_addc_u32 s34, s3, 0
	v_add_u32_e32 v3, v2, v3
	v_lshlrev_b32_e32 v4, 3, v15
	s_add_u32 s35, s2, 0x28200000
	v_ashrrev_i32_e32 v14, 6, v3
	v_and_b32_e32 v4, -16, v4
	s_addc_u32 s36, s3, 0
	v_add_u32_e32 v4, v14, v4
	v_and_b32_e32 v5, 3, v14
	s_ashr_i32 s44, s42, 31
	v_and_or_b32 v5, v4, s0, v5
	s_lshr_b32 s0, s44, 29
	s_add_i32 s0, s42, s0
	s_ashr_i32 s1, s0, 3
	s_and_b32 s0, s0, -8
	s_ashr_i32 s10, s7, 6
	s_sub_i32 s0, s42, s0
	s_ashr_i32 s8, s7, 8
	s_lshl_b32 s37, s10, 10
	s_lshl_b32 s5, s0, 4
	s_mul_i32 s4, s0, 17
	s_cmp_lt_i32 s0, 0
	s_cselect_b32 s0, s4, s5
	s_add_i32 s0, s0, s1
	s_ashr_i32 s1, s0, 31
	s_lshr_b32 s1, s1, 26
	v_lshrrev_b32_e32 v6, 2, v4
	v_lshlrev_b32_e32 v7, 1, v4
	v_and_b32_e32 v3, 0xc0, v3
	s_add_i32 s1, s0, s1
	v_and_b32_e32 v6, 4, v6
	v_and_b32_e32 v7, 24, v7
	v_sub_u32_e32 v2, v2, v3
	s_ashr_i32 s4, s1, 6
	v_or3_b32 v5, v5, v6, v7
	v_lshlrev_b32_e32 v6, 5, v15
	v_ashrrev_i16_sdwa v2, v232, sext(v2) dst_sel:DWORD dst_unused:UNUSED_PAD src0_sel:DWORD src1_sel:BYTE_0
	s_lshl_b32 s4, s4, 2
	v_and_b32_e32 v6, 32, v6
	v_bfe_i32 v16, v2, 0, 16
	s_sub_i32 s5, 8, s4
	v_add_lshl_u32 v2, v6, v16, 1
	s_min_u32 s5, s5, 4
	s_andn2_b32 s1, s1, 63
	v_lshl_add_u32 v134, v5, 12, v2
	s_sub_i32 s9, s0, s1
	v_cvt_f32_ubyte0_e32 v5, s5
	v_cvt_f32_i32_e32 v3, s9
	v_rcp_iflag_f32_e32 v6, v5
	v_lshl_add_u32 v136, v4, 12, v2
	s_ashr_i32 s0, s9, 30
	s_or_b32 s6, s0, 1
	v_mul_f32_e32 v2, v3, v6
	v_trunc_f32_e32 v2, v2
	v_fma_f32 v3, -v2, v5, v3
	v_cvt_i32_f32_e32 v2, v2
	v_cmp_ge_f32_e64 s[0:1], |v3|, v5
	s_and_b64 s[0:1], s[0:1], exec
	s_cselect_b32 s0, s6, 0
	v_readfirstlane_b32 s1, v2
	s_add_i32 s6, s1, s0
	s_mul_i32 s0, s6, s5
	s_sub_i32 s0, s9, s0
	s_sext_i32_i8 s0, s0
	s_add_i32 s0, s4, s0
	s_ashr_i32 s1, s0, 31
	s_bfe_i64 s[12:13], s[6:7], 0x80000
	s_lshl_b64 s[4:5], s[0:1], 20
	s_lshl_b64 s[12:13], s[12:13], 20
	s_add_u32 s26, s35, s12
	s_addc_u32 s27, s36, s13
	s_add_i32 s45, s37, 0
	s_add_i32 m0, s45, 0x10000
	v_mov_b32_e32 v135, v187
	global_load_lds_dwordx4 v134, s[26:27]
	s_add_i32 m0, s45, 0x12000
	s_add_u32 s12, s26, 0x80000
	global_load_lds_dwordx4 v130, s[26:27]
	s_addc_u32 s13, s27, 0
	s_add_i32 m0, s45, 0x14000
	v_mov_b32_e32 v131, v187
	global_load_lds_dwordx4 v134, s[12:13]
	s_add_i32 m0, s45, 0x16000
	s_add_u32 s24, s33, s4
	s_addc_u32 s25, s34, s5
	s_add_i32 s46, s45, 0x2000
	global_load_lds_dwordx4 v130, s[12:13]
	s_mov_b32 m0, s45
	s_add_u32 s4, s24, 0x80000
	global_load_lds_dwordx4 v136, s[24:25]
	s_mov_b32 m0, s46
	s_addc_u32 s5, s25, 0
	s_add_i32 s47, s45, 0x4000
	global_load_lds_dwordx4 v132, s[24:25]
	s_mov_b32 m0, s47
	s_add_i32 s50, s45, 0x6000
	global_load_lds_dwordx4 v136, s[4:5]
	s_mov_b32 m0, s50
	v_mov_b32_e32 v137, v187
	global_load_lds_dwordx4 v132, s[4:5]
	v_mov_b32_e32 v133, v187
	s_cmp_eq_u32 s8, 1
	v_lshl_add_u64 v[8:9], s[26:27], 0, v[134:135]
	v_lshl_add_u64 v[6:7], s[26:27], 0, v[130:131]
	v_lshl_add_u64 v[2:3], s[24:25], 0, v[136:137]
	s_cselect_b64 s[4:5], -1, 0
	s_cmp_lg_u32 s8, 1
	v_lshl_add_u64 v[4:5], s[24:25], 0, v[132:133]
	s_cbranch_scc1 .LBB0_756
.LBB0_756:
	s_and_b32 s1, s10, 3
	s_add_i32 m0, s45, 0x18000
	v_lshl_add_u64 v[8:9], v[8:9], 0, s[62:63]
	s_lshl_b32 s51, s8, 6
	s_lshl_b32 s11, s8, 13
	s_lshl_b32 s12, s10, 5
	s_lshl_b32 s1, s1, 12
	s_waitcnt vmcnt(2)
	s_barrier
	global_load_lds_dwordx4 v[8:9], off
	v_lshl_add_u64 v[6:7], v[6:7], 0, s[62:63]
	s_add_i32 m0, s45, 0x1a000
	s_add_i32 s53, s45, 0x8000
	s_add_i32 s56, s45, 0xa000
	global_load_lds_dwordx4 v[6:7], off
	v_lshl_add_u64 v[2:3], v[2:3], 0, s[62:63]
	s_mov_b32 m0, s53
	s_add_u32 s8, s26, 0x80080
	global_load_lds_dwordx4 v[2:3], off
	v_lshl_add_u64 v[2:3], v[4:5], 0, s[62:63]
	s_mov_b32 m0, s56
	s_addc_u32 s9, s27, 0
	global_load_lds_dwordx4 v[2:3], off
	s_add_i32 m0, s45, 0x1c000
	v_lshl_add_u64 v[2:3], s[8:9], 0, v[134:135]
	global_load_lds_dwordx4 v[2:3], off
	v_lshl_add_u64 v[2:3], s[8:9], 0, v[130:131]
	s_add_i32 m0, s45, 0x1e000
	v_and_b32_e32 v144, 15, v11
	global_load_lds_dwordx4 v[2:3], off
	v_lshrrev_b32_e32 v2, 1, v11
	v_and_b32_e32 v2, 24, v2
	v_lshlrev_b32_e32 v3, 1, v2
	v_lshlrev_b32_e32 v4, 2, v11
	v_lshl_or_b32 v3, v144, 6, v3
	v_and_b32_e32 v4, 32, v4
	v_bitop3_b32 v5, v3, s11, v4 bitop3:0xde
	v_bitop3_b32 v145, v3, s1, v4 bitop3:0xde
	v_lshlrev_b32_e32 v3, 15, v15
	v_and_b32_e32 v3, 0xffff0000, v3
	v_lshl_add_u32 v3, v14, 12, v3
	v_and_b32_e32 v4, 1, v15
	v_lshl_or_b32 v3, v4, 6, v3
	v_lshl_add_u32 v138, v16, 1, v3
	v_lshlrev_b32_e32 v3, 15, v10
	s_cmpk_lt_u32 s7, 0x100
	v_and_b32_e32 v3, 0xffff0000, v3
	s_waitcnt vmcnt(6)
	s_cselect_b64 s[8:9], -1, 0
	s_lshl_b32 s1, s10, 6
	v_lshl_add_u32 v3, v12, 12, v3
	v_and_b32_e32 v4, 1, v10
	s_sext_i32_i8 s22, s6
	s_and_b32 s1, s1, 0x80
	s_and_b32 s6, s12, 32
	v_lshl_or_b32 v3, v4, 6, v3
	s_ashr_i32 s60, s51, 31
	v_mov_b32_e32 v139, v187
	v_lshl_add_u32 v140, v13, 1, v3
	v_mov_b32_e32 v141, v187
	s_mov_b32 s61, 0
	v_add_u32_e32 v146, 0, v5
	s_lshl_b32 s16, s1, 1
	s_lshl_b32 s10, s6, 1
	v_lshlrev_b32_e32 v186, 1, v2
	s_barrier
	s_branch .LBB0_759

; #define PG8_STAGE(bufoff, gbase, voff) do { _Pragma("unroll") for (int _i = 0; _i < 2; ++_i) \
;         __builtin_amdgcn_global_load_lds((const unsigned*)((const char*)(gbase) + (voff)[_i]), (PG8_LAS unsigned*)(lds + (bufoff) + ldsw + _i * 8192), 16, 0, 0); } while (0)
; #define PG8_LDA(dst, b, h) do { _Pragma("unroll") for (int m = 0; m < 4; ++m) _Pragma("unroll") for (int k = 0; k < 2; ++k) dst[m][k] = *(const PG8_LAS bf16x8*)(lds + PG8_SA(b, h) + aoff + m * 2048 + k * 1024); } while (0)
; #define PG8_LDB(dst, b, h) do { _Pragma("unroll") for (int n = 0; n < 2; ++n) _Pragma("unroll") for (int k = 0; k < 2; ++k) dst[n][k] = *(const PG8_LAS bf16x8*)(lds + PG8_SB(b, h) + boff + n * 2048 + k * 1024); } while (0)
; #define PG8_BAR __builtin_amdgcn_s_barrier()
; #define PG8_SCHED __builtin_amdgcn_sched_barrier(0)
; template <class Epi, class Sched, bool ALIGN_EPI = false, bool SP2 = false, bool ABLK = false, bool BBLK = false>
; __device__ __forceinline__ void gemm_phase(PG8_LAS unsigned char* lds, const Gemm g, const Sched& S, const Epi& E) {
;     ...
;         const bool has_next = S.next(ui + 1, nxt);
;         const char* nA = has_next ? (const char*)g.A + (size_t)nxt.pm * tstepA : cA; const char* nB = has_next ? (const char*)g.Bt + (size_t)nxt.pn * tstepB : cB;
;         for (int t = 0; t < nt; t += 2) {
;             const bool last = (t == nt - 2);
;             const char* a1 = cA + (size_t)(t + 1) * kstepA;
;             const char* a2 = last ? nA : cA + (size_t)(t + 2) * kstepA; const char* b2 = last ? nB : cB + (size_t)(t + 2) * kstepB;
;             const char* a3 = a2 + kstepA; const char* b3 = b2 + kstepB;
;             if (last && has_next) S.a_ready(nxt);
;             if constexpr (SP2) {
;             PG8_LDB(B0, 0, 0); PG8_LDB(B1, 0, 1); PG8_SCHED; PG8_LDA(At, 0, 0); PG8_STAGE(PG8_SA(1, 1), a1 + hstepA, voffA);
;     ...
;         for (int a = 0; a < 2; ++a)
; #pragma unroll
;             for (int b = 0; b < 2; ++b)
; #pragma unroll
;                 for (int m = 0; m < 4; ++m)
; #pragma unroll
;                     for (int n = 0; n < 2; ++n) acc[a][b][m][n] = (f32x4){0.f, 0.f, 0.f, 0.f};
;         cur = nxt; cA = nA; cB = nB; ++ui;
;         if constexpr (ALIGN_EPI) { if (wr == 1) PG8_BAR; }
.LBB0_765:
	s_ashr_i32 s15, s14, 31
	s_lshl_b64 s[18:19], s[14:15], 20
	s_add_u32 s18, s33, s18
	s_addc_u32 s19, s34, s19
	s_and_b64 s[20:21], s[6:7], exec
	s_cselect_b32 s1, s19, s25
	s_cselect_b32 s11, s18, s24
	s_ashr_i32 s13, s12, 31
	s_lshl_b64 s[20:21], s[12:13], 20
	s_add_u32 s20, s35, s20
	s_addc_u32 s21, s36, s21
	s_and_b64 s[28:29], s[6:7], exec
	s_cselect_b32 s13, s21, s27
	s_cselect_b32 s15, s20, s26
	s_add_u32 s24, s24, 0x80080
	s_addc_u32 s25, s25, 0
	s_add_u32 s23, s26, 0x100
	v_mov_b32_e32 v2, 0
	s_addc_u32 s65, s27, 0
	s_mov_b32 s68, -2
	v_mov_b32_e32 v3, v2
	v_mov_b32_e32 v4, v2
	v_mov_b32_e32 v5, v2
	v_mov_b32_e32 v6, v2
	v_mov_b32_e32 v7, v2
	v_mov_b32_e32 v8, v2
	v_mov_b32_e32 v9, v2
	v_mov_b32_e32 v14, v2
	v_mov_b32_e32 v15, v2
	v_mov_b32_e32 v16, v2
	v_mov_b32_e32 v17, v2
	v_mov_b32_e32 v22, v2
	v_mov_b32_e32 v23, v2
	v_mov_b32_e32 v24, v2
	v_mov_b32_e32 v25, v2
	v_mov_b32_e32 v30, v2
	v_mov_b32_e32 v31, v2
	v_mov_b32_e32 v32, v2
	v_mov_b32_e32 v33, v2
	v_mov_b32_e32 v38, v2
	v_mov_b32_e32 v39, v2
	v_mov_b32_e32 v40, v2
	v_mov_b32_e32 v41, v2
	v_mov_b32_e32 v46, v2
	v_mov_b32_e32 v47, v2
	v_mov_b32_e32 v48, v2
	v_mov_b32_e32 v49, v2
	v_mov_b32_e32 v54, v2
	v_mov_b32_e32 v55, v2
	v_mov_b32_e32 v56, v2
	v_mov_b32_e32 v57, v2
	v_mov_b32_e32 v10, v2
	v_mov_b32_e32 v11, v2
	v_mov_b32_e32 v12, v2
	v_mov_b32_e32 v13, v2
	v_mov_b32_e32 v18, v2
	v_mov_b32_e32 v19, v2
	v_mov_b32_e32 v20, v2
	v_mov_b32_e32 v21, v2
	v_mov_b32_e32 v26, v2
	v_mov_b32_e32 v27, v2
	v_mov_b32_e32 v28, v2
	v_mov_b32_e32 v29, v2
	v_mov_b32_e32 v34, v2
	v_mov_b32_e32 v35, v2
	v_mov_b32_e32 v36, v2
	v_mov_b32_e32 v37, v2
	v_mov_b32_e32 v42, v2
	v_mov_b32_e32 v43, v2
	v_mov_b32_e32 v44, v2
	v_mov_b32_e32 v45, v2
	v_mov_b32_e32 v50, v2
	v_mov_b32_e32 v51, v2
	v_mov_b32_e32 v52, v2
	v_mov_b32_e32 v53, v2
	v_mov_b32_e32 v58, v2
	v_mov_b32_e32 v59, v2
	v_mov_b32_e32 v60, v2
	v_mov_b32_e32 v61, v2
	v_mov_b32_e32 v62, v2
	v_mov_b32_e32 v63, v2
	v_mov_b32_e32 v64, v2
	v_mov_b32_e32 v65, v2
	v_mov_b32_e32 v66, v2
	v_mov_b32_e32 v67, v2
	v_mov_b32_e32 v68, v2
	v_mov_b32_e32 v69, v2
	v_mov_b32_e32 v70, v2
	v_mov_b32_e32 v71, v2
	v_mov_b32_e32 v72, v2
	v_mov_b32_e32 v73, v2
	v_mov_b32_e32 v78, v2
	v_mov_b32_e32 v79, v2
	v_mov_b32_e32 v80, v2
	v_mov_b32_e32 v81, v2
	v_mov_b32_e32 v86, v2
	v_mov_b32_e32 v87, v2
	v_mov_b32_e32 v88, v2
	v_mov_b32_e32 v89, v2
	v_mov_b32_e32 v94, v2
	v_mov_b32_e32 v95, v2
	v_mov_b32_e32 v96, v2
	v_mov_b32_e32 v97, v2
	v_mov_b32_e32 v102, v2
	v_mov_b32_e32 v103, v2
	v_mov_b32_e32 v104, v2
	v_mov_b32_e32 v105, v2
	v_mov_b32_e32 v110, v2
	v_mov_b32_e32 v111, v2
	v_mov_b32_e32 v112, v2
	v_mov_b32_e32 v113, v2
	v_mov_b32_e32 v118, v2
	v_mov_b32_e32 v119, v2
	v_mov_b32_e32 v120, v2
	v_mov_b32_e32 v121, v2
	v_mov_b32_e32 v74, v2
	v_mov_b32_e32 v75, v2
	v_mov_b32_e32 v76, v2
	v_mov_b32_e32 v77, v2
	v_mov_b32_e32 v82, v2
	v_mov_b32_e32 v83, v2
	v_mov_b32_e32 v84, v2
	v_mov_b32_e32 v85, v2
	v_mov_b32_e32 v90, v2
	v_mov_b32_e32 v91, v2
	v_mov_b32_e32 v92, v2
	v_mov_b32_e32 v93, v2
	v_mov_b32_e32 v98, v2
	v_mov_b32_e32 v99, v2
	v_mov_b32_e32 v100, v2
	v_mov_b32_e32 v101, v2
	v_mov_b32_e32 v106, v2
	v_mov_b32_e32 v107, v2
	v_mov_b32_e32 v108, v2
	v_mov_b32_e32 v109, v2
	v_mov_b32_e32 v114, v2
	v_mov_b32_e32 v115, v2
	v_mov_b32_e32 v116, v2
	v_mov_b32_e32 v117, v2
	v_mov_b32_e32 v122, v2
	v_mov_b32_e32 v123, v2
	v_mov_b32_e32 v124, v2
	v_mov_b32_e32 v125, v2
	v_mov_b32_e32 v126, v2
	v_mov_b32_e32 v127, v2
	v_mov_b32_e32 v128, v2
	v_mov_b32_e32 v129, v2
	s_and_b64 vcc, exec, s[8:9]
	s_cbranch_vccnz .Lrb_dft0
	s_barrier
.Lrb_dft0:
.LBB0_766:
	s_add_u32 s26, s24, 0xfff80080
	s_addc_u32 s27, s25, -1
	s_add_i32 s72, 0, 0x10000
	s_cmp_eq_u32 s68, 28
	s_cselect_b32 s29, s1, s27
	s_cselect_b32 s28, s11, s26
	v_add_u32_e32 v142, s72, v145
	s_cselect_b32 s27, s13, s65
	s_cselect_b32 s26, s15, s23
	s_add_i32 s75, 0, 0x14000
	ds_read_b128 v[148:151], v142
	ds_read_b128 v[152:155], v142 offset:1024
	ds_read_b128 v[156:159], v142 offset:2048
	ds_read_b128 v[160:163], v142 offset:3072
	v_add_u32_e32 v142, s75, v145
	ds_read_b128 v[164:167], v142
	ds_read_b128 v[168:171], v142 offset:1024
	ds_read_b128 v[172:175], v142 offset:2048
	ds_read_b128 v[176:179], v142 offset:3072
	v_lshl_add_u64 v[142:143], s[24:25], 0, v[138:139]
	s_add_i32 m0, s45, 0xc000
	ds_read_b128 v[180:183], v146
	ds_read_b128 v[196:199], v146 offset:1024
	ds_read_b128 v[200:203], v146 offset:2048
	ds_read_b128 v[204:207], v146 offset:3072
	ds_read_b128 v[208:211], v146 offset:4096
	ds_read_b128 v[212:215], v146 offset:5120
	ds_read_b128 v[216:219], v146 offset:6144
	ds_read_b128 v[220:223], v146 offset:7168
	global_load_lds_dwordx4 v[142:143], off
	v_lshl_add_u64 v[142:143], s[24:25], 0, v[140:141]
	s_add_i32 m0, s45, 0xe000
	s_nop 0
	global_load_lds_dwordx4 v[142:143], off
	s_waitcnt vmcnt(8)
	s_waitcnt lgkmcnt(0)
	s_barrier
; #define PG8_STAGE(bufoff, gbase, voff) do { _Pragma("unroll") for (int _i = 0; _i < 2; ++_i) \
;         __builtin_amdgcn_global_load_lds((const unsigned*)((const char*)(gbase) + (voff)[_i]), (PG8_LAS unsigned*)(lds + (bufoff) + ldsw + _i * 8192), 16, 0, 0); } while (0)
; #define PG8_LDA(dst, b, h) do { _Pragma("unroll") for (int m = 0; m < 4; ++m) _Pragma("unroll") for (int k = 0; k < 2; ++k) dst[m][k] = *(const PG8_LAS bf16x8*)(lds + PG8_SA(b, h) + aoff + m * 2048 + k * 1024); } while (0)
; #define PG8_MMA(ai, bj, At, Bt) do { __builtin_amdgcn_s_setprio(1); _Pragma("unroll") for (int m = 0; m < 4; ++m) _Pragma("unroll") for (int n = 0; n < 2; ++n) _Pragma("unroll") for (int k = 0; k < 2; ++k) \
;         acc[ai][bj][m][n] = __builtin_amdgcn_mfma_f32_16x16x32_bf16(Bt[n][k], At[m][k], acc[ai][bj][m][n], 0, 0, 0); __builtin_amdgcn_s_setprio(0); } while (0)
; #define PG8_WAIT_V(n) asm volatile("s_waitcnt vmcnt(" #n ")" ::: "memory")
; #define PG8_WAIT_L(n) asm volatile("s_waitcnt lgkmcnt(" #n ")" ::: "memory")
; #define PG8_BAR __builtin_amdgcn_s_barrier()
; #define PG8_SCHED __builtin_amdgcn_sched_barrier(0)
; template <class Epi, class Sched, bool ALIGN_EPI = false, bool SP2 = false, bool ABLK = false, bool BBLK = false>
; __device__ __forceinline__ void gemm_phase(PG8_LAS unsigned char* lds, const Gemm g, const Sched& S, const Epi& E) {
;     ...
;             PG8_WAIT_V(8); PG8_WAIT_L(0); PG8_BAR; PG8_MMA(0, 0, At, B0); PG8_MMA(0, 1, At, B1); PG8_BAR; PG8_SCHED;
;             PG8_LDA(At, 0, 1); PG8_STAGE(PG8_SB(0, 0), b2, voffB); PG8_STAGE(PG8_SB(0, 1), b2 + hstepB, voffB); PG8_STAGE(PG8_SA(0, 0), a2, voffA);
;             PG8_WAIT_V(8); PG8_WAIT_L(0); PG8_BAR; PG8_MMA(1, 0, At, B0); PG8_MMA(1, 1, At, B1); PG8_BAR; PG8_SCHED;
	s_setprio 1
	s_waitcnt lgkmcnt(0)
	v_mfma_f32_16x16x32_bf16 v[126:129], v[148:151], v[180:183], v[126:129]
	v_mfma_f32_16x16x32_bf16 v[122:125], v[156:159], v[180:183], v[122:125]
	v_mfma_f32_16x16x32_bf16 v[114:117], v[148:151], v[200:203], v[114:117]
	v_mfma_f32_16x16x32_bf16 v[106:109], v[156:159], v[200:203], v[106:109]
	v_mfma_f32_16x16x32_bf16 v[98:101], v[148:151], v[208:211], v[98:101]
	v_mfma_f32_16x16x32_bf16 v[90:93], v[156:159], v[208:211], v[90:93]
	v_mfma_f32_16x16x32_bf16 v[82:85], v[148:151], v[216:219], v[82:85]
	v_mfma_f32_16x16x32_bf16 v[74:77], v[156:159], v[216:219], v[74:77]
	v_mfma_f32_16x16x32_bf16 v[126:129], v[152:155], v[196:199], v[126:129]
	v_mfma_f32_16x16x32_bf16 v[122:125], v[160:163], v[196:199], v[122:125]
	v_mfma_f32_16x16x32_bf16 v[114:117], v[152:155], v[204:207], v[114:117]
	v_mfma_f32_16x16x32_bf16 v[106:109], v[160:163], v[204:207], v[106:109]
	v_mfma_f32_16x16x32_bf16 v[98:101], v[152:155], v[212:215], v[98:101]
	v_mfma_f32_16x16x32_bf16 v[90:93], v[160:163], v[212:215], v[90:93]
	v_mfma_f32_16x16x32_bf16 v[82:85], v[152:155], v[220:223], v[82:85]
	v_mfma_f32_16x16x32_bf16 v[74:77], v[160:163], v[220:223], v[74:77]
	s_setprio 0
	s_setprio 1
	v_mfma_f32_16x16x32_bf16 v[118:121], v[164:167], v[180:183], v[118:121]
	v_mfma_f32_16x16x32_bf16 v[110:113], v[172:175], v[180:183], v[110:113]
	v_mfma_f32_16x16x32_bf16 v[102:105], v[164:167], v[200:203], v[102:105]
	v_mfma_f32_16x16x32_bf16 v[94:97], v[172:175], v[200:203], v[94:97]
	v_mfma_f32_16x16x32_bf16 v[86:89], v[164:167], v[208:211], v[86:89]
	v_mfma_f32_16x16x32_bf16 v[78:81], v[172:175], v[208:211], v[78:81]
	v_mfma_f32_16x16x32_bf16 v[70:73], v[164:167], v[216:219], v[70:73]
	v_mfma_f32_16x16x32_bf16 v[66:69], v[172:175], v[216:219], v[66:69]
	v_mfma_f32_16x16x32_bf16 v[118:121], v[168:171], v[196:199], v[118:121]
	v_mfma_f32_16x16x32_bf16 v[110:113], v[176:179], v[196:199], v[110:113]
	v_mfma_f32_16x16x32_bf16 v[102:105], v[168:171], v[204:207], v[102:105]
	v_mfma_f32_16x16x32_bf16 v[94:97], v[176:179], v[204:207], v[94:97]
	v_mfma_f32_16x16x32_bf16 v[86:89], v[168:171], v[212:215], v[86:89]
	v_mfma_f32_16x16x32_bf16 v[78:81], v[176:179], v[212:215], v[78:81]
	v_mfma_f32_16x16x32_bf16 v[70:73], v[168:171], v[220:223], v[70:73]
	v_mfma_f32_16x16x32_bf16 v[66:69], v[176:179], v[220:223], v[66:69]
	s_setprio 0
	s_barrier
	s_add_i32 s72, s72, s37
	v_lshl_add_u64 v[142:143], s[26:27], 0, v[134:135]
	s_mov_b32 m0, s72
	ds_read_b128 v[180:183], v146 offset:16384
	ds_read_b128 v[196:199], v146 offset:17408
	ds_read_b128 v[200:203], v146 offset:18432
	ds_read_b128 v[204:207], v146 offset:19456
	ds_read_b128 v[208:211], v146 offset:20480
	ds_read_b128 v[212:215], v146 offset:21504
	ds_read_b128 v[216:219], v146 offset:22528
	ds_read_b128 v[220:223], v146 offset:23552
	global_load_lds_dwordx4 v[142:143], off
	s_add_i32 m0, s72, 0x2000
	s_add_u32 s72, s26, 0x80000
	v_lshl_add_u64 v[184:185], s[26:27], 0, v[130:131]
	s_addc_u32 s73, s27, 0
	s_add_i32 s75, s75, s37
	global_load_lds_dwordx4 v[184:185], off
	v_lshl_add_u64 v[224:225], s[72:73], 0, v[134:135]
	s_mov_b32 m0, s75
	v_lshl_add_u64 v[226:227], s[28:29], 0, v[132:133]
	global_load_lds_dwordx4 v[224:225], off
	v_lshl_add_u64 v[224:225], s[72:73], 0, v[130:131]
	s_add_i32 m0, s75, 0x2000
	s_nop 0
	global_load_lds_dwordx4 v[224:225], off
	v_lshl_add_u64 v[224:225], s[28:29], 0, v[136:137]
	s_mov_b32 m0, s45
	s_nop 0
	global_load_lds_dwordx4 v[224:225], off
	s_mov_b32 m0, s46
	s_nop 0
	global_load_lds_dwordx4 v[226:227], off
	s_waitcnt vmcnt(8)
	s_waitcnt lgkmcnt(0)
	s_barrier
	s_setprio 1
	s_waitcnt lgkmcnt(0)
	v_mfma_f32_16x16x32_bf16 v[62:65], v[148:151], v[180:183], v[62:65]
	v_mfma_f32_16x16x32_bf16 v[58:61], v[156:159], v[180:183], v[58:61]
	v_mfma_f32_16x16x32_bf16 v[50:53], v[148:151], v[200:203], v[50:53]
	v_mfma_f32_16x16x32_bf16 v[42:45], v[156:159], v[200:203], v[42:45]
	v_mfma_f32_16x16x32_bf16 v[34:37], v[148:151], v[208:211], v[34:37]
	v_mfma_f32_16x16x32_bf16 v[26:29], v[156:159], v[208:211], v[26:29]
	v_mfma_f32_16x16x32_bf16 v[18:21], v[148:151], v[216:219], v[18:21]
	v_mfma_f32_16x16x32_bf16 v[10:13], v[156:159], v[216:219], v[10:13]
	v_mfma_f32_16x16x32_bf16 v[62:65], v[152:155], v[196:199], v[62:65]
	v_mfma_f32_16x16x32_bf16 v[58:61], v[160:163], v[196:199], v[58:61]
	v_mfma_f32_16x16x32_bf16 v[50:53], v[152:155], v[204:207], v[50:53]
	v_mfma_f32_16x16x32_bf16 v[42:45], v[160:163], v[204:207], v[42:45]
	v_mfma_f32_16x16x32_bf16 v[34:37], v[152:155], v[212:215], v[34:37]
	v_mfma_f32_16x16x32_bf16 v[26:29], v[160:163], v[212:215], v[26:29]
	v_mfma_f32_16x16x32_bf16 v[18:21], v[152:155], v[220:223], v[18:21]
	v_mfma_f32_16x16x32_bf16 v[10:13], v[160:163], v[220:223], v[10:13]
	s_setprio 0
	s_setprio 1
	v_mfma_f32_16x16x32_bf16 v[54:57], v[164:167], v[180:183], v[54:57]
	v_mfma_f32_16x16x32_bf16 v[46:49], v[172:175], v[180:183], v[46:49]
	v_mfma_f32_16x16x32_bf16 v[38:41], v[164:167], v[200:203], v[38:41]
	v_mfma_f32_16x16x32_bf16 v[30:33], v[172:175], v[200:203], v[30:33]
	v_mfma_f32_16x16x32_bf16 v[22:25], v[164:167], v[208:211], v[22:25]
	v_mfma_f32_16x16x32_bf16 v[14:17], v[172:175], v[208:211], v[14:17]
	v_mfma_f32_16x16x32_bf16 v[6:9], v[164:167], v[216:219], v[6:9]
	v_mfma_f32_16x16x32_bf16 v[2:5], v[172:175], v[216:219], v[2:5]
	v_mfma_f32_16x16x32_bf16 v[54:57], v[168:171], v[196:199], v[54:57]
	v_mfma_f32_16x16x32_bf16 v[46:49], v[176:179], v[196:199], v[46:49]
	v_mfma_f32_16x16x32_bf16 v[38:41], v[168:171], v[204:207], v[38:41]
	v_mfma_f32_16x16x32_bf16 v[30:33], v[176:179], v[204:207], v[30:33]
	v_mfma_f32_16x16x32_bf16 v[22:25], v[168:171], v[212:215], v[22:25]
	v_mfma_f32_16x16x32_bf16 v[14:17], v[176:179], v[212:215], v[14:17]
	v_mfma_f32_16x16x32_bf16 v[6:9], v[168:171], v[220:223], v[6:9]
	v_mfma_f32_16x16x32_bf16 v[2:5], v[176:179], v[220:223], v[2:5]
	s_setprio 0
	s_barrier
; #define PG8_STAGE(bufoff, gbase, voff) do { _Pragma("unroll") for (int _i = 0; _i < 2; ++_i) \
;         __builtin_amdgcn_global_load_lds((const unsigned*)((const char*)(gbase) + (voff)[_i]), (PG8_LAS unsigned*)(lds + (bufoff) + ldsw + _i * 8192), 16, 0, 0); } while (0)
; #define PG8_LDA(dst, b, h) do { _Pragma("unroll") for (int m = 0; m < 4; ++m) _Pragma("unroll") for (int k = 0; k < 2; ++k) dst[m][k] = *(const PG8_LAS bf16x8*)(lds + PG8_SA(b, h) + aoff + m * 2048 + k * 1024); } while (0)
; #define PG8_LDB(dst, b, h) do { _Pragma("unroll") for (int n = 0; n < 2; ++n) _Pragma("unroll") for (int k = 0; k < 2; ++k) dst[n][k] = *(const PG8_LAS bf16x8*)(lds + PG8_SB(b, h) + boff + n * 2048 + k * 1024); } while (0)
; #define PG8_MMA(ai, bj, At, Bt) do { __builtin_amdgcn_s_setprio(1); _Pragma("unroll") for (int m = 0; m < 4; ++m) _Pragma("unroll") for (int n = 0; n < 2; ++n) _Pragma("unroll") for (int k = 0; k < 2; ++k) \
;         acc[ai][bj][m][n] = __builtin_amdgcn_mfma_f32_16x16x32_bf16(Bt[n][k], At[m][k], acc[ai][bj][m][n], 0, 0, 0); __builtin_amdgcn_s_setprio(0); } while (0)
; #define PG8_WAIT_V(n) asm volatile("s_waitcnt vmcnt(" #n ")" ::: "memory")
; #define PG8_WAIT_L(n) asm volatile("s_waitcnt lgkmcnt(" #n ")" ::: "memory")
; #define PG8_BAR __builtin_amdgcn_s_barrier()
; #define PG8_SCHED __builtin_amdgcn_sched_barrier(0)
; template <class Epi, class Sched, bool ALIGN_EPI = false, bool SP2 = false, bool ABLK = false, bool BBLK = false>
; __device__ __forceinline__ void gemm_phase(PG8_LAS unsigned char* lds, const Gemm g, const Sched& S, const Epi& E) {
;     ...
;             PG8_LDB(B0, 1, 0); PG8_LDB(B1, 1, 1); PG8_SCHED; PG8_LDA(At, 1, 0); PG8_STAGE(PG8_SA(0, 1), a2 + hstepA, voffA);
;             PG8_WAIT_V(8); PG8_WAIT_L(0); PG8_BAR; PG8_MMA(0, 0, At, B0); PG8_MMA(0, 1, At, B1); PG8_BAR; PG8_SCHED;
;             PG8_LDA(At, 1, 1); PG8_STAGE(PG8_SB(1, 0), b3, voffB); PG8_STAGE(PG8_SB(1, 1), b3 + hstepB, voffB); PG8_STAGE(PG8_SA(1, 0), a3, voffA);
;             PG8_WAIT_V(8); PG8_WAIT_L(0); PG8_BAR; PG8_MMA(1, 0, At, B0); PG8_MMA(1, 1, At, B1); PG8_BAR; PG8_SCHED;
	s_add_i32 s72, 0, 0x18000
	v_add_u32_e32 v147, s72, v145
	s_add_i32 s73, 0, 0x1c000
	ds_read_b128 v[148:151], v147
	ds_read_b128 v[152:155], v147 offset:1024
	ds_read_b128 v[156:159], v147 offset:2048
	ds_read_b128 v[160:163], v147 offset:3072
	v_add_u32_e32 v147, s73, v145
	ds_read_b128 v[164:167], v147
	ds_read_b128 v[168:171], v147 offset:1024
	ds_read_b128 v[172:175], v147 offset:2048
	ds_read_b128 v[176:179], v147 offset:3072
	s_add_u32 s28, s28, 0x80000
	s_addc_u32 s29, s29, 0
	s_mov_b32 m0, s47
	v_lshl_add_u64 v[228:229], s[28:29], 0, v[136:137]
	ds_read_b128 v[180:183], v146 offset:32768
	ds_read_b128 v[196:199], v146 offset:33792
	ds_read_b128 v[200:203], v146 offset:34816
	ds_read_b128 v[204:207], v146 offset:35840
	ds_read_b128 v[208:211], v146 offset:36864
	ds_read_b128 v[212:215], v146 offset:37888
	ds_read_b128 v[216:219], v146 offset:38912
	ds_read_b128 v[220:223], v146 offset:39936
	global_load_lds_dwordx4 v[228:229], off
	v_lshl_add_u64 v[228:229], s[28:29], 0, v[132:133]
	s_mov_b32 m0, s50
	s_nop 0
	global_load_lds_dwordx4 v[228:229], off
	s_waitcnt vmcnt(8)
	s_waitcnt lgkmcnt(0)
	s_barrier
	s_setprio 1
	s_waitcnt lgkmcnt(0)
	v_mfma_f32_16x16x32_bf16 v[126:129], v[148:151], v[180:183], v[126:129]
	v_mfma_f32_16x16x32_bf16 v[122:125], v[156:159], v[180:183], v[122:125]
	v_mfma_f32_16x16x32_bf16 v[114:117], v[148:151], v[200:203], v[114:117]
	v_mfma_f32_16x16x32_bf16 v[106:109], v[156:159], v[200:203], v[106:109]
	v_mfma_f32_16x16x32_bf16 v[98:101], v[148:151], v[208:211], v[98:101]
	v_mfma_f32_16x16x32_bf16 v[90:93], v[156:159], v[208:211], v[90:93]
	v_mfma_f32_16x16x32_bf16 v[82:85], v[148:151], v[216:219], v[82:85]
	v_mfma_f32_16x16x32_bf16 v[74:77], v[156:159], v[216:219], v[74:77]
	v_mfma_f32_16x16x32_bf16 v[126:129], v[152:155], v[196:199], v[126:129]
	v_mfma_f32_16x16x32_bf16 v[122:125], v[160:163], v[196:199], v[122:125]
	v_mfma_f32_16x16x32_bf16 v[114:117], v[152:155], v[204:207], v[114:117]
	v_mfma_f32_16x16x32_bf16 v[106:109], v[160:163], v[204:207], v[106:109]
	v_mfma_f32_16x16x32_bf16 v[98:101], v[152:155], v[212:215], v[98:101]
	v_mfma_f32_16x16x32_bf16 v[90:93], v[160:163], v[212:215], v[90:93]
	v_mfma_f32_16x16x32_bf16 v[82:85], v[152:155], v[220:223], v[82:85]
	v_mfma_f32_16x16x32_bf16 v[74:77], v[160:163], v[220:223], v[74:77]
	s_setprio 0
	s_setprio 1
	v_mfma_f32_16x16x32_bf16 v[118:121], v[164:167], v[180:183], v[118:121]
	v_mfma_f32_16x16x32_bf16 v[110:113], v[172:175], v[180:183], v[110:113]
	v_mfma_f32_16x16x32_bf16 v[102:105], v[164:167], v[200:203], v[102:105]
	v_mfma_f32_16x16x32_bf16 v[94:97], v[172:175], v[200:203], v[94:97]
	v_mfma_f32_16x16x32_bf16 v[86:89], v[164:167], v[208:211], v[86:89]
	v_mfma_f32_16x16x32_bf16 v[78:81], v[172:175], v[208:211], v[78:81]
	v_mfma_f32_16x16x32_bf16 v[70:73], v[164:167], v[216:219], v[70:73]
	v_mfma_f32_16x16x32_bf16 v[66:69], v[172:175], v[216:219], v[66:69]
	v_mfma_f32_16x16x32_bf16 v[118:121], v[168:171], v[196:199], v[118:121]
	v_mfma_f32_16x16x32_bf16 v[110:113], v[176:179], v[196:199], v[110:113]
	v_mfma_f32_16x16x32_bf16 v[102:105], v[168:171], v[204:207], v[102:105]
	v_mfma_f32_16x16x32_bf16 v[94:97], v[176:179], v[204:207], v[94:97]
	v_mfma_f32_16x16x32_bf16 v[86:89], v[168:171], v[212:215], v[86:89]
	v_mfma_f32_16x16x32_bf16 v[78:81], v[176:179], v[212:215], v[78:81]
	v_mfma_f32_16x16x32_bf16 v[70:73], v[168:171], v[220:223], v[70:73]
	v_mfma_f32_16x16x32_bf16 v[66:69], v[176:179], v[220:223], v[66:69]
	s_setprio 0
	s_barrier
	s_add_i32 s28, s72, s37
	v_lshl_add_u64 v[142:143], v[142:143], 0, s[62:63]
	s_mov_b32 m0, s28
	ds_read_b128 v[180:183], v146 offset:49152
	ds_read_b128 v[196:199], v146 offset:50176
	ds_read_b128 v[200:203], v146 offset:51200
	ds_read_b128 v[204:207], v146 offset:52224
	ds_read_b128 v[208:211], v146 offset:53248
	ds_read_b128 v[212:215], v146 offset:54272
	ds_read_b128 v[216:219], v146 offset:55296
	ds_read_b128 v[220:223], v146 offset:56320
	global_load_lds_dwordx4 v[142:143], off
	s_add_i32 m0, s28, 0x2000
	s_add_u32 s26, s26, 0x80080
	v_lshl_add_u64 v[142:143], v[184:185], 0, s[62:63]
	s_addc_u32 s27, s27, 0
	s_add_i32 s28, s73, s37
	global_load_lds_dwordx4 v[142:143], off
	v_lshl_add_u64 v[142:143], s[26:27], 0, v[134:135]
	s_mov_b32 m0, s28
	s_nop 0
	global_load_lds_dwordx4 v[142:143], off
	v_lshl_add_u64 v[142:143], s[26:27], 0, v[130:131]
	s_add_i32 m0, s28, 0x2000
	s_nop 0
	global_load_lds_dwordx4 v[142:143], off
	v_lshl_add_u64 v[142:143], v[224:225], 0, s[62:63]
	s_mov_b32 m0, s53
	s_nop 0
	global_load_lds_dwordx4 v[142:143], off
	v_lshl_add_u64 v[142:143], v[226:227], 0, s[62:63]
	s_mov_b32 m0, s56
	s_nop 0
	global_load_lds_dwordx4 v[142:143], off
	s_waitcnt vmcnt(8)
	s_waitcnt lgkmcnt(0)
	s_barrier
; #define PG8_BAR __builtin_amdgcn_s_barrier()
;     __device__ __forceinline__ void operator()(const f32x4 (&acc)[2][2][4][2], const Unit& u, int wr, int wc, int fr_, int fq) const {
;         int fr = fr_; asm volatile("" : "+v"(fr));
;         bf16_t* ob = O0 + ((size_t)u.pn * L + u.pm * BM + wr * 64 + fr) * 512 + (wc >> 1) * 128 + type * 64 + (wc & 1) * 32 + 8 * fq;
; #pragma unroll
;         for (int ai = 0; ai < 2; ++ai)
; #pragma unroll
;             for (int m = 0; m < 4; ++m)
; #pragma unroll
;                 for (int bj = 0; bj < 2; ++bj) *(u32x4*)(ob + (size_t)(ai * HALF + m * 16) * 512 + bj * 256) = pack8(acc[ai][bj][m][0] * scale, acc[ai][bj][m][1] * scale);
; template <class Epi, class Sched, bool ALIGN_EPI = false, bool SP2 = false, bool ABLK = false, bool BBLK = false>
; __device__ __forceinline__ void gemm_phase(PG8_LAS unsigned char* lds, const Gemm g, const Sched& S, const Epi& E) {
;     ...
;             PG8_WAIT_V(8); PG8_WAIT_L(0); PG8_BAR; PG8_MMA(1, 0, At, B0); PG8_MMA(1, 1, At, B1); PG8_BAR; PG8_SCHED;
;             } else {
;             PG8_LDB(B0, 0, 0); PG8_SCHED; PG8_LDA(At, 0, 0); PG8_STAGE(PG8_SA(1, 1), a1 + hstepA, voffA);
;             PG8_WAIT_L(8); PG8_BAR; PG8_WAIT_L(0); PG8_MMA(0, 0, At, B0); PG8_BAR; PG8_SCHED;
;             PG8_LDB(B1, 0, 1); PG8_STAGE(PG8_SB(0, 0), b2, voffB);
;             PG8_BAR; PG8_WAIT_L(0); PG8_MMA(0, 1, At, B1); PG8_BAR;
;             PG8_LDA(At, 0, 1); PG8_STAGE(PG8_SA(0, 0), a2, voffA);
;             PG8_BAR; PG8_WAIT_L(0); PG8_MMA(1, 0, At, B0); PG8_BAR; PG8_SCHED;
;             PG8_STAGE(PG8_SB(0, 1), b2 + hstepB, voffB);
;             PG8_WAIT_V(6); PG8_BAR; PG8_MMA(1, 1, At, B1); PG8_BAR;
;             PG8_LDB(B0, 1, 0); PG8_SCHED; PG8_LDA(At, 1, 0); PG8_STAGE(PG8_SA(0, 1), a2 + hstepA, voffA);
;             PG8_WAIT_L(8); PG8_BAR; PG8_WAIT_L(0); PG8_MMA(0, 0, At, B0); PG8_BAR; PG8_SCHED;
;             PG8_LDB(B1, 1, 1); PG8_STAGE(PG8_SB(1, 0), b3, voffB);
;             PG8_BAR; PG8_WAIT_L(0); PG8_MMA(0, 1, At, B1); PG8_BAR;
;             PG8_LDA(At, 1, 1); PG8_STAGE(PG8_SA(1, 0), a3, voffA);
;             PG8_BAR; PG8_WAIT_L(0); PG8_MMA(1, 0, At, B0); PG8_BAR; PG8_SCHED;
;             PG8_STAGE(PG8_SB(1, 1), b3 + hstepB, voffB);
;             PG8_WAIT_V(6); PG8_BAR; PG8_MMA(1, 1, At, B1); PG8_BAR;
;             }
;         }
;         if constexpr (ALIGN_EPI) { if (wr == 0) PG8_BAR; }
	s_setprio 1
	s_waitcnt lgkmcnt(0)
	v_mfma_f32_16x16x32_bf16 v[62:65], v[148:151], v[180:183], v[62:65]
	v_mfma_f32_16x16x32_bf16 v[58:61], v[156:159], v[180:183], v[58:61]
	v_mfma_f32_16x16x32_bf16 v[50:53], v[148:151], v[200:203], v[50:53]
	v_mfma_f32_16x16x32_bf16 v[42:45], v[156:159], v[200:203], v[42:45]
	v_mfma_f32_16x16x32_bf16 v[34:37], v[148:151], v[208:211], v[34:37]
	v_mfma_f32_16x16x32_bf16 v[26:29], v[156:159], v[208:211], v[26:29]
	v_mfma_f32_16x16x32_bf16 v[18:21], v[148:151], v[216:219], v[18:21]
	v_mfma_f32_16x16x32_bf16 v[10:13], v[156:159], v[216:219], v[10:13]
	v_mfma_f32_16x16x32_bf16 v[62:65], v[152:155], v[196:199], v[62:65]
	v_mfma_f32_16x16x32_bf16 v[58:61], v[160:163], v[196:199], v[58:61]
	v_mfma_f32_16x16x32_bf16 v[50:53], v[152:155], v[204:207], v[50:53]
	v_mfma_f32_16x16x32_bf16 v[42:45], v[160:163], v[204:207], v[42:45]
	v_mfma_f32_16x16x32_bf16 v[34:37], v[152:155], v[212:215], v[34:37]
	v_mfma_f32_16x16x32_bf16 v[26:29], v[160:163], v[212:215], v[26:29]
	v_mfma_f32_16x16x32_bf16 v[18:21], v[152:155], v[220:223], v[18:21]
	v_mfma_f32_16x16x32_bf16 v[10:13], v[160:163], v[220:223], v[10:13]
	s_setprio 0
	s_setprio 1
	v_mfma_f32_16x16x32_bf16 v[54:57], v[164:167], v[180:183], v[54:57]
	v_mfma_f32_16x16x32_bf16 v[46:49], v[172:175], v[180:183], v[46:49]
	v_mfma_f32_16x16x32_bf16 v[38:41], v[164:167], v[200:203], v[38:41]
	v_mfma_f32_16x16x32_bf16 v[30:33], v[172:175], v[200:203], v[30:33]
	v_mfma_f32_16x16x32_bf16 v[22:25], v[164:167], v[208:211], v[22:25]
	v_mfma_f32_16x16x32_bf16 v[14:17], v[172:175], v[208:211], v[14:17]
	v_mfma_f32_16x16x32_bf16 v[6:9], v[164:167], v[216:219], v[6:9]
	v_mfma_f32_16x16x32_bf16 v[2:5], v[172:175], v[216:219], v[2:5]
	v_mfma_f32_16x16x32_bf16 v[54:57], v[168:171], v[196:199], v[54:57]
	v_mfma_f32_16x16x32_bf16 v[46:49], v[176:179], v[196:199], v[46:49]
	v_mfma_f32_16x16x32_bf16 v[38:41], v[168:171], v[204:207], v[38:41]
	v_mfma_f32_16x16x32_bf16 v[30:33], v[176:179], v[204:207], v[30:33]
	v_mfma_f32_16x16x32_bf16 v[22:25], v[168:171], v[212:215], v[22:25]
	v_mfma_f32_16x16x32_bf16 v[14:17], v[176:179], v[212:215], v[14:17]
	v_mfma_f32_16x16x32_bf16 v[6:9], v[168:171], v[220:223], v[6:9]
	v_mfma_f32_16x16x32_bf16 v[2:5], v[176:179], v[220:223], v[2:5]
	s_setprio 0
	s_barrier
	s_add_i32 s68, s68, 2
	s_add_u32 s24, s24, 0x100
	s_addc_u32 s25, s25, 0
	s_add_u32 s23, s23, 0x100
	s_addc_u32 s65, s65, 0
	s_cmp_gt_u32 s68, 29
	s_cbranch_scc0 .LBB0_766
	s_and_b64 vcc, exec, s[8:9]
	s_cbranch_vccz .LBB0_769
	s_barrier
.LBB0_769:
	s_lshl_b32 s0, s0, 8
	s_ashr_i32 s23, s22, 31
	s_ashr_i32 s1, s0, 31
	v_mov_b32_e32 v142, v144
	s_add_u32 s0, s0, s51
	s_addc_u32 s1, s1, s60
	v_ashrrev_i32_e32 v143, 31, v142
	v_lshl_add_u64 v[142:143], s[0:1], 0, v[142:143]
	s_lshl_b64 s[0:1], s[22:23], 21
	s_add_u32 s0, s30, s0
	v_lshlrev_b64 v[142:143], 10, v[142:143]
	s_addc_u32 s1, s31, s1
	v_lshl_add_u64 v[142:143], s[0:1], 0, v[142:143]
	v_lshl_add_u64 v[142:143], v[142:143], 0, s[16:17]
	s_mov_b32 s11, s17
	v_lshl_add_u64 v[142:143], v[142:143], 0, s[10:11]
	v_lshl_add_u64 v[142:143], v[142:143], 0, v[186:187]
	v_pk_mul_f32 v[128:129], v[128:129], s[64:65] op_sel_hi:[1,0]
	v_pk_mul_f32 v[126:127], v[126:127], s[64:65] op_sel_hi:[1,0]
	v_pk_mul_f32 v[148:149], v[124:125], s[64:65] op_sel_hi:[1,0]
	v_pk_mul_f32 v[124:125], v[122:123], s[64:65] op_sel_hi:[1,0]
	v_cvt_pk_bf16_f32 v122, v126, v127
	v_cvt_pk_bf16_f32 v123, v128, v129
	v_pk_mul_f32 v[120:121], v[120:121], s[64:65] op_sel_hi:[1,0]
	v_cvt_pk_bf16_f32 v124, v124, v125
	v_cvt_pk_bf16_f32 v125, v148, v149
	global_store_dwordx4 v[142:143], v[122:125], off
	v_pk_mul_f32 v[118:119], v[118:119], s[64:65] op_sel_hi:[1,0]
	v_pk_mul_f32 v[104:105], v[104:105], s[64:65] op_sel_hi:[1,0]
	v_pk_mul_f32 v[122:123], v[112:113], s[64:65] op_sel_hi:[1,0]
	v_pk_mul_f32 v[112:113], v[110:111], s[64:65] op_sel_hi:[1,0]
	v_cvt_pk_bf16_f32 v110, v118, v119
	v_cvt_pk_bf16_f32 v111, v120, v121
	v_pk_mul_f32 v[102:103], v[102:103], s[64:65] op_sel_hi:[1,0]
	v_cvt_pk_bf16_f32 v112, v112, v113
	v_cvt_pk_bf16_f32 v113, v122, v123
	global_store_dwordx4 v[142:143], v[110:113], off offset:512
	v_pk_mul_f32 v[88:89], v[88:89], s[64:65] op_sel_hi:[1,0]
	v_pk_mul_f32 v[86:87], v[86:87], s[64:65] op_sel_hi:[1,0]
	v_pk_mul_f32 v[110:111], v[116:117], s[64:65] op_sel_hi:[1,0]
	v_pk_mul_f32 v[112:113], v[114:115], s[64:65] op_sel_hi:[1,0]
	v_pk_mul_f32 v[114:115], v[108:109], s[64:65] op_sel_hi:[1,0]
	v_pk_mul_f32 v[108:109], v[106:107], s[64:65] op_sel_hi:[1,0]
	v_cvt_pk_bf16_f32 v106, v112, v113
	v_cvt_pk_bf16_f32 v107, v110, v111
	v_add_co_u32_e32 v110, vcc, s87, v142
	v_cvt_pk_bf16_f32 v108, v108, v109
	v_cvt_pk_bf16_f32 v109, v114, v115
	s_mov_b32 s0, 0xc000
	s_nop 0
	v_addc_co_u32_e32 v111, vcc, 0, v143, vcc
	global_store_dwordx4 v[110:111], v[106:109], off
	v_pk_mul_f32 v[72:73], v[72:73], s[64:65] op_sel_hi:[1,0]
	v_pk_mul_f32 v[70:71], v[70:71], s[64:65] op_sel_hi:[1,0]
	v_pk_mul_f32 v[106:107], v[96:97], s[64:65] op_sel_hi:[1,0]
	v_pk_mul_f32 v[96:97], v[94:95], s[64:65] op_sel_hi:[1,0]
	v_cvt_pk_bf16_f32 v94, v102, v103
	v_cvt_pk_bf16_f32 v95, v104, v105
	v_pk_mul_f32 v[62:63], v[62:63], s[64:65] op_sel_hi:[1,0]
	v_cvt_pk_bf16_f32 v96, v96, v97
	v_cvt_pk_bf16_f32 v97, v106, v107
	global_store_dwordx4 v[110:111], v[94:97], off offset:512
	v_pk_mul_f32 v[64:65], v[64:65], s[64:65] op_sel_hi:[1,0]
	v_pk_mul_f32 v[56:57], v[56:57], s[64:65] op_sel_hi:[1,0]
; __device__ __forceinline__ u32x4 pack8(const f32x4 v0, const f32x4 v1) { u32x4 w; w.x = cvt_pk_bf16(v0[0], v0[1]); w.y = cvt_pk_bf16(v0[2], v0[3]); w.z = cvt_pk_bf16(v1[0], v1[1]); w.w = cvt_pk_bf16(v1[2], v1[3]); return w; }
; #define PG8_BAR __builtin_amdgcn_s_barrier()
;     __device__ __forceinline__ void operator()(const f32x4 (&acc)[2][2][4][2], const Unit& u, int wr, int wc, int fr_, int fq) const {
;     ...
;         bf16_t* ob = O0 + ((size_t)u.pn * L + u.pm * BM + wr * 64 + fr) * 512 + (wc >> 1) * 128 + type * 64 + (wc & 1) * 32 + 8 * fq;
; #pragma unroll
;         for (int ai = 0; ai < 2; ++ai)
; #pragma unroll
;             for (int m = 0; m < 4; ++m)
; #pragma unroll
;                 for (int bj = 0; bj < 2; ++bj) *(u32x4*)(ob + (size_t)(ai * HALF + m * 16) * 512 + bj * 256) = pack8(acc[ai][bj][m][0] * scale, acc[ai][bj][m][1] * scale);
; template <class Epi, class Sched, bool ALIGN_EPI = false, bool SP2 = false, bool ABLK = false, bool BBLK = false>
; __device__ __forceinline__ void gemm_phase(PG8_LAS unsigned char* lds, const Gemm g, const Sched& S, const Epi& E) {
;     ...
;         if (!has_next) break;
; #pragma unroll
;         for (int a = 0; a < 2; ++a)
; #pragma unroll
;             for (int b = 0; b < 2; ++b)
; #pragma unroll
;                 for (int m = 0; m < 4; ++m)
; #pragma unroll
;                     for (int n = 0; n < 2; ++n) acc[a][b][m][n] = (f32x4){0.f, 0.f, 0.f, 0.f};
;         cur = nxt; cA = nA; cB = nB; ++ui;
;         if constexpr (ALIGN_EPI) { if (wr == 1) PG8_BAR; }
	v_pk_mul_f32 v[94:95], v[100:101], s[64:65] op_sel_hi:[1,0]
	v_pk_mul_f32 v[96:97], v[98:99], s[64:65] op_sel_hi:[1,0]
	v_pk_mul_f32 v[98:99], v[92:93], s[64:65] op_sel_hi:[1,0]
	v_pk_mul_f32 v[92:93], v[90:91], s[64:65] op_sel_hi:[1,0]
	v_cvt_pk_bf16_f32 v90, v96, v97
	v_cvt_pk_bf16_f32 v91, v94, v95
	v_add_co_u32_e32 v94, vcc, s69, v142
	v_cvt_pk_bf16_f32 v92, v92, v93
	v_cvt_pk_bf16_f32 v93, v98, v99
	v_pk_mul_f32 v[54:55], v[54:55], s[64:65] op_sel_hi:[1,0]
	s_nop 0
	v_addc_co_u32_e32 v95, vcc, 0, v143, vcc
	global_store_dwordx4 v[94:95], v[90:93], off
	v_pk_mul_f32 v[40:41], v[40:41], s[64:65] op_sel_hi:[1,0]
	v_pk_mul_f32 v[38:39], v[38:39], s[64:65] op_sel_hi:[1,0]
	v_pk_mul_f32 v[90:91], v[80:81], s[64:65] op_sel_hi:[1,0]
	v_pk_mul_f32 v[80:81], v[78:79], s[64:65] op_sel_hi:[1,0]
	v_cvt_pk_bf16_f32 v78, v86, v87
	v_cvt_pk_bf16_f32 v79, v88, v89
	v_pk_mul_f32 v[24:25], v[24:25], s[64:65] op_sel_hi:[1,0]
	v_cvt_pk_bf16_f32 v80, v80, v81
	v_cvt_pk_bf16_f32 v81, v90, v91
	global_store_dwordx4 v[94:95], v[78:81], off offset:512
	v_pk_mul_f32 v[22:23], v[22:23], s[64:65] op_sel_hi:[1,0]
	v_pk_mul_f32 v[8:9], v[8:9], s[64:65] op_sel_hi:[1,0]
	v_pk_mul_f32 v[78:79], v[84:85], s[64:65] op_sel_hi:[1,0]
	v_pk_mul_f32 v[80:81], v[82:83], s[64:65] op_sel_hi:[1,0]
	v_pk_mul_f32 v[82:83], v[76:77], s[64:65] op_sel_hi:[1,0]
	v_pk_mul_f32 v[76:77], v[74:75], s[64:65] op_sel_hi:[1,0]
	v_cvt_pk_bf16_f32 v74, v80, v81
	v_cvt_pk_bf16_f32 v75, v78, v79
	v_add_co_u32_e32 v78, vcc, s0, v142
	v_cvt_pk_bf16_f32 v76, v76, v77
	v_cvt_pk_bf16_f32 v77, v82, v83
	s_mov_b32 s0, 0x24000
	s_nop 0
	v_addc_co_u32_e32 v79, vcc, 0, v143, vcc
	global_store_dwordx4 v[78:79], v[74:77], off
	v_pk_mul_f32 v[6:7], v[6:7], s[64:65] op_sel_hi:[1,0]
	s_nop 0
	v_pk_mul_f32 v[74:75], v[68:69], s[64:65] op_sel_hi:[1,0]
	v_pk_mul_f32 v[68:69], v[66:67], s[64:65] op_sel_hi:[1,0]
	v_cvt_pk_bf16_f32 v66, v70, v71
	v_cvt_pk_bf16_f32 v67, v72, v73
	s_nop 0
	v_cvt_pk_bf16_f32 v68, v68, v69
	v_cvt_pk_bf16_f32 v69, v74, v75
	global_store_dwordx4 v[78:79], v[66:69], off offset:512
	s_nop 1
	v_pk_mul_f32 v[66:67], v[60:61], s[64:65] op_sel_hi:[1,0]
	v_pk_mul_f32 v[60:61], v[58:59], s[64:65] op_sel_hi:[1,0]
	v_cvt_pk_bf16_f32 v58, v62, v63
	v_add_co_u32_e32 v62, vcc, s95, v142
	v_cvt_pk_bf16_f32 v59, v64, v65
	v_cvt_pk_bf16_f32 v60, v60, v61
	v_cvt_pk_bf16_f32 v61, v66, v67
	s_nop 1
	v_addc_co_u32_e32 v63, vcc, 0, v143, vcc
	global_store_dwordx4 v[62:63], v[58:61], off
	s_nop 1
	v_pk_mul_f32 v[58:59], v[48:49], s[64:65] op_sel_hi:[1,0]
	v_pk_mul_f32 v[48:49], v[46:47], s[64:65] op_sel_hi:[1,0]
	v_cvt_pk_bf16_f32 v46, v54, v55
	v_cvt_pk_bf16_f32 v47, v56, v57
	s_nop 0
	v_cvt_pk_bf16_f32 v48, v48, v49
	v_cvt_pk_bf16_f32 v49, v58, v59
	global_store_dwordx4 v[62:63], v[46:49], off offset:512
	s_nop 1
	v_pk_mul_f32 v[46:47], v[52:53], s[64:65] op_sel_hi:[1,0]
	v_pk_mul_f32 v[48:49], v[50:51], s[64:65] op_sel_hi:[1,0]
	v_pk_mul_f32 v[50:51], v[44:45], s[64:65] op_sel_hi:[1,0]
	v_pk_mul_f32 v[44:45], v[42:43], s[64:65] op_sel_hi:[1,0]
	v_cvt_pk_bf16_f32 v42, v48, v49
	v_cvt_pk_bf16_f32 v43, v46, v47
	v_add_co_u32_e32 v46, vcc, s0, v142
	v_cvt_pk_bf16_f32 v44, v44, v45
	v_cvt_pk_bf16_f32 v45, v50, v51
	s_mov_b32 s0, 0x28000
	s_nop 0
	v_addc_co_u32_e32 v47, vcc, 0, v143, vcc
	global_store_dwordx4 v[46:47], v[42:45], off
	s_nop 1
	v_pk_mul_f32 v[42:43], v[32:33], s[64:65] op_sel_hi:[1,0]
	v_pk_mul_f32 v[32:33], v[30:31], s[64:65] op_sel_hi:[1,0]
	v_cvt_pk_bf16_f32 v30, v38, v39
	v_cvt_pk_bf16_f32 v31, v40, v41
	s_nop 0
	v_cvt_pk_bf16_f32 v32, v32, v33
	v_cvt_pk_bf16_f32 v33, v42, v43
	global_store_dwordx4 v[46:47], v[30:33], off offset:512
	s_nop 1
	v_pk_mul_f32 v[30:31], v[36:37], s[64:65] op_sel_hi:[1,0]
	v_pk_mul_f32 v[32:33], v[34:35], s[64:65] op_sel_hi:[1,0]
	v_pk_mul_f32 v[34:35], v[28:29], s[64:65] op_sel_hi:[1,0]
	v_pk_mul_f32 v[28:29], v[26:27], s[64:65] op_sel_hi:[1,0]
	v_cvt_pk_bf16_f32 v26, v32, v33
	v_cvt_pk_bf16_f32 v27, v30, v31
	v_add_co_u32_e32 v30, vcc, s0, v142
	v_cvt_pk_bf16_f32 v28, v28, v29
	v_cvt_pk_bf16_f32 v29, v34, v35
	s_mov_b32 s0, 0x2c000
	s_nop 0
	v_addc_co_u32_e32 v31, vcc, 0, v143, vcc
	global_store_dwordx4 v[30:31], v[26:29], off
	s_nop 1
	v_pk_mul_f32 v[26:27], v[16:17], s[64:65] op_sel_hi:[1,0]
	v_pk_mul_f32 v[16:17], v[14:15], s[64:65] op_sel_hi:[1,0]
	v_cvt_pk_bf16_f32 v14, v22, v23
	v_cvt_pk_bf16_f32 v15, v24, v25
	s_nop 0
	v_cvt_pk_bf16_f32 v16, v16, v17
	v_cvt_pk_bf16_f32 v17, v26, v27
	global_store_dwordx4 v[30:31], v[14:17], off offset:512
	s_nop 1
	v_pk_mul_f32 v[14:15], v[20:21], s[64:65] op_sel_hi:[1,0]
	v_pk_mul_f32 v[16:17], v[18:19], s[64:65] op_sel_hi:[1,0]
	v_pk_mul_f32 v[18:19], v[12:13], s[64:65] op_sel_hi:[1,0]
	v_pk_mul_f32 v[12:13], v[10:11], s[64:65] op_sel_hi:[1,0]
	v_cvt_pk_bf16_f32 v10, v16, v17
	v_cvt_pk_bf16_f32 v11, v14, v15
	v_add_co_u32_e32 v14, vcc, s0, v142
	v_cvt_pk_bf16_f32 v12, v12, v13
	v_cvt_pk_bf16_f32 v13, v18, v19
	s_mov_b64 s[0:1], -1
	s_nop 0
	v_addc_co_u32_e32 v15, vcc, 0, v143, vcc
	global_store_dwordx4 v[14:15], v[10:13], off
	s_andn2_b64 vcc, exec, s[6:7]
	s_nop 0
	v_pk_mul_f32 v[10:11], v[4:5], s[64:65] op_sel_hi:[1,0]
	v_pk_mul_f32 v[4:5], v[2:3], s[64:65] op_sel_hi:[1,0]
	v_cvt_pk_bf16_f32 v2, v6, v7
	v_cvt_pk_bf16_f32 v3, v8, v9
	s_nop 0
	v_cvt_pk_bf16_f32 v4, v4, v5
	v_cvt_pk_bf16_f32 v5, v10, v11
	global_store_dwordx4 v[14:15], v[2:5], off offset:512
	s_cbranch_vccnz .LBB0_758
	s_andn2_b64 vcc, exec, s[4:5]
	s_cbranch_vccnz .LBB0_757
	s_branch .LBB0_757

; #define PG8_WAIT_V(n) asm volatile("s_waitcnt vmcnt(" #n ")" ::: "memory")
; template <class Epi, class Sched, bool ALIGN_EPI = false, bool SP2 = false, bool ABLK = false, bool BBLK = false>
; __device__ __forceinline__ void gemm_phase(PG8_LAS unsigned char* lds, const Gemm g, const Sched& S, const Epi& E) {
;     ...
;     const int tid = tid_, wid = __builtin_amdgcn_readfirstlane(tid >> 6), lane = tid & 63, wr = wid >> 2, wc = wid & 3, fr = lane & 15, fq = lane >> 4;
;     const int K = g.K, nt = K / BK, LDA = g.lda ? g.lda : K, LDB = g.ldb ? g.ldb : K;
;     unsigned voffA[2], voffB[2];
; #pragma unroll
;     for (int i = 0; i < 2; ++i) { int R, C; stage_rc(tid * 16 + i * 8192, R, C); const int Rb = Epi::PERM ? ((R & ~31) + perm32(R & 31)) : R;
;         voffA[i] = ABLK ? (unsigned)(R * BK + C) * 2u : (unsigned)(R * LDA + C) * 2u; voffB[i] = BBLK ? (unsigned)(Rb * BK + C) * 2u : (unsigned)(Rb * LDB + C) * 2u; }
;     const size_t kstep = (size_t)(BK * 2);
;     const size_t hstepa = (size_t)HALF * LDA * 2, hstepb = (size_t)HALF * LDB * 2;
;     const size_t kstepA = ABLK ? (size_t)BM * BK * 2 : kstep, hstepA = ABLK ? (size_t)HALF * BK * 2 : hstepa, tstepA = ABLK ? (size_t)nt * BM * BK * 2 : 2 * hstepa;
;     const size_t kstepB = BBLK ? (size_t)BM * BK * 2 : kstep, hstepB = BBLK ? (size_t)HALF * BK * 2 : hstepb, tstepB = BBLK ? (size_t)nt * BM * BK * 2 : 2 * hstepb;
;     const unsigned ldsw = (unsigned)wid * 1024u;
;     const int aoff = lds_byte(wr * 64 + fr, fq * 8), boff = lds_byte(wc * 32 + fr, fq * 8);
;     ...
;     Unit cur, nxt; int ui = 0;
;     if (!S.next(0, cur)) return;
;     f32x4 acc[2][2][4][2];
; #pragma unroll
;     for (int a = 0; a < 2; ++a)
; #pragma unroll
;         for (int b = 0; b < 2; ++b)
; #pragma unroll
;             for (int m = 0; m < 4; ++m)
; #pragma unroll
;                 for (int n = 0; n < 2; ++n) acc[a][b][m][n] = (f32x4){0.f, 0.f, 0.f, 0.f};
;     bf16x8 At[4][2], B0[2][2], B1[2][2];
;     const char* cA = (const char*)g.A + (size_t)cur.pm * tstepA; const char* cB = (const char*)g.Bt + (size_t)cur.pn * tstepB;
;     S.a_ready(cur);
;     if constexpr (SP2) {
;         PG8_STAGE(PG8_SB(0, 0), cB, voffB); PG8_STAGE(PG8_SB(0, 1), cB + hstepB, voffB); PG8_STAGE(PG8_SA(0, 0), cA, voffA); PG8_STAGE(PG8_SA(0, 1), cA + hstepA, voffA);
;         if (wr == 1) PG8_BAR;
;         PG8_WAIT_V(2); PG8_BAR;
.LBB0_778:
	v_ashrrev_i32_e32 v3, 31, v10
	v_lshrrev_b32_e32 v3, 26, v3
	v_add_u32_e32 v3, v10, v3
	v_ashrrev_i32_e32 v11, 6, v3
	v_bfe_i32 v3, v10, 27, 1
	v_lshlrev_b32_e32 v2, 4, v10
	v_lshrrev_b32_e32 v3, 22, v3
	v_add_u32_e32 v3, v2, v3
	v_and_b32_e32 v3, 0xfffffc00, v3
	v_sub_u32_e32 v3, v2, v3
	v_lshrrev_b32_e32 v4, 4, v3
	v_bitop3_b32 v3, v4, v3, 32 bitop3:0x6c
	v_ashrrev_i32_e32 v5, 31, v3
	v_lshrrev_b32_e32 v5, 26, v5
	v_add_u32_e32 v5, v3, v5
	v_lshlrev_b32_e32 v4, 3, v11
	v_ashrrev_i32_e32 v12, 6, v5
	v_and_b32_e32 v5, 0xc0, v5
	v_and_b32_e32 v4, -16, v4
	v_sub_u32_e32 v3, v3, v5
	v_add_u32_e32 v4, v12, v4
	v_ashrrev_i16_sdwa v3, v232, sext(v3) dst_sel:DWORD dst_unused:UNUSED_PAD src0_sel:DWORD src1_sel:BYTE_0
	v_lshlrev_b32_e32 v6, 5, v11
	v_bfe_i32 v13, v3, 0, 16
	v_lshlrev_b32_e32 v3, 1, v4
	v_lshrrev_b32_e32 v5, 2, v4
	v_and_b32_e32 v7, 3, v12
	s_mov_b32 s1, 0xfffe0
	v_and_b32_e32 v6, 32, v6
	v_and_b32_e32 v3, 24, v3
	v_and_b32_e32 v5, 4, v5
	v_and_or_b32 v7, v4, s1, v7
	v_or3_b32 v3, v7, v5, v3
	v_add_lshl_u32 v5, v6, v13, 1
	v_add_u32_e32 v2, 0x2000, v2
	v_lshl_add_u32 v132, v3, 12, v5
	v_ashrrev_i32_e32 v3, 31, v2
	v_lshrrev_b32_e32 v3, 22, v3
	v_add_u32_e32 v3, v2, v3
	v_ashrrev_i32_e32 v14, 10, v3
	v_mul_i32_i24_e32 v3, 0x400, v14
	v_sub_u32_e32 v2, v2, v3
	v_lshrrev_b32_e32 v3, 4, v2
	v_bitop3_b32 v2, v3, v2, 32 bitop3:0x6c
	s_ashr_i32 s10, s7, 6
	s_ashr_i32 s8, s7, 8
	v_lshl_add_u32 v130, v4, 12, v5
	v_ashrrev_i32_e32 v4, 31, v2
	s_lshl_b32 s35, s10, 10
	v_lshrrev_b32_e32 v4, 26, v4
	s_add_u32 s36, s2, 0xc00000
	v_lshlrev_b32_e32 v3, 3, v14
	v_add_u32_e32 v4, v2, v4
	s_addc_u32 s37, s3, 0
	v_and_b32_e32 v3, -16, v3
	v_ashrrev_i32_e32 v15, 6, v4
	s_add_u32 s44, s2, 0x29200000
	v_add_u32_e32 v3, v15, v3
	v_and_b32_e32 v6, 3, v15
	s_addc_u32 s45, s3, 0
	s_add_i32 s0, s4, s0
	v_and_or_b32 v6, v3, s1, v6
	s_ashr_i32 s1, s0, 31
	s_lshr_b32 s1, s1, 26
	s_add_i32 s1, s0, s1
	s_ashr_i32 s4, s1, 6
	s_and_b32 s1, s1, 0xffc0
	s_sub_i32 s0, s0, s1
	s_bfe_i32 s1, s0, 0x80000
	s_bfe_u32 s1, s1, 0x2000d
	s_add_i32 s1, s0, s1
	s_bfe_i32 s5, s1, 0x80000
	s_and_b32 s1, s1, 0xfc
	s_sub_i32 s0, s0, s1
	s_lshl_b32 s4, s4, 2
	s_sext_i32_i16 s5, s5
	s_sext_i32_i8 s0, s0
	s_lshr_b32 s6, s5, 2
	s_add_i32 s0, s4, s0
	v_and_b32_e32 v4, 0xc0, v4
	s_ashr_i32 s1, s0, 31
	s_bfe_i64 s[12:13], s[6:7], 0x100000
	v_sub_u32_e32 v2, v2, v4
	s_lshl_b64 s[4:5], s[0:1], 20
	s_lshl_b64 s[12:13], s[12:13], 20
	v_ashrrev_i16_sdwa v2, v232, sext(v2) dst_sel:DWORD dst_unused:UNUSED_PAD src0_sel:DWORD src1_sel:BYTE_0
	s_add_u32 s26, s44, s12
	v_lshlrev_b32_e32 v5, 5, v14
	v_bfe_i32 v16, v2, 0, 16
	v_lshlrev_b32_e32 v2, 1, v3
	v_lshrrev_b32_e32 v4, 2, v3
	s_addc_u32 s27, s45, s13
	s_add_i32 s46, s35, 0
	v_and_b32_e32 v5, 32, v5
	v_and_b32_e32 v2, 24, v2
	v_and_b32_e32 v4, 4, v4
	s_add_i32 m0, s46, 0x10000
	v_or3_b32 v2, v6, v4, v2
	v_add_lshl_u32 v4, v5, v16, 1
	global_load_lds_dwordx4 v132, s[26:27]
	s_add_i32 m0, s46, 0x12000
	v_lshl_add_u32 v136, v2, 12, v4
	s_add_u32 s12, s26, 0x80000
	global_load_lds_dwordx4 v136, s[26:27]
	s_addc_u32 s13, s27, 0
	s_add_i32 m0, s46, 0x14000
	v_lshl_add_u32 v134, v3, 12, v4
	global_load_lds_dwordx4 v132, s[12:13]
	s_add_i32 m0, s46, 0x16000
	s_add_u32 s24, s36, s4
	s_addc_u32 s25, s37, s5
	s_add_i32 s47, s46, 0x2000
	global_load_lds_dwordx4 v136, s[12:13]
	s_mov_b32 m0, s46
	s_add_u32 s4, s24, 0x80000
	global_load_lds_dwordx4 v130, s[24:25]
	s_mov_b32 m0, s47
	s_addc_u32 s5, s25, 0
	s_add_i32 s53, s46, 0x4000
	global_load_lds_dwordx4 v134, s[24:25]
	s_mov_b32 m0, s53
	s_add_i32 s56, s46, 0x6000
	global_load_lds_dwordx4 v130, s[4:5]
	s_mov_b32 m0, s56
	v_mov_b32_e32 v133, v187
	global_load_lds_dwordx4 v134, s[4:5]
	v_mov_b32_e32 v137, v187
	v_mov_b32_e32 v131, v187
	v_mov_b32_e32 v135, v187
	s_cmp_eq_u32 s8, 1
	v_lshl_add_u64 v[8:9], s[26:27], 0, v[132:133]
	v_lshl_add_u64 v[6:7], s[26:27], 0, v[136:137]
	v_lshl_add_u64 v[2:3], s[24:25], 0, v[130:131]
	s_cselect_b64 s[4:5], -1, 0
	s_cmp_lg_u32 s8, 1
	v_lshl_add_u64 v[4:5], s[24:25], 0, v[134:135]
	s_cbranch_scc1 .LBB0_780
.LBB0_780:
	s_and_b32 s1, s10, 3
	s_add_i32 m0, s46, 0x18000
	v_lshl_add_u64 v[8:9], v[8:9], 0, s[62:63]
	s_lshl_b32 s60, s8, 6
	s_lshl_b32 s11, s8, 13
	s_lshl_b32 s12, s10, 5
	s_lshl_b32 s1, s1, 12
	s_waitcnt vmcnt(2)
	s_barrier
	global_load_lds_dwordx4 v[8:9], off
	v_lshl_add_u64 v[6:7], v[6:7], 0, s[62:63]
	s_add_i32 m0, s46, 0x1a000
	s_add_i32 s61, s46, 0x8000
	s_add_i32 s65, s46, 0xa000
	global_load_lds_dwordx4 v[6:7], off
	v_lshl_add_u64 v[2:3], v[2:3], 0, s[62:63]
	s_mov_b32 m0, s61
	s_add_u32 s8, s26, 0x80080
	global_load_lds_dwordx4 v[2:3], off
	v_lshl_add_u64 v[2:3], v[4:5], 0, s[62:63]
	s_mov_b32 m0, s65
	s_addc_u32 s9, s27, 0
	global_load_lds_dwordx4 v[2:3], off
	s_add_i32 m0, s46, 0x1c000
	v_lshl_add_u64 v[2:3], s[8:9], 0, v[132:133]
	global_load_lds_dwordx4 v[2:3], off
	v_lshl_add_u64 v[2:3], s[8:9], 0, v[136:137]
	s_add_i32 m0, s46, 0x1e000
	v_and_b32_e32 v144, 15, v10
	global_load_lds_dwordx4 v[2:3], off
	v_lshrrev_b32_e32 v2, 1, v10
	v_and_b32_e32 v2, 24, v2
	v_lshlrev_b32_e32 v3, 1, v2
	v_lshlrev_b32_e32 v4, 2, v10
	v_lshl_or_b32 v3, v144, 6, v3
	v_and_b32_e32 v4, 32, v4
	v_bitop3_b32 v5, v3, s11, v4 bitop3:0xde
	v_bitop3_b32 v145, v3, s1, v4 bitop3:0xde
	v_lshlrev_b32_e32 v3, 15, v11
	v_and_b32_e32 v3, 0xffff0000, v3
	v_lshl_add_u32 v3, v12, 12, v3
	v_and_b32_e32 v4, 1, v11
	v_lshl_or_b32 v3, v4, 6, v3
	v_lshl_add_u32 v138, v13, 1, v3
	v_lshlrev_b32_e32 v3, 15, v14
	s_cmpk_lt_u32 s7, 0x100
	v_and_b32_e32 v3, 0xffff0000, v3
	s_waitcnt vmcnt(6)
	s_cselect_b64 s[8:9], -1, 0
	s_lshl_b32 s1, s10, 6
	v_lshl_add_u32 v3, v15, 12, v3
	v_and_b32_e32 v4, 1, v14
	s_sext_i32_i8 s22, s6
	s_and_b32 s1, s1, 0x80
	s_and_b32 s6, s12, 32
	v_lshl_or_b32 v3, v4, 6, v3
	s_ashr_i32 s68, s60, 31
	v_mov_b32_e32 v139, v187
	v_lshl_add_u32 v140, v16, 1, v3
	v_mov_b32_e32 v141, v187
	s_mov_b32 s72, 0
	v_add_u32_e32 v146, 0, v5
	s_lshl_b32 s16, s1, 1
	s_lshl_b32 s10, s6, 1
	v_lshlrev_b32_e32 v186, 1, v2
	s_barrier
	s_branch .LBB0_783

; #define PG8_STAGE(bufoff, gbase, voff) do { _Pragma("unroll") for (int _i = 0; _i < 2; ++_i) \
;         __builtin_amdgcn_global_load_lds((const unsigned*)((const char*)(gbase) + (voff)[_i]), (PG8_LAS unsigned*)(lds + (bufoff) + ldsw + _i * 8192), 16, 0, 0); } while (0)
; #define PG8_LDA(dst, b, h) do { _Pragma("unroll") for (int m = 0; m < 4; ++m) _Pragma("unroll") for (int k = 0; k < 2; ++k) dst[m][k] = *(const PG8_LAS bf16x8*)(lds + PG8_SA(b, h) + aoff + m * 2048 + k * 1024); } while (0)
; #define PG8_LDB(dst, b, h) do { _Pragma("unroll") for (int n = 0; n < 2; ++n) _Pragma("unroll") for (int k = 0; k < 2; ++k) dst[n][k] = *(const PG8_LAS bf16x8*)(lds + PG8_SB(b, h) + boff + n * 2048 + k * 1024); } while (0)
; #define PG8_WAIT_V(n) asm volatile("s_waitcnt vmcnt(" #n ")" ::: "memory")
; #define PG8_BAR __builtin_amdgcn_s_barrier()
; template <class Epi, class Sched, bool ALIGN_EPI = false, bool SP2 = false, bool ABLK = false, bool BBLK = false>
; __device__ __forceinline__ void gemm_phase(PG8_LAS unsigned char* lds, const Gemm g, const Sched& S, const Epi& E) {
;     ...
;         const bool has_next = S.next(ui + 1, nxt);
;         const char* nA = has_next ? (const char*)g.A + (size_t)nxt.pm * tstepA : cA; const char* nB = has_next ? (const char*)g.Bt + (size_t)nxt.pn * tstepB : cB;
;         for (int t = 0; t < nt; t += 2) {
;             const bool last = (t == nt - 2);
;             const char* a1 = cA + (size_t)(t + 1) * kstepA;
;             const char* a2 = last ? nA : cA + (size_t)(t + 2) * kstepA; const char* b2 = last ? nB : cB + (size_t)(t + 2) * kstepB;
;             const char* a3 = a2 + kstepA; const char* b3 = b2 + kstepB;
;             if (last && has_next) S.a_ready(nxt);
;             if constexpr (SP2) {
;             PG8_LDB(B0, 0, 0); PG8_LDB(B1, 0, 1); PG8_SCHED; PG8_LDA(At, 0, 0); PG8_STAGE(PG8_SA(1, 1), a1 + hstepA, voffA);
;             PG8_WAIT_V(8); PG8_WAIT_L(0); PG8_BAR; PG8_MMA(0, 0, At, B0); PG8_MMA(0, 1, At, B1); PG8_BAR; PG8_SCHED;
;     ...
;         for (int a = 0; a < 2; ++a)
; #pragma unroll
;             for (int b = 0; b < 2; ++b)
; #pragma unroll
;                 for (int m = 0; m < 4; ++m)
; #pragma unroll
;                     for (int n = 0; n < 2; ++n) acc[a][b][m][n] = (f32x4){0.f, 0.f, 0.f, 0.f};
;         cur = nxt; cA = nA; cB = nB; ++ui;
;         if constexpr (ALIGN_EPI) { if (wr == 1) PG8_BAR; }
.LBB0_789:
	s_ashr_i32 s15, s14, 31
	s_lshl_b64 s[18:19], s[14:15], 20
	s_add_u32 s18, s36, s18
	s_addc_u32 s19, s37, s19
	s_and_b64 s[20:21], s[6:7], exec
	s_cselect_b32 s1, s19, s25
	s_cselect_b32 s11, s18, s24
	s_ashr_i32 s13, s12, 31
	s_lshl_b64 s[20:21], s[12:13], 20
	s_add_u32 s20, s44, s20
	s_addc_u32 s21, s45, s21
	s_and_b64 s[28:29], s[6:7], exec
	s_cselect_b32 s13, s21, s27
	s_cselect_b32 s15, s20, s26
	s_add_u32 s24, s24, 0x80080
	s_addc_u32 s25, s25, 0
	s_add_u32 s23, s26, 0x100
	v_mov_b32_e32 v2, 0
	s_addc_u32 s73, s27, 0
	s_mov_b32 s81, -2
	v_mov_b32_e32 v3, v2
	v_mov_b32_e32 v4, v2
	v_mov_b32_e32 v5, v2
	v_mov_b32_e32 v6, v2
	v_mov_b32_e32 v7, v2
	v_mov_b32_e32 v8, v2
	v_mov_b32_e32 v9, v2
	v_mov_b32_e32 v14, v2
	v_mov_b32_e32 v15, v2
	v_mov_b32_e32 v16, v2
	v_mov_b32_e32 v17, v2
	v_mov_b32_e32 v22, v2
	v_mov_b32_e32 v23, v2
	v_mov_b32_e32 v24, v2
	v_mov_b32_e32 v25, v2
	v_mov_b32_e32 v30, v2
	v_mov_b32_e32 v31, v2
	v_mov_b32_e32 v32, v2
	v_mov_b32_e32 v33, v2
	v_mov_b32_e32 v38, v2
	v_mov_b32_e32 v39, v2
	v_mov_b32_e32 v40, v2
	v_mov_b32_e32 v41, v2
	v_mov_b32_e32 v46, v2
	v_mov_b32_e32 v47, v2
	v_mov_b32_e32 v48, v2
	v_mov_b32_e32 v49, v2
	v_mov_b32_e32 v54, v2
	v_mov_b32_e32 v55, v2
	v_mov_b32_e32 v56, v2
	v_mov_b32_e32 v57, v2
	v_mov_b32_e32 v10, v2
	v_mov_b32_e32 v11, v2
	v_mov_b32_e32 v12, v2
	v_mov_b32_e32 v13, v2
	v_mov_b32_e32 v18, v2
	v_mov_b32_e32 v19, v2
	v_mov_b32_e32 v20, v2
	v_mov_b32_e32 v21, v2
	v_mov_b32_e32 v26, v2
	v_mov_b32_e32 v27, v2
	v_mov_b32_e32 v28, v2
	v_mov_b32_e32 v29, v2
	v_mov_b32_e32 v34, v2
	v_mov_b32_e32 v35, v2
	v_mov_b32_e32 v36, v2
	v_mov_b32_e32 v37, v2
	v_mov_b32_e32 v42, v2
	v_mov_b32_e32 v43, v2
	v_mov_b32_e32 v44, v2
	v_mov_b32_e32 v45, v2
	v_mov_b32_e32 v50, v2
	v_mov_b32_e32 v51, v2
	v_mov_b32_e32 v52, v2
	v_mov_b32_e32 v53, v2
	v_mov_b32_e32 v58, v2
	v_mov_b32_e32 v59, v2
	v_mov_b32_e32 v60, v2
	v_mov_b32_e32 v61, v2
	v_mov_b32_e32 v62, v2
	v_mov_b32_e32 v63, v2
	v_mov_b32_e32 v64, v2
	v_mov_b32_e32 v65, v2
	v_mov_b32_e32 v66, v2
	v_mov_b32_e32 v67, v2
	v_mov_b32_e32 v68, v2
	v_mov_b32_e32 v69, v2
	v_mov_b32_e32 v70, v2
	v_mov_b32_e32 v71, v2
	v_mov_b32_e32 v72, v2
	v_mov_b32_e32 v73, v2
	v_mov_b32_e32 v78, v2
	v_mov_b32_e32 v79, v2
	v_mov_b32_e32 v80, v2
	v_mov_b32_e32 v81, v2
	v_mov_b32_e32 v86, v2
	v_mov_b32_e32 v87, v2
	v_mov_b32_e32 v88, v2
	v_mov_b32_e32 v89, v2
	v_mov_b32_e32 v94, v2
	v_mov_b32_e32 v95, v2
	v_mov_b32_e32 v96, v2
	v_mov_b32_e32 v97, v2
	v_mov_b32_e32 v102, v2
	v_mov_b32_e32 v103, v2
	v_mov_b32_e32 v104, v2
	v_mov_b32_e32 v105, v2
	v_mov_b32_e32 v110, v2
	v_mov_b32_e32 v111, v2
	v_mov_b32_e32 v112, v2
	v_mov_b32_e32 v113, v2
	v_mov_b32_e32 v118, v2
	v_mov_b32_e32 v119, v2
	v_mov_b32_e32 v120, v2
	v_mov_b32_e32 v121, v2
	v_mov_b32_e32 v74, v2
	v_mov_b32_e32 v75, v2
	v_mov_b32_e32 v76, v2
	v_mov_b32_e32 v77, v2
	v_mov_b32_e32 v82, v2
	v_mov_b32_e32 v83, v2
	v_mov_b32_e32 v84, v2
	v_mov_b32_e32 v85, v2
	v_mov_b32_e32 v90, v2
	v_mov_b32_e32 v91, v2
	v_mov_b32_e32 v92, v2
	v_mov_b32_e32 v93, v2
	v_mov_b32_e32 v98, v2
	v_mov_b32_e32 v99, v2
	v_mov_b32_e32 v100, v2
	v_mov_b32_e32 v101, v2
	v_mov_b32_e32 v106, v2
	v_mov_b32_e32 v107, v2
	v_mov_b32_e32 v108, v2
	v_mov_b32_e32 v109, v2
	v_mov_b32_e32 v114, v2
	v_mov_b32_e32 v115, v2
	v_mov_b32_e32 v116, v2
	v_mov_b32_e32 v117, v2
	v_mov_b32_e32 v122, v2
	v_mov_b32_e32 v123, v2
	v_mov_b32_e32 v124, v2
	v_mov_b32_e32 v125, v2
	v_mov_b32_e32 v126, v2
	v_mov_b32_e32 v127, v2
	v_mov_b32_e32 v128, v2
	v_mov_b32_e32 v129, v2
	s_and_b64 vcc, exec, s[8:9]
	s_cbranch_vccnz .Lrb_dft1
	s_barrier
.Lrb_dft1:
.LBB0_790:
	s_add_u32 s26, s24, 0xfff80080
	s_addc_u32 s27, s25, -1
	s_add_i32 s51, 0, 0x10000
	s_cmp_eq_u32 s81, 28
	s_cselect_b32 s29, s1, s27
	s_cselect_b32 s28, s11, s26
	v_add_u32_e32 v142, s51, v145
	s_cselect_b32 s27, s13, s73
	s_cselect_b32 s26, s15, s23
	s_add_i32 s75, 0, 0x14000
	ds_read_b128 v[148:151], v142
	ds_read_b128 v[152:155], v142 offset:1024
	ds_read_b128 v[156:159], v142 offset:2048
	ds_read_b128 v[160:163], v142 offset:3072
	v_add_u32_e32 v142, s75, v145
	ds_read_b128 v[164:167], v142
	ds_read_b128 v[168:171], v142 offset:1024
	ds_read_b128 v[172:175], v142 offset:2048
	ds_read_b128 v[176:179], v142 offset:3072
	v_lshl_add_u64 v[142:143], s[24:25], 0, v[138:139]
	s_add_i32 m0, s46, 0xc000
	ds_read_b128 v[180:183], v146
	ds_read_b128 v[196:199], v146 offset:1024
	ds_read_b128 v[200:203], v146 offset:2048
	ds_read_b128 v[204:207], v146 offset:3072
	ds_read_b128 v[208:211], v146 offset:4096
	ds_read_b128 v[212:215], v146 offset:5120
	ds_read_b128 v[216:219], v146 offset:6144
	ds_read_b128 v[220:223], v146 offset:7168
	global_load_lds_dwordx4 v[142:143], off
	v_lshl_add_u64 v[142:143], s[24:25], 0, v[140:141]
	s_add_i32 m0, s46, 0xe000
	s_nop 0
	global_load_lds_dwordx4 v[142:143], off
	s_waitcnt vmcnt(8)
	s_waitcnt lgkmcnt(0)
	s_barrier
; #define PG8_STAGE(bufoff, gbase, voff) do { _Pragma("unroll") for (int _i = 0; _i < 2; ++_i) \
;         __builtin_amdgcn_global_load_lds((const unsigned*)((const char*)(gbase) + (voff)[_i]), (PG8_LAS unsigned*)(lds + (bufoff) + ldsw + _i * 8192), 16, 0, 0); } while (0)
; #define PG8_LDA(dst, b, h) do { _Pragma("unroll") for (int m = 0; m < 4; ++m) _Pragma("unroll") for (int k = 0; k < 2; ++k) dst[m][k] = *(const PG8_LAS bf16x8*)(lds + PG8_SA(b, h) + aoff + m * 2048 + k * 1024); } while (0)
; #define PG8_LDB(dst, b, h) do { _Pragma("unroll") for (int n = 0; n < 2; ++n) _Pragma("unroll") for (int k = 0; k < 2; ++k) dst[n][k] = *(const PG8_LAS bf16x8*)(lds + PG8_SB(b, h) + boff + n * 2048 + k * 1024); } while (0)
; #define PG8_MMA(ai, bj, At, Bt) do { __builtin_amdgcn_s_setprio(1); _Pragma("unroll") for (int m = 0; m < 4; ++m) _Pragma("unroll") for (int n = 0; n < 2; ++n) _Pragma("unroll") for (int k = 0; k < 2; ++k) \
;         acc[ai][bj][m][n] = __builtin_amdgcn_mfma_f32_16x16x32_bf16(Bt[n][k], At[m][k], acc[ai][bj][m][n], 0, 0, 0); __builtin_amdgcn_s_setprio(0); } while (0)
; #define PG8_WAIT_V(n) asm volatile("s_waitcnt vmcnt(" #n ")" ::: "memory")
; #define PG8_WAIT_L(n) asm volatile("s_waitcnt lgkmcnt(" #n ")" ::: "memory")
; #define PG8_BAR __builtin_amdgcn_s_barrier()
; #define PG8_SCHED __builtin_amdgcn_sched_barrier(0)
; template <class Epi, class Sched, bool ALIGN_EPI = false, bool SP2 = false, bool ABLK = false, bool BBLK = false>
; __device__ __forceinline__ void gemm_phase(PG8_LAS unsigned char* lds, const Gemm g, const Sched& S, const Epi& E) {
;     ...
;             PG8_LDB(B0, 0, 0); PG8_LDB(B1, 0, 1); PG8_SCHED; PG8_LDA(At, 0, 0); PG8_STAGE(PG8_SA(1, 1), a1 + hstepA, voffA);
;             PG8_WAIT_V(8); PG8_WAIT_L(0); PG8_BAR; PG8_MMA(0, 0, At, B0); PG8_MMA(0, 1, At, B1); PG8_BAR; PG8_SCHED;
;             PG8_LDA(At, 0, 1); PG8_STAGE(PG8_SB(0, 0), b2, voffB); PG8_STAGE(PG8_SB(0, 1), b2 + hstepB, voffB); PG8_STAGE(PG8_SA(0, 0), a2, voffA);
;             PG8_WAIT_V(8); PG8_WAIT_L(0); PG8_BAR; PG8_MMA(1, 0, At, B0); PG8_MMA(1, 1, At, B1); PG8_BAR; PG8_SCHED;
	s_setprio 1
	s_waitcnt lgkmcnt(0)
	v_mfma_f32_16x16x32_bf16 v[126:129], v[148:151], v[180:183], v[126:129]
	v_mfma_f32_16x16x32_bf16 v[122:125], v[156:159], v[180:183], v[122:125]
	v_mfma_f32_16x16x32_bf16 v[114:117], v[148:151], v[200:203], v[114:117]
	v_mfma_f32_16x16x32_bf16 v[106:109], v[156:159], v[200:203], v[106:109]
	v_mfma_f32_16x16x32_bf16 v[98:101], v[148:151], v[208:211], v[98:101]
	v_mfma_f32_16x16x32_bf16 v[90:93], v[156:159], v[208:211], v[90:93]
	v_mfma_f32_16x16x32_bf16 v[82:85], v[148:151], v[216:219], v[82:85]
	v_mfma_f32_16x16x32_bf16 v[74:77], v[156:159], v[216:219], v[74:77]
	v_mfma_f32_16x16x32_bf16 v[126:129], v[152:155], v[196:199], v[126:129]
	v_mfma_f32_16x16x32_bf16 v[122:125], v[160:163], v[196:199], v[122:125]
	v_mfma_f32_16x16x32_bf16 v[114:117], v[152:155], v[204:207], v[114:117]
	v_mfma_f32_16x16x32_bf16 v[106:109], v[160:163], v[204:207], v[106:109]
	v_mfma_f32_16x16x32_bf16 v[98:101], v[152:155], v[212:215], v[98:101]
	v_mfma_f32_16x16x32_bf16 v[90:93], v[160:163], v[212:215], v[90:93]
	v_mfma_f32_16x16x32_bf16 v[82:85], v[152:155], v[220:223], v[82:85]
	v_mfma_f32_16x16x32_bf16 v[74:77], v[160:163], v[220:223], v[74:77]
	s_setprio 0
	s_setprio 1
	v_mfma_f32_16x16x32_bf16 v[118:121], v[164:167], v[180:183], v[118:121]
	v_mfma_f32_16x16x32_bf16 v[110:113], v[172:175], v[180:183], v[110:113]
	v_mfma_f32_16x16x32_bf16 v[102:105], v[164:167], v[200:203], v[102:105]
	v_mfma_f32_16x16x32_bf16 v[94:97], v[172:175], v[200:203], v[94:97]
	v_mfma_f32_16x16x32_bf16 v[86:89], v[164:167], v[208:211], v[86:89]
	v_mfma_f32_16x16x32_bf16 v[78:81], v[172:175], v[208:211], v[78:81]
	v_mfma_f32_16x16x32_bf16 v[70:73], v[164:167], v[216:219], v[70:73]
	v_mfma_f32_16x16x32_bf16 v[66:69], v[172:175], v[216:219], v[66:69]
	v_mfma_f32_16x16x32_bf16 v[118:121], v[168:171], v[196:199], v[118:121]
	v_mfma_f32_16x16x32_bf16 v[110:113], v[176:179], v[196:199], v[110:113]
	v_mfma_f32_16x16x32_bf16 v[102:105], v[168:171], v[204:207], v[102:105]
	v_mfma_f32_16x16x32_bf16 v[94:97], v[176:179], v[204:207], v[94:97]
	v_mfma_f32_16x16x32_bf16 v[86:89], v[168:171], v[212:215], v[86:89]
	v_mfma_f32_16x16x32_bf16 v[78:81], v[176:179], v[212:215], v[78:81]
	v_mfma_f32_16x16x32_bf16 v[70:73], v[168:171], v[220:223], v[70:73]
	v_mfma_f32_16x16x32_bf16 v[66:69], v[176:179], v[220:223], v[66:69]
	s_setprio 0
	s_barrier
	s_add_i32 s51, s51, s35
	v_lshl_add_u64 v[142:143], s[26:27], 0, v[132:133]
	s_mov_b32 m0, s51
	ds_read_b128 v[180:183], v146 offset:16384
	ds_read_b128 v[196:199], v146 offset:17408
	ds_read_b128 v[200:203], v146 offset:18432
	ds_read_b128 v[204:207], v146 offset:19456
	ds_read_b128 v[208:211], v146 offset:20480
	ds_read_b128 v[212:215], v146 offset:21504
	ds_read_b128 v[216:219], v146 offset:22528
	ds_read_b128 v[220:223], v146 offset:23552
	global_load_lds_dwordx4 v[142:143], off
	s_add_i32 m0, s51, 0x2000
	s_add_u32 s82, s26, 0x80000
	v_lshl_add_u64 v[184:185], s[26:27], 0, v[136:137]
	s_addc_u32 s83, s27, 0
	s_add_i32 s51, s75, s35
	global_load_lds_dwordx4 v[184:185], off
	v_lshl_add_u64 v[224:225], s[82:83], 0, v[132:133]
	s_mov_b32 m0, s51
	v_lshl_add_u64 v[226:227], s[28:29], 0, v[134:135]
	global_load_lds_dwordx4 v[224:225], off
	v_lshl_add_u64 v[224:225], s[82:83], 0, v[136:137]
	s_add_i32 m0, s51, 0x2000
	s_nop 0
	global_load_lds_dwordx4 v[224:225], off
	v_lshl_add_u64 v[224:225], s[28:29], 0, v[130:131]
	s_mov_b32 m0, s46
	s_nop 0
	global_load_lds_dwordx4 v[224:225], off
	s_mov_b32 m0, s47
	s_nop 0
	global_load_lds_dwordx4 v[226:227], off
	s_waitcnt vmcnt(8)
	s_waitcnt lgkmcnt(0)
	s_barrier
	s_setprio 1
	s_waitcnt lgkmcnt(0)
	v_mfma_f32_16x16x32_bf16 v[62:65], v[148:151], v[180:183], v[62:65]
	v_mfma_f32_16x16x32_bf16 v[58:61], v[156:159], v[180:183], v[58:61]
	v_mfma_f32_16x16x32_bf16 v[50:53], v[148:151], v[200:203], v[50:53]
	v_mfma_f32_16x16x32_bf16 v[42:45], v[156:159], v[200:203], v[42:45]
	v_mfma_f32_16x16x32_bf16 v[34:37], v[148:151], v[208:211], v[34:37]
	v_mfma_f32_16x16x32_bf16 v[26:29], v[156:159], v[208:211], v[26:29]
	v_mfma_f32_16x16x32_bf16 v[18:21], v[148:151], v[216:219], v[18:21]
	v_mfma_f32_16x16x32_bf16 v[10:13], v[156:159], v[216:219], v[10:13]
	v_mfma_f32_16x16x32_bf16 v[62:65], v[152:155], v[196:199], v[62:65]
	v_mfma_f32_16x16x32_bf16 v[58:61], v[160:163], v[196:199], v[58:61]
	v_mfma_f32_16x16x32_bf16 v[50:53], v[152:155], v[204:207], v[50:53]
	v_mfma_f32_16x16x32_bf16 v[42:45], v[160:163], v[204:207], v[42:45]
	v_mfma_f32_16x16x32_bf16 v[34:37], v[152:155], v[212:215], v[34:37]
	v_mfma_f32_16x16x32_bf16 v[26:29], v[160:163], v[212:215], v[26:29]
	v_mfma_f32_16x16x32_bf16 v[18:21], v[152:155], v[220:223], v[18:21]
	v_mfma_f32_16x16x32_bf16 v[10:13], v[160:163], v[220:223], v[10:13]
	s_setprio 0
	s_setprio 1
	v_mfma_f32_16x16x32_bf16 v[54:57], v[164:167], v[180:183], v[54:57]
	v_mfma_f32_16x16x32_bf16 v[46:49], v[172:175], v[180:183], v[46:49]
	v_mfma_f32_16x16x32_bf16 v[38:41], v[164:167], v[200:203], v[38:41]
	v_mfma_f32_16x16x32_bf16 v[30:33], v[172:175], v[200:203], v[30:33]
	v_mfma_f32_16x16x32_bf16 v[22:25], v[164:167], v[208:211], v[22:25]
	v_mfma_f32_16x16x32_bf16 v[14:17], v[172:175], v[208:211], v[14:17]
	v_mfma_f32_16x16x32_bf16 v[6:9], v[164:167], v[216:219], v[6:9]
	v_mfma_f32_16x16x32_bf16 v[2:5], v[172:175], v[216:219], v[2:5]
	v_mfma_f32_16x16x32_bf16 v[54:57], v[168:171], v[196:199], v[54:57]
	v_mfma_f32_16x16x32_bf16 v[46:49], v[176:179], v[196:199], v[46:49]
	v_mfma_f32_16x16x32_bf16 v[38:41], v[168:171], v[204:207], v[38:41]
	v_mfma_f32_16x16x32_bf16 v[30:33], v[176:179], v[204:207], v[30:33]
	v_mfma_f32_16x16x32_bf16 v[22:25], v[168:171], v[212:215], v[22:25]
	v_mfma_f32_16x16x32_bf16 v[14:17], v[176:179], v[212:215], v[14:17]
	v_mfma_f32_16x16x32_bf16 v[6:9], v[168:171], v[220:223], v[6:9]
	v_mfma_f32_16x16x32_bf16 v[2:5], v[176:179], v[220:223], v[2:5]
	s_setprio 0
	s_barrier
; #define PG8_STAGE(bufoff, gbase, voff) do { _Pragma("unroll") for (int _i = 0; _i < 2; ++_i) \
;         __builtin_amdgcn_global_load_lds((const unsigned*)((const char*)(gbase) + (voff)[_i]), (PG8_LAS unsigned*)(lds + (bufoff) + ldsw + _i * 8192), 16, 0, 0); } while (0)
; #define PG8_LDA(dst, b, h) do { _Pragma("unroll") for (int m = 0; m < 4; ++m) _Pragma("unroll") for (int k = 0; k < 2; ++k) dst[m][k] = *(const PG8_LAS bf16x8*)(lds + PG8_SA(b, h) + aoff + m * 2048 + k * 1024); } while (0)
; #define PG8_LDB(dst, b, h) do { _Pragma("unroll") for (int n = 0; n < 2; ++n) _Pragma("unroll") for (int k = 0; k < 2; ++k) dst[n][k] = *(const PG8_LAS bf16x8*)(lds + PG8_SB(b, h) + boff + n * 2048 + k * 1024); } while (0)
; #define PG8_MMA(ai, bj, At, Bt) do { __builtin_amdgcn_s_setprio(1); _Pragma("unroll") for (int m = 0; m < 4; ++m) _Pragma("unroll") for (int n = 0; n < 2; ++n) _Pragma("unroll") for (int k = 0; k < 2; ++k) \
;         acc[ai][bj][m][n] = __builtin_amdgcn_mfma_f32_16x16x32_bf16(Bt[n][k], At[m][k], acc[ai][bj][m][n], 0, 0, 0); __builtin_amdgcn_s_setprio(0); } while (0)
; #define PG8_WAIT_V(n) asm volatile("s_waitcnt vmcnt(" #n ")" ::: "memory")
; #define PG8_WAIT_L(n) asm volatile("s_waitcnt lgkmcnt(" #n ")" ::: "memory")
; #define PG8_BAR __builtin_amdgcn_s_barrier()
; #define PG8_SCHED __builtin_amdgcn_sched_barrier(0)
; template <class Epi, class Sched, bool ALIGN_EPI = false, bool SP2 = false, bool ABLK = false, bool BBLK = false>
; __device__ __forceinline__ void gemm_phase(PG8_LAS unsigned char* lds, const Gemm g, const Sched& S, const Epi& E) {
;     ...
;             PG8_LDB(B0, 1, 0); PG8_LDB(B1, 1, 1); PG8_SCHED; PG8_LDA(At, 1, 0); PG8_STAGE(PG8_SA(0, 1), a2 + hstepA, voffA);
;             PG8_WAIT_V(8); PG8_WAIT_L(0); PG8_BAR; PG8_MMA(0, 0, At, B0); PG8_MMA(0, 1, At, B1); PG8_BAR; PG8_SCHED;
;             PG8_LDA(At, 1, 1); PG8_STAGE(PG8_SB(1, 0), b3, voffB); PG8_STAGE(PG8_SB(1, 1), b3 + hstepB, voffB); PG8_STAGE(PG8_SA(1, 0), a3, voffA);
	s_add_i32 s51, 0, 0x18000
	v_add_u32_e32 v147, s51, v145
	s_add_i32 s75, 0, 0x1c000
	ds_read_b128 v[148:151], v147
	ds_read_b128 v[152:155], v147 offset:1024
	ds_read_b128 v[156:159], v147 offset:2048
	ds_read_b128 v[160:163], v147 offset:3072
	v_add_u32_e32 v147, s75, v145
	ds_read_b128 v[164:167], v147
	ds_read_b128 v[168:171], v147 offset:1024
	ds_read_b128 v[172:175], v147 offset:2048
	ds_read_b128 v[176:179], v147 offset:3072
	s_add_u32 s28, s28, 0x80000
	s_addc_u32 s29, s29, 0
	s_mov_b32 m0, s53
	v_lshl_add_u64 v[228:229], s[28:29], 0, v[130:131]
	ds_read_b128 v[180:183], v146 offset:32768
	ds_read_b128 v[196:199], v146 offset:33792
	ds_read_b128 v[200:203], v146 offset:34816
	ds_read_b128 v[204:207], v146 offset:35840
	ds_read_b128 v[208:211], v146 offset:36864
	ds_read_b128 v[212:215], v146 offset:37888
	ds_read_b128 v[216:219], v146 offset:38912
	ds_read_b128 v[220:223], v146 offset:39936
	global_load_lds_dwordx4 v[228:229], off
	v_lshl_add_u64 v[228:229], s[28:29], 0, v[134:135]
	s_mov_b32 m0, s56
	s_nop 0
	global_load_lds_dwordx4 v[228:229], off
	s_waitcnt vmcnt(8)
	s_waitcnt lgkmcnt(0)
	s_barrier
	s_setprio 1
	s_waitcnt lgkmcnt(0)
	v_mfma_f32_16x16x32_bf16 v[126:129], v[148:151], v[180:183], v[126:129]
	v_mfma_f32_16x16x32_bf16 v[122:125], v[156:159], v[180:183], v[122:125]
	v_mfma_f32_16x16x32_bf16 v[114:117], v[148:151], v[200:203], v[114:117]
	v_mfma_f32_16x16x32_bf16 v[106:109], v[156:159], v[200:203], v[106:109]
	v_mfma_f32_16x16x32_bf16 v[98:101], v[148:151], v[208:211], v[98:101]
	v_mfma_f32_16x16x32_bf16 v[90:93], v[156:159], v[208:211], v[90:93]
	v_mfma_f32_16x16x32_bf16 v[82:85], v[148:151], v[216:219], v[82:85]
	v_mfma_f32_16x16x32_bf16 v[74:77], v[156:159], v[216:219], v[74:77]
	v_mfma_f32_16x16x32_bf16 v[126:129], v[152:155], v[196:199], v[126:129]
	v_mfma_f32_16x16x32_bf16 v[122:125], v[160:163], v[196:199], v[122:125]
	v_mfma_f32_16x16x32_bf16 v[114:117], v[152:155], v[204:207], v[114:117]
	v_mfma_f32_16x16x32_bf16 v[106:109], v[160:163], v[204:207], v[106:109]
	v_mfma_f32_16x16x32_bf16 v[98:101], v[152:155], v[212:215], v[98:101]
	v_mfma_f32_16x16x32_bf16 v[90:93], v[160:163], v[212:215], v[90:93]
	v_mfma_f32_16x16x32_bf16 v[82:85], v[152:155], v[220:223], v[82:85]
	v_mfma_f32_16x16x32_bf16 v[74:77], v[160:163], v[220:223], v[74:77]
	s_setprio 0
	s_setprio 1
	v_mfma_f32_16x16x32_bf16 v[118:121], v[164:167], v[180:183], v[118:121]
	v_mfma_f32_16x16x32_bf16 v[110:113], v[172:175], v[180:183], v[110:113]
	v_mfma_f32_16x16x32_bf16 v[102:105], v[164:167], v[200:203], v[102:105]
	v_mfma_f32_16x16x32_bf16 v[94:97], v[172:175], v[200:203], v[94:97]
	v_mfma_f32_16x16x32_bf16 v[86:89], v[164:167], v[208:211], v[86:89]
	v_mfma_f32_16x16x32_bf16 v[78:81], v[172:175], v[208:211], v[78:81]
	v_mfma_f32_16x16x32_bf16 v[70:73], v[164:167], v[216:219], v[70:73]
	v_mfma_f32_16x16x32_bf16 v[66:69], v[172:175], v[216:219], v[66:69]
	v_mfma_f32_16x16x32_bf16 v[118:121], v[168:171], v[196:199], v[118:121]
	v_mfma_f32_16x16x32_bf16 v[110:113], v[176:179], v[196:199], v[110:113]
	v_mfma_f32_16x16x32_bf16 v[102:105], v[168:171], v[204:207], v[102:105]
	v_mfma_f32_16x16x32_bf16 v[94:97], v[176:179], v[204:207], v[94:97]
	v_mfma_f32_16x16x32_bf16 v[86:89], v[168:171], v[212:215], v[86:89]
	v_mfma_f32_16x16x32_bf16 v[78:81], v[176:179], v[212:215], v[78:81]
	v_mfma_f32_16x16x32_bf16 v[70:73], v[168:171], v[220:223], v[70:73]
	v_mfma_f32_16x16x32_bf16 v[66:69], v[176:179], v[220:223], v[66:69]
	s_setprio 0
	s_barrier
	s_add_i32 s28, s51, s35
	v_lshl_add_u64 v[142:143], v[142:143], 0, s[62:63]
	s_mov_b32 m0, s28
	ds_read_b128 v[180:183], v146 offset:49152
	ds_read_b128 v[196:199], v146 offset:50176
	ds_read_b128 v[200:203], v146 offset:51200
	ds_read_b128 v[204:207], v146 offset:52224
	ds_read_b128 v[208:211], v146 offset:53248
	ds_read_b128 v[212:215], v146 offset:54272
	ds_read_b128 v[216:219], v146 offset:55296
	ds_read_b128 v[220:223], v146 offset:56320
	global_load_lds_dwordx4 v[142:143], off
	s_add_i32 m0, s28, 0x2000
	s_add_u32 s26, s26, 0x80080
	v_lshl_add_u64 v[142:143], v[184:185], 0, s[62:63]
	s_addc_u32 s27, s27, 0
	s_add_i32 s28, s75, s35
	global_load_lds_dwordx4 v[142:143], off
	v_lshl_add_u64 v[142:143], s[26:27], 0, v[132:133]
	s_mov_b32 m0, s28
	s_nop 0
	global_load_lds_dwordx4 v[142:143], off
	v_lshl_add_u64 v[142:143], s[26:27], 0, v[136:137]
	s_add_i32 m0, s28, 0x2000
	s_nop 0
	global_load_lds_dwordx4 v[142:143], off
	v_lshl_add_u64 v[142:143], v[224:225], 0, s[62:63]
	s_mov_b32 m0, s61
	s_nop 0
	global_load_lds_dwordx4 v[142:143], off
	v_lshl_add_u64 v[142:143], v[226:227], 0, s[62:63]
	s_mov_b32 m0, s65
	s_nop 0
	global_load_lds_dwordx4 v[142:143], off
	s_waitcnt vmcnt(8)
	s_waitcnt lgkmcnt(0)
	s_barrier
; #define PG8_WAIT_V(n) asm volatile("s_waitcnt vmcnt(" #n ")" ::: "memory")
;     __device__ __forceinline__ void operator()(const f32x4 (&acc)[2][2][4][2], const Unit& u, int wr, int wc, int fr_, int fq) const {
;         int fr = fr_; asm volatile("" : "+v"(fr));
;         bf16_t* ob = O0 + ((size_t)u.pn * L + u.pm * BM + wr * 64 + fr) * 512 + (wc >> 1) * 128 + type * 64 + (wc & 1) * 32 + 8 * fq;
; #pragma unroll
;         for (int ai = 0; ai < 2; ++ai)
; #pragma unroll
;             for (int m = 0; m < 4; ++m)
; #pragma unroll
; template <class Epi, class Sched, bool ALIGN_EPI = false, bool SP2 = false, bool ABLK = false, bool BBLK = false>
; __device__ __forceinline__ void gemm_phase(PG8_LAS unsigned char* lds, const Gemm g, const Sched& S, const Epi& E) {
;     ...
;             PG8_LDA(At, 1, 1); PG8_STAGE(PG8_SB(1, 0), b3, voffB); PG8_STAGE(PG8_SB(1, 1), b3 + hstepB, voffB); PG8_STAGE(PG8_SA(1, 0), a3, voffA);
;             PG8_WAIT_V(8); PG8_WAIT_L(0); PG8_BAR; PG8_MMA(1, 0, At, B0); PG8_MMA(1, 1, At, B1); PG8_BAR; PG8_SCHED;
;             } else {
;             PG8_LDB(B0, 0, 0); PG8_SCHED; PG8_LDA(At, 0, 0); PG8_STAGE(PG8_SA(1, 1), a1 + hstepA, voffA);
;             PG8_WAIT_L(8); PG8_BAR; PG8_WAIT_L(0); PG8_MMA(0, 0, At, B0); PG8_BAR; PG8_SCHED;
;             PG8_LDB(B1, 0, 1); PG8_STAGE(PG8_SB(0, 0), b2, voffB);
;             PG8_BAR; PG8_WAIT_L(0); PG8_MMA(0, 1, At, B1); PG8_BAR;
;             PG8_LDA(At, 0, 1); PG8_STAGE(PG8_SA(0, 0), a2, voffA);
;             PG8_BAR; PG8_WAIT_L(0); PG8_MMA(1, 0, At, B0); PG8_BAR; PG8_SCHED;
;             PG8_STAGE(PG8_SB(0, 1), b2 + hstepB, voffB);
;             PG8_WAIT_V(6); PG8_BAR; PG8_MMA(1, 1, At, B1); PG8_BAR;
;             PG8_LDB(B0, 1, 0); PG8_SCHED; PG8_LDA(At, 1, 0); PG8_STAGE(PG8_SA(0, 1), a2 + hstepA, voffA);
;             PG8_WAIT_L(8); PG8_BAR; PG8_WAIT_L(0); PG8_MMA(0, 0, At, B0); PG8_BAR; PG8_SCHED;
;             PG8_LDB(B1, 1, 1); PG8_STAGE(PG8_SB(1, 0), b3, voffB);
;             PG8_BAR; PG8_WAIT_L(0); PG8_MMA(0, 1, At, B1); PG8_BAR;
;             PG8_LDA(At, 1, 1); PG8_STAGE(PG8_SA(1, 0), a3, voffA);
;             PG8_BAR; PG8_WAIT_L(0); PG8_MMA(1, 0, At, B0); PG8_BAR; PG8_SCHED;
;             PG8_STAGE(PG8_SB(1, 1), b3 + hstepB, voffB);
;             PG8_WAIT_V(6); PG8_BAR; PG8_MMA(1, 1, At, B1); PG8_BAR;
;             }
;         }
;         if constexpr (ALIGN_EPI) { if (wr == 0) PG8_BAR; }
	s_setprio 1
	s_waitcnt lgkmcnt(0)
	v_mfma_f32_16x16x32_bf16 v[62:65], v[148:151], v[180:183], v[62:65]
	v_mfma_f32_16x16x32_bf16 v[58:61], v[156:159], v[180:183], v[58:61]
	v_mfma_f32_16x16x32_bf16 v[50:53], v[148:151], v[200:203], v[50:53]
	v_mfma_f32_16x16x32_bf16 v[42:45], v[156:159], v[200:203], v[42:45]
	v_mfma_f32_16x16x32_bf16 v[34:37], v[148:151], v[208:211], v[34:37]
	v_mfma_f32_16x16x32_bf16 v[26:29], v[156:159], v[208:211], v[26:29]
	v_mfma_f32_16x16x32_bf16 v[18:21], v[148:151], v[216:219], v[18:21]
	v_mfma_f32_16x16x32_bf16 v[10:13], v[156:159], v[216:219], v[10:13]
	v_mfma_f32_16x16x32_bf16 v[62:65], v[152:155], v[196:199], v[62:65]
	v_mfma_f32_16x16x32_bf16 v[58:61], v[160:163], v[196:199], v[58:61]
	v_mfma_f32_16x16x32_bf16 v[50:53], v[152:155], v[204:207], v[50:53]
	v_mfma_f32_16x16x32_bf16 v[42:45], v[160:163], v[204:207], v[42:45]
	v_mfma_f32_16x16x32_bf16 v[34:37], v[152:155], v[212:215], v[34:37]
	v_mfma_f32_16x16x32_bf16 v[26:29], v[160:163], v[212:215], v[26:29]
	v_mfma_f32_16x16x32_bf16 v[18:21], v[152:155], v[220:223], v[18:21]
	v_mfma_f32_16x16x32_bf16 v[10:13], v[160:163], v[220:223], v[10:13]
	s_setprio 0
	s_setprio 1
	v_mfma_f32_16x16x32_bf16 v[54:57], v[164:167], v[180:183], v[54:57]
	v_mfma_f32_16x16x32_bf16 v[46:49], v[172:175], v[180:183], v[46:49]
	v_mfma_f32_16x16x32_bf16 v[38:41], v[164:167], v[200:203], v[38:41]
	v_mfma_f32_16x16x32_bf16 v[30:33], v[172:175], v[200:203], v[30:33]
	v_mfma_f32_16x16x32_bf16 v[22:25], v[164:167], v[208:211], v[22:25]
	v_mfma_f32_16x16x32_bf16 v[14:17], v[172:175], v[208:211], v[14:17]
	v_mfma_f32_16x16x32_bf16 v[6:9], v[164:167], v[216:219], v[6:9]
	v_mfma_f32_16x16x32_bf16 v[2:5], v[172:175], v[216:219], v[2:5]
	v_mfma_f32_16x16x32_bf16 v[54:57], v[168:171], v[196:199], v[54:57]
	v_mfma_f32_16x16x32_bf16 v[46:49], v[176:179], v[196:199], v[46:49]
	v_mfma_f32_16x16x32_bf16 v[38:41], v[168:171], v[204:207], v[38:41]
	v_mfma_f32_16x16x32_bf16 v[30:33], v[176:179], v[204:207], v[30:33]
	v_mfma_f32_16x16x32_bf16 v[22:25], v[168:171], v[212:215], v[22:25]
	v_mfma_f32_16x16x32_bf16 v[14:17], v[176:179], v[212:215], v[14:17]
	v_mfma_f32_16x16x32_bf16 v[6:9], v[168:171], v[220:223], v[6:9]
	v_mfma_f32_16x16x32_bf16 v[2:5], v[176:179], v[220:223], v[2:5]
	s_setprio 0
	s_barrier
	s_add_i32 s81, s81, 2
	s_add_u32 s24, s24, 0x100
	s_addc_u32 s25, s25, 0
	s_add_u32 s23, s23, 0x100
	s_addc_u32 s73, s73, 0
	s_cmp_gt_u32 s81, 29
	s_cbranch_scc0 .LBB0_790
	s_and_b64 vcc, exec, s[8:9]
	s_cbranch_vccz .LBB0_793
	s_barrier
.LBB0_793:
	s_lshl_b32 s0, s0, 8
	s_ashr_i32 s23, s22, 31
	s_ashr_i32 s1, s0, 31
	v_mov_b32_e32 v142, v144
	s_add_u32 s0, s0, s60
	s_addc_u32 s1, s1, s68
	v_ashrrev_i32_e32 v143, 31, v142
	v_lshl_add_u64 v[142:143], s[0:1], 0, v[142:143]
	s_lshl_b64 s[0:1], s[22:23], 21
	s_add_u32 s0, s30, s0
	v_lshlrev_b64 v[142:143], 10, v[142:143]
	s_addc_u32 s1, s31, s1
	v_lshl_add_u64 v[142:143], s[0:1], 0, v[142:143]
	v_lshl_add_u64 v[142:143], v[142:143], 0, s[16:17]
	s_mov_b32 s11, s17
	v_lshl_add_u64 v[142:143], v[142:143], 0, s[10:11]
	v_lshl_add_u64 v[142:143], v[142:143], 0, v[186:187]
	v_pk_mul_f32 v[128:129], v[128:129], s[64:65] op_sel_hi:[1,0]
	v_pk_mul_f32 v[126:127], v[126:127], s[64:65] op_sel_hi:[1,0]
	v_pk_mul_f32 v[148:149], v[124:125], s[64:65] op_sel_hi:[1,0]
	v_pk_mul_f32 v[124:125], v[122:123], s[64:65] op_sel_hi:[1,0]
	v_cvt_pk_bf16_f32 v122, v126, v127
	v_cvt_pk_bf16_f32 v123, v128, v129
	v_pk_mul_f32 v[120:121], v[120:121], s[64:65] op_sel_hi:[1,0]
	v_cvt_pk_bf16_f32 v124, v124, v125
	v_cvt_pk_bf16_f32 v125, v148, v149
	global_store_dwordx4 v[142:143], v[122:125], off offset:128
	v_pk_mul_f32 v[118:119], v[118:119], s[64:65] op_sel_hi:[1,0]
	v_pk_mul_f32 v[104:105], v[104:105], s[64:65] op_sel_hi:[1,0]
	v_pk_mul_f32 v[122:123], v[112:113], s[64:65] op_sel_hi:[1,0]
	v_pk_mul_f32 v[112:113], v[110:111], s[64:65] op_sel_hi:[1,0]
	v_cvt_pk_bf16_f32 v110, v118, v119
	v_cvt_pk_bf16_f32 v111, v120, v121
	v_pk_mul_f32 v[102:103], v[102:103], s[64:65] op_sel_hi:[1,0]
	v_cvt_pk_bf16_f32 v112, v112, v113
	v_cvt_pk_bf16_f32 v113, v122, v123
	global_store_dwordx4 v[142:143], v[110:113], off offset:640
	v_pk_mul_f32 v[88:89], v[88:89], s[64:65] op_sel_hi:[1,0]
	v_pk_mul_f32 v[86:87], v[86:87], s[64:65] op_sel_hi:[1,0]
	v_pk_mul_f32 v[110:111], v[116:117], s[64:65] op_sel_hi:[1,0]
	v_pk_mul_f32 v[112:113], v[114:115], s[64:65] op_sel_hi:[1,0]
	v_pk_mul_f32 v[114:115], v[108:109], s[64:65] op_sel_hi:[1,0]
	v_pk_mul_f32 v[108:109], v[106:107], s[64:65] op_sel_hi:[1,0]
	v_cvt_pk_bf16_f32 v106, v112, v113
	v_cvt_pk_bf16_f32 v107, v110, v111
	v_add_co_u32_e32 v110, vcc, s87, v142
	v_cvt_pk_bf16_f32 v108, v108, v109
	v_cvt_pk_bf16_f32 v109, v114, v115
	s_mov_b32 s0, 0xc000
	s_nop 0
	v_addc_co_u32_e32 v111, vcc, 0, v143, vcc
	global_store_dwordx4 v[110:111], v[106:109], off offset:128
	v_pk_mul_f32 v[72:73], v[72:73], s[64:65] op_sel_hi:[1,0]
	v_pk_mul_f32 v[70:71], v[70:71], s[64:65] op_sel_hi:[1,0]
	v_pk_mul_f32 v[106:107], v[96:97], s[64:65] op_sel_hi:[1,0]
	v_pk_mul_f32 v[96:97], v[94:95], s[64:65] op_sel_hi:[1,0]
	v_cvt_pk_bf16_f32 v94, v102, v103
	v_cvt_pk_bf16_f32 v95, v104, v105
	v_pk_mul_f32 v[62:63], v[62:63], s[64:65] op_sel_hi:[1,0]
	v_cvt_pk_bf16_f32 v96, v96, v97
	v_cvt_pk_bf16_f32 v97, v106, v107
	global_store_dwordx4 v[110:111], v[94:97], off offset:640
	v_pk_mul_f32 v[64:65], v[64:65], s[64:65] op_sel_hi:[1,0]
	v_pk_mul_f32 v[56:57], v[56:57], s[64:65] op_sel_hi:[1,0]
	v_pk_mul_f32 v[94:95], v[100:101], s[64:65] op_sel_hi:[1,0]
; __device__ __forceinline__ u32x4 pack8(const f32x4 v0, const f32x4 v1) { u32x4 w; w.x = cvt_pk_bf16(v0[0], v0[1]); w.y = cvt_pk_bf16(v0[2], v0[3]); w.z = cvt_pk_bf16(v1[0], v1[1]); w.w = cvt_pk_bf16(v1[2], v1[3]); return w; }
; #define PG8_BAR __builtin_amdgcn_s_barrier()
;     __device__ __forceinline__ void operator()(const f32x4 (&acc)[2][2][4][2], const Unit& u, int wr, int wc, int fr_, int fq) const {
;     ...
;         bf16_t* ob = O0 + ((size_t)u.pn * L + u.pm * BM + wr * 64 + fr) * 512 + (wc >> 1) * 128 + type * 64 + (wc & 1) * 32 + 8 * fq;
; #pragma unroll
;         for (int ai = 0; ai < 2; ++ai)
; #pragma unroll
;             for (int m = 0; m < 4; ++m)
; #pragma unroll
;                 for (int bj = 0; bj < 2; ++bj) *(u32x4*)(ob + (size_t)(ai * HALF + m * 16) * 512 + bj * 256) = pack8(acc[ai][bj][m][0] * scale, acc[ai][bj][m][1] * scale);
; template <class Epi, class Sched, bool ALIGN_EPI = false, bool SP2 = false, bool ABLK = false, bool BBLK = false>
; __device__ __forceinline__ void gemm_phase(PG8_LAS unsigned char* lds, const Gemm g, const Sched& S, const Epi& E) {
;     ...
;         if (!has_next) break;
; #pragma unroll
;         for (int a = 0; a < 2; ++a)
; #pragma unroll
;             for (int b = 0; b < 2; ++b)
; #pragma unroll
;                 for (int m = 0; m < 4; ++m)
; #pragma unroll
;                     for (int n = 0; n < 2; ++n) acc[a][b][m][n] = (f32x4){0.f, 0.f, 0.f, 0.f};
;         cur = nxt; cA = nA; cB = nB; ++ui;
;         if constexpr (ALIGN_EPI) { if (wr == 1) PG8_BAR; }
	v_pk_mul_f32 v[96:97], v[98:99], s[64:65] op_sel_hi:[1,0]
	v_pk_mul_f32 v[98:99], v[92:93], s[64:65] op_sel_hi:[1,0]
	v_pk_mul_f32 v[92:93], v[90:91], s[64:65] op_sel_hi:[1,0]
	v_cvt_pk_bf16_f32 v90, v96, v97
	v_cvt_pk_bf16_f32 v91, v94, v95
	v_add_co_u32_e32 v94, vcc, s69, v142
	v_cvt_pk_bf16_f32 v92, v92, v93
	v_cvt_pk_bf16_f32 v93, v98, v99
	v_pk_mul_f32 v[54:55], v[54:55], s[64:65] op_sel_hi:[1,0]
	s_nop 0
	v_addc_co_u32_e32 v95, vcc, 0, v143, vcc
	global_store_dwordx4 v[94:95], v[90:93], off offset:128
	v_pk_mul_f32 v[40:41], v[40:41], s[64:65] op_sel_hi:[1,0]
	v_pk_mul_f32 v[38:39], v[38:39], s[64:65] op_sel_hi:[1,0]
	v_pk_mul_f32 v[90:91], v[80:81], s[64:65] op_sel_hi:[1,0]
	v_pk_mul_f32 v[80:81], v[78:79], s[64:65] op_sel_hi:[1,0]
	v_cvt_pk_bf16_f32 v78, v86, v87
	v_cvt_pk_bf16_f32 v79, v88, v89
	v_pk_mul_f32 v[24:25], v[24:25], s[64:65] op_sel_hi:[1,0]
	v_cvt_pk_bf16_f32 v80, v80, v81
	v_cvt_pk_bf16_f32 v81, v90, v91
	global_store_dwordx4 v[94:95], v[78:81], off offset:640
	v_pk_mul_f32 v[22:23], v[22:23], s[64:65] op_sel_hi:[1,0]
	v_pk_mul_f32 v[8:9], v[8:9], s[64:65] op_sel_hi:[1,0]
	v_pk_mul_f32 v[78:79], v[84:85], s[64:65] op_sel_hi:[1,0]
	v_pk_mul_f32 v[80:81], v[82:83], s[64:65] op_sel_hi:[1,0]
	v_pk_mul_f32 v[82:83], v[76:77], s[64:65] op_sel_hi:[1,0]
	v_pk_mul_f32 v[76:77], v[74:75], s[64:65] op_sel_hi:[1,0]
	v_cvt_pk_bf16_f32 v74, v80, v81
	v_cvt_pk_bf16_f32 v75, v78, v79
	v_add_co_u32_e32 v78, vcc, s0, v142
	v_cvt_pk_bf16_f32 v76, v76, v77
	v_cvt_pk_bf16_f32 v77, v82, v83
	s_mov_b32 s0, 0x24000
	s_nop 0
	v_addc_co_u32_e32 v79, vcc, 0, v143, vcc
	global_store_dwordx4 v[78:79], v[74:77], off offset:128
	v_pk_mul_f32 v[6:7], v[6:7], s[64:65] op_sel_hi:[1,0]
	s_nop 0
	v_pk_mul_f32 v[74:75], v[68:69], s[64:65] op_sel_hi:[1,0]
	v_pk_mul_f32 v[68:69], v[66:67], s[64:65] op_sel_hi:[1,0]
	v_cvt_pk_bf16_f32 v66, v70, v71
	v_cvt_pk_bf16_f32 v67, v72, v73
	s_nop 0
	v_cvt_pk_bf16_f32 v68, v68, v69
	v_cvt_pk_bf16_f32 v69, v74, v75
	global_store_dwordx4 v[78:79], v[66:69], off offset:640
	s_nop 1
	v_pk_mul_f32 v[66:67], v[60:61], s[64:65] op_sel_hi:[1,0]
	v_pk_mul_f32 v[60:61], v[58:59], s[64:65] op_sel_hi:[1,0]
	v_cvt_pk_bf16_f32 v58, v62, v63
	v_add_co_u32_e32 v62, vcc, s95, v142
	v_cvt_pk_bf16_f32 v59, v64, v65
	v_cvt_pk_bf16_f32 v60, v60, v61
	v_cvt_pk_bf16_f32 v61, v66, v67
	s_nop 1
	v_addc_co_u32_e32 v63, vcc, 0, v143, vcc
	global_store_dwordx4 v[62:63], v[58:61], off offset:128
	s_nop 1
	v_pk_mul_f32 v[58:59], v[48:49], s[64:65] op_sel_hi:[1,0]
	v_pk_mul_f32 v[48:49], v[46:47], s[64:65] op_sel_hi:[1,0]
	v_cvt_pk_bf16_f32 v46, v54, v55
	v_cvt_pk_bf16_f32 v47, v56, v57
	s_nop 0
	v_cvt_pk_bf16_f32 v48, v48, v49
	v_cvt_pk_bf16_f32 v49, v58, v59
	global_store_dwordx4 v[62:63], v[46:49], off offset:640
	s_nop 1
	v_pk_mul_f32 v[46:47], v[52:53], s[64:65] op_sel_hi:[1,0]
	v_pk_mul_f32 v[48:49], v[50:51], s[64:65] op_sel_hi:[1,0]
	v_pk_mul_f32 v[50:51], v[44:45], s[64:65] op_sel_hi:[1,0]
	v_pk_mul_f32 v[44:45], v[42:43], s[64:65] op_sel_hi:[1,0]
	v_cvt_pk_bf16_f32 v42, v48, v49
	v_cvt_pk_bf16_f32 v43, v46, v47
	v_add_co_u32_e32 v46, vcc, s0, v142
	v_cvt_pk_bf16_f32 v44, v44, v45
	v_cvt_pk_bf16_f32 v45, v50, v51
	s_mov_b32 s0, 0x28000
	s_nop 0
	v_addc_co_u32_e32 v47, vcc, 0, v143, vcc
	global_store_dwordx4 v[46:47], v[42:45], off offset:128
	s_nop 1
	v_pk_mul_f32 v[42:43], v[32:33], s[64:65] op_sel_hi:[1,0]
	v_pk_mul_f32 v[32:33], v[30:31], s[64:65] op_sel_hi:[1,0]
	v_cvt_pk_bf16_f32 v30, v38, v39
	v_cvt_pk_bf16_f32 v31, v40, v41
	s_nop 0
	v_cvt_pk_bf16_f32 v32, v32, v33
	v_cvt_pk_bf16_f32 v33, v42, v43
	global_store_dwordx4 v[46:47], v[30:33], off offset:640
	s_nop 1
	v_pk_mul_f32 v[30:31], v[36:37], s[64:65] op_sel_hi:[1,0]
	v_pk_mul_f32 v[32:33], v[34:35], s[64:65] op_sel_hi:[1,0]
	v_pk_mul_f32 v[34:35], v[28:29], s[64:65] op_sel_hi:[1,0]
	v_pk_mul_f32 v[28:29], v[26:27], s[64:65] op_sel_hi:[1,0]
	v_cvt_pk_bf16_f32 v26, v32, v33
	v_cvt_pk_bf16_f32 v27, v30, v31
	v_add_co_u32_e32 v30, vcc, s0, v142
	v_cvt_pk_bf16_f32 v28, v28, v29
	v_cvt_pk_bf16_f32 v29, v34, v35
	s_mov_b32 s0, 0x2c000
	s_nop 0
	v_addc_co_u32_e32 v31, vcc, 0, v143, vcc
	global_store_dwordx4 v[30:31], v[26:29], off offset:128
	s_nop 1
	v_pk_mul_f32 v[26:27], v[16:17], s[64:65] op_sel_hi:[1,0]
	v_pk_mul_f32 v[16:17], v[14:15], s[64:65] op_sel_hi:[1,0]
	v_cvt_pk_bf16_f32 v14, v22, v23
	v_cvt_pk_bf16_f32 v15, v24, v25
	s_nop 0
	v_cvt_pk_bf16_f32 v16, v16, v17
	v_cvt_pk_bf16_f32 v17, v26, v27
	global_store_dwordx4 v[30:31], v[14:17], off offset:640
	s_nop 1
	v_pk_mul_f32 v[14:15], v[20:21], s[64:65] op_sel_hi:[1,0]
	v_pk_mul_f32 v[16:17], v[18:19], s[64:65] op_sel_hi:[1,0]
	v_pk_mul_f32 v[18:19], v[12:13], s[64:65] op_sel_hi:[1,0]
	v_pk_mul_f32 v[12:13], v[10:11], s[64:65] op_sel_hi:[1,0]
	v_cvt_pk_bf16_f32 v10, v16, v17
	v_cvt_pk_bf16_f32 v11, v14, v15
	v_add_co_u32_e32 v14, vcc, s0, v142
	v_cvt_pk_bf16_f32 v12, v12, v13
	v_cvt_pk_bf16_f32 v13, v18, v19
	s_mov_b64 s[0:1], -1
	s_nop 0
	v_addc_co_u32_e32 v15, vcc, 0, v143, vcc
	global_store_dwordx4 v[14:15], v[10:13], off offset:128
	s_andn2_b64 vcc, exec, s[6:7]
	s_nop 0
	v_pk_mul_f32 v[10:11], v[4:5], s[64:65] op_sel_hi:[1,0]
	v_pk_mul_f32 v[4:5], v[2:3], s[64:65] op_sel_hi:[1,0]
	v_cvt_pk_bf16_f32 v2, v6, v7
	v_cvt_pk_bf16_f32 v3, v8, v9
	s_nop 0
	v_cvt_pk_bf16_f32 v4, v4, v5
	v_cvt_pk_bf16_f32 v5, v10, v11
	global_store_dwordx4 v[14:15], v[2:5], off offset:640
	s_cbranch_vccnz .LBB0_782
	s_andn2_b64 vcc, exec, s[4:5]
	s_cbranch_vccnz .LBB0_781
	s_branch .LBB0_781

; #define PG8_WAIT_V(n) asm volatile("s_waitcnt vmcnt(" #n ")" ::: "memory")
; template <class Epi, class Sched, bool ALIGN_EPI = false, bool SP2 = false, bool ABLK = false, bool BBLK = false>
; __device__ __forceinline__ void gemm_phase(PG8_LAS unsigned char* lds, const Gemm g, const Sched& S, const Epi& E) {
;     ...
;     const int tid = tid_, wid = __builtin_amdgcn_readfirstlane(tid >> 6), lane = tid & 63, wr = wid >> 2, wc = wid & 3, fr = lane & 15, fq = lane >> 4;
;     const int K = g.K, nt = K / BK, LDA = g.lda ? g.lda : K, LDB = g.ldb ? g.ldb : K;
;     unsigned voffA[2], voffB[2];
; #pragma unroll
;     for (int i = 0; i < 2; ++i) { int R, C; stage_rc(tid * 16 + i * 8192, R, C); const int Rb = Epi::PERM ? ((R & ~31) + perm32(R & 31)) : R;
;         voffA[i] = ABLK ? (unsigned)(R * BK + C) * 2u : (unsigned)(R * LDA + C) * 2u; voffB[i] = BBLK ? (unsigned)(Rb * BK + C) * 2u : (unsigned)(Rb * LDB + C) * 2u; }
;     const size_t kstep = (size_t)(BK * 2);
;     const size_t hstepa = (size_t)HALF * LDA * 2, hstepb = (size_t)HALF * LDB * 2;
;     const size_t kstepA = ABLK ? (size_t)BM * BK * 2 : kstep, hstepA = ABLK ? (size_t)HALF * BK * 2 : hstepa, tstepA = ABLK ? (size_t)nt * BM * BK * 2 : 2 * hstepa;
;     const size_t kstepB = BBLK ? (size_t)BM * BK * 2 : kstep, hstepB = BBLK ? (size_t)HALF * BK * 2 : hstepb, tstepB = BBLK ? (size_t)nt * BM * BK * 2 : 2 * hstepb;
;     const unsigned ldsw = (unsigned)wid * 1024u;
;     const int aoff = lds_byte(wr * 64 + fr, fq * 8), boff = lds_byte(wc * 32 + fr, fq * 8);
;     ...
;     Unit cur, nxt; int ui = 0;
;     if (!S.next(0, cur)) return;
;     f32x4 acc[2][2][4][2];
; #pragma unroll
;     for (int a = 0; a < 2; ++a)
; #pragma unroll
;         for (int b = 0; b < 2; ++b)
; #pragma unroll
;             for (int m = 0; m < 4; ++m)
; #pragma unroll
;                 for (int n = 0; n < 2; ++n) acc[a][b][m][n] = (f32x4){0.f, 0.f, 0.f, 0.f};
;     bf16x8 At[4][2], B0[2][2], B1[2][2];
;     const char* cA = (const char*)g.A + (size_t)cur.pm * tstepA; const char* cB = (const char*)g.Bt + (size_t)cur.pn * tstepB;
;     S.a_ready(cur);
;     if constexpr (SP2) {
;         PG8_STAGE(PG8_SB(0, 0), cB, voffB); PG8_STAGE(PG8_SB(0, 1), cB + hstepB, voffB); PG8_STAGE(PG8_SA(0, 0), cA, voffA); PG8_STAGE(PG8_SA(0, 1), cA + hstepA, voffA);
;         if (wr == 1) PG8_BAR;
;         PG8_WAIT_V(2); PG8_BAR;
.LBB0_1106:
	v_ashrrev_i32_e32 v3, 31, v6
	v_lshrrev_b32_e32 v3, 26, v3
	v_add_u32_e32 v3, v6, v3
	v_ashrrev_i32_e32 v7, 6, v3
	v_bfe_i32 v3, v6, 27, 1
	v_lshlrev_b32_e32 v2, 4, v6
	v_lshrrev_b32_e32 v3, 22, v3
	v_add_u32_e32 v3, v2, v3
	v_and_b32_e32 v3, 0xfffffc00, v3
	v_sub_u32_e32 v3, v2, v3
	v_lshrrev_b32_e32 v4, 4, v3
	v_bitop3_b32 v3, v4, v3, 32 bitop3:0x6c
	v_ashrrev_i32_e32 v5, 31, v3
	v_lshrrev_b32_e32 v5, 26, v5
	v_add_u32_e32 v5, v3, v5
	v_lshlrev_b32_e32 v4, 3, v7
	v_ashrrev_i32_e32 v8, 6, v5
	v_and_b32_e32 v5, 0xc0, v5
	v_and_b32_e32 v4, -16, v4
	v_sub_u32_e32 v3, v3, v5
	v_add_u32_e32 v4, v8, v4
	v_lshlrev_b32_e32 v9, 5, v7
	v_ashrrev_i16_sdwa v3, v232, sext(v3) dst_sel:DWORD dst_unused:UNUSED_PAD src0_sel:DWORD src1_sel:BYTE_0
	v_and_b32_e32 v10, 32, v9
	v_bfe_i32 v9, v3, 0, 16
	v_lshlrev_b32_e32 v3, 1, v4
	v_lshrrev_b32_e32 v5, 2, v4
	v_and_b32_e32 v11, 3, v8
	s_mov_b32 s0, 0x1ffffe0
	v_and_b32_e32 v3, 24, v3
	v_and_b32_e32 v5, 4, v5
	v_and_or_b32 v11, v4, s0, v11
	v_or3_b32 v3, v11, v5, v3
	v_add_lshl_u32 v5, v10, v9, 1
	v_add_u32_e32 v2, 0x2000, v2
	v_lshl_add_u32 v150, v3, 7, v5
	v_ashrrev_i32_e32 v3, 31, v2
	v_lshrrev_b32_e32 v3, 22, v3
	v_add_u32_e32 v3, v2, v3
	v_ashrrev_i32_e32 v10, 10, v3
	v_mul_i32_i24_e32 v3, 0x400, v10
	v_sub_u32_e32 v2, v2, v3
	v_lshrrev_b32_e32 v3, 4, v2
	v_bitop3_b32 v2, v3, v2, 32 bitop3:0x6c
	v_lshl_add_u32 v186, v4, 10, v5
	v_ashrrev_i32_e32 v4, 31, v2
	s_add_u32 s33, s60, 0x49e00000
	v_lshrrev_b32_e32 v4, 26, v4
	s_addc_u32 s44, s61, 0
	v_lshlrev_b32_e32 v3, 3, v10
	v_add_u32_e32 v4, v2, v4
	s_add_u32 s45, s60, 0xa100000
	v_and_b32_e32 v3, -16, v3
	v_ashrrev_i32_e32 v11, 6, v4
	s_addc_u32 s46, s61, 0
	v_add_u32_e32 v3, v11, v3
	v_and_b32_e32 v4, 0xc0, v4
	v_and_b32_e32 v13, 3, v11
	s_ashr_i32 s18, s6, 6
	s_ashr_i32 s31, s30, 31
	s_ashr_i32 s29, s28, 31
	s_ashr_i32 s7, s6, 8
	v_sub_u32_e32 v2, v2, v4
	v_and_or_b32 v13, v3, s0, v13
	s_lshl_b32 s47, s18, 10
	s_lshl_b64 s[12:13], s[30:31], 18
	s_lshl_b64 s[0:1], s[28:29], 18
	v_ashrrev_i16_sdwa v2, v232, sext(v2) dst_sel:DWORD dst_unused:UNUSED_PAD src0_sel:DWORD src1_sel:BYTE_0
	s_add_u32 s0, s45, s0
	v_lshlrev_b32_e32 v5, 5, v10
	v_bfe_i32 v12, v2, 0, 16
	v_lshlrev_b32_e32 v2, 1, v3
	v_lshrrev_b32_e32 v4, 2, v3
	s_addc_u32 s1, s46, s1
	s_add_i32 s29, s47, 0
	v_and_b32_e32 v5, 32, v5
	v_and_b32_e32 v2, 24, v2
	v_and_b32_e32 v4, 4, v4
	s_add_i32 m0, s29, 0x10000
	v_or3_b32 v2, v13, v4, v2
	v_add_lshl_u32 v4, v5, v12, 1
	global_load_lds_dwordx4 v150, s[0:1]
	s_add_i32 m0, s29, 0x12000
	v_lshl_add_u32 v154, v2, 7, v4
	s_add_u32 s14, s0, 0x4000
	global_load_lds_dwordx4 v154, s[0:1]
	s_addc_u32 s15, s1, 0
	s_add_i32 m0, s29, 0x14000
	v_lshl_add_u32 v152, v3, 10, v4
	global_load_lds_dwordx4 v150, s[14:15]
	s_add_i32 m0, s29, 0x16000
	s_add_u32 s34, s33, s12
	s_addc_u32 s35, s44, s13
	s_add_i32 s65, s29, 0x2000
	global_load_lds_dwordx4 v154, s[14:15]
	s_mov_b32 m0, s29
	s_add_u32 s12, s34, 0x20000
	global_load_lds_dwordx4 v186, s[34:35]
	s_mov_b32 m0, s65
	s_addc_u32 s13, s35, 0
	s_add_i32 s68, s29, 0x4000
	global_load_lds_dwordx4 v152, s[34:35]
	s_mov_b32 m0, s68
	s_add_i32 s72, s29, 0x6000
	global_load_lds_dwordx4 v186, s[12:13]
	s_mov_b32 m0, s72
	v_mov_b32_e32 v153, v187
	global_load_lds_dwordx4 v152, s[12:13]
	s_cmp_eq_u32 s7, 1
	v_lshl_add_u64 v[2:3], s[34:35], 0, v[186:187]
	s_cselect_b64 s[12:13], -1, 0
	s_cmp_lg_u32 s7, 1
	v_lshl_add_u64 v[4:5], s[34:35], 0, v[152:153]
	s_cbranch_scc1 .LBB0_1108
.LBB0_1108:
	v_lshrrev_b32_e32 v13, 1, v6
	v_and_b32_e32 v13, 24, v13
	s_add_u32 s14, s60, 0x2ca00000
	v_and_b32_e32 v162, 15, v6
	v_lshlrev_b32_e32 v14, 1, v13
	v_lshlrev_b32_e32 v6, 2, v6
	s_addc_u32 s15, s61, 0
	s_lshl_b32 s73, s7, 6
	v_lshl_or_b32 v14, v162, 6, v14
	s_lshl_b32 s7, s7, 13
	v_and_b32_e32 v6, 32, v6
	v_bitop3_b32 v16, v14, s7, v6 bitop3:0xde
	s_lshl_b32 s7, s18, 5
	s_and_b32 s7, s7, 0x60
	s_lshl_b32 s18, s7, 7
	v_bitop3_b32 v163, v14, s18, v6 bitop3:0xde
	s_add_u32 s18, s0, 0x8000
	v_mov_b32_e32 v151, v187
	s_addc_u32 s19, s1, 0
	v_mov_b32_e32 v155, v187
	s_add_i32 m0, s29, 0x18000
	v_lshl_add_u64 v[14:15], s[18:19], 0, v[150:151]
	s_waitcnt vmcnt(2)
	s_barrier
	global_load_lds_dwordx4 v[14:15], off
	v_lshl_add_u64 v[14:15], s[18:19], 0, v[154:155]
	s_add_i32 m0, s29, 0x1a000
	s_add_i32 s86, s29, 0x8000
	s_add_i32 s88, s29, 0xa000
	global_load_lds_dwordx4 v[14:15], off
	v_lshl_add_u64 v[2:3], v[2:3], 0, s[62:63]
	s_mov_b32 m0, s86
	s_add_u32 s18, s0, 0xc000
	global_load_lds_dwordx4 v[2:3], off
	v_lshl_add_u64 v[2:3], v[4:5], 0, s[62:63]
	s_mov_b32 m0, s88
	s_addc_u32 s19, s1, 0
	global_load_lds_dwordx4 v[2:3], off
	s_add_i32 m0, s29, 0x1c000
	v_lshl_add_u64 v[2:3], s[18:19], 0, v[150:151]
	global_load_lds_dwordx4 v[2:3], off
	v_lshl_add_u64 v[2:3], s[18:19], 0, v[154:155]
	s_add_i32 m0, s29, 0x1e000
	s_cmpk_lt_u32 s6, 0x100
	global_load_lds_dwordx4 v[2:3], off
	v_lshlrev_b32_e32 v2, 13, v7
	v_and_b32_e32 v2, 0xffffc000, v2
	v_lshl_add_u32 v2, v8, 10, v2
	v_and_b32_e32 v3, 1, v7
	v_lshl_or_b32 v2, v3, 6, v2
	v_lshl_add_u32 v156, v9, 1, v2
	v_lshlrev_b32_e32 v2, 13, v10
	v_and_b32_e32 v2, 0xffffc000, v2
	s_waitcnt vmcnt(6)
	v_lshl_add_u32 v2, v11, 10, v2
	v_and_b32_e32 v3, 1, v10
	v_lshl_or_b32 v2, v3, 6, v2
	s_cselect_b64 s[18:19], -1, 0
	s_ashr_i32 s89, s73, 31
	v_or_b32_e32 v164, s7, v13
	v_mov_b32_e32 v157, v187
	v_lshl_add_u32 v158, v12, 1, v2
	v_mov_b32_e32 v159, v187
	s_mov_b32 s21, 0
	v_add_u32_e32 v165, 0, v16
	s_barrier
	s_branch .LBB0_1111

; #define PG8_STAGE(bufoff, gbase, voff) do { _Pragma("unroll") for (int _i = 0; _i < 2; ++_i) \
;         __builtin_amdgcn_global_load_lds((const unsigned*)((const char*)(gbase) + (voff)[_i]), (PG8_LAS unsigned*)(lds + (bufoff) + ldsw + _i * 8192), 16, 0, 0); } while (0)
; #define PG8_LDA(dst, b, h) do { _Pragma("unroll") for (int m = 0; m < 4; ++m) _Pragma("unroll") for (int k = 0; k < 2; ++k) dst[m][k] = *(const PG8_LAS bf16x8*)(lds + PG8_SA(b, h) + aoff + m * 2048 + k * 1024); } while (0)
; #define PG8_LDB(dst, b, h) do { _Pragma("unroll") for (int n = 0; n < 2; ++n) _Pragma("unroll") for (int k = 0; k < 2; ++k) dst[n][k] = *(const PG8_LAS bf16x8*)(lds + PG8_SB(b, h) + boff + n * 2048 + k * 1024); } while (0)
; #define PG8_WAIT_V(n) asm volatile("s_waitcnt vmcnt(" #n ")" ::: "memory")
; #define PG8_BAR __builtin_amdgcn_s_barrier()
; template <class Epi, class Sched, bool ALIGN_EPI = false, bool SP2 = false, bool ABLK = false, bool BBLK = false>
; __device__ __forceinline__ void gemm_phase(PG8_LAS unsigned char* lds, const Gemm g, const Sched& S, const Epi& E) {
;     ...
;         const bool has_next = S.next(ui + 1, nxt);
;         const char* nA = has_next ? (const char*)g.A + (size_t)nxt.pm * tstepA : cA; const char* nB = has_next ? (const char*)g.Bt + (size_t)nxt.pn * tstepB : cB;
;         for (int t = 0; t < nt; t += 2) {
;             const bool last = (t == nt - 2);
;             const char* a1 = cA + (size_t)(t + 1) * kstepA;
;             const char* a2 = last ? nA : cA + (size_t)(t + 2) * kstepA; const char* b2 = last ? nB : cB + (size_t)(t + 2) * kstepB;
;             const char* a3 = a2 + kstepA; const char* b3 = b2 + kstepB;
;             if (last && has_next) S.a_ready(nxt);
;             if constexpr (SP2) {
;             PG8_LDB(B0, 0, 0); PG8_LDB(B1, 0, 1); PG8_SCHED; PG8_LDA(At, 0, 0); PG8_STAGE(PG8_SA(1, 1), a1 + hstepA, voffA);
;             PG8_WAIT_V(8); PG8_WAIT_L(0); PG8_BAR; PG8_MMA(0, 0, At, B0); PG8_MMA(0, 1, At, B1); PG8_BAR; PG8_SCHED;
;     ...
;         for (int a = 0; a < 2; ++a)
; #pragma unroll
;             for (int b = 0; b < 2; ++b)
; #pragma unroll
;                 for (int m = 0; m < 4; ++m)
; #pragma unroll
;                     for (int n = 0; n < 2; ++n) acc[a][b][m][n] = (f32x4){0.f, 0.f, 0.f, 0.f};
;         cur = nxt; cA = nA; cB = nB; ++ui;
;         if constexpr (ALIGN_EPI) { if (wr == 1) PG8_BAR; }
.LBB0_1116:
	s_ashr_i32 s23, s22, 31
	s_lshl_b64 s[24:25], s[22:23], 18
	s_add_u32 s24, s33, s24
	s_addc_u32 s25, s44, s25
	s_and_b64 s[26:27], s[6:7], exec
	s_cselect_b32 s23, s25, s35
	s_cselect_b32 s31, s24, s34
	s_ashr_i32 s21, s20, 31
	s_lshl_b64 s[26:27], s[20:21], 18
	s_add_u32 s26, s45, s26
	s_addc_u32 s27, s46, s27
	s_and_b64 s[36:37], s[6:7], exec
	s_cselect_b32 s21, s27, s1
	s_cselect_b32 s91, s26, s0
	s_add_u32 s92, s0, 0x10000
	s_addc_u32 s93, s1, 0
	s_add_u32 s0, s34, 0x20080
	v_mov_b32_e32 v2, 0
	s_addc_u32 s1, s35, 0
	s_mov_b32 s94, -2
	v_mov_b32_e32 v3, v2
	v_mov_b32_e32 v4, v2
	v_mov_b32_e32 v5, v2
	v_mov_b32_e32 v6, v2
	v_mov_b32_e32 v7, v2
	v_mov_b32_e32 v8, v2
	v_mov_b32_e32 v9, v2
	v_mov_b32_e32 v18, v2
	v_mov_b32_e32 v19, v2
	v_mov_b32_e32 v20, v2
	v_mov_b32_e32 v21, v2
	v_mov_b32_e32 v22, v2
	v_mov_b32_e32 v23, v2
	v_mov_b32_e32 v24, v2
	v_mov_b32_e32 v25, v2
	v_mov_b32_e32 v34, v2
	v_mov_b32_e32 v35, v2
	v_mov_b32_e32 v36, v2
	v_mov_b32_e32 v37, v2
	v_mov_b32_e32 v38, v2
	v_mov_b32_e32 v39, v2
	v_mov_b32_e32 v40, v2
	v_mov_b32_e32 v41, v2
	v_mov_b32_e32 v50, v2
	v_mov_b32_e32 v51, v2
	v_mov_b32_e32 v52, v2
	v_mov_b32_e32 v53, v2
	v_mov_b32_e32 v54, v2
	v_mov_b32_e32 v55, v2
	v_mov_b32_e32 v56, v2
	v_mov_b32_e32 v57, v2
	v_mov_b32_e32 v10, v2
	v_mov_b32_e32 v11, v2
	v_mov_b32_e32 v12, v2
	v_mov_b32_e32 v13, v2
	v_mov_b32_e32 v14, v2
	v_mov_b32_e32 v15, v2
	v_mov_b32_e32 v16, v2
	v_mov_b32_e32 v17, v2
	v_mov_b32_e32 v26, v2
	v_mov_b32_e32 v27, v2
	v_mov_b32_e32 v28, v2
	v_mov_b32_e32 v29, v2
	v_mov_b32_e32 v30, v2
	v_mov_b32_e32 v31, v2
	v_mov_b32_e32 v32, v2
	v_mov_b32_e32 v33, v2
	v_mov_b32_e32 v42, v2
	v_mov_b32_e32 v43, v2
	v_mov_b32_e32 v44, v2
	v_mov_b32_e32 v45, v2
	v_mov_b32_e32 v46, v2
	v_mov_b32_e32 v47, v2
	v_mov_b32_e32 v48, v2
	v_mov_b32_e32 v49, v2
	v_mov_b32_e32 v58, v2
	v_mov_b32_e32 v59, v2
	v_mov_b32_e32 v60, v2
	v_mov_b32_e32 v61, v2
	v_mov_b32_e32 v62, v2
	v_mov_b32_e32 v63, v2
	v_mov_b32_e32 v64, v2
	v_mov_b32_e32 v65, v2
	v_mov_b32_e32 v66, v2
	v_mov_b32_e32 v67, v2
	v_mov_b32_e32 v68, v2
	v_mov_b32_e32 v69, v2
	v_mov_b32_e32 v70, v2
	v_mov_b32_e32 v71, v2
	v_mov_b32_e32 v72, v2
	v_mov_b32_e32 v73, v2
	v_mov_b32_e32 v82, v2
	v_mov_b32_e32 v83, v2
	v_mov_b32_e32 v84, v2
	v_mov_b32_e32 v85, v2
	v_mov_b32_e32 v86, v2
	v_mov_b32_e32 v87, v2
	v_mov_b32_e32 v88, v2
	v_mov_b32_e32 v89, v2
	v_mov_b32_e32 v98, v2
	v_mov_b32_e32 v99, v2
	v_mov_b32_e32 v100, v2
	v_mov_b32_e32 v101, v2
	v_mov_b32_e32 v102, v2
	v_mov_b32_e32 v103, v2
	v_mov_b32_e32 v104, v2
	v_mov_b32_e32 v105, v2
	v_mov_b32_e32 v106, v2
	v_mov_b32_e32 v107, v2
	v_mov_b32_e32 v108, v2
	v_mov_b32_e32 v109, v2
	v_mov_b32_e32 v110, v2
	v_mov_b32_e32 v111, v2
	v_mov_b32_e32 v112, v2
	v_mov_b32_e32 v113, v2
	v_mov_b32_e32 v74, v2
	v_mov_b32_e32 v75, v2
	v_mov_b32_e32 v76, v2
	v_mov_b32_e32 v77, v2
	v_mov_b32_e32 v78, v2
	v_mov_b32_e32 v79, v2
	v_mov_b32_e32 v80, v2
	v_mov_b32_e32 v81, v2
	v_mov_b32_e32 v90, v2
	v_mov_b32_e32 v91, v2
	v_mov_b32_e32 v92, v2
	v_mov_b32_e32 v93, v2
	v_mov_b32_e32 v94, v2
	v_mov_b32_e32 v95, v2
	v_mov_b32_e32 v96, v2
	v_mov_b32_e32 v97, v2
	v_mov_b32_e32 v114, v2
	v_mov_b32_e32 v115, v2
	v_mov_b32_e32 v116, v2
	v_mov_b32_e32 v117, v2
	v_mov_b32_e32 v118, v2
	v_mov_b32_e32 v119, v2
	v_mov_b32_e32 v120, v2
	v_mov_b32_e32 v121, v2
	v_mov_b32_e32 v122, v2
	v_mov_b32_e32 v123, v2
	v_mov_b32_e32 v124, v2
	v_mov_b32_e32 v125, v2
	v_mov_b32_e32 v126, v2
	v_mov_b32_e32 v127, v2
	v_mov_b32_e32 v128, v2
	v_mov_b32_e32 v129, v2
	s_and_b64 vcc, exec, s[18:19]
	s_cbranch_vccnz .Lrb_m1
	s_barrier
.Lrb_m1:
.LBB0_1117:
	s_add_u32 s34, s0, 0xfffe0080
	s_addc_u32 s35, s1, -1
	s_add_i32 s52, 0, 0x10000
	s_cmp_eq_u32 s94, 4
	s_cselect_b32 s37, s23, s35
	s_cselect_b32 s36, s31, s34
	s_cselect_b32 s35, s21, s93
	s_cselect_b32 s34, s91, s92
	s_add_i32 s75, 0, 0x14000
	v_add_u32_e32 v142, s52, v163
	v_add_u32_e32 v160, s75, v163
	ds_read_b128 v[130:133], v142
	ds_read_b128 v[134:137], v142 offset:1024
	ds_read_b128 v[138:141], v142 offset:2048
	ds_read_b128 v[142:145], v142 offset:3072
	ds_read_b128 v[146:149], v160
	ds_read_b128 v[166:169], v160 offset:1024
	ds_read_b128 v[170:173], v160 offset:2048
	ds_read_b128 v[174:177], v160 offset:3072
	v_lshl_add_u64 v[160:161], s[0:1], 0, v[156:157]
	s_add_i32 m0, s29, 0xc000
	ds_read_b128 v[178:181], v165
	ds_read_b128 v[182:185], v165 offset:1024
	ds_read_b128 v[196:199], v165 offset:2048
	ds_read_b128 v[200:203], v165 offset:3072
	ds_read_b128 v[204:207], v165 offset:4096
	ds_read_b128 v[208:211], v165 offset:5120
	ds_read_b128 v[212:215], v165 offset:6144
	ds_read_b128 v[216:219], v165 offset:7168
	global_load_lds_dwordx4 v[160:161], off
	v_lshl_add_u64 v[160:161], s[0:1], 0, v[158:159]
	s_add_i32 m0, s29, 0xe000
	s_nop 0
	global_load_lds_dwordx4 v[160:161], off
	s_waitcnt vmcnt(8)
	s_waitcnt lgkmcnt(0)
	s_barrier
; #define PG8_STAGE(bufoff, gbase, voff) do { _Pragma("unroll") for (int _i = 0; _i < 2; ++_i) \
;         __builtin_amdgcn_global_load_lds((const unsigned*)((const char*)(gbase) + (voff)[_i]), (PG8_LAS unsigned*)(lds + (bufoff) + ldsw + _i * 8192), 16, 0, 0); } while (0)
; #define PG8_LDA(dst, b, h) do { _Pragma("unroll") for (int m = 0; m < 4; ++m) _Pragma("unroll") for (int k = 0; k < 2; ++k) dst[m][k] = *(const PG8_LAS bf16x8*)(lds + PG8_SA(b, h) + aoff + m * 2048 + k * 1024); } while (0)
; #define PG8_LDB(dst, b, h) do { _Pragma("unroll") for (int n = 0; n < 2; ++n) _Pragma("unroll") for (int k = 0; k < 2; ++k) dst[n][k] = *(const PG8_LAS bf16x8*)(lds + PG8_SB(b, h) + boff + n * 2048 + k * 1024); } while (0)
; #define PG8_MMA(ai, bj, At, Bt) do { __builtin_amdgcn_s_setprio(1); _Pragma("unroll") for (int m = 0; m < 4; ++m) _Pragma("unroll") for (int n = 0; n < 2; ++n) _Pragma("unroll") for (int k = 0; k < 2; ++k) \
;         acc[ai][bj][m][n] = __builtin_amdgcn_mfma_f32_16x16x32_bf16(Bt[n][k], At[m][k], acc[ai][bj][m][n], 0, 0, 0); __builtin_amdgcn_s_setprio(0); } while (0)
; #define PG8_WAIT_V(n) asm volatile("s_waitcnt vmcnt(" #n ")" ::: "memory")
; #define PG8_WAIT_L(n) asm volatile("s_waitcnt lgkmcnt(" #n ")" ::: "memory")
; #define PG8_BAR __builtin_amdgcn_s_barrier()
; #define PG8_SCHED __builtin_amdgcn_sched_barrier(0)
; template <class Epi, class Sched, bool ALIGN_EPI = false, bool SP2 = false, bool ABLK = false, bool BBLK = false>
; __device__ __forceinline__ void gemm_phase(PG8_LAS unsigned char* lds, const Gemm g, const Sched& S, const Epi& E) {
;     ...
;             PG8_LDB(B0, 0, 0); PG8_LDB(B1, 0, 1); PG8_SCHED; PG8_LDA(At, 0, 0); PG8_STAGE(PG8_SA(1, 1), a1 + hstepA, voffA);
;             PG8_WAIT_V(8); PG8_WAIT_L(0); PG8_BAR; PG8_MMA(0, 0, At, B0); PG8_MMA(0, 1, At, B1); PG8_BAR; PG8_SCHED;
;             PG8_LDA(At, 0, 1); PG8_STAGE(PG8_SB(0, 0), b2, voffB); PG8_STAGE(PG8_SB(0, 1), b2 + hstepB, voffB); PG8_STAGE(PG8_SA(0, 0), a2, voffA);
;             PG8_WAIT_V(8); PG8_WAIT_L(0); PG8_BAR; PG8_MMA(1, 0, At, B0); PG8_MMA(1, 1, At, B1); PG8_BAR; PG8_SCHED;
	s_setprio 1
	s_waitcnt lgkmcnt(0)
	v_mfma_f32_16x16x32_bf16 v[126:129], v[130:133], v[178:181], v[126:129]
	v_mfma_f32_16x16x32_bf16 v[122:125], v[138:141], v[178:181], v[122:125]
	v_mfma_f32_16x16x32_bf16 v[118:121], v[130:133], v[196:199], v[118:121]
	v_mfma_f32_16x16x32_bf16 v[114:117], v[138:141], v[196:199], v[114:117]
	v_mfma_f32_16x16x32_bf16 v[94:97], v[130:133], v[204:207], v[94:97]
	v_mfma_f32_16x16x32_bf16 v[90:93], v[138:141], v[204:207], v[90:93]
	v_mfma_f32_16x16x32_bf16 v[78:81], v[130:133], v[212:215], v[78:81]
	v_mfma_f32_16x16x32_bf16 v[74:77], v[138:141], v[212:215], v[74:77]
	v_mfma_f32_16x16x32_bf16 v[126:129], v[134:137], v[182:185], v[126:129]
	v_mfma_f32_16x16x32_bf16 v[122:125], v[142:145], v[182:185], v[122:125]
	v_mfma_f32_16x16x32_bf16 v[118:121], v[134:137], v[200:203], v[118:121]
	v_mfma_f32_16x16x32_bf16 v[114:117], v[142:145], v[200:203], v[114:117]
	v_mfma_f32_16x16x32_bf16 v[94:97], v[134:137], v[208:211], v[94:97]
	v_mfma_f32_16x16x32_bf16 v[90:93], v[142:145], v[208:211], v[90:93]
	v_mfma_f32_16x16x32_bf16 v[78:81], v[134:137], v[216:219], v[78:81]
	v_mfma_f32_16x16x32_bf16 v[74:77], v[142:145], v[216:219], v[74:77]
	s_setprio 0
	s_setprio 1
	v_mfma_f32_16x16x32_bf16 v[110:113], v[146:149], v[178:181], v[110:113]
	v_mfma_f32_16x16x32_bf16 v[106:109], v[170:173], v[178:181], v[106:109]
	v_mfma_f32_16x16x32_bf16 v[102:105], v[146:149], v[196:199], v[102:105]
	v_mfma_f32_16x16x32_bf16 v[98:101], v[170:173], v[196:199], v[98:101]
	v_mfma_f32_16x16x32_bf16 v[86:89], v[146:149], v[204:207], v[86:89]
	v_mfma_f32_16x16x32_bf16 v[82:85], v[170:173], v[204:207], v[82:85]
	v_mfma_f32_16x16x32_bf16 v[70:73], v[146:149], v[212:215], v[70:73]
	v_mfma_f32_16x16x32_bf16 v[66:69], v[170:173], v[212:215], v[66:69]
	v_mfma_f32_16x16x32_bf16 v[110:113], v[166:169], v[182:185], v[110:113]
	v_mfma_f32_16x16x32_bf16 v[106:109], v[174:177], v[182:185], v[106:109]
	v_mfma_f32_16x16x32_bf16 v[102:105], v[166:169], v[200:203], v[102:105]
	v_mfma_f32_16x16x32_bf16 v[98:101], v[174:177], v[200:203], v[98:101]
	v_mfma_f32_16x16x32_bf16 v[86:89], v[166:169], v[208:211], v[86:89]
	v_mfma_f32_16x16x32_bf16 v[82:85], v[174:177], v[208:211], v[82:85]
	v_mfma_f32_16x16x32_bf16 v[70:73], v[166:169], v[216:219], v[70:73]
	v_mfma_f32_16x16x32_bf16 v[66:69], v[174:177], v[216:219], v[66:69]
	s_setprio 0
	s_barrier
	s_add_i32 s52, s52, s47
	v_lshl_add_u64 v[160:161], s[34:35], 0, v[150:151]
	s_mov_b32 m0, s52
	ds_read_b128 v[178:181], v165 offset:16384
	ds_read_b128 v[182:185], v165 offset:17408
	ds_read_b128 v[196:199], v165 offset:18432
	ds_read_b128 v[200:203], v165 offset:19456
	ds_read_b128 v[204:207], v165 offset:20480
	ds_read_b128 v[208:211], v165 offset:21504
	ds_read_b128 v[212:215], v165 offset:22528
	ds_read_b128 v[216:219], v165 offset:23552
	global_load_lds_dwordx4 v[160:161], off
	s_add_i32 m0, s52, 0x2000
	s_add_u32 s96, s34, 0x4000
	v_lshl_add_u64 v[160:161], s[34:35], 0, v[154:155]
	s_addc_u32 s97, s35, 0
	s_add_i32 s52, s75, s47
	global_load_lds_dwordx4 v[160:161], off
	v_lshl_add_u64 v[160:161], s[96:97], 0, v[150:151]
	s_mov_b32 m0, s52
	v_lshl_add_u64 v[188:189], s[36:37], 0, v[152:153]
	global_load_lds_dwordx4 v[160:161], off
	v_lshl_add_u64 v[160:161], s[96:97], 0, v[154:155]
	s_add_i32 m0, s52, 0x2000
	s_nop 0
	global_load_lds_dwordx4 v[160:161], off
	v_lshl_add_u64 v[160:161], s[36:37], 0, v[186:187]
	s_mov_b32 m0, s29
	s_nop 0
	global_load_lds_dwordx4 v[160:161], off
	s_mov_b32 m0, s65
	s_nop 0
	global_load_lds_dwordx4 v[188:189], off
	s_waitcnt vmcnt(8)
	s_waitcnt lgkmcnt(0)
	s_barrier
	s_setprio 1
	s_waitcnt lgkmcnt(0)
	v_mfma_f32_16x16x32_bf16 v[62:65], v[130:133], v[178:181], v[62:65]
	v_mfma_f32_16x16x32_bf16 v[58:61], v[138:141], v[178:181], v[58:61]
	v_mfma_f32_16x16x32_bf16 v[46:49], v[130:133], v[196:199], v[46:49]
	v_mfma_f32_16x16x32_bf16 v[42:45], v[138:141], v[196:199], v[42:45]
	v_mfma_f32_16x16x32_bf16 v[30:33], v[130:133], v[204:207], v[30:33]
	v_mfma_f32_16x16x32_bf16 v[26:29], v[138:141], v[204:207], v[26:29]
	v_mfma_f32_16x16x32_bf16 v[14:17], v[130:133], v[212:215], v[14:17]
	v_mfma_f32_16x16x32_bf16 v[10:13], v[138:141], v[212:215], v[10:13]
	v_mfma_f32_16x16x32_bf16 v[62:65], v[134:137], v[182:185], v[62:65]
	v_mfma_f32_16x16x32_bf16 v[58:61], v[142:145], v[182:185], v[58:61]
	v_mfma_f32_16x16x32_bf16 v[46:49], v[134:137], v[200:203], v[46:49]
	v_mfma_f32_16x16x32_bf16 v[42:45], v[142:145], v[200:203], v[42:45]
	v_mfma_f32_16x16x32_bf16 v[30:33], v[134:137], v[208:211], v[30:33]
	v_mfma_f32_16x16x32_bf16 v[26:29], v[142:145], v[208:211], v[26:29]
	v_mfma_f32_16x16x32_bf16 v[14:17], v[134:137], v[216:219], v[14:17]
	v_mfma_f32_16x16x32_bf16 v[10:13], v[142:145], v[216:219], v[10:13]
	s_setprio 0
	s_setprio 1
	v_mfma_f32_16x16x32_bf16 v[54:57], v[146:149], v[178:181], v[54:57]
	v_mfma_f32_16x16x32_bf16 v[50:53], v[170:173], v[178:181], v[50:53]
	v_mfma_f32_16x16x32_bf16 v[38:41], v[146:149], v[196:199], v[38:41]
	v_mfma_f32_16x16x32_bf16 v[34:37], v[170:173], v[196:199], v[34:37]
	v_mfma_f32_16x16x32_bf16 v[22:25], v[146:149], v[204:207], v[22:25]
	v_mfma_f32_16x16x32_bf16 v[18:21], v[170:173], v[204:207], v[18:21]
	v_mfma_f32_16x16x32_bf16 v[6:9], v[146:149], v[212:215], v[6:9]
	v_mfma_f32_16x16x32_bf16 v[2:5], v[170:173], v[212:215], v[2:5]
	v_mfma_f32_16x16x32_bf16 v[54:57], v[166:169], v[182:185], v[54:57]
	v_mfma_f32_16x16x32_bf16 v[50:53], v[174:177], v[182:185], v[50:53]
	v_mfma_f32_16x16x32_bf16 v[38:41], v[166:169], v[200:203], v[38:41]
	v_mfma_f32_16x16x32_bf16 v[34:37], v[174:177], v[200:203], v[34:37]
	v_mfma_f32_16x16x32_bf16 v[22:25], v[166:169], v[208:211], v[22:25]
	v_mfma_f32_16x16x32_bf16 v[18:21], v[174:177], v[208:211], v[18:21]
	v_mfma_f32_16x16x32_bf16 v[6:9], v[166:169], v[216:219], v[6:9]
	v_mfma_f32_16x16x32_bf16 v[2:5], v[174:177], v[216:219], v[2:5]
	s_setprio 0
	s_barrier
; #define PG8_STAGE(bufoff, gbase, voff) do { _Pragma("unroll") for (int _i = 0; _i < 2; ++_i) \
;         __builtin_amdgcn_global_load_lds((const unsigned*)((const char*)(gbase) + (voff)[_i]), (PG8_LAS unsigned*)(lds + (bufoff) + ldsw + _i * 8192), 16, 0, 0); } while (0)
; #define PG8_LDA(dst, b, h) do { _Pragma("unroll") for (int m = 0; m < 4; ++m) _Pragma("unroll") for (int k = 0; k < 2; ++k) dst[m][k] = *(const PG8_LAS bf16x8*)(lds + PG8_SA(b, h) + aoff + m * 2048 + k * 1024); } while (0)
; #define PG8_LDB(dst, b, h) do { _Pragma("unroll") for (int n = 0; n < 2; ++n) _Pragma("unroll") for (int k = 0; k < 2; ++k) dst[n][k] = *(const PG8_LAS bf16x8*)(lds + PG8_SB(b, h) + boff + n * 2048 + k * 1024); } while (0)
; #define PG8_MMA(ai, bj, At, Bt) do { __builtin_amdgcn_s_setprio(1); _Pragma("unroll") for (int m = 0; m < 4; ++m) _Pragma("unroll") for (int n = 0; n < 2; ++n) _Pragma("unroll") for (int k = 0; k < 2; ++k) \
;         acc[ai][bj][m][n] = __builtin_amdgcn_mfma_f32_16x16x32_bf16(Bt[n][k], At[m][k], acc[ai][bj][m][n], 0, 0, 0); __builtin_amdgcn_s_setprio(0); } while (0)
; #define PG8_WAIT_V(n) asm volatile("s_waitcnt vmcnt(" #n ")" ::: "memory")
; #define PG8_WAIT_L(n) asm volatile("s_waitcnt lgkmcnt(" #n ")" ::: "memory")
; #define PG8_BAR __builtin_amdgcn_s_barrier()
; #define PG8_SCHED __builtin_amdgcn_sched_barrier(0)
; template <class Epi, class Sched, bool ALIGN_EPI = false, bool SP2 = false, bool ABLK = false, bool BBLK = false>
; __device__ __forceinline__ void gemm_phase(PG8_LAS unsigned char* lds, const Gemm g, const Sched& S, const Epi& E) {
;     ...
;             PG8_LDB(B0, 1, 0); PG8_LDB(B1, 1, 1); PG8_SCHED; PG8_LDA(At, 1, 0); PG8_STAGE(PG8_SA(0, 1), a2 + hstepA, voffA);
;             PG8_WAIT_V(8); PG8_WAIT_L(0); PG8_BAR; PG8_MMA(0, 0, At, B0); PG8_MMA(0, 1, At, B1); PG8_BAR; PG8_SCHED;
;             PG8_LDA(At, 1, 1); PG8_STAGE(PG8_SB(1, 0), b3, voffB); PG8_STAGE(PG8_SB(1, 1), b3 + hstepB, voffB); PG8_STAGE(PG8_SA(1, 0), a3, voffA);
	s_add_i32 s52, 0, 0x18000
	s_add_i32 s75, 0, 0x1c000
	v_add_u32_e32 v142, s52, v163
	v_add_u32_e32 v174, s75, v163
	ds_read_b128 v[130:133], v142
	ds_read_b128 v[134:137], v142 offset:1024
	ds_read_b128 v[138:141], v142 offset:2048
	ds_read_b128 v[142:145], v142 offset:3072
	ds_read_b128 v[146:149], v174
	ds_read_b128 v[166:169], v174 offset:1024
	ds_read_b128 v[170:173], v174 offset:2048
	ds_read_b128 v[174:177], v174 offset:3072
	s_add_u32 s36, s36, 0x20000
	s_addc_u32 s37, s37, 0
	s_mov_b32 m0, s68
	v_lshl_add_u64 v[190:191], s[36:37], 0, v[186:187]
	ds_read_b128 v[178:181], v165 offset:32768
	ds_read_b128 v[182:185], v165 offset:33792
	ds_read_b128 v[196:199], v165 offset:34816
	ds_read_b128 v[200:203], v165 offset:35840
	ds_read_b128 v[204:207], v165 offset:36864
	ds_read_b128 v[208:211], v165 offset:37888
	ds_read_b128 v[212:215], v165 offset:38912
	ds_read_b128 v[216:219], v165 offset:39936
	global_load_lds_dwordx4 v[190:191], off
	v_lshl_add_u64 v[190:191], s[36:37], 0, v[152:153]
	s_mov_b32 m0, s72
	s_nop 0
	global_load_lds_dwordx4 v[190:191], off
	s_waitcnt vmcnt(8)
	s_waitcnt lgkmcnt(0)
	s_barrier
	s_setprio 1
	s_waitcnt lgkmcnt(0)
	v_mfma_f32_16x16x32_bf16 v[126:129], v[130:133], v[178:181], v[126:129]
	v_mfma_f32_16x16x32_bf16 v[122:125], v[138:141], v[178:181], v[122:125]
	v_mfma_f32_16x16x32_bf16 v[118:121], v[130:133], v[196:199], v[118:121]
	v_mfma_f32_16x16x32_bf16 v[114:117], v[138:141], v[196:199], v[114:117]
	v_mfma_f32_16x16x32_bf16 v[94:97], v[130:133], v[204:207], v[94:97]
	v_mfma_f32_16x16x32_bf16 v[90:93], v[138:141], v[204:207], v[90:93]
	v_mfma_f32_16x16x32_bf16 v[78:81], v[130:133], v[212:215], v[78:81]
	v_mfma_f32_16x16x32_bf16 v[74:77], v[138:141], v[212:215], v[74:77]
	v_mfma_f32_16x16x32_bf16 v[126:129], v[134:137], v[182:185], v[126:129]
	v_mfma_f32_16x16x32_bf16 v[122:125], v[142:145], v[182:185], v[122:125]
	v_mfma_f32_16x16x32_bf16 v[118:121], v[134:137], v[200:203], v[118:121]
	v_mfma_f32_16x16x32_bf16 v[114:117], v[142:145], v[200:203], v[114:117]
	v_mfma_f32_16x16x32_bf16 v[94:97], v[134:137], v[208:211], v[94:97]
	v_mfma_f32_16x16x32_bf16 v[90:93], v[142:145], v[208:211], v[90:93]
	v_mfma_f32_16x16x32_bf16 v[78:81], v[134:137], v[216:219], v[78:81]
	v_mfma_f32_16x16x32_bf16 v[74:77], v[142:145], v[216:219], v[74:77]
	s_setprio 0
	s_setprio 1
	v_mfma_f32_16x16x32_bf16 v[110:113], v[146:149], v[178:181], v[110:113]
	v_mfma_f32_16x16x32_bf16 v[106:109], v[170:173], v[178:181], v[106:109]
	v_mfma_f32_16x16x32_bf16 v[102:105], v[146:149], v[196:199], v[102:105]
	v_mfma_f32_16x16x32_bf16 v[98:101], v[170:173], v[196:199], v[98:101]
	v_mfma_f32_16x16x32_bf16 v[86:89], v[146:149], v[204:207], v[86:89]
	v_mfma_f32_16x16x32_bf16 v[82:85], v[170:173], v[204:207], v[82:85]
	v_mfma_f32_16x16x32_bf16 v[70:73], v[146:149], v[212:215], v[70:73]
	v_mfma_f32_16x16x32_bf16 v[66:69], v[170:173], v[212:215], v[66:69]
	v_mfma_f32_16x16x32_bf16 v[110:113], v[166:169], v[182:185], v[110:113]
	v_mfma_f32_16x16x32_bf16 v[106:109], v[174:177], v[182:185], v[106:109]
	v_mfma_f32_16x16x32_bf16 v[102:105], v[166:169], v[200:203], v[102:105]
	v_mfma_f32_16x16x32_bf16 v[98:101], v[174:177], v[200:203], v[98:101]
	v_mfma_f32_16x16x32_bf16 v[86:89], v[166:169], v[208:211], v[86:89]
	v_mfma_f32_16x16x32_bf16 v[82:85], v[174:177], v[208:211], v[82:85]
	v_mfma_f32_16x16x32_bf16 v[70:73], v[166:169], v[216:219], v[70:73]
	v_mfma_f32_16x16x32_bf16 v[66:69], v[174:177], v[216:219], v[66:69]
	s_setprio 0
	s_barrier
	s_add_u32 s36, s34, 0x8000
	s_addc_u32 s37, s35, 0
	s_add_i32 s52, s52, s47
	v_lshl_add_u64 v[190:191], s[36:37], 0, v[150:151]
	s_mov_b32 m0, s52
	ds_read_b128 v[178:181], v165 offset:49152
	ds_read_b128 v[182:185], v165 offset:50176
	ds_read_b128 v[196:199], v165 offset:51200
	ds_read_b128 v[200:203], v165 offset:52224
	ds_read_b128 v[204:207], v165 offset:53248
	ds_read_b128 v[208:211], v165 offset:54272
	ds_read_b128 v[212:215], v165 offset:55296
	ds_read_b128 v[216:219], v165 offset:56320
	global_load_lds_dwordx4 v[190:191], off
	s_add_i32 m0, s52, 0x2000
	s_add_u32 s34, s34, 0xc000
	v_lshl_add_u64 v[190:191], s[36:37], 0, v[154:155]
	s_addc_u32 s35, s35, 0
	s_add_i32 s36, s75, s47
	global_load_lds_dwordx4 v[190:191], off
	v_lshl_add_u64 v[190:191], s[34:35], 0, v[150:151]
	s_mov_b32 m0, s36
	v_lshl_add_u64 v[160:161], v[160:161], 0, s[62:63]
	global_load_lds_dwordx4 v[190:191], off
	v_lshl_add_u64 v[190:191], s[34:35], 0, v[154:155]
	s_add_i32 m0, s36, 0x2000
	s_nop 0
	global_load_lds_dwordx4 v[190:191], off
	s_mov_b32 m0, s86
	s_nop 0
	global_load_lds_dwordx4 v[160:161], off
	v_lshl_add_u64 v[160:161], v[188:189], 0, s[62:63]
	s_mov_b32 m0, s88
	s_nop 0
	global_load_lds_dwordx4 v[160:161], off
	s_waitcnt vmcnt(8)
	s_waitcnt lgkmcnt(0)
	s_barrier
; #define PG8_WAIT_V(n) asm volatile("s_waitcnt vmcnt(" #n ")" ::: "memory")
;     __device__ __forceinline__ void operator()(const f32x4 (&acc)[2][2][4][2], const Unit& u, int wr, int wc, int fr_, int fq) const {
;     ...
;         const size_t row0 = (size_t)u.pm * BM + wr * 64 + fr; const int col0 = u.pn * BM + wc * 32 + 8 * fq;
; #pragma unroll
;         for (int ai = 0; ai < 2; ++ai) {
;             u32x4 gw[4][2], ow[4][2];
; #pragma unroll
;             for (int m = 0; m < 4; ++m)
; #pragma unroll
; template <class Epi, class Sched, bool ALIGN_EPI = false, bool SP2 = false, bool ABLK = false, bool BBLK = false>
; __device__ __forceinline__ void gemm_phase(PG8_LAS unsigned char* lds, const Gemm g, const Sched& S, const Epi& E) {
;     ...
;             PG8_LDA(At, 1, 1); PG8_STAGE(PG8_SB(1, 0), b3, voffB); PG8_STAGE(PG8_SB(1, 1), b3 + hstepB, voffB); PG8_STAGE(PG8_SA(1, 0), a3, voffA);
;             PG8_WAIT_V(8); PG8_WAIT_L(0); PG8_BAR; PG8_MMA(1, 0, At, B0); PG8_MMA(1, 1, At, B1); PG8_BAR; PG8_SCHED;
;             } else {
;             PG8_LDB(B0, 0, 0); PG8_SCHED; PG8_LDA(At, 0, 0); PG8_STAGE(PG8_SA(1, 1), a1 + hstepA, voffA);
;             PG8_WAIT_L(8); PG8_BAR; PG8_WAIT_L(0); PG8_MMA(0, 0, At, B0); PG8_BAR; PG8_SCHED;
;             PG8_LDB(B1, 0, 1); PG8_STAGE(PG8_SB(0, 0), b2, voffB);
;             PG8_BAR; PG8_WAIT_L(0); PG8_MMA(0, 1, At, B1); PG8_BAR;
;             PG8_LDA(At, 0, 1); PG8_STAGE(PG8_SA(0, 0), a2, voffA);
;             PG8_BAR; PG8_WAIT_L(0); PG8_MMA(1, 0, At, B0); PG8_BAR; PG8_SCHED;
;             PG8_STAGE(PG8_SB(0, 1), b2 + hstepB, voffB);
;             PG8_WAIT_V(6); PG8_BAR; PG8_MMA(1, 1, At, B1); PG8_BAR;
;             PG8_LDB(B0, 1, 0); PG8_SCHED; PG8_LDA(At, 1, 0); PG8_STAGE(PG8_SA(0, 1), a2 + hstepA, voffA);
;             PG8_WAIT_L(8); PG8_BAR; PG8_WAIT_L(0); PG8_MMA(0, 0, At, B0); PG8_BAR; PG8_SCHED;
;             PG8_LDB(B1, 1, 1); PG8_STAGE(PG8_SB(1, 0), b3, voffB);
;             PG8_BAR; PG8_WAIT_L(0); PG8_MMA(0, 1, At, B1); PG8_BAR;
;             PG8_LDA(At, 1, 1); PG8_STAGE(PG8_SA(1, 0), a3, voffA);
;             PG8_BAR; PG8_WAIT_L(0); PG8_MMA(1, 0, At, B0); PG8_BAR; PG8_SCHED;
;             PG8_STAGE(PG8_SB(1, 1), b3 + hstepB, voffB);
;             PG8_WAIT_V(6); PG8_BAR; PG8_MMA(1, 1, At, B1); PG8_BAR;
;             }
;         }
;         if constexpr (ALIGN_EPI) { if (wr == 0) PG8_BAR; }
	s_setprio 1
	s_waitcnt lgkmcnt(0)
	v_mfma_f32_16x16x32_bf16 v[62:65], v[130:133], v[178:181], v[62:65]
	v_mfma_f32_16x16x32_bf16 v[58:61], v[138:141], v[178:181], v[58:61]
	v_mfma_f32_16x16x32_bf16 v[46:49], v[130:133], v[196:199], v[46:49]
	v_mfma_f32_16x16x32_bf16 v[42:45], v[138:141], v[196:199], v[42:45]
	v_mfma_f32_16x16x32_bf16 v[30:33], v[130:133], v[204:207], v[30:33]
	v_mfma_f32_16x16x32_bf16 v[26:29], v[138:141], v[204:207], v[26:29]
	v_mfma_f32_16x16x32_bf16 v[14:17], v[130:133], v[212:215], v[14:17]
	v_mfma_f32_16x16x32_bf16 v[10:13], v[138:141], v[212:215], v[10:13]
	v_mfma_f32_16x16x32_bf16 v[62:65], v[134:137], v[182:185], v[62:65]
	v_mfma_f32_16x16x32_bf16 v[58:61], v[142:145], v[182:185], v[58:61]
	v_mfma_f32_16x16x32_bf16 v[46:49], v[134:137], v[200:203], v[46:49]
	v_mfma_f32_16x16x32_bf16 v[42:45], v[142:145], v[200:203], v[42:45]
	v_mfma_f32_16x16x32_bf16 v[30:33], v[134:137], v[208:211], v[30:33]
	v_mfma_f32_16x16x32_bf16 v[26:29], v[142:145], v[208:211], v[26:29]
	v_mfma_f32_16x16x32_bf16 v[14:17], v[134:137], v[216:219], v[14:17]
	v_mfma_f32_16x16x32_bf16 v[10:13], v[142:145], v[216:219], v[10:13]
	s_setprio 0
	s_setprio 1
	v_mfma_f32_16x16x32_bf16 v[54:57], v[146:149], v[178:181], v[54:57]
	v_mfma_f32_16x16x32_bf16 v[50:53], v[170:173], v[178:181], v[50:53]
	v_mfma_f32_16x16x32_bf16 v[38:41], v[146:149], v[196:199], v[38:41]
	v_mfma_f32_16x16x32_bf16 v[34:37], v[170:173], v[196:199], v[34:37]
	v_mfma_f32_16x16x32_bf16 v[22:25], v[146:149], v[204:207], v[22:25]
	v_mfma_f32_16x16x32_bf16 v[18:21], v[170:173], v[204:207], v[18:21]
	v_mfma_f32_16x16x32_bf16 v[6:9], v[146:149], v[212:215], v[6:9]
	v_mfma_f32_16x16x32_bf16 v[2:5], v[170:173], v[212:215], v[2:5]
	v_mfma_f32_16x16x32_bf16 v[54:57], v[166:169], v[182:185], v[54:57]
	v_mfma_f32_16x16x32_bf16 v[50:53], v[174:177], v[182:185], v[50:53]
	v_mfma_f32_16x16x32_bf16 v[38:41], v[166:169], v[200:203], v[38:41]
	v_mfma_f32_16x16x32_bf16 v[34:37], v[174:177], v[200:203], v[34:37]
	v_mfma_f32_16x16x32_bf16 v[22:25], v[166:169], v[208:211], v[22:25]
	v_mfma_f32_16x16x32_bf16 v[18:21], v[174:177], v[208:211], v[18:21]
	v_mfma_f32_16x16x32_bf16 v[6:9], v[166:169], v[216:219], v[6:9]
	v_mfma_f32_16x16x32_bf16 v[2:5], v[174:177], v[216:219], v[2:5]
	s_setprio 0
	s_barrier
	s_add_i32 s94, s94, 2
	s_add_u32 s92, s92, 0x10000
	s_addc_u32 s93, s93, 0
	s_add_u32 s0, s0, 0x100
	s_addc_u32 s1, s1, 0
	s_cmp_gt_u32 s94, 5
	s_cbranch_scc0 .LBB0_1117
	s_and_b64 vcc, exec, s[18:19]
	s_cbranch_vccz .LBB0_1120
	s_barrier
.LBB0_1120:
	s_ashr_i32 s31, s30, 31
	s_lshl_b64 s[0:1], s[30:31], 8
	v_mov_b32_e32 v130, v162
	s_add_u32 s0, s0, s73
	s_addc_u32 s1, s1, s89
	v_ashrrev_i32_e32 v131, 31, v130
	v_lshl_add_u64 v[178:179], s[0:1], 0, v[130:131]
	v_lshl_or_b32 v130, s28, 8, v164
	v_mov_b64_e32 v[132:133], s[14:15]
	s_movk_i32 s21, 0x3000
	v_ashrrev_i32_e32 v131, 31, v130
	v_mad_u64_u32 v[132:133], s[0:1], v178, s21, v[132:133]
	v_mad_i32_i24 v133, v179, s21, v133
	v_lshlrev_b64 v[180:181], 1, v[130:131]
	v_lshl_add_u64 v[160:161], v[132:133], 0, v[180:181]
	global_load_dwordx4 v[166:169], v[160:161], off
	global_load_dwordx4 v[170:173], v[160:161], off offset:256
	s_mov_b32 s91, 0x30000
	v_add_co_u32_e32 v132, vcc, s91, v160
	s_mov_b64 s[34:35], 0x30000
	s_nop 0
	v_addc_co_u32_e32 v133, vcc, 0, v161, vcc
	v_lshl_add_u64 v[130:131], v[160:161], 0, s[34:35]
	global_load_dwordx4 v[174:177], v[132:133], off
	global_load_dwordx4 v[146:149], v[130:131], off offset:256
	s_mov_b32 s94, 0x60000
	v_add_co_u32_e32 v132, vcc, s94, v160
	s_mov_b64 s[0:1], 0x60000
	s_nop 0
	v_addc_co_u32_e32 v133, vcc, 0, v161, vcc
	v_lshl_add_u64 v[130:131], v[160:161], 0, s[0:1]
	global_load_dwordx4 v[142:145], v[132:133], off
	global_load_dwordx4 v[138:141], v[130:131], off offset:256
	s_mov_b32 s0, 0x90000
	s_mov_b64 s[36:37], 0x90000
	v_add_co_u32_e32 v132, vcc, s0, v160
	v_lshl_add_u64 v[130:131], v[160:161], 0, s[36:37]
	s_nop 0
	v_addc_co_u32_e32 v133, vcc, 0, v161, vcc
	global_load_dwordx4 v[134:137], v[132:133], off
	s_nop 0
	global_load_dwordx4 v[130:133], v[130:131], off offset:256
	v_lshlrev_b64 v[178:179], 12, v[178:179]
	s_mov_b64 s[30:31], 0x20000
	s_mov_b32 s1, 0x180000
	s_mov_b32 s52, 0x80000
	s_waitcnt vmcnt(0)
	v_lshlrev_b32_e32 v182, 16, v166
	v_and_b32_e32 v183, 0xffff0000, v166
	v_lshlrev_b32_e32 v184, 16, v168
	v_and_b32_e32 v185, 0xffff0000, v168
	v_lshlrev_b32_e32 v166, 16, v167
	v_and_b32_e32 v167, 0xffff0000, v167
	v_lshlrev_b32_e32 v168, 16, v169
	v_and_b32_e32 v169, 0xffff0000, v169
	v_pk_mul_f32 v[126:127], v[126:127], v[182:183]
	v_pk_mul_f32 v[122:123], v[122:123], v[184:185]
	v_pk_mul_f32 v[128:129], v[128:129], v[166:167]
	v_pk_mul_f32 v[166:167], v[124:125], v[168:169]
	v_cvt_pk_bf16_f32 v124, v126, v127
	v_cvt_pk_bf16_f32 v125, v128, v129
	v_cvt_pk_bf16_f32 v126, v122, v123
	v_lshl_add_u64 v[122:123], s[2:3], 0, v[178:179]
	v_lshl_add_u64 v[122:123], v[122:123], 0, v[180:181]
	v_cvt_pk_bf16_f32 v127, v166, v167
	global_store_dwordx4 v[122:123], v[124:127], off
	v_lshlrev_b32_e32 v128, 16, v172
	v_and_b32_e32 v129, 0xffff0000, v172
	v_lshlrev_b32_e32 v124, 16, v170
	v_and_b32_e32 v125, 0xffff0000, v170
	v_lshlrev_b32_e32 v166, 16, v173
	v_and_b32_e32 v167, 0xffff0000, v173
	v_lshlrev_b32_e32 v126, 16, v171
	v_and_b32_e32 v127, 0xffff0000, v171
	v_pk_mul_f32 v[110:111], v[110:111], v[124:125]
	v_pk_mul_f32 v[124:125], v[108:109], v[166:167]
	v_pk_mul_f32 v[108:109], v[106:107], v[128:129]
	v_pk_mul_f32 v[112:113], v[112:113], v[126:127]
	v_cvt_pk_bf16_f32 v106, v110, v111
	v_lshlrev_b32_e32 v110, 16, v176
	v_cvt_pk_bf16_f32 v107, v112, v113
	v_cvt_pk_bf16_f32 v108, v108, v109
; __device__ __forceinline__ u32x4 pack8(const f32x4 v0, const f32x4 v1) { u32x4 w; w.x = cvt_pk_bf16(v0[0], v0[1]); w.y = cvt_pk_bf16(v0[2], v0[3]); w.z = cvt_pk_bf16(v1[0], v1[1]); w.w = cvt_pk_bf16(v1[2], v1[3]); return w; }
;     __device__ __forceinline__ void operator()(const f32x4 (&acc)[2][2][4][2], const Unit& u, int wr, int wc, int fr_, int fq) const {
;     ...
;         for (int ai = 0; ai < 2; ++ai) {
;             u32x4 gw[4][2], ow[4][2];
; #pragma unroll
;             for (int m = 0; m < 4; ++m)
; #pragma unroll
;                 for (int bj = 0; bj < 2; ++bj) { const size_t r = row0 + ai * HALF + m * 16; const int c = col0 + bj * HALF;
;                     gw[m][bj] = *(const u32x4*)(G + r * 6144 + goff + c); if (!FIRST) ow[m][bj] = *(const u32x4*)(Mo + r * DM + c); }
; #pragma unroll
;             for (int m = 0; m < 4; ++m)
; #pragma unroll
;                 for (int bj = 0; bj < 2; ++bj) { const size_t r = row0 + ai * HALF + m * 16; const int c = col0 + bj * HALF;
;                     f32x4 g0, g1; unpack8(gw[m][bj], g0, g1);
;                     f32x4 v0 = g0 * acc[ai][bj][m][0], v1 = g1 * acc[ai][bj][m][1];
;                     if (!FIRST) { f32x4 o0, o1; unpack8(ow[m][bj], o0, o1); v0 += o0; v1 += o1; }
;                     *(u32x4*)((Mdst ? Mdst : Mo) + r * DM + c) = pack8(v0, v1); }
;             asm volatile("" ::: "memory"); }
	v_cvt_pk_bf16_f32 v109, v124, v125
	global_store_dwordx4 v[122:123], v[106:109], off offset:256
	v_lshlrev_b32_e32 v112, 16, v177
	v_and_b32_e32 v113, 0xffff0000, v177
	v_lshlrev_b32_e32 v106, 16, v174
	v_and_b32_e32 v107, 0xffff0000, v174
	v_lshlrev_b32_e32 v108, 16, v175
	v_and_b32_e32 v109, 0xffff0000, v175
	v_and_b32_e32 v111, 0xffff0000, v176
	v_pk_mul_f32 v[108:109], v[120:121], v[108:109]
	v_pk_mul_f32 v[106:107], v[118:119], v[106:107]
	v_pk_mul_f32 v[112:113], v[116:117], v[112:113]
	v_pk_mul_f32 v[110:111], v[114:115], v[110:111]
	v_cvt_pk_bf16_f32 v106, v106, v107
	v_cvt_pk_bf16_f32 v107, v108, v109
	v_lshlrev_b32_e32 v114, 16, v149
	v_cvt_pk_bf16_f32 v108, v110, v111
	v_cvt_pk_bf16_f32 v109, v112, v113
	v_add_co_u32_e32 v112, vcc, s80, v122
	v_and_b32_e32 v115, 0xffff0000, v149
	s_nop 0
	v_addc_co_u32_e32 v113, vcc, 0, v123, vcc
	global_store_dwordx4 v[112:113], v[106:109], off
	v_lshlrev_b32_e32 v112, 16, v148
	v_and_b32_e32 v113, 0xffff0000, v148
	v_lshlrev_b32_e32 v106, 16, v146
	v_and_b32_e32 v107, 0xffff0000, v146
	v_lshlrev_b32_e32 v108, 16, v147
	v_and_b32_e32 v109, 0xffff0000, v147
	v_pk_mul_f32 v[102:103], v[102:103], v[106:107]
	v_pk_mul_f32 v[106:107], v[100:101], v[114:115]
	v_pk_mul_f32 v[100:101], v[98:99], v[112:113]
	v_lshl_add_u64 v[110:111], v[122:123], 0, s[48:49]
	v_pk_mul_f32 v[104:105], v[104:105], v[108:109]
	v_cvt_pk_bf16_f32 v98, v102, v103
	v_lshlrev_b32_e32 v102, 16, v144
	v_cvt_pk_bf16_f32 v99, v104, v105
	v_cvt_pk_bf16_f32 v100, v100, v101
	v_cvt_pk_bf16_f32 v101, v106, v107
	global_store_dwordx4 v[110:111], v[98:101], off offset:256
	v_and_b32_e32 v103, 0xffff0000, v144
	v_lshlrev_b32_e32 v104, 16, v145
	v_lshlrev_b32_e32 v100, 16, v143
	v_and_b32_e32 v101, 0xffff0000, v143
	v_lshlrev_b32_e32 v98, 16, v142
	v_and_b32_e32 v99, 0xffff0000, v142
	v_and_b32_e32 v105, 0xffff0000, v145
	v_pk_mul_f32 v[96:97], v[96:97], v[100:101]
	v_pk_mul_f32 v[94:95], v[94:95], v[98:99]
	v_pk_mul_f32 v[98:99], v[92:93], v[104:105]
	v_pk_mul_f32 v[92:93], v[90:91], v[102:103]
	v_cvt_pk_bf16_f32 v90, v94, v95
	v_cvt_pk_bf16_f32 v91, v96, v97
	v_add_co_u32_e32 v96, vcc, s95, v122
	v_cvt_pk_bf16_f32 v92, v92, v93
	v_cvt_pk_bf16_f32 v93, v98, v99
	v_lshlrev_b32_e32 v98, 16, v141
	s_nop 0
	v_addc_co_u32_e32 v97, vcc, 0, v123, vcc
	global_store_dwordx4 v[96:97], v[90:93], off
	v_lshlrev_b32_e32 v96, 16, v140
	v_and_b32_e32 v97, 0xffff0000, v140
	v_lshlrev_b32_e32 v90, 16, v138
	v_and_b32_e32 v91, 0xffff0000, v138
	v_and_b32_e32 v99, 0xffff0000, v141
	v_lshlrev_b32_e32 v92, 16, v139
	v_and_b32_e32 v93, 0xffff0000, v139
	v_pk_mul_f32 v[86:87], v[86:87], v[90:91]
	v_pk_mul_f32 v[90:91], v[84:85], v[98:99]
	v_pk_mul_f32 v[84:85], v[82:83], v[96:97]
	v_lshl_add_u64 v[94:95], v[122:123], 0, s[30:31]
	v_pk_mul_f32 v[88:89], v[88:89], v[92:93]
	v_cvt_pk_bf16_f32 v82, v86, v87
	v_lshlrev_b32_e32 v86, 16, v136
	v_cvt_pk_bf16_f32 v83, v88, v89
	v_cvt_pk_bf16_f32 v84, v84, v85
	v_cvt_pk_bf16_f32 v85, v90, v91
	global_store_dwordx4 v[94:95], v[82:85], off offset:256
	v_and_b32_e32 v87, 0xffff0000, v136
	v_lshlrev_b32_e32 v88, 16, v137
	v_lshlrev_b32_e32 v84, 16, v135
	v_and_b32_e32 v85, 0xffff0000, v135
	v_lshlrev_b32_e32 v82, 16, v134
	v_and_b32_e32 v83, 0xffff0000, v134
	v_and_b32_e32 v89, 0xffff0000, v137
	v_pk_mul_f32 v[80:81], v[80:81], v[84:85]
	v_pk_mul_f32 v[78:79], v[78:79], v[82:83]
	v_pk_mul_f32 v[82:83], v[76:77], v[88:89]
	v_pk_mul_f32 v[76:77], v[74:75], v[86:87]
	v_cvt_pk_bf16_f32 v74, v78, v79
	v_cvt_pk_bf16_f32 v75, v80, v81
	v_add_co_u32_e32 v80, vcc, s91, v122
	v_cvt_pk_bf16_f32 v76, v76, v77
	v_cvt_pk_bf16_f32 v77, v82, v83
	v_lshlrev_b32_e32 v82, 16, v133
	s_nop 0
	v_addc_co_u32_e32 v81, vcc, 0, v123, vcc
	global_store_dwordx4 v[80:81], v[74:77], off
	v_lshlrev_b32_e32 v80, 16, v132
	v_and_b32_e32 v81, 0xffff0000, v132
	v_lshlrev_b32_e32 v74, 16, v130
	v_and_b32_e32 v75, 0xffff0000, v130
	v_and_b32_e32 v83, 0xffff0000, v133
	v_lshlrev_b32_e32 v76, 16, v131
	v_and_b32_e32 v77, 0xffff0000, v131
	v_pk_mul_f32 v[70:71], v[70:71], v[74:75]
	v_pk_mul_f32 v[74:75], v[68:69], v[82:83]
	v_pk_mul_f32 v[68:69], v[66:67], v[80:81]
	v_lshl_add_u64 v[78:79], v[122:123], 0, s[34:35]
	v_pk_mul_f32 v[72:73], v[72:73], v[76:77]
	v_cvt_pk_bf16_f32 v66, v70, v71
	s_mov_b64 s[30:31], 0x180000
	v_cvt_pk_bf16_f32 v67, v72, v73
	v_cvt_pk_bf16_f32 v68, v68, v69
	v_cvt_pk_bf16_f32 v69, v74, v75
	global_store_dwordx4 v[78:79], v[66:69], off offset:256
	s_nop 1
	v_add_co_u32_e32 v68, vcc, s1, v160
	v_lshl_add_u64 v[66:67], v[160:161], 0, s[30:31]
	s_nop 0
	v_addc_co_u32_e32 v69, vcc, 0, v161, vcc
	global_load_dwordx4 v[74:77], v[68:69], off
	global_load_dwordx4 v[78:81], v[66:67], off offset:256
	s_mov_b32 s1, 0x1b0000
	v_add_co_u32_e32 v68, vcc, s1, v160
	s_mov_b64 s[30:31], 0x1b0000
	s_nop 0
	v_addc_co_u32_e32 v69, vcc, 0, v161, vcc
	v_lshl_add_u64 v[66:67], v[160:161], 0, s[30:31]
	global_load_dwordx4 v[82:85], v[68:69], off
	global_load_dwordx4 v[86:89], v[66:67], off offset:256
	s_mov_b32 s1, 0x1e0000
	v_add_co_u32_e32 v68, vcc, s1, v160
	s_mov_b64 s[30:31], 0x1e0000
	s_nop 0
	v_addc_co_u32_e32 v69, vcc, 0, v161, vcc
	v_lshl_add_u64 v[66:67], v[160:161], 0, s[30:31]
	global_load_dwordx4 v[90:93], v[68:69], off
	global_load_dwordx4 v[94:97], v[66:67], off offset:256
	s_mov_b32 s1, 0x210000
	s_mov_b64 s[30:31], 0x210000
	v_add_co_u32_e32 v68, vcc, s1, v160
	v_lshl_add_u64 v[66:67], v[160:161], 0, s[30:31]
	s_nop 0
	v_addc_co_u32_e32 v69, vcc, 0, v161, vcc
	global_load_dwordx4 v[70:73], v[68:69], off
	s_nop 0
	global_load_dwordx4 v[66:69], v[66:67], off offset:256
	s_mov_b64 s[30:31], 0x80000
	s_waitcnt vmcnt(7)
; __device__ __forceinline__ u32x4 pack8(const f32x4 v0, const f32x4 v1) { u32x4 w; w.x = cvt_pk_bf16(v0[0], v0[1]); w.y = cvt_pk_bf16(v0[2], v0[3]); w.z = cvt_pk_bf16(v1[0], v1[1]); w.w = cvt_pk_bf16(v1[2], v1[3]); return w; }
; #define PG8_BAR __builtin_amdgcn_s_barrier()
;     __device__ __forceinline__ void operator()(const f32x4 (&acc)[2][2][4][2], const Unit& u, int wr, int wc, int fr_, int fq) const {
;     ...
;             for (int m = 0; m < 4; ++m)
; #pragma unroll
;                 for (int bj = 0; bj < 2; ++bj) { const size_t r = row0 + ai * HALF + m * 16; const int c = col0 + bj * HALF;
;                     f32x4 g0, g1; unpack8(gw[m][bj], g0, g1);
;                     f32x4 v0 = g0 * acc[ai][bj][m][0], v1 = g1 * acc[ai][bj][m][1];
;                     if (!FIRST) { f32x4 o0, o1; unpack8(ow[m][bj], o0, o1); v0 += o0; v1 += o1; }
;                     *(u32x4*)((Mdst ? Mdst : Mo) + r * DM + c) = pack8(v0, v1); }
;             asm volatile("" ::: "memory"); }
; template <class Epi, class Sched, bool ALIGN_EPI = false, bool SP2 = false, bool ABLK = false, bool BBLK = false>
; __device__ __forceinline__ void gemm_phase(PG8_LAS unsigned char* lds, const Gemm g, const Sched& S, const Epi& E) {
;     ...
;         if (!has_next) break;
; #pragma unroll
;         for (int a = 0; a < 2; ++a)
; #pragma unroll
;             for (int b = 0; b < 2; ++b)
; #pragma unroll
;                 for (int m = 0; m < 4; ++m)
; #pragma unroll
;                     for (int n = 0; n < 2; ++n) acc[a][b][m][n] = (f32x4){0.f, 0.f, 0.f, 0.f};
;         cur = nxt; cA = nA; cB = nB; ++ui;
;         if constexpr (ALIGN_EPI) { if (wr == 1) PG8_BAR; }
	v_lshlrev_b32_e32 v98, 16, v74
	v_and_b32_e32 v99, 0xffff0000, v74
	v_lshlrev_b32_e32 v74, 16, v75
	v_and_b32_e32 v75, 0xffff0000, v75
	v_lshlrev_b32_e32 v100, 16, v76
	v_and_b32_e32 v101, 0xffff0000, v76
	v_lshlrev_b32_e32 v76, 16, v77
	v_and_b32_e32 v77, 0xffff0000, v77
	v_pk_mul_f32 v[64:65], v[64:65], v[74:75]
	v_pk_mul_f32 v[62:63], v[62:63], v[98:99]
	v_pk_mul_f32 v[74:75], v[60:61], v[76:77]
	v_pk_mul_f32 v[60:61], v[58:59], v[100:101]
	v_cvt_pk_bf16_f32 v58, v62, v63
	v_cvt_pk_bf16_f32 v59, v64, v65
	v_add_co_u32_e32 v64, vcc, s52, v122
	v_cvt_pk_bf16_f32 v60, v60, v61
	v_cvt_pk_bf16_f32 v61, v74, v75
	s_waitcnt vmcnt(6)
	v_lshlrev_b32_e32 v74, 16, v81
	v_addc_co_u32_e32 v65, vcc, 0, v123, vcc
	global_store_dwordx4 v[64:65], v[58:61], off
	v_lshlrev_b32_e32 v64, 16, v80
	v_and_b32_e32 v65, 0xffff0000, v80
	v_lshlrev_b32_e32 v58, 16, v78
	v_and_b32_e32 v59, 0xffff0000, v78
	v_and_b32_e32 v75, 0xffff0000, v81
	v_lshlrev_b32_e32 v60, 16, v79
	v_and_b32_e32 v61, 0xffff0000, v79
	v_pk_mul_f32 v[54:55], v[54:55], v[58:59]
	v_pk_mul_f32 v[58:59], v[52:53], v[74:75]
	v_pk_mul_f32 v[52:53], v[50:51], v[64:65]
	v_lshl_add_u64 v[62:63], v[122:123], 0, s[30:31]
	v_pk_mul_f32 v[56:57], v[56:57], v[60:61]
	v_cvt_pk_bf16_f32 v50, v54, v55
	s_waitcnt vmcnt(6)
	v_lshlrev_b32_e32 v54, 16, v84
	v_cvt_pk_bf16_f32 v51, v56, v57
	v_cvt_pk_bf16_f32 v52, v52, v53
	v_cvt_pk_bf16_f32 v53, v58, v59
	global_store_dwordx4 v[62:63], v[50:53], off offset:256
	v_and_b32_e32 v55, 0xffff0000, v84
	v_lshlrev_b32_e32 v56, 16, v85
	v_lshlrev_b32_e32 v52, 16, v83
	v_and_b32_e32 v53, 0xffff0000, v83
	v_lshlrev_b32_e32 v50, 16, v82
	v_and_b32_e32 v51, 0xffff0000, v82
	v_and_b32_e32 v57, 0xffff0000, v85
	v_pk_mul_f32 v[48:49], v[48:49], v[52:53]
	v_pk_mul_f32 v[46:47], v[46:47], v[50:51]
	v_pk_mul_f32 v[50:51], v[44:45], v[56:57]
	v_pk_mul_f32 v[44:45], v[42:43], v[54:55]
	v_cvt_pk_bf16_f32 v42, v46, v47
	v_cvt_pk_bf16_f32 v43, v48, v49
	v_add_co_u32_e32 v48, vcc, s0, v122
	v_cvt_pk_bf16_f32 v44, v44, v45
	v_cvt_pk_bf16_f32 v45, v50, v51
	s_waitcnt vmcnt(6)
	v_lshlrev_b32_e32 v50, 16, v89
	v_addc_co_u32_e32 v49, vcc, 0, v123, vcc
	global_store_dwordx4 v[48:49], v[42:45], off
	v_lshlrev_b32_e32 v48, 16, v88
	v_and_b32_e32 v49, 0xffff0000, v88
	v_lshlrev_b32_e32 v42, 16, v86
	v_and_b32_e32 v43, 0xffff0000, v86
	v_lshlrev_b32_e32 v44, 16, v87
	v_and_b32_e32 v45, 0xffff0000, v87
	v_and_b32_e32 v51, 0xffff0000, v89
	v_lshl_add_u64 v[46:47], v[122:123], 0, s[36:37]
	v_pk_mul_f32 v[40:41], v[40:41], v[44:45]
	v_pk_mul_f32 v[38:39], v[38:39], v[42:43]
	v_pk_mul_f32 v[42:43], v[36:37], v[50:51]
	v_pk_mul_f32 v[36:37], v[34:35], v[48:49]
	v_cvt_pk_bf16_f32 v34, v38, v39
	v_cvt_pk_bf16_f32 v35, v40, v41
	s_waitcnt vmcnt(6)
	v_lshlrev_b32_e32 v38, 16, v92
	v_cvt_pk_bf16_f32 v36, v36, v37
	v_cvt_pk_bf16_f32 v37, v42, v43
	global_store_dwordx4 v[46:47], v[34:37], off offset:256
	v_and_b32_e32 v39, 0xffff0000, v92
	v_lshlrev_b32_e32 v40, 16, v93
	v_lshlrev_b32_e32 v34, 16, v90
	v_and_b32_e32 v35, 0xffff0000, v90
	v_lshlrev_b32_e32 v36, 16, v91
	v_and_b32_e32 v37, 0xffff0000, v91
	v_and_b32_e32 v41, 0xffff0000, v93
	v_pk_mul_f32 v[30:31], v[30:31], v[34:35]
	s_mov_b64 s[0:1], 0xa0000
	v_pk_mul_f32 v[32:33], v[32:33], v[36:37]
	v_pk_mul_f32 v[34:35], v[28:29], v[40:41]
	v_pk_mul_f32 v[28:29], v[26:27], v[38:39]
	v_cvt_pk_bf16_f32 v26, v30, v31
	v_lshl_add_u64 v[30:31], v[122:123], 0, s[0:1]
	s_mov_b32 s0, 0xa0000
	v_cvt_pk_bf16_f32 v27, v32, v33
	v_add_co_u32_e32 v32, vcc, s0, v122
	v_cvt_pk_bf16_f32 v28, v28, v29
	v_cvt_pk_bf16_f32 v29, v34, v35
	s_waitcnt vmcnt(6)
	v_lshlrev_b32_e32 v34, 16, v97
	v_addc_co_u32_e32 v33, vcc, 0, v123, vcc
	global_store_dwordx4 v[32:33], v[26:29], off
	v_lshlrev_b32_e32 v32, 16, v96
	v_and_b32_e32 v33, 0xffff0000, v96
	v_lshlrev_b32_e32 v26, 16, v94
	v_and_b32_e32 v27, 0xffff0000, v94
	v_lshlrev_b32_e32 v28, 16, v95
	v_and_b32_e32 v29, 0xffff0000, v95
	v_and_b32_e32 v35, 0xffff0000, v97
	v_pk_mul_f32 v[24:25], v[24:25], v[28:29]
	v_pk_mul_f32 v[22:23], v[22:23], v[26:27]
	v_pk_mul_f32 v[26:27], v[20:21], v[34:35]
	v_pk_mul_f32 v[20:21], v[18:19], v[32:33]
	v_cvt_pk_bf16_f32 v18, v22, v23
	v_cvt_pk_bf16_f32 v19, v24, v25
	s_waitcnt vmcnt(6)
	v_lshlrev_b32_e32 v22, 16, v72
	v_cvt_pk_bf16_f32 v20, v20, v21
	v_cvt_pk_bf16_f32 v21, v26, v27
	global_store_dwordx4 v[30:31], v[18:21], off offset:256
	v_and_b32_e32 v23, 0xffff0000, v72
	v_lshlrev_b32_e32 v24, 16, v73
	v_lshlrev_b32_e32 v18, 16, v70
	v_and_b32_e32 v19, 0xffff0000, v70
	v_lshlrev_b32_e32 v20, 16, v71
	v_and_b32_e32 v21, 0xffff0000, v71
	v_and_b32_e32 v25, 0xffff0000, v73
	v_pk_mul_f32 v[14:15], v[14:15], v[18:19]
	s_mov_b64 s[0:1], 0xb0000
	v_pk_mul_f32 v[16:17], v[16:17], v[20:21]
	v_pk_mul_f32 v[18:19], v[12:13], v[24:25]
	v_pk_mul_f32 v[12:13], v[10:11], v[22:23]
	v_cvt_pk_bf16_f32 v10, v14, v15
	v_lshl_add_u64 v[14:15], v[122:123], 0, s[0:1]
	s_mov_b32 s0, 0xb0000
	v_cvt_pk_bf16_f32 v11, v16, v17
	v_add_co_u32_e32 v16, vcc, s0, v122
	v_cvt_pk_bf16_f32 v12, v12, v13
	v_cvt_pk_bf16_f32 v13, v18, v19
	s_waitcnt vmcnt(6)
	v_lshlrev_b32_e32 v18, 16, v69
	v_addc_co_u32_e32 v17, vcc, 0, v123, vcc
	global_store_dwordx4 v[16:17], v[10:13], off
	v_lshlrev_b32_e32 v16, 16, v68
	v_and_b32_e32 v17, 0xffff0000, v68
	v_lshlrev_b32_e32 v10, 16, v66
	v_and_b32_e32 v11, 0xffff0000, v66
	v_and_b32_e32 v19, 0xffff0000, v69
	v_lshlrev_b32_e32 v12, 16, v67
	v_and_b32_e32 v13, 0xffff0000, v67
	v_pk_mul_f32 v[6:7], v[6:7], v[10:11]
	v_pk_mul_f32 v[10:11], v[4:5], v[18:19]
	v_pk_mul_f32 v[4:5], v[2:3], v[16:17]
	v_pk_mul_f32 v[8:9], v[8:9], v[12:13]
	v_cvt_pk_bf16_f32 v2, v6, v7
	s_mov_b64 s[0:1], -1
	v_cvt_pk_bf16_f32 v3, v8, v9
	v_cvt_pk_bf16_f32 v4, v4, v5
	v_cvt_pk_bf16_f32 v5, v10, v11
	global_store_dwordx4 v[14:15], v[2:5], off offset:256
	s_andn2_b64 vcc, exec, s[6:7]
	s_cbranch_vccnz .LBB0_1110
	s_andn2_b64 vcc, exec, s[12:13]
	s_cbranch_vccnz .LBB0_1109
	s_branch .LBB0_1109

; #define PG8_WAIT_V(n) asm volatile("s_waitcnt vmcnt(" #n ")" ::: "memory")
; template <class Epi, class Sched, bool ALIGN_EPI = false, bool SP2 = false, bool ABLK = false, bool BBLK = false>
; __device__ __forceinline__ void gemm_phase(PG8_LAS unsigned char* lds, const Gemm g, const Sched& S, const Epi& E) {
;     ...
;     const int tid = tid_, wid = __builtin_amdgcn_readfirstlane(tid >> 6), lane = tid & 63, wr = wid >> 2, wc = wid & 3, fr = lane & 15, fq = lane >> 4;
;     const int K = g.K, nt = K / BK, LDA = g.lda ? g.lda : K, LDB = g.ldb ? g.ldb : K;
;     unsigned voffA[2], voffB[2];
; #pragma unroll
;     for (int i = 0; i < 2; ++i) { int R, C; stage_rc(tid * 16 + i * 8192, R, C); const int Rb = Epi::PERM ? ((R & ~31) + perm32(R & 31)) : R;
;         voffA[i] = ABLK ? (unsigned)(R * BK + C) * 2u : (unsigned)(R * LDA + C) * 2u; voffB[i] = BBLK ? (unsigned)(Rb * BK + C) * 2u : (unsigned)(Rb * LDB + C) * 2u; }
;     const size_t kstep = (size_t)(BK * 2);
;     const size_t hstepa = (size_t)HALF * LDA * 2, hstepb = (size_t)HALF * LDB * 2;
;     const size_t kstepA = ABLK ? (size_t)BM * BK * 2 : kstep, hstepA = ABLK ? (size_t)HALF * BK * 2 : hstepa, tstepA = ABLK ? (size_t)nt * BM * BK * 2 : 2 * hstepa;
;     const size_t kstepB = BBLK ? (size_t)BM * BK * 2 : kstep, hstepB = BBLK ? (size_t)HALF * BK * 2 : hstepb, tstepB = BBLK ? (size_t)nt * BM * BK * 2 : 2 * hstepb;
;     const unsigned ldsw = (unsigned)wid * 1024u;
;     const int aoff = lds_byte(wr * 64 + fr, fq * 8), boff = lds_byte(wc * 32 + fr, fq * 8);
;     ...
;     Unit cur, nxt; int ui = 0;
;     if (!S.next(0, cur)) return;
;     f32x4 acc[2][2][4][2];
; #pragma unroll
;     for (int a = 0; a < 2; ++a)
; #pragma unroll
;         for (int b = 0; b < 2; ++b)
; #pragma unroll
;             for (int m = 0; m < 4; ++m)
; #pragma unroll
;                 for (int n = 0; n < 2; ++n) acc[a][b][m][n] = (f32x4){0.f, 0.f, 0.f, 0.f};
;     bf16x8 At[4][2], B0[2][2], B1[2][2];
;     const char* cA = (const char*)g.A + (size_t)cur.pm * tstepA; const char* cB = (const char*)g.Bt + (size_t)cur.pn * tstepB;
;     S.a_ready(cur);
;     if constexpr (SP2) {
;         PG8_STAGE(PG8_SB(0, 0), cB, voffB); PG8_STAGE(PG8_SB(0, 1), cB + hstepB, voffB); PG8_STAGE(PG8_SA(0, 0), cA, voffA); PG8_STAGE(PG8_SA(0, 1), cA + hstepA, voffA);
;         if (wr == 1) PG8_BAR;
;         PG8_WAIT_V(2); PG8_BAR;
.LBB0_1129:
	v_ashrrev_i32_e32 v3, 31, v6
	v_lshrrev_b32_e32 v3, 26, v3
	v_add_u32_e32 v3, v6, v3
	v_ashrrev_i32_e32 v7, 6, v3
	v_bfe_i32 v3, v6, 27, 1
	v_lshlrev_b32_e32 v2, 4, v6
	v_lshrrev_b32_e32 v3, 22, v3
	v_add_u32_e32 v3, v2, v3
	v_and_b32_e32 v3, 0xfffffc00, v3
	v_sub_u32_e32 v3, v2, v3
	v_lshrrev_b32_e32 v4, 4, v3
	v_bitop3_b32 v3, v4, v3, 32 bitop3:0x6c
	v_ashrrev_i32_e32 v5, 31, v3
	v_lshrrev_b32_e32 v5, 26, v5
	v_add_u32_e32 v5, v3, v5
	v_lshlrev_b32_e32 v4, 3, v7
	v_ashrrev_i32_e32 v8, 6, v5
	v_and_b32_e32 v5, 0xc0, v5
	v_and_b32_e32 v4, -16, v4
	v_sub_u32_e32 v3, v3, v5
	v_add_u32_e32 v4, v8, v4
	v_lshlrev_b32_e32 v9, 5, v7
	v_ashrrev_i16_sdwa v3, v232, sext(v3) dst_sel:DWORD dst_unused:UNUSED_PAD src0_sel:DWORD src1_sel:BYTE_0
	v_and_b32_e32 v10, 32, v9
	v_bfe_i32 v9, v3, 0, 16
	v_lshlrev_b32_e32 v3, 1, v4
	v_lshrrev_b32_e32 v5, 2, v4
	v_and_b32_e32 v11, 3, v8
	s_mov_b32 s0, 0x1ffffe0
	v_and_b32_e32 v3, 24, v3
	v_and_b32_e32 v5, 4, v5
	v_and_or_b32 v11, v4, s0, v11
	v_or3_b32 v3, v11, v5, v3
	v_add_lshl_u32 v5, v10, v9, 1
	v_add_u32_e32 v2, 0x2000, v2
	v_lshl_add_u32 v196, v3, 7, v5
	v_ashrrev_i32_e32 v3, 31, v2
	v_lshrrev_b32_e32 v3, 22, v3
	v_add_u32_e32 v3, v2, v3
	v_ashrrev_i32_e32 v10, 10, v3
	v_mul_i32_i24_e32 v3, 0x400, v10
	v_sub_u32_e32 v2, v2, v3
	v_lshrrev_b32_e32 v3, 4, v2
	v_bitop3_b32 v2, v3, v2, 32 bitop3:0x6c
	s_add_u32 s33, s60, 0xa300000
	v_lshl_add_u32 v186, v4, 11, v5
	v_ashrrev_i32_e32 v4, 31, v2
	s_addc_u32 s44, s61, 0
	s_ashr_i32 s7, s6, 6
	v_lshrrev_b32_e32 v4, 26, v4
	v_lshlrev_b32_e32 v3, 3, v10
	v_add_u32_e32 v4, v2, v4
	s_ashr_i32 s14, s6, 8
	s_lshl_b32 s45, s7, 10
	v_and_b32_e32 v3, -16, v3
	v_ashrrev_i32_e32 v11, 6, v4
	s_add_u32 s46, s60, 0x18600000
	v_add_u32_e32 v3, v11, v3
	v_and_b32_e32 v4, 0xc0, v4
	v_and_b32_e32 v13, 3, v11
	s_addc_u32 s47, s61, 0
	s_ashr_i32 s31, s30, 31
	s_ashr_i32 s29, s28, 31
	v_sub_u32_e32 v2, v2, v4
	v_and_or_b32 v13, v3, s0, v13
	s_lshl_b64 s[12:13], s[30:31], 19
	s_lshl_b64 s[0:1], s[28:29], 19
	v_ashrrev_i16_sdwa v2, v232, sext(v2) dst_sel:DWORD dst_unused:UNUSED_PAD src0_sel:DWORD src1_sel:BYTE_0
	s_add_u32 s0, s33, s0
	v_lshlrev_b32_e32 v5, 5, v10
	v_bfe_i32 v12, v2, 0, 16
	v_lshlrev_b32_e32 v2, 1, v3
	v_lshrrev_b32_e32 v4, 2, v3
	s_addc_u32 s1, s44, s1
	s_add_i32 s29, s45, 0
	v_and_b32_e32 v5, 32, v5
	v_and_b32_e32 v2, 24, v2
	v_and_b32_e32 v4, 4, v4
	s_add_i32 m0, s29, 0x10000
	v_or3_b32 v2, v13, v4, v2
	v_add_lshl_u32 v4, v5, v12, 1
	global_load_lds_dwordx4 v196, s[0:1]
	s_add_i32 m0, s29, 0x12000
	v_lshl_add_u32 v200, v2, 7, v4
	s_add_u32 s18, s0, 0x4000
	global_load_lds_dwordx4 v200, s[0:1]
	s_addc_u32 s19, s1, 0
	s_add_i32 m0, s29, 0x14000
	v_lshl_add_u32 v198, v3, 11, v4
	global_load_lds_dwordx4 v196, s[18:19]
	s_add_i32 m0, s29, 0x16000
	s_add_u32 s34, s46, s12
	s_addc_u32 s35, s47, s13
	s_add_i32 s65, s29, 0x2000
	global_load_lds_dwordx4 v200, s[18:19]
	s_mov_b32 m0, s29
	s_add_u32 s12, s34, 0x40000
	global_load_lds_dwordx4 v186, s[34:35]
	s_mov_b32 m0, s65
	s_addc_u32 s13, s35, 0
	s_add_i32 s68, s29, 0x4000
	global_load_lds_dwordx4 v198, s[34:35]
	s_mov_b32 m0, s68
	s_add_i32 s72, s29, 0x6000
	global_load_lds_dwordx4 v186, s[12:13]
	s_mov_b32 m0, s72
	v_mov_b32_e32 v199, v187
	global_load_lds_dwordx4 v198, s[12:13]
	s_cmp_eq_u32 s14, 1
	v_lshl_add_u64 v[2:3], s[34:35], 0, v[186:187]
	s_cselect_b64 s[12:13], -1, 0
	s_cmp_lg_u32 s14, 1
	v_lshl_add_u64 v[4:5], s[34:35], 0, v[198:199]
	s_cbranch_scc1 .LBB0_1131
.LBB0_1131:
	v_lshrrev_b32_e32 v13, 1, v6
	v_and_b32_e32 v13, 24, v13
	v_and_b32_e32 v222, 15, v6
	v_lshlrev_b32_e32 v14, 1, v13
	v_lshlrev_b32_e32 v6, 2, v6
	s_lshl_b32 s7, s7, 5
	s_lshl_b32 s73, s14, 6
	v_lshl_or_b32 v14, v222, 6, v14
	s_lshl_b32 s14, s14, 13
	v_and_b32_e32 v6, 32, v6
	s_and_b32 s7, s7, 0x60
	v_bitop3_b32 v16, v14, s14, v6 bitop3:0xde
	s_lshl_b32 s14, s7, 7
	v_bitop3_b32 v223, v14, s14, v6 bitop3:0xde
	s_add_u32 s14, s0, 0x8000
	v_mov_b32_e32 v197, v187
	s_addc_u32 s15, s1, 0
	v_mov_b32_e32 v201, v187
	s_add_i32 m0, s29, 0x18000
	v_lshl_add_u64 v[14:15], s[14:15], 0, v[196:197]
	s_waitcnt vmcnt(2)
	s_barrier
	global_load_lds_dwordx4 v[14:15], off
	v_lshl_add_u64 v[14:15], s[14:15], 0, v[200:201]
	s_add_i32 m0, s29, 0x1a000
	s_add_i32 s86, s29, 0x8000
	s_add_i32 s88, s29, 0xa000
	global_load_lds_dwordx4 v[14:15], off
	v_lshl_add_u64 v[2:3], v[2:3], 0, s[62:63]
	s_mov_b32 m0, s86
	s_add_u32 s14, s0, 0xc000
	global_load_lds_dwordx4 v[2:3], off
	v_lshl_add_u64 v[2:3], v[4:5], 0, s[62:63]
	s_mov_b32 m0, s88
	s_addc_u32 s15, s1, 0
	global_load_lds_dwordx4 v[2:3], off
	s_add_i32 m0, s29, 0x1c000
	v_lshl_add_u64 v[2:3], s[14:15], 0, v[196:197]
	global_load_lds_dwordx4 v[2:3], off
	v_lshl_add_u64 v[2:3], s[14:15], 0, v[200:201]
	s_add_i32 m0, s29, 0x1e000
	s_cmpk_lt_u32 s6, 0x100
	global_load_lds_dwordx4 v[2:3], off
	v_lshlrev_b32_e32 v2, 14, v7
	v_and_b32_e32 v2, 0xffff8000, v2
	v_lshl_add_u32 v2, v8, 11, v2
	v_and_b32_e32 v3, 1, v7
	v_lshl_or_b32 v2, v3, 6, v2
	v_lshl_add_u32 v202, v9, 1, v2
	v_lshlrev_b32_e32 v2, 14, v10
	v_and_b32_e32 v2, 0xffff8000, v2
	s_waitcnt vmcnt(6)
	s_cselect_b64 s[14:15], -1, 0
	s_ashr_i32 s89, s73, 31
	v_lshl_add_u32 v2, v11, 11, v2
	v_and_b32_e32 v3, 1, v10
	s_add_u32 s18, s60, 0x2ca01000
	v_lshl_or_b32 v2, v3, 6, v2
	s_addc_u32 s19, s61, 0
	v_or_b32_e32 v224, s7, v13
	v_mov_b32_e32 v203, v187
	v_lshl_add_u32 v204, v12, 1, v2
	v_mov_b32_e32 v205, v187
	s_mov_b32 s21, 0
	v_add_u32_e32 v225, 0, v16
	s_barrier
	s_branch .LBB0_1134

; #define PG8_STAGE(bufoff, gbase, voff) do { _Pragma("unroll") for (int _i = 0; _i < 2; ++_i) \
;         __builtin_amdgcn_global_load_lds((const unsigned*)((const char*)(gbase) + (voff)[_i]), (PG8_LAS unsigned*)(lds + (bufoff) + ldsw + _i * 8192), 16, 0, 0); } while (0)
; #define PG8_LDA(dst, b, h) do { _Pragma("unroll") for (int m = 0; m < 4; ++m) _Pragma("unroll") for (int k = 0; k < 2; ++k) dst[m][k] = *(const PG8_LAS bf16x8*)(lds + PG8_SA(b, h) + aoff + m * 2048 + k * 1024); } while (0)
; #define PG8_LDB(dst, b, h) do { _Pragma("unroll") for (int n = 0; n < 2; ++n) _Pragma("unroll") for (int k = 0; k < 2; ++k) dst[n][k] = *(const PG8_LAS bf16x8*)(lds + PG8_SB(b, h) + boff + n * 2048 + k * 1024); } while (0)
; #define PG8_WAIT_V(n) asm volatile("s_waitcnt vmcnt(" #n ")" ::: "memory")
; #define PG8_BAR __builtin_amdgcn_s_barrier()
; template <class Epi, class Sched, bool ALIGN_EPI = false, bool SP2 = false, bool ABLK = false, bool BBLK = false>
; __device__ __forceinline__ void gemm_phase(PG8_LAS unsigned char* lds, const Gemm g, const Sched& S, const Epi& E) {
;     ...
;         const bool has_next = S.next(ui + 1, nxt);
;         const char* nA = has_next ? (const char*)g.A + (size_t)nxt.pm * tstepA : cA; const char* nB = has_next ? (const char*)g.Bt + (size_t)nxt.pn * tstepB : cB;
;         for (int t = 0; t < nt; t += 2) {
;             const bool last = (t == nt - 2);
;             const char* a1 = cA + (size_t)(t + 1) * kstepA;
;             const char* a2 = last ? nA : cA + (size_t)(t + 2) * kstepA; const char* b2 = last ? nB : cB + (size_t)(t + 2) * kstepB;
;             const char* a3 = a2 + kstepA; const char* b3 = b2 + kstepB;
;             if (last && has_next) S.a_ready(nxt);
;             if constexpr (SP2) {
;             PG8_LDB(B0, 0, 0); PG8_LDB(B1, 0, 1); PG8_SCHED; PG8_LDA(At, 0, 0); PG8_STAGE(PG8_SA(1, 1), a1 + hstepA, voffA);
;             PG8_WAIT_V(8); PG8_WAIT_L(0); PG8_BAR; PG8_MMA(0, 0, At, B0); PG8_MMA(0, 1, At, B1); PG8_BAR; PG8_SCHED;
;     ...
;         for (int a = 0; a < 2; ++a)
; #pragma unroll
;             for (int b = 0; b < 2; ++b)
; #pragma unroll
;                 for (int m = 0; m < 4; ++m)
; #pragma unroll
;                     for (int n = 0; n < 2; ++n) acc[a][b][m][n] = (f32x4){0.f, 0.f, 0.f, 0.f};
;         cur = nxt; cA = nA; cB = nB; ++ui;
;         if constexpr (ALIGN_EPI) { if (wr == 1) PG8_BAR; }
.LBB0_1139:
	s_ashr_i32 s23, s22, 31
	s_lshl_b64 s[24:25], s[22:23], 19
	s_add_u32 s24, s46, s24
	s_addc_u32 s25, s47, s25
	s_and_b64 s[26:27], s[6:7], exec
	s_cselect_b32 s23, s25, s35
	s_cselect_b32 s31, s24, s34
	s_ashr_i32 s21, s20, 31
	s_lshl_b64 s[26:27], s[20:21], 19
	s_add_u32 s26, s33, s26
	s_addc_u32 s27, s44, s27
	s_and_b64 s[36:37], s[6:7], exec
	s_cselect_b32 s21, s27, s1
	s_cselect_b32 s91, s26, s0
	s_add_u32 s92, s0, 0x10000
	s_addc_u32 s93, s1, 0
	s_add_u32 s0, s34, 0x40080
	v_mov_b32_e32 v2, 0
	s_addc_u32 s1, s35, 0
	s_mov_b32 s94, -2
	v_mov_b32_e32 v3, v2
	v_mov_b32_e32 v4, v2
	v_mov_b32_e32 v5, v2
	v_mov_b32_e32 v6, v2
	v_mov_b32_e32 v7, v2
	v_mov_b32_e32 v8, v2
	v_mov_b32_e32 v9, v2
	v_mov_b32_e32 v18, v2
	v_mov_b32_e32 v19, v2
	v_mov_b32_e32 v20, v2
	v_mov_b32_e32 v21, v2
	v_mov_b32_e32 v22, v2
	v_mov_b32_e32 v23, v2
	v_mov_b32_e32 v24, v2
	v_mov_b32_e32 v25, v2
	v_mov_b32_e32 v34, v2
	v_mov_b32_e32 v35, v2
	v_mov_b32_e32 v36, v2
	v_mov_b32_e32 v37, v2
	v_mov_b32_e32 v38, v2
	v_mov_b32_e32 v39, v2
	v_mov_b32_e32 v40, v2
	v_mov_b32_e32 v41, v2
	v_mov_b32_e32 v50, v2
	v_mov_b32_e32 v51, v2
	v_mov_b32_e32 v52, v2
	v_mov_b32_e32 v53, v2
	v_mov_b32_e32 v54, v2
	v_mov_b32_e32 v55, v2
	v_mov_b32_e32 v56, v2
	v_mov_b32_e32 v57, v2
	v_mov_b32_e32 v10, v2
	v_mov_b32_e32 v11, v2
	v_mov_b32_e32 v12, v2
	v_mov_b32_e32 v13, v2
	v_mov_b32_e32 v14, v2
	v_mov_b32_e32 v15, v2
	v_mov_b32_e32 v16, v2
	v_mov_b32_e32 v17, v2
	v_mov_b32_e32 v26, v2
	v_mov_b32_e32 v27, v2
	v_mov_b32_e32 v28, v2
	v_mov_b32_e32 v29, v2
	v_mov_b32_e32 v30, v2
	v_mov_b32_e32 v31, v2
	v_mov_b32_e32 v32, v2
	v_mov_b32_e32 v33, v2
	v_mov_b32_e32 v42, v2
	v_mov_b32_e32 v43, v2
	v_mov_b32_e32 v44, v2
	v_mov_b32_e32 v45, v2
	v_mov_b32_e32 v46, v2
	v_mov_b32_e32 v47, v2
	v_mov_b32_e32 v48, v2
	v_mov_b32_e32 v49, v2
	v_mov_b32_e32 v58, v2
	v_mov_b32_e32 v59, v2
	v_mov_b32_e32 v60, v2
	v_mov_b32_e32 v61, v2
	v_mov_b32_e32 v62, v2
	v_mov_b32_e32 v63, v2
	v_mov_b32_e32 v64, v2
	v_mov_b32_e32 v65, v2
	v_mov_b32_e32 v66, v2
	v_mov_b32_e32 v67, v2
	v_mov_b32_e32 v68, v2
	v_mov_b32_e32 v69, v2
	v_mov_b32_e32 v70, v2
	v_mov_b32_e32 v71, v2
	v_mov_b32_e32 v72, v2
	v_mov_b32_e32 v73, v2
	v_mov_b32_e32 v82, v2
	v_mov_b32_e32 v83, v2
	v_mov_b32_e32 v84, v2
	v_mov_b32_e32 v85, v2
	v_mov_b32_e32 v86, v2
	v_mov_b32_e32 v87, v2
	v_mov_b32_e32 v88, v2
	v_mov_b32_e32 v89, v2
	v_mov_b32_e32 v98, v2
	v_mov_b32_e32 v99, v2
	v_mov_b32_e32 v100, v2
	v_mov_b32_e32 v101, v2
	v_mov_b32_e32 v102, v2
	v_mov_b32_e32 v103, v2
	v_mov_b32_e32 v104, v2
	v_mov_b32_e32 v105, v2
	v_mov_b32_e32 v114, v2
	v_mov_b32_e32 v115, v2
	v_mov_b32_e32 v116, v2
	v_mov_b32_e32 v117, v2
	v_mov_b32_e32 v118, v2
	v_mov_b32_e32 v119, v2
	v_mov_b32_e32 v120, v2
	v_mov_b32_e32 v121, v2
	v_mov_b32_e32 v74, v2
	v_mov_b32_e32 v75, v2
	v_mov_b32_e32 v76, v2
	v_mov_b32_e32 v77, v2
	v_mov_b32_e32 v78, v2
	v_mov_b32_e32 v79, v2
	v_mov_b32_e32 v80, v2
	v_mov_b32_e32 v81, v2
	v_mov_b32_e32 v90, v2
	v_mov_b32_e32 v91, v2
	v_mov_b32_e32 v92, v2
	v_mov_b32_e32 v93, v2
	v_mov_b32_e32 v94, v2
	v_mov_b32_e32 v95, v2
	v_mov_b32_e32 v96, v2
	v_mov_b32_e32 v97, v2
	v_mov_b32_e32 v106, v2
	v_mov_b32_e32 v107, v2
	v_mov_b32_e32 v108, v2
	v_mov_b32_e32 v109, v2
	v_mov_b32_e32 v110, v2
	v_mov_b32_e32 v111, v2
	v_mov_b32_e32 v112, v2
	v_mov_b32_e32 v113, v2
	v_mov_b32_e32 v122, v2
	v_mov_b32_e32 v123, v2
	v_mov_b32_e32 v124, v2
	v_mov_b32_e32 v125, v2
	v_mov_b32_e32 v126, v2
	v_mov_b32_e32 v127, v2
	v_mov_b32_e32 v128, v2
	v_mov_b32_e32 v129, v2
	s_and_b64 vcc, exec, s[14:15]
	s_cbranch_vccnz .Lrb_m2
	s_barrier
.Lrb_m2:
.LBB0_1140:
	s_add_u32 s34, s0, 0xfffc0080
	s_addc_u32 s35, s1, -1
	s_add_i32 s52, 0, 0x10000
	s_cmp_eq_u32 s94, 12
	s_cselect_b32 s37, s23, s35
	s_cselect_b32 s36, s31, s34
	s_cselect_b32 s35, s21, s93
	s_cselect_b32 s34, s91, s92
	s_add_i32 s75, 0, 0x14000
	v_add_u32_e32 v142, s52, v223
	v_add_u32_e32 v158, s75, v223
	ds_read_b128 v[130:133], v142
	ds_read_b128 v[134:137], v142 offset:1024
	ds_read_b128 v[138:141], v142 offset:2048
	ds_read_b128 v[142:145], v142 offset:3072
	ds_read_b128 v[146:149], v158
	ds_read_b128 v[150:153], v158 offset:1024
	ds_read_b128 v[154:157], v158 offset:2048
	ds_read_b128 v[158:161], v158 offset:3072
	v_lshl_add_u64 v[188:189], s[0:1], 0, v[202:203]
	s_add_i32 m0, s29, 0xc000
	ds_read_b128 v[162:165], v225
	ds_read_b128 v[166:169], v225 offset:1024
	ds_read_b128 v[170:173], v225 offset:2048
	ds_read_b128 v[174:177], v225 offset:3072
	ds_read_b128 v[178:181], v225 offset:4096
	ds_read_b128 v[182:185], v225 offset:5120
	ds_read_b128 v[206:209], v225 offset:6144
	ds_read_b128 v[210:213], v225 offset:7168
	global_load_lds_dwordx4 v[188:189], off
	v_lshl_add_u64 v[188:189], s[0:1], 0, v[204:205]
	s_add_i32 m0, s29, 0xe000
	s_nop 0
	global_load_lds_dwordx4 v[188:189], off
	s_waitcnt vmcnt(8)
	s_waitcnt lgkmcnt(0)
	s_barrier
; #define PG8_STAGE(bufoff, gbase, voff) do { _Pragma("unroll") for (int _i = 0; _i < 2; ++_i) \
;         __builtin_amdgcn_global_load_lds((const unsigned*)((const char*)(gbase) + (voff)[_i]), (PG8_LAS unsigned*)(lds + (bufoff) + ldsw + _i * 8192), 16, 0, 0); } while (0)
; #define PG8_LDA(dst, b, h) do { _Pragma("unroll") for (int m = 0; m < 4; ++m) _Pragma("unroll") for (int k = 0; k < 2; ++k) dst[m][k] = *(const PG8_LAS bf16x8*)(lds + PG8_SA(b, h) + aoff + m * 2048 + k * 1024); } while (0)
; #define PG8_LDB(dst, b, h) do { _Pragma("unroll") for (int n = 0; n < 2; ++n) _Pragma("unroll") for (int k = 0; k < 2; ++k) dst[n][k] = *(const PG8_LAS bf16x8*)(lds + PG8_SB(b, h) + boff + n * 2048 + k * 1024); } while (0)
; #define PG8_MMA(ai, bj, At, Bt) do { __builtin_amdgcn_s_setprio(1); _Pragma("unroll") for (int m = 0; m < 4; ++m) _Pragma("unroll") for (int n = 0; n < 2; ++n) _Pragma("unroll") for (int k = 0; k < 2; ++k) \
;         acc[ai][bj][m][n] = __builtin_amdgcn_mfma_f32_16x16x32_bf16(Bt[n][k], At[m][k], acc[ai][bj][m][n], 0, 0, 0); __builtin_amdgcn_s_setprio(0); } while (0)
; #define PG8_WAIT_V(n) asm volatile("s_waitcnt vmcnt(" #n ")" ::: "memory")
; #define PG8_WAIT_L(n) asm volatile("s_waitcnt lgkmcnt(" #n ")" ::: "memory")
; #define PG8_BAR __builtin_amdgcn_s_barrier()
; #define PG8_SCHED __builtin_amdgcn_sched_barrier(0)
; template <class Epi, class Sched, bool ALIGN_EPI = false, bool SP2 = false, bool ABLK = false, bool BBLK = false>
; __device__ __forceinline__ void gemm_phase(PG8_LAS unsigned char* lds, const Gemm g, const Sched& S, const Epi& E) {
;     ...
;             PG8_LDB(B0, 0, 0); PG8_LDB(B1, 0, 1); PG8_SCHED; PG8_LDA(At, 0, 0); PG8_STAGE(PG8_SA(1, 1), a1 + hstepA, voffA);
;             PG8_WAIT_V(8); PG8_WAIT_L(0); PG8_BAR; PG8_MMA(0, 0, At, B0); PG8_MMA(0, 1, At, B1); PG8_BAR; PG8_SCHED;
;             PG8_LDA(At, 0, 1); PG8_STAGE(PG8_SB(0, 0), b2, voffB); PG8_STAGE(PG8_SB(0, 1), b2 + hstepB, voffB); PG8_STAGE(PG8_SA(0, 0), a2, voffA);
;             PG8_WAIT_V(8); PG8_WAIT_L(0); PG8_BAR; PG8_MMA(1, 0, At, B0); PG8_MMA(1, 1, At, B1); PG8_BAR; PG8_SCHED;
	s_setprio 1
	s_waitcnt lgkmcnt(0)
	v_mfma_f32_16x16x32_bf16 v[126:129], v[130:133], v[162:165], v[126:129]
	v_mfma_f32_16x16x32_bf16 v[122:125], v[138:141], v[162:165], v[122:125]
	v_mfma_f32_16x16x32_bf16 v[110:113], v[130:133], v[170:173], v[110:113]
	v_mfma_f32_16x16x32_bf16 v[106:109], v[138:141], v[170:173], v[106:109]
	v_mfma_f32_16x16x32_bf16 v[94:97], v[130:133], v[178:181], v[94:97]
	v_mfma_f32_16x16x32_bf16 v[90:93], v[138:141], v[178:181], v[90:93]
	v_mfma_f32_16x16x32_bf16 v[78:81], v[130:133], v[206:209], v[78:81]
	v_mfma_f32_16x16x32_bf16 v[74:77], v[138:141], v[206:209], v[74:77]
	v_mfma_f32_16x16x32_bf16 v[126:129], v[134:137], v[166:169], v[126:129]
	v_mfma_f32_16x16x32_bf16 v[122:125], v[142:145], v[166:169], v[122:125]
	v_mfma_f32_16x16x32_bf16 v[110:113], v[134:137], v[174:177], v[110:113]
	v_mfma_f32_16x16x32_bf16 v[106:109], v[142:145], v[174:177], v[106:109]
	v_mfma_f32_16x16x32_bf16 v[94:97], v[134:137], v[182:185], v[94:97]
	v_mfma_f32_16x16x32_bf16 v[90:93], v[142:145], v[182:185], v[90:93]
	v_mfma_f32_16x16x32_bf16 v[78:81], v[134:137], v[210:213], v[78:81]
	v_mfma_f32_16x16x32_bf16 v[74:77], v[142:145], v[210:213], v[74:77]
	s_setprio 0
	s_setprio 1
	v_mfma_f32_16x16x32_bf16 v[118:121], v[146:149], v[162:165], v[118:121]
	v_mfma_f32_16x16x32_bf16 v[114:117], v[154:157], v[162:165], v[114:117]
	v_mfma_f32_16x16x32_bf16 v[102:105], v[146:149], v[170:173], v[102:105]
	v_mfma_f32_16x16x32_bf16 v[98:101], v[154:157], v[170:173], v[98:101]
	v_mfma_f32_16x16x32_bf16 v[86:89], v[146:149], v[178:181], v[86:89]
	v_mfma_f32_16x16x32_bf16 v[82:85], v[154:157], v[178:181], v[82:85]
	v_mfma_f32_16x16x32_bf16 v[70:73], v[146:149], v[206:209], v[70:73]
	v_mfma_f32_16x16x32_bf16 v[66:69], v[154:157], v[206:209], v[66:69]
	v_mfma_f32_16x16x32_bf16 v[118:121], v[150:153], v[166:169], v[118:121]
	v_mfma_f32_16x16x32_bf16 v[114:117], v[158:161], v[166:169], v[114:117]
	v_mfma_f32_16x16x32_bf16 v[102:105], v[150:153], v[174:177], v[102:105]
	v_mfma_f32_16x16x32_bf16 v[98:101], v[158:161], v[174:177], v[98:101]
	v_mfma_f32_16x16x32_bf16 v[86:89], v[150:153], v[182:185], v[86:89]
	v_mfma_f32_16x16x32_bf16 v[82:85], v[158:161], v[182:185], v[82:85]
	v_mfma_f32_16x16x32_bf16 v[70:73], v[150:153], v[210:213], v[70:73]
	v_mfma_f32_16x16x32_bf16 v[66:69], v[158:161], v[210:213], v[66:69]
	s_setprio 0
	s_barrier
	s_add_i32 s52, s52, s45
	v_lshl_add_u64 v[188:189], s[34:35], 0, v[196:197]
	s_mov_b32 m0, s52
	ds_read_b128 v[162:165], v225 offset:16384
	ds_read_b128 v[166:169], v225 offset:17408
	ds_read_b128 v[170:173], v225 offset:18432
	ds_read_b128 v[174:177], v225 offset:19456
	ds_read_b128 v[178:181], v225 offset:20480
	ds_read_b128 v[182:185], v225 offset:21504
	ds_read_b128 v[206:209], v225 offset:22528
	ds_read_b128 v[210:213], v225 offset:23552
	global_load_lds_dwordx4 v[188:189], off
	s_add_i32 m0, s52, 0x2000
	s_add_u32 s96, s34, 0x4000
	v_lshl_add_u64 v[188:189], s[34:35], 0, v[200:201]
	s_addc_u32 s97, s35, 0
	s_add_i32 s52, s75, s45
	global_load_lds_dwordx4 v[188:189], off
	v_lshl_add_u64 v[188:189], s[96:97], 0, v[196:197]
	s_mov_b32 m0, s52
	v_lshl_add_u64 v[190:191], s[36:37], 0, v[198:199]
	global_load_lds_dwordx4 v[188:189], off
	v_lshl_add_u64 v[188:189], s[96:97], 0, v[200:201]
	s_add_i32 m0, s52, 0x2000
	s_nop 0
	global_load_lds_dwordx4 v[188:189], off
	v_lshl_add_u64 v[188:189], s[36:37], 0, v[186:187]
	s_mov_b32 m0, s29
	s_nop 0
	global_load_lds_dwordx4 v[188:189], off
	s_mov_b32 m0, s65
	s_nop 0
	global_load_lds_dwordx4 v[190:191], off
	s_waitcnt vmcnt(8)
	s_waitcnt lgkmcnt(0)
	s_barrier
	s_setprio 1
	s_waitcnt lgkmcnt(0)
	v_mfma_f32_16x16x32_bf16 v[62:65], v[130:133], v[162:165], v[62:65]
	v_mfma_f32_16x16x32_bf16 v[58:61], v[138:141], v[162:165], v[58:61]
	v_mfma_f32_16x16x32_bf16 v[46:49], v[130:133], v[170:173], v[46:49]
	v_mfma_f32_16x16x32_bf16 v[42:45], v[138:141], v[170:173], v[42:45]
	v_mfma_f32_16x16x32_bf16 v[30:33], v[130:133], v[178:181], v[30:33]
	v_mfma_f32_16x16x32_bf16 v[26:29], v[138:141], v[178:181], v[26:29]
	v_mfma_f32_16x16x32_bf16 v[14:17], v[130:133], v[206:209], v[14:17]
	v_mfma_f32_16x16x32_bf16 v[10:13], v[138:141], v[206:209], v[10:13]
	v_mfma_f32_16x16x32_bf16 v[62:65], v[134:137], v[166:169], v[62:65]
	v_mfma_f32_16x16x32_bf16 v[58:61], v[142:145], v[166:169], v[58:61]
	v_mfma_f32_16x16x32_bf16 v[46:49], v[134:137], v[174:177], v[46:49]
	v_mfma_f32_16x16x32_bf16 v[42:45], v[142:145], v[174:177], v[42:45]
	v_mfma_f32_16x16x32_bf16 v[30:33], v[134:137], v[182:185], v[30:33]
	v_mfma_f32_16x16x32_bf16 v[26:29], v[142:145], v[182:185], v[26:29]
	v_mfma_f32_16x16x32_bf16 v[14:17], v[134:137], v[210:213], v[14:17]
	v_mfma_f32_16x16x32_bf16 v[10:13], v[142:145], v[210:213], v[10:13]
	s_setprio 0
	s_setprio 1
	v_mfma_f32_16x16x32_bf16 v[54:57], v[146:149], v[162:165], v[54:57]
	v_mfma_f32_16x16x32_bf16 v[50:53], v[154:157], v[162:165], v[50:53]
	v_mfma_f32_16x16x32_bf16 v[38:41], v[146:149], v[170:173], v[38:41]
	v_mfma_f32_16x16x32_bf16 v[34:37], v[154:157], v[170:173], v[34:37]
	v_mfma_f32_16x16x32_bf16 v[22:25], v[146:149], v[178:181], v[22:25]
	v_mfma_f32_16x16x32_bf16 v[18:21], v[154:157], v[178:181], v[18:21]
	v_mfma_f32_16x16x32_bf16 v[6:9], v[146:149], v[206:209], v[6:9]
	v_mfma_f32_16x16x32_bf16 v[2:5], v[154:157], v[206:209], v[2:5]
	v_mfma_f32_16x16x32_bf16 v[54:57], v[150:153], v[166:169], v[54:57]
	v_mfma_f32_16x16x32_bf16 v[50:53], v[158:161], v[166:169], v[50:53]
	v_mfma_f32_16x16x32_bf16 v[38:41], v[150:153], v[174:177], v[38:41]
	v_mfma_f32_16x16x32_bf16 v[34:37], v[158:161], v[174:177], v[34:37]
	v_mfma_f32_16x16x32_bf16 v[22:25], v[150:153], v[182:185], v[22:25]
	v_mfma_f32_16x16x32_bf16 v[18:21], v[158:161], v[182:185], v[18:21]
	v_mfma_f32_16x16x32_bf16 v[6:9], v[150:153], v[210:213], v[6:9]
	v_mfma_f32_16x16x32_bf16 v[2:5], v[158:161], v[210:213], v[2:5]
	s_setprio 0
	s_barrier
; #define PG8_STAGE(bufoff, gbase, voff) do { _Pragma("unroll") for (int _i = 0; _i < 2; ++_i) \
;         __builtin_amdgcn_global_load_lds((const unsigned*)((const char*)(gbase) + (voff)[_i]), (PG8_LAS unsigned*)(lds + (bufoff) + ldsw + _i * 8192), 16, 0, 0); } while (0)
; #define PG8_LDA(dst, b, h) do { _Pragma("unroll") for (int m = 0; m < 4; ++m) _Pragma("unroll") for (int k = 0; k < 2; ++k) dst[m][k] = *(const PG8_LAS bf16x8*)(lds + PG8_SA(b, h) + aoff + m * 2048 + k * 1024); } while (0)
; #define PG8_LDB(dst, b, h) do { _Pragma("unroll") for (int n = 0; n < 2; ++n) _Pragma("unroll") for (int k = 0; k < 2; ++k) dst[n][k] = *(const PG8_LAS bf16x8*)(lds + PG8_SB(b, h) + boff + n * 2048 + k * 1024); } while (0)
; #define PG8_MMA(ai, bj, At, Bt) do { __builtin_amdgcn_s_setprio(1); _Pragma("unroll") for (int m = 0; m < 4; ++m) _Pragma("unroll") for (int n = 0; n < 2; ++n) _Pragma("unroll") for (int k = 0; k < 2; ++k) \
;         acc[ai][bj][m][n] = __builtin_amdgcn_mfma_f32_16x16x32_bf16(Bt[n][k], At[m][k], acc[ai][bj][m][n], 0, 0, 0); __builtin_amdgcn_s_setprio(0); } while (0)
; #define PG8_WAIT_V(n) asm volatile("s_waitcnt vmcnt(" #n ")" ::: "memory")
; #define PG8_WAIT_L(n) asm volatile("s_waitcnt lgkmcnt(" #n ")" ::: "memory")
; #define PG8_BAR __builtin_amdgcn_s_barrier()
; #define PG8_SCHED __builtin_amdgcn_sched_barrier(0)
; template <class Epi, class Sched, bool ALIGN_EPI = false, bool SP2 = false, bool ABLK = false, bool BBLK = false>
; __device__ __forceinline__ void gemm_phase(PG8_LAS unsigned char* lds, const Gemm g, const Sched& S, const Epi& E) {
;     ...
;             PG8_LDB(B0, 1, 0); PG8_LDB(B1, 1, 1); PG8_SCHED; PG8_LDA(At, 1, 0); PG8_STAGE(PG8_SA(0, 1), a2 + hstepA, voffA);
;             PG8_WAIT_V(8); PG8_WAIT_L(0); PG8_BAR; PG8_MMA(0, 0, At, B0); PG8_MMA(0, 1, At, B1); PG8_BAR; PG8_SCHED;
;             PG8_LDA(At, 1, 1); PG8_STAGE(PG8_SB(1, 0), b3, voffB); PG8_STAGE(PG8_SB(1, 1), b3 + hstepB, voffB); PG8_STAGE(PG8_SA(1, 0), a3, voffA);
	s_add_i32 s52, 0, 0x18000
	s_add_i32 s75, 0, 0x1c000
	v_add_u32_e32 v142, s52, v223
	v_add_u32_e32 v158, s75, v223
	ds_read_b128 v[130:133], v142
	ds_read_b128 v[134:137], v142 offset:1024
	ds_read_b128 v[138:141], v142 offset:2048
	ds_read_b128 v[142:145], v142 offset:3072
	ds_read_b128 v[146:149], v158
	ds_read_b128 v[150:153], v158 offset:1024
	ds_read_b128 v[154:157], v158 offset:2048
	ds_read_b128 v[158:161], v158 offset:3072
	s_add_u32 s36, s36, 0x40000
	s_addc_u32 s37, s37, 0
	s_mov_b32 m0, s68
	v_lshl_add_u64 v[192:193], s[36:37], 0, v[186:187]
	ds_read_b128 v[162:165], v225 offset:32768
	ds_read_b128 v[166:169], v225 offset:33792
	ds_read_b128 v[170:173], v225 offset:34816
	ds_read_b128 v[174:177], v225 offset:35840
	ds_read_b128 v[178:181], v225 offset:36864
	ds_read_b128 v[182:185], v225 offset:37888
	ds_read_b128 v[206:209], v225 offset:38912
	ds_read_b128 v[210:213], v225 offset:39936
	global_load_lds_dwordx4 v[192:193], off
	v_lshl_add_u64 v[192:193], s[36:37], 0, v[198:199]
	s_mov_b32 m0, s72
	s_nop 0
	global_load_lds_dwordx4 v[192:193], off
	s_waitcnt vmcnt(8)
	s_waitcnt lgkmcnt(0)
	s_barrier
	s_setprio 1
	s_waitcnt lgkmcnt(0)
	v_mfma_f32_16x16x32_bf16 v[126:129], v[130:133], v[162:165], v[126:129]
	v_mfma_f32_16x16x32_bf16 v[122:125], v[138:141], v[162:165], v[122:125]
	v_mfma_f32_16x16x32_bf16 v[110:113], v[130:133], v[170:173], v[110:113]
	v_mfma_f32_16x16x32_bf16 v[106:109], v[138:141], v[170:173], v[106:109]
	v_mfma_f32_16x16x32_bf16 v[94:97], v[130:133], v[178:181], v[94:97]
	v_mfma_f32_16x16x32_bf16 v[90:93], v[138:141], v[178:181], v[90:93]
	v_mfma_f32_16x16x32_bf16 v[78:81], v[130:133], v[206:209], v[78:81]
	v_mfma_f32_16x16x32_bf16 v[74:77], v[138:141], v[206:209], v[74:77]
	v_mfma_f32_16x16x32_bf16 v[126:129], v[134:137], v[166:169], v[126:129]
	v_mfma_f32_16x16x32_bf16 v[122:125], v[142:145], v[166:169], v[122:125]
	v_mfma_f32_16x16x32_bf16 v[110:113], v[134:137], v[174:177], v[110:113]
	v_mfma_f32_16x16x32_bf16 v[106:109], v[142:145], v[174:177], v[106:109]
	v_mfma_f32_16x16x32_bf16 v[94:97], v[134:137], v[182:185], v[94:97]
	v_mfma_f32_16x16x32_bf16 v[90:93], v[142:145], v[182:185], v[90:93]
	v_mfma_f32_16x16x32_bf16 v[78:81], v[134:137], v[210:213], v[78:81]
	v_mfma_f32_16x16x32_bf16 v[74:77], v[142:145], v[210:213], v[74:77]
	s_setprio 0
	s_setprio 1
	v_mfma_f32_16x16x32_bf16 v[118:121], v[146:149], v[162:165], v[118:121]
	v_mfma_f32_16x16x32_bf16 v[114:117], v[154:157], v[162:165], v[114:117]
	v_mfma_f32_16x16x32_bf16 v[102:105], v[146:149], v[170:173], v[102:105]
	v_mfma_f32_16x16x32_bf16 v[98:101], v[154:157], v[170:173], v[98:101]
	v_mfma_f32_16x16x32_bf16 v[86:89], v[146:149], v[178:181], v[86:89]
	v_mfma_f32_16x16x32_bf16 v[82:85], v[154:157], v[178:181], v[82:85]
	v_mfma_f32_16x16x32_bf16 v[70:73], v[146:149], v[206:209], v[70:73]
	v_mfma_f32_16x16x32_bf16 v[66:69], v[154:157], v[206:209], v[66:69]
	v_mfma_f32_16x16x32_bf16 v[118:121], v[150:153], v[166:169], v[118:121]
	v_mfma_f32_16x16x32_bf16 v[114:117], v[158:161], v[166:169], v[114:117]
	v_mfma_f32_16x16x32_bf16 v[102:105], v[150:153], v[174:177], v[102:105]
	v_mfma_f32_16x16x32_bf16 v[98:101], v[158:161], v[174:177], v[98:101]
	v_mfma_f32_16x16x32_bf16 v[86:89], v[150:153], v[182:185], v[86:89]
	v_mfma_f32_16x16x32_bf16 v[82:85], v[158:161], v[182:185], v[82:85]
	v_mfma_f32_16x16x32_bf16 v[70:73], v[150:153], v[210:213], v[70:73]
	v_mfma_f32_16x16x32_bf16 v[66:69], v[158:161], v[210:213], v[66:69]
	s_setprio 0
	s_barrier
	s_add_u32 s36, s34, 0x8000
	s_addc_u32 s37, s35, 0
	s_add_i32 s52, s52, s45
	v_lshl_add_u64 v[192:193], s[36:37], 0, v[196:197]
	s_mov_b32 m0, s52
	ds_read_b128 v[162:165], v225 offset:49152
	ds_read_b128 v[166:169], v225 offset:50176
	ds_read_b128 v[170:173], v225 offset:51200
	ds_read_b128 v[174:177], v225 offset:52224
	ds_read_b128 v[178:181], v225 offset:53248
	ds_read_b128 v[182:185], v225 offset:54272
	ds_read_b128 v[206:209], v225 offset:55296
	ds_read_b128 v[210:213], v225 offset:56320
	global_load_lds_dwordx4 v[192:193], off
	s_add_i32 m0, s52, 0x2000
	s_add_u32 s34, s34, 0xc000
	v_lshl_add_u64 v[192:193], s[36:37], 0, v[200:201]
	s_addc_u32 s35, s35, 0
	s_add_i32 s36, s75, s45
	global_load_lds_dwordx4 v[192:193], off
	v_lshl_add_u64 v[192:193], s[34:35], 0, v[196:197]
	s_mov_b32 m0, s36
	v_lshl_add_u64 v[188:189], v[188:189], 0, s[62:63]
	global_load_lds_dwordx4 v[192:193], off
	v_lshl_add_u64 v[192:193], s[34:35], 0, v[200:201]
	s_add_i32 m0, s36, 0x2000
	s_nop 0
	global_load_lds_dwordx4 v[192:193], off
	s_mov_b32 m0, s86
	s_nop 0
	global_load_lds_dwordx4 v[188:189], off
	v_lshl_add_u64 v[188:189], v[190:191], 0, s[62:63]
	s_mov_b32 m0, s88
	s_nop 0
	global_load_lds_dwordx4 v[188:189], off
	s_waitcnt vmcnt(8)
	s_waitcnt lgkmcnt(0)
	s_barrier
; #define PG8_WAIT_V(n) asm volatile("s_waitcnt vmcnt(" #n ")" ::: "memory")
;     __device__ __forceinline__ void operator()(const f32x4 (&acc)[2][2][4][2], const Unit& u, int wr, int wc, int fr_, int fq) const {
;     ...
;         const size_t row0 = (size_t)u.pm * BM + wr * 64 + fr; const int col0 = u.pn * BM + wc * 32 + 8 * fq;
; #pragma unroll
;         for (int ai = 0; ai < 2; ++ai) {
;             u32x4 gw[4][2], ow[4][2];
; #pragma unroll
;             for (int m = 0; m < 4; ++m)
; #pragma unroll
; template <class Epi, class Sched, bool ALIGN_EPI = false, bool SP2 = false, bool ABLK = false, bool BBLK = false>
; __device__ __forceinline__ void gemm_phase(PG8_LAS unsigned char* lds, const Gemm g, const Sched& S, const Epi& E) {
;     ...
;             PG8_LDA(At, 1, 1); PG8_STAGE(PG8_SB(1, 0), b3, voffB); PG8_STAGE(PG8_SB(1, 1), b3 + hstepB, voffB); PG8_STAGE(PG8_SA(1, 0), a3, voffA);
;             PG8_WAIT_V(8); PG8_WAIT_L(0); PG8_BAR; PG8_MMA(1, 0, At, B0); PG8_MMA(1, 1, At, B1); PG8_BAR; PG8_SCHED;
;             } else {
;             PG8_LDB(B0, 0, 0); PG8_SCHED; PG8_LDA(At, 0, 0); PG8_STAGE(PG8_SA(1, 1), a1 + hstepA, voffA);
;             PG8_WAIT_L(8); PG8_BAR; PG8_WAIT_L(0); PG8_MMA(0, 0, At, B0); PG8_BAR; PG8_SCHED;
;             PG8_LDB(B1, 0, 1); PG8_STAGE(PG8_SB(0, 0), b2, voffB);
;             PG8_BAR; PG8_WAIT_L(0); PG8_MMA(0, 1, At, B1); PG8_BAR;
;             PG8_LDA(At, 0, 1); PG8_STAGE(PG8_SA(0, 0), a2, voffA);
;             PG8_BAR; PG8_WAIT_L(0); PG8_MMA(1, 0, At, B0); PG8_BAR; PG8_SCHED;
;             PG8_STAGE(PG8_SB(0, 1), b2 + hstepB, voffB);
;             PG8_WAIT_V(6); PG8_BAR; PG8_MMA(1, 1, At, B1); PG8_BAR;
;             PG8_LDB(B0, 1, 0); PG8_SCHED; PG8_LDA(At, 1, 0); PG8_STAGE(PG8_SA(0, 1), a2 + hstepA, voffA);
;             PG8_WAIT_L(8); PG8_BAR; PG8_WAIT_L(0); PG8_MMA(0, 0, At, B0); PG8_BAR; PG8_SCHED;
;             PG8_LDB(B1, 1, 1); PG8_STAGE(PG8_SB(1, 0), b3, voffB);
;             PG8_BAR; PG8_WAIT_L(0); PG8_MMA(0, 1, At, B1); PG8_BAR;
;             PG8_LDA(At, 1, 1); PG8_STAGE(PG8_SA(1, 0), a3, voffA);
;             PG8_BAR; PG8_WAIT_L(0); PG8_MMA(1, 0, At, B0); PG8_BAR; PG8_SCHED;
;             PG8_STAGE(PG8_SB(1, 1), b3 + hstepB, voffB);
;             PG8_WAIT_V(6); PG8_BAR; PG8_MMA(1, 1, At, B1); PG8_BAR;
;             }
;         }
;         if constexpr (ALIGN_EPI) { if (wr == 0) PG8_BAR; }
	s_setprio 1
	s_waitcnt lgkmcnt(0)
	v_mfma_f32_16x16x32_bf16 v[62:65], v[130:133], v[162:165], v[62:65]
	v_mfma_f32_16x16x32_bf16 v[58:61], v[138:141], v[162:165], v[58:61]
	v_mfma_f32_16x16x32_bf16 v[46:49], v[130:133], v[170:173], v[46:49]
	v_mfma_f32_16x16x32_bf16 v[42:45], v[138:141], v[170:173], v[42:45]
	v_mfma_f32_16x16x32_bf16 v[30:33], v[130:133], v[178:181], v[30:33]
	v_mfma_f32_16x16x32_bf16 v[26:29], v[138:141], v[178:181], v[26:29]
	v_mfma_f32_16x16x32_bf16 v[14:17], v[130:133], v[206:209], v[14:17]
	v_mfma_f32_16x16x32_bf16 v[10:13], v[138:141], v[206:209], v[10:13]
	v_mfma_f32_16x16x32_bf16 v[62:65], v[134:137], v[166:169], v[62:65]
	v_mfma_f32_16x16x32_bf16 v[58:61], v[142:145], v[166:169], v[58:61]
	v_mfma_f32_16x16x32_bf16 v[46:49], v[134:137], v[174:177], v[46:49]
	v_mfma_f32_16x16x32_bf16 v[42:45], v[142:145], v[174:177], v[42:45]
	v_mfma_f32_16x16x32_bf16 v[30:33], v[134:137], v[182:185], v[30:33]
	v_mfma_f32_16x16x32_bf16 v[26:29], v[142:145], v[182:185], v[26:29]
	v_mfma_f32_16x16x32_bf16 v[14:17], v[134:137], v[210:213], v[14:17]
	v_mfma_f32_16x16x32_bf16 v[10:13], v[142:145], v[210:213], v[10:13]
	s_setprio 0
	s_setprio 1
	v_mfma_f32_16x16x32_bf16 v[54:57], v[146:149], v[162:165], v[54:57]
	v_mfma_f32_16x16x32_bf16 v[50:53], v[154:157], v[162:165], v[50:53]
	v_mfma_f32_16x16x32_bf16 v[38:41], v[146:149], v[170:173], v[38:41]
	v_mfma_f32_16x16x32_bf16 v[34:37], v[154:157], v[170:173], v[34:37]
	v_mfma_f32_16x16x32_bf16 v[22:25], v[146:149], v[178:181], v[22:25]
	v_mfma_f32_16x16x32_bf16 v[18:21], v[154:157], v[178:181], v[18:21]
	v_mfma_f32_16x16x32_bf16 v[6:9], v[146:149], v[206:209], v[6:9]
	v_mfma_f32_16x16x32_bf16 v[2:5], v[154:157], v[206:209], v[2:5]
	v_mfma_f32_16x16x32_bf16 v[54:57], v[150:153], v[166:169], v[54:57]
	v_mfma_f32_16x16x32_bf16 v[50:53], v[158:161], v[166:169], v[50:53]
	v_mfma_f32_16x16x32_bf16 v[38:41], v[150:153], v[174:177], v[38:41]
	v_mfma_f32_16x16x32_bf16 v[34:37], v[158:161], v[174:177], v[34:37]
	v_mfma_f32_16x16x32_bf16 v[22:25], v[150:153], v[182:185], v[22:25]
	v_mfma_f32_16x16x32_bf16 v[18:21], v[158:161], v[182:185], v[18:21]
	v_mfma_f32_16x16x32_bf16 v[6:9], v[150:153], v[210:213], v[6:9]
	v_mfma_f32_16x16x32_bf16 v[2:5], v[158:161], v[210:213], v[2:5]
	s_setprio 0
	s_barrier
	s_add_i32 s94, s94, 2
	s_add_u32 s92, s92, 0x10000
	s_addc_u32 s93, s93, 0
	s_add_u32 s0, s0, 0x100
	s_addc_u32 s1, s1, 0
	s_cmp_gt_u32 s94, 13
	s_cbranch_scc0 .LBB0_1140
	s_and_b64 vcc, exec, s[14:15]
	s_cbranch_vccz .LBB0_1143
	s_barrier
.LBB0_1143:
	s_ashr_i32 s31, s30, 31
	s_lshl_b64 s[0:1], s[30:31], 8
	v_mov_b32_e32 v130, v222
	s_add_u32 s0, s0, s73
	s_addc_u32 s1, s1, s89
	v_ashrrev_i32_e32 v131, 31, v130
	v_lshl_add_u64 v[130:131], s[0:1], 0, v[130:131]
	v_lshl_or_b32 v132, s28, 8, v224
	v_mov_b64_e32 v[134:135], s[18:19]
	s_movk_i32 s21, 0x3000
	v_ashrrev_i32_e32 v133, 31, v132
	v_mad_u64_u32 v[134:135], s[0:1], v130, s21, v[134:135]
	v_mad_i32_i24 v135, v131, s21, v135
	v_lshlrev_b64 v[132:133], 1, v[132:133]
	v_lshlrev_b64 v[130:131], 12, v[130:131]
	v_lshl_add_u64 v[206:207], v[134:135], 0, v[132:133]
	v_lshl_add_u64 v[130:131], s[2:3], 0, v[130:131]
	global_load_dwordx4 v[226:229], v[206:207], off
	v_lshl_add_u64 v[208:209], v[130:131], 0, v[132:133]
	global_load_dwordx4 v[244:247], v[208:209], off
	global_load_dwordx4 v[182:185], v[206:207], off offset:256
	global_load_dwordx4 v[178:181], v[208:209], off offset:256
	s_mov_b32 s91, 0x30000
	v_add_co_u32_e32 v132, vcc, s91, v206
	s_mov_b64 s[30:31], 0x30000
	s_nop 0
	v_addc_co_u32_e32 v133, vcc, 0, v207, vcc
	global_load_dwordx4 v[170:173], v[132:133], off
	v_add_co_u32_e32 v220, vcc, s80, v208
	v_lshl_add_u64 v[130:131], v[206:207], 0, s[30:31]
	s_nop 0
	v_addc_co_u32_e32 v221, vcc, 0, v209, vcc
	v_lshl_add_u64 v[218:219], v[208:209], 0, s[48:49]
	global_load_dwordx4 v[174:177], v[220:221], off
	global_load_dwordx4 v[166:169], v[130:131], off offset:256
	global_load_dwordx4 v[162:165], v[218:219], off offset:256
	s_mov_b32 s94, 0x60000
	v_add_co_u32_e32 v132, vcc, s94, v206
	s_mov_b64 s[0:1], 0x60000
	s_nop 0
	v_addc_co_u32_e32 v133, vcc, 0, v207, vcc
	global_load_dwordx4 v[154:157], v[132:133], off
	v_add_co_u32_e32 v216, vcc, s95, v208
	v_lshl_add_u64 v[130:131], v[206:207], 0, s[0:1]
	s_mov_b64 s[0:1], 0x20000
	v_addc_co_u32_e32 v217, vcc, 0, v209, vcc
	v_lshl_add_u64 v[214:215], v[208:209], 0, s[0:1]
	global_load_dwordx4 v[158:161], v[216:217], off
	global_load_dwordx4 v[150:153], v[130:131], off offset:256
	global_load_dwordx4 v[146:149], v[214:215], off offset:256
	s_mov_b32 s0, 0x90000
	v_add_co_u32_e32 v132, vcc, s0, v206
	s_mov_b64 s[34:35], 0x90000
	s_nop 0
	v_addc_co_u32_e32 v133, vcc, 0, v207, vcc
	global_load_dwordx4 v[138:141], v[132:133], off
	v_add_co_u32_e32 v212, vcc, s91, v208
	v_lshl_add_u64 v[130:131], v[206:207], 0, s[34:35]
	s_nop 0
	v_addc_co_u32_e32 v213, vcc, 0, v209, vcc
	v_lshl_add_u64 v[210:211], v[208:209], 0, s[30:31]
	global_load_dwordx4 v[142:145], v[212:213], off
	global_load_dwordx4 v[134:137], v[130:131], off offset:256
	s_nop 0
	global_load_dwordx4 v[130:133], v[210:211], off offset:256
	s_mov_b32 s1, 0x180000
	s_mov_b32 s52, 0x80000
	s_mov_b64 s[30:31], 0x180000
	s_waitcnt vmcnt(0)
; __device__ __forceinline__ u32x4 pack8(const f32x4 v0, const f32x4 v1) { u32x4 w; w.x = cvt_pk_bf16(v0[0], v0[1]); w.y = cvt_pk_bf16(v0[2], v0[3]); w.z = cvt_pk_bf16(v1[0], v1[1]); w.w = cvt_pk_bf16(v1[2], v1[3]); return w; }
;     __device__ __forceinline__ void operator()(const f32x4 (&acc)[2][2][4][2], const Unit& u, int wr, int wc, int fr_, int fq) const {
;     ...
;         const size_t row0 = (size_t)u.pm * BM + wr * 64 + fr; const int col0 = u.pn * BM + wc * 32 + 8 * fq;
; #pragma unroll
;         for (int ai = 0; ai < 2; ++ai) {
;             u32x4 gw[4][2], ow[4][2];
; #pragma unroll
;             for (int m = 0; m < 4; ++m)
; #pragma unroll
;                 for (int bj = 0; bj < 2; ++bj) { const size_t r = row0 + ai * HALF + m * 16; const int c = col0 + bj * HALF;
;                     gw[m][bj] = *(const u32x4*)(G + r * 6144 + goff + c); if (!FIRST) ow[m][bj] = *(const u32x4*)(Mo + r * DM + c); }
; #pragma unroll
;             for (int m = 0; m < 4; ++m)
; #pragma unroll
;                 for (int bj = 0; bj < 2; ++bj) { const size_t r = row0 + ai * HALF + m * 16; const int c = col0 + bj * HALF;
;                     f32x4 g0, g1; unpack8(gw[m][bj], g0, g1);
;                     f32x4 v0 = g0 * acc[ai][bj][m][0], v1 = g1 * acc[ai][bj][m][1];
;                     if (!FIRST) { f32x4 o0, o1; unpack8(ow[m][bj], o0, o1); v0 += o0; v1 += o1; }
;                     *(u32x4*)((Mdst ? Mdst : Mo) + r * DM + c) = pack8(v0, v1); }
;             asm volatile("" ::: "memory"); }
	v_lshlrev_b32_e32 v248, 16, v246
	v_lshlrev_b32_e32 v188, 16, v226
	v_and_b32_e32 v189, 0xffff0000, v226
	v_lshlrev_b32_e32 v190, 16, v227
	v_and_b32_e32 v191, 0xffff0000, v227
	v_lshlrev_b32_e32 v192, 16, v228
	v_and_b32_e32 v193, 0xffff0000, v228
	v_lshlrev_b32_e32 v226, 16, v229
	v_and_b32_e32 v227, 0xffff0000, v229
	v_lshlrev_b32_e32 v228, 16, v244
	v_and_b32_e32 v229, 0xffff0000, v244
	v_and_b32_e32 v249, 0xffff0000, v246
	v_lshlrev_b32_e32 v246, 16, v247
	v_and_b32_e32 v247, 0xffff0000, v247
	v_lshlrev_b32_e32 v244, 16, v245
	v_and_b32_e32 v245, 0xffff0000, v245
	v_pk_fma_f32 v[126:127], v[126:127], v[188:189], v[228:229]
	v_pk_fma_f32 v[188:189], v[124:125], v[226:227], v[246:247]
	v_pk_fma_f32 v[124:125], v[122:123], v[192:193], v[248:249]
	v_pk_fma_f32 v[128:129], v[128:129], v[190:191], v[244:245]
	v_cvt_pk_bf16_f32 v122, v126, v127
	v_lshlrev_b32_e32 v126, 16, v184
	v_cvt_pk_bf16_f32 v123, v128, v129
	v_cvt_pk_bf16_f32 v124, v124, v125
	v_cvt_pk_bf16_f32 v125, v188, v189
	global_store_dwordx4 v[208:209], v[122:125], off
	v_and_b32_e32 v127, 0xffff0000, v184
	v_lshlrev_b32_e32 v128, 16, v185
	v_lshlrev_b32_e32 v122, 16, v182
	v_and_b32_e32 v123, 0xffff0000, v182
	v_lshlrev_b32_e32 v124, 16, v183
	v_and_b32_e32 v125, 0xffff0000, v183
	v_and_b32_e32 v129, 0xffff0000, v185
	v_lshlrev_b32_e32 v182, 16, v178
	v_and_b32_e32 v183, 0xffff0000, v178
	v_lshlrev_b32_e32 v184, 16, v180
	v_and_b32_e32 v185, 0xffff0000, v180
	v_lshlrev_b32_e32 v180, 16, v181
	v_and_b32_e32 v181, 0xffff0000, v181
	v_lshlrev_b32_e32 v178, 16, v179
	v_and_b32_e32 v179, 0xffff0000, v179
	v_pk_fma_f32 v[118:119], v[118:119], v[122:123], v[182:183]
	v_pk_fma_f32 v[122:123], v[116:117], v[128:129], v[180:181]
	v_pk_fma_f32 v[116:117], v[114:115], v[126:127], v[184:185]
	v_pk_fma_f32 v[120:121], v[120:121], v[124:125], v[178:179]
	v_cvt_pk_bf16_f32 v114, v118, v119
	v_lshlrev_b32_e32 v118, 16, v172
	v_cvt_pk_bf16_f32 v115, v120, v121
	v_cvt_pk_bf16_f32 v116, v116, v117
	v_cvt_pk_bf16_f32 v117, v122, v123
	global_store_dwordx4 v[208:209], v[114:117], off offset:256
	v_and_b32_e32 v119, 0xffff0000, v172
	v_lshlrev_b32_e32 v120, 16, v173
	v_lshlrev_b32_e32 v114, 16, v170
	v_and_b32_e32 v115, 0xffff0000, v170
	v_lshlrev_b32_e32 v116, 16, v171
	v_and_b32_e32 v117, 0xffff0000, v171
	v_and_b32_e32 v121, 0xffff0000, v173
	v_lshlrev_b32_e32 v122, 16, v174
	v_and_b32_e32 v123, 0xffff0000, v174
	v_lshlrev_b32_e32 v124, 16, v175
	v_and_b32_e32 v125, 0xffff0000, v175
	v_lshlrev_b32_e32 v126, 16, v176
	v_and_b32_e32 v127, 0xffff0000, v176
	v_lshlrev_b32_e32 v128, 16, v177
	v_and_b32_e32 v129, 0xffff0000, v177
	v_pk_fma_f32 v[112:113], v[112:113], v[116:117], v[124:125]
	v_pk_fma_f32 v[110:111], v[110:111], v[114:115], v[122:123]
	v_pk_fma_f32 v[114:115], v[108:109], v[120:121], v[128:129]
	v_pk_fma_f32 v[108:109], v[106:107], v[118:119], v[126:127]
	v_cvt_pk_bf16_f32 v106, v110, v111
	v_cvt_pk_bf16_f32 v107, v112, v113
	v_lshlrev_b32_e32 v110, 16, v168
	v_cvt_pk_bf16_f32 v108, v108, v109
	v_cvt_pk_bf16_f32 v109, v114, v115
	global_store_dwordx4 v[220:221], v[106:109], off
	v_and_b32_e32 v111, 0xffff0000, v168
	v_lshlrev_b32_e32 v112, 16, v169
	v_lshlrev_b32_e32 v106, 16, v166
	v_and_b32_e32 v107, 0xffff0000, v166
	v_and_b32_e32 v113, 0xffff0000, v169
	v_lshlrev_b32_e32 v114, 16, v162
	v_and_b32_e32 v115, 0xffff0000, v162
	v_lshlrev_b32_e32 v118, 16, v164
	v_and_b32_e32 v119, 0xffff0000, v164
	v_lshlrev_b32_e32 v120, 16, v165
	v_and_b32_e32 v121, 0xffff0000, v165
	v_lshlrev_b32_e32 v108, 16, v167
	v_and_b32_e32 v109, 0xffff0000, v167
	v_lshlrev_b32_e32 v116, 16, v163
	v_and_b32_e32 v117, 0xffff0000, v163
	v_pk_fma_f32 v[102:103], v[102:103], v[106:107], v[114:115]
	v_pk_fma_f32 v[106:107], v[100:101], v[112:113], v[120:121]
	v_pk_fma_f32 v[100:101], v[98:99], v[110:111], v[118:119]
	v_pk_fma_f32 v[104:105], v[104:105], v[108:109], v[116:117]
	v_cvt_pk_bf16_f32 v98, v102, v103
	v_lshlrev_b32_e32 v102, 16, v156
	v_cvt_pk_bf16_f32 v99, v104, v105
	v_cvt_pk_bf16_f32 v100, v100, v101
	v_cvt_pk_bf16_f32 v101, v106, v107
	global_store_dwordx4 v[218:219], v[98:101], off offset:256
	v_and_b32_e32 v103, 0xffff0000, v156
	v_lshlrev_b32_e32 v104, 16, v157
	v_lshlrev_b32_e32 v98, 16, v154
	v_and_b32_e32 v99, 0xffff0000, v154
	v_lshlrev_b32_e32 v100, 16, v155
	v_and_b32_e32 v101, 0xffff0000, v155
	v_and_b32_e32 v105, 0xffff0000, v157
	v_lshlrev_b32_e32 v106, 16, v158
	v_and_b32_e32 v107, 0xffff0000, v158
	v_lshlrev_b32_e32 v108, 16, v159
	v_and_b32_e32 v109, 0xffff0000, v159
	v_lshlrev_b32_e32 v110, 16, v160
	v_and_b32_e32 v111, 0xffff0000, v160
	v_lshlrev_b32_e32 v112, 16, v161
	v_and_b32_e32 v113, 0xffff0000, v161
	v_pk_fma_f32 v[96:97], v[96:97], v[100:101], v[108:109]
	v_pk_fma_f32 v[94:95], v[94:95], v[98:99], v[106:107]
	v_pk_fma_f32 v[98:99], v[92:93], v[104:105], v[112:113]
	v_pk_fma_f32 v[92:93], v[90:91], v[102:103], v[110:111]
	v_cvt_pk_bf16_f32 v90, v94, v95
	v_cvt_pk_bf16_f32 v91, v96, v97
	v_lshlrev_b32_e32 v94, 16, v152
	v_cvt_pk_bf16_f32 v92, v92, v93
	v_cvt_pk_bf16_f32 v93, v98, v99
	global_store_dwordx4 v[216:217], v[90:93], off
	v_and_b32_e32 v95, 0xffff0000, v152
	v_lshlrev_b32_e32 v96, 16, v153
	v_lshlrev_b32_e32 v90, 16, v150
	v_and_b32_e32 v91, 0xffff0000, v150
	v_and_b32_e32 v97, 0xffff0000, v153
	v_lshlrev_b32_e32 v98, 16, v146
	v_and_b32_e32 v99, 0xffff0000, v146
	v_lshlrev_b32_e32 v102, 16, v148
	v_and_b32_e32 v103, 0xffff0000, v148
	v_lshlrev_b32_e32 v104, 16, v149
	v_and_b32_e32 v105, 0xffff0000, v149
	v_lshlrev_b32_e32 v92, 16, v151
	v_and_b32_e32 v93, 0xffff0000, v151
	v_lshlrev_b32_e32 v100, 16, v147
	v_and_b32_e32 v101, 0xffff0000, v147
; __device__ __forceinline__ u32x4 pack8(const f32x4 v0, const f32x4 v1) { u32x4 w; w.x = cvt_pk_bf16(v0[0], v0[1]); w.y = cvt_pk_bf16(v0[2], v0[3]); w.z = cvt_pk_bf16(v1[0], v1[1]); w.w = cvt_pk_bf16(v1[2], v1[3]); return w; }
;     __device__ __forceinline__ void operator()(const f32x4 (&acc)[2][2][4][2], const Unit& u, int wr, int wc, int fr_, int fq) const {
;     ...
;         const size_t row0 = (size_t)u.pm * BM + wr * 64 + fr; const int col0 = u.pn * BM + wc * 32 + 8 * fq;
; #pragma unroll
;         for (int ai = 0; ai < 2; ++ai) {
;             u32x4 gw[4][2], ow[4][2];
; #pragma unroll
;             for (int m = 0; m < 4; ++m)
; #pragma unroll
;                 for (int bj = 0; bj < 2; ++bj) { const size_t r = row0 + ai * HALF + m * 16; const int c = col0 + bj * HALF;
;                     gw[m][bj] = *(const u32x4*)(G + r * 6144 + goff + c); if (!FIRST) ow[m][bj] = *(const u32x4*)(Mo + r * DM + c); }
; #pragma unroll
;             for (int m = 0; m < 4; ++m)
; #pragma unroll
;                 for (int bj = 0; bj < 2; ++bj) { const size_t r = row0 + ai * HALF + m * 16; const int c = col0 + bj * HALF;
;                     f32x4 g0, g1; unpack8(gw[m][bj], g0, g1);
;                     f32x4 v0 = g0 * acc[ai][bj][m][0], v1 = g1 * acc[ai][bj][m][1];
;                     if (!FIRST) { f32x4 o0, o1; unpack8(ow[m][bj], o0, o1); v0 += o0; v1 += o1; }
;                     *(u32x4*)((Mdst ? Mdst : Mo) + r * DM + c) = pack8(v0, v1); }
;             asm volatile("" ::: "memory"); }
	v_pk_fma_f32 v[86:87], v[86:87], v[90:91], v[98:99]
	v_pk_fma_f32 v[90:91], v[84:85], v[96:97], v[104:105]
	v_pk_fma_f32 v[84:85], v[82:83], v[94:95], v[102:103]
	v_pk_fma_f32 v[88:89], v[88:89], v[92:93], v[100:101]
	v_cvt_pk_bf16_f32 v82, v86, v87
	v_lshlrev_b32_e32 v86, 16, v140
	v_cvt_pk_bf16_f32 v83, v88, v89
	v_cvt_pk_bf16_f32 v84, v84, v85
	v_cvt_pk_bf16_f32 v85, v90, v91
	global_store_dwordx4 v[214:215], v[82:85], off offset:256
	v_and_b32_e32 v87, 0xffff0000, v140
	v_lshlrev_b32_e32 v88, 16, v141
	v_lshlrev_b32_e32 v82, 16, v138
	v_and_b32_e32 v83, 0xffff0000, v138
	v_lshlrev_b32_e32 v84, 16, v139
	v_and_b32_e32 v85, 0xffff0000, v139
	v_and_b32_e32 v89, 0xffff0000, v141
	v_lshlrev_b32_e32 v90, 16, v142
	v_and_b32_e32 v91, 0xffff0000, v142
	v_lshlrev_b32_e32 v92, 16, v143
	v_and_b32_e32 v93, 0xffff0000, v143
	v_lshlrev_b32_e32 v94, 16, v144
	v_and_b32_e32 v95, 0xffff0000, v144
	v_lshlrev_b32_e32 v96, 16, v145
	v_and_b32_e32 v97, 0xffff0000, v145
	v_pk_fma_f32 v[80:81], v[80:81], v[84:85], v[92:93]
	v_pk_fma_f32 v[78:79], v[78:79], v[82:83], v[90:91]
	v_pk_fma_f32 v[82:83], v[76:77], v[88:89], v[96:97]
	v_pk_fma_f32 v[76:77], v[74:75], v[86:87], v[94:95]
	v_cvt_pk_bf16_f32 v74, v78, v79
	v_cvt_pk_bf16_f32 v75, v80, v81
	v_lshlrev_b32_e32 v78, 16, v136
	v_cvt_pk_bf16_f32 v76, v76, v77
	v_cvt_pk_bf16_f32 v77, v82, v83
	global_store_dwordx4 v[212:213], v[74:77], off
	v_and_b32_e32 v79, 0xffff0000, v136
	v_lshlrev_b32_e32 v80, 16, v137
	v_lshlrev_b32_e32 v74, 16, v134
	v_and_b32_e32 v75, 0xffff0000, v134
	v_and_b32_e32 v81, 0xffff0000, v137
	v_lshlrev_b32_e32 v82, 16, v130
	v_and_b32_e32 v83, 0xffff0000, v130
	v_lshlrev_b32_e32 v86, 16, v132
	v_and_b32_e32 v87, 0xffff0000, v132
	v_lshlrev_b32_e32 v88, 16, v133
	v_and_b32_e32 v89, 0xffff0000, v133
	v_lshlrev_b32_e32 v76, 16, v135
	v_and_b32_e32 v77, 0xffff0000, v135
	v_lshlrev_b32_e32 v84, 16, v131
	v_and_b32_e32 v85, 0xffff0000, v131
	v_pk_fma_f32 v[70:71], v[70:71], v[74:75], v[82:83]
	v_pk_fma_f32 v[74:75], v[68:69], v[80:81], v[88:89]
	v_pk_fma_f32 v[68:69], v[66:67], v[78:79], v[86:87]
	v_pk_fma_f32 v[72:73], v[72:73], v[76:77], v[84:85]
	v_cvt_pk_bf16_f32 v66, v70, v71
	v_lshl_add_u64 v[106:107], v[208:209], 0, s[34:35]
	v_cvt_pk_bf16_f32 v67, v72, v73
	v_cvt_pk_bf16_f32 v68, v68, v69
	v_cvt_pk_bf16_f32 v69, v74, v75
	global_store_dwordx4 v[210:211], v[66:69], off offset:256
	s_nop 1
	v_add_co_u32_e32 v68, vcc, s1, v206
	v_lshl_add_u64 v[66:67], v[206:207], 0, s[30:31]
	s_nop 0
	v_addc_co_u32_e32 v69, vcc, 0, v207, vcc
	global_load_dwordx4 v[108:111], v[68:69], off
	v_add_co_u32_e32 v142, vcc, s52, v208
	s_mov_b64 s[30:31], 0x80000
	s_nop 0
	v_addc_co_u32_e32 v143, vcc, 0, v209, vcc
	v_lshl_add_u64 v[140:141], v[208:209], 0, s[30:31]
	global_load_dwordx4 v[112:115], v[142:143], off
	global_load_dwordx4 v[116:119], v[66:67], off offset:256
	global_load_dwordx4 v[120:123], v[140:141], off offset:256
	s_mov_b32 s1, 0x1b0000
	v_add_co_u32_e32 v68, vcc, s1, v206
	s_mov_b64 s[30:31], 0x1b0000
	s_nop 0
	v_addc_co_u32_e32 v69, vcc, 0, v207, vcc
	global_load_dwordx4 v[124:127], v[68:69], off
	v_add_co_u32_e32 v144, vcc, s0, v208
	v_lshl_add_u64 v[66:67], v[206:207], 0, s[30:31]
	s_nop 0
	v_addc_co_u32_e32 v145, vcc, 0, v209, vcc
	s_mov_b64 s[0:1], 0x1e0000
	global_load_dwordx4 v[128:131], v[144:145], off
	global_load_dwordx4 v[132:135], v[66:67], off offset:256
	global_load_dwordx4 v[136:139], v[106:107], off offset:256
	v_lshl_add_u64 v[66:67], v[206:207], 0, s[0:1]
	s_mov_b32 s0, 0x1e0000
	v_add_co_u32_e32 v68, vcc, s0, v206
	s_mov_b64 s[0:1], 0xa0000
	s_nop 0
	v_addc_co_u32_e32 v69, vcc, 0, v207, vcc
	v_lshl_add_u64 v[102:103], v[208:209], 0, s[0:1]
	s_mov_b32 s0, 0xa0000
	global_load_dwordx4 v[94:97], v[68:69], off
	v_add_co_u32_e32 v104, vcc, s0, v208
	s_mov_b64 s[0:1], 0x210000
	s_nop 0
	v_addc_co_u32_e32 v105, vcc, 0, v209, vcc
	global_load_dwordx4 v[90:93], v[104:105], off
	global_load_dwordx4 v[86:89], v[66:67], off offset:256
	global_load_dwordx4 v[82:85], v[102:103], off offset:256
	v_lshl_add_u64 v[66:67], v[206:207], 0, s[0:1]
	s_mov_b32 s0, 0x210000
	v_add_co_u32_e32 v68, vcc, s0, v206
	s_mov_b64 s[0:1], 0xb0000
	s_nop 0
	v_addc_co_u32_e32 v69, vcc, 0, v207, vcc
	v_lshl_add_u64 v[98:99], v[208:209], 0, s[0:1]
	s_mov_b32 s0, 0xb0000
	global_load_dwordx4 v[78:81], v[68:69], off
	v_add_co_u32_e32 v100, vcc, s0, v208
	s_mov_b64 s[0:1], -1
	s_nop 0
	v_addc_co_u32_e32 v101, vcc, 0, v209, vcc
	global_load_dwordx4 v[74:77], v[100:101], off
	global_load_dwordx4 v[70:73], v[66:67], off offset:256
	s_nop 0
	global_load_dwordx4 v[66:69], v[98:99], off offset:256
	s_andn2_b64 vcc, exec, s[6:7]
	s_waitcnt vmcnt(15)
	v_lshlrev_b32_e32 v146, 16, v108
	v_and_b32_e32 v147, 0xffff0000, v108
	v_lshlrev_b32_e32 v108, 16, v109
	v_and_b32_e32 v109, 0xffff0000, v109
	v_lshlrev_b32_e32 v148, 16, v110
	v_and_b32_e32 v149, 0xffff0000, v110
	v_lshlrev_b32_e32 v110, 16, v111
	v_and_b32_e32 v111, 0xffff0000, v111
	s_waitcnt vmcnt(14)
	v_lshlrev_b32_e32 v150, 16, v112
	v_and_b32_e32 v151, 0xffff0000, v112
	v_lshlrev_b32_e32 v112, 16, v113
	v_and_b32_e32 v113, 0xffff0000, v113
	v_lshlrev_b32_e32 v152, 16, v114
	v_and_b32_e32 v153, 0xffff0000, v114
	v_lshlrev_b32_e32 v114, 16, v115
	v_and_b32_e32 v115, 0xffff0000, v115
	v_pk_fma_f32 v[64:65], v[64:65], v[108:109], v[112:113]
	v_pk_fma_f32 v[62:63], v[62:63], v[146:147], v[150:151]
	v_pk_fma_f32 v[108:109], v[60:61], v[110:111], v[114:115]
	v_pk_fma_f32 v[60:61], v[58:59], v[148:149], v[152:153]
	v_cvt_pk_bf16_f32 v58, v62, v63
	v_cvt_pk_bf16_f32 v59, v64, v65
	s_waitcnt vmcnt(13)
; __device__ __forceinline__ u32x4 pack8(const f32x4 v0, const f32x4 v1) { u32x4 w; w.x = cvt_pk_bf16(v0[0], v0[1]); w.y = cvt_pk_bf16(v0[2], v0[3]); w.z = cvt_pk_bf16(v1[0], v1[1]); w.w = cvt_pk_bf16(v1[2], v1[3]); return w; }
;     __device__ __forceinline__ void operator()(const f32x4 (&acc)[2][2][4][2], const Unit& u, int wr, int wc, int fr_, int fq) const {
;     ...
;             for (int m = 0; m < 4; ++m)
; #pragma unroll
;                 for (int bj = 0; bj < 2; ++bj) { const size_t r = row0 + ai * HALF + m * 16; const int c = col0 + bj * HALF;
;                     f32x4 g0, g1; unpack8(gw[m][bj], g0, g1);
;                     f32x4 v0 = g0 * acc[ai][bj][m][0], v1 = g1 * acc[ai][bj][m][1];
;                     if (!FIRST) { f32x4 o0, o1; unpack8(ow[m][bj], o0, o1); v0 += o0; v1 += o1; }
;                     *(u32x4*)((Mdst ? Mdst : Mo) + r * DM + c) = pack8(v0, v1); }
	v_lshlrev_b32_e32 v62, 16, v118
	v_cvt_pk_bf16_f32 v60, v60, v61
	v_cvt_pk_bf16_f32 v61, v108, v109
	global_store_dwordx4 v[142:143], v[58:61], off
	v_and_b32_e32 v63, 0xffff0000, v118
	v_lshlrev_b32_e32 v64, 16, v119
	v_lshlrev_b32_e32 v58, 16, v116
	v_and_b32_e32 v59, 0xffff0000, v116
	v_and_b32_e32 v65, 0xffff0000, v119
	s_waitcnt vmcnt(13)
	v_lshlrev_b32_e32 v108, 16, v120
	v_and_b32_e32 v109, 0xffff0000, v120
	v_lshlrev_b32_e32 v112, 16, v122
	v_and_b32_e32 v113, 0xffff0000, v122
	v_lshlrev_b32_e32 v114, 16, v123
	v_and_b32_e32 v115, 0xffff0000, v123
	v_lshlrev_b32_e32 v60, 16, v117
	v_and_b32_e32 v61, 0xffff0000, v117
	v_lshlrev_b32_e32 v110, 16, v121
	v_and_b32_e32 v111, 0xffff0000, v121
	v_pk_fma_f32 v[54:55], v[54:55], v[58:59], v[108:109]
	v_pk_fma_f32 v[58:59], v[52:53], v[64:65], v[114:115]
	v_pk_fma_f32 v[52:53], v[50:51], v[62:63], v[112:113]
	v_pk_fma_f32 v[56:57], v[56:57], v[60:61], v[110:111]
	v_cvt_pk_bf16_f32 v50, v54, v55
	s_waitcnt vmcnt(12)
	v_lshlrev_b32_e32 v54, 16, v126
	v_cvt_pk_bf16_f32 v51, v56, v57
	v_cvt_pk_bf16_f32 v52, v52, v53
	v_cvt_pk_bf16_f32 v53, v58, v59
	global_store_dwordx4 v[140:141], v[50:53], off offset:256
	v_and_b32_e32 v55, 0xffff0000, v126
	v_lshlrev_b32_e32 v56, 16, v127
	v_lshlrev_b32_e32 v50, 16, v124
	v_and_b32_e32 v51, 0xffff0000, v124
	v_lshlrev_b32_e32 v52, 16, v125
	v_and_b32_e32 v53, 0xffff0000, v125
	v_and_b32_e32 v57, 0xffff0000, v127
	s_waitcnt vmcnt(12)
	v_lshlrev_b32_e32 v58, 16, v128
	v_and_b32_e32 v59, 0xffff0000, v128
	v_lshlrev_b32_e32 v60, 16, v129
	v_and_b32_e32 v61, 0xffff0000, v129
	v_lshlrev_b32_e32 v62, 16, v130
	v_and_b32_e32 v63, 0xffff0000, v130
	v_lshlrev_b32_e32 v64, 16, v131
	v_and_b32_e32 v65, 0xffff0000, v131
	v_pk_fma_f32 v[48:49], v[48:49], v[52:53], v[60:61]
	v_pk_fma_f32 v[46:47], v[46:47], v[50:51], v[58:59]
	v_pk_fma_f32 v[50:51], v[44:45], v[56:57], v[64:65]
	v_pk_fma_f32 v[44:45], v[42:43], v[54:55], v[62:63]
	v_cvt_pk_bf16_f32 v42, v46, v47
	v_cvt_pk_bf16_f32 v43, v48, v49
	s_waitcnt vmcnt(11)
	v_lshlrev_b32_e32 v46, 16, v134
	v_cvt_pk_bf16_f32 v44, v44, v45
	v_cvt_pk_bf16_f32 v45, v50, v51
	global_store_dwordx4 v[144:145], v[42:45], off
	v_and_b32_e32 v47, 0xffff0000, v134
	v_lshlrev_b32_e32 v48, 16, v135
	v_lshlrev_b32_e32 v42, 16, v132
	v_and_b32_e32 v43, 0xffff0000, v132
	v_and_b32_e32 v49, 0xffff0000, v135
	s_waitcnt vmcnt(11)
	v_lshlrev_b32_e32 v50, 16, v136
	v_and_b32_e32 v51, 0xffff0000, v136
	v_lshlrev_b32_e32 v54, 16, v138
	v_and_b32_e32 v55, 0xffff0000, v138
	v_lshlrev_b32_e32 v56, 16, v139
	v_and_b32_e32 v57, 0xffff0000, v139
	v_lshlrev_b32_e32 v44, 16, v133
	v_and_b32_e32 v45, 0xffff0000, v133
	v_lshlrev_b32_e32 v52, 16, v137
	v_and_b32_e32 v53, 0xffff0000, v137
	v_pk_fma_f32 v[38:39], v[38:39], v[42:43], v[50:51]
	v_pk_fma_f32 v[42:43], v[36:37], v[48:49], v[56:57]
	v_pk_fma_f32 v[36:37], v[34:35], v[46:47], v[54:55]
	v_pk_fma_f32 v[40:41], v[40:41], v[44:45], v[52:53]
	v_cvt_pk_bf16_f32 v34, v38, v39
	s_waitcnt vmcnt(10)
	v_lshlrev_b32_e32 v38, 16, v96
	v_cvt_pk_bf16_f32 v35, v40, v41
	v_cvt_pk_bf16_f32 v36, v36, v37
	v_cvt_pk_bf16_f32 v37, v42, v43
	global_store_dwordx4 v[106:107], v[34:37], off offset:256
	v_and_b32_e32 v39, 0xffff0000, v96
	v_lshlrev_b32_e32 v40, 16, v97
	v_lshlrev_b32_e32 v34, 16, v94
	v_and_b32_e32 v35, 0xffff0000, v94
	v_lshlrev_b32_e32 v36, 16, v95
	v_and_b32_e32 v37, 0xffff0000, v95
	v_and_b32_e32 v41, 0xffff0000, v97
	s_waitcnt vmcnt(10)
; __device__ __forceinline__ u32x4 pack8(const f32x4 v0, const f32x4 v1) { u32x4 w; w.x = cvt_pk_bf16(v0[0], v0[1]); w.y = cvt_pk_bf16(v0[2], v0[3]); w.z = cvt_pk_bf16(v1[0], v1[1]); w.w = cvt_pk_bf16(v1[2], v1[3]); return w; }
; #define PG8_BAR __builtin_amdgcn_s_barrier()
;     __device__ __forceinline__ void operator()(const f32x4 (&acc)[2][2][4][2], const Unit& u, int wr, int wc, int fr_, int fq) const {
;     ...
;             for (int m = 0; m < 4; ++m)
; #pragma unroll
;                 for (int bj = 0; bj < 2; ++bj) { const size_t r = row0 + ai * HALF + m * 16; const int c = col0 + bj * HALF;
;                     f32x4 g0, g1; unpack8(gw[m][bj], g0, g1);
;                     f32x4 v0 = g0 * acc[ai][bj][m][0], v1 = g1 * acc[ai][bj][m][1];
;                     if (!FIRST) { f32x4 o0, o1; unpack8(ow[m][bj], o0, o1); v0 += o0; v1 += o1; }
;                     *(u32x4*)((Mdst ? Mdst : Mo) + r * DM + c) = pack8(v0, v1); }
;             asm volatile("" ::: "memory"); }
; template <class Epi, class Sched, bool ALIGN_EPI = false, bool SP2 = false, bool ABLK = false, bool BBLK = false>
; __device__ __forceinline__ void gemm_phase(PG8_LAS unsigned char* lds, const Gemm g, const Sched& S, const Epi& E) {
;     ...
;         if (!has_next) break;
; #pragma unroll
;         for (int a = 0; a < 2; ++a)
; #pragma unroll
;             for (int b = 0; b < 2; ++b)
; #pragma unroll
;                 for (int m = 0; m < 4; ++m)
; #pragma unroll
;                     for (int n = 0; n < 2; ++n) acc[a][b][m][n] = (f32x4){0.f, 0.f, 0.f, 0.f};
;         cur = nxt; cA = nA; cB = nB; ++ui;
;         if constexpr (ALIGN_EPI) { if (wr == 1) PG8_BAR; }
	v_lshlrev_b32_e32 v42, 16, v90
	v_and_b32_e32 v43, 0xffff0000, v90
	v_lshlrev_b32_e32 v44, 16, v91
	v_and_b32_e32 v45, 0xffff0000, v91
	v_lshlrev_b32_e32 v46, 16, v92
	v_and_b32_e32 v47, 0xffff0000, v92
	v_lshlrev_b32_e32 v48, 16, v93
	v_and_b32_e32 v49, 0xffff0000, v93
	v_pk_fma_f32 v[32:33], v[32:33], v[36:37], v[44:45]
	v_pk_fma_f32 v[30:31], v[30:31], v[34:35], v[42:43]
	v_pk_fma_f32 v[34:35], v[28:29], v[40:41], v[48:49]
	v_pk_fma_f32 v[28:29], v[26:27], v[38:39], v[46:47]
	v_cvt_pk_bf16_f32 v26, v30, v31
	v_cvt_pk_bf16_f32 v27, v32, v33
	s_waitcnt vmcnt(9)
	v_lshlrev_b32_e32 v30, 16, v88
	v_cvt_pk_bf16_f32 v28, v28, v29
	v_cvt_pk_bf16_f32 v29, v34, v35
	global_store_dwordx4 v[104:105], v[26:29], off
	v_and_b32_e32 v31, 0xffff0000, v88
	v_lshlrev_b32_e32 v32, 16, v89
	v_lshlrev_b32_e32 v26, 16, v86
	v_and_b32_e32 v27, 0xffff0000, v86
	v_and_b32_e32 v33, 0xffff0000, v89
	s_waitcnt vmcnt(9)
	v_lshlrev_b32_e32 v34, 16, v82
	v_and_b32_e32 v35, 0xffff0000, v82
	v_lshlrev_b32_e32 v38, 16, v84
	v_and_b32_e32 v39, 0xffff0000, v84
	v_lshlrev_b32_e32 v40, 16, v85
	v_and_b32_e32 v41, 0xffff0000, v85
	v_lshlrev_b32_e32 v28, 16, v87
	v_and_b32_e32 v29, 0xffff0000, v87
	v_lshlrev_b32_e32 v36, 16, v83
	v_and_b32_e32 v37, 0xffff0000, v83
	v_pk_fma_f32 v[22:23], v[22:23], v[26:27], v[34:35]
	v_pk_fma_f32 v[26:27], v[20:21], v[32:33], v[40:41]
	v_pk_fma_f32 v[20:21], v[18:19], v[30:31], v[38:39]
	v_pk_fma_f32 v[24:25], v[24:25], v[28:29], v[36:37]
	v_cvt_pk_bf16_f32 v18, v22, v23
	s_waitcnt vmcnt(8)
	v_lshlrev_b32_e32 v22, 16, v80
	v_cvt_pk_bf16_f32 v19, v24, v25
	v_cvt_pk_bf16_f32 v20, v20, v21
	v_cvt_pk_bf16_f32 v21, v26, v27
	global_store_dwordx4 v[102:103], v[18:21], off offset:256
	v_and_b32_e32 v23, 0xffff0000, v80
	v_lshlrev_b32_e32 v24, 16, v81
	v_lshlrev_b32_e32 v18, 16, v78
	v_and_b32_e32 v19, 0xffff0000, v78
	v_lshlrev_b32_e32 v20, 16, v79
	v_and_b32_e32 v21, 0xffff0000, v79
	v_and_b32_e32 v25, 0xffff0000, v81
	s_waitcnt vmcnt(8)
	v_lshlrev_b32_e32 v26, 16, v74
	v_and_b32_e32 v27, 0xffff0000, v74
	v_lshlrev_b32_e32 v28, 16, v75
	v_and_b32_e32 v29, 0xffff0000, v75
	v_lshlrev_b32_e32 v30, 16, v76
	v_and_b32_e32 v31, 0xffff0000, v76
	v_lshlrev_b32_e32 v32, 16, v77
	v_and_b32_e32 v33, 0xffff0000, v77
	v_pk_fma_f32 v[16:17], v[16:17], v[20:21], v[28:29]
	v_pk_fma_f32 v[14:15], v[14:15], v[18:19], v[26:27]
	v_pk_fma_f32 v[18:19], v[12:13], v[24:25], v[32:33]
	v_pk_fma_f32 v[12:13], v[10:11], v[22:23], v[30:31]
	v_cvt_pk_bf16_f32 v10, v14, v15
	v_cvt_pk_bf16_f32 v11, v16, v17
	s_waitcnt vmcnt(7)
	v_lshlrev_b32_e32 v14, 16, v72
	v_cvt_pk_bf16_f32 v12, v12, v13
	v_cvt_pk_bf16_f32 v13, v18, v19
	global_store_dwordx4 v[100:101], v[10:13], off
	v_and_b32_e32 v15, 0xffff0000, v72
	v_lshlrev_b32_e32 v16, 16, v73
	v_lshlrev_b32_e32 v10, 16, v70
	v_and_b32_e32 v11, 0xffff0000, v70
	v_and_b32_e32 v17, 0xffff0000, v73
	s_waitcnt vmcnt(7)
	v_lshlrev_b32_e32 v18, 16, v66
	v_and_b32_e32 v19, 0xffff0000, v66
	v_lshlrev_b32_e32 v22, 16, v68
	v_and_b32_e32 v23, 0xffff0000, v68
	v_lshlrev_b32_e32 v24, 16, v69
	v_and_b32_e32 v25, 0xffff0000, v69
	v_lshlrev_b32_e32 v12, 16, v71
	v_and_b32_e32 v13, 0xffff0000, v71
	v_lshlrev_b32_e32 v20, 16, v67
	v_and_b32_e32 v21, 0xffff0000, v67
	v_pk_fma_f32 v[6:7], v[6:7], v[10:11], v[18:19]
	v_pk_fma_f32 v[10:11], v[4:5], v[16:17], v[24:25]
	v_pk_fma_f32 v[4:5], v[2:3], v[14:15], v[22:23]
	v_pk_fma_f32 v[8:9], v[8:9], v[12:13], v[20:21]
	v_cvt_pk_bf16_f32 v2, v6, v7
	s_nop 0
	v_cvt_pk_bf16_f32 v3, v8, v9
	v_cvt_pk_bf16_f32 v4, v4, v5
	v_cvt_pk_bf16_f32 v5, v10, v11
	global_store_dwordx4 v[98:99], v[2:5], off offset:256
	s_cbranch_vccnz .LBB0_1133
	s_andn2_b64 vcc, exec, s[12:13]
	s_cbranch_vccnz .LBB0_1132
	s_branch .LBB0_1132

; #define PG8_WAIT_V(n) asm volatile("s_waitcnt vmcnt(" #n ")" ::: "memory")
; template <class Epi, class Sched, bool ALIGN_EPI = false, bool SP2 = false, bool ABLK = false, bool BBLK = false>
; __device__ __forceinline__ void gemm_phase(PG8_LAS unsigned char* lds, const Gemm g, const Sched& S, const Epi& E) {
;     ...
;     const int tid = tid_, wid = __builtin_amdgcn_readfirstlane(tid >> 6), lane = tid & 63, wr = wid >> 2, wc = wid & 3, fr = lane & 15, fq = lane >> 4;
;     const int K = g.K, nt = K / BK, LDA = g.lda ? g.lda : K, LDB = g.ldb ? g.ldb : K;
;     unsigned voffA[2], voffB[2];
; #pragma unroll
;     for (int i = 0; i < 2; ++i) { int R, C; stage_rc(tid * 16 + i * 8192, R, C); const int Rb = Epi::PERM ? ((R & ~31) + perm32(R & 31)) : R;
;         voffA[i] = ABLK ? (unsigned)(R * BK + C) * 2u : (unsigned)(R * LDA + C) * 2u; voffB[i] = BBLK ? (unsigned)(Rb * BK + C) * 2u : (unsigned)(Rb * LDB + C) * 2u; }
;     const size_t kstep = (size_t)(BK * 2);
;     const size_t hstepa = (size_t)HALF * LDA * 2, hstepb = (size_t)HALF * LDB * 2;
;     const size_t kstepA = ABLK ? (size_t)BM * BK * 2 : kstep, hstepA = ABLK ? (size_t)HALF * BK * 2 : hstepa, tstepA = ABLK ? (size_t)nt * BM * BK * 2 : 2 * hstepa;
;     const size_t kstepB = BBLK ? (size_t)BM * BK * 2 : kstep, hstepB = BBLK ? (size_t)HALF * BK * 2 : hstepb, tstepB = BBLK ? (size_t)nt * BM * BK * 2 : 2 * hstepb;
;     const unsigned ldsw = (unsigned)wid * 1024u;
;     const int aoff = lds_byte(wr * 64 + fr, fq * 8), boff = lds_byte(wc * 32 + fr, fq * 8);
;     ...
;     Unit cur, nxt; int ui = 0;
;     if (!S.next(0, cur)) return;
;     f32x4 acc[2][2][4][2];
; #pragma unroll
;     for (int a = 0; a < 2; ++a)
; #pragma unroll
;         for (int b = 0; b < 2; ++b)
; #pragma unroll
;             for (int m = 0; m < 4; ++m)
; #pragma unroll
;                 for (int n = 0; n < 2; ++n) acc[a][b][m][n] = (f32x4){0.f, 0.f, 0.f, 0.f};
;     bf16x8 At[4][2], B0[2][2], B1[2][2];
;     const char* cA = (const char*)g.A + (size_t)cur.pm * tstepA; const char* cB = (const char*)g.Bt + (size_t)cur.pn * tstepB;
;     S.a_ready(cur);
;     if constexpr (SP2) {
;         PG8_STAGE(PG8_SB(0, 0), cB, voffB); PG8_STAGE(PG8_SB(0, 1), cB + hstepB, voffB); PG8_STAGE(PG8_SA(0, 0), cA, voffA); PG8_STAGE(PG8_SA(0, 1), cA + hstepA, voffA);
;         if (wr == 1) PG8_BAR;
;         PG8_WAIT_V(2); PG8_BAR;
.LBB0_1152:
	v_ashrrev_i32_e32 v3, 31, v6
	v_lshrrev_b32_e32 v3, 26, v3
	v_add_u32_e32 v3, v6, v3
	v_ashrrev_i32_e32 v7, 6, v3
	v_bfe_i32 v3, v6, 27, 1
	v_lshlrev_b32_e32 v2, 4, v6
	v_lshrrev_b32_e32 v3, 22, v3
	v_add_u32_e32 v3, v2, v3
	v_and_b32_e32 v3, 0xfffffc00, v3
	v_sub_u32_e32 v3, v2, v3
	v_lshrrev_b32_e32 v4, 4, v3
	v_bitop3_b32 v3, v4, v3, 32 bitop3:0x6c
	v_ashrrev_i32_e32 v5, 31, v3
	v_lshrrev_b32_e32 v5, 26, v5
	v_add_u32_e32 v5, v3, v5
	v_lshlrev_b32_e32 v4, 3, v7
	v_ashrrev_i32_e32 v8, 6, v5
	v_and_b32_e32 v5, 0xc0, v5
	v_and_b32_e32 v4, -16, v4
	v_sub_u32_e32 v3, v3, v5
	v_add_u32_e32 v4, v8, v4
	v_lshlrev_b32_e32 v9, 5, v7
	v_ashrrev_i16_sdwa v3, v232, sext(v3) dst_sel:DWORD dst_unused:UNUSED_PAD src0_sel:DWORD src1_sel:BYTE_0
	v_and_b32_e32 v10, 32, v9
	v_bfe_i32 v9, v3, 0, 16
	v_lshlrev_b32_e32 v3, 1, v4
	v_lshrrev_b32_e32 v5, 2, v4
	v_and_b32_e32 v11, 3, v8
	s_mov_b32 s0, 0x1ffffe0
	v_and_b32_e32 v3, 24, v3
	v_and_b32_e32 v5, 4, v5
	v_and_or_b32 v11, v4, s0, v11
	v_or3_b32 v3, v11, v5, v3
	v_add_lshl_u32 v5, v10, v9, 1
	v_add_u32_e32 v2, 0x2000, v2
	v_lshl_add_u32 v196, v3, 7, v5
	v_ashrrev_i32_e32 v3, 31, v2
	v_lshrrev_b32_e32 v3, 22, v3
	v_add_u32_e32 v3, v2, v3
	v_ashrrev_i32_e32 v10, 10, v3
	v_mul_i32_i24_e32 v3, 0x400, v10
	v_sub_u32_e32 v2, v2, v3
	v_lshrrev_b32_e32 v3, 4, v2
	v_bitop3_b32 v2, v3, v2, 32 bitop3:0x6c
	v_lshl_add_u32 v186, v4, 10, v5
	v_ashrrev_i32_e32 v4, 31, v2
	s_add_u32 s33, s60, 0x47a00000
	v_lshrrev_b32_e32 v4, 26, v4
	s_addc_u32 s36, s61, 0
	v_lshlrev_b32_e32 v3, 3, v10
	v_add_u32_e32 v4, v2, v4
	s_add_u32 s37, s60, 0xa700000
	v_and_b32_e32 v3, -16, v3
	v_ashrrev_i32_e32 v11, 6, v4
	s_addc_u32 s44, s61, 0
	s_ashr_i32 s7, s6, 6
	v_add_u32_e32 v3, v11, v3
	v_and_b32_e32 v4, 0xc0, v4
	v_and_b32_e32 v13, 3, v11
	s_ashr_i32 s29, s28, 31
	s_ashr_i32 s27, s26, 31
	v_sub_u32_e32 v2, v2, v4
	v_and_or_b32 v13, v3, s0, v13
	s_ashr_i32 s12, s6, 8
	s_lshl_b32 s45, s7, 10
	s_lshl_b64 s[8:9], s[28:29], 18
	s_lshl_b64 s[0:1], s[26:27], 18
	v_ashrrev_i16_sdwa v2, v232, sext(v2) dst_sel:DWORD dst_unused:UNUSED_PAD src0_sel:DWORD src1_sel:BYTE_0
	s_add_u32 s0, s37, s0
	v_lshlrev_b32_e32 v5, 5, v10
	v_bfe_i32 v12, v2, 0, 16
	v_lshlrev_b32_e32 v2, 1, v3
	v_lshrrev_b32_e32 v4, 2, v3
	s_addc_u32 s1, s44, s1
	s_add_i32 s27, s45, 0
	v_and_b32_e32 v5, 32, v5
	v_and_b32_e32 v2, 24, v2
	v_and_b32_e32 v4, 4, v4
	s_add_i32 m0, s27, 0x10000
	v_or3_b32 v2, v13, v4, v2
	v_add_lshl_u32 v4, v5, v12, 1
	global_load_lds_dwordx4 v196, s[0:1]
	s_add_i32 m0, s27, 0x12000
	v_lshl_add_u32 v200, v2, 7, v4
	s_add_u32 s14, s0, 0x4000
	global_load_lds_dwordx4 v200, s[0:1]
	s_addc_u32 s15, s1, 0
	s_add_i32 m0, s27, 0x14000
	v_lshl_add_u32 v198, v3, 10, v4
	global_load_lds_dwordx4 v196, s[14:15]
	s_add_i32 m0, s27, 0x16000
	s_add_u32 s30, s33, s8
	s_addc_u32 s31, s36, s9
	s_add_i32 s46, s27, 0x2000
	global_load_lds_dwordx4 v200, s[14:15]
	s_mov_b32 m0, s27
	s_add_u32 s8, s30, 0x20000
	global_load_lds_dwordx4 v186, s[30:31]
	s_mov_b32 m0, s46
	s_addc_u32 s9, s31, 0
	s_add_i32 s47, s27, 0x4000
	global_load_lds_dwordx4 v198, s[30:31]
	s_mov_b32 m0, s47
	s_add_i32 s65, s27, 0x6000
	global_load_lds_dwordx4 v186, s[8:9]
	s_mov_b32 m0, s65
	v_mov_b32_e32 v199, v187
	global_load_lds_dwordx4 v198, s[8:9]
	s_cmp_eq_u32 s12, 1
	v_lshl_add_u64 v[2:3], s[30:31], 0, v[186:187]
	s_cselect_b64 s[8:9], -1, 0
	s_cmp_lg_u32 s12, 1
	v_lshl_add_u64 v[4:5], s[30:31], 0, v[198:199]
	s_cbranch_scc1 .LBB0_1154
.LBB0_1154:
	v_lshrrev_b32_e32 v13, 1, v6
	v_and_b32_e32 v13, 24, v13
	v_and_b32_e32 v222, 15, v6
	v_lshlrev_b32_e32 v14, 1, v13
	v_lshlrev_b32_e32 v6, 2, v6
	s_lshl_b32 s7, s7, 5
	s_lshl_b32 s68, s12, 6
	v_lshl_or_b32 v14, v222, 6, v14
	s_lshl_b32 s12, s12, 13
	v_and_b32_e32 v6, 32, v6
	s_and_b32 s7, s7, 0x60
	v_bitop3_b32 v16, v14, s12, v6 bitop3:0xde
	s_lshl_b32 s12, s7, 7
	v_bitop3_b32 v223, v14, s12, v6 bitop3:0xde
	s_add_u32 s12, s0, 0x8000
	v_mov_b32_e32 v197, v187
	s_addc_u32 s13, s1, 0
	v_mov_b32_e32 v201, v187
	s_add_i32 m0, s27, 0x18000
	v_lshl_add_u64 v[14:15], s[12:13], 0, v[196:197]
	s_waitcnt vmcnt(2)
	s_barrier
	global_load_lds_dwordx4 v[14:15], off
	v_lshl_add_u64 v[14:15], s[12:13], 0, v[200:201]
	s_add_i32 m0, s27, 0x1a000
	s_add_i32 s72, s27, 0x8000
	s_add_i32 s73, s27, 0xa000
	global_load_lds_dwordx4 v[14:15], off
	v_lshl_add_u64 v[2:3], v[2:3], 0, s[62:63]
	s_mov_b32 m0, s72
	s_add_u32 s12, s0, 0xc000
	global_load_lds_dwordx4 v[2:3], off
	v_lshl_add_u64 v[2:3], v[4:5], 0, s[62:63]
	s_mov_b32 m0, s73
	s_addc_u32 s13, s1, 0
	global_load_lds_dwordx4 v[2:3], off
	s_add_i32 m0, s27, 0x1c000
	v_lshl_add_u64 v[2:3], s[12:13], 0, v[196:197]
	global_load_lds_dwordx4 v[2:3], off
	v_lshl_add_u64 v[2:3], s[12:13], 0, v[200:201]
	s_add_i32 m0, s27, 0x1e000
	s_cmpk_lt_u32 s6, 0x100
	global_load_lds_dwordx4 v[2:3], off
	v_lshlrev_b32_e32 v2, 13, v7
	v_and_b32_e32 v2, 0xffffc000, v2
	v_lshl_add_u32 v2, v8, 10, v2
	v_and_b32_e32 v3, 1, v7
	v_lshl_or_b32 v2, v3, 6, v2
	v_lshl_add_u32 v202, v9, 1, v2
	v_lshlrev_b32_e32 v2, 13, v10
	v_and_b32_e32 v2, 0xffffc000, v2
	s_waitcnt vmcnt(6)
	s_cselect_b64 s[12:13], -1, 0
	s_ashr_i32 s81, s68, 31
	v_lshl_add_u32 v2, v11, 10, v2
	v_and_b32_e32 v3, 1, v10
	s_add_u32 s14, s60, 0x2ca02000
	v_lshl_or_b32 v2, v3, 6, v2
	s_addc_u32 s15, s61, 0
	v_or_b32_e32 v224, s7, v13
	v_mov_b32_e32 v203, v187
	v_lshl_add_u32 v204, v12, 1, v2
	v_mov_b32_e32 v205, v187
	s_mov_b32 s19, 0
	v_add_u32_e32 v225, 0, v16
	s_barrier
	s_branch .LBB0_1157

; #define PG8_STAGE(bufoff, gbase, voff) do { _Pragma("unroll") for (int _i = 0; _i < 2; ++_i) \
;         __builtin_amdgcn_global_load_lds((const unsigned*)((const char*)(gbase) + (voff)[_i]), (PG8_LAS unsigned*)(lds + (bufoff) + ldsw + _i * 8192), 16, 0, 0); } while (0)
; #define PG8_LDA(dst, b, h) do { _Pragma("unroll") for (int m = 0; m < 4; ++m) _Pragma("unroll") for (int k = 0; k < 2; ++k) dst[m][k] = *(const PG8_LAS bf16x8*)(lds + PG8_SA(b, h) + aoff + m * 2048 + k * 1024); } while (0)
; #define PG8_LDB(dst, b, h) do { _Pragma("unroll") for (int n = 0; n < 2; ++n) _Pragma("unroll") for (int k = 0; k < 2; ++k) dst[n][k] = *(const PG8_LAS bf16x8*)(lds + PG8_SB(b, h) + boff + n * 2048 + k * 1024); } while (0)
; #define PG8_WAIT_V(n) asm volatile("s_waitcnt vmcnt(" #n ")" ::: "memory")
; #define PG8_BAR __builtin_amdgcn_s_barrier()
; template <class Epi, class Sched, bool ALIGN_EPI = false, bool SP2 = false, bool ABLK = false, bool BBLK = false>
; __device__ __forceinline__ void gemm_phase(PG8_LAS unsigned char* lds, const Gemm g, const Sched& S, const Epi& E) {
;     ...
;         const bool has_next = S.next(ui + 1, nxt);
;         const char* nA = has_next ? (const char*)g.A + (size_t)nxt.pm * tstepA : cA; const char* nB = has_next ? (const char*)g.Bt + (size_t)nxt.pn * tstepB : cB;
;         for (int t = 0; t < nt; t += 2) {
;             const bool last = (t == nt - 2);
;             const char* a1 = cA + (size_t)(t + 1) * kstepA;
;             const char* a2 = last ? nA : cA + (size_t)(t + 2) * kstepA; const char* b2 = last ? nB : cB + (size_t)(t + 2) * kstepB;
;             const char* a3 = a2 + kstepA; const char* b3 = b2 + kstepB;
;             if (last && has_next) S.a_ready(nxt);
;             if constexpr (SP2) {
;             PG8_LDB(B0, 0, 0); PG8_LDB(B1, 0, 1); PG8_SCHED; PG8_LDA(At, 0, 0); PG8_STAGE(PG8_SA(1, 1), a1 + hstepA, voffA);
;             PG8_WAIT_V(8); PG8_WAIT_L(0); PG8_BAR; PG8_MMA(0, 0, At, B0); PG8_MMA(0, 1, At, B1); PG8_BAR; PG8_SCHED;
;     ...
; #pragma unroll
;         for (int a = 0; a < 2; ++a)
; #pragma unroll
;             for (int b = 0; b < 2; ++b)
; #pragma unroll
;                 for (int m = 0; m < 4; ++m)
; #pragma unroll
;                     for (int n = 0; n < 2; ++n) acc[a][b][m][n] = (f32x4){0.f, 0.f, 0.f, 0.f};
;         cur = nxt; cA = nA; cB = nB; ++ui;
;         if constexpr (ALIGN_EPI) { if (wr == 1) PG8_BAR; }
.LBB0_1162:
	s_ashr_i32 s21, s20, 31
	s_lshl_b64 s[22:23], s[20:21], 18
	s_add_u32 s22, s33, s22
	s_addc_u32 s23, s36, s23
	s_and_b64 s[24:25], s[6:7], exec
	s_cselect_b32 s21, s23, s31
	s_cselect_b32 s29, s22, s30
	s_ashr_i32 s19, s18, 31
	s_lshl_b64 s[24:25], s[18:19], 18
	s_add_u32 s24, s37, s24
	s_addc_u32 s25, s44, s25
	s_and_b64 s[34:35], s[6:7], exec
	s_cselect_b32 s19, s25, s1
	s_cselect_b32 s61, s24, s0
	s_add_u32 s83, s0, 0x10000
	s_addc_u32 s84, s1, 0
	s_add_u32 s0, s30, 0x20080
	v_mov_b32_e32 v2, 0
	s_addc_u32 s1, s31, 0
	s_mov_b32 s86, -2
	v_mov_b32_e32 v3, v2
	v_mov_b32_e32 v4, v2
	v_mov_b32_e32 v5, v2
	v_mov_b32_e32 v6, v2
	v_mov_b32_e32 v7, v2
	v_mov_b32_e32 v8, v2
	v_mov_b32_e32 v9, v2
	v_mov_b32_e32 v18, v2
	v_mov_b32_e32 v19, v2
	v_mov_b32_e32 v20, v2
	v_mov_b32_e32 v21, v2
	v_mov_b32_e32 v22, v2
	v_mov_b32_e32 v23, v2
	v_mov_b32_e32 v24, v2
	v_mov_b32_e32 v25, v2
	v_mov_b32_e32 v34, v2
	v_mov_b32_e32 v35, v2
	v_mov_b32_e32 v36, v2
	v_mov_b32_e32 v37, v2
	v_mov_b32_e32 v38, v2
	v_mov_b32_e32 v39, v2
	v_mov_b32_e32 v40, v2
	v_mov_b32_e32 v41, v2
	v_mov_b32_e32 v50, v2
	v_mov_b32_e32 v51, v2
	v_mov_b32_e32 v52, v2
	v_mov_b32_e32 v53, v2
	v_mov_b32_e32 v54, v2
	v_mov_b32_e32 v55, v2
	v_mov_b32_e32 v56, v2
	v_mov_b32_e32 v57, v2
	v_mov_b32_e32 v10, v2
	v_mov_b32_e32 v11, v2
	v_mov_b32_e32 v12, v2
	v_mov_b32_e32 v13, v2
	v_mov_b32_e32 v14, v2
	v_mov_b32_e32 v15, v2
	v_mov_b32_e32 v16, v2
	v_mov_b32_e32 v17, v2
	v_mov_b32_e32 v26, v2
	v_mov_b32_e32 v27, v2
	v_mov_b32_e32 v28, v2
	v_mov_b32_e32 v29, v2
	v_mov_b32_e32 v30, v2
	v_mov_b32_e32 v31, v2
	v_mov_b32_e32 v32, v2
	v_mov_b32_e32 v33, v2
	v_mov_b32_e32 v42, v2
	v_mov_b32_e32 v43, v2
	v_mov_b32_e32 v44, v2
	v_mov_b32_e32 v45, v2
	v_mov_b32_e32 v46, v2
	v_mov_b32_e32 v47, v2
	v_mov_b32_e32 v48, v2
	v_mov_b32_e32 v49, v2
	v_mov_b32_e32 v58, v2
	v_mov_b32_e32 v59, v2
	v_mov_b32_e32 v60, v2
	v_mov_b32_e32 v61, v2
	v_mov_b32_e32 v62, v2
	v_mov_b32_e32 v63, v2
	v_mov_b32_e32 v64, v2
	v_mov_b32_e32 v65, v2
	v_mov_b32_e32 v66, v2
	v_mov_b32_e32 v67, v2
	v_mov_b32_e32 v68, v2
	v_mov_b32_e32 v69, v2
	v_mov_b32_e32 v70, v2
	v_mov_b32_e32 v71, v2
	v_mov_b32_e32 v72, v2
	v_mov_b32_e32 v73, v2
	v_mov_b32_e32 v82, v2
	v_mov_b32_e32 v83, v2
	v_mov_b32_e32 v84, v2
	v_mov_b32_e32 v85, v2
	v_mov_b32_e32 v86, v2
	v_mov_b32_e32 v87, v2
	v_mov_b32_e32 v88, v2
	v_mov_b32_e32 v89, v2
	v_mov_b32_e32 v98, v2
	v_mov_b32_e32 v99, v2
	v_mov_b32_e32 v100, v2
	v_mov_b32_e32 v101, v2
	v_mov_b32_e32 v102, v2
	v_mov_b32_e32 v103, v2
	v_mov_b32_e32 v104, v2
	v_mov_b32_e32 v105, v2
	v_mov_b32_e32 v114, v2
	v_mov_b32_e32 v115, v2
	v_mov_b32_e32 v116, v2
	v_mov_b32_e32 v117, v2
	v_mov_b32_e32 v118, v2
	v_mov_b32_e32 v119, v2
	v_mov_b32_e32 v120, v2
	v_mov_b32_e32 v121, v2
	v_mov_b32_e32 v74, v2
	v_mov_b32_e32 v75, v2
	v_mov_b32_e32 v76, v2
	v_mov_b32_e32 v77, v2
	v_mov_b32_e32 v78, v2
	v_mov_b32_e32 v79, v2
	v_mov_b32_e32 v80, v2
	v_mov_b32_e32 v81, v2
	v_mov_b32_e32 v90, v2
	v_mov_b32_e32 v91, v2
	v_mov_b32_e32 v92, v2
	v_mov_b32_e32 v93, v2
	v_mov_b32_e32 v94, v2
	v_mov_b32_e32 v95, v2
	v_mov_b32_e32 v96, v2
	v_mov_b32_e32 v97, v2
	v_mov_b32_e32 v106, v2
	v_mov_b32_e32 v107, v2
	v_mov_b32_e32 v108, v2
	v_mov_b32_e32 v109, v2
	v_mov_b32_e32 v110, v2
	v_mov_b32_e32 v111, v2
	v_mov_b32_e32 v112, v2
	v_mov_b32_e32 v113, v2
	v_mov_b32_e32 v122, v2
	v_mov_b32_e32 v123, v2
	v_mov_b32_e32 v124, v2
	v_mov_b32_e32 v125, v2
	v_mov_b32_e32 v126, v2
	v_mov_b32_e32 v127, v2
	v_mov_b32_e32 v128, v2
	v_mov_b32_e32 v129, v2
	s_and_b64 vcc, exec, s[12:13]
	s_cbranch_vccnz .Lrb_m3
	s_barrier
.Lrb_m3:
.LBB0_1163:
	s_add_u32 s30, s0, 0xfffe0080
	s_addc_u32 s31, s1, -1
	s_add_i32 s52, 0, 0x10000
	s_cmp_eq_u32 s86, 4
	s_cselect_b32 s35, s21, s31
	s_cselect_b32 s34, s29, s30
	s_cselect_b32 s31, s19, s84
	s_cselect_b32 s30, s61, s83
	s_add_i32 s75, 0, 0x14000
	v_add_u32_e32 v142, s52, v223
	v_add_u32_e32 v158, s75, v223
	ds_read_b128 v[130:133], v142
	ds_read_b128 v[134:137], v142 offset:1024
	ds_read_b128 v[138:141], v142 offset:2048
	ds_read_b128 v[142:145], v142 offset:3072
	ds_read_b128 v[146:149], v158
	ds_read_b128 v[150:153], v158 offset:1024
	ds_read_b128 v[154:157], v158 offset:2048
	ds_read_b128 v[158:161], v158 offset:3072
	v_lshl_add_u64 v[188:189], s[0:1], 0, v[202:203]
	s_add_i32 m0, s27, 0xc000
	ds_read_b128 v[162:165], v225
	ds_read_b128 v[166:169], v225 offset:1024
	ds_read_b128 v[170:173], v225 offset:2048
	ds_read_b128 v[174:177], v225 offset:3072
	ds_read_b128 v[178:181], v225 offset:4096
	ds_read_b128 v[182:185], v225 offset:5120
	ds_read_b128 v[206:209], v225 offset:6144
	ds_read_b128 v[210:213], v225 offset:7168
	global_load_lds_dwordx4 v[188:189], off
	v_lshl_add_u64 v[188:189], s[0:1], 0, v[204:205]
	s_add_i32 m0, s27, 0xe000
	s_nop 0
	global_load_lds_dwordx4 v[188:189], off
	s_waitcnt vmcnt(8)
	s_waitcnt lgkmcnt(0)
	s_barrier
; #define PG8_STAGE(bufoff, gbase, voff) do { _Pragma("unroll") for (int _i = 0; _i < 2; ++_i) \
;         __builtin_amdgcn_global_load_lds((const unsigned*)((const char*)(gbase) + (voff)[_i]), (PG8_LAS unsigned*)(lds + (bufoff) + ldsw + _i * 8192), 16, 0, 0); } while (0)
; #define PG8_LDA(dst, b, h) do { _Pragma("unroll") for (int m = 0; m < 4; ++m) _Pragma("unroll") for (int k = 0; k < 2; ++k) dst[m][k] = *(const PG8_LAS bf16x8*)(lds + PG8_SA(b, h) + aoff + m * 2048 + k * 1024); } while (0)
; #define PG8_LDB(dst, b, h) do { _Pragma("unroll") for (int n = 0; n < 2; ++n) _Pragma("unroll") for (int k = 0; k < 2; ++k) dst[n][k] = *(const PG8_LAS bf16x8*)(lds + PG8_SB(b, h) + boff + n * 2048 + k * 1024); } while (0)
; #define PG8_MMA(ai, bj, At, Bt) do { __builtin_amdgcn_s_setprio(1); _Pragma("unroll") for (int m = 0; m < 4; ++m) _Pragma("unroll") for (int n = 0; n < 2; ++n) _Pragma("unroll") for (int k = 0; k < 2; ++k) \
;         acc[ai][bj][m][n] = __builtin_amdgcn_mfma_f32_16x16x32_bf16(Bt[n][k], At[m][k], acc[ai][bj][m][n], 0, 0, 0); __builtin_amdgcn_s_setprio(0); } while (0)
; #define PG8_WAIT_V(n) asm volatile("s_waitcnt vmcnt(" #n ")" ::: "memory")
; #define PG8_WAIT_L(n) asm volatile("s_waitcnt lgkmcnt(" #n ")" ::: "memory")
; #define PG8_BAR __builtin_amdgcn_s_barrier()
; #define PG8_SCHED __builtin_amdgcn_sched_barrier(0)
; template <class Epi, class Sched, bool ALIGN_EPI = false, bool SP2 = false, bool ABLK = false, bool BBLK = false>
; __device__ __forceinline__ void gemm_phase(PG8_LAS unsigned char* lds, const Gemm g, const Sched& S, const Epi& E) {
;     ...
;             PG8_WAIT_V(8); PG8_WAIT_L(0); PG8_BAR; PG8_MMA(0, 0, At, B0); PG8_MMA(0, 1, At, B1); PG8_BAR; PG8_SCHED;
;             PG8_LDA(At, 0, 1); PG8_STAGE(PG8_SB(0, 0), b2, voffB); PG8_STAGE(PG8_SB(0, 1), b2 + hstepB, voffB); PG8_STAGE(PG8_SA(0, 0), a2, voffA);
;             PG8_WAIT_V(8); PG8_WAIT_L(0); PG8_BAR; PG8_MMA(1, 0, At, B0); PG8_MMA(1, 1, At, B1); PG8_BAR; PG8_SCHED;
;             PG8_LDB(B0, 1, 0); PG8_LDB(B1, 1, 1); PG8_SCHED; PG8_LDA(At, 1, 0); PG8_STAGE(PG8_SA(0, 1), a2 + hstepA, voffA);
;             PG8_WAIT_V(8); PG8_WAIT_L(0); PG8_BAR; PG8_MMA(0, 0, At, B0); PG8_MMA(0, 1, At, B1); PG8_BAR; PG8_SCHED;
	s_setprio 1
	s_waitcnt lgkmcnt(0)
	v_mfma_f32_16x16x32_bf16 v[126:129], v[130:133], v[162:165], v[126:129]
	v_mfma_f32_16x16x32_bf16 v[122:125], v[138:141], v[162:165], v[122:125]
	v_mfma_f32_16x16x32_bf16 v[110:113], v[130:133], v[170:173], v[110:113]
	v_mfma_f32_16x16x32_bf16 v[106:109], v[138:141], v[170:173], v[106:109]
	v_mfma_f32_16x16x32_bf16 v[94:97], v[130:133], v[178:181], v[94:97]
	v_mfma_f32_16x16x32_bf16 v[90:93], v[138:141], v[178:181], v[90:93]
	v_mfma_f32_16x16x32_bf16 v[78:81], v[130:133], v[206:209], v[78:81]
	v_mfma_f32_16x16x32_bf16 v[74:77], v[138:141], v[206:209], v[74:77]
	v_mfma_f32_16x16x32_bf16 v[126:129], v[134:137], v[166:169], v[126:129]
	v_mfma_f32_16x16x32_bf16 v[122:125], v[142:145], v[166:169], v[122:125]
	v_mfma_f32_16x16x32_bf16 v[110:113], v[134:137], v[174:177], v[110:113]
	v_mfma_f32_16x16x32_bf16 v[106:109], v[142:145], v[174:177], v[106:109]
	v_mfma_f32_16x16x32_bf16 v[94:97], v[134:137], v[182:185], v[94:97]
	v_mfma_f32_16x16x32_bf16 v[90:93], v[142:145], v[182:185], v[90:93]
	v_mfma_f32_16x16x32_bf16 v[78:81], v[134:137], v[210:213], v[78:81]
	v_mfma_f32_16x16x32_bf16 v[74:77], v[142:145], v[210:213], v[74:77]
	s_setprio 0
	s_setprio 1
	v_mfma_f32_16x16x32_bf16 v[118:121], v[146:149], v[162:165], v[118:121]
	v_mfma_f32_16x16x32_bf16 v[114:117], v[154:157], v[162:165], v[114:117]
	v_mfma_f32_16x16x32_bf16 v[102:105], v[146:149], v[170:173], v[102:105]
	v_mfma_f32_16x16x32_bf16 v[98:101], v[154:157], v[170:173], v[98:101]
	v_mfma_f32_16x16x32_bf16 v[86:89], v[146:149], v[178:181], v[86:89]
	v_mfma_f32_16x16x32_bf16 v[82:85], v[154:157], v[178:181], v[82:85]
	v_mfma_f32_16x16x32_bf16 v[70:73], v[146:149], v[206:209], v[70:73]
	v_mfma_f32_16x16x32_bf16 v[66:69], v[154:157], v[206:209], v[66:69]
	v_mfma_f32_16x16x32_bf16 v[118:121], v[150:153], v[166:169], v[118:121]
	v_mfma_f32_16x16x32_bf16 v[114:117], v[158:161], v[166:169], v[114:117]
	v_mfma_f32_16x16x32_bf16 v[102:105], v[150:153], v[174:177], v[102:105]
	v_mfma_f32_16x16x32_bf16 v[98:101], v[158:161], v[174:177], v[98:101]
	v_mfma_f32_16x16x32_bf16 v[86:89], v[150:153], v[182:185], v[86:89]
	v_mfma_f32_16x16x32_bf16 v[82:85], v[158:161], v[182:185], v[82:85]
	v_mfma_f32_16x16x32_bf16 v[70:73], v[150:153], v[210:213], v[70:73]
	v_mfma_f32_16x16x32_bf16 v[66:69], v[158:161], v[210:213], v[66:69]
	s_setprio 0
	s_barrier
	s_add_i32 s52, s52, s45
	v_lshl_add_u64 v[188:189], s[30:31], 0, v[196:197]
	s_mov_b32 m0, s52
	ds_read_b128 v[162:165], v225 offset:16384
	ds_read_b128 v[166:169], v225 offset:17408
	ds_read_b128 v[170:173], v225 offset:18432
	ds_read_b128 v[174:177], v225 offset:19456
	ds_read_b128 v[178:181], v225 offset:20480
	ds_read_b128 v[182:185], v225 offset:21504
	ds_read_b128 v[206:209], v225 offset:22528
	ds_read_b128 v[210:213], v225 offset:23552
	global_load_lds_dwordx4 v[188:189], off
	s_add_i32 m0, s52, 0x2000
	s_add_u32 s88, s30, 0x4000
	v_lshl_add_u64 v[188:189], s[30:31], 0, v[200:201]
	s_addc_u32 s89, s31, 0
	s_add_i32 s52, s75, s45
	global_load_lds_dwordx4 v[188:189], off
	v_lshl_add_u64 v[188:189], s[88:89], 0, v[196:197]
	s_mov_b32 m0, s52
	v_lshl_add_u64 v[190:191], s[34:35], 0, v[198:199]
	global_load_lds_dwordx4 v[188:189], off
	v_lshl_add_u64 v[188:189], s[88:89], 0, v[200:201]
	s_add_i32 m0, s52, 0x2000
	s_nop 0
	global_load_lds_dwordx4 v[188:189], off
	v_lshl_add_u64 v[188:189], s[34:35], 0, v[186:187]
	s_mov_b32 m0, s27
	s_nop 0
	global_load_lds_dwordx4 v[188:189], off
	s_mov_b32 m0, s46
	s_nop 0
	global_load_lds_dwordx4 v[190:191], off
	s_waitcnt vmcnt(8)
	s_waitcnt lgkmcnt(0)
	s_barrier
	s_setprio 1
	s_waitcnt lgkmcnt(0)
	v_mfma_f32_16x16x32_bf16 v[62:65], v[130:133], v[162:165], v[62:65]
	v_mfma_f32_16x16x32_bf16 v[58:61], v[138:141], v[162:165], v[58:61]
	v_mfma_f32_16x16x32_bf16 v[46:49], v[130:133], v[170:173], v[46:49]
	v_mfma_f32_16x16x32_bf16 v[42:45], v[138:141], v[170:173], v[42:45]
	v_mfma_f32_16x16x32_bf16 v[30:33], v[130:133], v[178:181], v[30:33]
	v_mfma_f32_16x16x32_bf16 v[26:29], v[138:141], v[178:181], v[26:29]
	v_mfma_f32_16x16x32_bf16 v[14:17], v[130:133], v[206:209], v[14:17]
	v_mfma_f32_16x16x32_bf16 v[10:13], v[138:141], v[206:209], v[10:13]
	v_mfma_f32_16x16x32_bf16 v[62:65], v[134:137], v[166:169], v[62:65]
	v_mfma_f32_16x16x32_bf16 v[58:61], v[142:145], v[166:169], v[58:61]
	v_mfma_f32_16x16x32_bf16 v[46:49], v[134:137], v[174:177], v[46:49]
	v_mfma_f32_16x16x32_bf16 v[42:45], v[142:145], v[174:177], v[42:45]
	v_mfma_f32_16x16x32_bf16 v[30:33], v[134:137], v[182:185], v[30:33]
	v_mfma_f32_16x16x32_bf16 v[26:29], v[142:145], v[182:185], v[26:29]
	v_mfma_f32_16x16x32_bf16 v[14:17], v[134:137], v[210:213], v[14:17]
	v_mfma_f32_16x16x32_bf16 v[10:13], v[142:145], v[210:213], v[10:13]
	s_setprio 0
	s_setprio 1
	v_mfma_f32_16x16x32_bf16 v[54:57], v[146:149], v[162:165], v[54:57]
	v_mfma_f32_16x16x32_bf16 v[50:53], v[154:157], v[162:165], v[50:53]
	v_mfma_f32_16x16x32_bf16 v[38:41], v[146:149], v[170:173], v[38:41]
	v_mfma_f32_16x16x32_bf16 v[34:37], v[154:157], v[170:173], v[34:37]
	v_mfma_f32_16x16x32_bf16 v[22:25], v[146:149], v[178:181], v[22:25]
	v_mfma_f32_16x16x32_bf16 v[18:21], v[154:157], v[178:181], v[18:21]
	v_mfma_f32_16x16x32_bf16 v[6:9], v[146:149], v[206:209], v[6:9]
	v_mfma_f32_16x16x32_bf16 v[2:5], v[154:157], v[206:209], v[2:5]
	v_mfma_f32_16x16x32_bf16 v[54:57], v[150:153], v[166:169], v[54:57]
	v_mfma_f32_16x16x32_bf16 v[50:53], v[158:161], v[166:169], v[50:53]
	v_mfma_f32_16x16x32_bf16 v[38:41], v[150:153], v[174:177], v[38:41]
	v_mfma_f32_16x16x32_bf16 v[34:37], v[158:161], v[174:177], v[34:37]
	v_mfma_f32_16x16x32_bf16 v[22:25], v[150:153], v[182:185], v[22:25]
	v_mfma_f32_16x16x32_bf16 v[18:21], v[158:161], v[182:185], v[18:21]
	v_mfma_f32_16x16x32_bf16 v[6:9], v[150:153], v[210:213], v[6:9]
	v_mfma_f32_16x16x32_bf16 v[2:5], v[158:161], v[210:213], v[2:5]
	s_setprio 0
	s_barrier
; #define PG8_STAGE(bufoff, gbase, voff) do { _Pragma("unroll") for (int _i = 0; _i < 2; ++_i) \
;         __builtin_amdgcn_global_load_lds((const unsigned*)((const char*)(gbase) + (voff)[_i]), (PG8_LAS unsigned*)(lds + (bufoff) + ldsw + _i * 8192), 16, 0, 0); } while (0)
; #define PG8_LDA(dst, b, h) do { _Pragma("unroll") for (int m = 0; m < 4; ++m) _Pragma("unroll") for (int k = 0; k < 2; ++k) dst[m][k] = *(const PG8_LAS bf16x8*)(lds + PG8_SA(b, h) + aoff + m * 2048 + k * 1024); } while (0)
; #define PG8_LDB(dst, b, h) do { _Pragma("unroll") for (int n = 0; n < 2; ++n) _Pragma("unroll") for (int k = 0; k < 2; ++k) dst[n][k] = *(const PG8_LAS bf16x8*)(lds + PG8_SB(b, h) + boff + n * 2048 + k * 1024); } while (0)
; #define PG8_MMA(ai, bj, At, Bt) do { __builtin_amdgcn_s_setprio(1); _Pragma("unroll") for (int m = 0; m < 4; ++m) _Pragma("unroll") for (int n = 0; n < 2; ++n) _Pragma("unroll") for (int k = 0; k < 2; ++k) \
;         acc[ai][bj][m][n] = __builtin_amdgcn_mfma_f32_16x16x32_bf16(Bt[n][k], At[m][k], acc[ai][bj][m][n], 0, 0, 0); __builtin_amdgcn_s_setprio(0); } while (0)
; #define PG8_WAIT_V(n) asm volatile("s_waitcnt vmcnt(" #n ")" ::: "memory")
; #define PG8_WAIT_L(n) asm volatile("s_waitcnt lgkmcnt(" #n ")" ::: "memory")
; #define PG8_BAR __builtin_amdgcn_s_barrier()
; #define PG8_SCHED __builtin_amdgcn_sched_barrier(0)
; template <class Epi, class Sched, bool ALIGN_EPI = false, bool SP2 = false, bool ABLK = false, bool BBLK = false>
; __device__ __forceinline__ void gemm_phase(PG8_LAS unsigned char* lds, const Gemm g, const Sched& S, const Epi& E) {
;     ...
;             PG8_LDB(B0, 1, 0); PG8_LDB(B1, 1, 1); PG8_SCHED; PG8_LDA(At, 1, 0); PG8_STAGE(PG8_SA(0, 1), a2 + hstepA, voffA);
;             PG8_WAIT_V(8); PG8_WAIT_L(0); PG8_BAR; PG8_MMA(0, 0, At, B0); PG8_MMA(0, 1, At, B1); PG8_BAR; PG8_SCHED;
;             PG8_LDA(At, 1, 1); PG8_STAGE(PG8_SB(1, 0), b3, voffB); PG8_STAGE(PG8_SB(1, 1), b3 + hstepB, voffB); PG8_STAGE(PG8_SA(1, 0), a3, voffA);
;             PG8_WAIT_V(8); PG8_WAIT_L(0); PG8_BAR; PG8_MMA(1, 0, At, B0); PG8_MMA(1, 1, At, B1); PG8_BAR; PG8_SCHED;
	s_add_i32 s52, 0, 0x18000
	s_add_i32 s75, 0, 0x1c000
	v_add_u32_e32 v142, s52, v223
	v_add_u32_e32 v158, s75, v223
	ds_read_b128 v[130:133], v142
	ds_read_b128 v[134:137], v142 offset:1024
	ds_read_b128 v[138:141], v142 offset:2048
	ds_read_b128 v[142:145], v142 offset:3072
	ds_read_b128 v[146:149], v158
	ds_read_b128 v[150:153], v158 offset:1024
	ds_read_b128 v[154:157], v158 offset:2048
	ds_read_b128 v[158:161], v158 offset:3072
	s_add_u32 s34, s34, 0x20000
	s_addc_u32 s35, s35, 0
	s_mov_b32 m0, s47
	v_lshl_add_u64 v[192:193], s[34:35], 0, v[186:187]
	ds_read_b128 v[162:165], v225 offset:32768
	ds_read_b128 v[166:169], v225 offset:33792
	ds_read_b128 v[170:173], v225 offset:34816
	ds_read_b128 v[174:177], v225 offset:35840
	ds_read_b128 v[178:181], v225 offset:36864
	ds_read_b128 v[182:185], v225 offset:37888
	ds_read_b128 v[206:209], v225 offset:38912
	ds_read_b128 v[210:213], v225 offset:39936
	global_load_lds_dwordx4 v[192:193], off
	v_lshl_add_u64 v[192:193], s[34:35], 0, v[198:199]
	s_mov_b32 m0, s65
	s_nop 0
	global_load_lds_dwordx4 v[192:193], off
	s_waitcnt vmcnt(8)
	s_waitcnt lgkmcnt(0)
	s_barrier
	s_setprio 1
	s_waitcnt lgkmcnt(0)
	v_mfma_f32_16x16x32_bf16 v[126:129], v[130:133], v[162:165], v[126:129]
	v_mfma_f32_16x16x32_bf16 v[122:125], v[138:141], v[162:165], v[122:125]
	v_mfma_f32_16x16x32_bf16 v[110:113], v[130:133], v[170:173], v[110:113]
	v_mfma_f32_16x16x32_bf16 v[106:109], v[138:141], v[170:173], v[106:109]
	v_mfma_f32_16x16x32_bf16 v[94:97], v[130:133], v[178:181], v[94:97]
	v_mfma_f32_16x16x32_bf16 v[90:93], v[138:141], v[178:181], v[90:93]
	v_mfma_f32_16x16x32_bf16 v[78:81], v[130:133], v[206:209], v[78:81]
	v_mfma_f32_16x16x32_bf16 v[74:77], v[138:141], v[206:209], v[74:77]
	v_mfma_f32_16x16x32_bf16 v[126:129], v[134:137], v[166:169], v[126:129]
	v_mfma_f32_16x16x32_bf16 v[122:125], v[142:145], v[166:169], v[122:125]
	v_mfma_f32_16x16x32_bf16 v[110:113], v[134:137], v[174:177], v[110:113]
	v_mfma_f32_16x16x32_bf16 v[106:109], v[142:145], v[174:177], v[106:109]
	v_mfma_f32_16x16x32_bf16 v[94:97], v[134:137], v[182:185], v[94:97]
	v_mfma_f32_16x16x32_bf16 v[90:93], v[142:145], v[182:185], v[90:93]
	v_mfma_f32_16x16x32_bf16 v[78:81], v[134:137], v[210:213], v[78:81]
	v_mfma_f32_16x16x32_bf16 v[74:77], v[142:145], v[210:213], v[74:77]
	s_setprio 0
	s_setprio 1
	v_mfma_f32_16x16x32_bf16 v[118:121], v[146:149], v[162:165], v[118:121]
	v_mfma_f32_16x16x32_bf16 v[114:117], v[154:157], v[162:165], v[114:117]
	v_mfma_f32_16x16x32_bf16 v[102:105], v[146:149], v[170:173], v[102:105]
	v_mfma_f32_16x16x32_bf16 v[98:101], v[154:157], v[170:173], v[98:101]
	v_mfma_f32_16x16x32_bf16 v[86:89], v[146:149], v[178:181], v[86:89]
	v_mfma_f32_16x16x32_bf16 v[82:85], v[154:157], v[178:181], v[82:85]
	v_mfma_f32_16x16x32_bf16 v[70:73], v[146:149], v[206:209], v[70:73]
	v_mfma_f32_16x16x32_bf16 v[66:69], v[154:157], v[206:209], v[66:69]
	v_mfma_f32_16x16x32_bf16 v[118:121], v[150:153], v[166:169], v[118:121]
	v_mfma_f32_16x16x32_bf16 v[114:117], v[158:161], v[166:169], v[114:117]
	v_mfma_f32_16x16x32_bf16 v[102:105], v[150:153], v[174:177], v[102:105]
	v_mfma_f32_16x16x32_bf16 v[98:101], v[158:161], v[174:177], v[98:101]
	v_mfma_f32_16x16x32_bf16 v[86:89], v[150:153], v[182:185], v[86:89]
	v_mfma_f32_16x16x32_bf16 v[82:85], v[158:161], v[182:185], v[82:85]
	v_mfma_f32_16x16x32_bf16 v[70:73], v[150:153], v[210:213], v[70:73]
	v_mfma_f32_16x16x32_bf16 v[66:69], v[158:161], v[210:213], v[66:69]
	s_setprio 0
	s_barrier
	s_add_u32 s34, s30, 0x8000
	s_addc_u32 s35, s31, 0
	s_add_i32 s52, s52, s45
	v_lshl_add_u64 v[192:193], s[34:35], 0, v[196:197]
	s_mov_b32 m0, s52
	ds_read_b128 v[162:165], v225 offset:49152
	ds_read_b128 v[166:169], v225 offset:50176
	ds_read_b128 v[170:173], v225 offset:51200
	ds_read_b128 v[174:177], v225 offset:52224
	ds_read_b128 v[178:181], v225 offset:53248
	ds_read_b128 v[182:185], v225 offset:54272
	ds_read_b128 v[206:209], v225 offset:55296
	ds_read_b128 v[210:213], v225 offset:56320
	global_load_lds_dwordx4 v[192:193], off
	s_add_i32 m0, s52, 0x2000
	s_add_u32 s30, s30, 0xc000
	v_lshl_add_u64 v[192:193], s[34:35], 0, v[200:201]
	s_addc_u32 s31, s31, 0
	s_add_i32 s34, s75, s45
	global_load_lds_dwordx4 v[192:193], off
	v_lshl_add_u64 v[192:193], s[30:31], 0, v[196:197]
	s_mov_b32 m0, s34
	v_lshl_add_u64 v[188:189], v[188:189], 0, s[62:63]
	global_load_lds_dwordx4 v[192:193], off
	v_lshl_add_u64 v[192:193], s[30:31], 0, v[200:201]
	s_add_i32 m0, s34, 0x2000
	s_nop 0
	global_load_lds_dwordx4 v[192:193], off
	s_mov_b32 m0, s72
	s_nop 0
	global_load_lds_dwordx4 v[188:189], off
	v_lshl_add_u64 v[188:189], v[190:191], 0, s[62:63]
	s_mov_b32 m0, s73
	s_nop 0
	global_load_lds_dwordx4 v[188:189], off
	s_waitcnt vmcnt(8)
	s_waitcnt lgkmcnt(0)
	s_barrier
;     __device__ __forceinline__ void operator()(const f32x4 (&acc)[2][2][4][2], const Unit& u, int wr, int wc, int fr_, int fq) const {
;     ...
;         const size_t row0 = (size_t)u.pm * BM + wr * 64 + fr; const int col0 = u.pn * BM + wc * 32 + 8 * fq;
; #pragma unroll
;         for (int ai = 0; ai < 2; ++ai) {
;             u32x4 gw[4][2], ow[4][2];
; #pragma unroll
;             for (int m = 0; m < 4; ++m)
; #pragma unroll
;                 for (int bj = 0; bj < 2; ++bj) { const size_t r = row0 + ai * HALF + m * 16; const int c = col0 + bj * HALF;
;                     gw[m][bj] = *(const u32x4*)(G + r * 6144 + goff + c); if (!FIRST) ow[m][bj] = *(const u32x4*)(Mo + r * DM + c); }
; template <class Epi, class Sched, bool ALIGN_EPI = false, bool SP2 = false, bool ABLK = false, bool BBLK = false>
; __device__ __forceinline__ void gemm_phase(PG8_LAS unsigned char* lds, const Gemm g, const Sched& S, const Epi& E) {
;     ...
;             PG8_WAIT_V(8); PG8_WAIT_L(0); PG8_BAR; PG8_MMA(1, 0, At, B0); PG8_MMA(1, 1, At, B1); PG8_BAR; PG8_SCHED;
;             } else {
;             PG8_LDB(B0, 0, 0); PG8_SCHED; PG8_LDA(At, 0, 0); PG8_STAGE(PG8_SA(1, 1), a1 + hstepA, voffA);
;             PG8_WAIT_L(8); PG8_BAR; PG8_WAIT_L(0); PG8_MMA(0, 0, At, B0); PG8_BAR; PG8_SCHED;
;             PG8_LDB(B1, 0, 1); PG8_STAGE(PG8_SB(0, 0), b2, voffB);
;             PG8_BAR; PG8_WAIT_L(0); PG8_MMA(0, 1, At, B1); PG8_BAR;
;             PG8_LDA(At, 0, 1); PG8_STAGE(PG8_SA(0, 0), a2, voffA);
;             PG8_BAR; PG8_WAIT_L(0); PG8_MMA(1, 0, At, B0); PG8_BAR; PG8_SCHED;
;             PG8_STAGE(PG8_SB(0, 1), b2 + hstepB, voffB);
;             PG8_WAIT_V(6); PG8_BAR; PG8_MMA(1, 1, At, B1); PG8_BAR;
;             PG8_LDB(B0, 1, 0); PG8_SCHED; PG8_LDA(At, 1, 0); PG8_STAGE(PG8_SA(0, 1), a2 + hstepA, voffA);
;             PG8_WAIT_L(8); PG8_BAR; PG8_WAIT_L(0); PG8_MMA(0, 0, At, B0); PG8_BAR; PG8_SCHED;
;             PG8_LDB(B1, 1, 1); PG8_STAGE(PG8_SB(1, 0), b3, voffB);
;             PG8_BAR; PG8_WAIT_L(0); PG8_MMA(0, 1, At, B1); PG8_BAR;
;             PG8_LDA(At, 1, 1); PG8_STAGE(PG8_SA(1, 0), a3, voffA);
;             PG8_BAR; PG8_WAIT_L(0); PG8_MMA(1, 0, At, B0); PG8_BAR; PG8_SCHED;
;             PG8_STAGE(PG8_SB(1, 1), b3 + hstepB, voffB);
;             PG8_WAIT_V(6); PG8_BAR; PG8_MMA(1, 1, At, B1); PG8_BAR;
;             }
;         }
;         if constexpr (ALIGN_EPI) { if (wr == 0) PG8_BAR; }
	s_setprio 1
	s_waitcnt lgkmcnt(0)
	v_mfma_f32_16x16x32_bf16 v[62:65], v[130:133], v[162:165], v[62:65]
	v_mfma_f32_16x16x32_bf16 v[58:61], v[138:141], v[162:165], v[58:61]
	v_mfma_f32_16x16x32_bf16 v[46:49], v[130:133], v[170:173], v[46:49]
	v_mfma_f32_16x16x32_bf16 v[42:45], v[138:141], v[170:173], v[42:45]
	v_mfma_f32_16x16x32_bf16 v[30:33], v[130:133], v[178:181], v[30:33]
	v_mfma_f32_16x16x32_bf16 v[26:29], v[138:141], v[178:181], v[26:29]
	v_mfma_f32_16x16x32_bf16 v[14:17], v[130:133], v[206:209], v[14:17]
	v_mfma_f32_16x16x32_bf16 v[10:13], v[138:141], v[206:209], v[10:13]
	v_mfma_f32_16x16x32_bf16 v[62:65], v[134:137], v[166:169], v[62:65]
	v_mfma_f32_16x16x32_bf16 v[58:61], v[142:145], v[166:169], v[58:61]
	v_mfma_f32_16x16x32_bf16 v[46:49], v[134:137], v[174:177], v[46:49]
	v_mfma_f32_16x16x32_bf16 v[42:45], v[142:145], v[174:177], v[42:45]
	v_mfma_f32_16x16x32_bf16 v[30:33], v[134:137], v[182:185], v[30:33]
	v_mfma_f32_16x16x32_bf16 v[26:29], v[142:145], v[182:185], v[26:29]
	v_mfma_f32_16x16x32_bf16 v[14:17], v[134:137], v[210:213], v[14:17]
	v_mfma_f32_16x16x32_bf16 v[10:13], v[142:145], v[210:213], v[10:13]
	s_setprio 0
	s_setprio 1
	v_mfma_f32_16x16x32_bf16 v[54:57], v[146:149], v[162:165], v[54:57]
	v_mfma_f32_16x16x32_bf16 v[50:53], v[154:157], v[162:165], v[50:53]
	v_mfma_f32_16x16x32_bf16 v[38:41], v[146:149], v[170:173], v[38:41]
	v_mfma_f32_16x16x32_bf16 v[34:37], v[154:157], v[170:173], v[34:37]
	v_mfma_f32_16x16x32_bf16 v[22:25], v[146:149], v[178:181], v[22:25]
	v_mfma_f32_16x16x32_bf16 v[18:21], v[154:157], v[178:181], v[18:21]
	v_mfma_f32_16x16x32_bf16 v[6:9], v[146:149], v[206:209], v[6:9]
	v_mfma_f32_16x16x32_bf16 v[2:5], v[154:157], v[206:209], v[2:5]
	v_mfma_f32_16x16x32_bf16 v[54:57], v[150:153], v[166:169], v[54:57]
	v_mfma_f32_16x16x32_bf16 v[50:53], v[158:161], v[166:169], v[50:53]
	v_mfma_f32_16x16x32_bf16 v[38:41], v[150:153], v[174:177], v[38:41]
	v_mfma_f32_16x16x32_bf16 v[34:37], v[158:161], v[174:177], v[34:37]
	v_mfma_f32_16x16x32_bf16 v[22:25], v[150:153], v[182:185], v[22:25]
	v_mfma_f32_16x16x32_bf16 v[18:21], v[158:161], v[182:185], v[18:21]
	v_mfma_f32_16x16x32_bf16 v[6:9], v[150:153], v[210:213], v[6:9]
	v_mfma_f32_16x16x32_bf16 v[2:5], v[158:161], v[210:213], v[2:5]
	s_setprio 0
	s_barrier
	s_add_i32 s86, s86, 2
	s_add_u32 s83, s83, 0x10000
	s_addc_u32 s84, s84, 0
	s_add_u32 s0, s0, 0x100
	s_addc_u32 s1, s1, 0
	s_cmp_gt_u32 s86, 5
	s_cbranch_scc0 .LBB0_1163
	s_and_b64 vcc, exec, s[12:13]
	s_cbranch_vccz .LBB0_1166
	s_barrier
.LBB0_1166:
	s_ashr_i32 s29, s28, 31
	s_lshl_b64 s[0:1], s[28:29], 8
	v_mov_b32_e32 v130, v222
	s_add_u32 s0, s0, s68
	s_addc_u32 s1, s1, s81
	v_ashrrev_i32_e32 v131, 31, v130
	v_lshl_add_u64 v[130:131], s[0:1], 0, v[130:131]
	v_lshl_or_b32 v132, s26, 8, v224
	v_mov_b64_e32 v[134:135], s[14:15]
	s_movk_i32 s19, 0x3000
	v_ashrrev_i32_e32 v133, 31, v132
	v_mad_u64_u32 v[134:135], s[0:1], v130, s19, v[134:135]
	v_mad_i32_i24 v135, v131, s19, v135
	v_lshlrev_b64 v[132:133], 1, v[132:133]
	v_lshlrev_b64 v[130:131], 12, v[130:131]
	v_lshl_add_u64 v[206:207], v[134:135], 0, v[132:133]
	v_lshl_add_u64 v[130:131], s[2:3], 0, v[130:131]
	global_load_dwordx4 v[226:229], v[206:207], off
	v_lshl_add_u64 v[208:209], v[130:131], 0, v[132:133]
	global_load_dwordx4 v[244:247], v[208:209], off
	global_load_dwordx4 v[182:185], v[206:207], off offset:256
	global_load_dwordx4 v[178:181], v[208:209], off offset:256
	v_add_co_u32_e32 v132, vcc, s91, v206
	s_mov_b64 s[28:29], 0x30000
	s_nop 0
	v_addc_co_u32_e32 v133, vcc, 0, v207, vcc
	global_load_dwordx4 v[170:173], v[132:133], off
	v_add_co_u32_e32 v220, vcc, s80, v208
	v_lshl_add_u64 v[130:131], v[206:207], 0, s[28:29]
	s_nop 0
	v_addc_co_u32_e32 v221, vcc, 0, v209, vcc
	v_lshl_add_u64 v[218:219], v[208:209], 0, s[48:49]
	global_load_dwordx4 v[174:177], v[220:221], off
	global_load_dwordx4 v[166:169], v[130:131], off offset:256
	global_load_dwordx4 v[162:165], v[218:219], off offset:256
	v_add_co_u32_e32 v132, vcc, s94, v206
	s_mov_b64 s[0:1], 0x60000
	s_nop 0
	v_addc_co_u32_e32 v133, vcc, 0, v207, vcc
	global_load_dwordx4 v[154:157], v[132:133], off
	v_add_co_u32_e32 v216, vcc, s95, v208
	v_lshl_add_u64 v[130:131], v[206:207], 0, s[0:1]
	s_mov_b64 s[0:1], 0x20000
	v_addc_co_u32_e32 v217, vcc, 0, v209, vcc
	v_lshl_add_u64 v[214:215], v[208:209], 0, s[0:1]
	global_load_dwordx4 v[158:161], v[216:217], off
	global_load_dwordx4 v[150:153], v[130:131], off offset:256
	global_load_dwordx4 v[146:149], v[214:215], off offset:256
	s_mov_b32 s0, 0x90000
	v_add_co_u32_e32 v132, vcc, s0, v206
	s_mov_b64 s[30:31], 0x90000
	s_nop 0
	v_addc_co_u32_e32 v133, vcc, 0, v207, vcc
	global_load_dwordx4 v[138:141], v[132:133], off
	v_add_co_u32_e32 v212, vcc, s91, v208
	v_lshl_add_u64 v[130:131], v[206:207], 0, s[30:31]
	s_nop 0
	v_addc_co_u32_e32 v213, vcc, 0, v209, vcc
	v_lshl_add_u64 v[210:211], v[208:209], 0, s[28:29]
	global_load_dwordx4 v[142:145], v[212:213], off
	global_load_dwordx4 v[134:137], v[130:131], off offset:256
	s_nop 0
	global_load_dwordx4 v[130:133], v[210:211], off offset:256
	s_mov_b32 s1, 0x180000
	s_mov_b32 s52, 0x80000
	s_mov_b64 s[28:29], 0x180000
	s_mov_b32 s86, 0x9000
	s_mov_b32 s88, 0xf800000
	s_movk_i32 s89, 0xffe0
	s_waitcnt vmcnt(0)
; __device__ __forceinline__ u32x4 pack8(const f32x4 v0, const f32x4 v1) { u32x4 w; w.x = cvt_pk_bf16(v0[0], v0[1]); w.y = cvt_pk_bf16(v0[2], v0[3]); w.z = cvt_pk_bf16(v1[0], v1[1]); w.w = cvt_pk_bf16(v1[2], v1[3]); return w; }
;     __device__ __forceinline__ void operator()(const f32x4 (&acc)[2][2][4][2], const Unit& u, int wr, int wc, int fr_, int fq) const {
;     ...
; #pragma unroll
;             for (int m = 0; m < 4; ++m)
; #pragma unroll
;                 for (int bj = 0; bj < 2; ++bj) { const size_t r = row0 + ai * HALF + m * 16; const int c = col0 + bj * HALF;
;                     f32x4 g0, g1; unpack8(gw[m][bj], g0, g1);
;                     f32x4 v0 = g0 * acc[ai][bj][m][0], v1 = g1 * acc[ai][bj][m][1];
;                     if (!FIRST) { f32x4 o0, o1; unpack8(ow[m][bj], o0, o1); v0 += o0; v1 += o1; }
;                     *(u32x4*)((Mdst ? Mdst : Mo) + r * DM + c) = pack8(v0, v1); }
	v_lshlrev_b32_e32 v248, 16, v246
	v_lshlrev_b32_e32 v188, 16, v226
	v_and_b32_e32 v189, 0xffff0000, v226
	v_lshlrev_b32_e32 v190, 16, v227
	v_and_b32_e32 v191, 0xffff0000, v227
	v_lshlrev_b32_e32 v192, 16, v228
	v_and_b32_e32 v193, 0xffff0000, v228
	v_lshlrev_b32_e32 v226, 16, v229
	v_and_b32_e32 v227, 0xffff0000, v229
	v_lshlrev_b32_e32 v228, 16, v244
	v_and_b32_e32 v229, 0xffff0000, v244
	v_and_b32_e32 v249, 0xffff0000, v246
	v_lshlrev_b32_e32 v246, 16, v247
	v_and_b32_e32 v247, 0xffff0000, v247
	v_lshlrev_b32_e32 v244, 16, v245
	v_and_b32_e32 v245, 0xffff0000, v245
	v_pk_fma_f32 v[126:127], v[126:127], v[188:189], v[228:229]
	v_pk_fma_f32 v[188:189], v[124:125], v[226:227], v[246:247]
	v_pk_fma_f32 v[124:125], v[122:123], v[192:193], v[248:249]
	v_pk_fma_f32 v[128:129], v[128:129], v[190:191], v[244:245]
	v_cvt_pk_bf16_f32 v122, v126, v127
	v_lshlrev_b32_e32 v126, 16, v184
	v_cvt_pk_bf16_f32 v123, v128, v129
	v_cvt_pk_bf16_f32 v124, v124, v125
	v_cvt_pk_bf16_f32 v125, v188, v189
	global_store_dwordx4 v[208:209], v[122:125], off
	v_and_b32_e32 v127, 0xffff0000, v184
	v_lshlrev_b32_e32 v128, 16, v185
	v_lshlrev_b32_e32 v122, 16, v182
	v_and_b32_e32 v123, 0xffff0000, v182
	v_lshlrev_b32_e32 v124, 16, v183
	v_and_b32_e32 v125, 0xffff0000, v183
	v_and_b32_e32 v129, 0xffff0000, v185
	v_lshlrev_b32_e32 v182, 16, v178
	v_and_b32_e32 v183, 0xffff0000, v178
	v_lshlrev_b32_e32 v184, 16, v180
	v_and_b32_e32 v185, 0xffff0000, v180
	v_lshlrev_b32_e32 v180, 16, v181
	v_and_b32_e32 v181, 0xffff0000, v181
	v_lshlrev_b32_e32 v178, 16, v179
	v_and_b32_e32 v179, 0xffff0000, v179
	v_pk_fma_f32 v[118:119], v[118:119], v[122:123], v[182:183]
	v_pk_fma_f32 v[122:123], v[116:117], v[128:129], v[180:181]
	v_pk_fma_f32 v[116:117], v[114:115], v[126:127], v[184:185]
	v_pk_fma_f32 v[120:121], v[120:121], v[124:125], v[178:179]
	v_cvt_pk_bf16_f32 v114, v118, v119
	v_lshlrev_b32_e32 v118, 16, v172
	v_cvt_pk_bf16_f32 v115, v120, v121
	v_cvt_pk_bf16_f32 v116, v116, v117
	v_cvt_pk_bf16_f32 v117, v122, v123
	global_store_dwordx4 v[208:209], v[114:117], off offset:256
	v_and_b32_e32 v119, 0xffff0000, v172
	v_lshlrev_b32_e32 v120, 16, v173
	v_lshlrev_b32_e32 v114, 16, v170
	v_and_b32_e32 v115, 0xffff0000, v170
	v_lshlrev_b32_e32 v116, 16, v171
	v_and_b32_e32 v117, 0xffff0000, v171
	v_and_b32_e32 v121, 0xffff0000, v173
	v_lshlrev_b32_e32 v122, 16, v174
	v_and_b32_e32 v123, 0xffff0000, v174
	v_lshlrev_b32_e32 v124, 16, v175
	v_and_b32_e32 v125, 0xffff0000, v175
	v_lshlrev_b32_e32 v126, 16, v176
	v_and_b32_e32 v127, 0xffff0000, v176
	v_lshlrev_b32_e32 v128, 16, v177
	v_and_b32_e32 v129, 0xffff0000, v177
	v_pk_fma_f32 v[112:113], v[112:113], v[116:117], v[124:125]
	v_pk_fma_f32 v[110:111], v[110:111], v[114:115], v[122:123]
	v_pk_fma_f32 v[114:115], v[108:109], v[120:121], v[128:129]
	v_pk_fma_f32 v[108:109], v[106:107], v[118:119], v[126:127]
	v_cvt_pk_bf16_f32 v106, v110, v111
	v_cvt_pk_bf16_f32 v107, v112, v113
	v_lshlrev_b32_e32 v110, 16, v168
	v_cvt_pk_bf16_f32 v108, v108, v109
	v_cvt_pk_bf16_f32 v109, v114, v115
	global_store_dwordx4 v[220:221], v[106:109], off
	v_and_b32_e32 v111, 0xffff0000, v168
	v_lshlrev_b32_e32 v112, 16, v169
	v_lshlrev_b32_e32 v106, 16, v166
	v_and_b32_e32 v107, 0xffff0000, v166
	v_and_b32_e32 v113, 0xffff0000, v169
	v_lshlrev_b32_e32 v114, 16, v162
	v_and_b32_e32 v115, 0xffff0000, v162
	v_lshlrev_b32_e32 v118, 16, v164
	v_and_b32_e32 v119, 0xffff0000, v164
	v_lshlrev_b32_e32 v120, 16, v165
	v_and_b32_e32 v121, 0xffff0000, v165
	v_lshlrev_b32_e32 v108, 16, v167
	v_and_b32_e32 v109, 0xffff0000, v167
	v_lshlrev_b32_e32 v116, 16, v163
	v_and_b32_e32 v117, 0xffff0000, v163
	v_pk_fma_f32 v[102:103], v[102:103], v[106:107], v[114:115]
	v_pk_fma_f32 v[106:107], v[100:101], v[112:113], v[120:121]
	v_pk_fma_f32 v[100:101], v[98:99], v[110:111], v[118:119]
	v_pk_fma_f32 v[104:105], v[104:105], v[108:109], v[116:117]
	v_cvt_pk_bf16_f32 v98, v102, v103
	v_lshlrev_b32_e32 v102, 16, v156
	v_cvt_pk_bf16_f32 v99, v104, v105
	v_cvt_pk_bf16_f32 v100, v100, v101
	v_cvt_pk_bf16_f32 v101, v106, v107
	global_store_dwordx4 v[218:219], v[98:101], off offset:256
	v_and_b32_e32 v103, 0xffff0000, v156
	v_lshlrev_b32_e32 v104, 16, v157
	v_lshlrev_b32_e32 v98, 16, v154
	v_and_b32_e32 v99, 0xffff0000, v154
	v_lshlrev_b32_e32 v100, 16, v155
	v_and_b32_e32 v101, 0xffff0000, v155
	v_and_b32_e32 v105, 0xffff0000, v157
	v_lshlrev_b32_e32 v106, 16, v158
	v_and_b32_e32 v107, 0xffff0000, v158
	v_lshlrev_b32_e32 v108, 16, v159
	v_and_b32_e32 v109, 0xffff0000, v159
	v_lshlrev_b32_e32 v110, 16, v160
	v_and_b32_e32 v111, 0xffff0000, v160
	v_lshlrev_b32_e32 v112, 16, v161
	v_and_b32_e32 v113, 0xffff0000, v161
	v_pk_fma_f32 v[96:97], v[96:97], v[100:101], v[108:109]
	v_pk_fma_f32 v[94:95], v[94:95], v[98:99], v[106:107]
	v_pk_fma_f32 v[98:99], v[92:93], v[104:105], v[112:113]
	v_pk_fma_f32 v[92:93], v[90:91], v[102:103], v[110:111]
	v_cvt_pk_bf16_f32 v90, v94, v95
	v_cvt_pk_bf16_f32 v91, v96, v97
	v_lshlrev_b32_e32 v94, 16, v152
	v_cvt_pk_bf16_f32 v92, v92, v93
	v_cvt_pk_bf16_f32 v93, v98, v99
	global_store_dwordx4 v[216:217], v[90:93], off
	v_and_b32_e32 v95, 0xffff0000, v152
	v_lshlrev_b32_e32 v96, 16, v153
	v_lshlrev_b32_e32 v90, 16, v150
	v_and_b32_e32 v91, 0xffff0000, v150
	v_and_b32_e32 v97, 0xffff0000, v153
	v_lshlrev_b32_e32 v98, 16, v146
	v_and_b32_e32 v99, 0xffff0000, v146
	v_lshlrev_b32_e32 v102, 16, v148
	v_and_b32_e32 v103, 0xffff0000, v148
	v_lshlrev_b32_e32 v104, 16, v149
	v_and_b32_e32 v105, 0xffff0000, v149
	v_lshlrev_b32_e32 v92, 16, v151
	v_and_b32_e32 v93, 0xffff0000, v151
	v_lshlrev_b32_e32 v100, 16, v147
	v_and_b32_e32 v101, 0xffff0000, v147
; __device__ __forceinline__ u32x4 pack8(const f32x4 v0, const f32x4 v1) { u32x4 w; w.x = cvt_pk_bf16(v0[0], v0[1]); w.y = cvt_pk_bf16(v0[2], v0[3]); w.z = cvt_pk_bf16(v1[0], v1[1]); w.w = cvt_pk_bf16(v1[2], v1[3]); return w; }
;     __device__ __forceinline__ void operator()(const f32x4 (&acc)[2][2][4][2], const Unit& u, int wr, int wc, int fr_, int fq) const {
;     ...
;         for (int ai = 0; ai < 2; ++ai) {
;             u32x4 gw[4][2], ow[4][2];
; #pragma unroll
;             for (int m = 0; m < 4; ++m)
; #pragma unroll
;                 for (int bj = 0; bj < 2; ++bj) { const size_t r = row0 + ai * HALF + m * 16; const int c = col0 + bj * HALF;
;                     gw[m][bj] = *(const u32x4*)(G + r * 6144 + goff + c); if (!FIRST) ow[m][bj] = *(const u32x4*)(Mo + r * DM + c); }
; #pragma unroll
;             for (int m = 0; m < 4; ++m)
; #pragma unroll
;                 for (int bj = 0; bj < 2; ++bj) { const size_t r = row0 + ai * HALF + m * 16; const int c = col0 + bj * HALF;
;                     f32x4 g0, g1; unpack8(gw[m][bj], g0, g1);
;                     f32x4 v0 = g0 * acc[ai][bj][m][0], v1 = g1 * acc[ai][bj][m][1];
;                     if (!FIRST) { f32x4 o0, o1; unpack8(ow[m][bj], o0, o1); v0 += o0; v1 += o1; }
;                     *(u32x4*)((Mdst ? Mdst : Mo) + r * DM + c) = pack8(v0, v1); }
;             asm volatile("" ::: "memory"); }
	v_pk_fma_f32 v[86:87], v[86:87], v[90:91], v[98:99]
	v_pk_fma_f32 v[90:91], v[84:85], v[96:97], v[104:105]
	v_pk_fma_f32 v[84:85], v[82:83], v[94:95], v[102:103]
	v_pk_fma_f32 v[88:89], v[88:89], v[92:93], v[100:101]
	v_cvt_pk_bf16_f32 v82, v86, v87
	v_lshlrev_b32_e32 v86, 16, v140
	v_cvt_pk_bf16_f32 v83, v88, v89
	v_cvt_pk_bf16_f32 v84, v84, v85
	v_cvt_pk_bf16_f32 v85, v90, v91
	global_store_dwordx4 v[214:215], v[82:85], off offset:256
	v_and_b32_e32 v87, 0xffff0000, v140
	v_lshlrev_b32_e32 v88, 16, v141
	v_lshlrev_b32_e32 v82, 16, v138
	v_and_b32_e32 v83, 0xffff0000, v138
	v_lshlrev_b32_e32 v84, 16, v139
	v_and_b32_e32 v85, 0xffff0000, v139
	v_and_b32_e32 v89, 0xffff0000, v141
	v_lshlrev_b32_e32 v90, 16, v142
	v_and_b32_e32 v91, 0xffff0000, v142
	v_lshlrev_b32_e32 v92, 16, v143
	v_and_b32_e32 v93, 0xffff0000, v143
	v_lshlrev_b32_e32 v94, 16, v144
	v_and_b32_e32 v95, 0xffff0000, v144
	v_lshlrev_b32_e32 v96, 16, v145
	v_and_b32_e32 v97, 0xffff0000, v145
	v_pk_fma_f32 v[80:81], v[80:81], v[84:85], v[92:93]
	v_pk_fma_f32 v[78:79], v[78:79], v[82:83], v[90:91]
	v_pk_fma_f32 v[82:83], v[76:77], v[88:89], v[96:97]
	v_pk_fma_f32 v[76:77], v[74:75], v[86:87], v[94:95]
	v_cvt_pk_bf16_f32 v74, v78, v79
	v_cvt_pk_bf16_f32 v75, v80, v81
	v_lshlrev_b32_e32 v78, 16, v136
	v_cvt_pk_bf16_f32 v76, v76, v77
	v_cvt_pk_bf16_f32 v77, v82, v83
	global_store_dwordx4 v[212:213], v[74:77], off
	v_and_b32_e32 v79, 0xffff0000, v136
	v_lshlrev_b32_e32 v80, 16, v137
	v_lshlrev_b32_e32 v74, 16, v134
	v_and_b32_e32 v75, 0xffff0000, v134
	v_and_b32_e32 v81, 0xffff0000, v137
	v_lshlrev_b32_e32 v82, 16, v130
	v_and_b32_e32 v83, 0xffff0000, v130
	v_lshlrev_b32_e32 v86, 16, v132
	v_and_b32_e32 v87, 0xffff0000, v132
	v_lshlrev_b32_e32 v88, 16, v133
	v_and_b32_e32 v89, 0xffff0000, v133
	v_lshlrev_b32_e32 v76, 16, v135
	v_and_b32_e32 v77, 0xffff0000, v135
	v_lshlrev_b32_e32 v84, 16, v131
	v_and_b32_e32 v85, 0xffff0000, v131
	v_pk_fma_f32 v[70:71], v[70:71], v[74:75], v[82:83]
	v_pk_fma_f32 v[74:75], v[68:69], v[80:81], v[88:89]
	v_pk_fma_f32 v[68:69], v[66:67], v[78:79], v[86:87]
	v_pk_fma_f32 v[72:73], v[72:73], v[76:77], v[84:85]
	v_cvt_pk_bf16_f32 v66, v70, v71
	v_lshl_add_u64 v[106:107], v[208:209], 0, s[30:31]
	v_cvt_pk_bf16_f32 v67, v72, v73
	v_cvt_pk_bf16_f32 v68, v68, v69
	v_cvt_pk_bf16_f32 v69, v74, v75
	global_store_dwordx4 v[210:211], v[66:69], off offset:256
	s_nop 1
	v_add_co_u32_e32 v68, vcc, s1, v206
	v_lshl_add_u64 v[66:67], v[206:207], 0, s[28:29]
	s_nop 0
	v_addc_co_u32_e32 v69, vcc, 0, v207, vcc
	global_load_dwordx4 v[108:111], v[68:69], off
	v_add_co_u32_e32 v142, vcc, s52, v208
	s_mov_b64 s[28:29], 0x80000
	s_nop 0
	v_addc_co_u32_e32 v143, vcc, 0, v209, vcc
	v_lshl_add_u64 v[140:141], v[208:209], 0, s[28:29]
	global_load_dwordx4 v[112:115], v[142:143], off
	global_load_dwordx4 v[116:119], v[66:67], off offset:256
	global_load_dwordx4 v[120:123], v[140:141], off offset:256
	s_mov_b32 s1, 0x1b0000
	v_add_co_u32_e32 v68, vcc, s1, v206
	s_mov_b64 s[28:29], 0x1b0000
	s_nop 0
	v_addc_co_u32_e32 v69, vcc, 0, v207, vcc
	global_load_dwordx4 v[124:127], v[68:69], off
	v_add_co_u32_e32 v144, vcc, s0, v208
	v_lshl_add_u64 v[66:67], v[206:207], 0, s[28:29]
	s_nop 0
	v_addc_co_u32_e32 v145, vcc, 0, v209, vcc
	s_mov_b64 s[0:1], 0x1e0000
	global_load_dwordx4 v[128:131], v[144:145], off
	global_load_dwordx4 v[132:135], v[66:67], off offset:256
	global_load_dwordx4 v[136:139], v[106:107], off offset:256
	v_lshl_add_u64 v[66:67], v[206:207], 0, s[0:1]
	s_mov_b32 s0, 0x1e0000
	v_add_co_u32_e32 v68, vcc, s0, v206
	s_mov_b64 s[0:1], 0xa0000
	s_nop 0
	v_addc_co_u32_e32 v69, vcc, 0, v207, vcc
	v_lshl_add_u64 v[102:103], v[208:209], 0, s[0:1]
	s_mov_b32 s0, 0xa0000
	global_load_dwordx4 v[94:97], v[68:69], off
	v_add_co_u32_e32 v104, vcc, s0, v208
	s_mov_b64 s[0:1], 0x210000
	s_nop 0
	v_addc_co_u32_e32 v105, vcc, 0, v209, vcc
	global_load_dwordx4 v[90:93], v[104:105], off
	global_load_dwordx4 v[86:89], v[66:67], off offset:256
	global_load_dwordx4 v[82:85], v[102:103], off offset:256
	v_lshl_add_u64 v[66:67], v[206:207], 0, s[0:1]
	s_mov_b32 s0, 0x210000
	v_add_co_u32_e32 v68, vcc, s0, v206
	s_mov_b64 s[0:1], 0xb0000
	s_nop 0
	v_addc_co_u32_e32 v69, vcc, 0, v207, vcc
	v_lshl_add_u64 v[98:99], v[208:209], 0, s[0:1]
	s_mov_b32 s0, 0xb0000
	global_load_dwordx4 v[78:81], v[68:69], off
	v_add_co_u32_e32 v100, vcc, s0, v208
	s_mov_b64 s[0:1], -1
	s_nop 0
	v_addc_co_u32_e32 v101, vcc, 0, v209, vcc
	global_load_dwordx4 v[74:77], v[100:101], off
	global_load_dwordx4 v[70:73], v[66:67], off offset:256
	s_nop 0
	global_load_dwordx4 v[66:69], v[98:99], off offset:256
	s_andn2_b64 vcc, exec, s[6:7]
	s_waitcnt vmcnt(15)
	v_lshlrev_b32_e32 v146, 16, v108
	v_and_b32_e32 v147, 0xffff0000, v108
	v_lshlrev_b32_e32 v108, 16, v109
	v_and_b32_e32 v109, 0xffff0000, v109
	v_lshlrev_b32_e32 v148, 16, v110
	v_and_b32_e32 v149, 0xffff0000, v110
	v_lshlrev_b32_e32 v110, 16, v111
	v_and_b32_e32 v111, 0xffff0000, v111
	s_waitcnt vmcnt(14)
	v_lshlrev_b32_e32 v150, 16, v112
	v_and_b32_e32 v151, 0xffff0000, v112
	v_lshlrev_b32_e32 v112, 16, v113
	v_and_b32_e32 v113, 0xffff0000, v113
	v_lshlrev_b32_e32 v152, 16, v114
	v_and_b32_e32 v153, 0xffff0000, v114
	v_lshlrev_b32_e32 v114, 16, v115
	v_and_b32_e32 v115, 0xffff0000, v115
	v_pk_fma_f32 v[64:65], v[64:65], v[108:109], v[112:113]
	v_pk_fma_f32 v[62:63], v[62:63], v[146:147], v[150:151]
	v_pk_fma_f32 v[108:109], v[60:61], v[110:111], v[114:115]
	v_pk_fma_f32 v[60:61], v[58:59], v[148:149], v[152:153]
	v_cvt_pk_bf16_f32 v58, v62, v63
	v_cvt_pk_bf16_f32 v59, v64, v65
	s_waitcnt vmcnt(13)
; __device__ __forceinline__ u32x4 pack8(const f32x4 v0, const f32x4 v1) { u32x4 w; w.x = cvt_pk_bf16(v0[0], v0[1]); w.y = cvt_pk_bf16(v0[2], v0[3]); w.z = cvt_pk_bf16(v1[0], v1[1]); w.w = cvt_pk_bf16(v1[2], v1[3]); return w; }
;     __device__ __forceinline__ void operator()(const f32x4 (&acc)[2][2][4][2], const Unit& u, int wr, int wc, int fr_, int fq) const {
;     ...
; #pragma unroll
;             for (int m = 0; m < 4; ++m)
; #pragma unroll
;                 for (int bj = 0; bj < 2; ++bj) { const size_t r = row0 + ai * HALF + m * 16; const int c = col0 + bj * HALF;
;                     f32x4 g0, g1; unpack8(gw[m][bj], g0, g1);
;                     f32x4 v0 = g0 * acc[ai][bj][m][0], v1 = g1 * acc[ai][bj][m][1];
;                     if (!FIRST) { f32x4 o0, o1; unpack8(ow[m][bj], o0, o1); v0 += o0; v1 += o1; }
;                     *(u32x4*)((Mdst ? Mdst : Mo) + r * DM + c) = pack8(v0, v1); }
	v_lshlrev_b32_e32 v62, 16, v118
	v_cvt_pk_bf16_f32 v60, v60, v61
	v_cvt_pk_bf16_f32 v61, v108, v109
	global_store_dwordx4 v[142:143], v[58:61], off
	v_and_b32_e32 v63, 0xffff0000, v118
	v_lshlrev_b32_e32 v64, 16, v119
	v_lshlrev_b32_e32 v58, 16, v116
	v_and_b32_e32 v59, 0xffff0000, v116
	v_and_b32_e32 v65, 0xffff0000, v119
	s_waitcnt vmcnt(13)
	v_lshlrev_b32_e32 v108, 16, v120
	v_and_b32_e32 v109, 0xffff0000, v120
	v_lshlrev_b32_e32 v112, 16, v122
	v_and_b32_e32 v113, 0xffff0000, v122
	v_lshlrev_b32_e32 v114, 16, v123
	v_and_b32_e32 v115, 0xffff0000, v123
	v_lshlrev_b32_e32 v60, 16, v117
	v_and_b32_e32 v61, 0xffff0000, v117
	v_lshlrev_b32_e32 v110, 16, v121
	v_and_b32_e32 v111, 0xffff0000, v121
	v_pk_fma_f32 v[54:55], v[54:55], v[58:59], v[108:109]
	v_pk_fma_f32 v[58:59], v[52:53], v[64:65], v[114:115]
	v_pk_fma_f32 v[52:53], v[50:51], v[62:63], v[112:113]
	v_pk_fma_f32 v[56:57], v[56:57], v[60:61], v[110:111]
	v_cvt_pk_bf16_f32 v50, v54, v55
	s_waitcnt vmcnt(12)
	v_lshlrev_b32_e32 v54, 16, v126
	v_cvt_pk_bf16_f32 v51, v56, v57
	v_cvt_pk_bf16_f32 v52, v52, v53
	v_cvt_pk_bf16_f32 v53, v58, v59
	global_store_dwordx4 v[140:141], v[50:53], off offset:256
	v_and_b32_e32 v55, 0xffff0000, v126
	v_lshlrev_b32_e32 v56, 16, v127
	v_lshlrev_b32_e32 v50, 16, v124
	v_and_b32_e32 v51, 0xffff0000, v124
	v_lshlrev_b32_e32 v52, 16, v125
	v_and_b32_e32 v53, 0xffff0000, v125
	v_and_b32_e32 v57, 0xffff0000, v127
	s_waitcnt vmcnt(12)
	v_lshlrev_b32_e32 v58, 16, v128
	v_and_b32_e32 v59, 0xffff0000, v128
	v_lshlrev_b32_e32 v60, 16, v129
	v_and_b32_e32 v61, 0xffff0000, v129
	v_lshlrev_b32_e32 v62, 16, v130
	v_and_b32_e32 v63, 0xffff0000, v130
	v_lshlrev_b32_e32 v64, 16, v131
	v_and_b32_e32 v65, 0xffff0000, v131
	v_pk_fma_f32 v[48:49], v[48:49], v[52:53], v[60:61]
	v_pk_fma_f32 v[46:47], v[46:47], v[50:51], v[58:59]
	v_pk_fma_f32 v[50:51], v[44:45], v[56:57], v[64:65]
	v_pk_fma_f32 v[44:45], v[42:43], v[54:55], v[62:63]
	v_cvt_pk_bf16_f32 v42, v46, v47
	v_cvt_pk_bf16_f32 v43, v48, v49
	s_waitcnt vmcnt(11)
	v_lshlrev_b32_e32 v46, 16, v134
	v_cvt_pk_bf16_f32 v44, v44, v45
	v_cvt_pk_bf16_f32 v45, v50, v51
	global_store_dwordx4 v[144:145], v[42:45], off
	v_and_b32_e32 v47, 0xffff0000, v134
	v_lshlrev_b32_e32 v48, 16, v135
	v_lshlrev_b32_e32 v42, 16, v132
	v_and_b32_e32 v43, 0xffff0000, v132
	v_and_b32_e32 v49, 0xffff0000, v135
	s_waitcnt vmcnt(11)
	v_lshlrev_b32_e32 v50, 16, v136
	v_and_b32_e32 v51, 0xffff0000, v136
	v_lshlrev_b32_e32 v54, 16, v138
	v_and_b32_e32 v55, 0xffff0000, v138
	v_lshlrev_b32_e32 v56, 16, v139
	v_and_b32_e32 v57, 0xffff0000, v139
	v_lshlrev_b32_e32 v44, 16, v133
	v_and_b32_e32 v45, 0xffff0000, v133
	v_lshlrev_b32_e32 v52, 16, v137
	v_and_b32_e32 v53, 0xffff0000, v137
	v_pk_fma_f32 v[38:39], v[38:39], v[42:43], v[50:51]
	v_pk_fma_f32 v[42:43], v[36:37], v[48:49], v[56:57]
	v_pk_fma_f32 v[36:37], v[34:35], v[46:47], v[54:55]
	v_pk_fma_f32 v[40:41], v[40:41], v[44:45], v[52:53]
	v_cvt_pk_bf16_f32 v34, v38, v39
	s_waitcnt vmcnt(10)
	v_lshlrev_b32_e32 v38, 16, v96
	v_cvt_pk_bf16_f32 v35, v40, v41
	v_cvt_pk_bf16_f32 v36, v36, v37
	v_cvt_pk_bf16_f32 v37, v42, v43
	global_store_dwordx4 v[106:107], v[34:37], off offset:256
	v_and_b32_e32 v39, 0xffff0000, v96
	v_lshlrev_b32_e32 v40, 16, v97
	v_lshlrev_b32_e32 v34, 16, v94
	v_and_b32_e32 v35, 0xffff0000, v94
	v_lshlrev_b32_e32 v36, 16, v95
	v_and_b32_e32 v37, 0xffff0000, v95
	v_and_b32_e32 v41, 0xffff0000, v97
	s_waitcnt vmcnt(10)
; __device__ __forceinline__ u32x4 pack8(const f32x4 v0, const f32x4 v1) { u32x4 w; w.x = cvt_pk_bf16(v0[0], v0[1]); w.y = cvt_pk_bf16(v0[2], v0[3]); w.z = cvt_pk_bf16(v1[0], v1[1]); w.w = cvt_pk_bf16(v1[2], v1[3]); return w; }
; #define PG8_BAR __builtin_amdgcn_s_barrier()
;     __device__ __forceinline__ void operator()(const f32x4 (&acc)[2][2][4][2], const Unit& u, int wr, int wc, int fr_, int fq) const {
;     ...
; #pragma unroll
;             for (int m = 0; m < 4; ++m)
; #pragma unroll
;                 for (int bj = 0; bj < 2; ++bj) { const size_t r = row0 + ai * HALF + m * 16; const int c = col0 + bj * HALF;
;                     f32x4 g0, g1; unpack8(gw[m][bj], g0, g1);
;                     f32x4 v0 = g0 * acc[ai][bj][m][0], v1 = g1 * acc[ai][bj][m][1];
;                     if (!FIRST) { f32x4 o0, o1; unpack8(ow[m][bj], o0, o1); v0 += o0; v1 += o1; }
;                     *(u32x4*)((Mdst ? Mdst : Mo) + r * DM + c) = pack8(v0, v1); }
;             asm volatile("" ::: "memory"); }
; template <class Epi, class Sched, bool ALIGN_EPI = false, bool SP2 = false, bool ABLK = false, bool BBLK = false>
; __device__ __forceinline__ void gemm_phase(PG8_LAS unsigned char* lds, const Gemm g, const Sched& S, const Epi& E) {
;     ...
;         if (!has_next) break;
; #pragma unroll
;         for (int a = 0; a < 2; ++a)
; #pragma unroll
;             for (int b = 0; b < 2; ++b)
; #pragma unroll
;                 for (int m = 0; m < 4; ++m)
; #pragma unroll
;                     for (int n = 0; n < 2; ++n) acc[a][b][m][n] = (f32x4){0.f, 0.f, 0.f, 0.f};
;         cur = nxt; cA = nA; cB = nB; ++ui;
;         if constexpr (ALIGN_EPI) { if (wr == 1) PG8_BAR; }
;     }
	v_lshlrev_b32_e32 v42, 16, v90
	v_and_b32_e32 v43, 0xffff0000, v90
	v_lshlrev_b32_e32 v44, 16, v91
	v_and_b32_e32 v45, 0xffff0000, v91
	v_lshlrev_b32_e32 v46, 16, v92
	v_and_b32_e32 v47, 0xffff0000, v92
	v_lshlrev_b32_e32 v48, 16, v93
	v_and_b32_e32 v49, 0xffff0000, v93
	v_pk_fma_f32 v[32:33], v[32:33], v[36:37], v[44:45]
	v_pk_fma_f32 v[30:31], v[30:31], v[34:35], v[42:43]
	v_pk_fma_f32 v[34:35], v[28:29], v[40:41], v[48:49]
	v_pk_fma_f32 v[28:29], v[26:27], v[38:39], v[46:47]
	v_cvt_pk_bf16_f32 v26, v30, v31
	v_cvt_pk_bf16_f32 v27, v32, v33
	s_waitcnt vmcnt(9)
	v_lshlrev_b32_e32 v30, 16, v88
	v_cvt_pk_bf16_f32 v28, v28, v29
	v_cvt_pk_bf16_f32 v29, v34, v35
	global_store_dwordx4 v[104:105], v[26:29], off
	v_and_b32_e32 v31, 0xffff0000, v88
	v_lshlrev_b32_e32 v32, 16, v89
	v_lshlrev_b32_e32 v26, 16, v86
	v_and_b32_e32 v27, 0xffff0000, v86
	v_and_b32_e32 v33, 0xffff0000, v89
	s_waitcnt vmcnt(9)
	v_lshlrev_b32_e32 v34, 16, v82
	v_and_b32_e32 v35, 0xffff0000, v82
	v_lshlrev_b32_e32 v38, 16, v84
	v_and_b32_e32 v39, 0xffff0000, v84
	v_lshlrev_b32_e32 v40, 16, v85
	v_and_b32_e32 v41, 0xffff0000, v85
	v_lshlrev_b32_e32 v28, 16, v87
	v_and_b32_e32 v29, 0xffff0000, v87
	v_lshlrev_b32_e32 v36, 16, v83
	v_and_b32_e32 v37, 0xffff0000, v83
	v_pk_fma_f32 v[22:23], v[22:23], v[26:27], v[34:35]
	v_pk_fma_f32 v[26:27], v[20:21], v[32:33], v[40:41]
	v_pk_fma_f32 v[20:21], v[18:19], v[30:31], v[38:39]
	v_pk_fma_f32 v[24:25], v[24:25], v[28:29], v[36:37]
	v_cvt_pk_bf16_f32 v18, v22, v23
	s_waitcnt vmcnt(8)
	v_lshlrev_b32_e32 v22, 16, v80
	v_cvt_pk_bf16_f32 v19, v24, v25
	v_cvt_pk_bf16_f32 v20, v20, v21
	v_cvt_pk_bf16_f32 v21, v26, v27
	global_store_dwordx4 v[102:103], v[18:21], off offset:256
	v_and_b32_e32 v23, 0xffff0000, v80
	v_lshlrev_b32_e32 v24, 16, v81
	v_lshlrev_b32_e32 v18, 16, v78
	v_and_b32_e32 v19, 0xffff0000, v78
	v_lshlrev_b32_e32 v20, 16, v79
	v_and_b32_e32 v21, 0xffff0000, v79
	v_and_b32_e32 v25, 0xffff0000, v81
	s_waitcnt vmcnt(8)
	v_lshlrev_b32_e32 v26, 16, v74
	v_and_b32_e32 v27, 0xffff0000, v74
	v_lshlrev_b32_e32 v28, 16, v75
	v_and_b32_e32 v29, 0xffff0000, v75
	v_lshlrev_b32_e32 v30, 16, v76
	v_and_b32_e32 v31, 0xffff0000, v76
	v_lshlrev_b32_e32 v32, 16, v77
	v_and_b32_e32 v33, 0xffff0000, v77
	v_pk_fma_f32 v[16:17], v[16:17], v[20:21], v[28:29]
	v_pk_fma_f32 v[14:15], v[14:15], v[18:19], v[26:27]
	v_pk_fma_f32 v[18:19], v[12:13], v[24:25], v[32:33]
	v_pk_fma_f32 v[12:13], v[10:11], v[22:23], v[30:31]
	v_cvt_pk_bf16_f32 v10, v14, v15
	v_cvt_pk_bf16_f32 v11, v16, v17
	s_waitcnt vmcnt(7)
	v_lshlrev_b32_e32 v14, 16, v72
	v_cvt_pk_bf16_f32 v12, v12, v13
	v_cvt_pk_bf16_f32 v13, v18, v19
	global_store_dwordx4 v[100:101], v[10:13], off
	v_and_b32_e32 v15, 0xffff0000, v72
	v_lshlrev_b32_e32 v16, 16, v73
	v_lshlrev_b32_e32 v10, 16, v70
	v_and_b32_e32 v11, 0xffff0000, v70
	v_and_b32_e32 v17, 0xffff0000, v73
	s_waitcnt vmcnt(7)
	v_lshlrev_b32_e32 v18, 16, v66
	v_and_b32_e32 v19, 0xffff0000, v66
	v_lshlrev_b32_e32 v22, 16, v68
	v_and_b32_e32 v23, 0xffff0000, v68
	v_lshlrev_b32_e32 v24, 16, v69
	v_and_b32_e32 v25, 0xffff0000, v69
	v_lshlrev_b32_e32 v12, 16, v71
	v_and_b32_e32 v13, 0xffff0000, v71
	v_lshlrev_b32_e32 v20, 16, v67
	v_and_b32_e32 v21, 0xffff0000, v67
	v_pk_fma_f32 v[6:7], v[6:7], v[10:11], v[18:19]
	v_pk_fma_f32 v[10:11], v[4:5], v[16:17], v[24:25]
	v_pk_fma_f32 v[4:5], v[2:3], v[14:15], v[22:23]
	v_pk_fma_f32 v[8:9], v[8:9], v[12:13], v[20:21]
	v_cvt_pk_bf16_f32 v2, v6, v7
	s_nop 0
	v_cvt_pk_bf16_f32 v3, v8, v9
	v_cvt_pk_bf16_f32 v4, v4, v5
	v_cvt_pk_bf16_f32 v5, v10, v11
	global_store_dwordx4 v[98:99], v[2:5], off offset:256
	s_cbranch_vccnz .LBB0_1156
	s_andn2_b64 vcc, exec, s[8:9]
	s_cbranch_vccnz .LBB0_1155
	s_branch .LBB0_1155

; #define PG8_STAGE(bufoff, gbase, voff) do { _Pragma("unroll") for (int _i = 0; _i < 2; ++_i) \
;         __builtin_amdgcn_global_load_lds((const unsigned*)((const char*)(gbase) + (voff)[_i]), (PG8_LAS unsigned*)(lds + (bufoff) + ldsw + _i * 8192), 16, 0, 0); } while (0)
; #define PG8_WAIT_V(n) asm volatile("s_waitcnt vmcnt(" #n ")" ::: "memory")
; template <class Epi, class Sched, bool ALIGN_EPI = false, bool SP2 = false, bool ABLK = false, bool BBLK = false>
; __device__ __forceinline__ void gemm_phase(PG8_LAS unsigned char* lds, const Gemm g, const Sched& S, const Epi& E) {
;     ...
;     const int tid = tid_, wid = __builtin_amdgcn_readfirstlane(tid >> 6), lane = tid & 63, wr = wid >> 2, wc = wid & 3, fr = lane & 15, fq = lane >> 4;
;     const int K = g.K, nt = K / BK, LDA = g.lda ? g.lda : K, LDB = g.ldb ? g.ldb : K;
;     unsigned voffA[2], voffB[2];
; #pragma unroll
;     for (int i = 0; i < 2; ++i) { int R, C; stage_rc(tid * 16 + i * 8192, R, C); const int Rb = Epi::PERM ? ((R & ~31) + perm32(R & 31)) : R;
;         voffA[i] = ABLK ? (unsigned)(R * BK + C) * 2u : (unsigned)(R * LDA + C) * 2u; voffB[i] = BBLK ? (unsigned)(Rb * BK + C) * 2u : (unsigned)(Rb * LDB + C) * 2u; }
;     const size_t kstep = (size_t)(BK * 2);
;     const size_t hstepa = (size_t)HALF * LDA * 2, hstepb = (size_t)HALF * LDB * 2;
;     const size_t kstepA = ABLK ? (size_t)BM * BK * 2 : kstep, hstepA = ABLK ? (size_t)HALF * BK * 2 : hstepa, tstepA = ABLK ? (size_t)nt * BM * BK * 2 : 2 * hstepa;
;     const size_t kstepB = BBLK ? (size_t)BM * BK * 2 : kstep, hstepB = BBLK ? (size_t)HALF * BK * 2 : hstepb, tstepB = BBLK ? (size_t)nt * BM * BK * 2 : 2 * hstepb;
;     const unsigned ldsw = (unsigned)wid * 1024u;
;     const int aoff = lds_byte(wr * 64 + fr, fq * 8), boff = lds_byte(wc * 32 + fr, fq * 8);
;     ...
;     const char* cA = (const char*)g.A + (size_t)cur.pm * tstepA; const char* cB = (const char*)g.Bt + (size_t)cur.pn * tstepB;
;     S.a_ready(cur);
;     if constexpr (SP2) {
;         PG8_STAGE(PG8_SB(0, 0), cB, voffB); PG8_STAGE(PG8_SB(0, 1), cB + hstepB, voffB); PG8_STAGE(PG8_SA(0, 0), cA, voffA); PG8_STAGE(PG8_SA(0, 1), cA + hstepA, voffA);
;         if (wr == 1) PG8_BAR;
;         PG8_WAIT_V(2); PG8_BAR;
;         PG8_STAGE(PG8_SB(1, 0), cB + kstepB, voffB); PG8_STAGE(PG8_SA(1, 0), cA + kstepA, voffA); PG8_STAGE(PG8_SB(1, 1), cB + hstepB + kstepB, voffB);
.LBB0_1227:
	s_andn2_b64 vcc, exec, s[0:1]
	s_cbranch_vccnz .LBB0_1278
	v_ashrrev_i32_e32 v3, 31, v6
	v_lshrrev_b32_e32 v3, 26, v3
	v_add_u32_e32 v3, v6, v3
	v_ashrrev_i32_e32 v7, 6, v3
	v_bfe_i32 v3, v6, 27, 1
	v_lshlrev_b32_e32 v2, 4, v6
	v_lshrrev_b32_e32 v3, 22, v3
	v_add_u32_e32 v3, v2, v3
	v_and_b32_e32 v3, 0xfffffc00, v3
	v_sub_u32_e32 v3, v2, v3
	v_lshrrev_b32_e32 v4, 4, v3
	v_bitop3_b32 v3, v4, v3, 32 bitop3:0x6c
	v_ashrrev_i32_e32 v5, 31, v3
	v_lshrrev_b32_e32 v5, 26, v5
	v_add_u32_e32 v5, v3, v5
	v_lshlrev_b32_e32 v4, 3, v7
	v_ashrrev_i32_e32 v8, 6, v5
	v_and_b32_e32 v5, 0xc0, v5
	v_and_b32_e32 v4, -16, v4
	v_sub_u32_e32 v3, v3, v5
	v_readlane_b32 s0, v254, 7
	v_add_u32_e32 v4, v8, v4
	v_lshlrev_b32_e32 v9, 5, v7
	v_ashrrev_i16_sdwa v3, v232, sext(v3) dst_sel:DWORD dst_unused:UNUSED_PAD src0_sel:DWORD src1_sel:BYTE_0
	s_add_u32 s19, s0, s4
	v_and_b32_e32 v10, 32, v9
	v_bfe_i32 v9, v3, 0, 16
	v_lshlrev_b32_e32 v3, 1, v4
	v_lshrrev_b32_e32 v5, 2, v4
	v_and_b32_e32 v11, 3, v8
	s_mov_b32 s0, 0x1ffffe0
	v_and_b32_e32 v3, 24, v3
	v_and_b32_e32 v5, 4, v5
	v_and_or_b32 v11, v4, s0, v11
	v_or3_b32 v3, v11, v5, v3
	v_add_lshl_u32 v5, v10, v9, 1
	v_add_u32_e32 v2, 0x2000, v2
	v_lshl_add_u32 v178, v3, 7, v5
	v_ashrrev_i32_e32 v3, 31, v2
	v_lshrrev_b32_e32 v3, 22, v3
	v_add_u32_e32 v3, v2, v3
	v_ashrrev_i32_e32 v10, 10, v3
	v_mul_i32_i24_e32 v3, 0x400, v10
	v_sub_u32_e32 v2, v2, v3
	v_lshrrev_b32_e32 v3, 4, v2
	v_readlane_b32 s1, v254, 8
	v_bitop3_b32 v2, v3, v2, 32 bitop3:0x6c
	s_addc_u32 s20, s1, s5
	v_lshl_add_u32 v186, v4, 12, v5
	v_ashrrev_i32_e32 v4, 31, v2
	s_add_u32 s50, s19, 0xf600000
	v_lshrrev_b32_e32 v4, 26, v4
	s_addc_u32 s51, s20, 0
	v_lshlrev_b32_e32 v3, 3, v10
	v_add_u32_e32 v4, v2, v4
	s_add_u32 s53, s19, 0xa900000
	v_and_b32_e32 v3, -16, v3
	v_ashrrev_i32_e32 v11, 6, v4
	s_addc_u32 s56, s20, 0
	s_ashr_i32 s2, s18, 6
	v_add_u32_e32 v3, v11, v3
	v_and_b32_e32 v4, 0xc0, v4
	v_and_b32_e32 v13, 3, v11
	s_ashr_i32 s37, s36, 31
	s_ashr_i32 s35, s34, 31
	v_sub_u32_e32 v2, v2, v4
	v_and_or_b32 v13, v3, s0, v13
	s_ashr_i32 s3, s18, 8
	s_lshl_b32 s46, s2, 10
	s_lshl_b64 s[8:9], s[36:37], 20
	s_lshl_b64 s[0:1], s[34:35], 20
	v_ashrrev_i16_sdwa v2, v232, sext(v2) dst_sel:DWORD dst_unused:UNUSED_PAD src0_sel:DWORD src1_sel:BYTE_0
	s_add_u32 s0, s53, s0
	v_lshlrev_b32_e32 v5, 5, v10
	v_bfe_i32 v12, v2, 0, 16
	v_lshlrev_b32_e32 v2, 1, v3
	v_lshrrev_b32_e32 v4, 2, v3
	s_addc_u32 s1, s56, s1
	s_add_i32 s47, s46, 0
	v_and_b32_e32 v5, 32, v5
	v_and_b32_e32 v2, 24, v2
	v_and_b32_e32 v4, 4, v4
	s_add_i32 m0, s47, 0x10000
	v_or3_b32 v2, v13, v4, v2
	v_add_lshl_u32 v4, v5, v12, 1
	global_load_lds_dwordx4 v178, s[0:1]
	s_add_i32 m0, s47, 0x12000
	v_lshl_add_u32 v182, v2, 7, v4
	s_add_u32 s12, s0, 0x4000
	global_load_lds_dwordx4 v182, s[0:1]
	s_addc_u32 s13, s1, 0
	s_add_i32 m0, s47, 0x14000
	v_lshl_add_u32 v180, v3, 12, v4
	global_load_lds_dwordx4 v178, s[12:13]
	s_add_i32 m0, s47, 0x16000
	s_add_u32 s8, s50, s8
	s_addc_u32 s9, s51, s9
	s_add_i32 s65, s47, 0x2000
	global_load_lds_dwordx4 v182, s[12:13]
	s_mov_b32 m0, s47
	s_add_u32 s12, s8, 0x80000
	global_load_lds_dwordx4 v186, s[8:9]
	s_mov_b32 m0, s65
	s_addc_u32 s13, s9, 0
	s_add_i32 s68, s47, 0x4000
	global_load_lds_dwordx4 v180, s[8:9]
	s_mov_b32 m0, s68
	s_add_i32 s72, s47, 0x6000
	global_load_lds_dwordx4 v186, s[12:13]
	s_mov_b32 m0, s72
	s_cmp_eq_u32 s3, 1
	global_load_lds_dwordx4 v180, s[12:13]
	v_mov_b32_e32 v181, v187
	s_cselect_b64 s[12:13], -1, 0
	s_mov_b32 s38, 0x30000
	s_mov_b32 s82, 0x10000
	s_mov_b32 s80, 0x20000
	v_lshl_add_u64 v[2:3], s[8:9], 0, v[186:187]
	v_writelane_b32 v254, s12, 36
	s_cmp_lg_u32 s3, 1
	v_lshl_add_u64 v[4:5], s[8:9], 0, v[180:181]
	v_writelane_b32 v254, s13, 37
	s_cbranch_scc1 .LBB0_1230
; #define PG8_STAGE(bufoff, gbase, voff) do { _Pragma("unroll") for (int _i = 0; _i < 2; ++_i) \
;         __builtin_amdgcn_global_load_lds((const unsigned*)((const char*)(gbase) + (voff)[_i]), (PG8_LAS unsigned*)(lds + (bufoff) + ldsw + _i * 8192), 16, 0, 0); } while (0)
; #define PG8_WAIT_V(n) asm volatile("s_waitcnt vmcnt(" #n ")" ::: "memory")
; #define PG8_BAR __builtin_amdgcn_s_barrier()
; template <class Epi, class Sched, bool ALIGN_EPI = false, bool SP2 = false, bool ABLK = false, bool BBLK = false>
; __device__ __forceinline__ void gemm_phase(PG8_LAS unsigned char* lds, const Gemm g, const Sched& S, const Epi& E) {
;     ...
;         if (wr == 1) PG8_BAR;
;         PG8_WAIT_V(2); PG8_BAR;
;         PG8_STAGE(PG8_SB(1, 0), cB + kstepB, voffB); PG8_STAGE(PG8_SA(1, 0), cA + kstepA, voffA); PG8_STAGE(PG8_SB(1, 1), cB + hstepB + kstepB, voffB);
;         PG8_WAIT_V(6); PG8_BAR;
.LBB0_1230:
	v_readlane_b32 s12, v254, 24
	s_mul_i32 s16, s12, 0x4c800
	s_lshl_b32 s14, s12, 11
	s_mul_i32 s22, s12, 0x1b00
	s_lshl_b64 s[4:5], s[4:5], 2
	v_readlane_b32 s12, v254, 26
	v_readlane_b32 s13, v254, 27
	s_add_u32 s4, s12, s4
	s_addc_u32 s5, s13, s5
	s_add_u32 s12, s19, 0x1500000
	s_addc_u32 s13, s20, 0
	s_add_u32 s21, s19, 0x37a00000
	v_readlane_b32 s24, v254, 41
	s_addc_u32 s26, s20, 0
	v_readlane_b32 s25, v254, 42
	s_and_b64 s[24:25], s[24:25], exec
	s_cselect_b32 s73, s5, s26
	s_cselect_b32 s81, s4, s21
	s_lshl_b64 s[24:25], s[16:17], 2
	s_add_u32 s16, s19, s24
	s_addc_u32 s21, s20, s25
	s_mov_b32 s15, s17
	s_add_u32 s83, s16, 0x100000
	s_addc_u32 s84, s21, 0
	s_lshl_b64 s[14:15], s[14:15], 2
	s_waitcnt lgkmcnt(0)
	s_add_u32 s14, s6, s14
	s_addc_u32 s15, s7, s15
	s_mov_b32 s23, s17
	s_add_u32 s88, s19, 0xf400000
	s_addc_u32 s89, s20, 0
	s_lshl_b64 s[6:7], s[22:23], 2
	s_add_u32 s6, s19, s6
	s_addc_u32 s7, s20, s7
	v_bfe_u32 v205, v6, 4, 2
	s_add_u32 s94, s6, 0x12400
	v_and_b32_e32 v204, 15, v6
	v_lshlrev_b32_e32 v13, 4, v205
	v_lshlrev_b32_e32 v6, 2, v6
	s_addc_u32 s95, s7, 0
	s_and_b32 s16, s2, 3
	v_lshl_or_b32 v13, v204, 6, v13
	s_lshl_b32 s6, s3, 13
	v_and_b32_e32 v6, 32, v6
	s_lshl_b32 s96, s3, 6
	v_bitop3_b32 v16, v13, s6, v6 bitop3:0xde
	s_lshl_b32 s97, s16, 5
	s_lshl_b32 s6, s16, 12
	v_bitop3_b32 v206, v13, s6, v6 bitop3:0xde
	s_add_u32 s6, s0, 0x8000
	v_mov_b32_e32 v179, v187
	s_addc_u32 s7, s1, 0
	v_mov_b32_e32 v183, v187
	s_add_i32 m0, s47, 0x18000
	v_lshl_add_u64 v[14:15], s[6:7], 0, v[178:179]
	s_waitcnt vmcnt(2)
	s_barrier
	global_load_lds_dwordx4 v[14:15], off
	v_lshl_add_u64 v[14:15], s[6:7], 0, v[182:183]
	s_add_i32 m0, s47, 0x1a000
	s_add_i32 s33, s47, 0x8000
	s_add_i32 s91, s47, 0xa000
	global_load_lds_dwordx4 v[14:15], off
	v_lshl_add_u64 v[2:3], v[2:3], 0, s[62:63]
	s_mov_b32 m0, s33
	s_add_u32 s6, s0, 0xc000
	global_load_lds_dwordx4 v[2:3], off
	v_lshl_add_u64 v[2:3], v[4:5], 0, s[62:63]
	s_mov_b32 m0, s91
	s_addc_u32 s7, s1, 0
	global_load_lds_dwordx4 v[2:3], off
	s_add_i32 m0, s47, 0x1c000
	v_lshl_add_u64 v[2:3], s[6:7], 0, v[178:179]
	global_load_lds_dwordx4 v[2:3], off
	v_lshl_add_u64 v[2:3], s[6:7], 0, v[182:183]
	s_add_i32 m0, s47, 0x1e000
	s_cmpk_lt_u32 s18, 0x100
	global_load_lds_dwordx4 v[2:3], off
	s_cselect_b64 s[18:19], -1, 0
	s_lshl_b32 s3, s3, 2
	s_or_b32 s90, s3, s16
	s_lshl_b32 s86, s90, 5
	s_bfe_u32 s20, s2, 0x10001
	s_and_b32 s6, s97, 32
	s_ashr_i32 s44, s42, 31
	s_ashr_i32 s45, s43, 31
	s_cmpk_lg_i32 s42, 0x100
	v_readlane_b32 s22, v254, 30
	s_cselect_b64 s[2:3], -1, 0
	v_readlane_b32 s23, v254, 31
	s_or_b64 s[22:23], s[22:23], s[2:3]
	s_and_b32 s2, s43, 7
	s_lshl_b32 s2, s2, 2
	v_lshlrev_b32_e32 v2, 15, v7
	v_writelane_b32 v254, s2, 38
	s_bfe_u32 s2, s43, 0x20001
	v_and_b32_e32 v2, 0xffff0000, v2
	s_or_b32 s2, s2, 32
	v_lshl_add_u32 v2, v8, 12, v2
	v_and_b32_e32 v3, 1, v7
	v_writelane_b32 v254, s2, 39
	s_lshl_b32 s2, s43, 4
	v_lshl_or_b32 v2, v3, 6, v2
	s_ashr_i32 s39, s43, 3
	s_and_b32 s2, s2, 16
	v_lshl_add_u32 v184, v9, 1, v2
	v_lshlrev_b32_e32 v2, 15, v10
	v_writelane_b32 v254, s2, 41
	s_and_b32 s2, s39, 3
	v_and_b32_e32 v2, 0xffff0000, v2
	s_waitcnt vmcnt(6)
	v_writelane_b32 v254, s2, 46
	s_lshl_b32 s2, s16, 2
	v_lshl_add_u32 v2, v11, 12, v2
	v_and_b32_e32 v3, 1, v10
	s_add_i32 s2, s2, 0
	v_lshl_or_b32 v2, v3, 6, v2
	s_mov_b32 s21, s17
	s_add_i32 s2, s2, 0x20540
	v_mov_b32_e32 v185, v187
	v_lshl_add_u32 v196, v12, 1, v2
	v_mov_b32_e32 v197, v187
	s_mov_b32 s25, 0
	v_add_u32_e32 v207, 0, v16
	s_lshl_b32 s16, s6, 1
	s_barrier
	s_branch .LBB0_1233

; #define PG8_STAGE(bufoff, gbase, voff) do { _Pragma("unroll") for (int _i = 0; _i < 2; ++_i) \
;         __builtin_amdgcn_global_load_lds((const unsigned*)((const char*)(gbase) + (voff)[_i]), (PG8_LAS unsigned*)(lds + (bufoff) + ldsw + _i * 8192), 16, 0, 0); } while (0)
; #define PG8_LDA(dst, b, h) do { _Pragma("unroll") for (int m = 0; m < 4; ++m) _Pragma("unroll") for (int k = 0; k < 2; ++k) dst[m][k] = *(const PG8_LAS bf16x8*)(lds + PG8_SA(b, h) + aoff + m * 2048 + k * 1024); } while (0)
; #define PG8_LDB(dst, b, h) do { _Pragma("unroll") for (int n = 0; n < 2; ++n) _Pragma("unroll") for (int k = 0; k < 2; ++k) dst[n][k] = *(const PG8_LAS bf16x8*)(lds + PG8_SB(b, h) + boff + n * 2048 + k * 1024); } while (0)
; #define PG8_WAIT_V(n) asm volatile("s_waitcnt vmcnt(" #n ")" ::: "memory")
; #define PG8_BAR __builtin_amdgcn_s_barrier()
; template <class Epi, class Sched, bool ALIGN_EPI = false, bool SP2 = false, bool ABLK = false, bool BBLK = false>
; __device__ __forceinline__ void gemm_phase(PG8_LAS unsigned char* lds, const Gemm g, const Sched& S, const Epi& E) {
;     ...
;         const bool has_next = S.next(ui + 1, nxt);
;         const char* nA = has_next ? (const char*)g.A + (size_t)nxt.pm * tstepA : cA; const char* nB = has_next ? (const char*)g.Bt + (size_t)nxt.pn * tstepB : cB;
;         for (int t = 0; t < nt; t += 2) {
;             const bool last = (t == nt - 2);
;             const char* a1 = cA + (size_t)(t + 1) * kstepA;
;             const char* a2 = last ? nA : cA + (size_t)(t + 2) * kstepA; const char* b2 = last ? nB : cB + (size_t)(t + 2) * kstepB;
;             const char* a3 = a2 + kstepA; const char* b3 = b2 + kstepB;
;             if (last && has_next) S.a_ready(nxt);
;             if constexpr (SP2) {
;             PG8_LDB(B0, 0, 0); PG8_LDB(B1, 0, 1); PG8_SCHED; PG8_LDA(At, 0, 0); PG8_STAGE(PG8_SA(1, 1), a1 + hstepA, voffA);
;             PG8_WAIT_V(8); PG8_WAIT_L(0); PG8_BAR; PG8_MMA(0, 0, At, B0); PG8_MMA(0, 1, At, B1); PG8_BAR; PG8_SCHED;
;     ...
; #pragma unroll
;         for (int a = 0; a < 2; ++a)
; #pragma unroll
;             for (int b = 0; b < 2; ++b)
; #pragma unroll
;                 for (int m = 0; m < 4; ++m)
; #pragma unroll
;                     for (int n = 0; n < 2; ++n) acc[a][b][m][n] = (f32x4){0.f, 0.f, 0.f, 0.f};
;         cur = nxt; cA = nA; cB = nB; ++ui;
;         if constexpr (ALIGN_EPI) { if (wr == 1) PG8_BAR; }
.LBB0_1238:
	s_ashr_i32 s27, s26, 31
	s_lshl_b64 s[28:29], s[26:27], 20
	s_add_u32 s28, s50, s28
	s_addc_u32 s29, s51, s29
	s_and_b64 s[30:31], s[6:7], exec
	s_cselect_b32 s27, s29, s9
	s_cselect_b32 s35, s28, s8
	s_ashr_i32 s25, s24, 31
	s_lshl_b64 s[30:31], s[24:25], 20
	s_add_u32 s30, s53, s30
	s_addc_u32 s31, s56, s31
	s_and_b64 s[40:41], s[6:7], exec
	s_cselect_b32 s25, s31, s1
	s_cselect_b32 s37, s30, s0
	s_add_u32 s60, s0, 0x10000
	s_addc_u32 s61, s1, 0
	s_add_u32 s0, s8, 0x80080
	v_mov_b32_e32 v38, 0
	s_addc_u32 s1, s9, 0
	s_mov_b32 s92, -2
	v_mov_b32_e32 v39, v38
	v_mov_b32_e32 v40, v38
	v_mov_b32_e32 v41, v38
	v_mov_b32_e32 v34, v38
	v_mov_b32_e32 v35, v38
	v_mov_b32_e32 v36, v38
	v_mov_b32_e32 v37, v38
	v_mov_b32_e32 v42, v38
	v_mov_b32_e32 v43, v38
	v_mov_b32_e32 v44, v38
	v_mov_b32_e32 v45, v38
	v_mov_b32_e32 v58, v38
	v_mov_b32_e32 v59, v38
	v_mov_b32_e32 v60, v38
	v_mov_b32_e32 v61, v38
	v_mov_b32_e32 v66, v38
	v_mov_b32_e32 v67, v38
	v_mov_b32_e32 v68, v38
	v_mov_b32_e32 v69, v38
	v_mov_b32_e32 v82, v38
	v_mov_b32_e32 v83, v38
	v_mov_b32_e32 v84, v38
	v_mov_b32_e32 v85, v38
	v_mov_b32_e32 v90, v38
	v_mov_b32_e32 v91, v38
	v_mov_b32_e32 v92, v38
	v_mov_b32_e32 v93, v38
	v_mov_b32_e32 v98, v38
	v_mov_b32_e32 v99, v38
	v_mov_b32_e32 v100, v38
	v_mov_b32_e32 v101, v38
	v_mov_b32_e32 v46, v38
	v_mov_b32_e32 v47, v38
	v_mov_b32_e32 v48, v38
	v_mov_b32_e32 v49, v38
	v_mov_b32_e32 v130, v38
	v_mov_b32_e32 v131, v38
	v_mov_b32_e32 v132, v38
	v_mov_b32_e32 v133, v38
	v_mov_b32_e32 v62, v38
	v_mov_b32_e32 v63, v38
	v_mov_b32_e32 v64, v38
	v_mov_b32_e32 v65, v38
	v_mov_b32_e32 v70, v38
	v_mov_b32_e32 v71, v38
	v_mov_b32_e32 v72, v38
	v_mov_b32_e32 v73, v38
	v_mov_b32_e32 v86, v38
	v_mov_b32_e32 v87, v38
	v_mov_b32_e32 v88, v38
	v_mov_b32_e32 v89, v38
	v_mov_b32_e32 v94, v38
	v_mov_b32_e32 v95, v38
	v_mov_b32_e32 v96, v38
	v_mov_b32_e32 v97, v38
	v_mov_b32_e32 v102, v38
	v_mov_b32_e32 v103, v38
	v_mov_b32_e32 v104, v38
	v_mov_b32_e32 v105, v38
	v_mov_b32_e32 v106, v38
	v_mov_b32_e32 v107, v38
	v_mov_b32_e32 v108, v38
	v_mov_b32_e32 v109, v38
	v_mov_b32_e32 v6, v38
	v_mov_b32_e32 v7, v38
	v_mov_b32_e32 v8, v38
	v_mov_b32_e32 v9, v38
	v_mov_b32_e32 v2, v38
	v_mov_b32_e32 v3, v38
	v_mov_b32_e32 v4, v38
	v_mov_b32_e32 v5, v38
	v_mov_b32_e32 v10, v38
	v_mov_b32_e32 v11, v38
	v_mov_b32_e32 v12, v38
	v_mov_b32_e32 v13, v38
	v_mov_b32_e32 v18, v38
	v_mov_b32_e32 v19, v38
	v_mov_b32_e32 v20, v38
	v_mov_b32_e32 v21, v38
	v_mov_b32_e32 v26, v38
	v_mov_b32_e32 v27, v38
	v_mov_b32_e32 v28, v38
	v_mov_b32_e32 v29, v38
	v_mov_b32_e32 v50, v38
	v_mov_b32_e32 v51, v38
	v_mov_b32_e32 v52, v38
	v_mov_b32_e32 v53, v38
	v_mov_b32_e32 v54, v38
	v_mov_b32_e32 v55, v38
	v_mov_b32_e32 v56, v38
	v_mov_b32_e32 v57, v38
	v_mov_b32_e32 v74, v38
	v_mov_b32_e32 v75, v38
	v_mov_b32_e32 v76, v38
	v_mov_b32_e32 v77, v38
	v_mov_b32_e32 v14, v38
	v_mov_b32_e32 v15, v38
	v_mov_b32_e32 v16, v38
	v_mov_b32_e32 v17, v38
	v_mov_b32_e32 v110, v38
	v_mov_b32_e32 v111, v38
	v_mov_b32_e32 v112, v38
	v_mov_b32_e32 v113, v38
	v_mov_b32_e32 v22, v38
	v_mov_b32_e32 v23, v38
	v_mov_b32_e32 v24, v38
	v_mov_b32_e32 v25, v38
	v_mov_b32_e32 v30, v38
	v_mov_b32_e32 v31, v38
	v_mov_b32_e32 v32, v38
	v_mov_b32_e32 v33, v38
	v_mov_b32_e32 v134, v38
	v_mov_b32_e32 v135, v38
	v_mov_b32_e32 v136, v38
	v_mov_b32_e32 v137, v38
	v_mov_b32_e32 v78, v38
	v_mov_b32_e32 v79, v38
	v_mov_b32_e32 v80, v38
	v_mov_b32_e32 v81, v38
	v_mov_b32_e32 v114, v38
	v_mov_b32_e32 v115, v38
	v_mov_b32_e32 v116, v38
	v_mov_b32_e32 v117, v38
	v_mov_b32_e32 v118, v38
	v_mov_b32_e32 v119, v38
	v_mov_b32_e32 v120, v38
	v_mov_b32_e32 v121, v38
	s_and_b64 vcc, exec, s[18:19]
	s_cbranch_vccnz .Lrb_mo
	s_barrier
.Lrb_mo:
.LBB0_1239:
	s_add_u32 s8, s0, 0xfff80080
	s_addc_u32 s9, s1, -1
	s_add_i32 s52, 0, 0x10000
	s_cmp_eq_u32 s92, 28
	s_cselect_b32 s41, s27, s9
	s_cselect_b32 s40, s35, s8
	s_cselect_b32 s9, s25, s61
	s_cselect_b32 s8, s37, s60
	s_add_i32 s75, 0, 0x14000
	v_add_u32_e32 v142, s52, v206
	v_add_u32_e32 v158, s75, v206
	ds_read_b128 v[122:125], v142
	ds_read_b128 v[126:129], v142 offset:1024
	ds_read_b128 v[138:141], v142 offset:2048
	ds_read_b128 v[142:145], v142 offset:3072
	ds_read_b128 v[146:149], v158
	ds_read_b128 v[150:153], v158 offset:1024
	ds_read_b128 v[154:157], v158 offset:2048
	ds_read_b128 v[158:161], v158 offset:3072
	v_lshl_add_u64 v[188:189], s[0:1], 0, v[184:185]
	s_add_i32 m0, s47, 0xc000
	ds_read_b128 v[162:165], v207
	ds_read_b128 v[166:169], v207 offset:1024
	ds_read_b128 v[170:173], v207 offset:2048
	ds_read_b128 v[174:177], v207 offset:3072
	ds_read_b128 v[198:201], v207 offset:4096
	ds_read_b128 v[208:211], v207 offset:5120
	ds_read_b128 v[212:215], v207 offset:6144
	ds_read_b128 v[216:219], v207 offset:7168
	global_load_lds_dwordx4 v[188:189], off
	v_lshl_add_u64 v[188:189], s[0:1], 0, v[196:197]
	s_add_i32 m0, s47, 0xe000
	s_nop 0
	global_load_lds_dwordx4 v[188:189], off
	s_waitcnt vmcnt(8)
	s_waitcnt lgkmcnt(0)
	s_barrier
; #define PG8_STAGE(bufoff, gbase, voff) do { _Pragma("unroll") for (int _i = 0; _i < 2; ++_i) \
;         __builtin_amdgcn_global_load_lds((const unsigned*)((const char*)(gbase) + (voff)[_i]), (PG8_LAS unsigned*)(lds + (bufoff) + ldsw + _i * 8192), 16, 0, 0); } while (0)
; #define PG8_LDA(dst, b, h) do { _Pragma("unroll") for (int m = 0; m < 4; ++m) _Pragma("unroll") for (int k = 0; k < 2; ++k) dst[m][k] = *(const PG8_LAS bf16x8*)(lds + PG8_SA(b, h) + aoff + m * 2048 + k * 1024); } while (0)
; #define PG8_LDB(dst, b, h) do { _Pragma("unroll") for (int n = 0; n < 2; ++n) _Pragma("unroll") for (int k = 0; k < 2; ++k) dst[n][k] = *(const PG8_LAS bf16x8*)(lds + PG8_SB(b, h) + boff + n * 2048 + k * 1024); } while (0)
; #define PG8_MMA(ai, bj, At, Bt) do { __builtin_amdgcn_s_setprio(1); _Pragma("unroll") for (int m = 0; m < 4; ++m) _Pragma("unroll") for (int n = 0; n < 2; ++n) _Pragma("unroll") for (int k = 0; k < 2; ++k) \
;         acc[ai][bj][m][n] = __builtin_amdgcn_mfma_f32_16x16x32_bf16(Bt[n][k], At[m][k], acc[ai][bj][m][n], 0, 0, 0); __builtin_amdgcn_s_setprio(0); } while (0)
; #define PG8_WAIT_V(n) asm volatile("s_waitcnt vmcnt(" #n ")" ::: "memory")
; #define PG8_WAIT_L(n) asm volatile("s_waitcnt lgkmcnt(" #n ")" ::: "memory")
; #define PG8_BAR __builtin_amdgcn_s_barrier()
; #define PG8_SCHED __builtin_amdgcn_sched_barrier(0)
; template <class Epi, class Sched, bool ALIGN_EPI = false, bool SP2 = false, bool ABLK = false, bool BBLK = false>
; __device__ __forceinline__ void gemm_phase(PG8_LAS unsigned char* lds, const Gemm g, const Sched& S, const Epi& E) {
;     ...
;             PG8_WAIT_V(8); PG8_WAIT_L(0); PG8_BAR; PG8_MMA(0, 0, At, B0); PG8_MMA(0, 1, At, B1); PG8_BAR; PG8_SCHED;
;             PG8_LDA(At, 0, 1); PG8_STAGE(PG8_SB(0, 0), b2, voffB); PG8_STAGE(PG8_SB(0, 1), b2 + hstepB, voffB); PG8_STAGE(PG8_SA(0, 0), a2, voffA);
;             PG8_WAIT_V(8); PG8_WAIT_L(0); PG8_BAR; PG8_MMA(1, 0, At, B0); PG8_MMA(1, 1, At, B1); PG8_BAR; PG8_SCHED;
;             PG8_LDB(B0, 1, 0); PG8_LDB(B1, 1, 1); PG8_SCHED; PG8_LDA(At, 1, 0); PG8_STAGE(PG8_SA(0, 1), a2 + hstepA, voffA);
;             PG8_WAIT_V(8); PG8_WAIT_L(0); PG8_BAR; PG8_MMA(0, 0, At, B0); PG8_MMA(0, 1, At, B1); PG8_BAR; PG8_SCHED;
	s_setprio 1
	s_waitcnt lgkmcnt(0)
	v_mfma_f32_16x16x32_bf16 v[118:121], v[122:125], v[162:165], v[118:121]
	v_mfma_f32_16x16x32_bf16 v[114:117], v[138:141], v[162:165], v[114:117]
	v_mfma_f32_16x16x32_bf16 v[78:81], v[122:125], v[170:173], v[78:81]
	v_mfma_f32_16x16x32_bf16 v[134:137], v[138:141], v[170:173], v[134:137]
	v_mfma_f32_16x16x32_bf16 v[30:33], v[122:125], v[198:201], v[30:33]
	v_mfma_f32_16x16x32_bf16 v[22:25], v[138:141], v[198:201], v[22:25]
	v_mfma_f32_16x16x32_bf16 v[110:113], v[122:125], v[212:215], v[110:113]
	v_mfma_f32_16x16x32_bf16 v[14:17], v[138:141], v[212:215], v[14:17]
	v_mfma_f32_16x16x32_bf16 v[118:121], v[126:129], v[166:169], v[118:121]
	v_mfma_f32_16x16x32_bf16 v[114:117], v[142:145], v[166:169], v[114:117]
	v_mfma_f32_16x16x32_bf16 v[78:81], v[126:129], v[174:177], v[78:81]
	v_mfma_f32_16x16x32_bf16 v[134:137], v[142:145], v[174:177], v[134:137]
	v_mfma_f32_16x16x32_bf16 v[30:33], v[126:129], v[208:211], v[30:33]
	v_mfma_f32_16x16x32_bf16 v[22:25], v[142:145], v[208:211], v[22:25]
	v_mfma_f32_16x16x32_bf16 v[110:113], v[126:129], v[216:219], v[110:113]
	v_mfma_f32_16x16x32_bf16 v[14:17], v[142:145], v[216:219], v[14:17]
	s_setprio 0
	s_setprio 1
	v_mfma_f32_16x16x32_bf16 v[74:77], v[146:149], v[162:165], v[74:77]
	v_mfma_f32_16x16x32_bf16 v[54:57], v[154:157], v[162:165], v[54:57]
	v_mfma_f32_16x16x32_bf16 v[50:53], v[146:149], v[170:173], v[50:53]
	v_mfma_f32_16x16x32_bf16 v[26:29], v[154:157], v[170:173], v[26:29]
	v_mfma_f32_16x16x32_bf16 v[18:21], v[146:149], v[198:201], v[18:21]
	v_mfma_f32_16x16x32_bf16 v[10:13], v[154:157], v[198:201], v[10:13]
	v_mfma_f32_16x16x32_bf16 v[2:5], v[146:149], v[212:215], v[2:5]
	v_mfma_f32_16x16x32_bf16 v[6:9], v[154:157], v[212:215], v[6:9]
	v_mfma_f32_16x16x32_bf16 v[74:77], v[150:153], v[166:169], v[74:77]
	v_mfma_f32_16x16x32_bf16 v[54:57], v[158:161], v[166:169], v[54:57]
	v_mfma_f32_16x16x32_bf16 v[50:53], v[150:153], v[174:177], v[50:53]
	v_mfma_f32_16x16x32_bf16 v[26:29], v[158:161], v[174:177], v[26:29]
	v_mfma_f32_16x16x32_bf16 v[18:21], v[150:153], v[208:211], v[18:21]
	v_mfma_f32_16x16x32_bf16 v[10:13], v[158:161], v[208:211], v[10:13]
	v_mfma_f32_16x16x32_bf16 v[2:5], v[150:153], v[216:219], v[2:5]
	v_mfma_f32_16x16x32_bf16 v[6:9], v[158:161], v[216:219], v[6:9]
	s_setprio 0
	s_barrier
	s_add_i32 s52, s52, s46
	v_lshl_add_u64 v[188:189], s[8:9], 0, v[178:179]
	s_mov_b32 m0, s52
	ds_read_b128 v[162:165], v207 offset:16384
	ds_read_b128 v[166:169], v207 offset:17408
	ds_read_b128 v[170:173], v207 offset:18432
	ds_read_b128 v[174:177], v207 offset:19456
	ds_read_b128 v[198:201], v207 offset:20480
	ds_read_b128 v[208:211], v207 offset:21504
	ds_read_b128 v[212:215], v207 offset:22528
	ds_read_b128 v[216:219], v207 offset:23552
	global_load_lds_dwordx4 v[188:189], off
	s_add_i32 m0, s52, 0x2000
	s_add_u32 vcc_lo, s8, 0x4000
	v_lshl_add_u64 v[188:189], s[8:9], 0, v[182:183]
	s_addc_u32 vcc_hi, s9, 0
	s_add_i32 s52, s75, s46
	global_load_lds_dwordx4 v[188:189], off
	v_lshl_add_u64 v[188:189], vcc, 0, v[178:179]
	s_mov_b32 m0, s52
	v_lshl_add_u64 v[190:191], s[40:41], 0, v[180:181]
	global_load_lds_dwordx4 v[188:189], off
	v_lshl_add_u64 v[188:189], vcc, 0, v[182:183]
	s_add_i32 m0, s52, 0x2000
	s_nop 0
	global_load_lds_dwordx4 v[188:189], off
	v_lshl_add_u64 v[188:189], s[40:41], 0, v[186:187]
	s_mov_b32 m0, s47
	s_nop 0
	global_load_lds_dwordx4 v[188:189], off
	s_mov_b32 m0, s65
	s_nop 0
	global_load_lds_dwordx4 v[190:191], off
	s_waitcnt vmcnt(8)
	s_waitcnt lgkmcnt(0)
	s_barrier
	s_setprio 1
	s_waitcnt lgkmcnt(0)
	v_mfma_f32_16x16x32_bf16 v[106:109], v[122:125], v[162:165], v[106:109]
	v_mfma_f32_16x16x32_bf16 v[102:105], v[138:141], v[162:165], v[102:105]
	v_mfma_f32_16x16x32_bf16 v[94:97], v[122:125], v[170:173], v[94:97]
	v_mfma_f32_16x16x32_bf16 v[86:89], v[138:141], v[170:173], v[86:89]
	v_mfma_f32_16x16x32_bf16 v[70:73], v[122:125], v[198:201], v[70:73]
	v_mfma_f32_16x16x32_bf16 v[62:65], v[138:141], v[198:201], v[62:65]
	v_mfma_f32_16x16x32_bf16 v[46:49], v[138:141], v[212:215], v[46:49]
	v_mfma_f32_16x16x32_bf16 v[106:109], v[126:129], v[166:169], v[106:109]
	v_mfma_f32_16x16x32_bf16 v[102:105], v[142:145], v[166:169], v[102:105]
	v_mfma_f32_16x16x32_bf16 v[94:97], v[126:129], v[174:177], v[94:97]
	v_mfma_f32_16x16x32_bf16 v[86:89], v[142:145], v[174:177], v[86:89]
	v_mfma_f32_16x16x32_bf16 v[70:73], v[126:129], v[208:211], v[70:73]
	v_mfma_f32_16x16x32_bf16 v[62:65], v[142:145], v[208:211], v[62:65]
	v_mfma_f32_16x16x32_bf16 v[122:125], v[122:125], v[212:215], v[130:133]
	v_mfma_f32_16x16x32_bf16 v[46:49], v[142:145], v[216:219], v[46:49]
	v_mfma_f32_16x16x32_bf16 v[122:125], v[126:129], v[216:219], v[122:125]
	s_setprio 0
	s_setprio 1
	v_mfma_f32_16x16x32_bf16 v[98:101], v[146:149], v[162:165], v[98:101]
	v_mfma_f32_16x16x32_bf16 v[90:93], v[154:157], v[162:165], v[90:93]
	v_mfma_f32_16x16x32_bf16 v[82:85], v[146:149], v[170:173], v[82:85]
	v_mfma_f32_16x16x32_bf16 v[66:69], v[154:157], v[170:173], v[66:69]
	v_mfma_f32_16x16x32_bf16 v[58:61], v[146:149], v[198:201], v[58:61]
	v_mfma_f32_16x16x32_bf16 v[42:45], v[154:157], v[198:201], v[42:45]
	v_mfma_f32_16x16x32_bf16 v[34:37], v[146:149], v[212:215], v[34:37]
	v_mfma_f32_16x16x32_bf16 v[38:41], v[154:157], v[212:215], v[38:41]
	v_mfma_f32_16x16x32_bf16 v[98:101], v[150:153], v[166:169], v[98:101]
	v_mfma_f32_16x16x32_bf16 v[90:93], v[158:161], v[166:169], v[90:93]
	v_mfma_f32_16x16x32_bf16 v[82:85], v[150:153], v[174:177], v[82:85]
	v_mfma_f32_16x16x32_bf16 v[66:69], v[158:161], v[174:177], v[66:69]
	v_mfma_f32_16x16x32_bf16 v[58:61], v[150:153], v[208:211], v[58:61]
	v_mfma_f32_16x16x32_bf16 v[42:45], v[158:161], v[208:211], v[42:45]
	v_mfma_f32_16x16x32_bf16 v[34:37], v[150:153], v[216:219], v[34:37]
	v_mfma_f32_16x16x32_bf16 v[38:41], v[158:161], v[216:219], v[38:41]
	s_setprio 0
	s_barrier
; #define PG8_STAGE(bufoff, gbase, voff) do { _Pragma("unroll") for (int _i = 0; _i < 2; ++_i) \
;         __builtin_amdgcn_global_load_lds((const unsigned*)((const char*)(gbase) + (voff)[_i]), (PG8_LAS unsigned*)(lds + (bufoff) + ldsw + _i * 8192), 16, 0, 0); } while (0)
; #define PG8_LDA(dst, b, h) do { _Pragma("unroll") for (int m = 0; m < 4; ++m) _Pragma("unroll") for (int k = 0; k < 2; ++k) dst[m][k] = *(const PG8_LAS bf16x8*)(lds + PG8_SA(b, h) + aoff + m * 2048 + k * 1024); } while (0)
; #define PG8_LDB(dst, b, h) do { _Pragma("unroll") for (int n = 0; n < 2; ++n) _Pragma("unroll") for (int k = 0; k < 2; ++k) dst[n][k] = *(const PG8_LAS bf16x8*)(lds + PG8_SB(b, h) + boff + n * 2048 + k * 1024); } while (0)
; #define PG8_MMA(ai, bj, At, Bt) do { __builtin_amdgcn_s_setprio(1); _Pragma("unroll") for (int m = 0; m < 4; ++m) _Pragma("unroll") for (int n = 0; n < 2; ++n) _Pragma("unroll") for (int k = 0; k < 2; ++k) \
;         acc[ai][bj][m][n] = __builtin_amdgcn_mfma_f32_16x16x32_bf16(Bt[n][k], At[m][k], acc[ai][bj][m][n], 0, 0, 0); __builtin_amdgcn_s_setprio(0); } while (0)
; #define PG8_WAIT_V(n) asm volatile("s_waitcnt vmcnt(" #n ")" ::: "memory")
; #define PG8_WAIT_L(n) asm volatile("s_waitcnt lgkmcnt(" #n ")" ::: "memory")
; #define PG8_BAR __builtin_amdgcn_s_barrier()
; #define PG8_SCHED __builtin_amdgcn_sched_barrier(0)
; template <class Epi, class Sched, bool ALIGN_EPI = false, bool SP2 = false, bool ABLK = false, bool BBLK = false>
; __device__ __forceinline__ void gemm_phase(PG8_LAS unsigned char* lds, const Gemm g, const Sched& S, const Epi& E) {
;     ...
;             PG8_LDB(B0, 1, 0); PG8_LDB(B1, 1, 1); PG8_SCHED; PG8_LDA(At, 1, 0); PG8_STAGE(PG8_SA(0, 1), a2 + hstepA, voffA);
;             PG8_WAIT_V(8); PG8_WAIT_L(0); PG8_BAR; PG8_MMA(0, 0, At, B0); PG8_MMA(0, 1, At, B1); PG8_BAR; PG8_SCHED;
;             PG8_LDA(At, 1, 1); PG8_STAGE(PG8_SB(1, 0), b3, voffB); PG8_STAGE(PG8_SB(1, 1), b3 + hstepB, voffB); PG8_STAGE(PG8_SA(1, 0), a3, voffA);
;             PG8_WAIT_V(8); PG8_WAIT_L(0); PG8_BAR; PG8_MMA(1, 0, At, B0); PG8_MMA(1, 1, At, B1); PG8_BAR; PG8_SCHED;
	s_add_i32 s52, 0, 0x18000
	s_add_i32 s75, 0, 0x1c000
	v_add_u32_e32 v142, s52, v206
	v_add_u32_e32 v158, s75, v206
	ds_read_b128 v[126:129], v142
	ds_read_b128 v[130:133], v142 offset:1024
	ds_read_b128 v[138:141], v142 offset:2048
	ds_read_b128 v[142:145], v142 offset:3072
	ds_read_b128 v[146:149], v158
	ds_read_b128 v[150:153], v158 offset:1024
	ds_read_b128 v[154:157], v158 offset:2048
	ds_read_b128 v[158:161], v158 offset:3072
	s_add_u32 s40, s40, 0x80000
	s_addc_u32 s41, s41, 0
	s_mov_b32 m0, s68
	v_lshl_add_u64 v[192:193], s[40:41], 0, v[186:187]
	ds_read_b128 v[162:165], v207 offset:32768
	ds_read_b128 v[166:169], v207 offset:33792
	ds_read_b128 v[170:173], v207 offset:34816
	ds_read_b128 v[174:177], v207 offset:35840
	ds_read_b128 v[198:201], v207 offset:36864
	ds_read_b128 v[208:211], v207 offset:37888
	ds_read_b128 v[212:215], v207 offset:38912
	ds_read_b128 v[216:219], v207 offset:39936
	global_load_lds_dwordx4 v[192:193], off
	v_lshl_add_u64 v[192:193], s[40:41], 0, v[180:181]
	s_mov_b32 m0, s72
	s_nop 0
	global_load_lds_dwordx4 v[192:193], off
	s_waitcnt vmcnt(8)
	s_waitcnt lgkmcnt(0)
	s_barrier
	s_setprio 1
	s_waitcnt lgkmcnt(0)
	v_mfma_f32_16x16x32_bf16 v[118:121], v[126:129], v[162:165], v[118:121]
	v_mfma_f32_16x16x32_bf16 v[114:117], v[138:141], v[162:165], v[114:117]
	v_mfma_f32_16x16x32_bf16 v[78:81], v[126:129], v[170:173], v[78:81]
	v_mfma_f32_16x16x32_bf16 v[134:137], v[138:141], v[170:173], v[134:137]
	v_mfma_f32_16x16x32_bf16 v[30:33], v[126:129], v[198:201], v[30:33]
	v_mfma_f32_16x16x32_bf16 v[22:25], v[138:141], v[198:201], v[22:25]
	v_mfma_f32_16x16x32_bf16 v[110:113], v[126:129], v[212:215], v[110:113]
	v_mfma_f32_16x16x32_bf16 v[14:17], v[138:141], v[212:215], v[14:17]
	v_mfma_f32_16x16x32_bf16 v[118:121], v[130:133], v[166:169], v[118:121]
	v_mfma_f32_16x16x32_bf16 v[114:117], v[142:145], v[166:169], v[114:117]
	v_mfma_f32_16x16x32_bf16 v[78:81], v[130:133], v[174:177], v[78:81]
	v_mfma_f32_16x16x32_bf16 v[134:137], v[142:145], v[174:177], v[134:137]
	v_mfma_f32_16x16x32_bf16 v[30:33], v[130:133], v[208:211], v[30:33]
	v_mfma_f32_16x16x32_bf16 v[22:25], v[142:145], v[208:211], v[22:25]
	v_mfma_f32_16x16x32_bf16 v[110:113], v[130:133], v[216:219], v[110:113]
	v_mfma_f32_16x16x32_bf16 v[14:17], v[142:145], v[216:219], v[14:17]
	s_setprio 0
	s_setprio 1
	v_mfma_f32_16x16x32_bf16 v[74:77], v[146:149], v[162:165], v[74:77]
	v_mfma_f32_16x16x32_bf16 v[54:57], v[154:157], v[162:165], v[54:57]
	v_mfma_f32_16x16x32_bf16 v[50:53], v[146:149], v[170:173], v[50:53]
	v_mfma_f32_16x16x32_bf16 v[26:29], v[154:157], v[170:173], v[26:29]
	v_mfma_f32_16x16x32_bf16 v[18:21], v[146:149], v[198:201], v[18:21]
	v_mfma_f32_16x16x32_bf16 v[10:13], v[154:157], v[198:201], v[10:13]
	v_mfma_f32_16x16x32_bf16 v[2:5], v[146:149], v[212:215], v[2:5]
	v_mfma_f32_16x16x32_bf16 v[6:9], v[154:157], v[212:215], v[6:9]
	v_mfma_f32_16x16x32_bf16 v[74:77], v[150:153], v[166:169], v[74:77]
	v_mfma_f32_16x16x32_bf16 v[54:57], v[158:161], v[166:169], v[54:57]
	v_mfma_f32_16x16x32_bf16 v[50:53], v[150:153], v[174:177], v[50:53]
	v_mfma_f32_16x16x32_bf16 v[26:29], v[158:161], v[174:177], v[26:29]
	v_mfma_f32_16x16x32_bf16 v[18:21], v[150:153], v[208:211], v[18:21]
	v_mfma_f32_16x16x32_bf16 v[10:13], v[158:161], v[208:211], v[10:13]
	v_mfma_f32_16x16x32_bf16 v[2:5], v[150:153], v[216:219], v[2:5]
	v_mfma_f32_16x16x32_bf16 v[6:9], v[158:161], v[216:219], v[6:9]
	s_setprio 0
	s_barrier
; #define PG8_STAGE(bufoff, gbase, voff) do { _Pragma("unroll") for (int _i = 0; _i < 2; ++_i) \
;         __builtin_amdgcn_global_load_lds((const unsigned*)((const char*)(gbase) + (voff)[_i]), (PG8_LAS unsigned*)(lds + (bufoff) + ldsw + _i * 8192), 16, 0, 0); } while (0)
; #define PG8_LDA(dst, b, h) do { _Pragma("unroll") for (int m = 0; m < 4; ++m) _Pragma("unroll") for (int k = 0; k < 2; ++k) dst[m][k] = *(const PG8_LAS bf16x8*)(lds + PG8_SA(b, h) + aoff + m * 2048 + k * 1024); } while (0)
; template <class Epi, class Sched, bool ALIGN_EPI = false, bool SP2 = false, bool ABLK = false, bool BBLK = false>
; __device__ __forceinline__ void gemm_phase(PG8_LAS unsigned char* lds, const Gemm g, const Sched& S, const Epi& E) {
;     ...
;             PG8_LDA(At, 1, 1); PG8_STAGE(PG8_SB(1, 0), b3, voffB); PG8_STAGE(PG8_SB(1, 1), b3 + hstepB, voffB); PG8_STAGE(PG8_SA(1, 0), a3, voffA);
;             PG8_WAIT_V(8); PG8_WAIT_L(0); PG8_BAR; PG8_MMA(1, 0, At, B0); PG8_MMA(1, 1, At, B1); PG8_BAR; PG8_SCHED;
;             } else {
;             PG8_LDB(B0, 0, 0); PG8_SCHED; PG8_LDA(At, 0, 0); PG8_STAGE(PG8_SA(1, 1), a1 + hstepA, voffA);
;             PG8_WAIT_L(8); PG8_BAR; PG8_WAIT_L(0); PG8_MMA(0, 0, At, B0); PG8_BAR; PG8_SCHED;
;             PG8_LDB(B1, 0, 1); PG8_STAGE(PG8_SB(0, 0), b2, voffB);
;             PG8_BAR; PG8_WAIT_L(0); PG8_MMA(0, 1, At, B1); PG8_BAR;
;             PG8_LDA(At, 0, 1); PG8_STAGE(PG8_SA(0, 0), a2, voffA);
;             PG8_BAR; PG8_WAIT_L(0); PG8_MMA(1, 0, At, B0); PG8_BAR; PG8_SCHED;
;             PG8_STAGE(PG8_SB(0, 1), b2 + hstepB, voffB);
;             PG8_WAIT_V(6); PG8_BAR; PG8_MMA(1, 1, At, B1); PG8_BAR;
;             PG8_LDB(B0, 1, 0); PG8_SCHED; PG8_LDA(At, 1, 0); PG8_STAGE(PG8_SA(0, 1), a2 + hstepA, voffA);
;             PG8_WAIT_L(8); PG8_BAR; PG8_WAIT_L(0); PG8_MMA(0, 0, At, B0); PG8_BAR; PG8_SCHED;
;             PG8_LDB(B1, 1, 1); PG8_STAGE(PG8_SB(1, 0), b3, voffB);
;             PG8_BAR; PG8_WAIT_L(0); PG8_MMA(0, 1, At, B1); PG8_BAR;
;             PG8_LDA(At, 1, 1); PG8_STAGE(PG8_SA(1, 0), a3, voffA);
;             PG8_BAR; PG8_WAIT_L(0); PG8_MMA(1, 0, At, B0); PG8_BAR; PG8_SCHED;
;             PG8_STAGE(PG8_SB(1, 1), b3 + hstepB, voffB);
;             PG8_WAIT_V(6); PG8_BAR; PG8_MMA(1, 1, At, B1); PG8_BAR;
;             }
;         }
;         if constexpr (ALIGN_EPI) { if (wr == 0) PG8_BAR; }
	s_add_u32 s40, s8, 0x8000
	s_addc_u32 s41, s9, 0
	s_add_i32 s52, s52, s46
	v_lshl_add_u64 v[192:193], s[40:41], 0, v[178:179]
	s_mov_b32 m0, s52
	ds_read_b128 v[162:165], v207 offset:49152
	ds_read_b128 v[166:169], v207 offset:50176
	ds_read_b128 v[170:173], v207 offset:51200
	ds_read_b128 v[174:177], v207 offset:52224
	ds_read_b128 v[198:201], v207 offset:53248
	ds_read_b128 v[208:211], v207 offset:54272
	ds_read_b128 v[212:215], v207 offset:55296
	ds_read_b128 v[216:219], v207 offset:56320
	global_load_lds_dwordx4 v[192:193], off
	s_add_i32 m0, s52, 0x2000
	s_add_u32 s8, s8, 0xc000
	v_lshl_add_u64 v[192:193], s[40:41], 0, v[182:183]
	s_addc_u32 s9, s9, 0
	s_add_i32 s40, s75, s46
	global_load_lds_dwordx4 v[192:193], off
	v_lshl_add_u64 v[192:193], s[8:9], 0, v[178:179]
	s_mov_b32 m0, s40
	v_lshl_add_u64 v[188:189], v[188:189], 0, s[62:63]
	global_load_lds_dwordx4 v[192:193], off
	v_lshl_add_u64 v[192:193], s[8:9], 0, v[182:183]
	s_add_i32 m0, s40, 0x2000
	s_nop 0
	global_load_lds_dwordx4 v[192:193], off
	s_mov_b32 m0, s33
	s_nop 0
	global_load_lds_dwordx4 v[188:189], off
	v_lshl_add_u64 v[188:189], v[190:191], 0, s[62:63]
	s_mov_b32 m0, s91
	s_nop 0
	global_load_lds_dwordx4 v[188:189], off
	s_waitcnt vmcnt(8)
	s_waitcnt lgkmcnt(0)
	s_barrier
	s_setprio 1
	s_waitcnt lgkmcnt(0)
	v_mfma_f32_16x16x32_bf16 v[106:109], v[126:129], v[162:165], v[106:109]
	v_mfma_f32_16x16x32_bf16 v[102:105], v[138:141], v[162:165], v[102:105]
	v_mfma_f32_16x16x32_bf16 v[94:97], v[126:129], v[170:173], v[94:97]
	v_mfma_f32_16x16x32_bf16 v[86:89], v[138:141], v[170:173], v[86:89]
	v_mfma_f32_16x16x32_bf16 v[70:73], v[126:129], v[198:201], v[70:73]
	v_mfma_f32_16x16x32_bf16 v[62:65], v[138:141], v[198:201], v[62:65]
	v_mfma_f32_16x16x32_bf16 v[122:125], v[126:129], v[212:215], v[122:125]
	v_mfma_f32_16x16x32_bf16 v[46:49], v[138:141], v[212:215], v[46:49]
	v_mfma_f32_16x16x32_bf16 v[106:109], v[130:133], v[166:169], v[106:109]
	v_mfma_f32_16x16x32_bf16 v[102:105], v[142:145], v[166:169], v[102:105]
	v_mfma_f32_16x16x32_bf16 v[94:97], v[130:133], v[174:177], v[94:97]
	v_mfma_f32_16x16x32_bf16 v[86:89], v[142:145], v[174:177], v[86:89]
	v_mfma_f32_16x16x32_bf16 v[70:73], v[130:133], v[208:211], v[70:73]
	v_mfma_f32_16x16x32_bf16 v[62:65], v[142:145], v[208:211], v[62:65]
	v_mfma_f32_16x16x32_bf16 v[130:133], v[130:133], v[216:219], v[122:125]
	v_mfma_f32_16x16x32_bf16 v[46:49], v[142:145], v[216:219], v[46:49]
	s_setprio 0
	s_setprio 1
	v_mfma_f32_16x16x32_bf16 v[98:101], v[146:149], v[162:165], v[98:101]
	v_mfma_f32_16x16x32_bf16 v[90:93], v[154:157], v[162:165], v[90:93]
	v_mfma_f32_16x16x32_bf16 v[82:85], v[146:149], v[170:173], v[82:85]
	v_mfma_f32_16x16x32_bf16 v[66:69], v[154:157], v[170:173], v[66:69]
	v_mfma_f32_16x16x32_bf16 v[58:61], v[146:149], v[198:201], v[58:61]
	v_mfma_f32_16x16x32_bf16 v[42:45], v[154:157], v[198:201], v[42:45]
	v_mfma_f32_16x16x32_bf16 v[34:37], v[146:149], v[212:215], v[34:37]
	v_mfma_f32_16x16x32_bf16 v[38:41], v[154:157], v[212:215], v[38:41]
	v_mfma_f32_16x16x32_bf16 v[98:101], v[150:153], v[166:169], v[98:101]
	v_mfma_f32_16x16x32_bf16 v[90:93], v[158:161], v[166:169], v[90:93]
	v_mfma_f32_16x16x32_bf16 v[82:85], v[150:153], v[174:177], v[82:85]
	v_mfma_f32_16x16x32_bf16 v[66:69], v[158:161], v[174:177], v[66:69]
	v_mfma_f32_16x16x32_bf16 v[58:61], v[150:153], v[208:211], v[58:61]
	v_mfma_f32_16x16x32_bf16 v[42:45], v[158:161], v[208:211], v[42:45]
	v_mfma_f32_16x16x32_bf16 v[34:37], v[150:153], v[216:219], v[34:37]
	v_mfma_f32_16x16x32_bf16 v[38:41], v[158:161], v[216:219], v[38:41]
	s_setprio 0
	s_barrier
	s_add_i32 s92, s92, 2
	s_add_u32 s60, s60, 0x10000
	s_addc_u32 s61, s61, 0
	s_add_u32 s0, s0, 0x100
	s_addc_u32 s1, s1, 0
	s_cmp_gt_u32 s92, 29
	s_cbranch_scc0 .LBB0_1239
	s_and_b64 vcc, exec, s[18:19]
	s_cbranch_vccz .LBB0_1242
	s_barrier

; __device__ __forceinline__ u32x4 pack8(const f32x4 v0, const f32x4 v1) { u32x4 w; w.x = cvt_pk_bf16(v0[0], v0[1]); w.y = cvt_pk_bf16(v0[2], v0[3]); w.z = cvt_pk_bf16(v1[0], v1[1]); w.w = cvt_pk_bf16(v1[2], v1[3]); return w; }
;     __device__ __forceinline__ void operator()(f32x4 (&acc)[2][2][4][2], const Unit& u, int wr, int wc, int fr_, int fq_) const {
;     ...
;             for (int n = 0; n < 2; ++n) { const int col = col0 + bj * HALF + 4 * n; const f32x4 g = *(const f32x4*)(gain + col);
;                 if (FINAL) { av[bj][n] = g; sv[bj][n] = (f32x4){0.f, 0.f, 0.f, 0.f}; }
;                 else { const float* mp = nmod + (size_t)rb * NMODC; av[bj][n] = g * (*(const f32x4*)(mp + isc * DM + col) + 1.0f); sv[bj][n] = *(const f32x4*)(mp + ish * DM + col); } }
;         if (wid == 0) { if (lane == 0) { unsigned sp = 0u; while (__hip_atomic_load(cnt + 16 * u.pm, __ATOMIC_RELAXED, __HIP_MEMORY_SCOPE_AGENT) < 64u) { __builtin_amdgcn_s_sleep(1); if (++sp > (1u << 17)) break; } } }
;         asm volatile("s_waitcnt lgkmcnt(0)" ::: "memory"); __builtin_amdgcn_s_barrier(); asm volatile("" ::: "memory");
;         if (lane < 32) { const float* slot = xbuf + ((size_t)u.pm * BM + row) * 8; float t8[8];
; #pragma unroll
;             for (int t = 0; t < 8; ++t) t8[t] = __hip_atomic_load(slot + t, __ATOMIC_RELAXED, __HIP_MEMORY_SCOPE_AGENT);
;             const float tot = ((t8[0] + t8[1]) + (t8[2] + t8[3])) + ((t8[4] + t8[5]) + (t8[6] + t8[7]));
;             S[row] = __builtin_amdgcn_rsqf(tot * (1.0f / DM) + 1e-6f); }
;         asm volatile("s_waitcnt lgkmcnt(0)" ::: "memory"); __builtin_amdgcn_s_barrier(); asm volatile("" ::: "memory");
; #pragma unroll
;         for (int ai = 0; ai < 2; ++ai)
; #pragma unroll
;             for (int m = 0; m < 4; ++m) { const int r = ai * HALF + wr * 64 + m * 16 + fr; const float rs = S[r];
; #pragma unroll
;                 for (int bj = 0; bj < 2; ++bj) { const f32x4 y0 = acc[ai][bj][m][0] * rs * av[bj][0] + sv[bj][0], y1 = acc[ai][bj][m][1] * rs * av[bj][1] + sv[bj][1];
;                     if (FINAL) { float* o = OUTF + ((size_t)u.pm * BM + r) * DM + col0 + bj * HALF; *(f32x4*)o = y0; *(f32x4*)(o + 4) = y1; }
;                     else *(u32x4*)(XN + (((size_t)u.pm * (DM / BK) + u.pn * 4 + bj * 2 + (wc >> 1)) * BM + r) * BK + (wc & 1) * 32 + 8 * fq) = pack8(y0, y1); } }
.LBB0_1274:
	s_or_b64 exec, exec, s[0:1]
	s_waitcnt vmcnt(7)
	v_pk_add_f32 v[154:155], v[154:155], 1.0 op_sel_hi:[1,0]
	v_pk_add_f32 v[156:157], v[156:157], 1.0 op_sel_hi:[1,0]
	v_pk_mul_f32 v[146:147], v[146:147], v[154:155]
	v_lshl_add_u32 v154, v198, 2, 0
	s_waitcnt lgkmcnt(0)
	s_barrier
	s_lshl_b32 s8, s34, 2
	v_add_u32_e32 v154, 0x21540, v154
	v_pk_mul_f32 v[148:149], v[148:149], v[156:157]
	s_lshl_b64 s[0:1], s[36:37], 5
	s_ashr_i32 s9, s8, 31
	ds_read_b32 v156, v154
	s_add_u32 s0, s0, s8
	s_addc_u32 s1, s1, s9
	s_or_b64 s[0:1], s[0:1], s[20:21]
	s_waitcnt vmcnt(5)
	v_pk_add_f32 v[158:159], v[158:159], 1.0 op_sel_hi:[1,0]
	s_lshl_b64 s[0:1], s[0:1], 15
	v_pk_add_f32 v[160:161], v[160:161], 1.0 op_sel_hi:[1,0]
	v_pk_mul_f32 v[150:151], v[150:151], v[158:159]
	s_waitcnt lgkmcnt(0)
	v_pk_mul_f32 v[126:127], v[126:127], v[156:157] op_sel_hi:[1,0]
	v_pk_mul_f32 v[122:123], v[122:123], v[156:157] op_sel_hi:[1,0]
	s_add_u32 s0, s50, s0
	v_pk_mul_f32 v[152:153], v[152:153], v[160:161]
	v_lshlrev_b64 v[158:159], 7, v[198:199]
	v_pk_mul_f32 v[128:129], v[128:129], v[156:157] op_sel_hi:[1,0]
	s_waitcnt vmcnt(3)
	v_pk_fma_f32 v[126:127], v[146:147], v[126:127], v[142:143]
	v_pk_mul_f32 v[124:125], v[124:125], v[156:157] op_sel_hi:[1,0]
	s_waitcnt vmcnt(1)
	v_pk_fma_f32 v[122:123], v[150:151], v[122:123], v[138:139]
	s_addc_u32 s1, s51, s1
	v_ashrrev_i32_e32 v201, 31, v200
	v_pk_fma_f32 v[128:129], v[148:149], v[128:129], v[144:145]
	v_pk_fma_f32 v[160:161], v[152:153], v[124:125], v[140:141]
	v_cvt_pk_bf16_f32 v124, v126, v127
	v_cvt_pk_bf16_f32 v125, v128, v129
	v_cvt_pk_bf16_f32 v126, v122, v123
	v_lshl_add_u64 v[122:123], s[0:1], 0, v[158:159]
	v_pk_add_f32 v[176:177], v[176:177], 1.0 op_sel_hi:[1,0]
	v_pk_add_f32 v[174:175], v[174:175], 1.0 op_sel_hi:[1,0]
	v_pk_add_f32 v[172:173], v[172:173], 1.0 op_sel_hi:[1,0]
	v_lshl_add_u64 v[128:129], v[122:123], 0, s[16:17]
	v_lshlrev_b64 v[122:123], 1, v[200:201]
	v_pk_mul_f32 v[166:167], v[166:167], v[174:175]
	v_pk_mul_f32 v[168:169], v[168:169], v[176:177]
	v_pk_add_f32 v[170:171], v[170:171], 1.0 op_sel_hi:[1,0]
	v_pk_mul_f32 v[164:165], v[164:165], v[172:173]
	v_lshl_add_u64 v[128:129], v[128:129], 0, v[122:123]
	v_pk_mul_f32 v[120:121], v[120:121], v[156:157] op_sel_hi:[1,0]
	v_pk_mul_f32 v[114:115], v[114:115], v[156:157] op_sel_hi:[1,0]
	v_pk_mul_f32 v[116:117], v[116:117], v[156:157] op_sel_hi:[1,0]
	v_pk_mul_f32 v[162:163], v[162:163], v[170:171]
	v_cvt_pk_bf16_f32 v127, v160, v161
	global_store_dwordx4 v[128:129], v[124:127], off
	v_pk_mul_f32 v[118:119], v[118:119], v[156:157] op_sel_hi:[1,0]
	s_waitcnt vmcnt(1)
	v_pk_fma_f32 v[120:121], v[164:165], v[120:121], v[136:137]
	v_pk_fma_f32 v[124:125], v[168:169], v[116:117], v[132:133]
	v_pk_fma_f32 v[116:117], v[166:167], v[114:115], v[130:131]
	s_add_u32 s8, s0, 0x10000
	v_pk_fma_f32 v[118:119], v[162:163], v[118:119], v[134:135]
	s_addc_u32 s9, s1, 0
	v_cvt_pk_bf16_f32 v114, v118, v119
	v_cvt_pk_bf16_f32 v115, v120, v121
	v_cvt_pk_bf16_f32 v116, v116, v117
	v_cvt_pk_bf16_f32 v117, v124, v125
	ds_read_b32 v120, v154 offset:64
	v_lshl_add_u64 v[118:119], s[8:9], 0, v[158:159]
	v_lshl_add_u64 v[118:119], v[118:119], 0, s[16:17]
	v_lshl_add_u64 v[118:119], v[118:119], 0, v[122:123]
	global_store_dwordx4 v[118:119], v[114:117], off
	s_waitcnt lgkmcnt(0)
	v_pk_mul_f32 v[78:79], v[78:79], v[120:121] op_sel_hi:[1,0]
	v_pk_mul_f32 v[74:75], v[74:75], v[120:121] op_sel_hi:[1,0]
	v_add_u32_e32 v114, 16, v198
	v_ashrrev_i32_e32 v115, 31, v114
	v_lshlrev_b64 v[114:115], 7, v[114:115]
	v_pk_fma_f32 v[78:79], v[146:147], v[78:79], v[142:143]
	v_pk_mul_f32 v[76:77], v[76:77], v[120:121] op_sel_hi:[1,0]
	v_pk_mul_f32 v[50:51], v[50:51], v[120:121] op_sel_hi:[1,0]
	v_pk_fma_f32 v[116:117], v[152:153], v[76:77], v[140:141]
	v_pk_fma_f32 v[76:77], v[150:151], v[74:75], v[138:139]
	v_cvt_pk_bf16_f32 v74, v78, v79
	v_lshl_add_u64 v[78:79], s[0:1], 0, v[114:115]
	v_lshl_add_u64 v[78:79], v[78:79], 0, s[16:17]
	v_pk_mul_f32 v[52:53], v[52:53], v[120:121] op_sel_hi:[1,0]
	v_pk_mul_f32 v[56:57], v[56:57], v[120:121] op_sel_hi:[1,0]
	v_pk_mul_f32 v[80:81], v[80:81], v[120:121] op_sel_hi:[1,0]
	v_lshl_add_u64 v[78:79], v[78:79], 0, v[122:123]
	v_pk_fma_f32 v[52:53], v[164:165], v[52:53], v[136:137]
	v_pk_fma_f32 v[50:51], v[162:163], v[50:51], v[134:135]
	v_pk_mul_f32 v[54:55], v[54:55], v[120:121] op_sel_hi:[1,0]
	v_pk_fma_f32 v[56:57], v[168:169], v[56:57], v[132:133]
	v_pk_fma_f32 v[80:81], v[148:149], v[80:81], v[144:145]
	v_pk_fma_f32 v[54:55], v[166:167], v[54:55], v[130:131]
	v_cvt_pk_bf16_f32 v75, v80, v81
	v_cvt_pk_bf16_f32 v76, v76, v77
	v_cvt_pk_bf16_f32 v77, v116, v117
	global_store_dwordx4 v[78:79], v[74:77], off
	v_cvt_pk_bf16_f32 v50, v50, v51
	v_cvt_pk_bf16_f32 v51, v52, v53
	v_cvt_pk_bf16_f32 v52, v54, v55
	v_cvt_pk_bf16_f32 v53, v56, v57
	ds_read_b32 v56, v154 offset:128
	v_lshl_add_u64 v[54:55], s[8:9], 0, v[114:115]
	v_lshl_add_u64 v[54:55], v[54:55], 0, s[16:17]
	v_lshl_add_u64 v[54:55], v[54:55], 0, v[122:123]
	global_store_dwordx4 v[54:55], v[50:53], off
	s_waitcnt lgkmcnt(0)
; __device__ __forceinline__ u32x4 pack8(const f32x4 v0, const f32x4 v1) { u32x4 w; w.x = cvt_pk_bf16(v0[0], v0[1]); w.y = cvt_pk_bf16(v0[2], v0[3]); w.z = cvt_pk_bf16(v1[0], v1[1]); w.w = cvt_pk_bf16(v1[2], v1[3]); return w; }
;     __device__ __forceinline__ void operator()(f32x4 (&acc)[2][2][4][2], const Unit& u, int wr, int wc, int fr_, int fq_) const {
;     ...
; #pragma unroll
;         for (int ai = 0; ai < 2; ++ai)
; #pragma unroll
;             for (int m = 0; m < 4; ++m) { const int r = ai * HALF + wr * 64 + m * 16 + fr; const float rs = S[r];
; #pragma unroll
;                 for (int bj = 0; bj < 2; ++bj) { const f32x4 y0 = acc[ai][bj][m][0] * rs * av[bj][0] + sv[bj][0], y1 = acc[ai][bj][m][1] * rs * av[bj][1] + sv[bj][1];
;                     if (FINAL) { float* o = OUTF + ((size_t)u.pm * BM + r) * DM + col0 + bj * HALF; *(f32x4*)o = y0; *(f32x4*)(o + 4) = y1; }
;                     else *(u32x4*)(XN + (((size_t)u.pm * (DM / BK) + u.pn * 4 + bj * 2 + (wc >> 1)) * BM + r) * BK + (wc & 1) * 32 + 8 * fq) = pack8(y0, y1); } }
	v_pk_mul_f32 v[26:27], v[26:27], v[56:57] op_sel_hi:[1,0]
	v_pk_mul_f32 v[28:29], v[28:29], v[56:57] op_sel_hi:[1,0]
	v_add_u32_e32 v50, 32, v198
	v_ashrrev_i32_e32 v51, 31, v50
	v_pk_mul_f32 v[30:31], v[30:31], v[56:57] op_sel_hi:[1,0]
	v_lshlrev_b64 v[50:51], 7, v[50:51]
	v_pk_fma_f32 v[28:29], v[148:149], v[28:29], v[144:145]
	v_pk_fma_f32 v[26:27], v[146:147], v[26:27], v[142:143]
	v_pk_fma_f32 v[30:31], v[150:151], v[30:31], v[138:139]
	v_cvt_pk_bf16_f32 v26, v26, v27
	v_cvt_pk_bf16_f32 v27, v28, v29
	v_pk_mul_f32 v[18:19], v[18:19], v[56:57] op_sel_hi:[1,0]
	v_cvt_pk_bf16_f32 v28, v30, v31
	v_lshl_add_u64 v[30:31], s[0:1], 0, v[50:51]
	v_lshl_add_u64 v[30:31], v[30:31], 0, s[16:17]
	v_pk_mul_f32 v[20:21], v[20:21], v[56:57] op_sel_hi:[1,0]
	v_pk_mul_f32 v[24:25], v[24:25], v[56:57] op_sel_hi:[1,0]
	v_pk_mul_f32 v[32:33], v[32:33], v[56:57] op_sel_hi:[1,0]
	v_lshl_add_u64 v[30:31], v[30:31], 0, v[122:123]
	v_pk_fma_f32 v[20:21], v[164:165], v[20:21], v[136:137]
	v_pk_fma_f32 v[18:19], v[162:163], v[18:19], v[134:135]
	v_pk_mul_f32 v[22:23], v[22:23], v[56:57] op_sel_hi:[1,0]
	v_pk_fma_f32 v[24:25], v[168:169], v[24:25], v[132:133]
	v_pk_fma_f32 v[32:33], v[152:153], v[32:33], v[140:141]
	v_pk_fma_f32 v[22:23], v[166:167], v[22:23], v[130:131]
	v_cvt_pk_bf16_f32 v29, v32, v33
	global_store_dwordx4 v[30:31], v[26:29], off
	v_cvt_pk_bf16_f32 v18, v18, v19
	v_cvt_pk_bf16_f32 v19, v20, v21
	v_cvt_pk_bf16_f32 v20, v22, v23
	v_cvt_pk_bf16_f32 v21, v24, v25
	ds_read_b32 v24, v154 offset:192
	v_lshl_add_u64 v[22:23], s[8:9], 0, v[50:51]
	v_lshl_add_u64 v[22:23], v[22:23], 0, s[16:17]
	v_lshl_add_u64 v[22:23], v[22:23], 0, v[122:123]
	global_store_dwordx4 v[22:23], v[18:21], off
	s_waitcnt lgkmcnt(0)
	v_pk_mul_f32 v[10:11], v[10:11], v[24:25] op_sel_hi:[1,0]
	v_pk_mul_f32 v[12:13], v[12:13], v[24:25] op_sel_hi:[1,0]
	v_add_u32_e32 v18, 48, v198
	v_ashrrev_i32_e32 v19, 31, v18
	v_pk_mul_f32 v[14:15], v[14:15], v[24:25] op_sel_hi:[1,0]
	v_lshlrev_b64 v[18:19], 7, v[18:19]
	v_pk_fma_f32 v[12:13], v[148:149], v[12:13], v[144:145]
	v_pk_fma_f32 v[10:11], v[146:147], v[10:11], v[142:143]
	v_pk_fma_f32 v[14:15], v[150:151], v[14:15], v[138:139]
	v_cvt_pk_bf16_f32 v10, v10, v11
	v_cvt_pk_bf16_f32 v11, v12, v13
	v_pk_mul_f32 v[2:3], v[2:3], v[24:25] op_sel_hi:[1,0]
	v_cvt_pk_bf16_f32 v12, v14, v15
	v_lshl_add_u64 v[14:15], s[0:1], 0, v[18:19]
	v_lshl_add_u64 v[14:15], v[14:15], 0, s[16:17]
	v_pk_mul_f32 v[4:5], v[4:5], v[24:25] op_sel_hi:[1,0]
	v_pk_mul_f32 v[6:7], v[6:7], v[24:25] op_sel_hi:[1,0]
	v_pk_mul_f32 v[8:9], v[8:9], v[24:25] op_sel_hi:[1,0]
	v_pk_mul_f32 v[16:17], v[16:17], v[24:25] op_sel_hi:[1,0]
	v_lshl_add_u64 v[14:15], v[14:15], 0, v[122:123]
	v_pk_fma_f32 v[4:5], v[164:165], v[4:5], v[136:137]
	v_pk_fma_f32 v[2:3], v[162:163], v[2:3], v[134:135]
	v_pk_fma_f32 v[8:9], v[168:169], v[8:9], v[132:133]
	v_pk_fma_f32 v[6:7], v[166:167], v[6:7], v[130:131]
	v_pk_fma_f32 v[16:17], v[152:153], v[16:17], v[140:141]
	s_andn2_b64 vcc, exec, s[6:7]
	v_cvt_pk_bf16_f32 v13, v16, v17
	global_store_dwordx4 v[14:15], v[10:13], off
	v_cvt_pk_bf16_f32 v2, v2, v3
	v_cvt_pk_bf16_f32 v3, v4, v5
	v_cvt_pk_bf16_f32 v4, v6, v7
	v_cvt_pk_bf16_f32 v5, v8, v9
	v_lshl_add_u64 v[6:7], s[8:9], 0, v[18:19]
	ds_read_b32 v8, v154 offset:512
	v_lshl_add_u64 v[6:7], v[6:7], 0, s[16:17]
	v_lshl_add_u64 v[6:7], v[6:7], 0, v[122:123]
	global_store_dwordx4 v[6:7], v[2:5], off
	s_waitcnt lgkmcnt(0)
	v_pk_mul_f32 v[10:11], v[110:111], v[8:9] op_sel_hi:[1,0]
	v_add_u32_e32 v2, 0x80, v198
	v_ashrrev_i32_e32 v3, 31, v2
	v_lshlrev_b64 v[6:7], 7, v[2:3]
	v_pk_mul_f32 v[2:3], v[106:107], v[8:9] op_sel_hi:[1,0]
	v_pk_mul_f32 v[4:5], v[108:109], v[8:9] op_sel_hi:[1,0]
	v_pk_fma_f32 v[2:3], v[146:147], v[2:3], v[142:143]
	v_pk_fma_f32 v[4:5], v[148:149], v[4:5], v[144:145]
	v_pk_fma_f32 v[10:11], v[150:151], v[10:11], v[138:139]
	v_cvt_pk_bf16_f32 v2, v2, v3
	v_cvt_pk_bf16_f32 v3, v4, v5
	v_pk_mul_f32 v[12:13], v[112:113], v[8:9] op_sel_hi:[1,0]
	v_cvt_pk_bf16_f32 v4, v10, v11
	v_lshl_add_u64 v[10:11], s[0:1], 0, v[6:7]
	v_lshl_add_u64 v[10:11], v[10:11], 0, s[16:17]
	v_pk_fma_f32 v[12:13], v[152:153], v[12:13], v[140:141]
	v_lshl_add_u64 v[10:11], v[10:11], 0, v[122:123]
	v_cvt_pk_bf16_f32 v5, v12, v13
	global_store_dwordx4 v[10:11], v[2:5], off
	v_pk_mul_f32 v[10:11], v[102:103], v[8:9] op_sel_hi:[1,0]
	v_lshl_add_u64 v[6:7], s[8:9], 0, v[6:7]
	v_pk_mul_f32 v[2:3], v[98:99], v[8:9] op_sel_hi:[1,0]
	v_pk_mul_f32 v[4:5], v[100:101], v[8:9] op_sel_hi:[1,0]
	v_pk_mul_f32 v[8:9], v[104:105], v[8:9] op_sel_hi:[1,0]
	v_pk_fma_f32 v[4:5], v[164:165], v[4:5], v[136:137]
	v_pk_fma_f32 v[2:3], v[162:163], v[2:3], v[134:135]
	v_pk_fma_f32 v[8:9], v[168:169], v[8:9], v[132:133]
	v_pk_fma_f32 v[10:11], v[166:167], v[10:11], v[130:131]
	v_cvt_pk_bf16_f32 v2, v2, v3
	v_cvt_pk_bf16_f32 v3, v4, v5
	v_lshl_add_u64 v[6:7], v[6:7], 0, s[16:17]
	v_cvt_pk_bf16_f32 v4, v10, v11
	v_cvt_pk_bf16_f32 v5, v8, v9
	ds_read_b32 v8, v154 offset:576
	v_lshl_add_u64 v[6:7], v[6:7], 0, v[122:123]
	global_store_dwordx4 v[6:7], v[2:5], off
	s_waitcnt lgkmcnt(0)
; __device__ __forceinline__ u32x4 pack8(const f32x4 v0, const f32x4 v1) { u32x4 w; w.x = cvt_pk_bf16(v0[0], v0[1]); w.y = cvt_pk_bf16(v0[2], v0[3]); w.z = cvt_pk_bf16(v1[0], v1[1]); w.w = cvt_pk_bf16(v1[2], v1[3]); return w; }
; #define PG8_BAR __builtin_amdgcn_s_barrier()
;     __device__ __forceinline__ void operator()(f32x4 (&acc)[2][2][4][2], const Unit& u, int wr, int wc, int fr_, int fq_) const {
;     ...
; #pragma unroll
;         for (int ai = 0; ai < 2; ++ai)
; #pragma unroll
;             for (int m = 0; m < 4; ++m) { const int r = ai * HALF + wr * 64 + m * 16 + fr; const float rs = S[r];
; #pragma unroll
;                 for (int bj = 0; bj < 2; ++bj) { const f32x4 y0 = acc[ai][bj][m][0] * rs * av[bj][0] + sv[bj][0], y1 = acc[ai][bj][m][1] * rs * av[bj][1] + sv[bj][1];
;                     if (FINAL) { float* o = OUTF + ((size_t)u.pm * BM + r) * DM + col0 + bj * HALF; *(f32x4*)o = y0; *(f32x4*)(o + 4) = y1; }
;                     else *(u32x4*)(XN + (((size_t)u.pm * (DM / BK) + u.pn * 4 + bj * 2 + (wc >> 1)) * BM + r) * BK + (wc & 1) * 32 + 8 * fq) = pack8(y0, y1); } }
; template <class Epi, class Sched, bool ALIGN_EPI = false, bool SP2 = false, bool ABLK = false, bool BBLK = false>
; __device__ __forceinline__ void gemm_phase(PG8_LAS unsigned char* lds, const Gemm g, const Sched& S, const Epi& E) {
;     ...
;         if (!has_next) break;
; #pragma unroll
;         for (int a = 0; a < 2; ++a)
; #pragma unroll
;             for (int b = 0; b < 2; ++b)
; #pragma unroll
;                 for (int m = 0; m < 4; ++m)
; #pragma unroll
;                     for (int n = 0; n < 2; ++n) acc[a][b][m][n] = (f32x4){0.f, 0.f, 0.f, 0.f};
;         cur = nxt; cA = nA; cB = nB; ++ui;
;         if constexpr (ALIGN_EPI) { if (wr == 1) PG8_BAR; }
;     }
	v_pk_mul_f32 v[10:11], v[94:95], v[8:9] op_sel_hi:[1,0]
	v_add_u32_e32 v2, 0x90, v198
	v_ashrrev_i32_e32 v3, 31, v2
	v_lshlrev_b64 v[6:7], 7, v[2:3]
	v_pk_mul_f32 v[2:3], v[90:91], v[8:9] op_sel_hi:[1,0]
	v_pk_mul_f32 v[4:5], v[92:93], v[8:9] op_sel_hi:[1,0]
	v_pk_fma_f32 v[2:3], v[146:147], v[2:3], v[142:143]
	v_pk_fma_f32 v[4:5], v[148:149], v[4:5], v[144:145]
	v_pk_fma_f32 v[10:11], v[150:151], v[10:11], v[138:139]
	v_cvt_pk_bf16_f32 v2, v2, v3
	v_cvt_pk_bf16_f32 v3, v4, v5
	v_pk_mul_f32 v[12:13], v[96:97], v[8:9] op_sel_hi:[1,0]
	v_cvt_pk_bf16_f32 v4, v10, v11
	v_lshl_add_u64 v[10:11], s[0:1], 0, v[6:7]
	v_lshl_add_u64 v[10:11], v[10:11], 0, s[16:17]
	v_pk_fma_f32 v[12:13], v[152:153], v[12:13], v[140:141]
	v_lshl_add_u64 v[10:11], v[10:11], 0, v[122:123]
	v_cvt_pk_bf16_f32 v5, v12, v13
	global_store_dwordx4 v[10:11], v[2:5], off
	v_pk_mul_f32 v[10:11], v[86:87], v[8:9] op_sel_hi:[1,0]
	v_lshl_add_u64 v[6:7], s[8:9], 0, v[6:7]
	v_pk_mul_f32 v[2:3], v[82:83], v[8:9] op_sel_hi:[1,0]
	v_pk_mul_f32 v[4:5], v[84:85], v[8:9] op_sel_hi:[1,0]
	v_pk_mul_f32 v[8:9], v[88:89], v[8:9] op_sel_hi:[1,0]
	v_pk_fma_f32 v[4:5], v[164:165], v[4:5], v[136:137]
	v_pk_fma_f32 v[2:3], v[162:163], v[2:3], v[134:135]
	v_pk_fma_f32 v[8:9], v[168:169], v[8:9], v[132:133]
	v_pk_fma_f32 v[10:11], v[166:167], v[10:11], v[130:131]
	v_cvt_pk_bf16_f32 v2, v2, v3
	v_cvt_pk_bf16_f32 v3, v4, v5
	v_lshl_add_u64 v[6:7], v[6:7], 0, s[16:17]
	v_cvt_pk_bf16_f32 v4, v10, v11
	v_cvt_pk_bf16_f32 v5, v8, v9
	ds_read_b32 v8, v154 offset:640
	v_lshl_add_u64 v[6:7], v[6:7], 0, v[122:123]
	global_store_dwordx4 v[6:7], v[2:5], off
	s_waitcnt lgkmcnt(0)
	v_pk_mul_f32 v[10:11], v[70:71], v[8:9] op_sel_hi:[1,0]
	v_add_u32_e32 v2, 0xa0, v198
	v_ashrrev_i32_e32 v3, 31, v2
	v_lshlrev_b64 v[6:7], 7, v[2:3]
	v_pk_mul_f32 v[2:3], v[66:67], v[8:9] op_sel_hi:[1,0]
	v_pk_mul_f32 v[4:5], v[68:69], v[8:9] op_sel_hi:[1,0]
	v_pk_fma_f32 v[2:3], v[146:147], v[2:3], v[142:143]
	v_pk_fma_f32 v[4:5], v[148:149], v[4:5], v[144:145]
	v_pk_fma_f32 v[10:11], v[150:151], v[10:11], v[138:139]
	v_cvt_pk_bf16_f32 v2, v2, v3
	v_cvt_pk_bf16_f32 v3, v4, v5
	v_pk_mul_f32 v[12:13], v[72:73], v[8:9] op_sel_hi:[1,0]
	v_cvt_pk_bf16_f32 v4, v10, v11
	v_lshl_add_u64 v[10:11], s[0:1], 0, v[6:7]
	v_lshl_add_u64 v[10:11], v[10:11], 0, s[16:17]
	v_pk_fma_f32 v[12:13], v[152:153], v[12:13], v[140:141]
	v_lshl_add_u64 v[10:11], v[10:11], 0, v[122:123]
	v_cvt_pk_bf16_f32 v5, v12, v13
	global_store_dwordx4 v[10:11], v[2:5], off
	v_pk_mul_f32 v[10:11], v[62:63], v[8:9] op_sel_hi:[1,0]
	v_lshl_add_u64 v[6:7], s[8:9], 0, v[6:7]
	v_pk_mul_f32 v[2:3], v[58:59], v[8:9] op_sel_hi:[1,0]
	v_pk_mul_f32 v[4:5], v[60:61], v[8:9] op_sel_hi:[1,0]
	v_pk_mul_f32 v[8:9], v[64:65], v[8:9] op_sel_hi:[1,0]
	v_pk_fma_f32 v[4:5], v[164:165], v[4:5], v[136:137]
	v_pk_fma_f32 v[2:3], v[162:163], v[2:3], v[134:135]
	v_pk_fma_f32 v[8:9], v[168:169], v[8:9], v[132:133]
	v_pk_fma_f32 v[10:11], v[166:167], v[10:11], v[130:131]
	v_cvt_pk_bf16_f32 v2, v2, v3
	v_cvt_pk_bf16_f32 v3, v4, v5
	v_lshl_add_u64 v[6:7], v[6:7], 0, s[16:17]
	v_cvt_pk_bf16_f32 v4, v10, v11
	v_cvt_pk_bf16_f32 v5, v8, v9
	ds_read_b32 v8, v154 offset:704
	v_lshl_add_u64 v[6:7], v[6:7], 0, v[122:123]
	global_store_dwordx4 v[6:7], v[2:5], off
	s_waitcnt lgkmcnt(0)
	v_pk_mul_f32 v[10:11], v[46:47], v[8:9] op_sel_hi:[1,0]
	v_add_u32_e32 v2, 0xb0, v198
	v_ashrrev_i32_e32 v3, 31, v2
	v_lshlrev_b64 v[6:7], 7, v[2:3]
	v_pk_mul_f32 v[2:3], v[42:43], v[8:9] op_sel_hi:[1,0]
	v_pk_mul_f32 v[4:5], v[44:45], v[8:9] op_sel_hi:[1,0]
	v_pk_fma_f32 v[2:3], v[146:147], v[2:3], v[142:143]
	v_pk_fma_f32 v[4:5], v[148:149], v[4:5], v[144:145]
	v_pk_fma_f32 v[10:11], v[150:151], v[10:11], v[138:139]
	v_cvt_pk_bf16_f32 v2, v2, v3
	v_cvt_pk_bf16_f32 v3, v4, v5
	v_pk_mul_f32 v[12:13], v[48:49], v[8:9] op_sel_hi:[1,0]
	v_cvt_pk_bf16_f32 v4, v10, v11
	v_lshl_add_u64 v[10:11], s[0:1], 0, v[6:7]
	v_lshl_add_u64 v[10:11], v[10:11], 0, s[16:17]
	v_pk_fma_f32 v[12:13], v[152:153], v[12:13], v[140:141]
	v_lshl_add_u64 v[10:11], v[10:11], 0, v[122:123]
	v_cvt_pk_bf16_f32 v5, v12, v13
	v_lshl_add_u64 v[6:7], s[8:9], 0, v[6:7]
	global_store_dwordx4 v[10:11], v[2:5], off
	v_lshl_add_u64 v[6:7], v[6:7], 0, s[16:17]
	v_pk_mul_f32 v[10:11], v[38:39], v[8:9] op_sel_hi:[1,0]
	v_pk_mul_f32 v[2:3], v[34:35], v[8:9] op_sel_hi:[1,0]
	v_pk_mul_f32 v[4:5], v[36:37], v[8:9] op_sel_hi:[1,0]
	v_pk_fma_f32 v[2:3], v[162:163], v[2:3], v[134:135]
	v_pk_fma_f32 v[4:5], v[164:165], v[4:5], v[136:137]
	v_pk_mul_f32 v[8:9], v[40:41], v[8:9] op_sel_hi:[1,0]
	v_lshl_add_u64 v[6:7], v[6:7], 0, v[122:123]
	s_mov_b64 s[0:1], -1
	v_pk_fma_f32 v[8:9], v[168:169], v[8:9], v[132:133]
	v_pk_fma_f32 v[10:11], v[166:167], v[10:11], v[130:131]
	v_cvt_pk_bf16_f32 v2, v2, v3
	v_cvt_pk_bf16_f32 v3, v4, v5
	s_nop 0
	v_cvt_pk_bf16_f32 v4, v10, v11
	v_cvt_pk_bf16_f32 v5, v8, v9
	global_store_dwordx4 v[6:7], v[2:5], off
	s_cbranch_vccnz .LBB0_1232
	v_readlane_b32 s0, v254, 36
	v_readlane_b32 s1, v254, 37
	s_andn2_b64 vcc, exec, s[0:1]
	s_cbranch_vccnz .LBB0_1231
	s_branch .LBB0_1231

;     __device__ __forceinline__ bool next(int i, Unit& u) const {
;         const long L = (long)i * G + c; if (L >= total) return false;
;         if (nM1 == 144 && nN1 == 8 && nM2 == 0 && G == 256) {
;             const int xcd = c & 7, o = c >> 3;
;             const int grp = (i < 4) ? xcd * 4 + i : 32 + (xcd >> 1), idx = (i < 4) ? o : (xcd & 1) * 16 + o;
;             u.pm = grp * 4 + (idx & 3); u.pn = idx >> 2; return true; }
;         int w = (int)L; { const int q = total / NXCD, r = total % NXCD, xcd = w % NXCD, off = w / NXCD; w = (xcd < r ? xcd * (q + 1) : r * (q + 1) + (xcd - r) * q) + off; }
;         int nM = nM1, nN = nN1; const bool second = w >= n1; if (second) { w -= n1; nM = nM2; nN = nN2; }
;         const int wgm = 4;
;         const int nig = wgm * nN, gid = w / nig, fm = gid * wgm, gsz = (nM - fm) < wgm ? (nM - fm) : wgm;
;         int pm = fm + ((w % nig) % gsz), pn = (w % nig) / gsz;
;         if (second) { pm += pm2; pn = pn < split ? a0 + pn : a1 + pn; }
;         u.pm = pm; u.pn = pn; return true;
; template <class Epi, class Sched, bool ALIGN_EPI = false, bool SP2 = false, bool ABLK = false, bool BBLK = false>
; __device__ __forceinline__ void gemm_phase(PG8_LAS unsigned char* lds, const Gemm g, const Sched& S, const Epi& E) {
;     ...
;     const int tid = tid_, wid = __builtin_amdgcn_readfirstlane(tid >> 6), lane = tid & 63, wr = wid >> 2, wc = wid & 3, fr = lane & 15, fq = lane >> 4;
;     const int K = g.K, nt = K / BK, LDA = g.lda ? g.lda : K, LDB = g.ldb ? g.ldb : K;
;     unsigned voffA[2], voffB[2];
; #pragma unroll
;     for (int i = 0; i < 2; ++i) { int R, C; stage_rc(tid * 16 + i * 8192, R, C); const int Rb = Epi::PERM ? ((R & ~31) + perm32(R & 31)) : R;
;         voffA[i] = ABLK ? (unsigned)(R * BK + C) * 2u : (unsigned)(R * LDA + C) * 2u; voffB[i] = BBLK ? (unsigned)(Rb * BK + C) * 2u : (unsigned)(Rb * LDB + C) * 2u; }
;     const size_t kstep = (size_t)(BK * 2);
;     const size_t hstepa = (size_t)HALF * LDA * 2, hstepb = (size_t)HALF * LDB * 2;
;     const size_t kstepA = ABLK ? (size_t)BM * BK * 2 : kstep, hstepA = ABLK ? (size_t)HALF * BK * 2 : hstepa, tstepA = ABLK ? (size_t)nt * BM * BK * 2 : 2 * hstepa;
;     const size_t kstepB = BBLK ? (size_t)BM * BK * 2 : kstep, hstepB = BBLK ? (size_t)HALF * BK * 2 : hstepb, tstepB = BBLK ? (size_t)nt * BM * BK * 2 : 2 * hstepb;
;     const unsigned ldsw = (unsigned)wid * 1024u;
.LBB0_1331:
	s_or_b64 exec, exec, s[0:1]
	v_readlane_b32 s0, v254, 32
	s_mul_i32 s2, s0, 44
	s_waitcnt lgkmcnt(0)
	v_mov_b32_e32 v2, v0
	v_readlane_b32 s33, v254, 4
	v_readlane_b32 s0, v254, 6
	s_barrier
	v_readlane_b32 s36, v254, 5
	s_mov_b32 s0, s17
	v_mov_b32_e32 v3, v0
	s_cmp_lt_i32 s36, s2
	v_readfirstlane_b32 s6, v3
	s_cbranch_scc0 .LBB0_1347
	v_lshlrev_b32_e32 v6, 4, v3
	v_add_u32_e32 v4, 0x2000, v6
	v_ashrrev_i32_e32 v2, 31, v4
	v_lshrrev_b32_e32 v2, 22, v2
	v_add_u32_e32 v2, v4, v2
	v_ashrrev_i32_e32 v2, 10, v2
	v_mul_i32_i24_e32 v5, 0x400, v2
	v_sub_u32_e32 v4, v4, v5
	v_lshrrev_b32_e32 v5, 4, v4
	v_bitop3_b32 v5, v5, v4, 32 bitop3:0x6c
	v_ashrrev_i32_e32 v4, 31, v5
	v_lshrrev_b32_e32 v4, 26, v4
	v_add_u32_e32 v7, v5, v4
	v_lshlrev_b32_e32 v8, 3, v2
	v_ashrrev_i32_e32 v4, 6, v7
	v_and_b32_e32 v8, -16, v8
	s_lshr_b32 s37, s2, 3
	s_ashr_i32 s1, s0, 31
	v_readlane_b32 s4, v254, 7
	v_add_u32_e32 v8, v4, v8
	s_add_u32 s8, s4, s0
	v_and_b32_e32 v9, 3, v4
	s_mov_b32 s0, 0x1ffffe0
	v_lshrrev_b32_e32 v10, 2, v8
	v_lshlrev_b32_e32 v11, 1, v8
	v_and_b32_e32 v7, 0xc0, v7
	v_and_or_b32 v9, v8, s0, v9
	v_and_b32_e32 v10, 4, v10
	v_and_b32_e32 v11, 24, v11
	v_sub_u32_e32 v5, v5, v7
	v_or3_b32 v9, v9, v10, v11
	v_lshlrev_b32_e32 v10, 5, v2
	v_ashrrev_i16_sdwa v5, v232, sext(v5) dst_sel:DWORD dst_unused:UNUSED_PAD src0_sel:DWORD src1_sel:BYTE_0
	v_and_b32_e32 v10, 32, v10
	v_bfe_i32 v5, v5, 0, 16
	v_add_lshl_u32 v7, v10, v5, 1
	v_lshl_add_u32 v130, v9, 7, v7
	v_lshl_add_u32 v132, v8, 7, v7
	v_bfe_i32 v7, v3, 27, 1
	v_lshrrev_b32_e32 v7, 22, v7
	v_add_u32_e32 v7, v6, v7
	v_and_b32_e32 v7, 0xfffffc00, v7
	v_sub_u32_e32 v6, v6, v7
	v_lshrrev_b32_e32 v7, 4, v6
	v_bitop3_b32 v8, v7, v6, 32 bitop3:0x6c
	v_ashrrev_i32_e32 v7, 31, v3
	v_readlane_b32 s5, v254, 8
	v_lshrrev_b32_e32 v7, 26, v7
	s_addc_u32 s9, s5, s1
	v_ashrrev_i32_e32 v6, 31, v8
	v_add_u32_e32 v7, v3, v7
	s_add_u32 s40, s8, 0xf600000
	v_lshrrev_b32_e32 v6, 26, v6
	v_ashrrev_i32_e32 v7, 6, v7
	s_addc_u32 s41, s9, 0
	v_add_u32_e32 v9, v8, v6
	v_lshlrev_b32_e32 v10, 3, v7
	s_add_u32 s42, s8, 0xb100000
	v_ashrrev_i32_e32 v6, 6, v9
	v_and_b32_e32 v10, -16, v10
	s_addc_u32 s43, s9, 0
	v_add_u32_e32 v10, v6, v10
	v_and_b32_e32 v11, 3, v6
	s_ashr_i32 s45, s36, 31
	v_and_or_b32 v11, v10, s0, v11
	s_lshr_b32 s0, s45, 29
	s_add_i32 s0, s36, s0
	s_ashr_i32 s1, s0, 3
	s_and_b32 s0, s0, -8
	s_sub_i32 s0, s36, s0
	s_lshr_b32 s4, s0, 31
	s_or_b32 s4, s37, s4
	s_ashr_i32 s7, s6, 6
	s_mul_i32 s0, s0, s4
	s_ashr_i32 s3, s6, 8
	s_lshl_b32 s44, s7, 10
	s_add_i32 s0, s0, s1
	s_cmp_lt_i32 s0, s2
	v_and_b32_e32 v9, 0xc0, v9
	s_cselect_b32 s1, 0xb0, 4
	v_sub_u32_e32 v8, v8, v9
	v_cvt_f32_ubyte0_e32 v9, s1
	v_rcp_iflag_f32_e32 v9, v9
	v_readlane_b32 s5, v254, 32
	s_cselect_b32 s4, 0, s2
	s_cselect_b32 s5, s5, 0
	v_mul_f32_e32 v9, 0x4f7ffffe, v9
	v_cvt_u32_f32_e32 v9, v9
	s_sub_i32 s13, 0, s1
	s_sub_i32 s0, s0, s4
	s_abs_i32 s12, s0
	v_readfirstlane_b32 s14, v9
	s_mul_i32 s13, s13, s14
	s_mul_hi_u32 s13, s14, s13
	s_add_i32 s14, s14, s13
	s_mul_hi_u32 s13, s12, s14
	s_mul_i32 s14, s13, s1
	s_sub_i32 s12, s12, s14
	s_ashr_i32 s4, s0, 31
	s_add_i32 s14, s13, 1
	s_sub_i32 s15, s12, s1
	s_cmp_ge_u32 s12, s1
	s_cselect_b32 s13, s14, s13
	s_cselect_b32 s12, s15, s12
	s_add_i32 s14, s13, 1
	s_cmp_ge_u32 s12, s1
	s_cselect_b32 s12, s14, s13
	s_xor_b32 s12, s12, s4
	s_sub_i32 s4, s12, s4
	s_lshl_b32 s12, s4, 2
	s_sub_i32 s5, s5, s12
	s_min_i32 s5, s5, 4
	s_abs_i32 s13, s5
	v_cvt_f32_u32_e32 v9, s13
	s_sub_i32 s14, 0, s13
	s_mul_i32 s4, s4, s1
	s_sub_i32 s1, s0, s4
	v_rcp_iflag_f32_e32 v9, v9
	s_abs_i32 s4, s1
	s_xor_b32 s0, s1, s5
	s_ashr_i32 s0, s0, 31
	v_mul_f32_e32 v9, 0x4f7ffffe, v9
	v_cvt_u32_f32_e32 v9, v9
	v_lshrrev_b32_e32 v12, 2, v10
	v_lshlrev_b32_e32 v13, 1, v10
	v_and_b32_e32 v12, 4, v12
	v_readfirstlane_b32 s15, v9
	s_mul_i32 s14, s14, s15
	s_mul_hi_u32 s14, s15, s14
	s_add_i32 s15, s15, s14
	s_mul_hi_u32 s14, s4, s15
	s_mul_i32 s15, s14, s13
	s_sub_i32 s4, s4, s15
	s_add_i32 s15, s14, 1
	s_sub_i32 s16, s4, s13
	s_cmp_ge_u32 s4, s13
	s_cselect_b32 s14, s15, s14
	s_cselect_b32 s4, s16, s4
	s_add_i32 s15, s14, 1
	s_cmp_ge_u32 s4, s13
	s_cselect_b32 s4, s15, s14
	s_xor_b32 s4, s4, s0
	s_sub_i32 s0, s4, s0
	s_mul_i32 s4, s0, s5
	s_sub_i32 s1, s1, s4
	s_add_i32 s24, s1, s12
	v_and_b32_e32 v13, 24, v13
	s_ashr_i32 s25, s24, 31
	s_ashr_i32 s1, s0, 31
	v_or3_b32 v11, v11, v12, v13
	v_lshlrev_b32_e32 v12, 5, v7
	v_ashrrev_i16_sdwa v8, v232, sext(v8) dst_sel:DWORD dst_unused:UNUSED_PAD src0_sel:DWORD src1_sel:BYTE_0
	s_lshl_b64 s[4:5], s[24:25], 20
	s_lshl_b64 s[12:13], s[0:1], 20
	v_and_b32_e32 v12, 32, v12
	v_bfe_i32 v8, v8, 0, 16
	s_add_u32 s28, s42, s12
	v_add_lshl_u32 v12, v12, v8, 1
	s_addc_u32 s29, s43, s13
	s_add_i32 s25, s44, 0
	v_lshl_add_u32 v134, v11, 7, v12
	s_add_i32 m0, s25, 0x10000
	v_lshl_add_u32 v136, v10, 7, v12
	global_load_lds_dwordx4 v134, s[28:29]
	s_add_i32 m0, s25, 0x12000
	s_add_u32 s12, s28, 0x4000
	global_load_lds_dwordx4 v130, s[28:29]
	s_addc_u32 s13, s29, 0
	s_add_i32 m0, s25, 0x14000
	s_nop 0
	global_load_lds_dwordx4 v134, s[12:13]
	s_add_i32 m0, s25, 0x16000
	s_add_u32 s26, s40, s4
	s_addc_u32 s27, s41, s5
	s_add_i32 s46, s25, 0x2000
	global_load_lds_dwordx4 v130, s[12:13]
	s_mov_b32 m0, s25
	s_add_u32 s4, s26, 0x4000
	global_load_lds_dwordx4 v136, s[26:27]
	s_mov_b32 m0, s46
	s_addc_u32 s5, s27, 0
	s_add_i32 s47, s25, 0x4000
	global_load_lds_dwordx4 v132, s[26:27]
	s_mov_b32 m0, s47
	s_add_i32 s50, s25, 0x6000
	global_load_lds_dwordx4 v136, s[4:5]
	s_mov_b32 m0, s50
	s_cmp_eq_u32 s3, 1
	global_load_lds_dwordx4 v132, s[4:5]
	s_cselect_b64 s[4:5], -1, 0
	s_cmp_lg_u32 s3, 1
	s_cbranch_scc1 .LBB0_1334
; #define PG8_STAGE(bufoff, gbase, voff) do { _Pragma("unroll") for (int _i = 0; _i < 2; ++_i) \
;         __builtin_amdgcn_global_load_lds((const unsigned*)((const char*)(gbase) + (voff)[_i]), (PG8_LAS unsigned*)(lds + (bufoff) + ldsw + _i * 8192), 16, 0, 0); } while (0)
; #define PG8_WAIT_V(n) asm volatile("s_waitcnt vmcnt(" #n ")" ::: "memory")
; #define PG8_BAR __builtin_amdgcn_s_barrier()
; template <class Epi, class Sched, bool ALIGN_EPI = false, bool SP2 = false, bool ABLK = false, bool BBLK = false>
; __device__ __forceinline__ void gemm_phase(PG8_LAS unsigned char* lds, const Gemm g, const Sched& S, const Epi& E) {
;     ...
;     const int aoff = lds_byte(wr * 64 + fr, fq * 8), boff = lds_byte(wc * 32 + fr, fq * 8);
;     ...
;         if (wr == 1) PG8_BAR;
;         PG8_WAIT_V(2); PG8_BAR;
;         PG8_STAGE(PG8_SB(1, 0), cB + kstepB, voffB); PG8_STAGE(PG8_SA(1, 0), cA + kstepA, voffA); PG8_STAGE(PG8_SB(1, 1), cB + hstepB + kstepB, voffB);
;         PG8_WAIT_V(6); PG8_BAR;
.LBB0_1334:
	s_add_u32 s51, s8, 0x18600000
	s_addc_u32 s53, s9, 0
	s_and_b32 s1, s7, 3
	s_lshl_b32 s8, s3, 6
	s_lshl_b32 s9, s3, 13
	s_lshl_b32 s14, s7, 5
	s_lshl_b32 s1, s1, 12
	s_add_u32 s12, s28, 0x8000
	v_mov_b32_e32 v135, v187
	s_addc_u32 s13, s29, 0
	s_add_i32 m0, s25, 0x18000
	v_lshl_add_u64 v[10:11], s[12:13], 0, v[134:135]
	v_mov_b32_e32 v131, v187
	s_waitcnt vmcnt(2)
	s_barrier
	global_load_lds_dwordx4 v[10:11], off
	s_add_i32 m0, s25, 0x1a000
	v_lshl_add_u64 v[10:11], s[12:13], 0, v[130:131]
	s_add_u32 s12, s26, 0x8000
	v_mov_b32_e32 v137, v187
	s_addc_u32 s13, s27, 0
	s_add_i32 s56, s25, 0x8000
	v_mov_b32_e32 v133, v187
	global_load_lds_dwordx4 v[10:11], off
	v_lshl_add_u64 v[10:11], s[12:13], 0, v[136:137]
	s_mov_b32 m0, s56
	s_add_i32 s60, s25, 0xa000
	global_load_lds_dwordx4 v[10:11], off
	v_lshl_add_u64 v[10:11], s[12:13], 0, v[132:133]
	s_add_u32 s12, s28, 0xc000
	s_mov_b32 m0, s60
	s_addc_u32 s13, s29, 0
	global_load_lds_dwordx4 v[10:11], off
	s_add_i32 m0, s25, 0x1c000
	v_lshl_add_u64 v[10:11], s[12:13], 0, v[134:135]
	global_load_lds_dwordx4 v[10:11], off
	v_lshl_add_u64 v[10:11], s[12:13], 0, v[130:131]
	s_add_i32 m0, s25, 0x1e000
	v_lshrrev_b32_e32 v9, 1, v3
	global_load_lds_dwordx4 v[10:11], off
	v_and_b32_e32 v10, 24, v9
	v_and_b32_e32 v144, 15, v3
	v_lshlrev_b32_e32 v9, 1, v10
	v_lshlrev_b32_e32 v3, 2, v3
	v_lshl_or_b32 v9, v144, 6, v9
	v_and_b32_e32 v3, 32, v3
	v_bitop3_b32 v11, v9, s9, v3 bitop3:0xde
	v_bitop3_b32 v145, v9, s1, v3 bitop3:0xde
	v_lshlrev_b32_e32 v3, 10, v7
	v_and_b32_e32 v3, 0xfffff800, v3
	v_lshl_add_u32 v3, v6, 7, v3
	v_and_b32_e32 v6, 1, v7
	v_lshl_or_b32 v3, v6, 6, v3
	v_lshl_add_u32 v138, v8, 1, v3
	v_lshlrev_b32_e32 v3, 10, v2
	v_and_b32_e32 v3, 0xfffff800, v3
	s_waitcnt vmcnt(6)
	s_cmpk_lt_u32 s6, 0x100
	v_lshl_add_u32 v3, v4, 7, v3
	v_and_b32_e32 v2, 1, v2
	s_cselect_b64 s[12:13], -1, 0
	s_and_b32 s1, s14, 32
	v_lshl_or_b32 v2, v2, 6, v3
	s_mov_b32 s3, s17
	s_bfe_u32 s61, s7, 0x10001
	s_ashr_i32 s9, s8, 31
	s_ashr_i32 s65, s33, 31
	v_mov_b32_e32 v139, v187
	v_lshl_add_u32 v140, v5, 1, v2
	v_mov_b32_e32 v141, v187
	s_mov_b32 s68, 0
	v_add_u32_e32 v146, 0, v11
	s_lshl_b32 s16, s1, 1
	v_lshlrev_b32_e32 v186, 1, v10
	s_barrier
	s_branch .LBB0_1337

; #define PG8_STAGE(bufoff, gbase, voff) do { _Pragma("unroll") for (int _i = 0; _i < 2; ++_i) \
;         __builtin_amdgcn_global_load_lds((const unsigned*)((const char*)(gbase) + (voff)[_i]), (PG8_LAS unsigned*)(lds + (bufoff) + ldsw + _i * 8192), 16, 0, 0); } while (0)
; #define PG8_LDA(dst, b, h) do { _Pragma("unroll") for (int m = 0; m < 4; ++m) _Pragma("unroll") for (int k = 0; k < 2; ++k) dst[m][k] = *(const PG8_LAS bf16x8*)(lds + PG8_SA(b, h) + aoff + m * 2048 + k * 1024); } while (0)
; #define PG8_LDB(dst, b, h) do { _Pragma("unroll") for (int n = 0; n < 2; ++n) _Pragma("unroll") for (int k = 0; k < 2; ++k) dst[n][k] = *(const PG8_LAS bf16x8*)(lds + PG8_SB(b, h) + boff + n * 2048 + k * 1024); } while (0)
; #define PG8_WAIT_V(n) asm volatile("s_waitcnt vmcnt(" #n ")" ::: "memory")
; #define PG8_BAR __builtin_amdgcn_s_barrier()
; template <class Epi, class Sched, bool ALIGN_EPI = false, bool SP2 = false, bool ABLK = false, bool BBLK = false>
; __device__ __forceinline__ void gemm_phase(PG8_LAS unsigned char* lds, const Gemm g, const Sched& S, const Epi& E) {
;     ...
;         const bool has_next = S.next(ui + 1, nxt);
;         const char* nA = has_next ? (const char*)g.A + (size_t)nxt.pm * tstepA : cA; const char* nB = has_next ? (const char*)g.Bt + (size_t)nxt.pn * tstepB : cB;
;         for (int t = 0; t < nt; t += 2) {
;             const bool last = (t == nt - 2);
;             const char* a1 = cA + (size_t)(t + 1) * kstepA;
;             const char* a2 = last ? nA : cA + (size_t)(t + 2) * kstepA; const char* b2 = last ? nB : cB + (size_t)(t + 2) * kstepB;
;             const char* a3 = a2 + kstepA; const char* b3 = b2 + kstepB;
;             if (last && has_next) S.a_ready(nxt);
;             if constexpr (SP2) {
;             PG8_LDB(B0, 0, 0); PG8_LDB(B1, 0, 1); PG8_SCHED; PG8_LDA(At, 0, 0); PG8_STAGE(PG8_SA(1, 1), a1 + hstepA, voffA);
;             PG8_WAIT_V(8); PG8_WAIT_L(0); PG8_BAR; PG8_MMA(0, 0, At, B0); PG8_MMA(0, 1, At, B1); PG8_BAR; PG8_SCHED;
;     ...
; #pragma unroll
;         for (int a = 0; a < 2; ++a)
; #pragma unroll
;             for (int b = 0; b < 2; ++b)
; #pragma unroll
;                 for (int m = 0; m < 4; ++m)
; #pragma unroll
;                     for (int n = 0; n < 2; ++n) acc[a][b][m][n] = (f32x4){0.f, 0.f, 0.f, 0.f};
;         cur = nxt; cA = nA; cB = nB; ++ui;
;         if constexpr (ALIGN_EPI) { if (wr == 1) PG8_BAR; }
.LBB0_1339:
	s_ashr_i32 s19, s18, 31
	s_lshl_b64 s[20:21], s[18:19], 20
	s_add_u32 s20, s40, s20
	s_addc_u32 s21, s41, s21
	s_and_b64 s[22:23], s[6:7], exec
	s_cselect_b32 s1, s21, s27
	s_cselect_b32 s19, s20, s26
	s_ashr_i32 s15, s14, 31
	s_lshl_b64 s[22:23], s[14:15], 20
	s_add_u32 s22, s42, s22
	s_addc_u32 s23, s43, s23
	s_and_b64 s[30:31], s[6:7], exec
	s_cselect_b32 s15, s23, s29
	s_cselect_b32 s72, s22, s28
	s_add_u32 s26, s26, 0xc000
	s_addc_u32 s27, s27, 0
	s_add_u32 s73, s28, 0x10000
	v_mov_b32_e32 v2, 0
	s_addc_u32 s81, s29, 0
	s_mov_b32 s83, -2
	v_mov_b32_e32 v3, v2
	v_mov_b32_e32 v4, v2
	v_mov_b32_e32 v5, v2
	v_mov_b32_e32 v10, v2
	v_mov_b32_e32 v11, v2
	v_mov_b32_e32 v12, v2
	v_mov_b32_e32 v13, v2
	v_mov_b32_e32 v18, v2
	v_mov_b32_e32 v19, v2
	v_mov_b32_e32 v20, v2
	v_mov_b32_e32 v21, v2
	v_mov_b32_e32 v26, v2
	v_mov_b32_e32 v27, v2
	v_mov_b32_e32 v28, v2
	v_mov_b32_e32 v29, v2
	v_mov_b32_e32 v34, v2
	v_mov_b32_e32 v35, v2
	v_mov_b32_e32 v36, v2
	v_mov_b32_e32 v37, v2
	v_mov_b32_e32 v42, v2
	v_mov_b32_e32 v43, v2
	v_mov_b32_e32 v44, v2
	v_mov_b32_e32 v45, v2
	v_mov_b32_e32 v50, v2
	v_mov_b32_e32 v51, v2
	v_mov_b32_e32 v52, v2
	v_mov_b32_e32 v53, v2
	v_mov_b32_e32 v58, v2
	v_mov_b32_e32 v59, v2
	v_mov_b32_e32 v60, v2
	v_mov_b32_e32 v61, v2
	v_mov_b32_e32 v6, v2
	v_mov_b32_e32 v7, v2
	v_mov_b32_e32 v8, v2
	v_mov_b32_e32 v9, v2
	v_mov_b32_e32 v14, v2
	v_mov_b32_e32 v15, v2
	v_mov_b32_e32 v16, v2
	v_mov_b32_e32 v17, v2
	v_mov_b32_e32 v22, v2
	v_mov_b32_e32 v23, v2
	v_mov_b32_e32 v24, v2
	v_mov_b32_e32 v25, v2
	v_mov_b32_e32 v30, v2
	v_mov_b32_e32 v31, v2
	v_mov_b32_e32 v32, v2
	v_mov_b32_e32 v33, v2
	v_mov_b32_e32 v38, v2
	v_mov_b32_e32 v39, v2
	v_mov_b32_e32 v40, v2
	v_mov_b32_e32 v41, v2
	v_mov_b32_e32 v46, v2
	v_mov_b32_e32 v47, v2
	v_mov_b32_e32 v48, v2
	v_mov_b32_e32 v49, v2
	v_mov_b32_e32 v54, v2
	v_mov_b32_e32 v55, v2
	v_mov_b32_e32 v56, v2
	v_mov_b32_e32 v57, v2
	v_mov_b32_e32 v62, v2
	v_mov_b32_e32 v63, v2
	v_mov_b32_e32 v64, v2
	v_mov_b32_e32 v65, v2
	v_mov_b32_e32 v66, v2
	v_mov_b32_e32 v67, v2
	v_mov_b32_e32 v68, v2
	v_mov_b32_e32 v69, v2
	v_mov_b32_e32 v74, v2
	v_mov_b32_e32 v75, v2
	v_mov_b32_e32 v76, v2
	v_mov_b32_e32 v77, v2
	v_mov_b32_e32 v82, v2
	v_mov_b32_e32 v83, v2
	v_mov_b32_e32 v84, v2
	v_mov_b32_e32 v85, v2
	v_mov_b32_e32 v90, v2
	v_mov_b32_e32 v91, v2
	v_mov_b32_e32 v92, v2
	v_mov_b32_e32 v93, v2
	v_mov_b32_e32 v98, v2
	v_mov_b32_e32 v99, v2
	v_mov_b32_e32 v100, v2
	v_mov_b32_e32 v101, v2
	v_mov_b32_e32 v106, v2
	v_mov_b32_e32 v107, v2
	v_mov_b32_e32 v108, v2
	v_mov_b32_e32 v109, v2
	v_mov_b32_e32 v114, v2
	v_mov_b32_e32 v115, v2
	v_mov_b32_e32 v116, v2
	v_mov_b32_e32 v117, v2
	v_mov_b32_e32 v122, v2
	v_mov_b32_e32 v123, v2
	v_mov_b32_e32 v124, v2
	v_mov_b32_e32 v125, v2
	v_mov_b32_e32 v70, v2
	v_mov_b32_e32 v71, v2
	v_mov_b32_e32 v72, v2
	v_mov_b32_e32 v73, v2
	v_mov_b32_e32 v78, v2
	v_mov_b32_e32 v79, v2
	v_mov_b32_e32 v80, v2
	v_mov_b32_e32 v81, v2
	v_mov_b32_e32 v86, v2
	v_mov_b32_e32 v87, v2
	v_mov_b32_e32 v88, v2
	v_mov_b32_e32 v89, v2
	v_mov_b32_e32 v94, v2
	v_mov_b32_e32 v95, v2
	v_mov_b32_e32 v96, v2
	v_mov_b32_e32 v97, v2
	v_mov_b32_e32 v102, v2
	v_mov_b32_e32 v103, v2
	v_mov_b32_e32 v104, v2
	v_mov_b32_e32 v105, v2
	v_mov_b32_e32 v110, v2
	v_mov_b32_e32 v111, v2
	v_mov_b32_e32 v112, v2
	v_mov_b32_e32 v113, v2
	v_mov_b32_e32 v118, v2
	v_mov_b32_e32 v119, v2
	v_mov_b32_e32 v120, v2
	v_mov_b32_e32 v121, v2
	v_mov_b32_e32 v126, v2
	v_mov_b32_e32 v127, v2
	v_mov_b32_e32 v128, v2
	v_mov_b32_e32 v129, v2
	s_and_b64 vcc, exec, s[12:13]
	s_cbranch_vccnz .Lrb_f2a
	s_barrier
.Lrb_f2a:
.LBB0_1340:
	s_add_u32 s28, s26, 0x4000
	s_addc_u32 s29, s27, 0
	s_cmp_eq_u32 s83, 28
	s_cselect_b32 s34, s19, s28
	s_cselect_b32 s35, s1, s29
	s_cselect_b32 s30, s72, s73
	s_cselect_b32 s31, s15, s81
	s_add_u32 s28, s34, 0x8000
	s_addc_u32 s29, s35, 0
	s_add_i32 s52, 0, 0x10000
	v_add_u32_e32 v142, s52, v145
	s_add_i32 s75, 0, 0x14000
	ds_read_b128 v[148:151], v142
	ds_read_b128 v[152:155], v142 offset:1024
	ds_read_b128 v[156:159], v142 offset:2048
	ds_read_b128 v[160:163], v142 offset:3072
	v_add_u32_e32 v142, s75, v145
	ds_read_b128 v[164:167], v142
	ds_read_b128 v[168:171], v142 offset:1024
	ds_read_b128 v[172:175], v142 offset:2048
	ds_read_b128 v[176:179], v142 offset:3072
	v_lshl_add_u64 v[142:143], s[26:27], 0, v[138:139]
	s_add_i32 m0, s25, 0xc000
	ds_read_b128 v[180:183], v146
	ds_read_b128 v[196:199], v146 offset:1024
	ds_read_b128 v[200:203], v146 offset:2048
	ds_read_b128 v[204:207], v146 offset:3072
	ds_read_b128 v[208:211], v146 offset:4096
	ds_read_b128 v[212:215], v146 offset:5120
	ds_read_b128 v[216:219], v146 offset:6144
	ds_read_b128 v[220:223], v146 offset:7168
	global_load_lds_dwordx4 v[142:143], off
	v_lshl_add_u64 v[142:143], s[26:27], 0, v[140:141]
	s_add_i32 m0, s25, 0xe000
	s_nop 0
	global_load_lds_dwordx4 v[142:143], off
	s_waitcnt vmcnt(8)
	s_waitcnt lgkmcnt(0)
	s_barrier
; #define PG8_STAGE(bufoff, gbase, voff) do { _Pragma("unroll") for (int _i = 0; _i < 2; ++_i) \
;         __builtin_amdgcn_global_load_lds((const unsigned*)((const char*)(gbase) + (voff)[_i]), (PG8_LAS unsigned*)(lds + (bufoff) + ldsw + _i * 8192), 16, 0, 0); } while (0)
; #define PG8_LDA(dst, b, h) do { _Pragma("unroll") for (int m = 0; m < 4; ++m) _Pragma("unroll") for (int k = 0; k < 2; ++k) dst[m][k] = *(const PG8_LAS bf16x8*)(lds + PG8_SA(b, h) + aoff + m * 2048 + k * 1024); } while (0)
; #define PG8_LDB(dst, b, h) do { _Pragma("unroll") for (int n = 0; n < 2; ++n) _Pragma("unroll") for (int k = 0; k < 2; ++k) dst[n][k] = *(const PG8_LAS bf16x8*)(lds + PG8_SB(b, h) + boff + n * 2048 + k * 1024); } while (0)
; #define PG8_MMA(ai, bj, At, Bt) do { __builtin_amdgcn_s_setprio(1); _Pragma("unroll") for (int m = 0; m < 4; ++m) _Pragma("unroll") for (int n = 0; n < 2; ++n) _Pragma("unroll") for (int k = 0; k < 2; ++k) \
;         acc[ai][bj][m][n] = __builtin_amdgcn_mfma_f32_16x16x32_bf16(Bt[n][k], At[m][k], acc[ai][bj][m][n], 0, 0, 0); __builtin_amdgcn_s_setprio(0); } while (0)
; #define PG8_WAIT_V(n) asm volatile("s_waitcnt vmcnt(" #n ")" ::: "memory")
; #define PG8_WAIT_L(n) asm volatile("s_waitcnt lgkmcnt(" #n ")" ::: "memory")
; #define PG8_BAR __builtin_amdgcn_s_barrier()
; #define PG8_SCHED __builtin_amdgcn_sched_barrier(0)
; template <class Epi, class Sched, bool ALIGN_EPI = false, bool SP2 = false, bool ABLK = false, bool BBLK = false>
; __device__ __forceinline__ void gemm_phase(PG8_LAS unsigned char* lds, const Gemm g, const Sched& S, const Epi& E) {
;     ...
;             PG8_WAIT_V(8); PG8_WAIT_L(0); PG8_BAR; PG8_MMA(0, 0, At, B0); PG8_MMA(0, 1, At, B1); PG8_BAR; PG8_SCHED;
;             PG8_LDA(At, 0, 1); PG8_STAGE(PG8_SB(0, 0), b2, voffB); PG8_STAGE(PG8_SB(0, 1), b2 + hstepB, voffB); PG8_STAGE(PG8_SA(0, 0), a2, voffA);
;             PG8_WAIT_V(8); PG8_WAIT_L(0); PG8_BAR; PG8_MMA(1, 0, At, B0); PG8_MMA(1, 1, At, B1); PG8_BAR; PG8_SCHED;
;             PG8_LDB(B0, 1, 0); PG8_LDB(B1, 1, 1); PG8_SCHED; PG8_LDA(At, 1, 0); PG8_STAGE(PG8_SA(0, 1), a2 + hstepA, voffA);
;             PG8_WAIT_V(8); PG8_WAIT_L(0); PG8_BAR; PG8_MMA(0, 0, At, B0); PG8_MMA(0, 1, At, B1); PG8_BAR; PG8_SCHED;
	s_setprio 1
	s_waitcnt lgkmcnt(0)
	v_mfma_f32_16x16x32_bf16 v[126:129], v[148:151], v[180:183], v[126:129]
	v_mfma_f32_16x16x32_bf16 v[118:121], v[156:159], v[180:183], v[118:121]
	v_mfma_f32_16x16x32_bf16 v[110:113], v[148:151], v[200:203], v[110:113]
	v_mfma_f32_16x16x32_bf16 v[102:105], v[156:159], v[200:203], v[102:105]
	v_mfma_f32_16x16x32_bf16 v[94:97], v[148:151], v[208:211], v[94:97]
	v_mfma_f32_16x16x32_bf16 v[86:89], v[156:159], v[208:211], v[86:89]
	v_mfma_f32_16x16x32_bf16 v[78:81], v[148:151], v[216:219], v[78:81]
	v_mfma_f32_16x16x32_bf16 v[70:73], v[156:159], v[216:219], v[70:73]
	v_mfma_f32_16x16x32_bf16 v[126:129], v[152:155], v[196:199], v[126:129]
	v_mfma_f32_16x16x32_bf16 v[118:121], v[160:163], v[196:199], v[118:121]
	v_mfma_f32_16x16x32_bf16 v[110:113], v[152:155], v[204:207], v[110:113]
	v_mfma_f32_16x16x32_bf16 v[102:105], v[160:163], v[204:207], v[102:105]
	v_mfma_f32_16x16x32_bf16 v[94:97], v[152:155], v[212:215], v[94:97]
	v_mfma_f32_16x16x32_bf16 v[86:89], v[160:163], v[212:215], v[86:89]
	v_mfma_f32_16x16x32_bf16 v[78:81], v[152:155], v[220:223], v[78:81]
	v_mfma_f32_16x16x32_bf16 v[70:73], v[160:163], v[220:223], v[70:73]
	s_setprio 0
	s_setprio 1
	v_mfma_f32_16x16x32_bf16 v[122:125], v[164:167], v[180:183], v[122:125]
	v_mfma_f32_16x16x32_bf16 v[114:117], v[172:175], v[180:183], v[114:117]
	v_mfma_f32_16x16x32_bf16 v[106:109], v[164:167], v[200:203], v[106:109]
	v_mfma_f32_16x16x32_bf16 v[98:101], v[172:175], v[200:203], v[98:101]
	v_mfma_f32_16x16x32_bf16 v[90:93], v[164:167], v[208:211], v[90:93]
	v_mfma_f32_16x16x32_bf16 v[82:85], v[172:175], v[208:211], v[82:85]
	v_mfma_f32_16x16x32_bf16 v[74:77], v[164:167], v[216:219], v[74:77]
	v_mfma_f32_16x16x32_bf16 v[66:69], v[172:175], v[216:219], v[66:69]
	v_mfma_f32_16x16x32_bf16 v[122:125], v[168:171], v[196:199], v[122:125]
	v_mfma_f32_16x16x32_bf16 v[114:117], v[176:179], v[196:199], v[114:117]
	v_mfma_f32_16x16x32_bf16 v[106:109], v[168:171], v[204:207], v[106:109]
	v_mfma_f32_16x16x32_bf16 v[98:101], v[176:179], v[204:207], v[98:101]
	v_mfma_f32_16x16x32_bf16 v[90:93], v[168:171], v[212:215], v[90:93]
	v_mfma_f32_16x16x32_bf16 v[82:85], v[176:179], v[212:215], v[82:85]
	v_mfma_f32_16x16x32_bf16 v[74:77], v[168:171], v[220:223], v[74:77]
	v_mfma_f32_16x16x32_bf16 v[66:69], v[176:179], v[220:223], v[66:69]
	s_setprio 0
	s_barrier
	s_add_i32 s52, s52, s44
	v_lshl_add_u64 v[142:143], s[30:31], 0, v[134:135]
	s_mov_b32 m0, s52
	ds_read_b128 v[180:183], v146 offset:16384
	ds_read_b128 v[196:199], v146 offset:17408
	ds_read_b128 v[200:203], v146 offset:18432
	ds_read_b128 v[204:207], v146 offset:19456
	ds_read_b128 v[208:211], v146 offset:20480
	ds_read_b128 v[212:215], v146 offset:21504
	ds_read_b128 v[216:219], v146 offset:22528
	ds_read_b128 v[220:223], v146 offset:23552
	global_load_lds_dwordx4 v[142:143], off
	s_add_i32 m0, s52, 0x2000
	s_add_u32 s88, s30, 0x4000
	v_lshl_add_u64 v[142:143], s[30:31], 0, v[130:131]
	s_addc_u32 s89, s31, 0
	s_add_i32 s52, s75, s44
	global_load_lds_dwordx4 v[142:143], off
	v_lshl_add_u64 v[142:143], s[88:89], 0, v[134:135]
	s_mov_b32 m0, s52
	s_nop 0
	global_load_lds_dwordx4 v[142:143], off
	v_lshl_add_u64 v[142:143], s[88:89], 0, v[130:131]
	s_add_i32 m0, s52, 0x2000
	s_nop 0
	global_load_lds_dwordx4 v[142:143], off
	v_lshl_add_u64 v[142:143], s[34:35], 0, v[136:137]
	s_mov_b32 m0, s25
	s_nop 0
	global_load_lds_dwordx4 v[142:143], off
	v_lshl_add_u64 v[142:143], s[34:35], 0, v[132:133]
	s_mov_b32 m0, s46
	s_nop 0
	global_load_lds_dwordx4 v[142:143], off
	s_waitcnt vmcnt(8)
	s_waitcnt lgkmcnt(0)
	s_barrier
	s_setprio 1
	s_waitcnt lgkmcnt(0)
	v_mfma_f32_16x16x32_bf16 v[62:65], v[148:151], v[180:183], v[62:65]
	v_mfma_f32_16x16x32_bf16 v[54:57], v[156:159], v[180:183], v[54:57]
	v_mfma_f32_16x16x32_bf16 v[46:49], v[148:151], v[200:203], v[46:49]
	v_mfma_f32_16x16x32_bf16 v[38:41], v[156:159], v[200:203], v[38:41]
	v_mfma_f32_16x16x32_bf16 v[30:33], v[148:151], v[208:211], v[30:33]
	v_mfma_f32_16x16x32_bf16 v[22:25], v[156:159], v[208:211], v[22:25]
	v_mfma_f32_16x16x32_bf16 v[14:17], v[148:151], v[216:219], v[14:17]
	v_mfma_f32_16x16x32_bf16 v[6:9], v[156:159], v[216:219], v[6:9]
	v_mfma_f32_16x16x32_bf16 v[62:65], v[152:155], v[196:199], v[62:65]
	v_mfma_f32_16x16x32_bf16 v[54:57], v[160:163], v[196:199], v[54:57]
	v_mfma_f32_16x16x32_bf16 v[46:49], v[152:155], v[204:207], v[46:49]
	v_mfma_f32_16x16x32_bf16 v[38:41], v[160:163], v[204:207], v[38:41]
	v_mfma_f32_16x16x32_bf16 v[30:33], v[152:155], v[212:215], v[30:33]
	v_mfma_f32_16x16x32_bf16 v[22:25], v[160:163], v[212:215], v[22:25]
	v_mfma_f32_16x16x32_bf16 v[14:17], v[152:155], v[220:223], v[14:17]
	v_mfma_f32_16x16x32_bf16 v[6:9], v[160:163], v[220:223], v[6:9]
	s_setprio 0
	s_setprio 1
	v_mfma_f32_16x16x32_bf16 v[58:61], v[164:167], v[180:183], v[58:61]
	v_mfma_f32_16x16x32_bf16 v[50:53], v[172:175], v[180:183], v[50:53]
	v_mfma_f32_16x16x32_bf16 v[42:45], v[164:167], v[200:203], v[42:45]
	v_mfma_f32_16x16x32_bf16 v[34:37], v[172:175], v[200:203], v[34:37]
	v_mfma_f32_16x16x32_bf16 v[26:29], v[164:167], v[208:211], v[26:29]
	v_mfma_f32_16x16x32_bf16 v[18:21], v[172:175], v[208:211], v[18:21]
	v_mfma_f32_16x16x32_bf16 v[10:13], v[164:167], v[216:219], v[10:13]
	v_mfma_f32_16x16x32_bf16 v[2:5], v[172:175], v[216:219], v[2:5]
	v_mfma_f32_16x16x32_bf16 v[58:61], v[168:171], v[196:199], v[58:61]
	v_mfma_f32_16x16x32_bf16 v[50:53], v[176:179], v[196:199], v[50:53]
	v_mfma_f32_16x16x32_bf16 v[42:45], v[168:171], v[204:207], v[42:45]
	v_mfma_f32_16x16x32_bf16 v[34:37], v[176:179], v[204:207], v[34:37]
	v_mfma_f32_16x16x32_bf16 v[26:29], v[168:171], v[212:215], v[26:29]
	v_mfma_f32_16x16x32_bf16 v[18:21], v[176:179], v[212:215], v[18:21]
	v_mfma_f32_16x16x32_bf16 v[10:13], v[168:171], v[220:223], v[10:13]
	v_mfma_f32_16x16x32_bf16 v[2:5], v[176:179], v[220:223], v[2:5]
	s_setprio 0
	s_barrier
; #define PG8_STAGE(bufoff, gbase, voff) do { _Pragma("unroll") for (int _i = 0; _i < 2; ++_i) \
;         __builtin_amdgcn_global_load_lds((const unsigned*)((const char*)(gbase) + (voff)[_i]), (PG8_LAS unsigned*)(lds + (bufoff) + ldsw + _i * 8192), 16, 0, 0); } while (0)
; #define PG8_LDA(dst, b, h) do { _Pragma("unroll") for (int m = 0; m < 4; ++m) _Pragma("unroll") for (int k = 0; k < 2; ++k) dst[m][k] = *(const PG8_LAS bf16x8*)(lds + PG8_SA(b, h) + aoff + m * 2048 + k * 1024); } while (0)
; #define PG8_LDB(dst, b, h) do { _Pragma("unroll") for (int n = 0; n < 2; ++n) _Pragma("unroll") for (int k = 0; k < 2; ++k) dst[n][k] = *(const PG8_LAS bf16x8*)(lds + PG8_SB(b, h) + boff + n * 2048 + k * 1024); } while (0)
; #define PG8_MMA(ai, bj, At, Bt) do { __builtin_amdgcn_s_setprio(1); _Pragma("unroll") for (int m = 0; m < 4; ++m) _Pragma("unroll") for (int n = 0; n < 2; ++n) _Pragma("unroll") for (int k = 0; k < 2; ++k) \
;         acc[ai][bj][m][n] = __builtin_amdgcn_mfma_f32_16x16x32_bf16(Bt[n][k], At[m][k], acc[ai][bj][m][n], 0, 0, 0); __builtin_amdgcn_s_setprio(0); } while (0)
; #define PG8_WAIT_V(n) asm volatile("s_waitcnt vmcnt(" #n ")" ::: "memory")
; #define PG8_WAIT_L(n) asm volatile("s_waitcnt lgkmcnt(" #n ")" ::: "memory")
; #define PG8_BAR __builtin_amdgcn_s_barrier()
; #define PG8_SCHED __builtin_amdgcn_sched_barrier(0)
; template <class Epi, class Sched, bool ALIGN_EPI = false, bool SP2 = false, bool ABLK = false, bool BBLK = false>
; __device__ __forceinline__ void gemm_phase(PG8_LAS unsigned char* lds, const Gemm g, const Sched& S, const Epi& E) {
;     ...
;             PG8_LDB(B0, 1, 0); PG8_LDB(B1, 1, 1); PG8_SCHED; PG8_LDA(At, 1, 0); PG8_STAGE(PG8_SA(0, 1), a2 + hstepA, voffA);
;             PG8_WAIT_V(8); PG8_WAIT_L(0); PG8_BAR; PG8_MMA(0, 0, At, B0); PG8_MMA(0, 1, At, B1); PG8_BAR; PG8_SCHED;
;             PG8_LDA(At, 1, 1); PG8_STAGE(PG8_SB(1, 0), b3, voffB); PG8_STAGE(PG8_SB(1, 1), b3 + hstepB, voffB); PG8_STAGE(PG8_SA(1, 0), a3, voffA);
;             PG8_WAIT_V(8); PG8_WAIT_L(0); PG8_BAR; PG8_MMA(1, 0, At, B0); PG8_MMA(1, 1, At, B1); PG8_BAR; PG8_SCHED;
	s_add_i32 s52, 0, 0x18000
	v_add_u32_e32 v142, s52, v145
	s_add_i32 s75, 0, 0x1c000
	ds_read_b128 v[148:151], v142
	ds_read_b128 v[152:155], v142 offset:1024
	ds_read_b128 v[156:159], v142 offset:2048
	ds_read_b128 v[160:163], v142 offset:3072
	v_add_u32_e32 v142, s75, v145
	ds_read_b128 v[164:167], v142
	ds_read_b128 v[168:171], v142 offset:1024
	ds_read_b128 v[172:175], v142 offset:2048
	ds_read_b128 v[176:179], v142 offset:3072
	s_add_u32 s34, s34, 0x4000
	s_addc_u32 s35, s35, 0
	s_mov_b32 m0, s47
	v_lshl_add_u64 v[142:143], s[34:35], 0, v[136:137]
	ds_read_b128 v[180:183], v146 offset:32768
	ds_read_b128 v[196:199], v146 offset:33792
	ds_read_b128 v[200:203], v146 offset:34816
	ds_read_b128 v[204:207], v146 offset:35840
	ds_read_b128 v[208:211], v146 offset:36864
	ds_read_b128 v[212:215], v146 offset:37888
	ds_read_b128 v[216:219], v146 offset:38912
	ds_read_b128 v[220:223], v146 offset:39936
	global_load_lds_dwordx4 v[142:143], off
	v_lshl_add_u64 v[142:143], s[34:35], 0, v[132:133]
	s_mov_b32 m0, s50
	s_nop 0
	global_load_lds_dwordx4 v[142:143], off
	s_waitcnt vmcnt(8)
	s_waitcnt lgkmcnt(0)
	s_barrier
	s_setprio 1
	s_waitcnt lgkmcnt(0)
	v_mfma_f32_16x16x32_bf16 v[126:129], v[148:151], v[180:183], v[126:129]
	v_mfma_f32_16x16x32_bf16 v[118:121], v[156:159], v[180:183], v[118:121]
	v_mfma_f32_16x16x32_bf16 v[110:113], v[148:151], v[200:203], v[110:113]
	v_mfma_f32_16x16x32_bf16 v[102:105], v[156:159], v[200:203], v[102:105]
	v_mfma_f32_16x16x32_bf16 v[94:97], v[148:151], v[208:211], v[94:97]
	v_mfma_f32_16x16x32_bf16 v[86:89], v[156:159], v[208:211], v[86:89]
	v_mfma_f32_16x16x32_bf16 v[78:81], v[148:151], v[216:219], v[78:81]
	v_mfma_f32_16x16x32_bf16 v[70:73], v[156:159], v[216:219], v[70:73]
	v_mfma_f32_16x16x32_bf16 v[126:129], v[152:155], v[196:199], v[126:129]
	v_mfma_f32_16x16x32_bf16 v[118:121], v[160:163], v[196:199], v[118:121]
	v_mfma_f32_16x16x32_bf16 v[110:113], v[152:155], v[204:207], v[110:113]
	v_mfma_f32_16x16x32_bf16 v[102:105], v[160:163], v[204:207], v[102:105]
	v_mfma_f32_16x16x32_bf16 v[94:97], v[152:155], v[212:215], v[94:97]
	v_mfma_f32_16x16x32_bf16 v[86:89], v[160:163], v[212:215], v[86:89]
	v_mfma_f32_16x16x32_bf16 v[78:81], v[152:155], v[220:223], v[78:81]
	v_mfma_f32_16x16x32_bf16 v[70:73], v[160:163], v[220:223], v[70:73]
	s_setprio 0
	s_setprio 1
	v_mfma_f32_16x16x32_bf16 v[122:125], v[164:167], v[180:183], v[122:125]
	v_mfma_f32_16x16x32_bf16 v[114:117], v[172:175], v[180:183], v[114:117]
	v_mfma_f32_16x16x32_bf16 v[106:109], v[164:167], v[200:203], v[106:109]
	v_mfma_f32_16x16x32_bf16 v[98:101], v[172:175], v[200:203], v[98:101]
	v_mfma_f32_16x16x32_bf16 v[90:93], v[164:167], v[208:211], v[90:93]
	v_mfma_f32_16x16x32_bf16 v[82:85], v[172:175], v[208:211], v[82:85]
	v_mfma_f32_16x16x32_bf16 v[74:77], v[164:167], v[216:219], v[74:77]
	v_mfma_f32_16x16x32_bf16 v[66:69], v[172:175], v[216:219], v[66:69]
	v_mfma_f32_16x16x32_bf16 v[122:125], v[168:171], v[196:199], v[122:125]
	v_mfma_f32_16x16x32_bf16 v[114:117], v[176:179], v[196:199], v[114:117]
	v_mfma_f32_16x16x32_bf16 v[106:109], v[168:171], v[204:207], v[106:109]
	v_mfma_f32_16x16x32_bf16 v[98:101], v[176:179], v[204:207], v[98:101]
	v_mfma_f32_16x16x32_bf16 v[90:93], v[168:171], v[212:215], v[90:93]
	v_mfma_f32_16x16x32_bf16 v[82:85], v[176:179], v[212:215], v[82:85]
	v_mfma_f32_16x16x32_bf16 v[74:77], v[168:171], v[220:223], v[74:77]
	v_mfma_f32_16x16x32_bf16 v[66:69], v[176:179], v[220:223], v[66:69]
	s_setprio 0
	s_barrier
	s_add_u32 s34, s30, 0x8000
	s_addc_u32 s35, s31, 0
	s_add_i32 s52, s52, s44
	v_lshl_add_u64 v[142:143], s[34:35], 0, v[134:135]
	s_mov_b32 m0, s52
	ds_read_b128 v[180:183], v146 offset:49152
	ds_read_b128 v[196:199], v146 offset:50176
	ds_read_b128 v[200:203], v146 offset:51200
	ds_read_b128 v[204:207], v146 offset:52224
	ds_read_b128 v[208:211], v146 offset:53248
	ds_read_b128 v[212:215], v146 offset:54272
	ds_read_b128 v[216:219], v146 offset:55296
	ds_read_b128 v[220:223], v146 offset:56320
	global_load_lds_dwordx4 v[142:143], off
	s_add_i32 m0, s52, 0x2000
	s_add_u32 s30, s30, 0xc000
	v_lshl_add_u64 v[142:143], s[34:35], 0, v[130:131]
	s_addc_u32 s31, s31, 0
	s_add_i32 s34, s75, s44
	global_load_lds_dwordx4 v[142:143], off
	v_lshl_add_u64 v[142:143], s[30:31], 0, v[134:135]
	s_mov_b32 m0, s34
	s_nop 0
	global_load_lds_dwordx4 v[142:143], off
	v_lshl_add_u64 v[142:143], s[30:31], 0, v[130:131]
	s_add_i32 m0, s34, 0x2000
	s_nop 0
	global_load_lds_dwordx4 v[142:143], off
	v_lshl_add_u64 v[142:143], s[28:29], 0, v[136:137]
	s_mov_b32 m0, s56
	s_nop 0
	global_load_lds_dwordx4 v[142:143], off
	v_lshl_add_u64 v[142:143], s[28:29], 0, v[132:133]
	s_mov_b32 m0, s60
	s_nop 0
	global_load_lds_dwordx4 v[142:143], off
	s_waitcnt vmcnt(8)
	s_waitcnt lgkmcnt(0)
	s_barrier
;     __device__ __forceinline__ void operator()(const f32x4 (&acc)[2][2][4][2], const Unit& u, int wr, int wc, int fr_, int fq) const {
;     ...
;         bf16_t* Hblk = H + ((size_t)(u.pm * (ldh / BK) + 2 * u.pn + (wc >> 1)) * BM + wr * 64 + fr) * BK + (wc & 1) * 32 + 8 * fq;
; #pragma unroll
;         for (int ai = 0; ai < 2; ++ai)
; #pragma unroll
;             for (int m = 0; m < 4; ++m) {
;                 f32x4 v0, v1;
; #pragma unroll
;                 for (int j = 0; j < 4; ++j) { const float g0 = acc[ai][0][m][0][j], g1 = acc[ai][0][m][1][j];
;                     v0[j] = g0 * fast_sigmoid(g0) * acc[ai][1][m][0][j]; v1[j] = g1 * fast_sigmoid(g1) * acc[ai][1][m][1][j]; }
; template <class Epi, class Sched, bool ALIGN_EPI = false, bool SP2 = false, bool ABLK = false, bool BBLK = false>
; __device__ __forceinline__ void gemm_phase(PG8_LAS unsigned char* lds, const Gemm g, const Sched& S, const Epi& E) {
;     ...
;             PG8_WAIT_V(8); PG8_WAIT_L(0); PG8_BAR; PG8_MMA(1, 0, At, B0); PG8_MMA(1, 1, At, B1); PG8_BAR; PG8_SCHED;
;             } else {
;             PG8_LDB(B0, 0, 0); PG8_SCHED; PG8_LDA(At, 0, 0); PG8_STAGE(PG8_SA(1, 1), a1 + hstepA, voffA);
;             PG8_WAIT_L(8); PG8_BAR; PG8_WAIT_L(0); PG8_MMA(0, 0, At, B0); PG8_BAR; PG8_SCHED;
;             PG8_LDB(B1, 0, 1); PG8_STAGE(PG8_SB(0, 0), b2, voffB);
;             PG8_BAR; PG8_WAIT_L(0); PG8_MMA(0, 1, At, B1); PG8_BAR;
;             PG8_LDA(At, 0, 1); PG8_STAGE(PG8_SA(0, 0), a2, voffA);
;             PG8_BAR; PG8_WAIT_L(0); PG8_MMA(1, 0, At, B0); PG8_BAR; PG8_SCHED;
;             PG8_STAGE(PG8_SB(0, 1), b2 + hstepB, voffB);
;             PG8_WAIT_V(6); PG8_BAR; PG8_MMA(1, 1, At, B1); PG8_BAR;
;             PG8_LDB(B0, 1, 0); PG8_SCHED; PG8_LDA(At, 1, 0); PG8_STAGE(PG8_SA(0, 1), a2 + hstepA, voffA);
;             PG8_WAIT_L(8); PG8_BAR; PG8_WAIT_L(0); PG8_MMA(0, 0, At, B0); PG8_BAR; PG8_SCHED;
;             PG8_LDB(B1, 1, 1); PG8_STAGE(PG8_SB(1, 0), b3, voffB);
;             PG8_BAR; PG8_WAIT_L(0); PG8_MMA(0, 1, At, B1); PG8_BAR;
;             PG8_LDA(At, 1, 1); PG8_STAGE(PG8_SA(1, 0), a3, voffA);
;             PG8_BAR; PG8_WAIT_L(0); PG8_MMA(1, 0, At, B0); PG8_BAR; PG8_SCHED;
;             PG8_STAGE(PG8_SB(1, 1), b3 + hstepB, voffB);
;             PG8_WAIT_V(6); PG8_BAR; PG8_MMA(1, 1, At, B1); PG8_BAR;
;             }
;         }
;         if constexpr (ALIGN_EPI) { if (wr == 0) PG8_BAR; }
	s_setprio 1
	s_waitcnt lgkmcnt(0)
	v_mfma_f32_16x16x32_bf16 v[62:65], v[148:151], v[180:183], v[62:65]
	v_mfma_f32_16x16x32_bf16 v[54:57], v[156:159], v[180:183], v[54:57]
	v_mfma_f32_16x16x32_bf16 v[46:49], v[148:151], v[200:203], v[46:49]
	v_mfma_f32_16x16x32_bf16 v[38:41], v[156:159], v[200:203], v[38:41]
	v_mfma_f32_16x16x32_bf16 v[30:33], v[148:151], v[208:211], v[30:33]
	v_mfma_f32_16x16x32_bf16 v[22:25], v[156:159], v[208:211], v[22:25]
	v_mfma_f32_16x16x32_bf16 v[14:17], v[148:151], v[216:219], v[14:17]
	v_mfma_f32_16x16x32_bf16 v[6:9], v[156:159], v[216:219], v[6:9]
	v_mfma_f32_16x16x32_bf16 v[62:65], v[152:155], v[196:199], v[62:65]
	v_mfma_f32_16x16x32_bf16 v[54:57], v[160:163], v[196:199], v[54:57]
	v_mfma_f32_16x16x32_bf16 v[46:49], v[152:155], v[204:207], v[46:49]
	v_mfma_f32_16x16x32_bf16 v[38:41], v[160:163], v[204:207], v[38:41]
	v_mfma_f32_16x16x32_bf16 v[30:33], v[152:155], v[212:215], v[30:33]
	v_mfma_f32_16x16x32_bf16 v[22:25], v[160:163], v[212:215], v[22:25]
	v_mfma_f32_16x16x32_bf16 v[14:17], v[152:155], v[220:223], v[14:17]
	v_mfma_f32_16x16x32_bf16 v[6:9], v[160:163], v[220:223], v[6:9]
	s_setprio 0
	s_setprio 1
	v_mfma_f32_16x16x32_bf16 v[58:61], v[164:167], v[180:183], v[58:61]
	v_mfma_f32_16x16x32_bf16 v[50:53], v[172:175], v[180:183], v[50:53]
	v_mfma_f32_16x16x32_bf16 v[42:45], v[164:167], v[200:203], v[42:45]
	v_mfma_f32_16x16x32_bf16 v[34:37], v[172:175], v[200:203], v[34:37]
	v_mfma_f32_16x16x32_bf16 v[26:29], v[164:167], v[208:211], v[26:29]
	v_mfma_f32_16x16x32_bf16 v[18:21], v[172:175], v[208:211], v[18:21]
	v_mfma_f32_16x16x32_bf16 v[10:13], v[164:167], v[216:219], v[10:13]
	v_mfma_f32_16x16x32_bf16 v[2:5], v[172:175], v[216:219], v[2:5]
	v_mfma_f32_16x16x32_bf16 v[58:61], v[168:171], v[196:199], v[58:61]
	v_mfma_f32_16x16x32_bf16 v[50:53], v[176:179], v[196:199], v[50:53]
	v_mfma_f32_16x16x32_bf16 v[42:45], v[168:171], v[204:207], v[42:45]
	v_mfma_f32_16x16x32_bf16 v[34:37], v[176:179], v[204:207], v[34:37]
	v_mfma_f32_16x16x32_bf16 v[26:29], v[168:171], v[212:215], v[26:29]
	v_mfma_f32_16x16x32_bf16 v[18:21], v[176:179], v[212:215], v[18:21]
	v_mfma_f32_16x16x32_bf16 v[10:13], v[168:171], v[220:223], v[10:13]
	v_mfma_f32_16x16x32_bf16 v[2:5], v[176:179], v[220:223], v[2:5]
	s_setprio 0
	s_barrier
	s_add_i32 s83, s83, 2
	s_add_u32 s26, s26, 0x10000
	s_addc_u32 s27, s27, 0
	s_add_u32 s73, s73, 0x10000
	s_addc_u32 s81, s81, 0
	s_cmp_gt_u32 s83, 29
	s_cbranch_scc0 .LBB0_1340
	s_and_b64 vcc, exec, s[12:13]
	s_cbranch_vccz .LBB0_1343
	s_barrier
.LBB0_1343:
	v_mov_b32_e32 v184, 0xbfb8aa3b
	v_mov_b32_e32 v185, 0xbfb8aa3b
	v_mov_b32_e32 v188, 1.0
	v_mov_b32_e32 v189, 1.0
	v_pk_mul_f32 v[190:191], v[126:127], v[184:185]
	v_pk_mul_f32 v[192:193], v[128:129], v[184:185]
	v_pk_mul_f32 v[224:225], v[118:119], v[184:185]
	v_pk_mul_f32 v[226:227], v[120:121], v[184:185]
	v_exp_f32_e32 v190, v190
	v_exp_f32_e32 v191, v191
	v_exp_f32_e32 v192, v192
	v_exp_f32_e32 v193, v193
	v_exp_f32_e32 v224, v224
	v_exp_f32_e32 v225, v225
	v_exp_f32_e32 v226, v226
	v_exp_f32_e32 v227, v227
	v_pk_add_f32 v[190:191], v[190:191], v[188:189]
	v_pk_add_f32 v[192:193], v[192:193], v[188:189]
	v_pk_add_f32 v[224:225], v[224:225], v[188:189]
	v_pk_add_f32 v[226:227], v[226:227], v[188:189]
	v_rcp_f32_e32 v190, v190
	v_rcp_f32_e32 v191, v191
	v_rcp_f32_e32 v192, v192
	v_rcp_f32_e32 v193, v193
	v_rcp_f32_e32 v224, v224
	v_rcp_f32_e32 v225, v225
	v_rcp_f32_e32 v226, v226
	v_rcp_f32_e32 v227, v227
	v_pk_mul_f32 v[126:127], v[126:127], v[190:191]
	v_pk_mul_f32 v[128:129], v[128:129], v[192:193]
	v_pk_mul_f32 v[118:119], v[118:119], v[224:225]
	v_pk_mul_f32 v[120:121], v[120:121], v[226:227]
	v_pk_mul_f32 v[126:127], v[126:127], v[122:123]
	v_pk_mul_f32 v[128:129], v[128:129], v[124:125]
	v_pk_mul_f32 v[118:119], v[118:119], v[114:115]
	v_pk_mul_f32 v[120:121], v[120:121], v[116:117]
	v_cvt_pk_bf16_f32 v114, v126, v127
	v_cvt_pk_bf16_f32 v115, v128, v129
	v_cvt_pk_bf16_f32 v116, v118, v119
	v_cvt_pk_bf16_f32 v117, v120, v121
	s_lshl_b32 s0, s0, 1
	s_mul_i32 s1, s24, 0x58
	s_or_b32 s0, s0, s61
	s_add_i32 s0, s0, s1
	v_mov_b32_e32 v142, v144
	s_ashr_i32 s1, s0, 31
	s_lshl_b64 s[0:1], s[0:1], 15
	v_ashrrev_i32_e32 v143, 31, v142
	v_lshl_add_u64 v[142:143], v[142:143], 0, s[8:9]
	s_add_u32 s0, s51, s0
	v_lshlrev_b64 v[142:143], 7, v[142:143]
	s_addc_u32 s1, s53, s1
	v_lshl_add_u64 v[142:143], s[0:1], 0, v[142:143]
	v_lshl_add_u64 v[142:143], v[142:143], 0, s[16:17]
	v_lshl_add_u64 v[142:143], v[142:143], 0, v[186:187]
	s_movk_i32 s0, 0x5000
	s_mov_b32 s88, 0xf800000
	s_movk_i32 s89, 0xffe0
	s_mov_b32 s52, 0x80000
	global_store_dwordx4 v[142:143], v[114:117], off
	v_pk_mul_f32 v[190:191], v[110:111], v[184:185]
	v_pk_mul_f32 v[192:193], v[112:113], v[184:185]
	v_pk_mul_f32 v[224:225], v[102:103], v[184:185]
	v_pk_mul_f32 v[226:227], v[104:105], v[184:185]
	v_exp_f32_e32 v190, v190
	v_exp_f32_e32 v191, v191
	v_exp_f32_e32 v192, v192
	v_exp_f32_e32 v193, v193
	v_exp_f32_e32 v224, v224
	v_exp_f32_e32 v225, v225
	v_exp_f32_e32 v226, v226
	v_exp_f32_e32 v227, v227
	v_pk_add_f32 v[190:191], v[190:191], v[188:189]
	v_pk_add_f32 v[192:193], v[192:193], v[188:189]
	v_pk_add_f32 v[224:225], v[224:225], v[188:189]
	v_pk_add_f32 v[226:227], v[226:227], v[188:189]
	v_rcp_f32_e32 v190, v190
	v_rcp_f32_e32 v191, v191
	v_rcp_f32_e32 v192, v192
	v_rcp_f32_e32 v193, v193
	v_rcp_f32_e32 v224, v224
	v_rcp_f32_e32 v225, v225
	v_rcp_f32_e32 v226, v226
	v_rcp_f32_e32 v227, v227
	v_pk_mul_f32 v[110:111], v[110:111], v[190:191]
	v_pk_mul_f32 v[112:113], v[112:113], v[192:193]
	v_pk_mul_f32 v[102:103], v[102:103], v[224:225]
	v_pk_mul_f32 v[104:105], v[104:105], v[226:227]
; __device__ __forceinline__ float fast_sigmoid(float x) { return __builtin_amdgcn_rcpf(1.0f + __builtin_amdgcn_exp2f(-1.4426950408889634f * x)); }
; __device__ __forceinline__ u32x4 pack8(const f32x4 v0, const f32x4 v1) { u32x4 w; w.x = cvt_pk_bf16(v0[0], v0[1]); w.y = cvt_pk_bf16(v0[2], v0[3]); w.z = cvt_pk_bf16(v1[0], v1[1]); w.w = cvt_pk_bf16(v1[2], v1[3]); return w; }
;     __device__ __forceinline__ void operator()(const f32x4 (&acc)[2][2][4][2], const Unit& u, int wr, int wc, int fr_, int fq) const {
;     ...
;                 for (int j = 0; j < 4; ++j) { const float g0 = acc[ai][0][m][0][j], g1 = acc[ai][0][m][1][j];
;                     v0[j] = g0 * fast_sigmoid(g0) * acc[ai][1][m][0][j]; v1[j] = g1 * fast_sigmoid(g1) * acc[ai][1][m][1][j]; }
;                 *(u32x4*)(Hblk + (size_t)(ai * HALF + m * 16) * BK) = pack8(v0, v1); }
	v_pk_mul_f32 v[110:111], v[110:111], v[106:107]
	v_pk_mul_f32 v[112:113], v[112:113], v[108:109]
	v_pk_mul_f32 v[102:103], v[102:103], v[98:99]
	v_pk_mul_f32 v[104:105], v[104:105], v[100:101]
	v_cvt_pk_bf16_f32 v98, v110, v111
	v_cvt_pk_bf16_f32 v99, v112, v113
	v_cvt_pk_bf16_f32 v100, v102, v103
	v_cvt_pk_bf16_f32 v101, v104, v105
	global_store_dwordx4 v[142:143], v[98:101], off offset:2048
	v_pk_mul_f32 v[190:191], v[94:95], v[184:185]
	v_pk_mul_f32 v[192:193], v[96:97], v[184:185]
	v_pk_mul_f32 v[224:225], v[86:87], v[184:185]
	v_pk_mul_f32 v[226:227], v[88:89], v[184:185]
	v_exp_f32_e32 v190, v190
	v_exp_f32_e32 v191, v191
	v_exp_f32_e32 v192, v192
	v_exp_f32_e32 v193, v193
	v_exp_f32_e32 v224, v224
	v_exp_f32_e32 v225, v225
	v_exp_f32_e32 v226, v226
	v_exp_f32_e32 v227, v227
	v_pk_add_f32 v[190:191], v[190:191], v[188:189]
	v_pk_add_f32 v[192:193], v[192:193], v[188:189]
	v_pk_add_f32 v[224:225], v[224:225], v[188:189]
	v_pk_add_f32 v[226:227], v[226:227], v[188:189]
	v_rcp_f32_e32 v190, v190
	v_rcp_f32_e32 v191, v191
	v_rcp_f32_e32 v192, v192
	v_rcp_f32_e32 v193, v193
	v_rcp_f32_e32 v224, v224
	v_rcp_f32_e32 v225, v225
	v_rcp_f32_e32 v226, v226
	v_rcp_f32_e32 v227, v227
	v_pk_mul_f32 v[94:95], v[94:95], v[190:191]
	v_pk_mul_f32 v[96:97], v[96:97], v[192:193]
	v_pk_mul_f32 v[86:87], v[86:87], v[224:225]
	v_pk_mul_f32 v[88:89], v[88:89], v[226:227]
	v_pk_mul_f32 v[94:95], v[94:95], v[90:91]
	v_pk_mul_f32 v[96:97], v[96:97], v[92:93]
	v_pk_mul_f32 v[86:87], v[86:87], v[82:83]
	v_pk_mul_f32 v[88:89], v[88:89], v[84:85]
	v_cvt_pk_bf16_f32 v82, v94, v95
	v_cvt_pk_bf16_f32 v83, v96, v97
	v_cvt_pk_bf16_f32 v84, v86, v87
	v_cvt_pk_bf16_f32 v85, v88, v89
	v_add_co_u32_e32 v86, vcc, s67, v142
	s_nop 1
	v_addc_co_u32_e32 v87, vcc, 0, v143, vcc
	global_store_dwordx4 v[86:87], v[82:85], off
	v_pk_mul_f32 v[190:191], v[78:79], v[184:185]
	v_pk_mul_f32 v[192:193], v[80:81], v[184:185]
	v_pk_mul_f32 v[224:225], v[70:71], v[184:185]
	v_pk_mul_f32 v[226:227], v[72:73], v[184:185]
	v_exp_f32_e32 v190, v190
	v_exp_f32_e32 v191, v191
	v_exp_f32_e32 v192, v192
	v_exp_f32_e32 v193, v193
	v_exp_f32_e32 v224, v224
	v_exp_f32_e32 v225, v225
	v_exp_f32_e32 v226, v226
	v_exp_f32_e32 v227, v227
	v_pk_add_f32 v[190:191], v[190:191], v[188:189]
	v_pk_add_f32 v[192:193], v[192:193], v[188:189]
	v_pk_add_f32 v[224:225], v[224:225], v[188:189]
	v_pk_add_f32 v[226:227], v[226:227], v[188:189]
	v_rcp_f32_e32 v190, v190
	v_rcp_f32_e32 v191, v191
	v_rcp_f32_e32 v192, v192
	v_rcp_f32_e32 v193, v193
	v_rcp_f32_e32 v224, v224
	v_rcp_f32_e32 v225, v225
	v_rcp_f32_e32 v226, v226
	v_rcp_f32_e32 v227, v227
	v_pk_mul_f32 v[78:79], v[78:79], v[190:191]
	v_pk_mul_f32 v[80:81], v[80:81], v[192:193]
	v_pk_mul_f32 v[70:71], v[70:71], v[224:225]
	v_pk_mul_f32 v[72:73], v[72:73], v[226:227]
	v_pk_mul_f32 v[78:79], v[78:79], v[74:75]
	v_pk_mul_f32 v[80:81], v[80:81], v[76:77]
	v_pk_mul_f32 v[70:71], v[70:71], v[66:67]
	v_pk_mul_f32 v[72:73], v[72:73], v[68:69]
	v_cvt_pk_bf16_f32 v66, v78, v79
	v_cvt_pk_bf16_f32 v67, v80, v81
	v_cvt_pk_bf16_f32 v68, v70, v71
	v_cvt_pk_bf16_f32 v69, v72, v73
	global_store_dwordx4 v[86:87], v[66:69], off offset:2048
	v_pk_mul_f32 v[190:191], v[62:63], v[184:185]
	v_pk_mul_f32 v[192:193], v[64:65], v[184:185]
	v_pk_mul_f32 v[224:225], v[54:55], v[184:185]
	v_pk_mul_f32 v[226:227], v[56:57], v[184:185]
	v_exp_f32_e32 v190, v190
	v_exp_f32_e32 v191, v191
	v_exp_f32_e32 v192, v192
	v_exp_f32_e32 v193, v193
	v_exp_f32_e32 v224, v224
	v_exp_f32_e32 v225, v225
	v_exp_f32_e32 v226, v226
	v_exp_f32_e32 v227, v227
	v_pk_add_f32 v[190:191], v[190:191], v[188:189]
	v_pk_add_f32 v[192:193], v[192:193], v[188:189]
	v_pk_add_f32 v[224:225], v[224:225], v[188:189]
	v_pk_add_f32 v[226:227], v[226:227], v[188:189]
	v_rcp_f32_e32 v190, v190
	v_rcp_f32_e32 v191, v191
	v_rcp_f32_e32 v192, v192
	v_rcp_f32_e32 v193, v193
	v_rcp_f32_e32 v224, v224
	v_rcp_f32_e32 v225, v225
	v_rcp_f32_e32 v226, v226
	v_rcp_f32_e32 v227, v227
	v_pk_mul_f32 v[62:63], v[62:63], v[190:191]
	v_pk_mul_f32 v[64:65], v[64:65], v[192:193]
	v_pk_mul_f32 v[54:55], v[54:55], v[224:225]
	v_pk_mul_f32 v[56:57], v[56:57], v[226:227]
	v_pk_mul_f32 v[62:63], v[62:63], v[58:59]
	v_pk_mul_f32 v[64:65], v[64:65], v[60:61]
	v_pk_mul_f32 v[54:55], v[54:55], v[50:51]
	v_pk_mul_f32 v[56:57], v[56:57], v[52:53]
	v_cvt_pk_bf16_f32 v52, v62, v63
	v_cvt_pk_bf16_f32 v53, v64, v65
	v_cvt_pk_bf16_f32 v54, v54, v55
; __device__ __forceinline__ float fast_sigmoid(float x) { return __builtin_amdgcn_rcpf(1.0f + __builtin_amdgcn_exp2f(-1.4426950408889634f * x)); }
; __device__ __forceinline__ u32x4 pack8(const f32x4 v0, const f32x4 v1) { u32x4 w; w.x = cvt_pk_bf16(v0[0], v0[1]); w.y = cvt_pk_bf16(v0[2], v0[3]); w.z = cvt_pk_bf16(v1[0], v1[1]); w.w = cvt_pk_bf16(v1[2], v1[3]); return w; }
; #define PG8_BAR __builtin_amdgcn_s_barrier()
;     __device__ __forceinline__ void operator()(const f32x4 (&acc)[2][2][4][2], const Unit& u, int wr, int wc, int fr_, int fq) const {
;     ...
;                 for (int j = 0; j < 4; ++j) { const float g0 = acc[ai][0][m][0][j], g1 = acc[ai][0][m][1][j];
;                     v0[j] = g0 * fast_sigmoid(g0) * acc[ai][1][m][0][j]; v1[j] = g1 * fast_sigmoid(g1) * acc[ai][1][m][1][j]; }
;                 *(u32x4*)(Hblk + (size_t)(ai * HALF + m * 16) * BK) = pack8(v0, v1); }
; template <class Epi, class Sched, bool ALIGN_EPI = false, bool SP2 = false, bool ABLK = false, bool BBLK = false>
; __device__ __forceinline__ void gemm_phase(PG8_LAS unsigned char* lds, const Gemm g, const Sched& S, const Epi& E) {
;     ...
;         if (!has_next) break;
; #pragma unroll
;         for (int a = 0; a < 2; ++a)
; #pragma unroll
;             for (int b = 0; b < 2; ++b)
; #pragma unroll
;                 for (int m = 0; m < 4; ++m)
; #pragma unroll
;                     for (int n = 0; n < 2; ++n) acc[a][b][m][n] = (f32x4){0.f, 0.f, 0.f, 0.f};
;         cur = nxt; cA = nA; cB = nB; ++ui;
;         if constexpr (ALIGN_EPI) { if (wr == 1) PG8_BAR; }
;     }
	v_cvt_pk_bf16_f32 v55, v56, v57
	v_add_co_u32_e32 v56, vcc, s87, v142
	s_nop 1
	v_addc_co_u32_e32 v57, vcc, 0, v143, vcc
	v_add_co_u32_e32 v50, vcc, s0, v142
	s_nop 1
	s_mov_b64 s[0:1], -1
	v_addc_co_u32_e32 v51, vcc, 0, v143, vcc
	global_store_dwordx4 v[50:51], v[52:55], off offset:-4096
	v_pk_mul_f32 v[190:191], v[46:47], v[184:185]
	v_pk_mul_f32 v[192:193], v[48:49], v[184:185]
	v_pk_mul_f32 v[224:225], v[38:39], v[184:185]
	v_pk_mul_f32 v[226:227], v[40:41], v[184:185]
	v_exp_f32_e32 v190, v190
	v_exp_f32_e32 v191, v191
	v_exp_f32_e32 v192, v192
	v_exp_f32_e32 v193, v193
	v_exp_f32_e32 v224, v224
	v_exp_f32_e32 v225, v225
	v_exp_f32_e32 v226, v226
	v_exp_f32_e32 v227, v227
	v_pk_add_f32 v[190:191], v[190:191], v[188:189]
	v_pk_add_f32 v[192:193], v[192:193], v[188:189]
	v_pk_add_f32 v[224:225], v[224:225], v[188:189]
	v_pk_add_f32 v[226:227], v[226:227], v[188:189]
	v_rcp_f32_e32 v190, v190
	v_rcp_f32_e32 v191, v191
	v_rcp_f32_e32 v192, v192
	v_rcp_f32_e32 v193, v193
	v_rcp_f32_e32 v224, v224
	v_rcp_f32_e32 v225, v225
	v_rcp_f32_e32 v226, v226
	v_rcp_f32_e32 v227, v227
	v_pk_mul_f32 v[46:47], v[46:47], v[190:191]
	v_pk_mul_f32 v[48:49], v[48:49], v[192:193]
	v_pk_mul_f32 v[38:39], v[38:39], v[224:225]
	v_pk_mul_f32 v[40:41], v[40:41], v[226:227]
	v_pk_mul_f32 v[46:47], v[46:47], v[42:43]
	v_pk_mul_f32 v[48:49], v[48:49], v[44:45]
	v_pk_mul_f32 v[38:39], v[38:39], v[34:35]
	v_pk_mul_f32 v[40:41], v[40:41], v[36:37]
	v_cvt_pk_bf16_f32 v34, v46, v47
	v_cvt_pk_bf16_f32 v35, v48, v49
	v_cvt_pk_bf16_f32 v36, v38, v39
	v_cvt_pk_bf16_f32 v37, v40, v41
	s_andn2_b64 vcc, exec, s[6:7]
	global_store_dwordx4 v[56:57], v[34:37], off offset:2048
	v_pk_mul_f32 v[190:191], v[30:31], v[184:185]
	v_pk_mul_f32 v[192:193], v[32:33], v[184:185]
	v_pk_mul_f32 v[224:225], v[22:23], v[184:185]
	v_pk_mul_f32 v[226:227], v[24:25], v[184:185]
	v_exp_f32_e32 v190, v190
	v_exp_f32_e32 v191, v191
	v_exp_f32_e32 v192, v192
	v_exp_f32_e32 v193, v193
	v_exp_f32_e32 v224, v224
	v_exp_f32_e32 v225, v225
	v_exp_f32_e32 v226, v226
	v_exp_f32_e32 v227, v227
	v_pk_add_f32 v[190:191], v[190:191], v[188:189]
	v_pk_add_f32 v[192:193], v[192:193], v[188:189]
	v_pk_add_f32 v[224:225], v[224:225], v[188:189]
	v_pk_add_f32 v[226:227], v[226:227], v[188:189]
	v_rcp_f32_e32 v190, v190
	v_rcp_f32_e32 v191, v191
	v_rcp_f32_e32 v192, v192
	v_rcp_f32_e32 v193, v193
	v_rcp_f32_e32 v224, v224
	v_rcp_f32_e32 v225, v225
	v_rcp_f32_e32 v226, v226
	v_rcp_f32_e32 v227, v227
	v_pk_mul_f32 v[30:31], v[30:31], v[190:191]
	v_pk_mul_f32 v[32:33], v[32:33], v[192:193]
	v_pk_mul_f32 v[22:23], v[22:23], v[224:225]
	v_pk_mul_f32 v[24:25], v[24:25], v[226:227]
	v_pk_mul_f32 v[30:31], v[30:31], v[26:27]
	v_pk_mul_f32 v[32:33], v[32:33], v[28:29]
	v_pk_mul_f32 v[22:23], v[22:23], v[18:19]
	v_pk_mul_f32 v[24:25], v[24:25], v[20:21]
	v_cvt_pk_bf16_f32 v18, v30, v31
	v_cvt_pk_bf16_f32 v19, v32, v33
	v_cvt_pk_bf16_f32 v20, v22, v23
	v_cvt_pk_bf16_f32 v21, v24, v25
	global_store_dwordx4 v[50:51], v[18:21], off
	v_pk_mul_f32 v[190:191], v[14:15], v[184:185]
	v_pk_mul_f32 v[192:193], v[16:17], v[184:185]
	v_pk_mul_f32 v[224:225], v[6:7], v[184:185]
	v_pk_mul_f32 v[226:227], v[8:9], v[184:185]
	v_exp_f32_e32 v190, v190
	v_exp_f32_e32 v191, v191
	v_exp_f32_e32 v192, v192
	v_exp_f32_e32 v193, v193
	v_exp_f32_e32 v224, v224
	v_exp_f32_e32 v225, v225
	v_exp_f32_e32 v226, v226
	v_exp_f32_e32 v227, v227
	v_pk_add_f32 v[190:191], v[190:191], v[188:189]
	v_pk_add_f32 v[192:193], v[192:193], v[188:189]
	v_pk_add_f32 v[224:225], v[224:225], v[188:189]
	v_pk_add_f32 v[226:227], v[226:227], v[188:189]
	v_rcp_f32_e32 v190, v190
	v_rcp_f32_e32 v191, v191
	v_rcp_f32_e32 v192, v192
	v_rcp_f32_e32 v193, v193
	v_rcp_f32_e32 v224, v224
	v_rcp_f32_e32 v225, v225
	v_rcp_f32_e32 v226, v226
	v_rcp_f32_e32 v227, v227
	v_pk_mul_f32 v[14:15], v[14:15], v[190:191]
	v_pk_mul_f32 v[16:17], v[16:17], v[192:193]
	v_pk_mul_f32 v[6:7], v[6:7], v[224:225]
	v_pk_mul_f32 v[8:9], v[8:9], v[226:227]
	v_pk_mul_f32 v[14:15], v[14:15], v[10:11]
	v_pk_mul_f32 v[16:17], v[16:17], v[12:13]
	v_pk_mul_f32 v[6:7], v[6:7], v[2:3]
	v_pk_mul_f32 v[8:9], v[8:9], v[4:5]
	v_cvt_pk_bf16_f32 v2, v14, v15
	v_cvt_pk_bf16_f32 v3, v16, v17
	v_cvt_pk_bf16_f32 v4, v6, v7
	v_cvt_pk_bf16_f32 v5, v8, v9
	global_store_dwordx4 v[50:51], v[2:5], off offset:2048
	s_cbranch_vccnz .LBB0_1336
	s_andn2_b64 vcc, exec, s[4:5]
	s_cbranch_vccnz .LBB0_1335
	s_branch .LBB0_1335

; #define PG8_STAGE(bufoff, gbase, voff) do { _Pragma("unroll") for (int _i = 0; _i < 2; ++_i) \
;         __builtin_amdgcn_global_load_lds((const unsigned*)((const char*)(gbase) + (voff)[_i]), (PG8_LAS unsigned*)(lds + (bufoff) + ldsw + _i * 8192), 16, 0, 0); } while (0)
; #define PG8_BAR __builtin_amdgcn_s_barrier()
; template <class Epi, class Sched, bool ALIGN_EPI = false, bool SP2 = false, bool ABLK = false, bool BBLK = false>
; __device__ __forceinline__ void gemm_phase(PG8_LAS unsigned char* lds, const Gemm g, const Sched& S, const Epi& E) {
;     ...
;     const int tid = tid_, wid = __builtin_amdgcn_readfirstlane(tid >> 6), lane = tid & 63, wr = wid >> 2, wc = wid & 3, fr = lane & 15, fq = lane >> 4;
;     const int K = g.K, nt = K / BK, LDA = g.lda ? g.lda : K, LDB = g.ldb ? g.ldb : K;
;     unsigned voffA[2], voffB[2];
; #pragma unroll
;     for (int i = 0; i < 2; ++i) { int R, C; stage_rc(tid * 16 + i * 8192, R, C); const int Rb = Epi::PERM ? ((R & ~31) + perm32(R & 31)) : R;
;         voffA[i] = ABLK ? (unsigned)(R * BK + C) * 2u : (unsigned)(R * LDA + C) * 2u; voffB[i] = BBLK ? (unsigned)(Rb * BK + C) * 2u : (unsigned)(Rb * LDB + C) * 2u; }
;     const size_t kstep = (size_t)(BK * 2);
;     const size_t hstepa = (size_t)HALF * LDA * 2, hstepb = (size_t)HALF * LDB * 2;
;     const size_t kstepA = ABLK ? (size_t)BM * BK * 2 : kstep, hstepA = ABLK ? (size_t)HALF * BK * 2 : hstepa, tstepA = ABLK ? (size_t)nt * BM * BK * 2 : 2 * hstepa;
;     const size_t kstepB = BBLK ? (size_t)BM * BK * 2 : kstep, hstepB = BBLK ? (size_t)HALF * BK * 2 : hstepb, tstepB = BBLK ? (size_t)nt * BM * BK * 2 : 2 * hstepb;
;     const unsigned ldsw = (unsigned)wid * 1024u;
;     const int aoff = lds_byte(wr * 64 + fr, fq * 8), boff = lds_byte(wc * 32 + fr, fq * 8);
;     ...
;     const char* cA = (const char*)g.A + (size_t)cur.pm * tstepA; const char* cB = (const char*)g.Bt + (size_t)cur.pn * tstepB;
;     S.a_ready(cur);
;     if constexpr (SP2) {
;         PG8_STAGE(PG8_SB(0, 0), cB, voffB); PG8_STAGE(PG8_SB(0, 1), cB + hstepB, voffB); PG8_STAGE(PG8_SA(0, 0), cA, voffA); PG8_STAGE(PG8_SA(0, 1), cA + hstepA, voffA);
;         if (wr == 1) PG8_BAR;
;         PG8_WAIT_V(2); PG8_BAR;
;         PG8_STAGE(PG8_SB(1, 0), cB + kstepB, voffB); PG8_STAGE(PG8_SA(1, 0), cA + kstepA, voffA); PG8_STAGE(PG8_SB(1, 1), cB + hstepB + kstepB, voffB);
;         PG8_WAIT_V(6); PG8_BAR;
.LBB0_1407:
	s_load_dwordx2 s[4:5], s[0:1], 0xc8
	s_andn2_b64 vcc, exec, s[6:7]
	s_cbranch_vccnz .LBB0_1460
	v_bfe_i32 v4, v2, 27, 1
	v_lshlrev_b32_e32 v6, 4, v2
	v_lshrrev_b32_e32 v4, 22, v4
	v_ashrrev_i32_e32 v3, 31, v2
	v_add_u32_e32 v4, v6, v4
	v_lshrrev_b32_e32 v3, 26, v3
	v_and_b32_e32 v4, 0xfffffc00, v4
	v_add_u32_e32 v3, v2, v3
	v_sub_u32_e32 v4, v6, v4
	v_ashrrev_i32_e32 v3, 6, v3
	v_lshrrev_b32_e32 v5, 4, v4
	v_bitop3_b32 v5, v5, v4, 32 bitop3:0x6c
	v_lshlrev_b32_e32 v4, 3, v3
	v_and_b32_e32 v7, -16, v4
	v_ashrrev_i32_e32 v4, 31, v5
	v_lshrrev_b32_e32 v4, 26, v4
	v_add_u32_e32 v8, v5, v4
	v_ashrrev_i32_e32 v4, 6, v8
	v_and_b32_e32 v8, 0xc0, v8
	v_sub_u32_e32 v5, v5, v8
	v_lshlrev_b32_e32 v9, 5, v3
	v_ashrrev_i16_sdwa v5, v232, sext(v5) dst_sel:DWORD dst_unused:UNUSED_PAD src0_sel:DWORD src1_sel:BYTE_0
	v_and_b32_e32 v9, 32, v9
	v_bfe_i32 v5, v5, 0, 16
	v_add_u32_e32 v7, v4, v7
	v_and_b32_e32 v11, 3, v4
	s_mov_b32 s0, 0x1ffffe0
	v_add_lshl_u32 v9, v9, v5, 1
	v_lshlrev_b32_e32 v8, 1, v7
	v_lshrrev_b32_e32 v10, 2, v7
	v_and_or_b32 v11, v7, s0, v11
	v_lshl_add_u32 v146, v7, 7, v9
	v_add_u32_e32 v7, 0x2000, v6
	v_ashrrev_i32_e32 v6, 31, v7
	v_lshrrev_b32_e32 v6, 22, v6
	v_and_b32_e32 v8, 24, v8
	v_and_b32_e32 v10, 4, v10
	v_add_u32_e32 v6, v7, v6
	v_or3_b32 v8, v11, v10, v8
	v_ashrrev_i32_e32 v6, 10, v6
	v_lshl_add_u32 v186, v8, 7, v9
	v_mul_i32_i24_e32 v8, 0x400, v6
	v_sub_u32_e32 v7, v7, v8
	v_lshrrev_b32_e32 v8, 4, v7
	v_bitop3_b32 v8, v8, v7, 32 bitop3:0x6c
	v_lshlrev_b32_e32 v7, 3, v6
	v_and_b32_e32 v9, -16, v7
	v_ashrrev_i32_e32 v7, 31, v8
	v_lshrrev_b32_e32 v7, 26, v7
	v_add_u32_e32 v10, v8, v7
	s_ashr_i32 s6, s8, 6
	v_ashrrev_i32_e32 v7, 6, v10
	v_add_u32_e32 v9, v7, v9
	v_and_b32_e32 v10, 0xc0, v10
	v_and_b32_e32 v13, 3, v7
	s_ashr_i32 s7, s8, 8
	s_lshl_b32 s2, s6, 10
	s_mul_i32 s1, s24, 0x2c0000
	v_sub_u32_e32 v8, v8, v10
	v_and_or_b32 v13, v9, s0, v13
	s_mul_hi_i32 s0, s24, 0x2c0000
	s_add_u32 s26, s90, s1
	v_lshlrev_b32_e32 v11, 5, v6
	v_ashrrev_i16_sdwa v8, v232, sext(v8) dst_sel:DWORD dst_unused:UNUSED_PAD src0_sel:DWORD src1_sel:BYTE_0
	v_lshlrev_b32_e32 v10, 1, v9
	v_lshrrev_b32_e32 v12, 2, v9
	s_addc_u32 s27, s96, s0
	s_add_i32 s3, s2, 0
	v_and_b32_e32 v11, 32, v11
	v_bfe_i32 v8, v8, 0, 16
	v_and_b32_e32 v10, 24, v10
	v_and_b32_e32 v12, 4, v12
	s_add_i32 m0, s3, 0x10000
	v_or3_b32 v10, v13, v12, v10
	v_add_lshl_u32 v11, v11, v8, 1
	global_load_lds_dwordx4 v186, s[26:27]
	s_add_i32 m0, s3, 0x12000
	v_lshl_add_u32 v150, v10, 7, v11
	s_add_u32 s0, s26, 0x4000
	global_load_lds_dwordx4 v150, s[26:27]
	s_addc_u32 s1, s27, 0
	s_add_i32 m0, s3, 0x14000
	s_mul_i32 s12, s22, 0x2c0000
	global_load_lds_dwordx4 v186, s[0:1]
	s_add_i32 m0, s3, 0x16000
	s_mul_hi_i32 s9, s22, 0x2c0000
	global_load_lds_dwordx4 v150, s[0:1]
	s_add_u32 s0, s83, s12
	s_addc_u32 s1, s84, s9
	s_add_i32 s16, s3, 0x2000
	s_mov_b32 m0, s3
	s_add_u32 s12, s0, 0x4000
	v_lshl_add_u32 v148, v9, 7, v11
	global_load_lds_dwordx4 v146, s[0:1]
	s_mov_b32 m0, s16
	s_addc_u32 s13, s1, 0
	s_add_i32 s30, s3, 0x4000
	global_load_lds_dwordx4 v148, s[0:1]
	s_mov_b32 m0, s30
	s_add_i32 s31, s3, 0x6000
	global_load_lds_dwordx4 v146, s[12:13]
	s_mov_b32 m0, s31
	s_cmp_eq_u32 s7, 1
	global_load_lds_dwordx4 v148, s[12:13]
	s_mov_b32 s82, 0x10000
	s_cselect_b64 s[12:13], -1, 0
	s_cmp_lg_u32 s7, 1
	s_cbranch_scc1 .LBB0_1410
.LBB0_1410:
	s_lshl_b64 s[14:15], s[92:93], 2
	v_readlane_b32 s18, v254, 26
	v_readlane_b32 s19, v254, 27
	s_add_u32 s33, s18, s14
	s_addc_u32 s34, s19, s15
	s_add_u32 s35, s43, 0xf400000
	s_addc_u32 s36, s50, 0
	s_add_u32 s37, s43, 0x1b400
	s_addc_u32 s40, s50, 0
	s_and_b32 s6, s6, 3
	s_lshl_b32 s41, s7, 6
	s_lshl_b32 s9, s7, 13
	s_lshl_b32 s44, s6, 5
	s_lshl_b32 s18, s6, 12
	s_add_u32 s14, s26, 0x8000
	s_addc_u32 s15, s27, 0
	s_add_i32 m0, s3, 0x18000
	v_lshl_add_u64 v[10:11], s[14:15], 0, v[186:187]
	v_mov_b32_e32 v151, v187
	s_waitcnt vmcnt(2)
	s_barrier
	global_load_lds_dwordx4 v[10:11], off
	s_add_i32 m0, s3, 0x1a000
	v_lshl_add_u64 v[10:11], s[14:15], 0, v[150:151]
	s_add_u32 s14, s0, 0x8000
	v_mov_b32_e32 v147, v187
	s_addc_u32 s15, s1, 0
	s_add_i32 s45, s3, 0x8000
	v_mov_b32_e32 v149, v187
	global_load_lds_dwordx4 v[10:11], off
	v_lshl_add_u64 v[10:11], s[14:15], 0, v[146:147]
	s_mov_b32 m0, s45
	s_add_i32 s46, s3, 0xa000
	global_load_lds_dwordx4 v[10:11], off
	v_lshl_add_u64 v[10:11], s[14:15], 0, v[148:149]
	s_add_u32 s14, s26, 0xc000
	s_mov_b32 m0, s46
	s_addc_u32 s15, s27, 0
	global_load_lds_dwordx4 v[10:11], off
	s_add_i32 m0, s3, 0x1c000
	v_lshl_add_u64 v[10:11], s[14:15], 0, v[186:187]
	global_load_lds_dwordx4 v[10:11], off
	v_lshl_add_u64 v[10:11], s[14:15], 0, v[150:151]
	s_add_i32 m0, s3, 0x1e000
	v_bfe_u32 v179, v2, 4, 2
	global_load_lds_dwordx4 v[10:11], off
	v_and_b32_e32 v178, 15, v2
	v_lshlrev_b32_e32 v9, 4, v179
	v_lshlrev_b32_e32 v2, 2, v2
	v_lshl_or_b32 v9, v178, 6, v9
	v_and_b32_e32 v2, 32, v2
	v_bitop3_b32 v10, v9, s9, v2 bitop3:0xde
	v_bitop3_b32 v180, v9, s18, v2 bitop3:0xde
	v_lshlrev_b32_e32 v2, 10, v3
	v_and_b32_e32 v2, 0xfffff800, v2
	v_lshl_add_u32 v2, v4, 7, v2
	v_and_b32_e32 v3, 1, v3
	v_lshl_or_b32 v2, v3, 6, v2
	s_cmpk_lt_u32 s8, 0x100
	v_lshl_add_u32 v152, v5, 1, v2
	v_lshlrev_b32_e32 v2, 10, v6
	s_cselect_b64 s[14:15], -1, 0
	s_lshl_b32 s7, s7, 2
	v_and_b32_e32 v2, 0xfffff800, v2
	s_waitcnt vmcnt(6)
	s_or_b32 s47, s7, s6
	s_lshl_b32 s6, s6, 2
	v_lshl_add_u32 v2, v7, 7, v2
	v_and_b32_e32 v3, 1, v6
	s_add_i32 s61, s6, 0
	v_lshl_or_b32 v2, v3, 6, v2
	s_lshl_b32 s53, s47, 5
	s_ashr_i32 s56, s42, 31
	s_ashr_i32 s60, s51, 31
	s_add_i32 s61, s61, 0x20540
	v_mov_b32_e32 v153, v187
	v_lshl_add_u32 v154, v8, 1, v2
	v_mov_b32_e32 v155, v187
	s_mov_b32 s65, 0
	v_add_u32_e32 v181, 0, v10
	s_barrier
	s_branch .LBB0_1413

; #define PG8_STAGE(bufoff, gbase, voff) do { _Pragma("unroll") for (int _i = 0; _i < 2; ++_i) \
;         __builtin_amdgcn_global_load_lds((const unsigned*)((const char*)(gbase) + (voff)[_i]), (PG8_LAS unsigned*)(lds + (bufoff) + ldsw + _i * 8192), 16, 0, 0); } while (0)
; #define PG8_LDA(dst, b, h) do { _Pragma("unroll") for (int m = 0; m < 4; ++m) _Pragma("unroll") for (int k = 0; k < 2; ++k) dst[m][k] = *(const PG8_LAS bf16x8*)(lds + PG8_SA(b, h) + aoff + m * 2048 + k * 1024); } while (0)
; #define PG8_LDB(dst, b, h) do { _Pragma("unroll") for (int n = 0; n < 2; ++n) _Pragma("unroll") for (int k = 0; k < 2; ++k) dst[n][k] = *(const PG8_LAS bf16x8*)(lds + PG8_SB(b, h) + boff + n * 2048 + k * 1024); } while (0)
; #define PG8_MMA(ai, bj, At, Bt) do { __builtin_amdgcn_s_setprio(1); _Pragma("unroll") for (int m = 0; m < 4; ++m) _Pragma("unroll") for (int n = 0; n < 2; ++n) _Pragma("unroll") for (int k = 0; k < 2; ++k) \
;         acc[ai][bj][m][n] = __builtin_amdgcn_mfma_f32_16x16x32_bf16(Bt[n][k], At[m][k], acc[ai][bj][m][n], 0, 0, 0); __builtin_amdgcn_s_setprio(0); } while (0)
; #define PG8_WAIT_V(n) asm volatile("s_waitcnt vmcnt(" #n ")" ::: "memory")
; #define PG8_WAIT_L(n) asm volatile("s_waitcnt lgkmcnt(" #n ")" ::: "memory")
; #define PG8_BAR __builtin_amdgcn_s_barrier()
; #define PG8_SCHED __builtin_amdgcn_sched_barrier(0)
; template <class Epi, class Sched, bool ALIGN_EPI = false, bool SP2 = false, bool ABLK = false, bool BBLK = false>
; __device__ __forceinline__ void gemm_phase(PG8_LAS unsigned char* lds, const Gemm g, const Sched& S, const Epi& E) {
;     ...
;             PG8_LDB(B0, 0, 0); PG8_LDB(B1, 0, 1); PG8_SCHED; PG8_LDA(At, 0, 0); PG8_STAGE(PG8_SA(1, 1), a1 + hstepA, voffA);
;             PG8_WAIT_V(8); PG8_WAIT_L(0); PG8_BAR; PG8_MMA(0, 0, At, B0); PG8_MMA(0, 1, At, B1); PG8_BAR; PG8_SCHED;
;     ...
;         for (int a = 0; a < 2; ++a)
; #pragma unroll
;             for (int b = 0; b < 2; ++b)
; #pragma unroll
;                 for (int m = 0; m < 4; ++m)
; #pragma unroll
;                     for (int n = 0; n < 2; ++n) acc[a][b][m][n] = (f32x4){0.f, 0.f, 0.f, 0.f};
;         cur = nxt; cA = nA; cB = nB; ++ui;
;         if constexpr (ALIGN_EPI) { if (wr == 1) PG8_BAR; }
.LBB0_1419:
	s_add_u32 s0, s0, 0xc000
	s_addc_u32 s1, s1, 0
	s_add_u32 s23, s26, 0x10000
	v_mov_b32_e32 v2, 0
	s_addc_u32 s25, s27, 0
	s_mov_b32 s73, -2
	v_mov_b32_e32 v3, v2
	v_mov_b32_e32 v4, v2
	v_mov_b32_e32 v5, v2
	v_mov_b32_e32 v6, v2
	v_mov_b32_e32 v7, v2
	v_mov_b32_e32 v8, v2
	v_mov_b32_e32 v9, v2
	v_mov_b32_e32 v18, v2
	v_mov_b32_e32 v19, v2
	v_mov_b32_e32 v20, v2
	v_mov_b32_e32 v21, v2
	v_mov_b32_e32 v22, v2
	v_mov_b32_e32 v23, v2
	v_mov_b32_e32 v24, v2
	v_mov_b32_e32 v25, v2
	v_mov_b32_e32 v34, v2
	v_mov_b32_e32 v35, v2
	v_mov_b32_e32 v36, v2
	v_mov_b32_e32 v37, v2
	v_mov_b32_e32 v38, v2
	v_mov_b32_e32 v39, v2
	v_mov_b32_e32 v40, v2
	v_mov_b32_e32 v41, v2
	v_mov_b32_e32 v62, v2
	v_mov_b32_e32 v63, v2
	v_mov_b32_e32 v64, v2
	v_mov_b32_e32 v65, v2
	v_mov_b32_e32 v74, v2
	v_mov_b32_e32 v75, v2
	v_mov_b32_e32 v76, v2
	v_mov_b32_e32 v77, v2
	v_mov_b32_e32 v10, v2
	v_mov_b32_e32 v11, v2
	v_mov_b32_e32 v12, v2
	v_mov_b32_e32 v13, v2
	v_mov_b32_e32 v14, v2
	v_mov_b32_e32 v15, v2
	v_mov_b32_e32 v16, v2
	v_mov_b32_e32 v17, v2
	v_mov_b32_e32 v26, v2
	v_mov_b32_e32 v27, v2
	v_mov_b32_e32 v28, v2
	v_mov_b32_e32 v29, v2
	v_mov_b32_e32 v30, v2
	v_mov_b32_e32 v31, v2
	v_mov_b32_e32 v32, v2
	v_mov_b32_e32 v33, v2
	v_mov_b32_e32 v42, v2
	v_mov_b32_e32 v43, v2
	v_mov_b32_e32 v44, v2
	v_mov_b32_e32 v45, v2
	v_mov_b32_e32 v46, v2
	v_mov_b32_e32 v47, v2
	v_mov_b32_e32 v48, v2
	v_mov_b32_e32 v49, v2
	v_mov_b32_e32 v82, v2
	v_mov_b32_e32 v83, v2
	v_mov_b32_e32 v84, v2
	v_mov_b32_e32 v85, v2
	v_mov_b32_e32 v90, v2
	v_mov_b32_e32 v91, v2
	v_mov_b32_e32 v92, v2
	v_mov_b32_e32 v93, v2
	v_mov_b32_e32 v126, v2
	v_mov_b32_e32 v127, v2
	v_mov_b32_e32 v128, v2
	v_mov_b32_e32 v129, v2
	v_mov_b32_e32 v122, v2
	v_mov_b32_e32 v123, v2
	v_mov_b32_e32 v124, v2
	v_mov_b32_e32 v125, v2
	v_mov_b32_e32 v110, v2
	v_mov_b32_e32 v111, v2
	v_mov_b32_e32 v112, v2
	v_mov_b32_e32 v113, v2
	v_mov_b32_e32 v106, v2
	v_mov_b32_e32 v107, v2
	v_mov_b32_e32 v108, v2
	v_mov_b32_e32 v109, v2
	v_mov_b32_e32 v94, v2
	v_mov_b32_e32 v95, v2
	v_mov_b32_e32 v96, v2
	v_mov_b32_e32 v97, v2
	v_mov_b32_e32 v86, v2
	v_mov_b32_e32 v87, v2
	v_mov_b32_e32 v88, v2
	v_mov_b32_e32 v89, v2
	v_mov_b32_e32 v54, v2
	v_mov_b32_e32 v55, v2
	v_mov_b32_e32 v56, v2
	v_mov_b32_e32 v57, v2
	v_mov_b32_e32 v66, v2
	v_mov_b32_e32 v67, v2
	v_mov_b32_e32 v68, v2
	v_mov_b32_e32 v69, v2
	v_mov_b32_e32 v118, v2
	v_mov_b32_e32 v119, v2
	v_mov_b32_e32 v120, v2
	v_mov_b32_e32 v121, v2
	v_mov_b32_e32 v114, v2
	v_mov_b32_e32 v115, v2
	v_mov_b32_e32 v116, v2
	v_mov_b32_e32 v117, v2
	v_mov_b32_e32 v102, v2
	v_mov_b32_e32 v103, v2
	v_mov_b32_e32 v104, v2
	v_mov_b32_e32 v105, v2
	v_mov_b32_e32 v98, v2
	v_mov_b32_e32 v99, v2
	v_mov_b32_e32 v100, v2
	v_mov_b32_e32 v101, v2
	v_mov_b32_e32 v70, v2
	v_mov_b32_e32 v71, v2
	v_mov_b32_e32 v72, v2
	v_mov_b32_e32 v73, v2
	v_mov_b32_e32 v78, v2
	v_mov_b32_e32 v79, v2
	v_mov_b32_e32 v80, v2
	v_mov_b32_e32 v81, v2
	v_mov_b32_e32 v50, v2
	v_mov_b32_e32 v51, v2
	v_mov_b32_e32 v52, v2
	v_mov_b32_e32 v53, v2
	v_mov_b32_e32 v58, v2
	v_mov_b32_e32 v59, v2
	v_mov_b32_e32 v60, v2
	v_mov_b32_e32 v61, v2
	s_and_b64 vcc, exec, s[14:15]
	s_cbranch_vccnz .Lrb_f2b0
	s_barrier
.Lrb_f2b0:
.LBB0_1420:
	s_add_u32 s8, s0, 0x4000
	s_addc_u32 s9, s1, 0
	s_cmpk_eq_i32 s73, 0x54
	s_cselect_b32 s28, s18, s8
	s_cselect_b32 s29, s19, s9
	s_cselect_b32 s26, s20, s23
	s_cselect_b32 s27, s21, s25
	s_add_u32 s8, s28, 0x8000
	s_addc_u32 s9, s29, 0
	s_add_i32 s52, 0, 0x10000
	s_add_i32 s75, 0, 0x14000
	v_add_u32_e32 v142, s52, v180
	v_add_u32_e32 v168, s75, v180
	ds_read_b128 v[130:133], v142
	ds_read_b128 v[134:137], v142 offset:1024
	ds_read_b128 v[138:141], v142 offset:2048
	ds_read_b128 v[142:145], v142 offset:3072
	ds_read_b128 v[156:159], v168
	ds_read_b128 v[160:163], v168 offset:1024
	ds_read_b128 v[164:167], v168 offset:2048
	ds_read_b128 v[168:171], v168 offset:3072
	v_lshl_add_u64 v[176:177], s[0:1], 0, v[152:153]
	s_add_i32 m0, s3, 0xc000
	ds_read_b128 v[172:175], v181
	ds_read_b128 v[182:185], v181 offset:1024
	ds_read_b128 v[196:199], v181 offset:2048
	ds_read_b128 v[200:203], v181 offset:3072
	ds_read_b128 v[204:207], v181 offset:4096
	ds_read_b128 v[208:211], v181 offset:5120
	ds_read_b128 v[212:215], v181 offset:6144
	ds_read_b128 v[216:219], v181 offset:7168
	global_load_lds_dwordx4 v[176:177], off
	v_lshl_add_u64 v[176:177], s[0:1], 0, v[154:155]
	s_add_i32 m0, s3, 0xe000
	s_nop 0
	global_load_lds_dwordx4 v[176:177], off
	s_waitcnt vmcnt(8)
	s_waitcnt lgkmcnt(0)
	s_barrier
; #define PG8_STAGE(bufoff, gbase, voff) do { _Pragma("unroll") for (int _i = 0; _i < 2; ++_i) \
;         __builtin_amdgcn_global_load_lds((const unsigned*)((const char*)(gbase) + (voff)[_i]), (PG8_LAS unsigned*)(lds + (bufoff) + ldsw + _i * 8192), 16, 0, 0); } while (0)
; #define PG8_LDA(dst, b, h) do { _Pragma("unroll") for (int m = 0; m < 4; ++m) _Pragma("unroll") for (int k = 0; k < 2; ++k) dst[m][k] = *(const PG8_LAS bf16x8*)(lds + PG8_SA(b, h) + aoff + m * 2048 + k * 1024); } while (0)
; #define PG8_MMA(ai, bj, At, Bt) do { __builtin_amdgcn_s_setprio(1); _Pragma("unroll") for (int m = 0; m < 4; ++m) _Pragma("unroll") for (int n = 0; n < 2; ++n) _Pragma("unroll") for (int k = 0; k < 2; ++k) \
;         acc[ai][bj][m][n] = __builtin_amdgcn_mfma_f32_16x16x32_bf16(Bt[n][k], At[m][k], acc[ai][bj][m][n], 0, 0, 0); __builtin_amdgcn_s_setprio(0); } while (0)
; #define PG8_WAIT_V(n) asm volatile("s_waitcnt vmcnt(" #n ")" ::: "memory")
; #define PG8_WAIT_L(n) asm volatile("s_waitcnt lgkmcnt(" #n ")" ::: "memory")
; #define PG8_BAR __builtin_amdgcn_s_barrier()
; #define PG8_SCHED __builtin_amdgcn_sched_barrier(0)
; template <class Epi, class Sched, bool ALIGN_EPI = false, bool SP2 = false, bool ABLK = false, bool BBLK = false>
; __device__ __forceinline__ void gemm_phase(PG8_LAS unsigned char* lds, const Gemm g, const Sched& S, const Epi& E) {
;     ...
;             PG8_WAIT_V(8); PG8_WAIT_L(0); PG8_BAR; PG8_MMA(0, 0, At, B0); PG8_MMA(0, 1, At, B1); PG8_BAR; PG8_SCHED;
;             PG8_LDA(At, 0, 1); PG8_STAGE(PG8_SB(0, 0), b2, voffB); PG8_STAGE(PG8_SB(0, 1), b2 + hstepB, voffB); PG8_STAGE(PG8_SA(0, 0), a2, voffA);
;             PG8_WAIT_V(8); PG8_WAIT_L(0); PG8_BAR; PG8_MMA(1, 0, At, B0); PG8_MMA(1, 1, At, B1); PG8_BAR; PG8_SCHED;
	s_setprio 1
	s_waitcnt lgkmcnt(0)
	v_mfma_f32_16x16x32_bf16 v[58:61], v[130:133], v[172:175], v[58:61]
	v_mfma_f32_16x16x32_bf16 v[50:53], v[138:141], v[172:175], v[50:53]
	v_mfma_f32_16x16x32_bf16 v[78:81], v[130:133], v[196:199], v[78:81]
	v_mfma_f32_16x16x32_bf16 v[70:73], v[138:141], v[196:199], v[70:73]
	v_mfma_f32_16x16x32_bf16 v[98:101], v[130:133], v[204:207], v[98:101]
	v_mfma_f32_16x16x32_bf16 v[102:105], v[138:141], v[204:207], v[102:105]
	v_mfma_f32_16x16x32_bf16 v[114:117], v[130:133], v[212:215], v[114:117]
	v_mfma_f32_16x16x32_bf16 v[118:121], v[138:141], v[212:215], v[118:121]
	v_mfma_f32_16x16x32_bf16 v[58:61], v[134:137], v[182:185], v[58:61]
	v_mfma_f32_16x16x32_bf16 v[50:53], v[142:145], v[182:185], v[50:53]
	v_mfma_f32_16x16x32_bf16 v[78:81], v[134:137], v[200:203], v[78:81]
	v_mfma_f32_16x16x32_bf16 v[70:73], v[142:145], v[200:203], v[70:73]
	v_mfma_f32_16x16x32_bf16 v[98:101], v[134:137], v[208:211], v[98:101]
	v_mfma_f32_16x16x32_bf16 v[102:105], v[142:145], v[208:211], v[102:105]
	v_mfma_f32_16x16x32_bf16 v[114:117], v[134:137], v[216:219], v[114:117]
	v_mfma_f32_16x16x32_bf16 v[118:121], v[142:145], v[216:219], v[118:121]
	s_setprio 0
	s_setprio 1
	v_mfma_f32_16x16x32_bf16 v[66:69], v[156:159], v[172:175], v[66:69]
	v_mfma_f32_16x16x32_bf16 v[54:57], v[164:167], v[172:175], v[54:57]
	v_mfma_f32_16x16x32_bf16 v[86:89], v[156:159], v[196:199], v[86:89]
	v_mfma_f32_16x16x32_bf16 v[94:97], v[164:167], v[196:199], v[94:97]
	v_mfma_f32_16x16x32_bf16 v[106:109], v[156:159], v[204:207], v[106:109]
	v_mfma_f32_16x16x32_bf16 v[110:113], v[164:167], v[204:207], v[110:113]
	v_mfma_f32_16x16x32_bf16 v[122:125], v[156:159], v[212:215], v[122:125]
	v_mfma_f32_16x16x32_bf16 v[126:129], v[164:167], v[212:215], v[126:129]
	v_mfma_f32_16x16x32_bf16 v[66:69], v[160:163], v[182:185], v[66:69]
	v_mfma_f32_16x16x32_bf16 v[54:57], v[168:171], v[182:185], v[54:57]
	v_mfma_f32_16x16x32_bf16 v[86:89], v[160:163], v[200:203], v[86:89]
	v_mfma_f32_16x16x32_bf16 v[94:97], v[168:171], v[200:203], v[94:97]
	v_mfma_f32_16x16x32_bf16 v[106:109], v[160:163], v[208:211], v[106:109]
	v_mfma_f32_16x16x32_bf16 v[110:113], v[168:171], v[208:211], v[110:113]
	v_mfma_f32_16x16x32_bf16 v[122:125], v[160:163], v[216:219], v[122:125]
	v_mfma_f32_16x16x32_bf16 v[126:129], v[168:171], v[216:219], v[126:129]
	s_setprio 0
	s_barrier
	s_add_i32 s52, s52, s2
	v_lshl_add_u64 v[176:177], s[26:27], 0, v[186:187]
	s_mov_b32 m0, s52
	ds_read_b128 v[172:175], v181 offset:16384
	ds_read_b128 v[182:185], v181 offset:17408
	ds_read_b128 v[196:199], v181 offset:18432
	ds_read_b128 v[200:203], v181 offset:19456
	ds_read_b128 v[204:207], v181 offset:20480
	ds_read_b128 v[208:211], v181 offset:21504
	ds_read_b128 v[212:215], v181 offset:22528
	ds_read_b128 v[216:219], v181 offset:23552
	global_load_lds_dwordx4 v[176:177], off
	s_add_i32 m0, s52, 0x2000
	s_add_u32 s80, s26, 0x4000
	v_lshl_add_u64 v[176:177], s[26:27], 0, v[150:151]
	s_addc_u32 s81, s27, 0
	s_add_i32 s52, s75, s2
	global_load_lds_dwordx4 v[176:177], off
	v_lshl_add_u64 v[176:177], s[80:81], 0, v[186:187]
	s_mov_b32 m0, s52
	s_nop 0
	global_load_lds_dwordx4 v[176:177], off
	v_lshl_add_u64 v[176:177], s[80:81], 0, v[150:151]
	s_add_i32 m0, s52, 0x2000
	s_nop 0
	global_load_lds_dwordx4 v[176:177], off
	v_lshl_add_u64 v[176:177], s[28:29], 0, v[146:147]
	s_mov_b32 m0, s3
	s_nop 0
	global_load_lds_dwordx4 v[176:177], off
	v_lshl_add_u64 v[176:177], s[28:29], 0, v[148:149]
	s_mov_b32 m0, s16
	s_nop 0
	global_load_lds_dwordx4 v[176:177], off
	s_waitcnt vmcnt(8)
	s_waitcnt lgkmcnt(0)
	s_barrier
	s_setprio 1
	s_waitcnt lgkmcnt(0)
	v_mfma_f32_16x16x32_bf16 v[90:93], v[130:133], v[172:175], v[90:93]
	v_mfma_f32_16x16x32_bf16 v[82:85], v[138:141], v[172:175], v[82:85]
	v_mfma_f32_16x16x32_bf16 v[46:49], v[130:133], v[196:199], v[46:49]
	v_mfma_f32_16x16x32_bf16 v[42:45], v[138:141], v[196:199], v[42:45]
	v_mfma_f32_16x16x32_bf16 v[30:33], v[130:133], v[204:207], v[30:33]
	v_mfma_f32_16x16x32_bf16 v[26:29], v[138:141], v[204:207], v[26:29]
	v_mfma_f32_16x16x32_bf16 v[14:17], v[130:133], v[212:215], v[14:17]
	v_mfma_f32_16x16x32_bf16 v[10:13], v[138:141], v[212:215], v[10:13]
	v_mfma_f32_16x16x32_bf16 v[90:93], v[134:137], v[182:185], v[90:93]
	v_mfma_f32_16x16x32_bf16 v[82:85], v[142:145], v[182:185], v[82:85]
	v_mfma_f32_16x16x32_bf16 v[46:49], v[134:137], v[200:203], v[46:49]
	v_mfma_f32_16x16x32_bf16 v[42:45], v[142:145], v[200:203], v[42:45]
	v_mfma_f32_16x16x32_bf16 v[30:33], v[134:137], v[208:211], v[30:33]
	v_mfma_f32_16x16x32_bf16 v[26:29], v[142:145], v[208:211], v[26:29]
	v_mfma_f32_16x16x32_bf16 v[14:17], v[134:137], v[216:219], v[14:17]
	v_mfma_f32_16x16x32_bf16 v[10:13], v[142:145], v[216:219], v[10:13]
	s_setprio 0
	s_setprio 1
	v_mfma_f32_16x16x32_bf16 v[74:77], v[156:159], v[172:175], v[74:77]
	v_mfma_f32_16x16x32_bf16 v[62:65], v[164:167], v[172:175], v[62:65]
	v_mfma_f32_16x16x32_bf16 v[38:41], v[156:159], v[196:199], v[38:41]
	v_mfma_f32_16x16x32_bf16 v[34:37], v[164:167], v[196:199], v[34:37]
	v_mfma_f32_16x16x32_bf16 v[22:25], v[156:159], v[204:207], v[22:25]
	v_mfma_f32_16x16x32_bf16 v[18:21], v[164:167], v[204:207], v[18:21]
	v_mfma_f32_16x16x32_bf16 v[6:9], v[156:159], v[212:215], v[6:9]
	v_mfma_f32_16x16x32_bf16 v[2:5], v[164:167], v[212:215], v[2:5]
	v_mfma_f32_16x16x32_bf16 v[74:77], v[160:163], v[182:185], v[74:77]
	v_mfma_f32_16x16x32_bf16 v[62:65], v[168:171], v[182:185], v[62:65]
	v_mfma_f32_16x16x32_bf16 v[38:41], v[160:163], v[200:203], v[38:41]
	v_mfma_f32_16x16x32_bf16 v[34:37], v[168:171], v[200:203], v[34:37]
	v_mfma_f32_16x16x32_bf16 v[22:25], v[160:163], v[208:211], v[22:25]
	v_mfma_f32_16x16x32_bf16 v[18:21], v[168:171], v[208:211], v[18:21]
	v_mfma_f32_16x16x32_bf16 v[6:9], v[160:163], v[216:219], v[6:9]
	v_mfma_f32_16x16x32_bf16 v[2:5], v[168:171], v[216:219], v[2:5]
	s_setprio 0
	s_barrier
; #define PG8_STAGE(bufoff, gbase, voff) do { _Pragma("unroll") for (int _i = 0; _i < 2; ++_i) \
;         __builtin_amdgcn_global_load_lds((const unsigned*)((const char*)(gbase) + (voff)[_i]), (PG8_LAS unsigned*)(lds + (bufoff) + ldsw + _i * 8192), 16, 0, 0); } while (0)
; #define PG8_LDA(dst, b, h) do { _Pragma("unroll") for (int m = 0; m < 4; ++m) _Pragma("unroll") for (int k = 0; k < 2; ++k) dst[m][k] = *(const PG8_LAS bf16x8*)(lds + PG8_SA(b, h) + aoff + m * 2048 + k * 1024); } while (0)
; #define PG8_LDB(dst, b, h) do { _Pragma("unroll") for (int n = 0; n < 2; ++n) _Pragma("unroll") for (int k = 0; k < 2; ++k) dst[n][k] = *(const PG8_LAS bf16x8*)(lds + PG8_SB(b, h) + boff + n * 2048 + k * 1024); } while (0)
; #define PG8_MMA(ai, bj, At, Bt) do { __builtin_amdgcn_s_setprio(1); _Pragma("unroll") for (int m = 0; m < 4; ++m) _Pragma("unroll") for (int n = 0; n < 2; ++n) _Pragma("unroll") for (int k = 0; k < 2; ++k) \
;         acc[ai][bj][m][n] = __builtin_amdgcn_mfma_f32_16x16x32_bf16(Bt[n][k], At[m][k], acc[ai][bj][m][n], 0, 0, 0); __builtin_amdgcn_s_setprio(0); } while (0)
; #define PG8_WAIT_V(n) asm volatile("s_waitcnt vmcnt(" #n ")" ::: "memory")
; #define PG8_WAIT_L(n) asm volatile("s_waitcnt lgkmcnt(" #n ")" ::: "memory")
; #define PG8_BAR __builtin_amdgcn_s_barrier()
; #define PG8_SCHED __builtin_amdgcn_sched_barrier(0)
; template <class Epi, class Sched, bool ALIGN_EPI = false, bool SP2 = false, bool ABLK = false, bool BBLK = false>
; __device__ __forceinline__ void gemm_phase(PG8_LAS unsigned char* lds, const Gemm g, const Sched& S, const Epi& E) {
;     ...
;             PG8_LDB(B0, 1, 0); PG8_LDB(B1, 1, 1); PG8_SCHED; PG8_LDA(At, 1, 0); PG8_STAGE(PG8_SA(0, 1), a2 + hstepA, voffA);
;             PG8_WAIT_V(8); PG8_WAIT_L(0); PG8_BAR; PG8_MMA(0, 0, At, B0); PG8_MMA(0, 1, At, B1); PG8_BAR; PG8_SCHED;
	s_add_i32 s52, 0, 0x18000
	s_add_i32 s75, 0, 0x1c000
	v_add_u32_e32 v142, s52, v180
	v_add_u32_e32 v168, s75, v180
	ds_read_b128 v[130:133], v142
	ds_read_b128 v[134:137], v142 offset:1024
	ds_read_b128 v[138:141], v142 offset:2048
	ds_read_b128 v[142:145], v142 offset:3072
	ds_read_b128 v[156:159], v168
	ds_read_b128 v[160:163], v168 offset:1024
	ds_read_b128 v[164:167], v168 offset:2048
	ds_read_b128 v[168:171], v168 offset:3072
	s_add_u32 s28, s28, 0x4000
	s_addc_u32 s29, s29, 0
	s_mov_b32 m0, s30
	v_lshl_add_u64 v[176:177], s[28:29], 0, v[146:147]
	ds_read_b128 v[172:175], v181 offset:32768
	ds_read_b128 v[182:185], v181 offset:33792
	ds_read_b128 v[196:199], v181 offset:34816
	ds_read_b128 v[200:203], v181 offset:35840
	ds_read_b128 v[204:207], v181 offset:36864
	ds_read_b128 v[208:211], v181 offset:37888
	ds_read_b128 v[212:215], v181 offset:38912
	ds_read_b128 v[216:219], v181 offset:39936
	global_load_lds_dwordx4 v[176:177], off
	v_lshl_add_u64 v[176:177], s[28:29], 0, v[148:149]
	s_mov_b32 m0, s31
	s_nop 0
	global_load_lds_dwordx4 v[176:177], off
	s_waitcnt vmcnt(8)
	s_waitcnt lgkmcnt(0)
	s_barrier
	s_setprio 1
	s_waitcnt lgkmcnt(0)
	v_mfma_f32_16x16x32_bf16 v[58:61], v[130:133], v[172:175], v[58:61]
	v_mfma_f32_16x16x32_bf16 v[50:53], v[138:141], v[172:175], v[50:53]
	v_mfma_f32_16x16x32_bf16 v[78:81], v[130:133], v[196:199], v[78:81]
	v_mfma_f32_16x16x32_bf16 v[70:73], v[138:141], v[196:199], v[70:73]
	v_mfma_f32_16x16x32_bf16 v[98:101], v[130:133], v[204:207], v[98:101]
	v_mfma_f32_16x16x32_bf16 v[102:105], v[138:141], v[204:207], v[102:105]
	v_mfma_f32_16x16x32_bf16 v[114:117], v[130:133], v[212:215], v[114:117]
	v_mfma_f32_16x16x32_bf16 v[118:121], v[138:141], v[212:215], v[118:121]
	v_mfma_f32_16x16x32_bf16 v[58:61], v[134:137], v[182:185], v[58:61]
	v_mfma_f32_16x16x32_bf16 v[50:53], v[142:145], v[182:185], v[50:53]
	v_mfma_f32_16x16x32_bf16 v[78:81], v[134:137], v[200:203], v[78:81]
	v_mfma_f32_16x16x32_bf16 v[70:73], v[142:145], v[200:203], v[70:73]
	v_mfma_f32_16x16x32_bf16 v[98:101], v[134:137], v[208:211], v[98:101]
	v_mfma_f32_16x16x32_bf16 v[102:105], v[142:145], v[208:211], v[102:105]
	v_mfma_f32_16x16x32_bf16 v[114:117], v[134:137], v[216:219], v[114:117]
	v_mfma_f32_16x16x32_bf16 v[118:121], v[142:145], v[216:219], v[118:121]
	s_setprio 0
	s_setprio 1
	v_mfma_f32_16x16x32_bf16 v[66:69], v[156:159], v[172:175], v[66:69]
	v_mfma_f32_16x16x32_bf16 v[54:57], v[164:167], v[172:175], v[54:57]
	v_mfma_f32_16x16x32_bf16 v[86:89], v[156:159], v[196:199], v[86:89]
	v_mfma_f32_16x16x32_bf16 v[94:97], v[164:167], v[196:199], v[94:97]
	v_mfma_f32_16x16x32_bf16 v[106:109], v[156:159], v[204:207], v[106:109]
	v_mfma_f32_16x16x32_bf16 v[110:113], v[164:167], v[204:207], v[110:113]
	v_mfma_f32_16x16x32_bf16 v[122:125], v[156:159], v[212:215], v[122:125]
	v_mfma_f32_16x16x32_bf16 v[126:129], v[164:167], v[212:215], v[126:129]
	v_mfma_f32_16x16x32_bf16 v[66:69], v[160:163], v[182:185], v[66:69]
	v_mfma_f32_16x16x32_bf16 v[54:57], v[168:171], v[182:185], v[54:57]
	v_mfma_f32_16x16x32_bf16 v[86:89], v[160:163], v[200:203], v[86:89]
	v_mfma_f32_16x16x32_bf16 v[94:97], v[168:171], v[200:203], v[94:97]
	v_mfma_f32_16x16x32_bf16 v[106:109], v[160:163], v[208:211], v[106:109]
	v_mfma_f32_16x16x32_bf16 v[110:113], v[168:171], v[208:211], v[110:113]
	v_mfma_f32_16x16x32_bf16 v[122:125], v[160:163], v[216:219], v[122:125]
	v_mfma_f32_16x16x32_bf16 v[126:129], v[168:171], v[216:219], v[126:129]
	s_setprio 0
	s_barrier
; #define PG8_STAGE(bufoff, gbase, voff) do { _Pragma("unroll") for (int _i = 0; _i < 2; ++_i) \
;         __builtin_amdgcn_global_load_lds((const unsigned*)((const char*)(gbase) + (voff)[_i]), (PG8_LAS unsigned*)(lds + (bufoff) + ldsw + _i * 8192), 16, 0, 0); } while (0)
; #define PG8_LDA(dst, b, h) do { _Pragma("unroll") for (int m = 0; m < 4; ++m) _Pragma("unroll") for (int k = 0; k < 2; ++k) dst[m][k] = *(const PG8_LAS bf16x8*)(lds + PG8_SA(b, h) + aoff + m * 2048 + k * 1024); } while (0)
; #define PG8_MMA(ai, bj, At, Bt) do { __builtin_amdgcn_s_setprio(1); _Pragma("unroll") for (int m = 0; m < 4; ++m) _Pragma("unroll") for (int n = 0; n < 2; ++n) _Pragma("unroll") for (int k = 0; k < 2; ++k) \
;         acc[ai][bj][m][n] = __builtin_amdgcn_mfma_f32_16x16x32_bf16(Bt[n][k], At[m][k], acc[ai][bj][m][n], 0, 0, 0); __builtin_amdgcn_s_setprio(0); } while (0)
; #define PG8_WAIT_V(n) asm volatile("s_waitcnt vmcnt(" #n ")" ::: "memory")
; #define PG8_WAIT_L(n) asm volatile("s_waitcnt lgkmcnt(" #n ")" ::: "memory")
; #define PG8_BAR __builtin_amdgcn_s_barrier()
; #define PG8_SCHED __builtin_amdgcn_sched_barrier(0)
; template <class Epi, class Sched, bool ALIGN_EPI = false, bool SP2 = false, bool ABLK = false, bool BBLK = false>
; __device__ __forceinline__ void gemm_phase(PG8_LAS unsigned char* lds, const Gemm g, const Sched& S, const Epi& E) {
;     ...
;             PG8_LDA(At, 1, 1); PG8_STAGE(PG8_SB(1, 0), b3, voffB); PG8_STAGE(PG8_SB(1, 1), b3 + hstepB, voffB); PG8_STAGE(PG8_SA(1, 0), a3, voffA);
;             PG8_WAIT_V(8); PG8_WAIT_L(0); PG8_BAR; PG8_MMA(1, 0, At, B0); PG8_MMA(1, 1, At, B1); PG8_BAR; PG8_SCHED;
;     ...
;         if constexpr (ALIGN_EPI) { if (wr == 0) PG8_BAR; }
	s_add_u32 s28, s26, 0x8000
	s_addc_u32 s29, s27, 0
	s_add_i32 s52, s52, s2
	v_lshl_add_u64 v[176:177], s[28:29], 0, v[186:187]
	s_mov_b32 m0, s52
	ds_read_b128 v[172:175], v181 offset:49152
	ds_read_b128 v[182:185], v181 offset:50176
	ds_read_b128 v[196:199], v181 offset:51200
	ds_read_b128 v[200:203], v181 offset:52224
	ds_read_b128 v[204:207], v181 offset:53248
	ds_read_b128 v[208:211], v181 offset:54272
	ds_read_b128 v[212:215], v181 offset:55296
	ds_read_b128 v[216:219], v181 offset:56320
	global_load_lds_dwordx4 v[176:177], off
	s_add_i32 m0, s52, 0x2000
	s_add_u32 s26, s26, 0xc000
	v_lshl_add_u64 v[176:177], s[28:29], 0, v[150:151]
	s_addc_u32 s27, s27, 0
	s_add_i32 s28, s75, s2
	global_load_lds_dwordx4 v[176:177], off
	v_lshl_add_u64 v[176:177], s[26:27], 0, v[186:187]
	s_mov_b32 m0, s28
	s_nop 0
	global_load_lds_dwordx4 v[176:177], off
	v_lshl_add_u64 v[176:177], s[26:27], 0, v[150:151]
	s_add_i32 m0, s28, 0x2000
	s_nop 0
	global_load_lds_dwordx4 v[176:177], off
	v_lshl_add_u64 v[176:177], s[8:9], 0, v[146:147]
	s_mov_b32 m0, s45
	s_nop 0
	global_load_lds_dwordx4 v[176:177], off
	v_lshl_add_u64 v[176:177], s[8:9], 0, v[148:149]
	s_mov_b32 m0, s46
	s_nop 0
	global_load_lds_dwordx4 v[176:177], off
	s_waitcnt vmcnt(8)
	s_waitcnt lgkmcnt(0)
	s_barrier
	s_setprio 1
	s_waitcnt lgkmcnt(0)
	v_mfma_f32_16x16x32_bf16 v[90:93], v[130:133], v[172:175], v[90:93]
	v_mfma_f32_16x16x32_bf16 v[82:85], v[138:141], v[172:175], v[82:85]
	v_mfma_f32_16x16x32_bf16 v[46:49], v[130:133], v[196:199], v[46:49]
	v_mfma_f32_16x16x32_bf16 v[42:45], v[138:141], v[196:199], v[42:45]
	v_mfma_f32_16x16x32_bf16 v[30:33], v[130:133], v[204:207], v[30:33]
	v_mfma_f32_16x16x32_bf16 v[26:29], v[138:141], v[204:207], v[26:29]
	v_mfma_f32_16x16x32_bf16 v[14:17], v[130:133], v[212:215], v[14:17]
	v_mfma_f32_16x16x32_bf16 v[10:13], v[138:141], v[212:215], v[10:13]
	v_mfma_f32_16x16x32_bf16 v[90:93], v[134:137], v[182:185], v[90:93]
	v_mfma_f32_16x16x32_bf16 v[82:85], v[142:145], v[182:185], v[82:85]
	v_mfma_f32_16x16x32_bf16 v[46:49], v[134:137], v[200:203], v[46:49]
	v_mfma_f32_16x16x32_bf16 v[42:45], v[142:145], v[200:203], v[42:45]
	v_mfma_f32_16x16x32_bf16 v[30:33], v[134:137], v[208:211], v[30:33]
	v_mfma_f32_16x16x32_bf16 v[26:29], v[142:145], v[208:211], v[26:29]
	v_mfma_f32_16x16x32_bf16 v[14:17], v[134:137], v[216:219], v[14:17]
	v_mfma_f32_16x16x32_bf16 v[10:13], v[142:145], v[216:219], v[10:13]
	s_setprio 0
	s_setprio 1
	v_mfma_f32_16x16x32_bf16 v[74:77], v[156:159], v[172:175], v[74:77]
	v_mfma_f32_16x16x32_bf16 v[62:65], v[164:167], v[172:175], v[62:65]
	v_mfma_f32_16x16x32_bf16 v[38:41], v[156:159], v[196:199], v[38:41]
	v_mfma_f32_16x16x32_bf16 v[34:37], v[164:167], v[196:199], v[34:37]
	v_mfma_f32_16x16x32_bf16 v[22:25], v[156:159], v[204:207], v[22:25]
	v_mfma_f32_16x16x32_bf16 v[18:21], v[164:167], v[204:207], v[18:21]
	v_mfma_f32_16x16x32_bf16 v[6:9], v[156:159], v[212:215], v[6:9]
	v_mfma_f32_16x16x32_bf16 v[2:5], v[164:167], v[212:215], v[2:5]
	v_mfma_f32_16x16x32_bf16 v[74:77], v[160:163], v[182:185], v[74:77]
	v_mfma_f32_16x16x32_bf16 v[62:65], v[168:171], v[182:185], v[62:65]
	v_mfma_f32_16x16x32_bf16 v[38:41], v[160:163], v[200:203], v[38:41]
	v_mfma_f32_16x16x32_bf16 v[34:37], v[168:171], v[200:203], v[34:37]
	v_mfma_f32_16x16x32_bf16 v[22:25], v[160:163], v[208:211], v[22:25]
	v_mfma_f32_16x16x32_bf16 v[18:21], v[168:171], v[208:211], v[18:21]
	v_mfma_f32_16x16x32_bf16 v[6:9], v[160:163], v[216:219], v[6:9]
	v_mfma_f32_16x16x32_bf16 v[2:5], v[168:171], v[216:219], v[2:5]
	s_setprio 0
	s_barrier
	s_add_i32 s73, s73, 2
	s_add_u32 s0, s0, 0x10000
	s_addc_u32 s1, s1, 0
	s_add_u32 s23, s23, 0x10000
	s_addc_u32 s25, s25, 0
	s_cmpk_gt_u32 s73, 0x55
	s_cbranch_scc0 .LBB0_1420
	s_and_b64 vcc, exec, s[14:15]
	s_cbranch_vccz .LBB0_1423
	s_barrier

;     __device__ __forceinline__ void operator()(f32x4 (&acc)[2][2][4][2], const Unit& u, int wr, int wc, int fr_, int fq_) const {
;     ...
;         if (lane < 32) { const float* slot = xbuf + ((size_t)u.pm * BM + row) * 8; float t8[8];
; #pragma unroll
;             for (int t = 0; t < 8; ++t) t8[t] = __hip_atomic_load(slot + t, __ATOMIC_RELAXED, __HIP_MEMORY_SCOPE_AGENT);
;             const float tot = ((t8[0] + t8[1]) + (t8[2] + t8[3])) + ((t8[4] + t8[5]) + (t8[6] + t8[7]));
;             S[row] = __builtin_amdgcn_rsqf(tot * (1.0f / DM) + 1e-6f); }
;         asm volatile("s_waitcnt lgkmcnt(0)" ::: "memory"); __builtin_amdgcn_s_barrier(); asm volatile("" ::: "memory");
; #pragma unroll
;         for (int ai = 0; ai < 2; ++ai)
; #pragma unroll
;             for (int m = 0; m < 4; ++m) { const int r = ai * HALF + wr * 64 + m * 16 + fr; const float rs = S[r];
; #pragma unroll
;                 for (int bj = 0; bj < 2; ++bj) { const f32x4 y0 = acc[ai][bj][m][0] * rs * av[bj][0] + sv[bj][0], y1 = acc[ai][bj][m][1] * rs * av[bj][1] + sv[bj][1];
;                     if (FINAL) { float* o = OUTF + ((size_t)u.pm * BM + r) * DM + col0 + bj * HALF; *(f32x4*)o = y0; *(f32x4*)(o + 4) = y1; }
.LBB0_1456:
	s_or_b64 exec, exec, s[0:1]
	v_lshl_add_u32 v160, v156, 2, 0
	s_waitcnt lgkmcnt(0)
	s_barrier
	v_add_u32_e32 v168, 0x21540, v160
	ds_read2_b32 v[164:165], v168 offset1:16
	s_lshl_b64 s[0:1], s[22:23], 21
	s_add_u32 s0, s33, s0
	v_lshlrev_b64 v[166:167], 13, v[156:157]
	s_addc_u32 s1, s34, s1
	s_waitcnt lgkmcnt(0)
	v_pk_mul_f32 v[50:51], v[50:51], v[164:165] op_sel_hi:[1,0]
	v_pk_mul_f32 v[52:53], v[52:53], v[164:165] op_sel_hi:[1,0]
	v_pk_mul_f32 v[58:59], v[58:59], v[164:165] op_sel_hi:[1,0]
	v_pk_mul_f32 v[60:61], v[60:61], v[164:165] op_sel_hi:[1,0]
	s_waitcnt vmcnt(3)
	v_pk_fma_f32 v[162:163], v[140:141], v[52:53], 0 op_sel_hi:[1,1,0]
	v_pk_fma_f32 v[160:161], v[138:139], v[50:51], 0 op_sel_hi:[1,1,0]
	v_lshl_add_u64 v[52:53], s[0:1], 0, v[166:167]
	v_lshlrev_b64 v[50:51], 2, v[158:159]
	s_waitcnt vmcnt(2)
	v_pk_fma_f32 v[60:61], v[144:145], v[60:61], 0 op_sel_hi:[1,1,0]
	v_pk_fma_f32 v[58:59], v[142:143], v[58:59], 0 op_sel_hi:[1,1,0]
	v_lshl_add_u64 v[158:159], v[52:53], 0, v[50:51]
	global_store_dwordx4 v[158:159], v[58:61], off
	global_store_dwordx4 v[158:159], v[160:163], off offset:16
	v_pk_mul_f32 v[52:53], v[66:67], v[164:165] op_sel_hi:[1,0]
	v_pk_mul_f32 v[58:59], v[68:69], v[164:165] op_sel_hi:[1,0]
	v_mov_b32_e32 v66, v165
	s_waitcnt vmcnt(2)
	v_pk_fma_f32 v[60:61], v[136:137], v[58:59], 0 op_sel_hi:[1,1,0]
	v_pk_fma_f32 v[58:59], v[134:135], v[52:53], 0 op_sel_hi:[1,1,0]
	v_pk_mul_f32 v[52:53], v[54:55], v[164:165] op_sel_hi:[1,0]
	v_pk_mul_f32 v[54:55], v[56:57], v[164:165] op_sel_hi:[1,0]
	v_pk_fma_f32 v[52:53], v[130:131], v[52:53], 0 op_sel_hi:[1,1,0]
	v_pk_fma_f32 v[54:55], v[132:133], v[54:55], 0 op_sel_hi:[1,1,0]
	global_store_dwordx4 v[158:159], v[58:61], off offset:512
	global_store_dwordx4 v[158:159], v[52:55], off offset:528
	v_pk_mul_f32 v[56:57], v[70:71], v[66:67] op_sel_hi:[1,0]
	v_pk_mul_f32 v[58:59], v[72:73], v[66:67] op_sel_hi:[1,0]
	v_add_u32_e32 v52, 16, v156
	v_ashrrev_i32_e32 v53, 31, v52
	v_lshlrev_b64 v[60:61], 13, v[52:53]
	v_pk_mul_f32 v[52:53], v[78:79], v[66:67] op_sel_hi:[1,0]
	v_pk_mul_f32 v[54:55], v[80:81], v[66:67] op_sel_hi:[1,0]
	v_lshl_add_u64 v[60:61], s[0:1], 0, v[60:61]
	v_pk_fma_f32 v[54:55], v[144:145], v[54:55], 0 op_sel_hi:[1,1,0]
	v_pk_fma_f32 v[52:53], v[142:143], v[52:53], 0 op_sel_hi:[1,1,0]
	v_lshl_add_u64 v[60:61], v[60:61], 0, v[50:51]
	v_pk_fma_f32 v[58:59], v[140:141], v[58:59], 0 op_sel_hi:[1,1,0]
	v_pk_fma_f32 v[56:57], v[138:139], v[56:57], 0 op_sel_hi:[1,1,0]
	global_store_dwordx4 v[60:61], v[52:55], off
	global_store_dwordx4 v[60:61], v[56:59], off offset:16
	s_and_b64 vcc, exec, s[6:7]
	v_pk_mul_f32 v[52:53], v[86:87], v[66:67] op_sel_hi:[1,0]
	v_pk_mul_f32 v[54:55], v[88:89], v[66:67] op_sel_hi:[1,0]
	v_pk_mul_f32 v[56:57], v[94:95], v[66:67] op_sel_hi:[1,0]
	v_pk_mul_f32 v[58:59], v[96:97], v[66:67] op_sel_hi:[1,0]
	ds_read2_b32 v[66:67], v168 offset0:32 offset1:48
	v_pk_fma_f32 v[54:55], v[136:137], v[54:55], 0 op_sel_hi:[1,1,0]
	v_pk_fma_f32 v[52:53], v[134:135], v[52:53], 0 op_sel_hi:[1,1,0]
	global_store_dwordx4 v[60:61], v[52:55], off offset:512
	v_pk_fma_f32 v[58:59], v[132:133], v[58:59], 0 op_sel_hi:[1,1,0]
	v_pk_fma_f32 v[56:57], v[130:131], v[56:57], 0 op_sel_hi:[1,1,0]
	v_add_u32_e32 v52, 32, v156
	v_ashrrev_i32_e32 v53, 31, v52
	global_store_dwordx4 v[60:61], v[56:59], off offset:528
	v_lshlrev_b64 v[60:61], 13, v[52:53]
	s_waitcnt lgkmcnt(0)
	v_pk_mul_f32 v[52:53], v[98:99], v[66:67] op_sel_hi:[1,0]
	v_pk_mul_f32 v[54:55], v[100:101], v[66:67] op_sel_hi:[1,0]
	v_lshl_add_u64 v[60:61], s[0:1], 0, v[60:61]
	v_pk_fma_f32 v[54:55], v[144:145], v[54:55], 0 op_sel_hi:[1,1,0]
	v_pk_fma_f32 v[52:53], v[142:143], v[52:53], 0 op_sel_hi:[1,1,0]
	v_pk_mul_f32 v[56:57], v[102:103], v[66:67] op_sel_hi:[1,0]
	v_pk_mul_f32 v[58:59], v[104:105], v[66:67] op_sel_hi:[1,0]
	v_lshl_add_u64 v[60:61], v[60:61], 0, v[50:51]
	v_pk_fma_f32 v[58:59], v[140:141], v[58:59], 0 op_sel_hi:[1,1,0]
	v_pk_fma_f32 v[56:57], v[138:139], v[56:57], 0 op_sel_hi:[1,1,0]
	global_store_dwordx4 v[60:61], v[52:55], off
	global_store_dwordx4 v[60:61], v[56:59], off offset:16
	s_nop 0
	v_pk_mul_f32 v[52:53], v[106:107], v[66:67] op_sel_hi:[1,0]
	v_pk_mul_f32 v[54:55], v[108:109], v[66:67] op_sel_hi:[1,0]
	v_pk_fma_f32 v[52:53], v[134:135], v[52:53], 0 op_sel_hi:[1,1,0]
	v_pk_fma_f32 v[54:55], v[136:137], v[54:55], 0 op_sel_hi:[1,1,0]
	v_pk_mul_f32 v[56:57], v[110:111], v[66:67] op_sel_hi:[1,0]
	v_pk_mul_f32 v[58:59], v[112:113], v[66:67] op_sel_hi:[1,0]
	v_pk_fma_f32 v[56:57], v[130:131], v[56:57], 0 op_sel_hi:[1,1,0]
	v_pk_fma_f32 v[58:59], v[132:133], v[58:59], 0 op_sel_hi:[1,1,0]
	global_store_dwordx4 v[60:61], v[52:55], off offset:512
	global_store_dwordx4 v[60:61], v[56:59], off offset:528
	v_mov_b32_e32 v66, v67
	v_add_u32_e32 v52, 48, v156
	v_ashrrev_i32_e32 v53, 31, v52
	v_lshlrev_b64 v[60:61], 13, v[52:53]
	v_pk_mul_f32 v[52:53], v[114:115], v[66:67] op_sel_hi:[1,0]
	v_pk_mul_f32 v[54:55], v[116:117], v[66:67] op_sel_hi:[1,0]
	v_lshl_add_u64 v[60:61], s[0:1], 0, v[60:61]
	v_pk_fma_f32 v[54:55], v[144:145], v[54:55], 0 op_sel_hi:[1,1,0]
	v_pk_fma_f32 v[52:53], v[142:143], v[52:53], 0 op_sel_hi:[1,1,0]
	v_pk_mul_f32 v[56:57], v[118:119], v[66:67] op_sel_hi:[1,0]
	v_pk_mul_f32 v[58:59], v[120:121], v[66:67] op_sel_hi:[1,0]
	v_lshl_add_u64 v[60:61], v[60:61], 0, v[50:51]
	v_pk_fma_f32 v[58:59], v[140:141], v[58:59], 0 op_sel_hi:[1,1,0]
	v_pk_fma_f32 v[56:57], v[138:139], v[56:57], 0 op_sel_hi:[1,1,0]
	global_store_dwordx4 v[60:61], v[52:55], off
	global_store_dwordx4 v[60:61], v[56:59], off offset:16
	s_nop 0
	v_pk_mul_f32 v[52:53], v[122:123], v[66:67] op_sel_hi:[1,0]
	v_pk_mul_f32 v[54:55], v[124:125], v[66:67] op_sel_hi:[1,0]
	v_pk_mul_f32 v[56:57], v[126:127], v[66:67] op_sel_hi:[1,0]
	v_pk_mul_f32 v[58:59], v[128:129], v[66:67] op_sel_hi:[1,0]
	ds_read2_b32 v[66:67], v168 offset0:128 offset1:144
	v_pk_fma_f32 v[54:55], v[136:137], v[54:55], 0 op_sel_hi:[1,1,0]
	v_pk_fma_f32 v[52:53], v[134:135], v[52:53], 0 op_sel_hi:[1,1,0]
	global_store_dwordx4 v[60:61], v[52:55], off offset:512
	v_pk_fma_f32 v[58:59], v[132:133], v[58:59], 0 op_sel_hi:[1,1,0]
	v_pk_fma_f32 v[56:57], v[130:131], v[56:57], 0 op_sel_hi:[1,1,0]
	v_add_u32_e32 v52, 0x80, v156
	v_ashrrev_i32_e32 v53, 31, v52
	global_store_dwordx4 v[60:61], v[56:59], off offset:528
	v_lshlrev_b64 v[60:61], 13, v[52:53]
	s_waitcnt lgkmcnt(0)
; #define PG8_BAR __builtin_amdgcn_s_barrier()
;     __device__ __forceinline__ void operator()(f32x4 (&acc)[2][2][4][2], const Unit& u, int wr, int wc, int fr_, int fq_) const {
;     ...
; #pragma unroll
;         for (int ai = 0; ai < 2; ++ai)
; #pragma unroll
;             for (int m = 0; m < 4; ++m) { const int r = ai * HALF + wr * 64 + m * 16 + fr; const float rs = S[r];
; #pragma unroll
;                 for (int bj = 0; bj < 2; ++bj) { const f32x4 y0 = acc[ai][bj][m][0] * rs * av[bj][0] + sv[bj][0], y1 = acc[ai][bj][m][1] * rs * av[bj][1] + sv[bj][1];
;                     if (FINAL) { float* o = OUTF + ((size_t)u.pm * BM + r) * DM + col0 + bj * HALF; *(f32x4*)o = y0; *(f32x4*)(o + 4) = y1; }
; template <class Epi, class Sched, bool ALIGN_EPI = false, bool SP2 = false, bool ABLK = false, bool BBLK = false>
; __device__ __forceinline__ void gemm_phase(PG8_LAS unsigned char* lds, const Gemm g, const Sched& S, const Epi& E) {
;     ...
;         if (!has_next) break;
; #pragma unroll
;         for (int a = 0; a < 2; ++a)
; #pragma unroll
;             for (int b = 0; b < 2; ++b)
; #pragma unroll
;                 for (int m = 0; m < 4; ++m)
; #pragma unroll
;                     for (int n = 0; n < 2; ++n) acc[a][b][m][n] = (f32x4){0.f, 0.f, 0.f, 0.f};
;         cur = nxt; cA = nA; cB = nB; ++ui;
;         if constexpr (ALIGN_EPI) { if (wr == 1) PG8_BAR; }
;     }
	v_pk_mul_f32 v[52:53], v[90:91], v[66:67] op_sel_hi:[1,0]
	v_pk_mul_f32 v[54:55], v[92:93], v[66:67] op_sel_hi:[1,0]
	v_lshl_add_u64 v[60:61], s[0:1], 0, v[60:61]
	v_pk_fma_f32 v[54:55], v[144:145], v[54:55], 0 op_sel_hi:[1,1,0]
	v_pk_fma_f32 v[52:53], v[142:143], v[52:53], 0 op_sel_hi:[1,1,0]
	v_pk_mul_f32 v[56:57], v[82:83], v[66:67] op_sel_hi:[1,0]
	v_pk_mul_f32 v[58:59], v[84:85], v[66:67] op_sel_hi:[1,0]
	v_lshl_add_u64 v[60:61], v[60:61], 0, v[50:51]
	v_pk_fma_f32 v[58:59], v[140:141], v[58:59], 0 op_sel_hi:[1,1,0]
	v_pk_fma_f32 v[56:57], v[138:139], v[56:57], 0 op_sel_hi:[1,1,0]
	global_store_dwordx4 v[60:61], v[52:55], off
	global_store_dwordx4 v[60:61], v[56:59], off offset:16
	s_nop 0
	v_pk_mul_f32 v[52:53], v[74:75], v[66:67] op_sel_hi:[1,0]
	v_pk_mul_f32 v[54:55], v[76:77], v[66:67] op_sel_hi:[1,0]
	v_pk_fma_f32 v[52:53], v[134:135], v[52:53], 0 op_sel_hi:[1,1,0]
	v_pk_fma_f32 v[54:55], v[136:137], v[54:55], 0 op_sel_hi:[1,1,0]
	v_pk_mul_f32 v[56:57], v[62:63], v[66:67] op_sel_hi:[1,0]
	v_pk_mul_f32 v[58:59], v[64:65], v[66:67] op_sel_hi:[1,0]
	v_pk_fma_f32 v[56:57], v[130:131], v[56:57], 0 op_sel_hi:[1,1,0]
	v_pk_fma_f32 v[58:59], v[132:133], v[58:59], 0 op_sel_hi:[1,1,0]
	global_store_dwordx4 v[60:61], v[52:55], off offset:512
	global_store_dwordx4 v[60:61], v[56:59], off offset:528
	s_nop 0
	v_add_u32_e32 v52, 0x90, v156
	v_ashrrev_i32_e32 v53, 31, v52
	v_lshlrev_b64 v[52:53], 13, v[52:53]
	v_mov_b32_e32 v54, v67
	v_pk_mul_f32 v[46:47], v[46:47], v[54:55] op_sel_hi:[1,0]
	v_pk_mul_f32 v[48:49], v[48:49], v[54:55] op_sel_hi:[1,0]
	v_lshl_add_u64 v[52:53], s[0:1], 0, v[52:53]
	v_pk_fma_f32 v[48:49], v[144:145], v[48:49], 0 op_sel_hi:[1,1,0]
	v_pk_fma_f32 v[46:47], v[142:143], v[46:47], 0 op_sel_hi:[1,1,0]
	v_pk_mul_f32 v[42:43], v[42:43], v[54:55] op_sel_hi:[1,0]
	v_pk_mul_f32 v[44:45], v[44:45], v[54:55] op_sel_hi:[1,0]
	v_lshl_add_u64 v[52:53], v[52:53], 0, v[50:51]
	v_pk_mul_f32 v[38:39], v[38:39], v[54:55] op_sel_hi:[1,0]
	v_pk_mul_f32 v[40:41], v[40:41], v[54:55] op_sel_hi:[1,0]
	v_pk_fma_f32 v[44:45], v[140:141], v[44:45], 0 op_sel_hi:[1,1,0]
	v_pk_fma_f32 v[42:43], v[138:139], v[42:43], 0 op_sel_hi:[1,1,0]
	global_store_dwordx4 v[52:53], v[46:49], off
	global_store_dwordx4 v[52:53], v[42:45], off offset:16
	v_pk_fma_f32 v[40:41], v[136:137], v[40:41], 0 op_sel_hi:[1,1,0]
	v_pk_fma_f32 v[38:39], v[134:135], v[38:39], 0 op_sel_hi:[1,1,0]
	v_pk_mul_f32 v[34:35], v[34:35], v[54:55] op_sel_hi:[1,0]
	v_pk_mul_f32 v[36:37], v[36:37], v[54:55] op_sel_hi:[1,0]
	global_store_dwordx4 v[52:53], v[38:41], off offset:512
	ds_read2_b32 v[38:39], v168 offset0:160 offset1:176
	v_pk_fma_f32 v[36:37], v[132:133], v[36:37], 0 op_sel_hi:[1,1,0]
	v_pk_fma_f32 v[34:35], v[130:131], v[34:35], 0 op_sel_hi:[1,1,0]
	global_store_dwordx4 v[52:53], v[34:37], off offset:528
	s_waitcnt lgkmcnt(0)
	v_pk_mul_f32 v[30:31], v[30:31], v[38:39] op_sel_hi:[1,0]
	v_add_u32_e32 v34, 0xa0, v156
	v_ashrrev_i32_e32 v35, 31, v34
	v_lshlrev_b64 v[34:35], 13, v[34:35]
	v_pk_mul_f32 v[32:33], v[32:33], v[38:39] op_sel_hi:[1,0]
	v_lshl_add_u64 v[34:35], s[0:1], 0, v[34:35]
	v_pk_mul_f32 v[22:23], v[22:23], v[38:39] op_sel_hi:[1,0]
	v_pk_mul_f32 v[24:25], v[24:25], v[38:39] op_sel_hi:[1,0]
	v_pk_mul_f32 v[18:19], v[18:19], v[38:39] op_sel_hi:[1,0]
	v_pk_fma_f32 v[32:33], v[144:145], v[32:33], 0 op_sel_hi:[1,1,0]
	v_pk_fma_f32 v[30:31], v[142:143], v[30:31], 0 op_sel_hi:[1,1,0]
	v_pk_mul_f32 v[26:27], v[26:27], v[38:39] op_sel_hi:[1,0]
	v_pk_mul_f32 v[28:29], v[28:29], v[38:39] op_sel_hi:[1,0]
	v_lshl_add_u64 v[34:35], v[34:35], 0, v[50:51]
	v_pk_fma_f32 v[24:25], v[136:137], v[24:25], 0 op_sel_hi:[1,1,0]
	v_pk_fma_f32 v[22:23], v[134:135], v[22:23], 0 op_sel_hi:[1,1,0]
	v_pk_mul_f32 v[20:21], v[20:21], v[38:39] op_sel_hi:[1,0]
	v_pk_fma_f32 v[18:19], v[130:131], v[18:19], 0 op_sel_hi:[1,1,0]
	v_pk_fma_f32 v[28:29], v[140:141], v[28:29], 0 op_sel_hi:[1,1,0]
	v_pk_fma_f32 v[26:27], v[138:139], v[26:27], 0 op_sel_hi:[1,1,0]
	global_store_dwordx4 v[34:35], v[30:33], off
	global_store_dwordx4 v[34:35], v[26:29], off offset:16
	v_pk_fma_f32 v[20:21], v[132:133], v[20:21], 0 op_sel_hi:[1,1,0]
	global_store_dwordx4 v[34:35], v[22:25], off offset:512
	global_store_dwordx4 v[34:35], v[18:21], off offset:528
	s_nop 1
	v_add_u32_e32 v18, 0xb0, v156
	v_ashrrev_i32_e32 v19, 31, v18
	v_lshlrev_b64 v[18:19], 13, v[18:19]
	v_mov_b32_e32 v20, v39
	v_pk_mul_f32 v[14:15], v[14:15], v[20:21] op_sel_hi:[1,0]
	v_pk_mul_f32 v[16:17], v[16:17], v[20:21] op_sel_hi:[1,0]
	v_lshl_add_u64 v[18:19], s[0:1], 0, v[18:19]
	v_pk_mul_f32 v[6:7], v[6:7], v[20:21] op_sel_hi:[1,0]
	v_pk_mul_f32 v[8:9], v[8:9], v[20:21] op_sel_hi:[1,0]
	v_pk_fma_f32 v[16:17], v[144:145], v[16:17], 0 op_sel_hi:[1,1,0]
	v_pk_fma_f32 v[14:15], v[142:143], v[14:15], 0 op_sel_hi:[1,1,0]
	v_pk_mul_f32 v[10:11], v[10:11], v[20:21] op_sel_hi:[1,0]
	v_pk_mul_f32 v[12:13], v[12:13], v[20:21] op_sel_hi:[1,0]
	v_lshl_add_u64 v[18:19], v[18:19], 0, v[50:51]
	v_pk_fma_f32 v[8:9], v[136:137], v[8:9], 0 op_sel_hi:[1,1,0]
	v_pk_fma_f32 v[6:7], v[134:135], v[6:7], 0 op_sel_hi:[1,1,0]
	v_pk_mul_f32 v[2:3], v[2:3], v[20:21] op_sel_hi:[1,0]
	v_pk_mul_f32 v[4:5], v[4:5], v[20:21] op_sel_hi:[1,0]
	s_mov_b64 s[0:1], -1
	v_pk_fma_f32 v[12:13], v[140:141], v[12:13], 0 op_sel_hi:[1,1,0]
	v_pk_fma_f32 v[10:11], v[138:139], v[10:11], 0 op_sel_hi:[1,1,0]
	global_store_dwordx4 v[18:19], v[14:17], off
	global_store_dwordx4 v[18:19], v[10:13], off offset:16
	v_pk_fma_f32 v[4:5], v[132:133], v[4:5], 0 op_sel_hi:[1,1,0]
	v_pk_fma_f32 v[2:3], v[130:131], v[2:3], 0 op_sel_hi:[1,1,0]
	global_store_dwordx4 v[18:19], v[6:9], off offset:512
	global_store_dwordx4 v[18:19], v[2:5], off offset:528
	s_cbranch_vccnz .LBB0_1412
	s_andn2_b64 vcc, exec, s[12:13]
	s_cbranch_vccnz .LBB0_1411
	s_branch .LBB0_1411

; #define PG8_WAIT_V(n) asm volatile("s_waitcnt vmcnt(" #n ")" ::: "memory")
; template <class Epi, class Sched, bool ALIGN_EPI = false, bool SP2 = false, bool ABLK = false, bool BBLK = false>
; __device__ __forceinline__ void gemm_phase(PG8_LAS unsigned char* lds, const Gemm g, const Sched& S, const Epi& E) {
;     ...
;     const int tid = tid_, wid = __builtin_amdgcn_readfirstlane(tid >> 6), lane = tid & 63, wr = wid >> 2, wc = wid & 3, fr = lane & 15, fq = lane >> 4;
;     const int K = g.K, nt = K / BK, LDA = g.lda ? g.lda : K, LDB = g.ldb ? g.ldb : K;
;     unsigned voffA[2], voffB[2];
; #pragma unroll
;     for (int i = 0; i < 2; ++i) { int R, C; stage_rc(tid * 16 + i * 8192, R, C); const int Rb = Epi::PERM ? ((R & ~31) + perm32(R & 31)) : R;
;         voffA[i] = ABLK ? (unsigned)(R * BK + C) * 2u : (unsigned)(R * LDA + C) * 2u; voffB[i] = BBLK ? (unsigned)(Rb * BK + C) * 2u : (unsigned)(Rb * LDB + C) * 2u; }
;     const size_t kstep = (size_t)(BK * 2);
;     const size_t hstepa = (size_t)HALF * LDA * 2, hstepb = (size_t)HALF * LDB * 2;
;     const size_t kstepA = ABLK ? (size_t)BM * BK * 2 : kstep, hstepA = ABLK ? (size_t)HALF * BK * 2 : hstepa, tstepA = ABLK ? (size_t)nt * BM * BK * 2 : 2 * hstepa;
;     const size_t kstepB = BBLK ? (size_t)BM * BK * 2 : kstep, hstepB = BBLK ? (size_t)HALF * BK * 2 : hstepb, tstepB = BBLK ? (size_t)nt * BM * BK * 2 : 2 * hstepb;
;     const unsigned ldsw = (unsigned)wid * 1024u;
;     const int aoff = lds_byte(wr * 64 + fr, fq * 8), boff = lds_byte(wc * 32 + fr, fq * 8);
;     ...
;     Unit cur, nxt; int ui = 0;
;     if (!S.next(0, cur)) return;
;     f32x4 acc[2][2][4][2];
; #pragma unroll
;     for (int a = 0; a < 2; ++a)
; #pragma unroll
;         for (int b = 0; b < 2; ++b)
; #pragma unroll
;             for (int m = 0; m < 4; ++m)
; #pragma unroll
;                 for (int n = 0; n < 2; ++n) acc[a][b][m][n] = (f32x4){0.f, 0.f, 0.f, 0.f};
;     bf16x8 At[4][2], B0[2][2], B1[2][2];
;     const char* cA = (const char*)g.A + (size_t)cur.pm * tstepA; const char* cB = (const char*)g.Bt + (size_t)cur.pn * tstepB;
;     S.a_ready(cur);
;     if constexpr (SP2) {
;         PG8_STAGE(PG8_SB(0, 0), cB, voffB); PG8_STAGE(PG8_SB(0, 1), cB + hstepB, voffB); PG8_STAGE(PG8_SA(0, 0), cA, voffA); PG8_STAGE(PG8_SA(0, 1), cA + hstepA, voffA);
;         if (wr == 1) PG8_BAR;
;         PG8_WAIT_V(2); PG8_BAR;
.LBB0_1467:
	s_andn2_b64 vcc, exec, s[0:1]
	s_cbranch_vccnz .LBB0_1522
	v_bfe_i32 v4, v2, 27, 1
	v_lshlrev_b32_e32 v6, 4, v2
	v_lshrrev_b32_e32 v4, 22, v4
	v_ashrrev_i32_e32 v3, 31, v2
	v_add_u32_e32 v4, v6, v4
	v_lshrrev_b32_e32 v3, 26, v3
	v_and_b32_e32 v4, 0xfffffc00, v4
	v_add_u32_e32 v3, v2, v3
	v_sub_u32_e32 v4, v6, v4
	v_ashrrev_i32_e32 v3, 6, v3
	v_lshrrev_b32_e32 v5, 4, v4
	v_bitop3_b32 v5, v5, v4, 32 bitop3:0x6c
	v_lshlrev_b32_e32 v4, 3, v3
	v_and_b32_e32 v7, -16, v4
	v_ashrrev_i32_e32 v4, 31, v5
	v_lshrrev_b32_e32 v4, 26, v4
	v_add_u32_e32 v8, v5, v4
	v_ashrrev_i32_e32 v4, 6, v8
	v_and_b32_e32 v8, 0xc0, v8
	v_sub_u32_e32 v5, v5, v8
	v_lshlrev_b32_e32 v9, 5, v3
	v_ashrrev_i16_sdwa v5, v232, sext(v5) dst_sel:DWORD dst_unused:UNUSED_PAD src0_sel:DWORD src1_sel:BYTE_0
	v_and_b32_e32 v9, 32, v9
	v_bfe_i32 v5, v5, 0, 16
	v_add_u32_e32 v7, v4, v7
	v_and_b32_e32 v11, 3, v4
	s_mov_b32 s0, 0x1ffffe0
	v_add_lshl_u32 v9, v9, v5, 1
	v_lshlrev_b32_e32 v8, 1, v7
	v_lshrrev_b32_e32 v10, 2, v7
	v_and_or_b32 v11, v7, s0, v11
	v_lshl_add_u32 v178, v7, 7, v9
	v_add_u32_e32 v7, 0x2000, v6
	v_ashrrev_i32_e32 v6, 31, v7
	v_lshrrev_b32_e32 v6, 22, v6
	v_and_b32_e32 v8, 24, v8
	v_and_b32_e32 v10, 4, v10
	v_add_u32_e32 v6, v7, v6
	v_or3_b32 v8, v11, v10, v8
	v_ashrrev_i32_e32 v6, 10, v6
	v_lshl_add_u32 v186, v8, 7, v9
	v_mul_i32_i24_e32 v8, 0x400, v6
	v_sub_u32_e32 v7, v7, v8
	v_lshrrev_b32_e32 v8, 4, v7
	v_bitop3_b32 v8, v8, v7, 32 bitop3:0x6c
	v_lshlrev_b32_e32 v7, 3, v6
	v_and_b32_e32 v9, -16, v7
	v_ashrrev_i32_e32 v7, 31, v8
	v_lshrrev_b32_e32 v7, 26, v7
	v_add_u32_e32 v10, v8, v7
	s_ashr_i32 s9, s8, 6
	v_ashrrev_i32_e32 v7, 6, v10
	v_add_u32_e32 v9, v7, v9
	v_and_b32_e32 v10, 0xc0, v10
	v_and_b32_e32 v13, 3, v7
	s_ashr_i32 s16, s8, 8
	s_lshl_b32 s65, s9, 10
	s_mul_i32 s1, s30, 0x2c0000
	v_sub_u32_e32 v8, v8, v10
	v_and_or_b32 v13, v9, s0, v13
	s_mul_hi_i32 s0, s30, 0x2c0000
	s_add_u32 s36, s90, s1
	v_lshlrev_b32_e32 v11, 5, v6
	v_ashrrev_i16_sdwa v8, v232, sext(v8) dst_sel:DWORD dst_unused:UNUSED_PAD src0_sel:DWORD src1_sel:BYTE_0
	v_lshlrev_b32_e32 v10, 1, v9
	v_lshrrev_b32_e32 v12, 2, v9
	s_addc_u32 s37, s96, s0
	s_add_i32 s68, s65, 0
	v_and_b32_e32 v11, 32, v11
	v_bfe_i32 v8, v8, 0, 16
	v_and_b32_e32 v10, 24, v10
	v_and_b32_e32 v12, 4, v12
	s_add_i32 m0, s68, 0x10000
	v_or3_b32 v10, v13, v12, v10
	v_add_lshl_u32 v11, v11, v8, 1
	global_load_lds_dwordx4 v186, s[36:37]
	s_add_i32 m0, s68, 0x12000
	v_lshl_add_u32 v182, v10, 7, v11
	s_add_u32 s0, s36, 0x4000
	global_load_lds_dwordx4 v182, s[36:37]
	s_addc_u32 s1, s37, 0
	s_add_i32 m0, s68, 0x14000
	s_mul_i32 s3, s34, 0x2c0000
	global_load_lds_dwordx4 v186, s[0:1]
	s_add_i32 m0, s68, 0x16000
	s_mul_hi_i32 s2, s34, 0x2c0000
	global_load_lds_dwordx4 v182, s[0:1]
	s_add_u32 s0, s83, s3
	s_addc_u32 s1, s84, s2
	s_add_i32 s72, s68, 0x2000
	s_mov_b32 m0, s68
	s_add_u32 s2, s0, 0x4000
	v_lshl_add_u32 v180, v9, 7, v11
	global_load_lds_dwordx4 v178, s[0:1]
	s_mov_b32 m0, s72
	s_addc_u32 s3, s1, 0
	s_add_i32 s73, s68, 0x4000
	s_mov_b32 s91, s84
	global_load_lds_dwordx4 v180, s[0:1]
	s_mov_b32 m0, s73
	s_add_i32 s84, s68, 0x6000
	global_load_lds_dwordx4 v178, s[2:3]
	s_mov_b32 m0, s84
	s_load_dwordx2 s[6:7], s[4:5], 0x30
	global_load_lds_dwordx4 v180, s[2:3]
	v_writelane_b32 v254, s90, 36
	s_cmp_eq_u32 s16, 1
	v_writelane_b32 v254, s96, 38
	s_cselect_b64 s[2:3], -1, 0
	s_mov_b32 s82, 0x30000
	s_mov_b32 s80, 0x10000
	s_mov_b32 s75, 0x20000
	s_mov_b32 s90, s83
	v_writelane_b32 v254, s2, 39
	s_cmp_lg_u32 s16, 1
	s_nop 0
	v_writelane_b32 v254, s3, 40
	s_cbranch_scc1 .LBB0_1470
.LBB0_1470:
	v_writelane_b32 v254, s92, 24
	s_lshl_b64 s[2:3], s[92:93], 2
	v_mov_b32_e32 v183, v187
	v_writelane_b32 v254, s93, 25
	s_waitcnt vmcnt(2)
	s_barrier
	v_readlane_b32 s4, v254, 26
	v_readlane_b32 s5, v254, 27
	s_add_u32 s12, s4, s2
	s_addc_u32 s13, s5, s3
	s_add_u32 s14, s43, 0x1500000
	s_addc_u32 s15, s50, 0
	s_waitcnt lgkmcnt(0)
	s_add_u32 s18, s6, 0x2000
	s_addc_u32 s19, s7, 0
	s_add_u32 s92, s43, 0x232000
	s_addc_u32 s93, s50, 0
	s_add_u32 s94, s43, 0xf600000
	s_addc_u32 s95, s50, 0
	s_add_u32 s96, s43, 0xf400000
	s_addc_u32 s97, s50, 0
	s_add_u32 s4, s43, 0x14800
	s_addc_u32 s5, s50, 0
	s_and_b32 s26, s9, 3
	s_lshl_b32 s2, s16, 6
	s_lshl_b32 s20, s16, 13
	s_lshl_b32 s3, s26, 5
	s_lshl_b32 s21, s26, 12
	s_add_u32 s6, s36, 0x8000
	s_addc_u32 s7, s37, 0
	s_add_i32 m0, s68, 0x18000
	v_lshl_add_u64 v[10:11], s[6:7], 0, v[186:187]
	global_load_lds_dwordx4 v[10:11], off
	s_add_i32 m0, s68, 0x1a000
	v_lshl_add_u64 v[10:11], s[6:7], 0, v[182:183]
	s_add_u32 s6, s0, 0x8000
	v_mov_b32_e32 v179, v187
	s_addc_u32 s7, s1, 0
	s_add_i32 s24, s68, 0x8000
	v_mov_b32_e32 v181, v187
	global_load_lds_dwordx4 v[10:11], off
	v_lshl_add_u64 v[10:11], s[6:7], 0, v[178:179]
	s_mov_b32 m0, s24
	s_add_i32 s25, s68, 0xa000
	global_load_lds_dwordx4 v[10:11], off
	v_lshl_add_u64 v[10:11], s[6:7], 0, v[180:181]
	s_add_u32 s6, s36, 0xc000
	s_mov_b32 m0, s25
	s_addc_u32 s7, s37, 0
	global_load_lds_dwordx4 v[10:11], off
	s_add_i32 m0, s68, 0x1c000
	v_lshl_add_u64 v[10:11], s[6:7], 0, v[186:187]
	global_load_lds_dwordx4 v[10:11], off
	v_lshl_add_u64 v[10:11], s[6:7], 0, v[182:183]
	s_add_i32 m0, s68, 0x1e000
	v_bfe_u32 v205, v2, 4, 2
	global_load_lds_dwordx4 v[10:11], off
	v_and_b32_e32 v204, 15, v2
	v_lshlrev_b32_e32 v9, 4, v205
	v_lshlrev_b32_e32 v2, 2, v2
	v_lshl_or_b32 v9, v204, 6, v9
	v_and_b32_e32 v2, 32, v2
	s_cmpk_lt_u32 s8, 0x100
	v_bitop3_b32 v10, v9, s20, v2 bitop3:0xde
	v_bitop3_b32 v206, v9, s21, v2 bitop3:0xde
	s_cselect_b64 s[20:21], -1, 0
	s_lshl_b32 s6, s16, 2
	s_or_b32 s53, s6, s26
	s_lshl_b32 s56, s53, 5
	s_bfe_u32 s22, s9, 0x10001
	s_and_b32 s6, s3, 32
	s_ashr_i32 s81, s42, 31
	s_ashr_i32 s83, s51, 31
	s_cmpk_lg_i32 s42, 0x100
	s_cselect_b64 s[8:9], -1, 0
	v_writelane_b32 v254, s8, 41
	s_and_b32 s7, s51, 7
	s_lshl_b32 s7, s7, 2
	v_writelane_b32 v254, s9, 42
	v_writelane_b32 v254, s7, 46
	s_bfe_u32 s7, s51, 0x20001
	v_lshlrev_b32_e32 v2, 10, v3
	s_or_b32 s7, s7, 32
	v_and_b32_e32 v2, 0xfffff800, v2
	v_writelane_b32 v254, s7, 48
	s_lshl_b32 s7, s51, 4
	v_lshl_add_u32 v2, v4, 7, v2
	v_and_b32_e32 v3, 1, v3
	s_and_b32 s7, s7, 16
	v_lshl_or_b32 v2, v3, 6, v2
	s_ashr_i32 s8, s51, 3
	v_writelane_b32 v254, s7, 50
	v_lshl_add_u32 v184, v5, 1, v2
	v_lshlrev_b32_e32 v2, 10, v6
	v_writelane_b32 v254, s8, 30
	s_and_b32 s7, s8, 3
	v_and_b32_e32 v2, 0xfffff800, v2
	s_waitcnt vmcnt(6)
	v_writelane_b32 v254, s7, 55
	s_lshl_b32 s7, s26, 2
	v_lshl_add_u32 v2, v7, 7, v2
	v_and_b32_e32 v3, 1, v6
	s_add_i32 s88, s7, 0
	v_lshl_or_b32 v2, v3, 6, v2
	s_mov_b32 s23, s17
	s_add_i32 s88, s88, 0x20540
	v_mov_b32_e32 v185, v187
	v_lshl_add_u32 v196, v8, 1, v2
	v_mov_b32_e32 v197, v187
	s_mov_b32 s28, 0
	v_add_u32_e32 v207, 0, v10
	s_lshl_b32 s16, s6, 1
	s_barrier
	s_branch .LBB0_1473

; #define PG8_STAGE(bufoff, gbase, voff) do { _Pragma("unroll") for (int _i = 0; _i < 2; ++_i) \
;         __builtin_amdgcn_global_load_lds((const unsigned*)((const char*)(gbase) + (voff)[_i]), (PG8_LAS unsigned*)(lds + (bufoff) + ldsw + _i * 8192), 16, 0, 0); } while (0)
; #define PG8_LDA(dst, b, h) do { _Pragma("unroll") for (int m = 0; m < 4; ++m) _Pragma("unroll") for (int k = 0; k < 2; ++k) dst[m][k] = *(const PG8_LAS bf16x8*)(lds + PG8_SA(b, h) + aoff + m * 2048 + k * 1024); } while (0)
; #define PG8_LDB(dst, b, h) do { _Pragma("unroll") for (int n = 0; n < 2; ++n) _Pragma("unroll") for (int k = 0; k < 2; ++k) dst[n][k] = *(const PG8_LAS bf16x8*)(lds + PG8_SB(b, h) + boff + n * 2048 + k * 1024); } while (0)
; #define PG8_MMA(ai, bj, At, Bt) do { __builtin_amdgcn_s_setprio(1); _Pragma("unroll") for (int m = 0; m < 4; ++m) _Pragma("unroll") for (int n = 0; n < 2; ++n) _Pragma("unroll") for (int k = 0; k < 2; ++k) \
;         acc[ai][bj][m][n] = __builtin_amdgcn_mfma_f32_16x16x32_bf16(Bt[n][k], At[m][k], acc[ai][bj][m][n], 0, 0, 0); __builtin_amdgcn_s_setprio(0); } while (0)
; #define PG8_WAIT_V(n) asm volatile("s_waitcnt vmcnt(" #n ")" ::: "memory")
; #define PG8_WAIT_L(n) asm volatile("s_waitcnt lgkmcnt(" #n ")" ::: "memory")
; #define PG8_BAR __builtin_amdgcn_s_barrier()
; #define PG8_SCHED __builtin_amdgcn_sched_barrier(0)
; template <class Epi, class Sched, bool ALIGN_EPI = false, bool SP2 = false, bool ABLK = false, bool BBLK = false>
; __device__ __forceinline__ void gemm_phase(PG8_LAS unsigned char* lds, const Gemm g, const Sched& S, const Epi& E) {
;     ...
;             PG8_LDB(B0, 0, 0); PG8_LDB(B1, 0, 1); PG8_SCHED; PG8_LDA(At, 0, 0); PG8_STAGE(PG8_SA(1, 1), a1 + hstepA, voffA);
;             PG8_WAIT_V(8); PG8_WAIT_L(0); PG8_BAR; PG8_MMA(0, 0, At, B0); PG8_MMA(0, 1, At, B1); PG8_BAR; PG8_SCHED;
;     ...
;         for (int a = 0; a < 2; ++a)
; #pragma unroll
;             for (int b = 0; b < 2; ++b)
; #pragma unroll
;                 for (int m = 0; m < 4; ++m)
; #pragma unroll
;                     for (int n = 0; n < 2; ++n) acc[a][b][m][n] = (f32x4){0.f, 0.f, 0.f, 0.f};
;         cur = nxt; cA = nA; cB = nB; ++ui;
;         if constexpr (ALIGN_EPI) { if (wr == 1) PG8_BAR; }
.LBB0_1482:
	s_add_u32 s0, s0, 0xc000
	s_addc_u32 s1, s1, 0
	s_add_u32 s31, s36, 0x10000
	v_mov_b32_e32 v2, 0
	s_addc_u32 s33, s37, 0
	s_mov_b32 s35, -2
	v_mov_b32_e32 v3, v2
	v_mov_b32_e32 v4, v2
	v_mov_b32_e32 v5, v2
	v_mov_b32_e32 v6, v2
	v_mov_b32_e32 v7, v2
	v_mov_b32_e32 v8, v2
	v_mov_b32_e32 v9, v2
	v_mov_b32_e32 v58, v2
	v_mov_b32_e32 v59, v2
	v_mov_b32_e32 v60, v2
	v_mov_b32_e32 v61, v2
	v_mov_b32_e32 v62, v2
	v_mov_b32_e32 v63, v2
	v_mov_b32_e32 v64, v2
	v_mov_b32_e32 v65, v2
	v_mov_b32_e32 v98, v2
	v_mov_b32_e32 v99, v2
	v_mov_b32_e32 v100, v2
	v_mov_b32_e32 v101, v2
	v_mov_b32_e32 v102, v2
	v_mov_b32_e32 v103, v2
	v_mov_b32_e32 v104, v2
	v_mov_b32_e32 v105, v2
	v_mov_b32_e32 v118, v2
	v_mov_b32_e32 v119, v2
	v_mov_b32_e32 v120, v2
	v_mov_b32_e32 v121, v2
	v_mov_b32_e32 v114, v2
	v_mov_b32_e32 v115, v2
	v_mov_b32_e32 v116, v2
	v_mov_b32_e32 v117, v2
	v_mov_b32_e32 v34, v2
	v_mov_b32_e32 v35, v2
	v_mov_b32_e32 v36, v2
	v_mov_b32_e32 v37, v2
	v_mov_b32_e32 v38, v2
	v_mov_b32_e32 v39, v2
	v_mov_b32_e32 v40, v2
	v_mov_b32_e32 v41, v2
	v_mov_b32_e32 v90, v2
	v_mov_b32_e32 v91, v2
	v_mov_b32_e32 v92, v2
	v_mov_b32_e32 v93, v2
	v_mov_b32_e32 v94, v2
	v_mov_b32_e32 v95, v2
	v_mov_b32_e32 v96, v2
	v_mov_b32_e32 v97, v2
	v_mov_b32_e32 v126, v2
	v_mov_b32_e32 v127, v2
	v_mov_b32_e32 v128, v2
	v_mov_b32_e32 v129, v2
	v_mov_b32_e32 v122, v2
	v_mov_b32_e32 v123, v2
	v_mov_b32_e32 v124, v2
	v_mov_b32_e32 v125, v2
	v_mov_b32_e32 v110, v2
	v_mov_b32_e32 v111, v2
	v_mov_b32_e32 v112, v2
	v_mov_b32_e32 v113, v2
	v_mov_b32_e32 v106, v2
	v_mov_b32_e32 v107, v2
	v_mov_b32_e32 v108, v2
	v_mov_b32_e32 v109, v2
	v_mov_b32_e32 v86, v2
	v_mov_b32_e32 v87, v2
	v_mov_b32_e32 v88, v2
	v_mov_b32_e32 v89, v2
	v_mov_b32_e32 v82, v2
	v_mov_b32_e32 v83, v2
	v_mov_b32_e32 v84, v2
	v_mov_b32_e32 v85, v2
	v_mov_b32_e32 v70, v2
	v_mov_b32_e32 v71, v2
	v_mov_b32_e32 v72, v2
	v_mov_b32_e32 v73, v2
	v_mov_b32_e32 v66, v2
	v_mov_b32_e32 v67, v2
	v_mov_b32_e32 v68, v2
	v_mov_b32_e32 v69, v2
	v_mov_b32_e32 v46, v2
	v_mov_b32_e32 v47, v2
	v_mov_b32_e32 v48, v2
	v_mov_b32_e32 v49, v2
	v_mov_b32_e32 v42, v2
	v_mov_b32_e32 v43, v2
	v_mov_b32_e32 v44, v2
	v_mov_b32_e32 v45, v2
	v_mov_b32_e32 v14, v2
	v_mov_b32_e32 v15, v2
	v_mov_b32_e32 v16, v2
	v_mov_b32_e32 v17, v2
	v_mov_b32_e32 v26, v2
	v_mov_b32_e32 v27, v2
	v_mov_b32_e32 v28, v2
	v_mov_b32_e32 v29, v2
	v_mov_b32_e32 v78, v2
	v_mov_b32_e32 v79, v2
	v_mov_b32_e32 v80, v2
	v_mov_b32_e32 v81, v2
	v_mov_b32_e32 v74, v2
	v_mov_b32_e32 v75, v2
	v_mov_b32_e32 v76, v2
	v_mov_b32_e32 v77, v2
	v_mov_b32_e32 v54, v2
	v_mov_b32_e32 v55, v2
	v_mov_b32_e32 v56, v2
	v_mov_b32_e32 v57, v2
	v_mov_b32_e32 v50, v2
	v_mov_b32_e32 v51, v2
	v_mov_b32_e32 v52, v2
	v_mov_b32_e32 v53, v2
	v_mov_b32_e32 v10, v2
	v_mov_b32_e32 v11, v2
	v_mov_b32_e32 v12, v2
	v_mov_b32_e32 v13, v2
	v_mov_b32_e32 v18, v2
	v_mov_b32_e32 v19, v2
	v_mov_b32_e32 v20, v2
	v_mov_b32_e32 v21, v2
	v_mov_b32_e32 v22, v2
	v_mov_b32_e32 v23, v2
	v_mov_b32_e32 v24, v2
	v_mov_b32_e32 v25, v2
	v_mov_b32_e32 v30, v2
	v_mov_b32_e32 v31, v2
	v_mov_b32_e32 v32, v2
	v_mov_b32_e32 v33, v2
	s_and_b64 vcc, exec, s[20:21]
	s_cbranch_vccnz .Lrb_f2b1
	s_barrier
.Lrb_f2b1:
.LBB0_1483:
	s_add_u32 s8, s0, 0x4000
	s_addc_u32 s9, s1, 0
	s_cmpk_eq_i32 s35, 0x54
	s_cselect_b32 s40, s26, s8
	s_cselect_b32 s41, s27, s9
	s_cselect_b32 s36, s28, s31
	s_cselect_b32 s37, s29, s33
	s_add_u32 s8, s40, 0x8000
	s_addc_u32 s9, s41, 0
	s_add_i32 s44, 0, 0x10000
	s_add_i32 s52, 0, 0x14000
	v_add_u32_e32 v142, s44, v206
	v_add_u32_e32 v158, s52, v206
	ds_read_b128 v[130:133], v142
	ds_read_b128 v[134:137], v142 offset:1024
	ds_read_b128 v[138:141], v142 offset:2048
	ds_read_b128 v[142:145], v142 offset:3072
	ds_read_b128 v[146:149], v158
	ds_read_b128 v[150:153], v158 offset:1024
	ds_read_b128 v[154:157], v158 offset:2048
	ds_read_b128 v[158:161], v158 offset:3072
	v_lshl_add_u64 v[188:189], s[0:1], 0, v[184:185]
	s_add_i32 m0, s68, 0xc000
	ds_read_b128 v[162:165], v207
	ds_read_b128 v[166:169], v207 offset:1024
	ds_read_b128 v[170:173], v207 offset:2048
	ds_read_b128 v[174:177], v207 offset:3072
	ds_read_b128 v[198:201], v207 offset:4096
	ds_read_b128 v[208:211], v207 offset:5120
	ds_read_b128 v[212:215], v207 offset:6144
	ds_read_b128 v[216:219], v207 offset:7168
	global_load_lds_dwordx4 v[188:189], off
	v_lshl_add_u64 v[188:189], s[0:1], 0, v[196:197]
	s_add_i32 m0, s68, 0xe000
	s_nop 0
	global_load_lds_dwordx4 v[188:189], off
	s_waitcnt vmcnt(8)
	s_waitcnt lgkmcnt(0)
	s_barrier
	s_setprio 1
	s_waitcnt lgkmcnt(0)
	v_mfma_f32_16x16x32_bf16 v[30:33], v[130:133], v[162:165], v[30:33]
	v_mfma_f32_16x16x32_bf16 v[22:25], v[138:141], v[162:165], v[22:25]
	v_mfma_f32_16x16x32_bf16 v[18:21], v[130:133], v[170:173], v[18:21]
	v_mfma_f32_16x16x32_bf16 v[10:13], v[138:141], v[170:173], v[10:13]
	v_mfma_f32_16x16x32_bf16 v[50:53], v[130:133], v[198:201], v[50:53]
	v_mfma_f32_16x16x32_bf16 v[54:57], v[138:141], v[198:201], v[54:57]
	v_mfma_f32_16x16x32_bf16 v[74:77], v[130:133], v[212:215], v[74:77]
	v_mfma_f32_16x16x32_bf16 v[78:81], v[138:141], v[212:215], v[78:81]
	v_mfma_f32_16x16x32_bf16 v[30:33], v[134:137], v[166:169], v[30:33]
	v_mfma_f32_16x16x32_bf16 v[22:25], v[142:145], v[166:169], v[22:25]
	v_mfma_f32_16x16x32_bf16 v[18:21], v[134:137], v[174:177], v[18:21]
	v_mfma_f32_16x16x32_bf16 v[10:13], v[142:145], v[174:177], v[10:13]
	v_mfma_f32_16x16x32_bf16 v[50:53], v[134:137], v[208:211], v[50:53]
	v_mfma_f32_16x16x32_bf16 v[54:57], v[142:145], v[208:211], v[54:57]
	v_mfma_f32_16x16x32_bf16 v[74:77], v[134:137], v[216:219], v[74:77]
	v_mfma_f32_16x16x32_bf16 v[78:81], v[142:145], v[216:219], v[78:81]
	s_setprio 0
	s_setprio 1
	v_mfma_f32_16x16x32_bf16 v[26:29], v[146:149], v[162:165], v[26:29]
	v_mfma_f32_16x16x32_bf16 v[14:17], v[154:157], v[162:165], v[14:17]
	v_mfma_f32_16x16x32_bf16 v[42:45], v[146:149], v[170:173], v[42:45]
	v_mfma_f32_16x16x32_bf16 v[46:49], v[154:157], v[170:173], v[46:49]
	v_mfma_f32_16x16x32_bf16 v[66:69], v[146:149], v[198:201], v[66:69]
	v_mfma_f32_16x16x32_bf16 v[70:73], v[154:157], v[198:201], v[70:73]
	v_mfma_f32_16x16x32_bf16 v[82:85], v[146:149], v[212:215], v[82:85]
	v_mfma_f32_16x16x32_bf16 v[86:89], v[154:157], v[212:215], v[86:89]
	v_mfma_f32_16x16x32_bf16 v[26:29], v[150:153], v[166:169], v[26:29]
	v_mfma_f32_16x16x32_bf16 v[14:17], v[158:161], v[166:169], v[14:17]
	v_mfma_f32_16x16x32_bf16 v[42:45], v[150:153], v[174:177], v[42:45]
	v_mfma_f32_16x16x32_bf16 v[46:49], v[158:161], v[174:177], v[46:49]
	v_mfma_f32_16x16x32_bf16 v[66:69], v[150:153], v[208:211], v[66:69]
	v_mfma_f32_16x16x32_bf16 v[70:73], v[158:161], v[208:211], v[70:73]
	v_mfma_f32_16x16x32_bf16 v[82:85], v[150:153], v[216:219], v[82:85]
	v_mfma_f32_16x16x32_bf16 v[86:89], v[158:161], v[216:219], v[86:89]
	s_setprio 0
	s_barrier
; #define PG8_STAGE(bufoff, gbase, voff) do { _Pragma("unroll") for (int _i = 0; _i < 2; ++_i) \
;         __builtin_amdgcn_global_load_lds((const unsigned*)((const char*)(gbase) + (voff)[_i]), (PG8_LAS unsigned*)(lds + (bufoff) + ldsw + _i * 8192), 16, 0, 0); } while (0)
; #define PG8_LDA(dst, b, h) do { _Pragma("unroll") for (int m = 0; m < 4; ++m) _Pragma("unroll") for (int k = 0; k < 2; ++k) dst[m][k] = *(const PG8_LAS bf16x8*)(lds + PG8_SA(b, h) + aoff + m * 2048 + k * 1024); } while (0)
; #define PG8_LDB(dst, b, h) do { _Pragma("unroll") for (int n = 0; n < 2; ++n) _Pragma("unroll") for (int k = 0; k < 2; ++k) dst[n][k] = *(const PG8_LAS bf16x8*)(lds + PG8_SB(b, h) + boff + n * 2048 + k * 1024); } while (0)
; #define PG8_MMA(ai, bj, At, Bt) do { __builtin_amdgcn_s_setprio(1); _Pragma("unroll") for (int m = 0; m < 4; ++m) _Pragma("unroll") for (int n = 0; n < 2; ++n) _Pragma("unroll") for (int k = 0; k < 2; ++k) \
;         acc[ai][bj][m][n] = __builtin_amdgcn_mfma_f32_16x16x32_bf16(Bt[n][k], At[m][k], acc[ai][bj][m][n], 0, 0, 0); __builtin_amdgcn_s_setprio(0); } while (0)
; #define PG8_WAIT_V(n) asm volatile("s_waitcnt vmcnt(" #n ")" ::: "memory")
; #define PG8_WAIT_L(n) asm volatile("s_waitcnt lgkmcnt(" #n ")" ::: "memory")
; #define PG8_BAR __builtin_amdgcn_s_barrier()
; #define PG8_SCHED __builtin_amdgcn_sched_barrier(0)
; template <class Epi, class Sched, bool ALIGN_EPI = false, bool SP2 = false, bool ABLK = false, bool BBLK = false>
; __device__ __forceinline__ void gemm_phase(PG8_LAS unsigned char* lds, const Gemm g, const Sched& S, const Epi& E) {
;     ...
;             PG8_LDA(At, 0, 1); PG8_STAGE(PG8_SB(0, 0), b2, voffB); PG8_STAGE(PG8_SB(0, 1), b2 + hstepB, voffB); PG8_STAGE(PG8_SA(0, 0), a2, voffA);
;             PG8_WAIT_V(8); PG8_WAIT_L(0); PG8_BAR; PG8_MMA(1, 0, At, B0); PG8_MMA(1, 1, At, B1); PG8_BAR; PG8_SCHED;
;             PG8_LDB(B0, 1, 0); PG8_LDB(B1, 1, 1); PG8_SCHED; PG8_LDA(At, 1, 0); PG8_STAGE(PG8_SA(0, 1), a2 + hstepA, voffA);
;             PG8_WAIT_V(8); PG8_WAIT_L(0); PG8_BAR; PG8_MMA(0, 0, At, B0); PG8_MMA(0, 1, At, B1); PG8_BAR; PG8_SCHED;
;             PG8_LDA(At, 1, 1); PG8_STAGE(PG8_SB(1, 0), b3, voffB); PG8_STAGE(PG8_SB(1, 1), b3 + hstepB, voffB); PG8_STAGE(PG8_SA(1, 0), a3, voffA);
	s_add_i32 s44, s44, s65
	v_lshl_add_u64 v[188:189], s[36:37], 0, v[186:187]
	s_mov_b32 m0, s44
	ds_read_b128 v[162:165], v207 offset:16384
	ds_read_b128 v[166:169], v207 offset:17408
	ds_read_b128 v[170:173], v207 offset:18432
	ds_read_b128 v[174:177], v207 offset:19456
	ds_read_b128 v[198:201], v207 offset:20480
	ds_read_b128 v[208:211], v207 offset:21504
	ds_read_b128 v[212:215], v207 offset:22528
	ds_read_b128 v[216:219], v207 offset:23552
	global_load_lds_dwordx4 v[188:189], off
	s_add_i32 m0, s44, 0x2000
	s_add_u32 s44, s36, 0x4000
	v_lshl_add_u64 v[188:189], s[36:37], 0, v[182:183]
	s_addc_u32 s45, s37, 0
	s_add_i32 s52, s52, s65
	global_load_lds_dwordx4 v[188:189], off
	v_lshl_add_u64 v[188:189], s[44:45], 0, v[186:187]
	s_mov_b32 m0, s52
	s_nop 0
	global_load_lds_dwordx4 v[188:189], off
	v_lshl_add_u64 v[188:189], s[44:45], 0, v[182:183]
	s_add_i32 m0, s52, 0x2000
	s_nop 0
	global_load_lds_dwordx4 v[188:189], off
	v_lshl_add_u64 v[188:189], s[40:41], 0, v[178:179]
	s_mov_b32 m0, s68
	s_nop 0
	global_load_lds_dwordx4 v[188:189], off
	v_lshl_add_u64 v[188:189], s[40:41], 0, v[180:181]
	s_mov_b32 m0, s72
	s_nop 0
	global_load_lds_dwordx4 v[188:189], off
	s_waitcnt vmcnt(8)
	s_waitcnt lgkmcnt(0)
	s_barrier
	s_setprio 1
	s_waitcnt lgkmcnt(0)
	v_mfma_f32_16x16x32_bf16 v[106:109], v[130:133], v[162:165], v[106:109]
	v_mfma_f32_16x16x32_bf16 v[110:113], v[138:141], v[162:165], v[110:113]
	v_mfma_f32_16x16x32_bf16 v[122:125], v[130:133], v[170:173], v[122:125]
	v_mfma_f32_16x16x32_bf16 v[126:129], v[138:141], v[170:173], v[126:129]
	v_mfma_f32_16x16x32_bf16 v[94:97], v[130:133], v[198:201], v[94:97]
	v_mfma_f32_16x16x32_bf16 v[90:93], v[138:141], v[198:201], v[90:93]
	v_mfma_f32_16x16x32_bf16 v[38:41], v[130:133], v[212:215], v[38:41]
	v_mfma_f32_16x16x32_bf16 v[34:37], v[138:141], v[212:215], v[34:37]
	v_mfma_f32_16x16x32_bf16 v[106:109], v[134:137], v[166:169], v[106:109]
	v_mfma_f32_16x16x32_bf16 v[110:113], v[142:145], v[166:169], v[110:113]
	v_mfma_f32_16x16x32_bf16 v[122:125], v[134:137], v[174:177], v[122:125]
	v_mfma_f32_16x16x32_bf16 v[126:129], v[142:145], v[174:177], v[126:129]
	v_mfma_f32_16x16x32_bf16 v[94:97], v[134:137], v[208:211], v[94:97]
	v_mfma_f32_16x16x32_bf16 v[90:93], v[142:145], v[208:211], v[90:93]
	v_mfma_f32_16x16x32_bf16 v[38:41], v[134:137], v[216:219], v[38:41]
	v_mfma_f32_16x16x32_bf16 v[34:37], v[142:145], v[216:219], v[34:37]
	s_setprio 0
	s_setprio 1
	v_mfma_f32_16x16x32_bf16 v[114:117], v[146:149], v[162:165], v[114:117]
	v_mfma_f32_16x16x32_bf16 v[118:121], v[154:157], v[162:165], v[118:121]
	v_mfma_f32_16x16x32_bf16 v[102:105], v[146:149], v[170:173], v[102:105]
	v_mfma_f32_16x16x32_bf16 v[98:101], v[154:157], v[170:173], v[98:101]
	v_mfma_f32_16x16x32_bf16 v[62:65], v[146:149], v[198:201], v[62:65]
	v_mfma_f32_16x16x32_bf16 v[58:61], v[154:157], v[198:201], v[58:61]
	v_mfma_f32_16x16x32_bf16 v[6:9], v[146:149], v[212:215], v[6:9]
	v_mfma_f32_16x16x32_bf16 v[2:5], v[154:157], v[212:215], v[2:5]
	v_mfma_f32_16x16x32_bf16 v[114:117], v[150:153], v[166:169], v[114:117]
	v_mfma_f32_16x16x32_bf16 v[118:121], v[158:161], v[166:169], v[118:121]
	v_mfma_f32_16x16x32_bf16 v[102:105], v[150:153], v[174:177], v[102:105]
	v_mfma_f32_16x16x32_bf16 v[98:101], v[158:161], v[174:177], v[98:101]
	v_mfma_f32_16x16x32_bf16 v[62:65], v[150:153], v[208:211], v[62:65]
	v_mfma_f32_16x16x32_bf16 v[58:61], v[158:161], v[208:211], v[58:61]
	v_mfma_f32_16x16x32_bf16 v[6:9], v[150:153], v[216:219], v[6:9]
	v_mfma_f32_16x16x32_bf16 v[2:5], v[158:161], v[216:219], v[2:5]
	s_setprio 0
	s_barrier
	s_add_i32 s44, 0, 0x18000
	s_add_i32 s45, 0, 0x1c000
	v_add_u32_e32 v142, s44, v206
	v_add_u32_e32 v158, s45, v206
	ds_read_b128 v[130:133], v142
	ds_read_b128 v[134:137], v142 offset:1024
	ds_read_b128 v[138:141], v142 offset:2048
	ds_read_b128 v[142:145], v142 offset:3072
	ds_read_b128 v[146:149], v158
	ds_read_b128 v[150:153], v158 offset:1024
	ds_read_b128 v[154:157], v158 offset:2048
	ds_read_b128 v[158:161], v158 offset:3072
	s_add_u32 s40, s40, 0x4000
	s_addc_u32 s41, s41, 0
	s_mov_b32 m0, s73
	v_lshl_add_u64 v[188:189], s[40:41], 0, v[178:179]
	ds_read_b128 v[162:165], v207 offset:32768
	ds_read_b128 v[166:169], v207 offset:33792
	ds_read_b128 v[170:173], v207 offset:34816
	ds_read_b128 v[174:177], v207 offset:35840
	ds_read_b128 v[198:201], v207 offset:36864
	ds_read_b128 v[208:211], v207 offset:37888
	ds_read_b128 v[212:215], v207 offset:38912
	ds_read_b128 v[216:219], v207 offset:39936
	global_load_lds_dwordx4 v[188:189], off
	v_lshl_add_u64 v[188:189], s[40:41], 0, v[180:181]
	s_mov_b32 m0, s84
	s_nop 0
	global_load_lds_dwordx4 v[188:189], off
	s_waitcnt vmcnt(8)
	s_waitcnt lgkmcnt(0)
	s_barrier
; #define PG8_STAGE(bufoff, gbase, voff) do { _Pragma("unroll") for (int _i = 0; _i < 2; ++_i) \
;         __builtin_amdgcn_global_load_lds((const unsigned*)((const char*)(gbase) + (voff)[_i]), (PG8_LAS unsigned*)(lds + (bufoff) + ldsw + _i * 8192), 16, 0, 0); } while (0)
; #define PG8_LDA(dst, b, h) do { _Pragma("unroll") for (int m = 0; m < 4; ++m) _Pragma("unroll") for (int k = 0; k < 2; ++k) dst[m][k] = *(const PG8_LAS bf16x8*)(lds + PG8_SA(b, h) + aoff + m * 2048 + k * 1024); } while (0)
; #define PG8_MMA(ai, bj, At, Bt) do { __builtin_amdgcn_s_setprio(1); _Pragma("unroll") for (int m = 0; m < 4; ++m) _Pragma("unroll") for (int n = 0; n < 2; ++n) _Pragma("unroll") for (int k = 0; k < 2; ++k) \
;         acc[ai][bj][m][n] = __builtin_amdgcn_mfma_f32_16x16x32_bf16(Bt[n][k], At[m][k], acc[ai][bj][m][n], 0, 0, 0); __builtin_amdgcn_s_setprio(0); } while (0)
; #define PG8_WAIT_V(n) asm volatile("s_waitcnt vmcnt(" #n ")" ::: "memory")
; #define PG8_WAIT_L(n) asm volatile("s_waitcnt lgkmcnt(" #n ")" ::: "memory")
; #define PG8_BAR __builtin_amdgcn_s_barrier()
; #define PG8_SCHED __builtin_amdgcn_sched_barrier(0)
; template <class Epi, class Sched, bool ALIGN_EPI = false, bool SP2 = false, bool ABLK = false, bool BBLK = false>
; __device__ __forceinline__ void gemm_phase(PG8_LAS unsigned char* lds, const Gemm g, const Sched& S, const Epi& E) {
;     ...
;             PG8_WAIT_V(8); PG8_WAIT_L(0); PG8_BAR; PG8_MMA(0, 0, At, B0); PG8_MMA(0, 1, At, B1); PG8_BAR; PG8_SCHED;
;             PG8_LDA(At, 1, 1); PG8_STAGE(PG8_SB(1, 0), b3, voffB); PG8_STAGE(PG8_SB(1, 1), b3 + hstepB, voffB); PG8_STAGE(PG8_SA(1, 0), a3, voffA);
;             PG8_WAIT_V(8); PG8_WAIT_L(0); PG8_BAR; PG8_MMA(1, 0, At, B0); PG8_MMA(1, 1, At, B1); PG8_BAR; PG8_SCHED;
;     ...
;         if constexpr (ALIGN_EPI) { if (wr == 0) PG8_BAR; }
	s_setprio 1
	s_waitcnt lgkmcnt(0)
	v_mfma_f32_16x16x32_bf16 v[30:33], v[130:133], v[162:165], v[30:33]
	v_mfma_f32_16x16x32_bf16 v[22:25], v[138:141], v[162:165], v[22:25]
	v_mfma_f32_16x16x32_bf16 v[18:21], v[130:133], v[170:173], v[18:21]
	v_mfma_f32_16x16x32_bf16 v[10:13], v[138:141], v[170:173], v[10:13]
	v_mfma_f32_16x16x32_bf16 v[50:53], v[130:133], v[198:201], v[50:53]
	v_mfma_f32_16x16x32_bf16 v[54:57], v[138:141], v[198:201], v[54:57]
	v_mfma_f32_16x16x32_bf16 v[74:77], v[130:133], v[212:215], v[74:77]
	v_mfma_f32_16x16x32_bf16 v[78:81], v[138:141], v[212:215], v[78:81]
	v_mfma_f32_16x16x32_bf16 v[30:33], v[134:137], v[166:169], v[30:33]
	v_mfma_f32_16x16x32_bf16 v[22:25], v[142:145], v[166:169], v[22:25]
	v_mfma_f32_16x16x32_bf16 v[18:21], v[134:137], v[174:177], v[18:21]
	v_mfma_f32_16x16x32_bf16 v[10:13], v[142:145], v[174:177], v[10:13]
	v_mfma_f32_16x16x32_bf16 v[50:53], v[134:137], v[208:211], v[50:53]
	v_mfma_f32_16x16x32_bf16 v[54:57], v[142:145], v[208:211], v[54:57]
	v_mfma_f32_16x16x32_bf16 v[74:77], v[134:137], v[216:219], v[74:77]
	v_mfma_f32_16x16x32_bf16 v[78:81], v[142:145], v[216:219], v[78:81]
	s_setprio 0
	s_setprio 1
	v_mfma_f32_16x16x32_bf16 v[26:29], v[146:149], v[162:165], v[26:29]
	v_mfma_f32_16x16x32_bf16 v[14:17], v[154:157], v[162:165], v[14:17]
	v_mfma_f32_16x16x32_bf16 v[42:45], v[146:149], v[170:173], v[42:45]
	v_mfma_f32_16x16x32_bf16 v[46:49], v[154:157], v[170:173], v[46:49]
	v_mfma_f32_16x16x32_bf16 v[66:69], v[146:149], v[198:201], v[66:69]
	v_mfma_f32_16x16x32_bf16 v[70:73], v[154:157], v[198:201], v[70:73]
	v_mfma_f32_16x16x32_bf16 v[82:85], v[146:149], v[212:215], v[82:85]
	v_mfma_f32_16x16x32_bf16 v[86:89], v[154:157], v[212:215], v[86:89]
	v_mfma_f32_16x16x32_bf16 v[26:29], v[150:153], v[166:169], v[26:29]
	v_mfma_f32_16x16x32_bf16 v[14:17], v[158:161], v[166:169], v[14:17]
	v_mfma_f32_16x16x32_bf16 v[42:45], v[150:153], v[174:177], v[42:45]
	v_mfma_f32_16x16x32_bf16 v[46:49], v[158:161], v[174:177], v[46:49]
	v_mfma_f32_16x16x32_bf16 v[66:69], v[150:153], v[208:211], v[66:69]
	v_mfma_f32_16x16x32_bf16 v[70:73], v[158:161], v[208:211], v[70:73]
	v_mfma_f32_16x16x32_bf16 v[82:85], v[150:153], v[216:219], v[82:85]
	v_mfma_f32_16x16x32_bf16 v[86:89], v[158:161], v[216:219], v[86:89]
	s_setprio 0
	s_barrier
	s_add_u32 s40, s36, 0x8000
	s_addc_u32 s41, s37, 0
	s_add_i32 s44, s44, s65
	v_lshl_add_u64 v[188:189], s[40:41], 0, v[186:187]
	s_mov_b32 m0, s44
	ds_read_b128 v[162:165], v207 offset:49152
	ds_read_b128 v[166:169], v207 offset:50176
	ds_read_b128 v[170:173], v207 offset:51200
	ds_read_b128 v[174:177], v207 offset:52224
	ds_read_b128 v[198:201], v207 offset:53248
	ds_read_b128 v[208:211], v207 offset:54272
	ds_read_b128 v[212:215], v207 offset:55296
	ds_read_b128 v[216:219], v207 offset:56320
	global_load_lds_dwordx4 v[188:189], off
	s_add_i32 m0, s44, 0x2000
	s_add_u32 s36, s36, 0xc000
	v_lshl_add_u64 v[188:189], s[40:41], 0, v[182:183]
	s_addc_u32 s37, s37, 0
	s_add_i32 s40, s45, s65
	global_load_lds_dwordx4 v[188:189], off
	v_lshl_add_u64 v[188:189], s[36:37], 0, v[186:187]
	s_mov_b32 m0, s40
	s_nop 0
	global_load_lds_dwordx4 v[188:189], off
	v_lshl_add_u64 v[188:189], s[36:37], 0, v[182:183]
	s_add_i32 m0, s40, 0x2000
	s_nop 0
	global_load_lds_dwordx4 v[188:189], off
	v_lshl_add_u64 v[188:189], s[8:9], 0, v[178:179]
	s_mov_b32 m0, s24
	s_nop 0
	global_load_lds_dwordx4 v[188:189], off
	v_lshl_add_u64 v[188:189], s[8:9], 0, v[180:181]
	s_mov_b32 m0, s25
	s_nop 0
	global_load_lds_dwordx4 v[188:189], off
	s_waitcnt vmcnt(8)
	s_waitcnt lgkmcnt(0)
	s_barrier
	s_setprio 1
	s_waitcnt lgkmcnt(0)
	v_mfma_f32_16x16x32_bf16 v[106:109], v[130:133], v[162:165], v[106:109]
	v_mfma_f32_16x16x32_bf16 v[110:113], v[138:141], v[162:165], v[110:113]
	v_mfma_f32_16x16x32_bf16 v[122:125], v[130:133], v[170:173], v[122:125]
	v_mfma_f32_16x16x32_bf16 v[126:129], v[138:141], v[170:173], v[126:129]
	v_mfma_f32_16x16x32_bf16 v[94:97], v[130:133], v[198:201], v[94:97]
	v_mfma_f32_16x16x32_bf16 v[90:93], v[138:141], v[198:201], v[90:93]
	v_mfma_f32_16x16x32_bf16 v[38:41], v[130:133], v[212:215], v[38:41]
	v_mfma_f32_16x16x32_bf16 v[34:37], v[138:141], v[212:215], v[34:37]
	v_mfma_f32_16x16x32_bf16 v[106:109], v[134:137], v[166:169], v[106:109]
	v_mfma_f32_16x16x32_bf16 v[110:113], v[142:145], v[166:169], v[110:113]
	v_mfma_f32_16x16x32_bf16 v[122:125], v[134:137], v[174:177], v[122:125]
	v_mfma_f32_16x16x32_bf16 v[126:129], v[142:145], v[174:177], v[126:129]
	v_mfma_f32_16x16x32_bf16 v[94:97], v[134:137], v[208:211], v[94:97]
	v_mfma_f32_16x16x32_bf16 v[90:93], v[142:145], v[208:211], v[90:93]
	v_mfma_f32_16x16x32_bf16 v[38:41], v[134:137], v[216:219], v[38:41]
	v_mfma_f32_16x16x32_bf16 v[34:37], v[142:145], v[216:219], v[34:37]
	s_setprio 0
	s_setprio 1
	v_mfma_f32_16x16x32_bf16 v[114:117], v[146:149], v[162:165], v[114:117]
	v_mfma_f32_16x16x32_bf16 v[118:121], v[154:157], v[162:165], v[118:121]
	v_mfma_f32_16x16x32_bf16 v[102:105], v[146:149], v[170:173], v[102:105]
	v_mfma_f32_16x16x32_bf16 v[98:101], v[154:157], v[170:173], v[98:101]
	v_mfma_f32_16x16x32_bf16 v[62:65], v[146:149], v[198:201], v[62:65]
	v_mfma_f32_16x16x32_bf16 v[58:61], v[154:157], v[198:201], v[58:61]
	v_mfma_f32_16x16x32_bf16 v[6:9], v[146:149], v[212:215], v[6:9]
	v_mfma_f32_16x16x32_bf16 v[2:5], v[154:157], v[212:215], v[2:5]
	v_mfma_f32_16x16x32_bf16 v[114:117], v[150:153], v[166:169], v[114:117]
	v_mfma_f32_16x16x32_bf16 v[118:121], v[158:161], v[166:169], v[118:121]
	v_mfma_f32_16x16x32_bf16 v[102:105], v[150:153], v[174:177], v[102:105]
	v_mfma_f32_16x16x32_bf16 v[98:101], v[158:161], v[174:177], v[98:101]
	v_mfma_f32_16x16x32_bf16 v[62:65], v[150:153], v[208:211], v[62:65]
	v_mfma_f32_16x16x32_bf16 v[58:61], v[158:161], v[208:211], v[58:61]
	v_mfma_f32_16x16x32_bf16 v[6:9], v[150:153], v[216:219], v[6:9]
	v_mfma_f32_16x16x32_bf16 v[2:5], v[158:161], v[216:219], v[2:5]
	s_setprio 0
	s_barrier
	s_add_i32 s35, s35, 2
	s_add_u32 s0, s0, 0x10000
	s_addc_u32 s1, s1, 0
	s_add_u32 s31, s31, 0x10000
	s_addc_u32 s33, s33, 0
	s_cmpk_gt_u32 s35, 0x55
	s_cbranch_scc0 .LBB0_1483
	s_and_b64 vcc, exec, s[20:21]
	s_cbranch_vccz .LBB0_1486
	s_barrier

;     __device__ __forceinline__ void operator()(f32x4 (&acc)[2][2][4][2], const Unit& u, int wr, int wc, int fr_, int fq_) const {
;     ...
;         f32x4 av[2][2], sv[2][2];
; #pragma unroll
;         for (int bj = 0; bj < 2; ++bj)
; #pragma unroll
;             for (int n = 0; n < 2; ++n) { const int col = col0 + bj * HALF + 4 * n; const f32x4 g = *(const f32x4*)(gain + col);
;                 if (FINAL) { av[bj][n] = g; sv[bj][n] = (f32x4){0.f, 0.f, 0.f, 0.f}; }
;                 else { const float* mp = nmod + (size_t)rb * NMODC; av[bj][n] = g * (*(const f32x4*)(mp + isc * DM + col) + 1.0f); sv[bj][n] = *(const f32x4*)(mp + ish * DM + col); } }
;         if (wid == 0) { if (lane == 0) { unsigned sp = 0u; while (__hip_atomic_load(cnt + 16 * u.pm, __ATOMIC_RELAXED, __HIP_MEMORY_SCOPE_AGENT) < 64u) { __builtin_amdgcn_s_sleep(1); if (++sp > (1u << 17)) break; } } }
;         asm volatile("s_waitcnt lgkmcnt(0)" ::: "memory"); __builtin_amdgcn_s_barrier(); asm volatile("" ::: "memory");
;         if (lane < 32) { const float* slot = xbuf + ((size_t)u.pm * BM + row) * 8; float t8[8];
; #pragma unroll
;             for (int t = 0; t < 8; ++t) t8[t] = __hip_atomic_load(slot + t, __ATOMIC_RELAXED, __HIP_MEMORY_SCOPE_AGENT);
;             const float tot = ((t8[0] + t8[1]) + (t8[2] + t8[3])) + ((t8[4] + t8[5]) + (t8[6] + t8[7]));
;             S[row] = __builtin_amdgcn_rsqf(tot * (1.0f / DM) + 1e-6f); }
;         asm volatile("s_waitcnt lgkmcnt(0)" ::: "memory"); __builtin_amdgcn_s_barrier(); asm volatile("" ::: "memory");
; #pragma unroll
;         for (int ai = 0; ai < 2; ++ai)
; #pragma unroll
;             for (int m = 0; m < 4; ++m) { const int r = ai * HALF + wr * 64 + m * 16 + fr; const float rs = S[r];
; #pragma unroll
;                 for (int bj = 0; bj < 2; ++bj) { const f32x4 y0 = acc[ai][bj][m][0] * rs * av[bj][0] + sv[bj][0], y1 = acc[ai][bj][m][1] * rs * av[bj][1] + sv[bj][1];
;                     if (FINAL) { float* o = OUTF + ((size_t)u.pm * BM + r) * DM + col0 + bj * HALF; *(f32x4*)o = y0; *(f32x4*)(o + 4) = y1; }
;                     else *(u32x4*)(XN + (((size_t)u.pm * (DM / BK) + u.pn * 4 + bj * 2 + (wc >> 1)) * BM + r) * BK + (wc & 1) * 32 + 8 * fq) = pack8(y0, y1); } }
.LBB0_1518:
	s_or_b64 exec, exec, s[0:1]
	s_waitcnt vmcnt(5)
	v_pk_add_f32 v[154:155], v[154:155], 1.0 op_sel_hi:[1,0]
	v_pk_add_f32 v[156:157], v[156:157], 1.0 op_sel_hi:[1,0]
	v_pk_mul_f32 v[146:147], v[146:147], v[154:155]
	v_lshl_add_u32 v154, v198, 2, 0
	s_waitcnt lgkmcnt(0)
	s_barrier
	s_lshl_b32 s8, s30, 2
	v_add_u32_e32 v154, 0x21540, v154
	v_pk_mul_f32 v[148:149], v[148:149], v[156:157]
	s_lshl_b64 s[0:1], s[34:35], 5
	s_ashr_i32 s9, s8, 31
	ds_read_b32 v156, v154
	s_add_u32 s0, s0, s8
	s_addc_u32 s1, s1, s9
	s_or_b64 s[0:1], s[0:1], s[22:23]
	s_waitcnt vmcnt(3)
	v_pk_add_f32 v[158:159], v[158:159], 1.0 op_sel_hi:[1,0]
	s_lshl_b64 s[0:1], s[0:1], 15
	v_pk_add_f32 v[160:161], v[160:161], 1.0 op_sel_hi:[1,0]
	v_pk_mul_f32 v[150:151], v[150:151], v[158:159]
	s_waitcnt lgkmcnt(0)
	v_pk_mul_f32 v[30:31], v[30:31], v[156:157] op_sel_hi:[1,0]
	v_pk_mul_f32 v[32:33], v[32:33], v[156:157] op_sel_hi:[1,0]
	v_pk_mul_f32 v[22:23], v[22:23], v[156:157] op_sel_hi:[1,0]
	s_add_u32 s0, s94, s0
	v_pk_mul_f32 v[152:153], v[152:153], v[160:161]
	v_lshlrev_b64 v[158:159], 7, v[198:199]
	v_pk_fma_f32 v[32:33], v[148:149], v[32:33], v[144:145]
	v_pk_fma_f32 v[30:31], v[146:147], v[30:31], v[142:143]
	v_pk_mul_f32 v[24:25], v[24:25], v[156:157] op_sel_hi:[1,0]
	v_pk_fma_f32 v[22:23], v[150:151], v[22:23], v[138:139]
	s_addc_u32 s1, s95, s1
	v_ashrrev_i32_e32 v201, 31, v200
	v_pk_fma_f32 v[24:25], v[152:153], v[24:25], v[140:141]
	v_cvt_pk_bf16_f32 v30, v30, v31
	v_cvt_pk_bf16_f32 v31, v32, v33
	v_cvt_pk_bf16_f32 v32, v22, v23
	v_lshl_add_u64 v[22:23], s[0:1], 0, v[158:159]
	v_cvt_pk_bf16_f32 v33, v24, v25
	v_lshl_add_u64 v[24:25], v[22:23], 0, s[16:17]
	v_lshlrev_b64 v[22:23], 1, v[200:201]
	v_pk_add_f32 v[176:177], v[176:177], 1.0 op_sel_hi:[1,0]
	v_pk_add_f32 v[174:175], v[174:175], 1.0 op_sel_hi:[1,0]
	s_waitcnt vmcnt(2)
	v_pk_add_f32 v[172:173], v[172:173], 1.0 op_sel_hi:[1,0]
	v_lshl_add_u64 v[24:25], v[24:25], 0, v[22:23]
	v_pk_mul_f32 v[166:167], v[166:167], v[174:175]
	v_pk_mul_f32 v[168:169], v[168:169], v[176:177]
	v_pk_add_f32 v[170:171], v[170:171], 1.0 op_sel_hi:[1,0]
	v_pk_mul_f32 v[164:165], v[164:165], v[172:173]
	global_store_dwordx4 v[24:25], v[30:33], off
	v_pk_mul_f32 v[24:25], v[26:27], v[156:157] op_sel_hi:[1,0]
	v_pk_mul_f32 v[26:27], v[28:29], v[156:157] op_sel_hi:[1,0]
	v_pk_mul_f32 v[14:15], v[14:15], v[156:157] op_sel_hi:[1,0]
	v_pk_mul_f32 v[16:17], v[16:17], v[156:157] op_sel_hi:[1,0]
	v_pk_mul_f32 v[162:163], v[162:163], v[170:171]
	s_waitcnt vmcnt(1)
	v_pk_fma_f32 v[26:27], v[164:165], v[26:27], v[136:137]
	v_pk_fma_f32 v[28:29], v[168:169], v[16:17], v[132:133]
	v_pk_fma_f32 v[16:17], v[166:167], v[14:15], v[130:131]
	s_add_u32 s8, s0, 0x10000
	v_pk_fma_f32 v[24:25], v[162:163], v[24:25], v[134:135]
	s_addc_u32 s9, s1, 0
	v_cvt_pk_bf16_f32 v14, v24, v25
	v_cvt_pk_bf16_f32 v15, v26, v27
	v_cvt_pk_bf16_f32 v16, v16, v17
	v_cvt_pk_bf16_f32 v17, v28, v29
	ds_read_b32 v26, v154 offset:64
	v_lshl_add_u64 v[24:25], s[8:9], 0, v[158:159]
	v_lshl_add_u64 v[24:25], v[24:25], 0, s[16:17]
	v_lshl_add_u64 v[24:25], v[24:25], 0, v[22:23]
	global_store_dwordx4 v[24:25], v[14:17], off
	s_waitcnt lgkmcnt(0)
	v_pk_mul_f32 v[10:11], v[10:11], v[26:27] op_sel_hi:[1,0]
	v_pk_mul_f32 v[12:13], v[12:13], v[26:27] op_sel_hi:[1,0]
	v_add_u32_e32 v14, 16, v198
	v_ashrrev_i32_e32 v15, 31, v14
	v_pk_mul_f32 v[16:17], v[18:19], v[26:27] op_sel_hi:[1,0]
	v_lshlrev_b64 v[14:15], 7, v[14:15]
	v_pk_fma_f32 v[16:17], v[146:147], v[16:17], v[142:143]
	v_pk_mul_f32 v[18:19], v[20:21], v[26:27] op_sel_hi:[1,0]
	v_pk_fma_f32 v[20:21], v[152:153], v[12:13], v[140:141]
	v_pk_fma_f32 v[12:13], v[150:151], v[10:11], v[138:139]
	v_cvt_pk_bf16_f32 v10, v16, v17
	v_lshl_add_u64 v[16:17], s[0:1], 0, v[14:15]
	v_lshl_add_u64 v[16:17], v[16:17], 0, s[16:17]
	v_pk_fma_f32 v[18:19], v[148:149], v[18:19], v[144:145]
	v_lshl_add_u64 v[16:17], v[16:17], 0, v[22:23]
	v_cvt_pk_bf16_f32 v11, v18, v19
	v_cvt_pk_bf16_f32 v12, v12, v13
	v_cvt_pk_bf16_f32 v13, v20, v21
	global_store_dwordx4 v[16:17], v[10:13], off
	v_pk_mul_f32 v[16:17], v[46:47], v[26:27] op_sel_hi:[1,0]
	v_pk_mul_f32 v[18:19], v[48:49], v[26:27] op_sel_hi:[1,0]
	v_pk_mul_f32 v[10:11], v[42:43], v[26:27] op_sel_hi:[1,0]
	v_pk_mul_f32 v[12:13], v[44:45], v[26:27] op_sel_hi:[1,0]
	v_pk_fma_f32 v[10:11], v[162:163], v[10:11], v[134:135]
	v_pk_fma_f32 v[12:13], v[164:165], v[12:13], v[136:137]
	v_pk_fma_f32 v[16:17], v[166:167], v[16:17], v[130:131]
	v_pk_fma_f32 v[18:19], v[168:169], v[18:19], v[132:133]
	v_cvt_pk_bf16_f32 v10, v10, v11
	v_cvt_pk_bf16_f32 v11, v12, v13
	v_cvt_pk_bf16_f32 v12, v16, v17
	v_lshl_add_u64 v[14:15], s[8:9], 0, v[14:15]
	v_cvt_pk_bf16_f32 v13, v18, v19
	ds_read_b32 v16, v154 offset:128
	v_lshl_add_u64 v[14:15], v[14:15], 0, s[16:17]
	v_lshl_add_u64 v[14:15], v[14:15], 0, v[22:23]
	global_store_dwordx4 v[14:15], v[10:13], off
	s_and_b64 vcc, exec, s[6:7]
	s_waitcnt lgkmcnt(0)
; __device__ __forceinline__ u32x4 pack8(const f32x4 v0, const f32x4 v1) { u32x4 w; w.x = cvt_pk_bf16(v0[0], v0[1]); w.y = cvt_pk_bf16(v0[2], v0[3]); w.z = cvt_pk_bf16(v1[0], v1[1]); w.w = cvt_pk_bf16(v1[2], v1[3]); return w; }
;     __device__ __forceinline__ void operator()(f32x4 (&acc)[2][2][4][2], const Unit& u, int wr, int wc, int fr_, int fq_) const {
;     ...
; #pragma unroll
;         for (int ai = 0; ai < 2; ++ai)
; #pragma unroll
;             for (int m = 0; m < 4; ++m) { const int r = ai * HALF + wr * 64 + m * 16 + fr; const float rs = S[r];
; #pragma unroll
;                 for (int bj = 0; bj < 2; ++bj) { const f32x4 y0 = acc[ai][bj][m][0] * rs * av[bj][0] + sv[bj][0], y1 = acc[ai][bj][m][1] * rs * av[bj][1] + sv[bj][1];
;                     if (FINAL) { float* o = OUTF + ((size_t)u.pm * BM + r) * DM + col0 + bj * HALF; *(f32x4*)o = y0; *(f32x4*)(o + 4) = y1; }
;                     else *(u32x4*)(XN + (((size_t)u.pm * (DM / BK) + u.pn * 4 + bj * 2 + (wc >> 1)) * BM + r) * BK + (wc & 1) * 32 + 8 * fq) = pack8(y0, y1); } }
	v_pk_mul_f32 v[18:19], v[54:55], v[16:17] op_sel_hi:[1,0]
	v_add_u32_e32 v10, 32, v198
	v_ashrrev_i32_e32 v11, 31, v10
	v_lshlrev_b64 v[14:15], 7, v[10:11]
	v_pk_mul_f32 v[10:11], v[50:51], v[16:17] op_sel_hi:[1,0]
	v_pk_mul_f32 v[12:13], v[52:53], v[16:17] op_sel_hi:[1,0]
	v_pk_fma_f32 v[10:11], v[146:147], v[10:11], v[142:143]
	v_pk_fma_f32 v[12:13], v[148:149], v[12:13], v[144:145]
	v_pk_fma_f32 v[18:19], v[150:151], v[18:19], v[138:139]
	v_cvt_pk_bf16_f32 v10, v10, v11
	v_cvt_pk_bf16_f32 v11, v12, v13
	v_pk_mul_f32 v[20:21], v[56:57], v[16:17] op_sel_hi:[1,0]
	v_cvt_pk_bf16_f32 v12, v18, v19
	v_lshl_add_u64 v[18:19], s[0:1], 0, v[14:15]
	v_lshl_add_u64 v[18:19], v[18:19], 0, s[16:17]
	v_pk_fma_f32 v[20:21], v[152:153], v[20:21], v[140:141]
	v_lshl_add_u64 v[18:19], v[18:19], 0, v[22:23]
	v_cvt_pk_bf16_f32 v13, v20, v21
	global_store_dwordx4 v[18:19], v[10:13], off
	v_pk_mul_f32 v[18:19], v[70:71], v[16:17] op_sel_hi:[1,0]
	v_lshl_add_u64 v[14:15], s[8:9], 0, v[14:15]
	v_pk_mul_f32 v[10:11], v[66:67], v[16:17] op_sel_hi:[1,0]
	v_pk_mul_f32 v[12:13], v[68:69], v[16:17] op_sel_hi:[1,0]
	v_pk_mul_f32 v[16:17], v[72:73], v[16:17] op_sel_hi:[1,0]
	v_pk_fma_f32 v[12:13], v[164:165], v[12:13], v[136:137]
	v_pk_fma_f32 v[10:11], v[162:163], v[10:11], v[134:135]
	v_pk_fma_f32 v[16:17], v[168:169], v[16:17], v[132:133]
	v_pk_fma_f32 v[18:19], v[166:167], v[18:19], v[130:131]
	v_cvt_pk_bf16_f32 v10, v10, v11
	v_cvt_pk_bf16_f32 v11, v12, v13
	v_lshl_add_u64 v[14:15], v[14:15], 0, s[16:17]
	v_cvt_pk_bf16_f32 v12, v18, v19
	v_cvt_pk_bf16_f32 v13, v16, v17
	ds_read_b32 v16, v154 offset:192
	v_lshl_add_u64 v[14:15], v[14:15], 0, v[22:23]
	global_store_dwordx4 v[14:15], v[10:13], off
	s_waitcnt lgkmcnt(0)
	v_pk_mul_f32 v[18:19], v[78:79], v[16:17] op_sel_hi:[1,0]
	v_add_u32_e32 v10, 48, v198
	v_ashrrev_i32_e32 v11, 31, v10
	v_lshlrev_b64 v[14:15], 7, v[10:11]
	v_pk_mul_f32 v[10:11], v[74:75], v[16:17] op_sel_hi:[1,0]
	v_pk_mul_f32 v[12:13], v[76:77], v[16:17] op_sel_hi:[1,0]
	v_pk_fma_f32 v[10:11], v[146:147], v[10:11], v[142:143]
	v_pk_fma_f32 v[12:13], v[148:149], v[12:13], v[144:145]
	v_pk_fma_f32 v[18:19], v[150:151], v[18:19], v[138:139]
	v_cvt_pk_bf16_f32 v10, v10, v11
	v_cvt_pk_bf16_f32 v11, v12, v13
	v_pk_mul_f32 v[20:21], v[80:81], v[16:17] op_sel_hi:[1,0]
	v_cvt_pk_bf16_f32 v12, v18, v19
	v_lshl_add_u64 v[18:19], s[0:1], 0, v[14:15]
	v_lshl_add_u64 v[18:19], v[18:19], 0, s[16:17]
	v_pk_fma_f32 v[20:21], v[152:153], v[20:21], v[140:141]
	v_lshl_add_u64 v[18:19], v[18:19], 0, v[22:23]
	v_cvt_pk_bf16_f32 v13, v20, v21
	global_store_dwordx4 v[18:19], v[10:13], off
	v_pk_mul_f32 v[18:19], v[86:87], v[16:17] op_sel_hi:[1,0]
	v_lshl_add_u64 v[14:15], s[8:9], 0, v[14:15]
	v_pk_mul_f32 v[10:11], v[82:83], v[16:17] op_sel_hi:[1,0]
	v_pk_mul_f32 v[12:13], v[84:85], v[16:17] op_sel_hi:[1,0]
	v_pk_mul_f32 v[16:17], v[88:89], v[16:17] op_sel_hi:[1,0]
	v_pk_fma_f32 v[12:13], v[164:165], v[12:13], v[136:137]
	v_pk_fma_f32 v[10:11], v[162:163], v[10:11], v[134:135]
	v_pk_fma_f32 v[16:17], v[168:169], v[16:17], v[132:133]
	v_pk_fma_f32 v[18:19], v[166:167], v[18:19], v[130:131]
	v_cvt_pk_bf16_f32 v10, v10, v11
	v_cvt_pk_bf16_f32 v11, v12, v13
	v_lshl_add_u64 v[14:15], v[14:15], 0, s[16:17]
	v_cvt_pk_bf16_f32 v12, v18, v19
	v_cvt_pk_bf16_f32 v13, v16, v17
	ds_read_b32 v16, v154 offset:512
	v_lshl_add_u64 v[14:15], v[14:15], 0, v[22:23]
	global_store_dwordx4 v[14:15], v[10:13], off
	s_waitcnt lgkmcnt(0)
	v_pk_mul_f32 v[18:19], v[110:111], v[16:17] op_sel_hi:[1,0]
	v_add_u32_e32 v10, 0x80, v198
	v_ashrrev_i32_e32 v11, 31, v10
	v_lshlrev_b64 v[14:15], 7, v[10:11]
	v_pk_mul_f32 v[10:11], v[106:107], v[16:17] op_sel_hi:[1,0]
	v_pk_mul_f32 v[12:13], v[108:109], v[16:17] op_sel_hi:[1,0]
	v_pk_fma_f32 v[10:11], v[146:147], v[10:11], v[142:143]
	v_pk_fma_f32 v[12:13], v[148:149], v[12:13], v[144:145]
	v_pk_fma_f32 v[18:19], v[150:151], v[18:19], v[138:139]
	v_cvt_pk_bf16_f32 v10, v10, v11
	v_cvt_pk_bf16_f32 v11, v12, v13
	v_pk_mul_f32 v[20:21], v[112:113], v[16:17] op_sel_hi:[1,0]
	v_cvt_pk_bf16_f32 v12, v18, v19
	v_lshl_add_u64 v[18:19], s[0:1], 0, v[14:15]
	v_lshl_add_u64 v[18:19], v[18:19], 0, s[16:17]
	v_pk_fma_f32 v[20:21], v[152:153], v[20:21], v[140:141]
	v_lshl_add_u64 v[18:19], v[18:19], 0, v[22:23]
	v_cvt_pk_bf16_f32 v13, v20, v21
	global_store_dwordx4 v[18:19], v[10:13], off
	v_pk_mul_f32 v[18:19], v[118:119], v[16:17] op_sel_hi:[1,0]
	v_lshl_add_u64 v[14:15], s[8:9], 0, v[14:15]
	v_pk_mul_f32 v[10:11], v[114:115], v[16:17] op_sel_hi:[1,0]
	v_pk_mul_f32 v[12:13], v[116:117], v[16:17] op_sel_hi:[1,0]
	v_pk_mul_f32 v[16:17], v[120:121], v[16:17] op_sel_hi:[1,0]
	v_pk_fma_f32 v[12:13], v[164:165], v[12:13], v[136:137]
	v_pk_fma_f32 v[10:11], v[162:163], v[10:11], v[134:135]
	v_pk_fma_f32 v[16:17], v[168:169], v[16:17], v[132:133]
	v_pk_fma_f32 v[18:19], v[166:167], v[18:19], v[130:131]
	v_cvt_pk_bf16_f32 v10, v10, v11
	v_cvt_pk_bf16_f32 v11, v12, v13
	v_lshl_add_u64 v[14:15], v[14:15], 0, s[16:17]
	v_cvt_pk_bf16_f32 v12, v18, v19
	v_cvt_pk_bf16_f32 v13, v16, v17
	ds_read_b32 v16, v154 offset:576
	v_lshl_add_u64 v[14:15], v[14:15], 0, v[22:23]
	global_store_dwordx4 v[14:15], v[10:13], off
	s_waitcnt lgkmcnt(0)
; __device__ __forceinline__ u32x4 pack8(const f32x4 v0, const f32x4 v1) { u32x4 w; w.x = cvt_pk_bf16(v0[0], v0[1]); w.y = cvt_pk_bf16(v0[2], v0[3]); w.z = cvt_pk_bf16(v1[0], v1[1]); w.w = cvt_pk_bf16(v1[2], v1[3]); return w; }
; #define PG8_BAR __builtin_amdgcn_s_barrier()
;     __device__ __forceinline__ void operator()(f32x4 (&acc)[2][2][4][2], const Unit& u, int wr, int wc, int fr_, int fq_) const {
;     ...
; #pragma unroll
;         for (int ai = 0; ai < 2; ++ai)
; #pragma unroll
;             for (int m = 0; m < 4; ++m) { const int r = ai * HALF + wr * 64 + m * 16 + fr; const float rs = S[r];
; #pragma unroll
;                 for (int bj = 0; bj < 2; ++bj) { const f32x4 y0 = acc[ai][bj][m][0] * rs * av[bj][0] + sv[bj][0], y1 = acc[ai][bj][m][1] * rs * av[bj][1] + sv[bj][1];
;                     if (FINAL) { float* o = OUTF + ((size_t)u.pm * BM + r) * DM + col0 + bj * HALF; *(f32x4*)o = y0; *(f32x4*)(o + 4) = y1; }
;                     else *(u32x4*)(XN + (((size_t)u.pm * (DM / BK) + u.pn * 4 + bj * 2 + (wc >> 1)) * BM + r) * BK + (wc & 1) * 32 + 8 * fq) = pack8(y0, y1); } }
; template <class Epi, class Sched, bool ALIGN_EPI = false, bool SP2 = false, bool ABLK = false, bool BBLK = false>
; __device__ __forceinline__ void gemm_phase(PG8_LAS unsigned char* lds, const Gemm g, const Sched& S, const Epi& E) {
;     ...
;         if (!has_next) break;
; #pragma unroll
;         for (int a = 0; a < 2; ++a)
; #pragma unroll
;             for (int b = 0; b < 2; ++b)
; #pragma unroll
;                 for (int m = 0; m < 4; ++m)
; #pragma unroll
;                     for (int n = 0; n < 2; ++n) acc[a][b][m][n] = (f32x4){0.f, 0.f, 0.f, 0.f};
;         cur = nxt; cA = nA; cB = nB; ++ui;
;         if constexpr (ALIGN_EPI) { if (wr == 1) PG8_BAR; }
;     }
	v_pk_mul_f32 v[18:19], v[126:127], v[16:17] op_sel_hi:[1,0]
	v_add_u32_e32 v10, 0x90, v198
	v_ashrrev_i32_e32 v11, 31, v10
	v_lshlrev_b64 v[14:15], 7, v[10:11]
	v_pk_mul_f32 v[10:11], v[122:123], v[16:17] op_sel_hi:[1,0]
	v_pk_mul_f32 v[12:13], v[124:125], v[16:17] op_sel_hi:[1,0]
	v_pk_fma_f32 v[10:11], v[146:147], v[10:11], v[142:143]
	v_pk_fma_f32 v[12:13], v[148:149], v[12:13], v[144:145]
	v_pk_fma_f32 v[18:19], v[150:151], v[18:19], v[138:139]
	v_cvt_pk_bf16_f32 v10, v10, v11
	v_cvt_pk_bf16_f32 v11, v12, v13
	v_pk_mul_f32 v[20:21], v[128:129], v[16:17] op_sel_hi:[1,0]
	v_cvt_pk_bf16_f32 v12, v18, v19
	v_lshl_add_u64 v[18:19], s[0:1], 0, v[14:15]
	v_lshl_add_u64 v[18:19], v[18:19], 0, s[16:17]
	v_pk_fma_f32 v[20:21], v[152:153], v[20:21], v[140:141]
	v_lshl_add_u64 v[18:19], v[18:19], 0, v[22:23]
	v_cvt_pk_bf16_f32 v13, v20, v21
	global_store_dwordx4 v[18:19], v[10:13], off
	v_pk_mul_f32 v[18:19], v[98:99], v[16:17] op_sel_hi:[1,0]
	v_lshl_add_u64 v[14:15], s[8:9], 0, v[14:15]
	v_pk_mul_f32 v[10:11], v[102:103], v[16:17] op_sel_hi:[1,0]
	v_pk_mul_f32 v[12:13], v[104:105], v[16:17] op_sel_hi:[1,0]
	v_pk_mul_f32 v[16:17], v[100:101], v[16:17] op_sel_hi:[1,0]
	v_pk_fma_f32 v[12:13], v[164:165], v[12:13], v[136:137]
	v_pk_fma_f32 v[10:11], v[162:163], v[10:11], v[134:135]
	v_pk_fma_f32 v[16:17], v[168:169], v[16:17], v[132:133]
	v_pk_fma_f32 v[18:19], v[166:167], v[18:19], v[130:131]
	v_cvt_pk_bf16_f32 v10, v10, v11
	v_cvt_pk_bf16_f32 v11, v12, v13
	v_lshl_add_u64 v[14:15], v[14:15], 0, s[16:17]
	v_cvt_pk_bf16_f32 v12, v18, v19
	v_cvt_pk_bf16_f32 v13, v16, v17
	ds_read_b32 v16, v154 offset:640
	v_lshl_add_u64 v[14:15], v[14:15], 0, v[22:23]
	global_store_dwordx4 v[14:15], v[10:13], off
	s_waitcnt lgkmcnt(0)
	v_pk_mul_f32 v[18:19], v[90:91], v[16:17] op_sel_hi:[1,0]
	v_add_u32_e32 v10, 0xa0, v198
	v_ashrrev_i32_e32 v11, 31, v10
	v_lshlrev_b64 v[14:15], 7, v[10:11]
	v_pk_mul_f32 v[10:11], v[94:95], v[16:17] op_sel_hi:[1,0]
	v_pk_mul_f32 v[12:13], v[96:97], v[16:17] op_sel_hi:[1,0]
	v_pk_fma_f32 v[10:11], v[146:147], v[10:11], v[142:143]
	v_pk_fma_f32 v[12:13], v[148:149], v[12:13], v[144:145]
	v_pk_fma_f32 v[18:19], v[150:151], v[18:19], v[138:139]
	v_cvt_pk_bf16_f32 v10, v10, v11
	v_cvt_pk_bf16_f32 v11, v12, v13
	v_pk_mul_f32 v[20:21], v[92:93], v[16:17] op_sel_hi:[1,0]
	v_cvt_pk_bf16_f32 v12, v18, v19
	v_lshl_add_u64 v[18:19], s[0:1], 0, v[14:15]
	v_lshl_add_u64 v[18:19], v[18:19], 0, s[16:17]
	v_pk_fma_f32 v[20:21], v[152:153], v[20:21], v[140:141]
	v_lshl_add_u64 v[18:19], v[18:19], 0, v[22:23]
	v_cvt_pk_bf16_f32 v13, v20, v21
	global_store_dwordx4 v[18:19], v[10:13], off
	v_pk_mul_f32 v[18:19], v[58:59], v[16:17] op_sel_hi:[1,0]
	v_lshl_add_u64 v[14:15], s[8:9], 0, v[14:15]
	v_pk_mul_f32 v[10:11], v[62:63], v[16:17] op_sel_hi:[1,0]
	v_pk_mul_f32 v[12:13], v[64:65], v[16:17] op_sel_hi:[1,0]
	v_pk_mul_f32 v[16:17], v[60:61], v[16:17] op_sel_hi:[1,0]
	v_pk_fma_f32 v[12:13], v[164:165], v[12:13], v[136:137]
	v_pk_fma_f32 v[10:11], v[162:163], v[10:11], v[134:135]
	v_pk_fma_f32 v[16:17], v[168:169], v[16:17], v[132:133]
	v_pk_fma_f32 v[18:19], v[166:167], v[18:19], v[130:131]
	v_cvt_pk_bf16_f32 v10, v10, v11
	v_cvt_pk_bf16_f32 v11, v12, v13
	v_lshl_add_u64 v[14:15], v[14:15], 0, s[16:17]
	v_cvt_pk_bf16_f32 v12, v18, v19
	v_cvt_pk_bf16_f32 v13, v16, v17
	ds_read_b32 v16, v154 offset:704
	v_lshl_add_u64 v[14:15], v[14:15], 0, v[22:23]
	global_store_dwordx4 v[14:15], v[10:13], off
	s_waitcnt lgkmcnt(0)
	v_pk_mul_f32 v[18:19], v[34:35], v[16:17] op_sel_hi:[1,0]
	v_add_u32_e32 v10, 0xb0, v198
	v_ashrrev_i32_e32 v11, 31, v10
	v_lshlrev_b64 v[14:15], 7, v[10:11]
	v_pk_mul_f32 v[10:11], v[38:39], v[16:17] op_sel_hi:[1,0]
	v_pk_mul_f32 v[12:13], v[40:41], v[16:17] op_sel_hi:[1,0]
	v_pk_fma_f32 v[10:11], v[146:147], v[10:11], v[142:143]
	v_pk_fma_f32 v[12:13], v[148:149], v[12:13], v[144:145]
	v_pk_fma_f32 v[18:19], v[150:151], v[18:19], v[138:139]
	v_cvt_pk_bf16_f32 v10, v10, v11
	v_cvt_pk_bf16_f32 v11, v12, v13
	v_pk_mul_f32 v[6:7], v[6:7], v[16:17] op_sel_hi:[1,0]
	v_cvt_pk_bf16_f32 v12, v18, v19
	v_lshl_add_u64 v[18:19], s[0:1], 0, v[14:15]
	v_lshl_add_u64 v[18:19], v[18:19], 0, s[16:17]
	v_pk_mul_f32 v[20:21], v[36:37], v[16:17] op_sel_hi:[1,0]
	v_lshl_add_u64 v[18:19], v[18:19], 0, v[22:23]
	v_pk_fma_f32 v[6:7], v[162:163], v[6:7], v[134:135]
	v_pk_mul_f32 v[2:3], v[2:3], v[16:17] op_sel_hi:[1,0]
	v_pk_mul_f32 v[4:5], v[4:5], v[16:17] op_sel_hi:[1,0]
	v_pk_fma_f32 v[20:21], v[152:153], v[20:21], v[140:141]
	v_pk_mul_f32 v[8:9], v[8:9], v[16:17] op_sel_hi:[1,0]
	v_cvt_pk_bf16_f32 v13, v20, v21
	global_store_dwordx4 v[18:19], v[10:13], off
	s_mov_b64 s[0:1], -1
	v_pk_fma_f32 v[8:9], v[164:165], v[8:9], v[136:137]
	v_pk_fma_f32 v[10:11], v[168:169], v[4:5], v[132:133]
	v_pk_fma_f32 v[4:5], v[166:167], v[2:3], v[130:131]
	v_cvt_pk_bf16_f32 v2, v6, v7
	v_lshl_add_u64 v[6:7], s[8:9], 0, v[14:15]
	v_lshl_add_u64 v[6:7], v[6:7], 0, s[16:17]
	v_lshl_add_u64 v[6:7], v[6:7], 0, v[22:23]
	v_cvt_pk_bf16_f32 v3, v8, v9
	v_cvt_pk_bf16_f32 v4, v4, v5
	v_cvt_pk_bf16_f32 v5, v10, v11
	global_store_dwordx4 v[6:7], v[2:5], off
	s_cbranch_vccnz .LBB0_1472
	v_readlane_b32 s0, v254, 39
	v_readlane_b32 s1, v254, 40
	s_andn2_b64 vcc, exec, s[0:1]
	s_cbranch_vccnz .LBB0_1471
	s_branch .LBB0_1471
